# loop counter and exit compare moved into the last load segment; leading-half extra barrier placed behind the epilogue's first loads
# baseline (speedup 1.0000x reference)
; #define PG8_STAGE(bufoff, gbase, voff) do { _Pragma("unroll") for (int _i = 0; _i < 2; ++_i) \
;         __builtin_amdgcn_global_load_lds((const unsigned*)((const char*)(gbase) + (voff)[_i]), (LAS unsigned*)(lds + (bufoff) + ldsw + _i * 8192), 16, 0, 0); } while (0)
; #define PG8_LDA(dst, b, h) do { _Pragma("unroll") for (int m = 0; m < 4; ++m) _Pragma("unroll") for (int k = 0; k < 2; ++k) dst[m][k] = *(const LAS h16x8*)(lds + PG8_SA(b, h) + aoff + m * 2048 + k * 1024); } while (0)
; #define PG8_LDB(dst, b, h) do { _Pragma("unroll") for (int n = 0; n < 2; ++n) _Pragma("unroll") for (int k = 0; k < 2; ++k) dst[n][k] = *(const LAS h16x8*)(lds + PG8_SB(b, h) + boff + n * 2048 + k * 1024); } while (0)
; #define PG8_MMA(ai, bj, At, Bt_) do { __builtin_amdgcn_s_setprio(1); _Pragma("unroll") for (int m = 0; m < 4; ++m) _Pragma("unroll") for (int n = 0; n < 2; ++n) _Pragma("unroll") for (int k = 0; k < 2; ++k) \
;         acc[ai][bj][m][n] = __builtin_amdgcn_mfma_f32_16x16x32_f16(Bt_[n][k], At[m][k], acc[ai][bj][m][n], 0, 0, 0); __builtin_amdgcn_s_setprio(0); } while (0)
; #define PG8_WAIT_V(n) asm volatile("s_waitcnt vmcnt(" #n ")" ::: "memory")
; template <class Epi, class AMap>
; __device__ __forceinline__ void gemm_phase(LAS unsigned char* lds, const AMap am, const int lda, const h16* Bt, const int ldb, const int M, const int N, const int K, const Epi& E) {
;     ...
;         for (int t = 0; t < nt; t += 2) {
;             const bool last = (t == nt - 2);
;             const char* a1 = cA + (size_t)(t + 1) * kstep;
;             const char* a2 = last ? nA : cA + (size_t)(t + 2) * kstep; const char* b2 = last ? nB : cB + (size_t)(t + 2) * kstep;
;             const char* a3 = a2 + kstep; const char* b3 = b2 + kstep;
;             PG8_LDB(B0, 0, 0); PG8_SCHED; PG8_LDA(At, 0, 0); PG8_STAGE(PG8_SA(1, 1), a1 + hstepA, voffA);
;             PG8_WAIT_L(8); PG8_BAR; PG8_WAIT_L(0); PG8_MMA(0, 0, At, B0); PG8_BAR; PG8_SCHED;
;             PG8_LDB(B1, 0, 1); PG8_STAGE(PG8_SB(0, 0), b2, voffB);
;             PG8_BAR; PG8_WAIT_L(0); PG8_MMA(0, 1, At, B1); PG8_BAR;
;             PG8_LDA(At, 0, 1); PG8_STAGE(PG8_SA(0, 0), a2, voffA);
;             PG8_BAR; PG8_WAIT_L(0); PG8_MMA(1, 0, At, B0); PG8_BAR; PG8_SCHED;
;             PG8_STAGE(PG8_SB(0, 1), b2 + hstepB, voffB);
;             PG8_WAIT_V(6); PG8_BAR; PG8_MMA(1, 1, At, B1); PG8_BAR;
.LBB0_61:
	s_add_u32 s26, s22, 0x100
	s_addc_u32 s27, s23, 0
	s_add_i32 s51, 0, 0x10000
	v_add_u32_e32 v144, s51, v147
	ds_read_b128 v[140:143], v144
	ds_read_b128 v[150:153], v144 offset:1024
	ds_read_b128 v[154:157], v144 offset:2048
	ds_read_b128 v[158:161], v144 offset:3072
	s_cmpk_eq_i32 s29, 0x52
	s_cselect_b32 s45, s1, s27
	s_cselect_b32 s44, s0, s26
	s_cselect_b32 s43, s41, s21
	s_cselect_b32 s42, s40, s20
	v_lshl_add_u64 v[144:145], s[22:23], 0, v[136:137]
	s_add_i32 m0, s63, 0xc000
	ds_read_b128 v[162:165], v149
	ds_read_b128 v[166:169], v149 offset:1024
	ds_read_b128 v[170:173], v149 offset:2048
	ds_read_b128 v[174:177], v149 offset:3072
	ds_read_b128 v[178:181], v149 offset:4096
	ds_read_b128 v[182:185], v149 offset:5120
	ds_read_b128 v[186:189], v149 offset:6144
	ds_read_b128 v[190:193], v149 offset:7168
	global_load_lds_dwordx4 v[144:145], off
	v_lshl_add_u64 v[144:145], s[22:23], 0, v[138:139]
	s_add_i32 m0, s63, 0xe000
	s_nop 0
	global_load_lds_dwordx4 v[144:145], off
	s_waitcnt lgkmcnt(11)
	s_add_i32 s60, 0, 0x14000
	v_add_u32_e32 v144, s60, v147
	s_add_i32 s22, s51, s48
	ds_read_b128 v[194:197], v144
	ds_read_b128 v[198:201], v144 offset:1024
	ds_read_b128 v[202:205], v144 offset:2048
	ds_read_b128 v[220:223], v144 offset:3072
	s_waitcnt vmcnt(8) lgkmcnt(0)
	s_barrier
	v_mfma_f32_16x16x32_f16 v[126:129], v[140:143], v[162:165], v[126:129]
	v_mfma_f32_16x16x32_f16 v[122:125], v[154:157], v[162:165], v[122:125]
	v_mfma_f32_16x16x32_f16 v[110:113], v[140:143], v[170:173], v[110:113]
	v_mfma_f32_16x16x32_f16 v[106:109], v[154:157], v[170:173], v[106:109]
	v_mfma_f32_16x16x32_f16 v[94:97], v[140:143], v[178:181], v[94:97]
	v_mfma_f32_16x16x32_f16 v[90:93], v[154:157], v[178:181], v[90:93]
	v_mfma_f32_16x16x32_f16 v[78:81], v[140:143], v[186:189], v[78:81]
	v_mfma_f32_16x16x32_f16 v[74:77], v[154:157], v[186:189], v[74:77]
	v_mfma_f32_16x16x32_f16 v[126:129], v[150:153], v[166:169], v[126:129]
	v_mfma_f32_16x16x32_f16 v[122:125], v[158:161], v[166:169], v[122:125]
	v_mfma_f32_16x16x32_f16 v[110:113], v[150:153], v[174:177], v[110:113]
	v_mfma_f32_16x16x32_f16 v[106:109], v[158:161], v[174:177], v[106:109]
	v_mfma_f32_16x16x32_f16 v[94:97], v[150:153], v[182:185], v[94:97]
	v_mfma_f32_16x16x32_f16 v[90:93], v[158:161], v[182:185], v[90:93]
	v_mfma_f32_16x16x32_f16 v[78:81], v[150:153], v[190:193], v[78:81]
	v_mfma_f32_16x16x32_f16 v[74:77], v[158:161], v[190:193], v[74:77]
	v_mfma_f32_16x16x32_f16 v[118:121], v[194:197], v[162:165], v[118:121]
	v_mfma_f32_16x16x32_f16 v[114:117], v[202:205], v[162:165], v[114:117]
	v_mfma_f32_16x16x32_f16 v[102:105], v[194:197], v[170:173], v[102:105]
	v_mfma_f32_16x16x32_f16 v[98:101], v[202:205], v[170:173], v[98:101]
	v_mfma_f32_16x16x32_f16 v[86:89], v[194:197], v[178:181], v[86:89]
	v_mfma_f32_16x16x32_f16 v[82:85], v[202:205], v[178:181], v[82:85]
	v_mfma_f32_16x16x32_f16 v[70:73], v[194:197], v[186:189], v[70:73]
	v_mfma_f32_16x16x32_f16 v[66:69], v[202:205], v[186:189], v[66:69]
	v_mfma_f32_16x16x32_f16 v[118:121], v[198:201], v[166:169], v[118:121]
	v_mfma_f32_16x16x32_f16 v[114:117], v[220:223], v[166:169], v[114:117]
	v_mfma_f32_16x16x32_f16 v[102:105], v[198:201], v[174:177], v[102:105]
	v_mfma_f32_16x16x32_f16 v[98:101], v[220:223], v[174:177], v[98:101]
	v_mfma_f32_16x16x32_f16 v[86:89], v[198:201], v[182:185], v[86:89]
	v_mfma_f32_16x16x32_f16 v[82:85], v[220:223], v[182:185], v[82:85]
	v_mfma_f32_16x16x32_f16 v[70:73], v[198:201], v[190:193], v[70:73]
	v_mfma_f32_16x16x32_f16 v[66:69], v[220:223], v[190:193], v[66:69]
	s_barrier
	v_lshl_add_u64 v[144:145], s[42:43], 0, v[0:1]
	s_mov_b32 m0, s22
	v_lshl_add_u64 v[206:207], s[42:43], 0, v[134:135]
	global_load_lds_dwordx4 v[144:145], off
	s_add_i32 m0, s22, 0x2000
	s_nop 0
	global_load_lds_dwordx4 v[206:207], off
	s_mov_b32 m0, s63
	v_lshl_add_u64 v[212:213], s[44:45], 0, v[130:131]
	ds_read_b128 v[162:165], v149 offset:16384
	ds_read_b128 v[166:169], v149 offset:17408
	ds_read_b128 v[170:173], v149 offset:18432
	ds_read_b128 v[174:177], v149 offset:19456
	ds_read_b128 v[178:181], v149 offset:20480
	ds_read_b128 v[182:185], v149 offset:21504
	ds_read_b128 v[186:189], v149 offset:22528
	ds_read_b128 v[190:193], v149 offset:23552
	global_load_lds_dwordx4 v[212:213], off
	v_lshl_add_u64 v[214:215], s[44:45], 0, v[132:133]
	s_mov_b32 m0, s64
	s_nop 0
	global_load_lds_dwordx4 v[214:215], off
	s_add_u32 s22, s42, 0x158000
	s_addc_u32 s23, s43, 0
	s_add_i32 s51, s60, s48
	v_lshl_add_u64 v[232:233], s[22:23], 0, v[0:1]
	s_mov_b32 m0, s51
	s_nop 0
	global_load_lds_dwordx4 v[232:233], off
	v_lshl_add_u64 v[232:233], s[22:23], 0, v[134:135]
	s_add_i32 m0, s51, 0x2000
	s_nop 0
	global_load_lds_dwordx4 v[232:233], off
	s_waitcnt vmcnt(8) lgkmcnt(0)
	s_barrier
; #define PG8_STAGE(bufoff, gbase, voff) do { _Pragma("unroll") for (int _i = 0; _i < 2; ++_i) \
;         __builtin_amdgcn_global_load_lds((const unsigned*)((const char*)(gbase) + (voff)[_i]), (LAS unsigned*)(lds + (bufoff) + ldsw + _i * 8192), 16, 0, 0); } while (0)
; #define PG8_LDA(dst, b, h) do { _Pragma("unroll") for (int m = 0; m < 4; ++m) _Pragma("unroll") for (int k = 0; k < 2; ++k) dst[m][k] = *(const LAS h16x8*)(lds + PG8_SA(b, h) + aoff + m * 2048 + k * 1024); } while (0)
; #define PG8_LDB(dst, b, h) do { _Pragma("unroll") for (int n = 0; n < 2; ++n) _Pragma("unroll") for (int k = 0; k < 2; ++k) dst[n][k] = *(const LAS h16x8*)(lds + PG8_SB(b, h) + boff + n * 2048 + k * 1024); } while (0)
; #define PG8_MMA(ai, bj, At, Bt_) do { __builtin_amdgcn_s_setprio(1); _Pragma("unroll") for (int m = 0; m < 4; ++m) _Pragma("unroll") for (int n = 0; n < 2; ++n) _Pragma("unroll") for (int k = 0; k < 2; ++k) \
;         acc[ai][bj][m][n] = __builtin_amdgcn_mfma_f32_16x16x32_f16(Bt_[n][k], At[m][k], acc[ai][bj][m][n], 0, 0, 0); __builtin_amdgcn_s_setprio(0); } while (0)
; #define PG8_WAIT_V(n) asm volatile("s_waitcnt vmcnt(" #n ")" ::: "memory")
; #define PG8_WAIT_L(n) asm volatile("s_waitcnt lgkmcnt(" #n ")" ::: "memory")
; #define PG8_BAR __builtin_amdgcn_s_barrier()
; #define PG8_SCHED __builtin_amdgcn_sched_barrier(0)
; template <class Epi, class AMap>
; __device__ __forceinline__ void gemm_phase(LAS unsigned char* lds, const AMap am, const int lda, const h16* Bt, const int ldb, const int M, const int N, const int K, const Epi& E) {
;     ...
;             PG8_WAIT_V(6); PG8_BAR; PG8_MMA(1, 1, At, B1); PG8_BAR;
;             PG8_LDB(B0, 1, 0); PG8_SCHED; PG8_LDA(At, 1, 0); PG8_STAGE(PG8_SA(0, 1), a2 + hstepA, voffA);
;             PG8_WAIT_L(8); PG8_BAR; PG8_WAIT_L(0); PG8_MMA(0, 0, At, B0); PG8_BAR; PG8_SCHED;
;             PG8_LDB(B1, 1, 1); PG8_STAGE(PG8_SB(1, 0), b3, voffB);
;             PG8_BAR; PG8_WAIT_L(0); PG8_MMA(0, 1, At, B1); PG8_BAR;
	v_mfma_f32_16x16x32_f16 v[62:65], v[140:143], v[162:165], v[62:65]
	v_mfma_f32_16x16x32_f16 v[58:61], v[154:157], v[162:165], v[58:61]
	v_mfma_f32_16x16x32_f16 v[46:49], v[140:143], v[170:173], v[46:49]
	v_mfma_f32_16x16x32_f16 v[42:45], v[154:157], v[170:173], v[42:45]
	v_mfma_f32_16x16x32_f16 v[30:33], v[140:143], v[178:181], v[30:33]
	v_mfma_f32_16x16x32_f16 v[26:29], v[154:157], v[178:181], v[26:29]
	v_mfma_f32_16x16x32_f16 v[14:17], v[140:143], v[186:189], v[14:17]
	v_mfma_f32_16x16x32_f16 v[10:13], v[154:157], v[186:189], v[10:13]
	v_mfma_f32_16x16x32_f16 v[62:65], v[150:153], v[166:169], v[62:65]
	v_mfma_f32_16x16x32_f16 v[58:61], v[158:161], v[166:169], v[58:61]
	v_mfma_f32_16x16x32_f16 v[46:49], v[150:153], v[174:177], v[46:49]
	v_mfma_f32_16x16x32_f16 v[42:45], v[158:161], v[174:177], v[42:45]
	v_mfma_f32_16x16x32_f16 v[30:33], v[150:153], v[182:185], v[30:33]
	v_mfma_f32_16x16x32_f16 v[26:29], v[158:161], v[182:185], v[26:29]
	v_mfma_f32_16x16x32_f16 v[14:17], v[150:153], v[190:193], v[14:17]
	v_mfma_f32_16x16x32_f16 v[10:13], v[158:161], v[190:193], v[10:13]
	v_mfma_f32_16x16x32_f16 v[54:57], v[194:197], v[162:165], v[54:57]
	v_mfma_f32_16x16x32_f16 v[50:53], v[202:205], v[162:165], v[50:53]
	v_mfma_f32_16x16x32_f16 v[38:41], v[194:197], v[170:173], v[38:41]
	v_mfma_f32_16x16x32_f16 v[34:37], v[202:205], v[170:173], v[34:37]
	v_mfma_f32_16x16x32_f16 v[22:25], v[194:197], v[178:181], v[22:25]
	v_mfma_f32_16x16x32_f16 v[18:21], v[202:205], v[178:181], v[18:21]
	v_mfma_f32_16x16x32_f16 v[6:9], v[194:197], v[186:189], v[6:9]
	v_mfma_f32_16x16x32_f16 v[2:5], v[202:205], v[186:189], v[2:5]
	v_mfma_f32_16x16x32_f16 v[54:57], v[198:201], v[166:169], v[54:57]
	v_mfma_f32_16x16x32_f16 v[50:53], v[220:223], v[166:169], v[50:53]
	v_mfma_f32_16x16x32_f16 v[38:41], v[198:201], v[174:177], v[38:41]
	v_mfma_f32_16x16x32_f16 v[34:37], v[220:223], v[174:177], v[34:37]
	v_mfma_f32_16x16x32_f16 v[22:25], v[198:201], v[182:185], v[22:25]
	v_mfma_f32_16x16x32_f16 v[18:21], v[220:223], v[182:185], v[18:21]
	v_mfma_f32_16x16x32_f16 v[6:9], v[198:201], v[190:193], v[6:9]
	v_mfma_f32_16x16x32_f16 v[2:5], v[220:223], v[190:193], v[2:5]
	s_barrier
	s_add_i32 s51, 0, 0x18000
	v_add_u32_e32 v234, s51, v147
	ds_read_b128 v[140:143], v234
	ds_read_b128 v[150:153], v234 offset:1024
	ds_read_b128 v[154:157], v234 offset:2048
	ds_read_b128 v[158:161], v234 offset:3072
	s_add_u32 s22, s44, 0x158000
	s_addc_u32 s23, s45, 0
	s_mov_b32 m0, s65
	v_lshl_add_u64 v[232:233], s[22:23], 0, v[130:131]
	ds_read_b128 v[162:165], v149 offset:32768
	ds_read_b128 v[166:169], v149 offset:33792
	ds_read_b128 v[170:173], v149 offset:34816
	ds_read_b128 v[174:177], v149 offset:35840
	ds_read_b128 v[178:181], v149 offset:36864
	ds_read_b128 v[182:185], v149 offset:37888
	ds_read_b128 v[186:189], v149 offset:38912
	ds_read_b128 v[190:193], v149 offset:39936
	global_load_lds_dwordx4 v[232:233], off
	v_lshl_add_u64 v[232:233], s[22:23], 0, v[132:133]
	s_mov_b32 m0, s68
	s_nop 0
	global_load_lds_dwordx4 v[232:233], off
	s_waitcnt lgkmcnt(11)
	s_add_i32 s44, 0, 0x1c000
	s_add_i32 s22, s51, s48
	v_add_u32_e32 v216, s44, v147
	v_lshl_add_u64 v[144:145], v[144:145], 0, s[92:93]
	s_mov_b32 m0, s22
	ds_read_b128 v[194:197], v216
	ds_read_b128 v[198:201], v216 offset:1024
	ds_read_b128 v[202:205], v216 offset:2048
	ds_read_b128 v[220:223], v216 offset:3072
	s_waitcnt vmcnt(8) lgkmcnt(0)
	s_barrier
	v_mfma_f32_16x16x32_f16 v[126:129], v[140:143], v[162:165], v[126:129]
	v_mfma_f32_16x16x32_f16 v[122:125], v[154:157], v[162:165], v[122:125]
	v_mfma_f32_16x16x32_f16 v[110:113], v[140:143], v[170:173], v[110:113]
	v_mfma_f32_16x16x32_f16 v[106:109], v[154:157], v[170:173], v[106:109]
	v_mfma_f32_16x16x32_f16 v[94:97], v[140:143], v[178:181], v[94:97]
	v_mfma_f32_16x16x32_f16 v[90:93], v[154:157], v[178:181], v[90:93]
	v_mfma_f32_16x16x32_f16 v[78:81], v[140:143], v[186:189], v[78:81]
	v_mfma_f32_16x16x32_f16 v[74:77], v[154:157], v[186:189], v[74:77]
	v_mfma_f32_16x16x32_f16 v[126:129], v[150:153], v[166:169], v[126:129]
	v_mfma_f32_16x16x32_f16 v[122:125], v[158:161], v[166:169], v[122:125]
	v_mfma_f32_16x16x32_f16 v[110:113], v[150:153], v[174:177], v[110:113]
	v_mfma_f32_16x16x32_f16 v[106:109], v[158:161], v[174:177], v[106:109]
	v_mfma_f32_16x16x32_f16 v[94:97], v[150:153], v[182:185], v[94:97]
	v_mfma_f32_16x16x32_f16 v[90:93], v[158:161], v[182:185], v[90:93]
	v_mfma_f32_16x16x32_f16 v[78:81], v[150:153], v[190:193], v[78:81]
	v_mfma_f32_16x16x32_f16 v[74:77], v[158:161], v[190:193], v[74:77]
	v_mfma_f32_16x16x32_f16 v[118:121], v[194:197], v[162:165], v[118:121]
	v_mfma_f32_16x16x32_f16 v[114:117], v[202:205], v[162:165], v[114:117]
	v_mfma_f32_16x16x32_f16 v[102:105], v[194:197], v[170:173], v[102:105]
	v_mfma_f32_16x16x32_f16 v[98:101], v[202:205], v[170:173], v[98:101]
	v_mfma_f32_16x16x32_f16 v[86:89], v[194:197], v[178:181], v[86:89]
	v_mfma_f32_16x16x32_f16 v[82:85], v[202:205], v[178:181], v[82:85]
	v_mfma_f32_16x16x32_f16 v[70:73], v[194:197], v[186:189], v[70:73]
	v_mfma_f32_16x16x32_f16 v[66:69], v[202:205], v[186:189], v[66:69]
	v_mfma_f32_16x16x32_f16 v[118:121], v[198:201], v[166:169], v[118:121]
	v_mfma_f32_16x16x32_f16 v[114:117], v[220:223], v[166:169], v[114:117]
	v_mfma_f32_16x16x32_f16 v[102:105], v[198:201], v[174:177], v[102:105]
	v_mfma_f32_16x16x32_f16 v[98:101], v[220:223], v[174:177], v[98:101]
	v_mfma_f32_16x16x32_f16 v[86:89], v[198:201], v[182:185], v[86:89]
	v_mfma_f32_16x16x32_f16 v[82:85], v[220:223], v[182:185], v[82:85]
	v_mfma_f32_16x16x32_f16 v[70:73], v[198:201], v[190:193], v[70:73]
	v_mfma_f32_16x16x32_f16 v[66:69], v[220:223], v[190:193], v[66:69]
	s_barrier
; #define PG8_STAGE(bufoff, gbase, voff) do { _Pragma("unroll") for (int _i = 0; _i < 2; ++_i) \
;         __builtin_amdgcn_global_load_lds((const unsigned*)((const char*)(gbase) + (voff)[_i]), (LAS unsigned*)(lds + (bufoff) + ldsw + _i * 8192), 16, 0, 0); } while (0)
; #define PG8_LDA(dst, b, h) do { _Pragma("unroll") for (int m = 0; m < 4; ++m) _Pragma("unroll") for (int k = 0; k < 2; ++k) dst[m][k] = *(const LAS h16x8*)(lds + PG8_SA(b, h) + aoff + m * 2048 + k * 1024); } while (0)
; #define PG8_MMA(ai, bj, At, Bt_) do { __builtin_amdgcn_s_setprio(1); _Pragma("unroll") for (int m = 0; m < 4; ++m) _Pragma("unroll") for (int n = 0; n < 2; ++n) _Pragma("unroll") for (int k = 0; k < 2; ++k) \
;         acc[ai][bj][m][n] = __builtin_amdgcn_mfma_f32_16x16x32_f16(Bt_[n][k], At[m][k], acc[ai][bj][m][n], 0, 0, 0); __builtin_amdgcn_s_setprio(0); } while (0)
; #define PG8_WAIT_V(n) asm volatile("s_waitcnt vmcnt(" #n ")" ::: "memory")
; #define PG8_WAIT_L(n) asm volatile("s_waitcnt lgkmcnt(" #n ")" ::: "memory")
; #define PG8_BAR __builtin_amdgcn_s_barrier()
; #define PG8_SCHED __builtin_amdgcn_sched_barrier(0)
; template <class Epi, class AMap>
; __device__ __forceinline__ void gemm_phase(LAS unsigned char* lds, const AMap am, const int lda, const h16* Bt, const int ldb, const int M, const int N, const int K, const Epi& E) {
;     ...
;             PG8_LDA(At, 1, 1); PG8_STAGE(PG8_SA(1, 0), a3, voffA);
;             PG8_BAR; PG8_WAIT_L(0); PG8_MMA(1, 0, At, B0); PG8_BAR; PG8_SCHED;
;             PG8_STAGE(PG8_SB(1, 1), b3 + hstepB, voffB);
;             PG8_WAIT_V(6); PG8_BAR; PG8_MMA(1, 1, At, B1); PG8_BAR;
;         }
;     __device__ __forceinline__ void operator()(const f32x4 (&acc)[2][2][4][2], const Unit& u, int wr, int wc, int fr, int fq) const {
;     ...
;             for (int m = 0; m < 4; ++m) { const size_t off = (size_t)(row0 + ai * 128 + m * 16) * DM + colt;
; #pragma unroll
;                 for (int bj = 0; bj < 2; ++bj) {
;                     const h16x8 x = *(const h16x8*)(X + off + bj * 128);
	global_load_lds_dwordx4 v[144:145], off
	v_lshl_add_u64 v[144:145], v[206:207], 0, s[92:93]
	s_add_i32 m0, s22, 0x2000
	s_nop 0
	global_load_lds_dwordx4 v[144:145], off
	s_mov_b32 m0, s69
	v_lshl_add_u64 v[144:145], v[212:213], 0, s[92:93]
	ds_read_b128 v[162:165], v149 offset:49152
	ds_read_b128 v[166:169], v149 offset:50176
	ds_read_b128 v[170:173], v149 offset:51200
	ds_read_b128 v[174:177], v149 offset:52224
	ds_read_b128 v[178:181], v149 offset:53248
	ds_read_b128 v[182:185], v149 offset:54272
	ds_read_b128 v[186:189], v149 offset:55296
	ds_read_b128 v[190:193], v149 offset:56320
	global_load_lds_dwordx4 v[144:145], off
	v_lshl_add_u64 v[144:145], v[214:215], 0, s[92:93]
	s_mov_b32 m0, s70
	s_nop 0
	global_load_lds_dwordx4 v[144:145], off
	s_add_u32 s22, s42, 0x158080
	s_addc_u32 s23, s43, 0
	s_add_i32 s42, s44, s48
	v_lshl_add_u64 v[232:233], s[22:23], 0, v[0:1]
	s_mov_b32 m0, s42
	s_nop 0
	global_load_lds_dwordx4 v[232:233], off
	v_lshl_add_u64 v[232:233], s[22:23], 0, v[134:135]
	s_add_i32 m0, s42, 0x2000
	s_nop 0
	global_load_lds_dwordx4 v[232:233], off
	s_add_i32 s29, s29, 2
	s_add_u32 s20, s20, 0x100
	s_addc_u32 s21, s21, 0
	s_cmpk_gt_u32 s29, 0x53
	s_mov_b64 s[22:23], s[26:27]
	s_waitcnt vmcnt(8) lgkmcnt(0)
	s_barrier
	v_mfma_f32_16x16x32_f16 v[62:65], v[140:143], v[162:165], v[62:65]
	v_mfma_f32_16x16x32_f16 v[58:61], v[154:157], v[162:165], v[58:61]
	v_mfma_f32_16x16x32_f16 v[46:49], v[140:143], v[170:173], v[46:49]
	v_mfma_f32_16x16x32_f16 v[42:45], v[154:157], v[170:173], v[42:45]
	v_mfma_f32_16x16x32_f16 v[30:33], v[140:143], v[178:181], v[30:33]
	v_mfma_f32_16x16x32_f16 v[26:29], v[154:157], v[178:181], v[26:29]
	v_mfma_f32_16x16x32_f16 v[14:17], v[140:143], v[186:189], v[14:17]
	v_mfma_f32_16x16x32_f16 v[10:13], v[154:157], v[186:189], v[10:13]
	v_mfma_f32_16x16x32_f16 v[62:65], v[150:153], v[166:169], v[62:65]
	v_mfma_f32_16x16x32_f16 v[58:61], v[158:161], v[166:169], v[58:61]
	v_mfma_f32_16x16x32_f16 v[46:49], v[150:153], v[174:177], v[46:49]
	v_mfma_f32_16x16x32_f16 v[42:45], v[158:161], v[174:177], v[42:45]
	v_mfma_f32_16x16x32_f16 v[30:33], v[150:153], v[182:185], v[30:33]
	v_mfma_f32_16x16x32_f16 v[26:29], v[158:161], v[182:185], v[26:29]
	v_mfma_f32_16x16x32_f16 v[14:17], v[150:153], v[190:193], v[14:17]
	v_mfma_f32_16x16x32_f16 v[10:13], v[158:161], v[190:193], v[10:13]
	v_mfma_f32_16x16x32_f16 v[54:57], v[194:197], v[162:165], v[54:57]
	v_mfma_f32_16x16x32_f16 v[50:53], v[202:205], v[162:165], v[50:53]
	v_mfma_f32_16x16x32_f16 v[38:41], v[194:197], v[170:173], v[38:41]
	v_mfma_f32_16x16x32_f16 v[34:37], v[202:205], v[170:173], v[34:37]
	v_mfma_f32_16x16x32_f16 v[22:25], v[194:197], v[178:181], v[22:25]
	v_mfma_f32_16x16x32_f16 v[18:21], v[202:205], v[178:181], v[18:21]
	v_mfma_f32_16x16x32_f16 v[6:9], v[194:197], v[186:189], v[6:9]
	v_mfma_f32_16x16x32_f16 v[2:5], v[202:205], v[186:189], v[2:5]
	v_mfma_f32_16x16x32_f16 v[54:57], v[198:201], v[166:169], v[54:57]
	v_mfma_f32_16x16x32_f16 v[50:53], v[220:223], v[166:169], v[50:53]
	v_mfma_f32_16x16x32_f16 v[38:41], v[198:201], v[174:177], v[38:41]
	v_mfma_f32_16x16x32_f16 v[34:37], v[220:223], v[174:177], v[34:37]
	v_mfma_f32_16x16x32_f16 v[22:25], v[198:201], v[182:185], v[22:25]
	v_mfma_f32_16x16x32_f16 v[18:21], v[220:223], v[182:185], v[18:21]
	v_mfma_f32_16x16x32_f16 v[6:9], v[198:201], v[190:193], v[6:9]
	v_mfma_f32_16x16x32_f16 v[2:5], v[220:223], v[190:193], v[2:5]
	s_barrier
	s_cbranch_scc0 .LBB0_61
	v_lshl_add_u32 v144, s35, 8, v146
	v_lshl_or_b32 v142, s50, 8, v148
	v_ashrrev_i32_e32 v145, 31, v144
	v_ashrrev_i32_e32 v143, 31, v142
	v_lshlrev_b64 v[140:141], 11, v[144:145]
	v_lshl_add_u64 v[140:141], v[140:141], 0, v[142:143]
	v_lshlrev_b64 v[140:141], 1, v[140:141]
	v_lshl_add_u64 v[154:155], s[94:95], 0, v[140:141]
	s_mov_b32 s101, 0
	global_load_dwordx4 v[158:161], v[154:155], off
	global_load_dwordx4 v[162:165], v[154:155], off offset:256
	s_mov_b32 s100, 0x10000
	v_lshl_add_u64 v[232:233], v[154:155], 0, s[100:101]
	global_load_dwordx4 v[166:169], v[232:233], off
	global_load_dwordx4 v[170:173], v[232:233], off offset:256
	s_mov_b32 s100, 0x20000
	v_lshl_add_u64 v[232:233], v[154:155], 0, s[100:101]
	global_load_dwordx4 v[174:177], v[232:233], off
	global_load_dwordx4 v[178:181], v[232:233], off offset:256
	s_mov_b32 s100, 0x30000
	v_lshl_add_u64 v[232:233], v[154:155], 0, s[100:101]
	global_load_dwordx4 v[182:185], v[232:233], off
	global_load_dwordx4 v[186:189], v[232:233], off offset:256
	s_mov_b32 s100, 0x80000
	v_lshl_add_u64 v[232:233], v[154:155], 0, s[100:101]
	global_load_dwordx4 v[190:193], v[232:233], off
	global_load_dwordx4 v[194:197], v[232:233], off offset:256
	s_mov_b32 s100, 0x90000
	v_lshl_add_u64 v[232:233], v[154:155], 0, s[100:101]
	global_load_dwordx4 v[198:201], v[232:233], off
	global_load_dwordx4 v[202:205], v[232:233], off offset:256
	s_mov_b32 s100, 0xa0000
	v_lshl_add_u64 v[232:233], v[154:155], 0, s[100:101]
	global_load_dwordx4 v[212:215], v[232:233], off
	global_load_dwordx4 v[220:223], v[232:233], off offset:256
	s_mov_b32 s100, 0xb0000
	v_lshl_add_u64 v[232:233], v[154:155], 0, s[100:101]
	global_load_dwordx4 v[224:227], v[232:233], off
	global_load_dwordx4 v[228:231], v[232:233], off offset:256
	s_mov_b64 s[4:5], 0xb0000
	s_and_b64 vcc, exec, s[38:39]
	s_mov_b32 s50, s72
	s_mov_b64 s[26:27], s[40:41]
	s_mov_b64 s[22:23], s[0:1]
	s_cmpk_gt_u32 s46, 0xff
	s_cbranch_scc1 .Lgx0
	s_barrier
;     __device__ __forceinline__ void operator()(const f32x4 (&acc)[2][2][4][2], const Unit& u, int wr, int wc, int fr, int fq) const {
;     ...
;             for (int m = 0; m < 4; ++m) { const size_t off = (size_t)(row0 + ai * 128 + m * 16) * DM + colt;
; #pragma unroll
;                 for (int bj = 0; bj < 2; ++bj) {
;                     const h16x8 x = *(const h16x8*)(X + off + bj * 128);
;                     f32x4 o0, o1;
; #pragma unroll
;                     for (int e = 0; e < 4; ++e) { o0[e] = (float)x[e] * ALPHA + acc[ai][bj][m][0][e]; o1[e] = (float)x[4 + e] * ALPHA + acc[ai][bj][m][1][e]; }
;                     *(u32x4*)(PRE + off + bj * 128) = pack8(o0, o1); } }
.Lgx0:
	s_waitcnt vmcnt(15)
	v_mov_b64_e32 v[150:151], v[158:159]
	v_mov_b64_e32 v[152:153], v[160:161]
	v_cvt_f32_f16_e32 v156, v150
	v_cvt_f32_f16_sdwa v157, v150 dst_sel:DWORD dst_unused:UNUSED_PAD src0_sel:WORD_1
	v_cvt_f32_f16_e32 v150, v151
	v_cvt_f32_f16_sdwa v151, v151 dst_sel:DWORD dst_unused:UNUSED_PAD src0_sel:WORD_1
	v_pk_fma_f32 v[126:127], v[156:157], s[34:35], v[126:127] op_sel_hi:[1,0,1]
	s_nop 0
	v_cvt_pk_f16_f32 v126, v126, v127
	v_pk_fma_f32 v[128:129], v[150:151], s[34:35], v[128:129] op_sel_hi:[1,0,1]
	v_lshl_add_u64 v[150:151], s[8:9], 0, v[140:141]
	v_cvt_pk_f16_f32 v127, v128, v129
	v_cvt_f32_f16_e32 v128, v152
	v_cvt_f32_f16_sdwa v129, v152 dst_sel:DWORD dst_unused:UNUSED_PAD src0_sel:WORD_1
	v_pk_fma_f32 v[122:123], v[128:129], s[34:35], v[122:123] op_sel_hi:[1,0,1]
	s_nop 0
	v_cvt_pk_f16_f32 v128, v122, v123
	v_cvt_f32_f16_e32 v122, v153
	v_cvt_f32_f16_sdwa v123, v153 dst_sel:DWORD dst_unused:UNUSED_PAD src0_sel:WORD_1
	v_pk_fma_f32 v[122:123], v[122:123], s[34:35], v[124:125] op_sel_hi:[1,0,1]
	s_nop 0
	v_cvt_pk_f16_f32 v129, v122, v123
	s_nop 0
	global_store_dwordx4 v[150:151], v[126:129], off
	s_waitcnt vmcnt(15)
	v_mov_b64_e32 v[122:123], v[162:163]
	v_mov_b64_e32 v[124:125], v[164:165]
	s_nop 0
	v_cvt_f32_f16_e32 v126, v122
	v_cvt_f32_f16_sdwa v127, v122 dst_sel:DWORD dst_unused:UNUSED_PAD src0_sel:WORD_1
	v_cvt_f32_f16_e32 v122, v123
	v_cvt_f32_f16_sdwa v123, v123 dst_sel:DWORD dst_unused:UNUSED_PAD src0_sel:WORD_1
	v_pk_fma_f32 v[118:119], v[126:127], s[34:35], v[118:119] op_sel_hi:[1,0,1]
	s_nop 0
	v_cvt_pk_f16_f32 v118, v118, v119
	v_pk_fma_f32 v[120:121], v[122:123], s[34:35], v[120:121] op_sel_hi:[1,0,1]
	s_nop 0
	v_cvt_pk_f16_f32 v119, v120, v121
	v_cvt_f32_f16_e32 v120, v124
	v_cvt_f32_f16_sdwa v121, v124 dst_sel:DWORD dst_unused:UNUSED_PAD src0_sel:WORD_1
	v_pk_fma_f32 v[114:115], v[120:121], s[34:35], v[114:115] op_sel_hi:[1,0,1]
	s_nop 0
	v_cvt_pk_f16_f32 v120, v114, v115
	v_cvt_f32_f16_e32 v114, v125
	v_cvt_f32_f16_sdwa v115, v125 dst_sel:DWORD dst_unused:UNUSED_PAD src0_sel:WORD_1
	v_pk_fma_f32 v[114:115], v[114:115], s[34:35], v[116:117] op_sel_hi:[1,0,1]
	s_nop 0
	v_cvt_pk_f16_f32 v121, v114, v115
	v_or_b32_e32 v114, 16, v144
	v_ashrrev_i32_e32 v115, 31, v114
	v_lshlrev_b64 v[114:115], 11, v[114:115]
	v_lshl_add_u64 v[114:115], v[114:115], 0, v[142:143]
	global_store_dwordx4 v[150:151], v[118:121], off offset:256
	s_nop 1
	v_lshlrev_b64 v[118:119], 1, v[114:115]
	v_lshl_add_u64 v[120:121], s[94:95], 0, v[118:119]
	s_waitcnt vmcnt(15)
	v_mov_b64_e32 v[114:115], v[166:167]
	v_mov_b64_e32 v[116:117], v[168:169]
	v_cvt_f32_f16_e32 v122, v114
	v_cvt_f32_f16_sdwa v123, v114 dst_sel:DWORD dst_unused:UNUSED_PAD src0_sel:WORD_1
	v_cvt_f32_f16_e32 v114, v115
	v_cvt_f32_f16_sdwa v115, v115 dst_sel:DWORD dst_unused:UNUSED_PAD src0_sel:WORD_1
	v_pk_fma_f32 v[110:111], v[122:123], s[34:35], v[110:111] op_sel_hi:[1,0,1]
	s_nop 0
	v_cvt_pk_f16_f32 v110, v110, v111
	v_pk_fma_f32 v[112:113], v[114:115], s[34:35], v[112:113] op_sel_hi:[1,0,1]
	v_lshl_add_u64 v[114:115], s[8:9], 0, v[118:119]
	v_cvt_pk_f16_f32 v111, v112, v113
	v_cvt_f32_f16_e32 v112, v116
	v_cvt_f32_f16_sdwa v113, v116 dst_sel:DWORD dst_unused:UNUSED_PAD src0_sel:WORD_1
	v_pk_fma_f32 v[106:107], v[112:113], s[34:35], v[106:107] op_sel_hi:[1,0,1]
	s_nop 0
	v_cvt_pk_f16_f32 v112, v106, v107
	v_cvt_f32_f16_e32 v106, v117
	v_cvt_f32_f16_sdwa v107, v117 dst_sel:DWORD dst_unused:UNUSED_PAD src0_sel:WORD_1
	v_pk_fma_f32 v[106:107], v[106:107], s[34:35], v[108:109] op_sel_hi:[1,0,1]
	s_nop 0
	v_cvt_pk_f16_f32 v113, v106, v107
	s_nop 0
	global_store_dwordx4 v[114:115], v[110:113], off
	s_waitcnt vmcnt(15)
	v_mov_b64_e32 v[106:107], v[170:171]
	v_mov_b64_e32 v[108:109], v[172:173]
	s_nop 0
	v_cvt_f32_f16_e32 v110, v106
	v_cvt_f32_f16_sdwa v111, v106 dst_sel:DWORD dst_unused:UNUSED_PAD src0_sel:WORD_1
	v_cvt_f32_f16_e32 v106, v107
	v_cvt_f32_f16_sdwa v107, v107 dst_sel:DWORD dst_unused:UNUSED_PAD src0_sel:WORD_1
	v_pk_fma_f32 v[102:103], v[110:111], s[34:35], v[102:103] op_sel_hi:[1,0,1]
	s_nop 0
	v_cvt_pk_f16_f32 v102, v102, v103
	v_pk_fma_f32 v[104:105], v[106:107], s[34:35], v[104:105] op_sel_hi:[1,0,1]
	s_nop 0
	v_cvt_pk_f16_f32 v103, v104, v105
	v_cvt_f32_f16_e32 v104, v108
	v_cvt_f32_f16_sdwa v105, v108 dst_sel:DWORD dst_unused:UNUSED_PAD src0_sel:WORD_1
	v_pk_fma_f32 v[98:99], v[104:105], s[34:35], v[98:99] op_sel_hi:[1,0,1]
	s_nop 0
	v_cvt_pk_f16_f32 v104, v98, v99
	v_cvt_f32_f16_e32 v98, v109
	v_cvt_f32_f16_sdwa v99, v109 dst_sel:DWORD dst_unused:UNUSED_PAD src0_sel:WORD_1
	v_pk_fma_f32 v[98:99], v[98:99], s[34:35], v[100:101] op_sel_hi:[1,0,1]
	s_nop 0
	v_cvt_pk_f16_f32 v105, v98, v99
	v_or_b32_e32 v98, 32, v144
	v_ashrrev_i32_e32 v99, 31, v98
	v_lshlrev_b64 v[98:99], 11, v[98:99]
	v_lshl_add_u64 v[98:99], v[98:99], 0, v[142:143]
	global_store_dwordx4 v[114:115], v[102:105], off offset:256
	s_nop 1
	v_lshlrev_b64 v[102:103], 1, v[98:99]
	v_lshl_add_u64 v[104:105], s[94:95], 0, v[102:103]
	s_waitcnt vmcnt(15)
	v_mov_b64_e32 v[98:99], v[174:175]
	v_mov_b64_e32 v[100:101], v[176:177]
	v_cvt_f32_f16_e32 v106, v98
	v_cvt_f32_f16_sdwa v107, v98 dst_sel:DWORD dst_unused:UNUSED_PAD src0_sel:WORD_1
	v_cvt_f32_f16_e32 v98, v99
	v_cvt_f32_f16_sdwa v99, v99 dst_sel:DWORD dst_unused:UNUSED_PAD src0_sel:WORD_1
	v_pk_fma_f32 v[94:95], v[106:107], s[34:35], v[94:95] op_sel_hi:[1,0,1]
	s_nop 0
	v_cvt_pk_f16_f32 v94, v94, v95
	v_pk_fma_f32 v[96:97], v[98:99], s[34:35], v[96:97] op_sel_hi:[1,0,1]
	v_lshl_add_u64 v[98:99], s[8:9], 0, v[102:103]
	v_cvt_pk_f16_f32 v95, v96, v97
	v_cvt_f32_f16_e32 v96, v100
	v_cvt_f32_f16_sdwa v97, v100 dst_sel:DWORD dst_unused:UNUSED_PAD src0_sel:WORD_1
	v_pk_fma_f32 v[90:91], v[96:97], s[34:35], v[90:91] op_sel_hi:[1,0,1]
	s_nop 0
	v_cvt_pk_f16_f32 v96, v90, v91
	v_cvt_f32_f16_e32 v90, v101
	v_cvt_f32_f16_sdwa v91, v101 dst_sel:DWORD dst_unused:UNUSED_PAD src0_sel:WORD_1
	v_pk_fma_f32 v[90:91], v[90:91], s[34:35], v[92:93] op_sel_hi:[1,0,1]
	s_nop 0
	v_cvt_pk_f16_f32 v97, v90, v91
	s_nop 0
	global_store_dwordx4 v[98:99], v[94:97], off
	s_waitcnt vmcnt(15)
;     __device__ __forceinline__ void operator()(const f32x4 (&acc)[2][2][4][2], const Unit& u, int wr, int wc, int fr, int fq) const {
;     ...
;             for (int m = 0; m < 4; ++m) { const size_t off = (size_t)(row0 + ai * 128 + m * 16) * DM + colt;
; #pragma unroll
;                 for (int bj = 0; bj < 2; ++bj) {
;                     const h16x8 x = *(const h16x8*)(X + off + bj * 128);
;                     f32x4 o0, o1;
; #pragma unroll
;                     for (int e = 0; e < 4; ++e) { o0[e] = (float)x[e] * ALPHA + acc[ai][bj][m][0][e]; o1[e] = (float)x[4 + e] * ALPHA + acc[ai][bj][m][1][e]; }
;                     *(u32x4*)(PRE + off + bj * 128) = pack8(o0, o1); } }
	v_mov_b64_e32 v[90:91], v[178:179]
	v_mov_b64_e32 v[92:93], v[180:181]
	s_nop 0
	v_cvt_f32_f16_e32 v94, v90
	v_cvt_f32_f16_sdwa v95, v90 dst_sel:DWORD dst_unused:UNUSED_PAD src0_sel:WORD_1
	v_cvt_f32_f16_e32 v90, v91
	v_cvt_f32_f16_sdwa v91, v91 dst_sel:DWORD dst_unused:UNUSED_PAD src0_sel:WORD_1
	v_pk_fma_f32 v[86:87], v[94:95], s[34:35], v[86:87] op_sel_hi:[1,0,1]
	s_nop 0
	v_cvt_pk_f16_f32 v86, v86, v87
	v_pk_fma_f32 v[88:89], v[90:91], s[34:35], v[88:89] op_sel_hi:[1,0,1]
	s_nop 0
	v_cvt_pk_f16_f32 v87, v88, v89
	v_cvt_f32_f16_e32 v88, v92
	v_cvt_f32_f16_sdwa v89, v92 dst_sel:DWORD dst_unused:UNUSED_PAD src0_sel:WORD_1
	v_pk_fma_f32 v[82:83], v[88:89], s[34:35], v[82:83] op_sel_hi:[1,0,1]
	s_nop 0
	v_cvt_pk_f16_f32 v88, v82, v83
	v_cvt_f32_f16_e32 v82, v93
	v_cvt_f32_f16_sdwa v83, v93 dst_sel:DWORD dst_unused:UNUSED_PAD src0_sel:WORD_1
	v_pk_fma_f32 v[82:83], v[82:83], s[34:35], v[84:85] op_sel_hi:[1,0,1]
	s_nop 0
	v_cvt_pk_f16_f32 v89, v82, v83
	v_or_b32_e32 v82, 48, v144
	v_ashrrev_i32_e32 v83, 31, v82
	v_lshlrev_b64 v[82:83], 11, v[82:83]
	v_lshl_add_u64 v[82:83], v[82:83], 0, v[142:143]
	global_store_dwordx4 v[98:99], v[86:89], off offset:256
	s_nop 1
	v_lshlrev_b64 v[86:87], 1, v[82:83]
	v_lshl_add_u64 v[88:89], s[94:95], 0, v[86:87]
	s_waitcnt vmcnt(15)
	v_mov_b64_e32 v[82:83], v[182:183]
	v_mov_b64_e32 v[84:85], v[184:185]
	v_cvt_f32_f16_e32 v90, v82
	v_cvt_f32_f16_sdwa v91, v82 dst_sel:DWORD dst_unused:UNUSED_PAD src0_sel:WORD_1
	v_cvt_f32_f16_e32 v82, v83
	v_cvt_f32_f16_sdwa v83, v83 dst_sel:DWORD dst_unused:UNUSED_PAD src0_sel:WORD_1
	v_pk_fma_f32 v[78:79], v[90:91], s[34:35], v[78:79] op_sel_hi:[1,0,1]
	s_nop 0
	v_cvt_pk_f16_f32 v78, v78, v79
	v_pk_fma_f32 v[80:81], v[82:83], s[34:35], v[80:81] op_sel_hi:[1,0,1]
	v_lshl_add_u64 v[82:83], s[8:9], 0, v[86:87]
	v_cvt_pk_f16_f32 v79, v80, v81
	v_cvt_f32_f16_e32 v80, v84
	v_cvt_f32_f16_sdwa v81, v84 dst_sel:DWORD dst_unused:UNUSED_PAD src0_sel:WORD_1
	v_pk_fma_f32 v[74:75], v[80:81], s[34:35], v[74:75] op_sel_hi:[1,0,1]
	s_nop 0
	v_cvt_pk_f16_f32 v80, v74, v75
	v_cvt_f32_f16_e32 v74, v85
	v_cvt_f32_f16_sdwa v75, v85 dst_sel:DWORD dst_unused:UNUSED_PAD src0_sel:WORD_1
	v_pk_fma_f32 v[74:75], v[74:75], s[34:35], v[76:77] op_sel_hi:[1,0,1]
	s_nop 0
	v_cvt_pk_f16_f32 v81, v74, v75
	s_nop 0
	global_store_dwordx4 v[82:83], v[78:81], off
	s_waitcnt vmcnt(15)
	v_mov_b64_e32 v[74:75], v[186:187]
	v_mov_b64_e32 v[76:77], v[188:189]
	s_nop 0
	v_cvt_f32_f16_e32 v78, v74
	v_cvt_f32_f16_sdwa v79, v74 dst_sel:DWORD dst_unused:UNUSED_PAD src0_sel:WORD_1
	v_cvt_f32_f16_e32 v74, v75
	v_cvt_f32_f16_sdwa v75, v75 dst_sel:DWORD dst_unused:UNUSED_PAD src0_sel:WORD_1
	v_pk_fma_f32 v[70:71], v[78:79], s[34:35], v[70:71] op_sel_hi:[1,0,1]
	s_nop 0
	v_cvt_pk_f16_f32 v70, v70, v71
	v_pk_fma_f32 v[72:73], v[74:75], s[34:35], v[72:73] op_sel_hi:[1,0,1]
	s_nop 0
	v_cvt_pk_f16_f32 v71, v72, v73
	v_cvt_f32_f16_e32 v72, v76
	v_cvt_f32_f16_sdwa v73, v76 dst_sel:DWORD dst_unused:UNUSED_PAD src0_sel:WORD_1
	v_pk_fma_f32 v[66:67], v[72:73], s[34:35], v[66:67] op_sel_hi:[1,0,1]
	s_nop 0
	v_cvt_pk_f16_f32 v72, v66, v67
	v_cvt_f32_f16_e32 v66, v77
	v_cvt_f32_f16_sdwa v67, v77 dst_sel:DWORD dst_unused:UNUSED_PAD src0_sel:WORD_1
	v_pk_fma_f32 v[66:67], v[66:67], s[34:35], v[68:69] op_sel_hi:[1,0,1]
	s_nop 0
	v_cvt_pk_f16_f32 v73, v66, v67
	global_store_dwordx4 v[82:83], v[70:73], off offset:256
	s_nop 1
	v_lshl_add_u64 v[70:71], v[140:141], 0, s[16:17]
	v_lshl_add_u64 v[72:73], s[94:95], 0, v[70:71]
	s_waitcnt vmcnt(15)
	v_mov_b64_e32 v[66:67], v[190:191]
	v_mov_b64_e32 v[68:69], v[192:193]
	v_cvt_f32_f16_e32 v74, v66
	v_cvt_f32_f16_sdwa v75, v66 dst_sel:DWORD dst_unused:UNUSED_PAD src0_sel:WORD_1
	v_cvt_f32_f16_e32 v66, v67
	v_cvt_f32_f16_sdwa v67, v67 dst_sel:DWORD dst_unused:UNUSED_PAD src0_sel:WORD_1
	v_pk_fma_f32 v[62:63], v[74:75], s[34:35], v[62:63] op_sel_hi:[1,0,1]
	s_nop 0
	v_cvt_pk_f16_f32 v62, v62, v63
	v_pk_fma_f32 v[64:65], v[66:67], s[34:35], v[64:65] op_sel_hi:[1,0,1]
	v_lshl_add_u64 v[66:67], s[8:9], 0, v[70:71]
	v_cvt_pk_f16_f32 v63, v64, v65
	v_cvt_f32_f16_e32 v64, v68
	v_cvt_f32_f16_sdwa v65, v68 dst_sel:DWORD dst_unused:UNUSED_PAD src0_sel:WORD_1
	v_pk_fma_f32 v[58:59], v[64:65], s[34:35], v[58:59] op_sel_hi:[1,0,1]
	s_nop 0
	v_cvt_pk_f16_f32 v64, v58, v59
	v_cvt_f32_f16_e32 v58, v69
	v_cvt_f32_f16_sdwa v59, v69 dst_sel:DWORD dst_unused:UNUSED_PAD src0_sel:WORD_1
	v_pk_fma_f32 v[58:59], v[58:59], s[34:35], v[60:61] op_sel_hi:[1,0,1]
	s_nop 0
	v_cvt_pk_f16_f32 v65, v58, v59
	s_nop 0
	global_store_dwordx4 v[66:67], v[62:65], off
	s_waitcnt vmcnt(15)
	v_mov_b64_e32 v[58:59], v[194:195]
	v_mov_b64_e32 v[60:61], v[196:197]
	s_nop 0
	v_cvt_f32_f16_e32 v62, v58
	v_cvt_f32_f16_sdwa v63, v58 dst_sel:DWORD dst_unused:UNUSED_PAD src0_sel:WORD_1
	v_cvt_f32_f16_e32 v58, v59
	v_cvt_f32_f16_sdwa v59, v59 dst_sel:DWORD dst_unused:UNUSED_PAD src0_sel:WORD_1
	v_pk_fma_f32 v[54:55], v[62:63], s[34:35], v[54:55] op_sel_hi:[1,0,1]
	s_nop 0
	v_cvt_pk_f16_f32 v54, v54, v55
	v_pk_fma_f32 v[56:57], v[58:59], s[34:35], v[56:57] op_sel_hi:[1,0,1]
	s_nop 0
	v_cvt_pk_f16_f32 v55, v56, v57
	v_cvt_f32_f16_e32 v56, v60
	v_cvt_f32_f16_sdwa v57, v60 dst_sel:DWORD dst_unused:UNUSED_PAD src0_sel:WORD_1
	v_pk_fma_f32 v[50:51], v[56:57], s[34:35], v[50:51] op_sel_hi:[1,0,1]
	s_nop 0
	v_cvt_pk_f16_f32 v56, v50, v51
	v_cvt_f32_f16_e32 v50, v61
	v_cvt_f32_f16_sdwa v51, v61 dst_sel:DWORD dst_unused:UNUSED_PAD src0_sel:WORD_1
	v_pk_fma_f32 v[50:51], v[50:51], s[34:35], v[52:53] op_sel_hi:[1,0,1]
	s_nop 0
	v_cvt_pk_f16_f32 v57, v50, v51
	global_store_dwordx4 v[66:67], v[54:57], off offset:256
	s_nop 1
	v_lshl_add_u64 v[54:55], v[140:141], 0, s[18:19]
	v_lshl_add_u64 v[56:57], s[94:95], 0, v[54:55]
	s_waitcnt vmcnt(15)
; template <class Epi, class AMap>
; __device__ __forceinline__ void gemm_phase(LAS unsigned char* lds, const AMap am, const int lda, const h16* Bt, const int ldb, const int M, const int N, const int K, const Epi& E) {
;     ...
;         if (!has_next) break;
; #pragma unroll
;         for (int a = 0; a < 2; ++a)
; #pragma unroll
;             for (int b = 0; b < 2; ++b)
; #pragma unroll
;                 for (int m = 0; m < 4; ++m)
; #pragma unroll
;                     for (int n = 0; n < 2; ++n) acc[a][b][m][n] = (f32x4){0.f, 0.f, 0.f, 0.f};
;         cur = nxt; cA = nA; cB = nB; ++ui;
;     __device__ __forceinline__ void operator()(const f32x4 (&acc)[2][2][4][2], const Unit& u, int wr, int wc, int fr, int fq) const {
;     ...
;             for (int m = 0; m < 4; ++m) { const size_t off = (size_t)(row0 + ai * 128 + m * 16) * DM + colt;
; #pragma unroll
;                 for (int bj = 0; bj < 2; ++bj) {
;                     const h16x8 x = *(const h16x8*)(X + off + bj * 128);
;                     f32x4 o0, o1;
; #pragma unroll
;                     for (int e = 0; e < 4; ++e) { o0[e] = (float)x[e] * ALPHA + acc[ai][bj][m][0][e]; o1[e] = (float)x[4 + e] * ALPHA + acc[ai][bj][m][1][e]; }
;                     *(u32x4*)(PRE + off + bj * 128) = pack8(o0, o1); } }
	v_mov_b64_e32 v[50:51], v[198:199]
	v_mov_b64_e32 v[52:53], v[200:201]
	v_cvt_f32_f16_e32 v58, v50
	v_cvt_f32_f16_sdwa v59, v50 dst_sel:DWORD dst_unused:UNUSED_PAD src0_sel:WORD_1
	v_cvt_f32_f16_e32 v50, v51
	v_cvt_f32_f16_sdwa v51, v51 dst_sel:DWORD dst_unused:UNUSED_PAD src0_sel:WORD_1
	v_pk_fma_f32 v[46:47], v[58:59], s[34:35], v[46:47] op_sel_hi:[1,0,1]
	s_nop 0
	v_cvt_pk_f16_f32 v46, v46, v47
	v_pk_fma_f32 v[48:49], v[50:51], s[34:35], v[48:49] op_sel_hi:[1,0,1]
	v_lshl_add_u64 v[50:51], s[8:9], 0, v[54:55]
	v_cvt_pk_f16_f32 v47, v48, v49
	v_cvt_f32_f16_e32 v48, v52
	v_cvt_f32_f16_sdwa v49, v52 dst_sel:DWORD dst_unused:UNUSED_PAD src0_sel:WORD_1
	v_pk_fma_f32 v[42:43], v[48:49], s[34:35], v[42:43] op_sel_hi:[1,0,1]
	s_nop 0
	v_cvt_pk_f16_f32 v48, v42, v43
	v_cvt_f32_f16_e32 v42, v53
	v_cvt_f32_f16_sdwa v43, v53 dst_sel:DWORD dst_unused:UNUSED_PAD src0_sel:WORD_1
	v_pk_fma_f32 v[42:43], v[42:43], s[34:35], v[44:45] op_sel_hi:[1,0,1]
	s_nop 0
	v_cvt_pk_f16_f32 v49, v42, v43
	s_nop 0
	global_store_dwordx4 v[50:51], v[46:49], off
	s_waitcnt vmcnt(15)
	v_mov_b64_e32 v[42:43], v[202:203]
	v_mov_b64_e32 v[44:45], v[204:205]
	s_nop 0
	v_cvt_f32_f16_e32 v46, v42
	v_cvt_f32_f16_sdwa v47, v42 dst_sel:DWORD dst_unused:UNUSED_PAD src0_sel:WORD_1
	v_cvt_f32_f16_e32 v42, v43
	v_cvt_f32_f16_sdwa v43, v43 dst_sel:DWORD dst_unused:UNUSED_PAD src0_sel:WORD_1
	v_pk_fma_f32 v[38:39], v[46:47], s[34:35], v[38:39] op_sel_hi:[1,0,1]
	s_nop 0
	v_cvt_pk_f16_f32 v38, v38, v39
	v_pk_fma_f32 v[40:41], v[42:43], s[34:35], v[40:41] op_sel_hi:[1,0,1]
	s_nop 0
	v_cvt_pk_f16_f32 v39, v40, v41
	v_cvt_f32_f16_e32 v40, v44
	v_cvt_f32_f16_sdwa v41, v44 dst_sel:DWORD dst_unused:UNUSED_PAD src0_sel:WORD_1
	v_pk_fma_f32 v[34:35], v[40:41], s[34:35], v[34:35] op_sel_hi:[1,0,1]
	s_nop 0
	v_cvt_pk_f16_f32 v40, v34, v35
	v_cvt_f32_f16_e32 v34, v45
	v_cvt_f32_f16_sdwa v35, v45 dst_sel:DWORD dst_unused:UNUSED_PAD src0_sel:WORD_1
	v_pk_fma_f32 v[34:35], v[34:35], s[34:35], v[36:37] op_sel_hi:[1,0,1]
	s_nop 0
	v_cvt_pk_f16_f32 v41, v34, v35
	global_store_dwordx4 v[50:51], v[38:41], off offset:256
	s_nop 1
	v_lshl_add_u64 v[38:39], v[140:141], 0, s[14:15]
	v_lshl_add_u64 v[40:41], s[94:95], 0, v[38:39]
	s_waitcnt vmcnt(15)
	v_mov_b64_e32 v[34:35], v[212:213]
	v_mov_b64_e32 v[36:37], v[214:215]
	v_cvt_f32_f16_e32 v42, v34
	v_cvt_f32_f16_sdwa v43, v34 dst_sel:DWORD dst_unused:UNUSED_PAD src0_sel:WORD_1
	v_cvt_f32_f16_e32 v34, v35
	v_cvt_f32_f16_sdwa v35, v35 dst_sel:DWORD dst_unused:UNUSED_PAD src0_sel:WORD_1
	v_pk_fma_f32 v[30:31], v[42:43], s[34:35], v[30:31] op_sel_hi:[1,0,1]
	s_nop 0
	v_cvt_pk_f16_f32 v30, v30, v31
	v_pk_fma_f32 v[32:33], v[34:35], s[34:35], v[32:33] op_sel_hi:[1,0,1]
	v_lshl_add_u64 v[34:35], s[8:9], 0, v[38:39]
	v_cvt_pk_f16_f32 v31, v32, v33
	v_cvt_f32_f16_e32 v32, v36
	v_cvt_f32_f16_sdwa v33, v36 dst_sel:DWORD dst_unused:UNUSED_PAD src0_sel:WORD_1
	v_pk_fma_f32 v[26:27], v[32:33], s[34:35], v[26:27] op_sel_hi:[1,0,1]
	s_nop 0
	v_cvt_pk_f16_f32 v32, v26, v27
	v_cvt_f32_f16_e32 v26, v37
	v_cvt_f32_f16_sdwa v27, v37 dst_sel:DWORD dst_unused:UNUSED_PAD src0_sel:WORD_1
	v_pk_fma_f32 v[26:27], v[26:27], s[34:35], v[28:29] op_sel_hi:[1,0,1]
	s_nop 0
	v_cvt_pk_f16_f32 v33, v26, v27
	s_nop 0
	global_store_dwordx4 v[34:35], v[30:33], off
	s_waitcnt vmcnt(15)
	v_mov_b64_e32 v[26:27], v[220:221]
	v_mov_b64_e32 v[28:29], v[222:223]
	s_nop 0
	v_cvt_f32_f16_e32 v30, v26
	v_cvt_f32_f16_sdwa v31, v26 dst_sel:DWORD dst_unused:UNUSED_PAD src0_sel:WORD_1
	v_cvt_f32_f16_e32 v26, v27
	v_cvt_f32_f16_sdwa v27, v27 dst_sel:DWORD dst_unused:UNUSED_PAD src0_sel:WORD_1
	v_pk_fma_f32 v[22:23], v[30:31], s[34:35], v[22:23] op_sel_hi:[1,0,1]
	s_nop 0
	v_cvt_pk_f16_f32 v22, v22, v23
	v_pk_fma_f32 v[24:25], v[26:27], s[34:35], v[24:25] op_sel_hi:[1,0,1]
	s_nop 0
	v_cvt_pk_f16_f32 v23, v24, v25
	v_cvt_f32_f16_e32 v24, v28
	v_cvt_f32_f16_sdwa v25, v28 dst_sel:DWORD dst_unused:UNUSED_PAD src0_sel:WORD_1
	v_pk_fma_f32 v[18:19], v[24:25], s[34:35], v[18:19] op_sel_hi:[1,0,1]
	s_nop 0
	v_cvt_pk_f16_f32 v24, v18, v19
	v_cvt_f32_f16_e32 v18, v29
	v_cvt_f32_f16_sdwa v19, v29 dst_sel:DWORD dst_unused:UNUSED_PAD src0_sel:WORD_1
	v_pk_fma_f32 v[18:19], v[18:19], s[34:35], v[20:21] op_sel_hi:[1,0,1]
	s_nop 0
	v_cvt_pk_f16_f32 v25, v18, v19
	global_store_dwordx4 v[34:35], v[22:25], off offset:256
	s_nop 1
	v_lshl_add_u64 v[22:23], v[140:141], 0, s[4:5]
	v_lshl_add_u64 v[24:25], s[94:95], 0, v[22:23]
	s_waitcnt vmcnt(15)
	v_mov_b64_e32 v[18:19], v[224:225]
	v_mov_b64_e32 v[20:21], v[226:227]
	v_cvt_f32_f16_e32 v26, v18
	v_cvt_f32_f16_sdwa v27, v18 dst_sel:DWORD dst_unused:UNUSED_PAD src0_sel:WORD_1
	v_cvt_f32_f16_e32 v18, v19
	v_cvt_f32_f16_sdwa v19, v19 dst_sel:DWORD dst_unused:UNUSED_PAD src0_sel:WORD_1
	v_pk_fma_f32 v[14:15], v[26:27], s[34:35], v[14:15] op_sel_hi:[1,0,1]
	s_nop 0
	v_cvt_pk_f16_f32 v14, v14, v15
	v_pk_fma_f32 v[16:17], v[18:19], s[34:35], v[16:17] op_sel_hi:[1,0,1]
	v_lshl_add_u64 v[18:19], s[8:9], 0, v[22:23]
	v_cvt_pk_f16_f32 v15, v16, v17
	v_cvt_f32_f16_e32 v16, v20
	v_cvt_f32_f16_sdwa v17, v20 dst_sel:DWORD dst_unused:UNUSED_PAD src0_sel:WORD_1
	v_pk_fma_f32 v[10:11], v[16:17], s[34:35], v[10:11] op_sel_hi:[1,0,1]
	s_nop 0
	v_cvt_pk_f16_f32 v16, v10, v11
	v_cvt_f32_f16_e32 v10, v21
	v_cvt_f32_f16_sdwa v11, v21 dst_sel:DWORD dst_unused:UNUSED_PAD src0_sel:WORD_1
	v_pk_fma_f32 v[10:11], v[10:11], s[34:35], v[12:13] op_sel_hi:[1,0,1]
	s_nop 0
	v_cvt_pk_f16_f32 v17, v10, v11
	s_nop 0
	global_store_dwordx4 v[18:19], v[14:17], off
	s_waitcnt vmcnt(15)
	v_mov_b64_e32 v[10:11], v[228:229]
	v_mov_b64_e32 v[12:13], v[230:231]
	s_nop 0
	v_cvt_f32_f16_e32 v14, v10
	v_cvt_f32_f16_sdwa v15, v10 dst_sel:DWORD dst_unused:UNUSED_PAD src0_sel:WORD_1
	v_cvt_f32_f16_e32 v10, v11
	v_cvt_f32_f16_sdwa v11, v11 dst_sel:DWORD dst_unused:UNUSED_PAD src0_sel:WORD_1
	v_pk_fma_f32 v[6:7], v[14:15], s[34:35], v[6:7] op_sel_hi:[1,0,1]
	s_nop 0
	v_cvt_pk_f16_f32 v6, v6, v7
	v_pk_fma_f32 v[8:9], v[10:11], s[34:35], v[8:9] op_sel_hi:[1,0,1]
	s_nop 0
	v_cvt_pk_f16_f32 v7, v8, v9
	v_cvt_f32_f16_e32 v8, v12
	v_cvt_f32_f16_sdwa v9, v12 dst_sel:DWORD dst_unused:UNUSED_PAD src0_sel:WORD_1
	v_pk_fma_f32 v[2:3], v[8:9], s[34:35], v[2:3] op_sel_hi:[1,0,1]
	s_nop 0
	v_cvt_pk_f16_f32 v8, v2, v3
	v_cvt_f32_f16_e32 v2, v13
	v_cvt_f32_f16_sdwa v3, v13 dst_sel:DWORD dst_unused:UNUSED_PAD src0_sel:WORD_1
	v_pk_fma_f32 v[2:3], v[2:3], s[34:35], v[4:5] op_sel_hi:[1,0,1]
	s_nop 0
	v_cvt_pk_f16_f32 v9, v2, v3
	s_mov_b32 s35, s73
	global_store_dwordx4 v[18:19], v[6:9], off offset:256
	s_cmpk_lt_u32 s46, 0x100
	s_cbranch_scc1 .Lgy0
	s_barrier

; #define PG8_STAGE(bufoff, gbase, voff) do { _Pragma("unroll") for (int _i = 0; _i < 2; ++_i) \
;         __builtin_amdgcn_global_load_lds((const unsigned*)((const char*)(gbase) + (voff)[_i]), (LAS unsigned*)(lds + (bufoff) + ldsw + _i * 8192), 16, 0, 0); } while (0)
; #define PG8_LDA(dst, b, h) do { _Pragma("unroll") for (int m = 0; m < 4; ++m) _Pragma("unroll") for (int k = 0; k < 2; ++k) dst[m][k] = *(const LAS h16x8*)(lds + PG8_SA(b, h) + aoff + m * 2048 + k * 1024); } while (0)
; #define PG8_LDB(dst, b, h) do { _Pragma("unroll") for (int n = 0; n < 2; ++n) _Pragma("unroll") for (int k = 0; k < 2; ++k) dst[n][k] = *(const LAS h16x8*)(lds + PG8_SB(b, h) + boff + n * 2048 + k * 1024); } while (0)
; #define PG8_MMA(ai, bj, At, Bt_) do { __builtin_amdgcn_s_setprio(1); _Pragma("unroll") for (int m = 0; m < 4; ++m) _Pragma("unroll") for (int n = 0; n < 2; ++n) _Pragma("unroll") for (int k = 0; k < 2; ++k) \
;         acc[ai][bj][m][n] = __builtin_amdgcn_mfma_f32_16x16x32_f16(Bt_[n][k], At[m][k], acc[ai][bj][m][n], 0, 0, 0); __builtin_amdgcn_s_setprio(0); } while (0)
; #define PG8_WAIT_V(n) asm volatile("s_waitcnt vmcnt(" #n ")" ::: "memory")
; template <class Epi, class AMap>
; __device__ __forceinline__ void gemm_phase(LAS unsigned char* lds, const AMap am, const int lda, const h16* Bt, const int ldb, const int M, const int N, const int K, const Epi& E) {
;     ...
;         for (int t = 0; t < nt; t += 2) {
;             const bool last = (t == nt - 2);
;             const char* a1 = cA + (size_t)(t + 1) * kstep;
;             const char* a2 = last ? nA : cA + (size_t)(t + 2) * kstep; const char* b2 = last ? nB : cB + (size_t)(t + 2) * kstep;
;             const char* a3 = a2 + kstep; const char* b3 = b2 + kstep;
;             PG8_LDB(B0, 0, 0); PG8_SCHED; PG8_LDA(At, 0, 0); PG8_STAGE(PG8_SA(1, 1), a1 + hstepA, voffA);
;             PG8_WAIT_L(8); PG8_BAR; PG8_WAIT_L(0); PG8_MMA(0, 0, At, B0); PG8_BAR; PG8_SCHED;
;             PG8_LDB(B1, 0, 1); PG8_STAGE(PG8_SB(0, 0), b2, voffB);
;             PG8_BAR; PG8_WAIT_L(0); PG8_MMA(0, 1, At, B1); PG8_BAR;
;             PG8_LDA(At, 0, 1); PG8_STAGE(PG8_SA(0, 0), a2, voffA);
;             PG8_BAR; PG8_WAIT_L(0); PG8_MMA(1, 0, At, B0); PG8_BAR; PG8_SCHED;
;             PG8_STAGE(PG8_SB(0, 1), b2 + hstepB, voffB);
;             PG8_WAIT_V(6); PG8_BAR; PG8_MMA(1, 1, At, B1); PG8_BAR;
.LBB0_92:
	s_add_u32 s0, vcc_lo, 0xfff80080
	s_addc_u32 s1, vcc_hi, -1
	s_add_i32 s67, 0, 0x10000
	v_add_u32_e32 v226, s67, v169
	ds_read_b128 v[66:69], v226
	ds_read_b128 v[70:73], v226 offset:1024
	ds_read_b128 v[74:77], v226 offset:2048
	ds_read_b128 v[78:81], v226 offset:3072
	s_cmp_eq_u32 s60, 28
	s_cselect_b32 s27, s69, s1
	s_cselect_b32 s26, s29, s0
	s_cselect_b32 s49, s73, s66
	s_cselect_b32 s48, s20, s21
	v_lshl_add_u64 v[192:193], vcc, 0, v[172:173]
	s_add_i32 m0, s81, 0xc000
	ds_read_b128 v[90:93], v195
	ds_read_b128 v[94:97], v195 offset:1024
	ds_read_b128 v[98:101], v195 offset:2048
	ds_read_b128 v[102:105], v195 offset:3072
	ds_read_b128 v[176:179], v195 offset:4096
	ds_read_b128 v[180:183], v195 offset:5120
	ds_read_b128 v[184:187], v195 offset:6144
	ds_read_b128 v[188:191], v195 offset:7168
	global_load_lds_dwordx4 v[192:193], off
	v_lshl_add_u64 v[192:193], vcc, 0, v[174:175]
	s_add_i32 m0, s81, 0xe000
	s_nop 0
	global_load_lds_dwordx4 v[192:193], off
	s_waitcnt lgkmcnt(11)
	s_add_i32 s65, 0, 0x14000
	v_add_u32_e32 v192, s65, v169
	s_add_i32 s0, s67, s64
	ds_read_b128 v[196:199], v192
	ds_read_b128 v[200:203], v192 offset:1024
	ds_read_b128 v[204:207], v192 offset:2048
	ds_read_b128 v[220:223], v192 offset:3072
	s_waitcnt vmcnt(8) lgkmcnt(0)
	s_barrier
	v_mfma_f32_16x16x32_f16 v[158:161], v[66:69], v[90:93], v[158:161]
	v_mfma_f32_16x16x32_f16 v[154:157], v[74:77], v[90:93], v[154:157]
	v_mfma_f32_16x16x32_f16 v[142:145], v[66:69], v[98:101], v[142:145]
	v_mfma_f32_16x16x32_f16 v[134:137], v[74:77], v[98:101], v[134:137]
	v_mfma_f32_16x16x32_f16 v[126:129], v[66:69], v[176:179], v[126:129]
	v_mfma_f32_16x16x32_f16 v[118:121], v[74:77], v[176:179], v[118:121]
	v_mfma_f32_16x16x32_f16 v[110:113], v[66:69], v[184:187], v[110:113]
	v_mfma_f32_16x16x32_f16 v[106:109], v[74:77], v[184:187], v[106:109]
	v_mfma_f32_16x16x32_f16 v[158:161], v[70:73], v[94:97], v[158:161]
	v_mfma_f32_16x16x32_f16 v[154:157], v[78:81], v[94:97], v[154:157]
	v_mfma_f32_16x16x32_f16 v[142:145], v[70:73], v[102:105], v[142:145]
	v_mfma_f32_16x16x32_f16 v[134:137], v[78:81], v[102:105], v[134:137]
	v_mfma_f32_16x16x32_f16 v[126:129], v[70:73], v[180:183], v[126:129]
	v_mfma_f32_16x16x32_f16 v[118:121], v[78:81], v[180:183], v[118:121]
	v_mfma_f32_16x16x32_f16 v[110:113], v[70:73], v[188:191], v[110:113]
	v_mfma_f32_16x16x32_f16 v[106:109], v[78:81], v[188:191], v[106:109]
	v_mfma_f32_16x16x32_f16 v[150:153], v[196:199], v[90:93], v[150:153]
	v_mfma_f32_16x16x32_f16 v[146:149], v[204:207], v[90:93], v[146:149]
	v_mfma_f32_16x16x32_f16 v[150:153], v[200:203], v[94:97], v[150:153]
	v_mfma_f32_16x16x32_f16 v[146:149], v[220:223], v[94:97], v[146:149]
	v_mfma_f32_16x16x32_f16 v[138:141], v[196:199], v[98:101], v[138:141]
	v_mfma_f32_16x16x32_f16 v[130:133], v[204:207], v[98:101], v[130:133]
	v_mfma_f32_16x16x32_f16 v[114:117], v[204:207], v[176:179], v[114:117]
	v_mfma_f32_16x16x32_f16 v[86:89], v[196:199], v[184:187], v[86:89]
	v_mfma_f32_16x16x32_f16 v[82:85], v[204:207], v[184:187], v[82:85]
	v_mfma_f32_16x16x32_f16 v[138:141], v[200:203], v[102:105], v[138:141]
	v_mfma_f32_16x16x32_f16 v[130:133], v[220:223], v[102:105], v[130:133]
	v_mfma_f32_16x16x32_f16 v[122:125], v[196:199], v[176:179], v[122:125]
	v_mfma_f32_16x16x32_f16 v[114:117], v[220:223], v[180:183], v[114:117]
	v_mfma_f32_16x16x32_f16 v[86:89], v[200:203], v[188:191], v[86:89]
	v_mfma_f32_16x16x32_f16 v[82:85], v[220:223], v[188:191], v[82:85]
	v_mfma_f32_16x16x32_f16 v[122:125], v[200:203], v[180:183], v[122:125]
	s_barrier
	v_lshl_add_u64 v[192:193], s[48:49], 0, v[0:1]
	s_mov_b32 m0, s0
	v_lshl_add_u64 v[212:213], s[48:49], 0, v[162:163]
	global_load_lds_dwordx4 v[192:193], off
	s_add_i32 m0, s0, 0x2000
	s_nop 0
	global_load_lds_dwordx4 v[212:213], off
	s_mov_b32 m0, s81
	v_lshl_add_u64 v[214:215], s[26:27], 0, v[166:167]
	ds_read_b128 v[90:93], v195 offset:16384
	ds_read_b128 v[94:97], v195 offset:17408
	ds_read_b128 v[98:101], v195 offset:18432
	ds_read_b128 v[102:105], v195 offset:19456
	ds_read_b128 v[176:179], v195 offset:20480
	ds_read_b128 v[180:183], v195 offset:21504
	ds_read_b128 v[184:187], v195 offset:22528
	ds_read_b128 v[188:191], v195 offset:23552
	global_load_lds_dwordx4 v[214:215], off
	v_lshl_add_u64 v[216:217], s[26:27], 0, v[164:165]
	s_mov_b32 m0, s82
	s_nop 0
	global_load_lds_dwordx4 v[216:217], off
	s_add_u32 s0, s48, 0x80000
	s_addc_u32 s1, s49, 0
	s_add_i32 s65, s65, s64
	v_lshl_add_u64 v[224:225], s[0:1], 0, v[0:1]
	s_mov_b32 m0, s65
	s_nop 0
	global_load_lds_dwordx4 v[224:225], off
	v_lshl_add_u64 v[224:225], s[0:1], 0, v[162:163]
	s_add_i32 m0, s65, 0x2000
	s_nop 0
	global_load_lds_dwordx4 v[224:225], off
	s_waitcnt vmcnt(8) lgkmcnt(0)
	s_barrier
; #define PG8_STAGE(bufoff, gbase, voff) do { _Pragma("unroll") for (int _i = 0; _i < 2; ++_i) \
;         __builtin_amdgcn_global_load_lds((const unsigned*)((const char*)(gbase) + (voff)[_i]), (LAS unsigned*)(lds + (bufoff) + ldsw + _i * 8192), 16, 0, 0); } while (0)
; #define PG8_LDA(dst, b, h) do { _Pragma("unroll") for (int m = 0; m < 4; ++m) _Pragma("unroll") for (int k = 0; k < 2; ++k) dst[m][k] = *(const LAS h16x8*)(lds + PG8_SA(b, h) + aoff + m * 2048 + k * 1024); } while (0)
; #define PG8_LDB(dst, b, h) do { _Pragma("unroll") for (int n = 0; n < 2; ++n) _Pragma("unroll") for (int k = 0; k < 2; ++k) dst[n][k] = *(const LAS h16x8*)(lds + PG8_SB(b, h) + boff + n * 2048 + k * 1024); } while (0)
; #define PG8_MMA(ai, bj, At, Bt_) do { __builtin_amdgcn_s_setprio(1); _Pragma("unroll") for (int m = 0; m < 4; ++m) _Pragma("unroll") for (int n = 0; n < 2; ++n) _Pragma("unroll") for (int k = 0; k < 2; ++k) \
;         acc[ai][bj][m][n] = __builtin_amdgcn_mfma_f32_16x16x32_f16(Bt_[n][k], At[m][k], acc[ai][bj][m][n], 0, 0, 0); __builtin_amdgcn_s_setprio(0); } while (0)
; #define PG8_WAIT_V(n) asm volatile("s_waitcnt vmcnt(" #n ")" ::: "memory")
; #define PG8_WAIT_L(n) asm volatile("s_waitcnt lgkmcnt(" #n ")" ::: "memory")
; #define PG8_BAR __builtin_amdgcn_s_barrier()
; #define PG8_SCHED __builtin_amdgcn_sched_barrier(0)
; template <class Epi, class AMap>
; __device__ __forceinline__ void gemm_phase(LAS unsigned char* lds, const AMap am, const int lda, const h16* Bt, const int ldb, const int M, const int N, const int K, const Epi& E) {
;     ...
;             PG8_WAIT_V(6); PG8_BAR; PG8_MMA(1, 1, At, B1); PG8_BAR;
;             PG8_LDB(B0, 1, 0); PG8_SCHED; PG8_LDA(At, 1, 0); PG8_STAGE(PG8_SA(0, 1), a2 + hstepA, voffA);
;             PG8_WAIT_L(8); PG8_BAR; PG8_WAIT_L(0); PG8_MMA(0, 0, At, B0); PG8_BAR; PG8_SCHED;
;             PG8_LDB(B1, 1, 1); PG8_STAGE(PG8_SB(1, 0), b3, voffB);
;             PG8_BAR; PG8_WAIT_L(0); PG8_MMA(0, 1, At, B1); PG8_BAR;
	v_mfma_f32_16x16x32_f16 v[62:65], v[66:69], v[90:93], v[62:65]
	v_mfma_f32_16x16x32_f16 v[58:61], v[74:77], v[90:93], v[58:61]
	v_mfma_f32_16x16x32_f16 v[46:49], v[66:69], v[98:101], v[46:49]
	v_mfma_f32_16x16x32_f16 v[38:41], v[74:77], v[98:101], v[38:41]
	v_mfma_f32_16x16x32_f16 v[30:33], v[66:69], v[176:179], v[30:33]
	v_mfma_f32_16x16x32_f16 v[22:25], v[74:77], v[176:179], v[22:25]
	v_mfma_f32_16x16x32_f16 v[14:17], v[66:69], v[184:187], v[14:17]
	v_mfma_f32_16x16x32_f16 v[10:13], v[74:77], v[184:187], v[10:13]
	v_mfma_f32_16x16x32_f16 v[62:65], v[70:73], v[94:97], v[62:65]
	v_mfma_f32_16x16x32_f16 v[58:61], v[78:81], v[94:97], v[58:61]
	v_mfma_f32_16x16x32_f16 v[46:49], v[70:73], v[102:105], v[46:49]
	v_mfma_f32_16x16x32_f16 v[38:41], v[78:81], v[102:105], v[38:41]
	v_mfma_f32_16x16x32_f16 v[30:33], v[70:73], v[180:183], v[30:33]
	v_mfma_f32_16x16x32_f16 v[22:25], v[78:81], v[180:183], v[22:25]
	v_mfma_f32_16x16x32_f16 v[14:17], v[70:73], v[188:191], v[14:17]
	v_mfma_f32_16x16x32_f16 v[10:13], v[78:81], v[188:191], v[10:13]
	v_mfma_f32_16x16x32_f16 v[54:57], v[196:199], v[90:93], v[54:57]
	v_mfma_f32_16x16x32_f16 v[50:53], v[204:207], v[90:93], v[50:53]
	v_mfma_f32_16x16x32_f16 v[42:45], v[196:199], v[98:101], v[42:45]
	v_mfma_f32_16x16x32_f16 v[34:37], v[204:207], v[98:101], v[34:37]
	v_mfma_f32_16x16x32_f16 v[26:29], v[196:199], v[176:179], v[26:29]
	v_mfma_f32_16x16x32_f16 v[18:21], v[204:207], v[176:179], v[18:21]
	v_mfma_f32_16x16x32_f16 v[6:9], v[196:199], v[184:187], v[6:9]
	v_mfma_f32_16x16x32_f16 v[2:5], v[204:207], v[184:187], v[2:5]
	v_mfma_f32_16x16x32_f16 v[54:57], v[200:203], v[94:97], v[54:57]
	v_mfma_f32_16x16x32_f16 v[50:53], v[220:223], v[94:97], v[50:53]
	v_mfma_f32_16x16x32_f16 v[42:45], v[200:203], v[102:105], v[42:45]
	v_mfma_f32_16x16x32_f16 v[34:37], v[220:223], v[102:105], v[34:37]
	v_mfma_f32_16x16x32_f16 v[26:29], v[200:203], v[180:183], v[26:29]
	v_mfma_f32_16x16x32_f16 v[18:21], v[220:223], v[180:183], v[18:21]
	v_mfma_f32_16x16x32_f16 v[6:9], v[200:203], v[188:191], v[6:9]
	v_mfma_f32_16x16x32_f16 v[2:5], v[220:223], v[188:191], v[2:5]
	s_barrier
	s_add_i32 s65, 0, 0x18000
	v_add_u32_e32 v226, s65, v169
	ds_read_b128 v[66:69], v226
	ds_read_b128 v[70:73], v226 offset:1024
	ds_read_b128 v[74:77], v226 offset:2048
	ds_read_b128 v[78:81], v226 offset:3072
	s_add_u32 s0, s26, 0x80000
	s_addc_u32 s1, s27, 0
	s_mov_b32 m0, s83
	v_lshl_add_u64 v[224:225], s[0:1], 0, v[166:167]
	ds_read_b128 v[90:93], v195 offset:32768
	ds_read_b128 v[94:97], v195 offset:33792
	ds_read_b128 v[98:101], v195 offset:34816
	ds_read_b128 v[102:105], v195 offset:35840
	ds_read_b128 v[176:179], v195 offset:36864
	ds_read_b128 v[180:183], v195 offset:37888
	ds_read_b128 v[184:187], v195 offset:38912
	ds_read_b128 v[188:191], v195 offset:39936
	global_load_lds_dwordx4 v[224:225], off
	v_lshl_add_u64 v[224:225], s[0:1], 0, v[164:165]
	s_mov_b32 m0, s50
	s_nop 0
	global_load_lds_dwordx4 v[224:225], off
	s_waitcnt lgkmcnt(11)
	s_add_i32 s26, 0, 0x1c000
	v_add_u32_e32 v226, s26, v169
	s_add_i32 s0, s65, s64
	ds_read_b128 v[196:199], v226
	ds_read_b128 v[200:203], v226 offset:1024
	ds_read_b128 v[204:207], v226 offset:2048
	ds_read_b128 v[220:223], v226 offset:3072
	s_waitcnt vmcnt(8) lgkmcnt(0)
	s_barrier
	v_mfma_f32_16x16x32_f16 v[158:161], v[66:69], v[90:93], v[158:161]
	v_mfma_f32_16x16x32_f16 v[158:161], v[70:73], v[94:97], v[158:161]
	v_mfma_f32_16x16x32_f16 v[154:157], v[74:77], v[90:93], v[154:157]
	v_mfma_f32_16x16x32_f16 v[154:157], v[78:81], v[94:97], v[154:157]
	v_mfma_f32_16x16x32_f16 v[142:145], v[66:69], v[98:101], v[142:145]
	v_mfma_f32_16x16x32_f16 v[134:137], v[74:77], v[98:101], v[134:137]
	v_mfma_f32_16x16x32_f16 v[126:129], v[66:69], v[176:179], v[126:129]
	v_mfma_f32_16x16x32_f16 v[118:121], v[74:77], v[176:179], v[118:121]
	v_mfma_f32_16x16x32_f16 v[110:113], v[66:69], v[184:187], v[110:113]
	v_mfma_f32_16x16x32_f16 v[106:109], v[74:77], v[184:187], v[106:109]
	v_mfma_f32_16x16x32_f16 v[142:145], v[70:73], v[102:105], v[142:145]
	v_mfma_f32_16x16x32_f16 v[134:137], v[78:81], v[102:105], v[134:137]
	v_mfma_f32_16x16x32_f16 v[126:129], v[70:73], v[180:183], v[126:129]
	v_mfma_f32_16x16x32_f16 v[118:121], v[78:81], v[180:183], v[118:121]
	v_mfma_f32_16x16x32_f16 v[110:113], v[70:73], v[188:191], v[110:113]
	v_mfma_f32_16x16x32_f16 v[106:109], v[78:81], v[188:191], v[106:109]
	v_mfma_f32_16x16x32_f16 v[146:149], v[204:207], v[90:93], v[146:149]
	v_mfma_f32_16x16x32_f16 v[150:153], v[196:199], v[90:93], v[150:153]
	v_mfma_f32_16x16x32_f16 v[146:149], v[220:223], v[94:97], v[146:149]
	v_mfma_f32_16x16x32_f16 v[138:141], v[196:199], v[98:101], v[138:141]
	v_mfma_f32_16x16x32_f16 v[150:153], v[200:203], v[94:97], v[150:153]
	v_mfma_f32_16x16x32_f16 v[138:141], v[200:203], v[102:105], v[138:141]
	v_mfma_f32_16x16x32_f16 v[130:133], v[204:207], v[98:101], v[130:133]
	v_mfma_f32_16x16x32_f16 v[130:133], v[220:223], v[102:105], v[130:133]
	v_mfma_f32_16x16x32_f16 v[122:125], v[196:199], v[176:179], v[122:125]
	v_mfma_f32_16x16x32_f16 v[122:125], v[200:203], v[180:183], v[122:125]
	v_mfma_f32_16x16x32_f16 v[114:117], v[204:207], v[176:179], v[114:117]
	v_mfma_f32_16x16x32_f16 v[86:89], v[196:199], v[184:187], v[86:89]
	v_mfma_f32_16x16x32_f16 v[82:85], v[204:207], v[184:187], v[82:85]
	v_mfma_f32_16x16x32_f16 v[114:117], v[220:223], v[180:183], v[114:117]
	v_mfma_f32_16x16x32_f16 v[86:89], v[200:203], v[188:191], v[86:89]
	v_mfma_f32_16x16x32_f16 v[82:85], v[220:223], v[188:191], v[82:85]
	s_barrier
; #define PG8_STAGE(bufoff, gbase, voff) do { _Pragma("unroll") for (int _i = 0; _i < 2; ++_i) \
;         __builtin_amdgcn_global_load_lds((const unsigned*)((const char*)(gbase) + (voff)[_i]), (LAS unsigned*)(lds + (bufoff) + ldsw + _i * 8192), 16, 0, 0); } while (0)
; #define PG8_LDA(dst, b, h) do { _Pragma("unroll") for (int m = 0; m < 4; ++m) _Pragma("unroll") for (int k = 0; k < 2; ++k) dst[m][k] = *(const LAS h16x8*)(lds + PG8_SA(b, h) + aoff + m * 2048 + k * 1024); } while (0)
; #define PG8_MMA(ai, bj, At, Bt_) do { __builtin_amdgcn_s_setprio(1); _Pragma("unroll") for (int m = 0; m < 4; ++m) _Pragma("unroll") for (int n = 0; n < 2; ++n) _Pragma("unroll") for (int k = 0; k < 2; ++k) \
;         acc[ai][bj][m][n] = __builtin_amdgcn_mfma_f32_16x16x32_f16(Bt_[n][k], At[m][k], acc[ai][bj][m][n], 0, 0, 0); __builtin_amdgcn_s_setprio(0); } while (0)
; #define PG8_WAIT_V(n) asm volatile("s_waitcnt vmcnt(" #n ")" ::: "memory")
; #define PG8_WAIT_L(n) asm volatile("s_waitcnt lgkmcnt(" #n ")" ::: "memory")
; #define PG8_BAR __builtin_amdgcn_s_barrier()
; #define PG8_SCHED __builtin_amdgcn_sched_barrier(0)
; template <class Epi, class AMap>
; __device__ __forceinline__ void gemm_phase(LAS unsigned char* lds, const AMap am, const int lda, const h16* Bt, const int ldb, const int M, const int N, const int K, const Epi& E) {
;     ...
;             PG8_LDA(At, 1, 1); PG8_STAGE(PG8_SA(1, 0), a3, voffA);
;             PG8_BAR; PG8_WAIT_L(0); PG8_MMA(1, 0, At, B0); PG8_BAR; PG8_SCHED;
;             PG8_STAGE(PG8_SB(1, 1), b3 + hstepB, voffB);
;             PG8_WAIT_V(6); PG8_BAR; PG8_MMA(1, 1, At, B1); PG8_BAR;
;         }
;     __device__ __forceinline__ void operator()(const f32x4 (&acc)[2][2][4][2], const Unit& u, int wr, int wc, int fr, int fq) const {
;         const int row0 = u.pm * 256 + wr * 64 + fr, f0 = u.pn * 128 + wc * 32 + 8 * fq;
;         f32x4 w0[2], w1[2], w2[2], bb[2];
; #pragma unroll
;         for (int n = 0; n < 2; ++n) { w0[n] = *(const f32x4*)(cw + f0 + 4 * n); w1[n] = *(const f32x4*)(cw + FF + f0 + 4 * n); w2[n] = *(const f32x4*)(cw + 2 * FF + f0 + 4 * n); bb[n] = *(const f32x4*)(cb + f0 + 4 * n); }
	v_lshl_add_u64 v[224:225], v[192:193], 0, s[92:93]
	s_mov_b32 m0, s0
	s_nop 0
	global_load_lds_dwordx4 v[224:225], off
	v_lshl_add_u64 v[224:225], v[212:213], 0, s[92:93]
	s_add_i32 m0, s0, 0x2000
	s_nop 0
	global_load_lds_dwordx4 v[224:225], off
	s_mov_b32 m0, s89
	v_lshl_add_u64 v[192:193], v[214:215], 0, s[92:93]
	ds_read_b128 v[90:93], v195 offset:49152
	ds_read_b128 v[94:97], v195 offset:50176
	ds_read_b128 v[98:101], v195 offset:51200
	ds_read_b128 v[102:105], v195 offset:52224
	ds_read_b128 v[176:179], v195 offset:53248
	ds_read_b128 v[180:183], v195 offset:54272
	ds_read_b128 v[184:187], v195 offset:55296
	ds_read_b128 v[188:191], v195 offset:56320
	global_load_lds_dwordx4 v[192:193], off
	v_lshl_add_u64 v[192:193], v[216:217], 0, s[92:93]
	s_mov_b32 m0, s35
	s_nop 0
	global_load_lds_dwordx4 v[192:193], off
	s_add_u32 s0, s48, 0x80080
	s_addc_u32 s1, s49, 0
	s_add_i32 s26, s26, s64
	v_lshl_add_u64 v[224:225], s[0:1], 0, v[0:1]
	s_mov_b32 m0, s26
	s_nop 0
	global_load_lds_dwordx4 v[224:225], off
	v_lshl_add_u64 v[224:225], s[0:1], 0, v[162:163]
	s_add_i32 m0, s26, 0x2000
	s_nop 0
	global_load_lds_dwordx4 v[224:225], off
	s_add_i32 s60, s60, 2
	s_add_u32 vcc_lo, vcc_lo, 0x100
	s_addc_u32 vcc_hi, vcc_hi, 0
	s_add_u32 s21, s21, 0x100
	s_addc_u32 s66, s66, 0
	s_cmp_gt_u32 s60, 29
	s_waitcnt vmcnt(8) lgkmcnt(0)
	s_barrier
	v_mfma_f32_16x16x32_f16 v[62:65], v[66:69], v[90:93], v[62:65]
	v_mfma_f32_16x16x32_f16 v[58:61], v[74:77], v[90:93], v[58:61]
	v_mfma_f32_16x16x32_f16 v[46:49], v[66:69], v[98:101], v[46:49]
	v_mfma_f32_16x16x32_f16 v[38:41], v[74:77], v[98:101], v[38:41]
	v_mfma_f32_16x16x32_f16 v[30:33], v[66:69], v[176:179], v[30:33]
	v_mfma_f32_16x16x32_f16 v[22:25], v[74:77], v[176:179], v[22:25]
	v_mfma_f32_16x16x32_f16 v[14:17], v[66:69], v[184:187], v[14:17]
	v_mfma_f32_16x16x32_f16 v[10:13], v[74:77], v[184:187], v[10:13]
	v_mfma_f32_16x16x32_f16 v[62:65], v[70:73], v[94:97], v[62:65]
	v_mfma_f32_16x16x32_f16 v[58:61], v[78:81], v[94:97], v[58:61]
	v_mfma_f32_16x16x32_f16 v[46:49], v[70:73], v[102:105], v[46:49]
	v_mfma_f32_16x16x32_f16 v[38:41], v[78:81], v[102:105], v[38:41]
	v_mfma_f32_16x16x32_f16 v[30:33], v[70:73], v[180:183], v[30:33]
	v_mfma_f32_16x16x32_f16 v[22:25], v[78:81], v[180:183], v[22:25]
	v_mfma_f32_16x16x32_f16 v[14:17], v[70:73], v[188:191], v[14:17]
	v_mfma_f32_16x16x32_f16 v[10:13], v[78:81], v[188:191], v[10:13]
	v_mfma_f32_16x16x32_f16 v[54:57], v[196:199], v[90:93], v[54:57]
	v_mfma_f32_16x16x32_f16 v[50:53], v[204:207], v[90:93], v[50:53]
	v_mfma_f32_16x16x32_f16 v[42:45], v[196:199], v[98:101], v[42:45]
	v_mfma_f32_16x16x32_f16 v[34:37], v[204:207], v[98:101], v[34:37]
	v_mfma_f32_16x16x32_f16 v[26:29], v[196:199], v[176:179], v[26:29]
	v_mfma_f32_16x16x32_f16 v[18:21], v[204:207], v[176:179], v[18:21]
	v_mfma_f32_16x16x32_f16 v[6:9], v[196:199], v[184:187], v[6:9]
	v_mfma_f32_16x16x32_f16 v[2:5], v[204:207], v[184:187], v[2:5]
	v_mfma_f32_16x16x32_f16 v[54:57], v[200:203], v[94:97], v[54:57]
	v_mfma_f32_16x16x32_f16 v[50:53], v[220:223], v[94:97], v[50:53]
	v_mfma_f32_16x16x32_f16 v[42:45], v[200:203], v[102:105], v[42:45]
	v_mfma_f32_16x16x32_f16 v[34:37], v[220:223], v[102:105], v[34:37]
	v_mfma_f32_16x16x32_f16 v[26:29], v[200:203], v[180:183], v[26:29]
	v_mfma_f32_16x16x32_f16 v[18:21], v[220:223], v[180:183], v[18:21]
	v_mfma_f32_16x16x32_f16 v[6:9], v[200:203], v[188:191], v[6:9]
	v_mfma_f32_16x16x32_f16 v[2:5], v[220:223], v[188:191], v[2:5]
	s_barrier
	s_cbranch_scc0 .LBB0_92
	v_lshl_or_b32 v176, s23, 7, v194
	v_ashrrev_i32_e32 v177, 31, v176
	v_lshlrev_b64 v[66:67], 2, v[176:177]
	v_lshl_add_u64 v[70:71], s[74:75], 0, v[66:67]
	v_lshl_add_u64 v[74:75], s[8:9], 0, v[66:67]
	v_lshl_add_u64 v[78:79], s[70:71], 0, v[66:67]
	v_lshl_add_u64 v[102:103], s[78:79], 0, v[66:67]
	global_load_dwordx4 v[66:69], v[70:71], off offset:16
	global_load_dwordx4 v[90:93], v[70:71], off
	s_nop 0
	global_load_dwordx4 v[70:73], v[74:75], off offset:16
	global_load_dwordx4 v[94:97], v[74:75], off
	s_nop 0
	global_load_dwordx4 v[74:77], v[78:79], off offset:16
	global_load_dwordx4 v[98:101], v[78:79], off
	s_nop 0
	global_load_dwordx4 v[78:81], v[102:103], off offset:16
	s_nop 0
	global_load_dwordx4 v[102:105], v[102:103], off
	s_cmpk_gt_u32 s10, 0xff
	s_cbranch_scc1 .Lgx1
	s_barrier
; template <int CTRL> __device__ __forceinline__ float dpp_f(float x) { return __int_as_float(__builtin_amdgcn_update_dpp(0, __float_as_int(x), CTRL, 0xF, 0xF, true)); }
;     __device__ __forceinline__ void operator()(const f32x4 (&acc)[2][2][4][2], const Unit& u, int wr, int wc, int fr, int fq) const {
;         const int row0 = u.pm * 256 + wr * 64 + fr, f0 = u.pn * 128 + wc * 32 + 8 * fq;
;         f32x4 w0[2], w1[2], w2[2], bb[2];
; #pragma unroll
;         for (int n = 0; n < 2; ++n) { w0[n] = *(const f32x4*)(cw + f0 + 4 * n); w1[n] = *(const f32x4*)(cw + FF + f0 + 4 * n); w2[n] = *(const f32x4*)(cw + 2 * FF + f0 + 4 * n); bb[n] = *(const f32x4*)(cb + f0 + 4 * n); }
; #pragma unroll
;         for (int ai = 0; ai < 2; ++ai) {
;             f32x4 p1[2], p2[2];
; #pragma unroll
;             for (int n = 0; n < 2; ++n) { p1[n] = (f32x4){0.f, 0.f, 0.f, 0.f}; p2[n] = p1[n]; }
; #pragma unroll
;             for (int m = 0; m < 4; ++m) {
;                 const int row = row0 + ai * 128 + m * 16;
;                 f32x4 r1[2], r2[2], o[2];
; #pragma unroll
;                 for (int n = 0; n < 2; ++n)
; #pragma unroll
;                     for (int e = 0; e < 4; ++e) {
;                         const float g = acc[ai][1][m][n][e];
;                         r1[n][e] = dpp_f<0x121>(g); r2[n][e] = dpp_f<0x122>(g);
;                         const float g1 = fr >= 1 ? r1[n][e] : p1[n][e], g2 = fr >= 2 ? r2[n][e] : p2[n][e];
;                         const float gc = bb[n][e] + g2 * w0[n][e] + g1 * w1[n][e] + g * w2[n][e];
;                         o[n][e] = gelu_mul(acc[ai][0][m][n][e], gc);
;                     }
;                 if (m > 0 || fr >= 2) *(u32x4*)(ACT + (size_t)row * FF + f0) = pack8(o[0], o[1]);
.Lgx1:
	s_lshl_b32 s20, s22, 8
	s_add_i32 s20, s20, s51
	v_or_b32_e32 v196, s20, v168
	v_mov_b32_dpp v192, v150 row_ror:1 row_mask:0xf bank_mask:0xf bound_ctrl:1
	v_mov_b32_dpp v190, v150 row_ror:2 row_mask:0xf bank_mask:0xf bound_ctrl:1
	v_mov_b32_dpp v193, v151 row_ror:1 row_mask:0xf bank_mask:0xf bound_ctrl:1
	v_mov_b32_dpp v191, v151 row_ror:2 row_mask:0xf bank_mask:0xf bound_ctrl:1
	v_mov_b32_dpp v188, v152 row_ror:1 row_mask:0xf bank_mask:0xf bound_ctrl:1
	v_mov_b32_dpp v186, v152 row_ror:2 row_mask:0xf bank_mask:0xf bound_ctrl:1
	v_mov_b32_dpp v189, v153 row_ror:1 row_mask:0xf bank_mask:0xf bound_ctrl:1
	v_mov_b32_dpp v187, v153 row_ror:2 row_mask:0xf bank_mask:0xf bound_ctrl:1
	v_mov_b32_dpp v184, v146 row_ror:1 row_mask:0xf bank_mask:0xf bound_ctrl:1
	v_mov_b32_dpp v182, v146 row_ror:2 row_mask:0xf bank_mask:0xf bound_ctrl:1
	v_mov_b32_dpp v185, v147 row_ror:1 row_mask:0xf bank_mask:0xf bound_ctrl:1
	v_mov_b32_dpp v183, v147 row_ror:2 row_mask:0xf bank_mask:0xf bound_ctrl:1
	v_mov_b32_dpp v180, v148 row_ror:1 row_mask:0xf bank_mask:0xf bound_ctrl:1
	v_mov_b32_dpp v178, v148 row_ror:2 row_mask:0xf bank_mask:0xf bound_ctrl:1
	v_mov_b32_dpp v181, v149 row_ror:1 row_mask:0xf bank_mask:0xf bound_ctrl:1
	v_mov_b32_dpp v179, v149 row_ror:2 row_mask:0xf bank_mask:0xf bound_ctrl:1
	s_and_saveexec_b64 s[22:23], s[40:41]
	s_cbranch_execz .LBB0_95
	s_waitcnt vmcnt(0)
	v_pk_fma_f32 v[198:199], v[90:91], v[190:191], v[102:103]
	v_readlane_b32 s0, v254, 58
	v_pk_fma_f32 v[198:199], v[94:95], v[192:193], v[198:199]
	v_readlane_b32 s1, v254, 59
	v_pk_fma_f32 v[198:199], v[150:151], v[98:99], v[198:199]
	s_nop 0
	v_pk_mul_f32 v[200:201], v[198:199], v[198:199]
	v_pk_mul_f32 v[202:203], v[158:159], v[198:199]
	v_fmamk_f32 v197, v201, 0x3dd2d3e7, v241
	v_mul_f32_e64 v197, v199, -v197
	v_exp_f32_e32 v197, v197
	s_nop 0
	v_add_f32_e32 v197, 1.0, v197
	v_rcp_f32_e32 v201, v197
	v_fmamk_f32 v197, v200, 0x3dd2d3e7, v241
	v_mul_f32_e64 v197, v198, -v197
	v_exp_f32_e32 v197, v197
	s_nop 0
	v_add_f32_e32 v197, 1.0, v197
	v_rcp_f32_e32 v200, v197
	s_nop 0
	v_pk_mul_f32 v[198:199], v[202:203], v[200:201]
	v_pk_fma_f32 v[200:201], v[92:93], v[186:187], v[104:105]
	v_cvt_pk_f16_f32 v198, v198, v199
	v_pk_fma_f32 v[200:201], v[96:97], v[188:189], v[200:201]
	s_nop 0
	v_pk_fma_f32 v[200:201], v[152:153], v[100:101], v[200:201]
	s_nop 0
	v_pk_mul_f32 v[202:203], v[200:201], v[200:201]
	v_pk_mul_f32 v[204:205], v[160:161], v[200:201]
	v_fmamk_f32 v197, v203, 0x3dd2d3e7, v241
	v_mul_f32_e64 v197, v201, -v197
	v_exp_f32_e32 v197, v197
	s_nop 0
	v_add_f32_e32 v197, 1.0, v197
	v_rcp_f32_e32 v203, v197
	v_fmamk_f32 v197, v202, 0x3dd2d3e7, v241
	v_mul_f32_e64 v197, v200, -v197
	v_exp_f32_e32 v197, v197
	s_nop 0
	v_add_f32_e32 v197, 1.0, v197
	v_rcp_f32_e32 v202, v197
	s_nop 0
	v_pk_mul_f32 v[200:201], v[204:205], v[202:203]
	s_nop 0
	v_cvt_pk_f16_f32 v199, v200, v201
	v_pk_fma_f32 v[200:201], v[66:67], v[182:183], v[78:79]
	s_nop 0
	v_pk_fma_f32 v[200:201], v[70:71], v[184:185], v[200:201]
	s_nop 0
	v_pk_fma_f32 v[200:201], v[146:147], v[74:75], v[200:201]
	s_nop 0
	v_pk_mul_f32 v[202:203], v[200:201], v[200:201]
	v_pk_mul_f32 v[204:205], v[154:155], v[200:201]
	v_fmamk_f32 v197, v203, 0x3dd2d3e7, v241
	v_mul_f32_e64 v197, v201, -v197
	v_exp_f32_e32 v197, v197
	s_nop 0
	v_add_f32_e32 v197, 1.0, v197
	v_rcp_f32_e32 v203, v197
	v_fmamk_f32 v197, v202, 0x3dd2d3e7, v241
	v_mul_f32_e64 v197, v200, -v197
	v_exp_f32_e32 v197, v197
	s_nop 0
	v_add_f32_e32 v197, 1.0, v197
	v_rcp_f32_e32 v202, v197
	s_nop 0
	v_pk_mul_f32 v[200:201], v[204:205], v[202:203]
	v_pk_fma_f32 v[202:203], v[68:69], v[178:179], v[80:81]
	v_cvt_pk_f16_f32 v200, v200, v201
	v_pk_fma_f32 v[202:203], v[72:73], v[180:181], v[202:203]
	s_nop 0
	v_pk_fma_f32 v[202:203], v[148:149], v[76:77], v[202:203]
	s_nop 0
	v_pk_mul_f32 v[204:205], v[202:203], v[202:203]
	v_pk_mul_f32 v[206:207], v[156:157], v[202:203]
	v_fmamk_f32 v197, v204, 0x3dd2d3e7, v241
	v_mul_f32_e64 v197, v202, -v197
	v_exp_f32_e32 v197, v197
	s_nop 0
	v_add_f32_e32 v197, 1.0, v197
	v_rcp_f32_e32 v204, v197
	v_fmamk_f32 v197, v205, 0x3dd2d3e7, v241
	v_mul_f32_e64 v197, v203, -v197
	v_exp_f32_e32 v197, v197
	s_nop 0
	v_add_f32_e32 v197, 1.0, v197
	v_rcp_f32_e32 v205, v197
	s_nop 0
	v_pk_mul_f32 v[202:203], v[206:207], v[204:205]
	s_nop 0
	v_cvt_pk_f16_f32 v201, v202, v203
	v_mov_b64_e32 v[202:203], s[0:1]
	v_mad_i64_i32 v[202:203], s[26:27], v196, s13, v[202:203]
	v_lshl_add_u64 v[202:203], v[176:177], 1, v[202:203]
	global_store_dwordx4 v[202:203], v[198:201], off

; #define PG8_STAGE(bufoff, gbase, voff) do { _Pragma("unroll") for (int _i = 0; _i < 2; ++_i) \
;         __builtin_amdgcn_global_load_lds((const unsigned*)((const char*)(gbase) + (voff)[_i]), (LAS unsigned*)(lds + (bufoff) + ldsw + _i * 8192), 16, 0, 0); } while (0)
; #define PG8_LDA(dst, b, h) do { _Pragma("unroll") for (int m = 0; m < 4; ++m) _Pragma("unroll") for (int k = 0; k < 2; ++k) dst[m][k] = *(const LAS h16x8*)(lds + PG8_SA(b, h) + aoff + m * 2048 + k * 1024); } while (0)
; #define PG8_LDB(dst, b, h) do { _Pragma("unroll") for (int n = 0; n < 2; ++n) _Pragma("unroll") for (int k = 0; k < 2; ++k) dst[n][k] = *(const LAS h16x8*)(lds + PG8_SB(b, h) + boff + n * 2048 + k * 1024); } while (0)
; #define PG8_MMA(ai, bj, At, Bt_) do { __builtin_amdgcn_s_setprio(1); _Pragma("unroll") for (int m = 0; m < 4; ++m) _Pragma("unroll") for (int n = 0; n < 2; ++n) _Pragma("unroll") for (int k = 0; k < 2; ++k) \
;         acc[ai][bj][m][n] = __builtin_amdgcn_mfma_f32_16x16x32_f16(Bt_[n][k], At[m][k], acc[ai][bj][m][n], 0, 0, 0); __builtin_amdgcn_s_setprio(0); } while (0)
; #define PG8_WAIT_V(n) asm volatile("s_waitcnt vmcnt(" #n ")" ::: "memory")
; template <class Epi, class AMap>
; __device__ __forceinline__ void gemm_phase(LAS unsigned char* lds, const AMap am, const int lda, const h16* Bt, const int ldb, const int M, const int N, const int K, const Epi& E) {
;     ...
;         for (int t = 0; t < nt; t += 2) {
;             const bool last = (t == nt - 2);
;             const char* a1 = cA + (size_t)(t + 1) * kstep;
;             const char* a2 = last ? nA : cA + (size_t)(t + 2) * kstep; const char* b2 = last ? nB : cB + (size_t)(t + 2) * kstep;
;             const char* a3 = a2 + kstep; const char* b3 = b2 + kstep;
;             PG8_LDB(B0, 0, 0); PG8_SCHED; PG8_LDA(At, 0, 0); PG8_STAGE(PG8_SA(1, 1), a1 + hstepA, voffA);
;             PG8_WAIT_L(8); PG8_BAR; PG8_WAIT_L(0); PG8_MMA(0, 0, At, B0); PG8_BAR; PG8_SCHED;
;             PG8_LDB(B1, 0, 1); PG8_STAGE(PG8_SB(0, 0), b2, voffB);
;             PG8_BAR; PG8_WAIT_L(0); PG8_MMA(0, 1, At, B1); PG8_BAR;
;             PG8_LDA(At, 0, 1); PG8_STAGE(PG8_SA(0, 0), a2, voffA);
;             PG8_BAR; PG8_WAIT_L(0); PG8_MMA(1, 0, At, B0); PG8_BAR; PG8_SCHED;
;             PG8_STAGE(PG8_SB(0, 1), b2 + hstepB, voffB);
;             PG8_WAIT_V(6); PG8_BAR; PG8_MMA(1, 1, At, B1); PG8_BAR;
.LBB0_147:
	s_add_u32 s46, s26, 0xfff80080
	s_addc_u32 s47, s27, -1
	s_add_i32 s60, 0, 0x10000
	v_add_u32_e32 v144, s60, v147
	ds_read_b128 v[140:143], v144
	ds_read_b128 v[150:153], v144 offset:1024
	ds_read_b128 v[154:157], v144 offset:2048
	ds_read_b128 v[158:161], v144 offset:3072
	s_cmp_eq_u32 s51, 28
	s_cselect_b32 s49, s41, s47
	s_cselect_b32 s48, s29, s46
	s_cselect_b32 s47, s1, s50
	s_cselect_b32 s46, s20, s21
	v_lshl_add_u64 v[144:145], s[26:27], 0, v[136:137]
	s_add_i32 m0, s23, 0xc000
	ds_read_b128 v[162:165], v149
	ds_read_b128 v[166:169], v149 offset:1024
	ds_read_b128 v[170:173], v149 offset:2048
	ds_read_b128 v[174:177], v149 offset:3072
	ds_read_b128 v[178:181], v149 offset:4096
	ds_read_b128 v[182:185], v149 offset:5120
	ds_read_b128 v[186:189], v149 offset:6144
	ds_read_b128 v[190:193], v149 offset:7168
	global_load_lds_dwordx4 v[144:145], off
	v_lshl_add_u64 v[144:145], s[26:27], 0, v[138:139]
	s_add_i32 m0, s23, 0xe000
	s_nop 0
	global_load_lds_dwordx4 v[144:145], off
	s_waitcnt lgkmcnt(11)
	s_add_i32 s66, 0, 0x14000
	v_add_u32_e32 v144, s66, v147
	s_add_i32 s60, s60, s64
	ds_read_b128 v[194:197], v144
	ds_read_b128 v[198:201], v144 offset:1024
	ds_read_b128 v[202:205], v144 offset:2048
	ds_read_b128 v[220:223], v144 offset:3072
	s_waitcnt vmcnt(8) lgkmcnt(0)
	s_barrier
	v_mfma_f32_16x16x32_f16 v[126:129], v[140:143], v[162:165], v[126:129]
	v_mfma_f32_16x16x32_f16 v[122:125], v[154:157], v[162:165], v[122:125]
	v_mfma_f32_16x16x32_f16 v[110:113], v[140:143], v[170:173], v[110:113]
	v_mfma_f32_16x16x32_f16 v[106:109], v[154:157], v[170:173], v[106:109]
	v_mfma_f32_16x16x32_f16 v[94:97], v[140:143], v[178:181], v[94:97]
	v_mfma_f32_16x16x32_f16 v[90:93], v[154:157], v[178:181], v[90:93]
	v_mfma_f32_16x16x32_f16 v[78:81], v[140:143], v[186:189], v[78:81]
	v_mfma_f32_16x16x32_f16 v[74:77], v[154:157], v[186:189], v[74:77]
	v_mfma_f32_16x16x32_f16 v[126:129], v[150:153], v[166:169], v[126:129]
	v_mfma_f32_16x16x32_f16 v[122:125], v[158:161], v[166:169], v[122:125]
	v_mfma_f32_16x16x32_f16 v[110:113], v[150:153], v[174:177], v[110:113]
	v_mfma_f32_16x16x32_f16 v[106:109], v[158:161], v[174:177], v[106:109]
	v_mfma_f32_16x16x32_f16 v[94:97], v[150:153], v[182:185], v[94:97]
	v_mfma_f32_16x16x32_f16 v[90:93], v[158:161], v[182:185], v[90:93]
	v_mfma_f32_16x16x32_f16 v[78:81], v[150:153], v[190:193], v[78:81]
	v_mfma_f32_16x16x32_f16 v[74:77], v[158:161], v[190:193], v[74:77]
	v_mfma_f32_16x16x32_f16 v[118:121], v[194:197], v[162:165], v[118:121]
	v_mfma_f32_16x16x32_f16 v[114:117], v[202:205], v[162:165], v[114:117]
	v_mfma_f32_16x16x32_f16 v[102:105], v[194:197], v[170:173], v[102:105]
	v_mfma_f32_16x16x32_f16 v[98:101], v[202:205], v[170:173], v[98:101]
	v_mfma_f32_16x16x32_f16 v[86:89], v[194:197], v[178:181], v[86:89]
	v_mfma_f32_16x16x32_f16 v[82:85], v[202:205], v[178:181], v[82:85]
	v_mfma_f32_16x16x32_f16 v[70:73], v[194:197], v[186:189], v[70:73]
	v_mfma_f32_16x16x32_f16 v[66:69], v[202:205], v[186:189], v[66:69]
	v_mfma_f32_16x16x32_f16 v[118:121], v[198:201], v[166:169], v[118:121]
	v_mfma_f32_16x16x32_f16 v[114:117], v[220:223], v[166:169], v[114:117]
	v_mfma_f32_16x16x32_f16 v[102:105], v[198:201], v[174:177], v[102:105]
	v_mfma_f32_16x16x32_f16 v[98:101], v[220:223], v[174:177], v[98:101]
	v_mfma_f32_16x16x32_f16 v[86:89], v[198:201], v[182:185], v[86:89]
	v_mfma_f32_16x16x32_f16 v[82:85], v[220:223], v[182:185], v[82:85]
	v_mfma_f32_16x16x32_f16 v[70:73], v[198:201], v[190:193], v[70:73]
	v_mfma_f32_16x16x32_f16 v[66:69], v[220:223], v[190:193], v[66:69]
	s_barrier
	v_lshl_add_u64 v[144:145], s[46:47], 0, v[0:1]
	s_mov_b32 m0, s60
	v_lshl_add_u64 v[206:207], s[46:47], 0, v[134:135]
	global_load_lds_dwordx4 v[144:145], off
	s_add_i32 m0, s60, 0x2000
	s_nop 0
	global_load_lds_dwordx4 v[206:207], off
	s_mov_b32 m0, s23
	v_lshl_add_u64 v[212:213], s[48:49], 0, v[130:131]
	ds_read_b128 v[162:165], v149 offset:16384
	ds_read_b128 v[166:169], v149 offset:17408
	ds_read_b128 v[170:173], v149 offset:18432
	ds_read_b128 v[174:177], v149 offset:19456
	ds_read_b128 v[178:181], v149 offset:20480
	ds_read_b128 v[182:185], v149 offset:21504
	ds_read_b128 v[186:189], v149 offset:22528
	ds_read_b128 v[190:193], v149 offset:23552
	global_load_lds_dwordx4 v[212:213], off
	v_lshl_add_u64 v[214:215], s[48:49], 0, v[132:133]
	s_mov_b32 m0, s71
	s_nop 0
	global_load_lds_dwordx4 v[214:215], off
	s_add_u32 s78, s46, 0x80000
	s_addc_u32 s79, s47, 0
	s_add_i32 s60, s66, s64
	v_lshl_add_u64 v[232:233], s[78:79], 0, v[0:1]
	s_mov_b32 m0, s60
	s_nop 0
	global_load_lds_dwordx4 v[232:233], off
	v_lshl_add_u64 v[232:233], s[78:79], 0, v[134:135]
	s_add_i32 m0, s60, 0x2000
	s_nop 0
	global_load_lds_dwordx4 v[232:233], off
	s_waitcnt vmcnt(8) lgkmcnt(0)
	s_barrier
; #define PG8_STAGE(bufoff, gbase, voff) do { _Pragma("unroll") for (int _i = 0; _i < 2; ++_i) \
;         __builtin_amdgcn_global_load_lds((const unsigned*)((const char*)(gbase) + (voff)[_i]), (LAS unsigned*)(lds + (bufoff) + ldsw + _i * 8192), 16, 0, 0); } while (0)
; #define PG8_LDA(dst, b, h) do { _Pragma("unroll") for (int m = 0; m < 4; ++m) _Pragma("unroll") for (int k = 0; k < 2; ++k) dst[m][k] = *(const LAS h16x8*)(lds + PG8_SA(b, h) + aoff + m * 2048 + k * 1024); } while (0)
; #define PG8_LDB(dst, b, h) do { _Pragma("unroll") for (int n = 0; n < 2; ++n) _Pragma("unroll") for (int k = 0; k < 2; ++k) dst[n][k] = *(const LAS h16x8*)(lds + PG8_SB(b, h) + boff + n * 2048 + k * 1024); } while (0)
; #define PG8_MMA(ai, bj, At, Bt_) do { __builtin_amdgcn_s_setprio(1); _Pragma("unroll") for (int m = 0; m < 4; ++m) _Pragma("unroll") for (int n = 0; n < 2; ++n) _Pragma("unroll") for (int k = 0; k < 2; ++k) \
;         acc[ai][bj][m][n] = __builtin_amdgcn_mfma_f32_16x16x32_f16(Bt_[n][k], At[m][k], acc[ai][bj][m][n], 0, 0, 0); __builtin_amdgcn_s_setprio(0); } while (0)
; #define PG8_WAIT_V(n) asm volatile("s_waitcnt vmcnt(" #n ")" ::: "memory")
; #define PG8_WAIT_L(n) asm volatile("s_waitcnt lgkmcnt(" #n ")" ::: "memory")
; #define PG8_BAR __builtin_amdgcn_s_barrier()
; #define PG8_SCHED __builtin_amdgcn_sched_barrier(0)
; template <class Epi, class AMap>
; __device__ __forceinline__ void gemm_phase(LAS unsigned char* lds, const AMap am, const int lda, const h16* Bt, const int ldb, const int M, const int N, const int K, const Epi& E) {
;     ...
;             PG8_WAIT_V(6); PG8_BAR; PG8_MMA(1, 1, At, B1); PG8_BAR;
;             PG8_LDB(B0, 1, 0); PG8_SCHED; PG8_LDA(At, 1, 0); PG8_STAGE(PG8_SA(0, 1), a2 + hstepA, voffA);
;             PG8_WAIT_L(8); PG8_BAR; PG8_WAIT_L(0); PG8_MMA(0, 0, At, B0); PG8_BAR; PG8_SCHED;
;             PG8_LDB(B1, 1, 1); PG8_STAGE(PG8_SB(1, 0), b3, voffB);
;             PG8_BAR; PG8_WAIT_L(0); PG8_MMA(0, 1, At, B1); PG8_BAR;
	v_mfma_f32_16x16x32_f16 v[62:65], v[140:143], v[162:165], v[62:65]
	v_mfma_f32_16x16x32_f16 v[58:61], v[154:157], v[162:165], v[58:61]
	v_mfma_f32_16x16x32_f16 v[46:49], v[140:143], v[170:173], v[46:49]
	v_mfma_f32_16x16x32_f16 v[42:45], v[154:157], v[170:173], v[42:45]
	v_mfma_f32_16x16x32_f16 v[30:33], v[140:143], v[178:181], v[30:33]
	v_mfma_f32_16x16x32_f16 v[26:29], v[154:157], v[178:181], v[26:29]
	v_mfma_f32_16x16x32_f16 v[14:17], v[140:143], v[186:189], v[14:17]
	v_mfma_f32_16x16x32_f16 v[10:13], v[154:157], v[186:189], v[10:13]
	v_mfma_f32_16x16x32_f16 v[62:65], v[150:153], v[166:169], v[62:65]
	v_mfma_f32_16x16x32_f16 v[58:61], v[158:161], v[166:169], v[58:61]
	v_mfma_f32_16x16x32_f16 v[46:49], v[150:153], v[174:177], v[46:49]
	v_mfma_f32_16x16x32_f16 v[42:45], v[158:161], v[174:177], v[42:45]
	v_mfma_f32_16x16x32_f16 v[30:33], v[150:153], v[182:185], v[30:33]
	v_mfma_f32_16x16x32_f16 v[26:29], v[158:161], v[182:185], v[26:29]
	v_mfma_f32_16x16x32_f16 v[14:17], v[150:153], v[190:193], v[14:17]
	v_mfma_f32_16x16x32_f16 v[10:13], v[158:161], v[190:193], v[10:13]
	v_mfma_f32_16x16x32_f16 v[54:57], v[194:197], v[162:165], v[54:57]
	v_mfma_f32_16x16x32_f16 v[50:53], v[202:205], v[162:165], v[50:53]
	v_mfma_f32_16x16x32_f16 v[38:41], v[194:197], v[170:173], v[38:41]
	v_mfma_f32_16x16x32_f16 v[34:37], v[202:205], v[170:173], v[34:37]
	v_mfma_f32_16x16x32_f16 v[22:25], v[194:197], v[178:181], v[22:25]
	v_mfma_f32_16x16x32_f16 v[18:21], v[202:205], v[178:181], v[18:21]
	v_mfma_f32_16x16x32_f16 v[6:9], v[194:197], v[186:189], v[6:9]
	v_mfma_f32_16x16x32_f16 v[2:5], v[202:205], v[186:189], v[2:5]
	v_mfma_f32_16x16x32_f16 v[54:57], v[198:201], v[166:169], v[54:57]
	v_mfma_f32_16x16x32_f16 v[50:53], v[220:223], v[166:169], v[50:53]
	v_mfma_f32_16x16x32_f16 v[38:41], v[198:201], v[174:177], v[38:41]
	v_mfma_f32_16x16x32_f16 v[34:37], v[220:223], v[174:177], v[34:37]
	v_mfma_f32_16x16x32_f16 v[22:25], v[198:201], v[182:185], v[22:25]
	v_mfma_f32_16x16x32_f16 v[18:21], v[220:223], v[182:185], v[18:21]
	v_mfma_f32_16x16x32_f16 v[6:9], v[198:201], v[190:193], v[6:9]
	v_mfma_f32_16x16x32_f16 v[2:5], v[220:223], v[190:193], v[2:5]
	s_barrier
	s_add_i32 s60, 0, 0x18000
	v_add_u32_e32 v234, s60, v147
	ds_read_b128 v[140:143], v234
	ds_read_b128 v[150:153], v234 offset:1024
	ds_read_b128 v[154:157], v234 offset:2048
	ds_read_b128 v[158:161], v234 offset:3072
	s_add_u32 s48, s48, 0x80000
	s_addc_u32 s49, s49, 0
	s_mov_b32 m0, s72
	v_lshl_add_u64 v[232:233], s[48:49], 0, v[130:131]
	ds_read_b128 v[162:165], v149 offset:32768
	ds_read_b128 v[166:169], v149 offset:33792
	ds_read_b128 v[170:173], v149 offset:34816
	ds_read_b128 v[174:177], v149 offset:35840
	ds_read_b128 v[178:181], v149 offset:36864
	ds_read_b128 v[182:185], v149 offset:37888
	ds_read_b128 v[186:189], v149 offset:38912
	ds_read_b128 v[190:193], v149 offset:39936
	global_load_lds_dwordx4 v[232:233], off
	v_lshl_add_u64 v[232:233], s[48:49], 0, v[132:133]
	s_mov_b32 m0, s73
	s_nop 0
	global_load_lds_dwordx4 v[232:233], off
	s_waitcnt lgkmcnt(11)
	s_add_i32 s48, 0, 0x1c000
	s_add_i32 s49, s60, s64
	v_add_u32_e32 v216, s48, v147
	v_lshl_add_u64 v[144:145], v[144:145], 0, s[92:93]
	s_mov_b32 m0, s49
	ds_read_b128 v[194:197], v216
	ds_read_b128 v[198:201], v216 offset:1024
	ds_read_b128 v[202:205], v216 offset:2048
	ds_read_b128 v[220:223], v216 offset:3072
	s_waitcnt vmcnt(8) lgkmcnt(0)
	s_barrier
	v_mfma_f32_16x16x32_f16 v[126:129], v[140:143], v[162:165], v[126:129]
	v_mfma_f32_16x16x32_f16 v[122:125], v[154:157], v[162:165], v[122:125]
	v_mfma_f32_16x16x32_f16 v[110:113], v[140:143], v[170:173], v[110:113]
	v_mfma_f32_16x16x32_f16 v[106:109], v[154:157], v[170:173], v[106:109]
	v_mfma_f32_16x16x32_f16 v[94:97], v[140:143], v[178:181], v[94:97]
	v_mfma_f32_16x16x32_f16 v[90:93], v[154:157], v[178:181], v[90:93]
	v_mfma_f32_16x16x32_f16 v[78:81], v[140:143], v[186:189], v[78:81]
	v_mfma_f32_16x16x32_f16 v[74:77], v[154:157], v[186:189], v[74:77]
	v_mfma_f32_16x16x32_f16 v[126:129], v[150:153], v[166:169], v[126:129]
	v_mfma_f32_16x16x32_f16 v[122:125], v[158:161], v[166:169], v[122:125]
	v_mfma_f32_16x16x32_f16 v[110:113], v[150:153], v[174:177], v[110:113]
	v_mfma_f32_16x16x32_f16 v[106:109], v[158:161], v[174:177], v[106:109]
	v_mfma_f32_16x16x32_f16 v[94:97], v[150:153], v[182:185], v[94:97]
	v_mfma_f32_16x16x32_f16 v[90:93], v[158:161], v[182:185], v[90:93]
	v_mfma_f32_16x16x32_f16 v[78:81], v[150:153], v[190:193], v[78:81]
	v_mfma_f32_16x16x32_f16 v[74:77], v[158:161], v[190:193], v[74:77]
	v_mfma_f32_16x16x32_f16 v[118:121], v[194:197], v[162:165], v[118:121]
	v_mfma_f32_16x16x32_f16 v[114:117], v[202:205], v[162:165], v[114:117]
	v_mfma_f32_16x16x32_f16 v[102:105], v[194:197], v[170:173], v[102:105]
	v_mfma_f32_16x16x32_f16 v[98:101], v[202:205], v[170:173], v[98:101]
	v_mfma_f32_16x16x32_f16 v[86:89], v[194:197], v[178:181], v[86:89]
	v_mfma_f32_16x16x32_f16 v[82:85], v[202:205], v[178:181], v[82:85]
	v_mfma_f32_16x16x32_f16 v[70:73], v[194:197], v[186:189], v[70:73]
	v_mfma_f32_16x16x32_f16 v[66:69], v[202:205], v[186:189], v[66:69]
	v_mfma_f32_16x16x32_f16 v[118:121], v[198:201], v[166:169], v[118:121]
	v_mfma_f32_16x16x32_f16 v[114:117], v[220:223], v[166:169], v[114:117]
	v_mfma_f32_16x16x32_f16 v[102:105], v[198:201], v[174:177], v[102:105]
	v_mfma_f32_16x16x32_f16 v[98:101], v[220:223], v[174:177], v[98:101]
	v_mfma_f32_16x16x32_f16 v[86:89], v[198:201], v[182:185], v[86:89]
	v_mfma_f32_16x16x32_f16 v[82:85], v[220:223], v[182:185], v[82:85]
	v_mfma_f32_16x16x32_f16 v[70:73], v[198:201], v[190:193], v[70:73]
	v_mfma_f32_16x16x32_f16 v[66:69], v[220:223], v[190:193], v[66:69]
	s_barrier
; #define PG8_STAGE(bufoff, gbase, voff) do { _Pragma("unroll") for (int _i = 0; _i < 2; ++_i) \
;         __builtin_amdgcn_global_load_lds((const unsigned*)((const char*)(gbase) + (voff)[_i]), (LAS unsigned*)(lds + (bufoff) + ldsw + _i * 8192), 16, 0, 0); } while (0)
; #define PG8_LDA(dst, b, h) do { _Pragma("unroll") for (int m = 0; m < 4; ++m) _Pragma("unroll") for (int k = 0; k < 2; ++k) dst[m][k] = *(const LAS h16x8*)(lds + PG8_SA(b, h) + aoff + m * 2048 + k * 1024); } while (0)
; #define PG8_MMA(ai, bj, At, Bt_) do { __builtin_amdgcn_s_setprio(1); _Pragma("unroll") for (int m = 0; m < 4; ++m) _Pragma("unroll") for (int n = 0; n < 2; ++n) _Pragma("unroll") for (int k = 0; k < 2; ++k) \
;         acc[ai][bj][m][n] = __builtin_amdgcn_mfma_f32_16x16x32_f16(Bt_[n][k], At[m][k], acc[ai][bj][m][n], 0, 0, 0); __builtin_amdgcn_s_setprio(0); } while (0)
; #define PG8_WAIT_V(n) asm volatile("s_waitcnt vmcnt(" #n ")" ::: "memory")
; #define PG8_WAIT_L(n) asm volatile("s_waitcnt lgkmcnt(" #n ")" ::: "memory")
; #define PG8_BAR __builtin_amdgcn_s_barrier()
; #define PG8_SCHED __builtin_amdgcn_sched_barrier(0)
; template <class Epi, class AMap>
; __device__ __forceinline__ void gemm_phase(LAS unsigned char* lds, const AMap am, const int lda, const h16* Bt, const int ldb, const int M, const int N, const int K, const Epi& E) {
;     ...
;             PG8_LDA(At, 1, 1); PG8_STAGE(PG8_SA(1, 0), a3, voffA);
;             PG8_BAR; PG8_WAIT_L(0); PG8_MMA(1, 0, At, B0); PG8_BAR; PG8_SCHED;
;             PG8_STAGE(PG8_SB(1, 1), b3 + hstepB, voffB);
;             PG8_WAIT_V(6); PG8_BAR; PG8_MMA(1, 1, At, B1); PG8_BAR;
;         }
;     __device__ __forceinline__ void operator()(const f32x4 (&acc)[2][2][4][2], const Unit& u, int wr, int wc, int fr, int fq) const {
;     ...
;             for (int m = 0; m < 4; ++m) { const size_t off = (size_t)(row0 + ai * 128 + m * 16) * DM + colt;
; #pragma unroll
;                 for (int bj = 0; bj < 2; ++bj) {
;                     const h16x8 x = *(const h16x8*)(X + off + bj * 128);
	global_load_lds_dwordx4 v[144:145], off
	v_lshl_add_u64 v[144:145], v[206:207], 0, s[92:93]
	s_add_i32 m0, s49, 0x2000
	s_nop 0
	global_load_lds_dwordx4 v[144:145], off
	s_mov_b32 m0, s74
	v_lshl_add_u64 v[144:145], v[212:213], 0, s[92:93]
	ds_read_b128 v[162:165], v149 offset:49152
	ds_read_b128 v[166:169], v149 offset:50176
	ds_read_b128 v[170:173], v149 offset:51200
	ds_read_b128 v[174:177], v149 offset:52224
	ds_read_b128 v[178:181], v149 offset:53248
	ds_read_b128 v[182:185], v149 offset:54272
	ds_read_b128 v[186:189], v149 offset:55296
	ds_read_b128 v[190:193], v149 offset:56320
	global_load_lds_dwordx4 v[144:145], off
	v_lshl_add_u64 v[144:145], v[214:215], 0, s[92:93]
	s_mov_b32 m0, s75
	s_nop 0
	global_load_lds_dwordx4 v[144:145], off
	s_add_u32 s46, s46, 0x80080
	s_addc_u32 s47, s47, 0
	s_add_i32 s48, s48, s64
	v_lshl_add_u64 v[232:233], s[46:47], 0, v[0:1]
	s_mov_b32 m0, s48
	s_nop 0
	global_load_lds_dwordx4 v[232:233], off
	v_lshl_add_u64 v[232:233], s[46:47], 0, v[134:135]
	s_add_i32 m0, s48, 0x2000
	s_nop 0
	global_load_lds_dwordx4 v[232:233], off
	s_add_i32 s51, s51, 2
	s_add_u32 s26, s26, 0x100
	s_addc_u32 s27, s27, 0
	s_add_u32 s21, s21, 0x100
	s_addc_u32 s50, s50, 0
	s_cmp_gt_u32 s51, 29
	s_waitcnt vmcnt(8) lgkmcnt(0)
	s_barrier
	v_mfma_f32_16x16x32_f16 v[62:65], v[140:143], v[162:165], v[62:65]
	v_mfma_f32_16x16x32_f16 v[58:61], v[154:157], v[162:165], v[58:61]
	v_mfma_f32_16x16x32_f16 v[46:49], v[140:143], v[170:173], v[46:49]
	v_mfma_f32_16x16x32_f16 v[42:45], v[154:157], v[170:173], v[42:45]
	v_mfma_f32_16x16x32_f16 v[30:33], v[140:143], v[178:181], v[30:33]
	v_mfma_f32_16x16x32_f16 v[26:29], v[154:157], v[178:181], v[26:29]
	v_mfma_f32_16x16x32_f16 v[14:17], v[140:143], v[186:189], v[14:17]
	v_mfma_f32_16x16x32_f16 v[10:13], v[154:157], v[186:189], v[10:13]
	v_mfma_f32_16x16x32_f16 v[62:65], v[150:153], v[166:169], v[62:65]
	v_mfma_f32_16x16x32_f16 v[58:61], v[158:161], v[166:169], v[58:61]
	v_mfma_f32_16x16x32_f16 v[46:49], v[150:153], v[174:177], v[46:49]
	v_mfma_f32_16x16x32_f16 v[42:45], v[158:161], v[174:177], v[42:45]
	v_mfma_f32_16x16x32_f16 v[30:33], v[150:153], v[182:185], v[30:33]
	v_mfma_f32_16x16x32_f16 v[26:29], v[158:161], v[182:185], v[26:29]
	v_mfma_f32_16x16x32_f16 v[14:17], v[150:153], v[190:193], v[14:17]
	v_mfma_f32_16x16x32_f16 v[10:13], v[158:161], v[190:193], v[10:13]
	v_mfma_f32_16x16x32_f16 v[54:57], v[194:197], v[162:165], v[54:57]
	v_mfma_f32_16x16x32_f16 v[50:53], v[202:205], v[162:165], v[50:53]
	v_mfma_f32_16x16x32_f16 v[38:41], v[194:197], v[170:173], v[38:41]
	v_mfma_f32_16x16x32_f16 v[34:37], v[202:205], v[170:173], v[34:37]
	v_mfma_f32_16x16x32_f16 v[22:25], v[194:197], v[178:181], v[22:25]
	v_mfma_f32_16x16x32_f16 v[18:21], v[202:205], v[178:181], v[18:21]
	v_mfma_f32_16x16x32_f16 v[6:9], v[194:197], v[186:189], v[6:9]
	v_mfma_f32_16x16x32_f16 v[2:5], v[202:205], v[186:189], v[2:5]
	v_mfma_f32_16x16x32_f16 v[54:57], v[198:201], v[166:169], v[54:57]
	v_mfma_f32_16x16x32_f16 v[50:53], v[220:223], v[166:169], v[50:53]
	v_mfma_f32_16x16x32_f16 v[38:41], v[198:201], v[174:177], v[38:41]
	v_mfma_f32_16x16x32_f16 v[34:37], v[220:223], v[174:177], v[34:37]
	v_mfma_f32_16x16x32_f16 v[22:25], v[198:201], v[182:185], v[22:25]
	v_mfma_f32_16x16x32_f16 v[18:21], v[220:223], v[182:185], v[18:21]
	v_mfma_f32_16x16x32_f16 v[6:9], v[198:201], v[190:193], v[6:9]
	v_mfma_f32_16x16x32_f16 v[2:5], v[220:223], v[190:193], v[2:5]
	s_barrier
	s_cbranch_scc0 .LBB0_147
	v_lshl_add_u32 v144, s22, 8, v146
	v_lshl_or_b32 v142, s35, 8, v148
	v_ashrrev_i32_e32 v145, 31, v144
	v_ashrrev_i32_e32 v143, 31, v142
	v_lshlrev_b64 v[140:141], 11, v[144:145]
	v_lshl_add_u64 v[140:141], v[140:141], 0, v[142:143]
	v_lshlrev_b64 v[140:141], 1, v[140:141]
	v_lshl_add_u64 v[154:155], s[94:95], 0, v[140:141]
	s_mov_b32 s101, 0
	global_load_dwordx4 v[158:161], v[154:155], off
	global_load_dwordx4 v[162:165], v[154:155], off offset:256
	s_mov_b32 s100, 0x10000
	v_lshl_add_u64 v[232:233], v[154:155], 0, s[100:101]
	global_load_dwordx4 v[166:169], v[232:233], off
	global_load_dwordx4 v[170:173], v[232:233], off offset:256
	s_mov_b32 s100, 0x20000
	v_lshl_add_u64 v[232:233], v[154:155], 0, s[100:101]
	global_load_dwordx4 v[174:177], v[232:233], off
	global_load_dwordx4 v[178:181], v[232:233], off offset:256
	s_mov_b32 s100, 0x30000
	v_lshl_add_u64 v[232:233], v[154:155], 0, s[100:101]
	global_load_dwordx4 v[182:185], v[232:233], off
	global_load_dwordx4 v[186:189], v[232:233], off offset:256
	s_mov_b32 s100, 0x80000
	v_lshl_add_u64 v[232:233], v[154:155], 0, s[100:101]
	global_load_dwordx4 v[190:193], v[232:233], off
	global_load_dwordx4 v[194:197], v[232:233], off offset:256
	s_mov_b32 s100, 0x90000
	v_lshl_add_u64 v[232:233], v[154:155], 0, s[100:101]
	global_load_dwordx4 v[198:201], v[232:233], off
	global_load_dwordx4 v[202:205], v[232:233], off offset:256
	s_mov_b32 s100, 0xa0000
	v_lshl_add_u64 v[232:233], v[154:155], 0, s[100:101]
	global_load_dwordx4 v[212:215], v[232:233], off
	global_load_dwordx4 v[220:223], v[232:233], off offset:256
	s_mov_b32 s100, 0xb0000
	v_lshl_add_u64 v[232:233], v[154:155], 0, s[100:101]
	global_load_dwordx4 v[224:227], v[232:233], off
	global_load_dwordx4 v[228:231], v[232:233], off offset:256
	s_mov_b64 s[2:3], 0xb0000
	s_and_b64 vcc, exec, s[38:39]
	s_mov_b32 s22, s40
	s_mov_b64 s[46:47], s[44:45]
	s_mov_b64 s[26:27], s[42:43]
	s_movk_i32 s66, 0x80
	s_cmpk_gt_u32 s62, 0xff
	s_cbranch_scc1 .Lgx2
	s_barrier
;     __device__ __forceinline__ void operator()(const f32x4 (&acc)[2][2][4][2], const Unit& u, int wr, int wc, int fr, int fq) const {
;     ...
;             for (int m = 0; m < 4; ++m) { const size_t off = (size_t)(row0 + ai * 128 + m * 16) * DM + colt;
; #pragma unroll
;                 for (int bj = 0; bj < 2; ++bj) {
;                     const h16x8 x = *(const h16x8*)(X + off + bj * 128);
;                     f32x4 o0, o1;
; #pragma unroll
;                     for (int e = 0; e < 4; ++e) { o0[e] = (float)x[e] * ALPHA + acc[ai][bj][m][0][e]; o1[e] = (float)x[4 + e] * ALPHA + acc[ai][bj][m][1][e]; }
;                     *(u32x4*)(PRE + off + bj * 128) = pack8(o0, o1); } }
.Lgx2:
	s_waitcnt vmcnt(15)
	v_mov_b64_e32 v[150:151], v[158:159]
	v_mov_b64_e32 v[152:153], v[160:161]
	v_cvt_f32_f16_e32 v156, v150
	v_cvt_f32_f16_sdwa v157, v150 dst_sel:DWORD dst_unused:UNUSED_PAD src0_sel:WORD_1
	v_cvt_f32_f16_e32 v150, v151
	v_cvt_f32_f16_sdwa v151, v151 dst_sel:DWORD dst_unused:UNUSED_PAD src0_sel:WORD_1
	v_pk_fma_f32 v[126:127], v[156:157], s[34:35], v[126:127] op_sel_hi:[1,0,1]
	s_nop 0
	v_cvt_pk_f16_f32 v126, v126, v127
	v_pk_fma_f32 v[128:129], v[150:151], s[34:35], v[128:129] op_sel_hi:[1,0,1]
	v_lshl_add_u64 v[150:151], s[4:5], 0, v[140:141]
	v_cvt_pk_f16_f32 v127, v128, v129
	v_cvt_f32_f16_e32 v128, v152
	v_cvt_f32_f16_sdwa v129, v152 dst_sel:DWORD dst_unused:UNUSED_PAD src0_sel:WORD_1
	v_pk_fma_f32 v[122:123], v[128:129], s[34:35], v[122:123] op_sel_hi:[1,0,1]
	s_nop 0
	v_cvt_pk_f16_f32 v128, v122, v123
	v_cvt_f32_f16_e32 v122, v153
	v_cvt_f32_f16_sdwa v123, v153 dst_sel:DWORD dst_unused:UNUSED_PAD src0_sel:WORD_1
	v_pk_fma_f32 v[122:123], v[122:123], s[34:35], v[124:125] op_sel_hi:[1,0,1]
	s_nop 0
	v_cvt_pk_f16_f32 v129, v122, v123
	s_nop 0
	global_store_dwordx4 v[150:151], v[126:129], off
	s_waitcnt vmcnt(15)
	v_mov_b64_e32 v[122:123], v[162:163]
	v_mov_b64_e32 v[124:125], v[164:165]
	s_nop 0
	v_cvt_f32_f16_e32 v126, v122
	v_cvt_f32_f16_sdwa v127, v122 dst_sel:DWORD dst_unused:UNUSED_PAD src0_sel:WORD_1
	v_cvt_f32_f16_e32 v122, v123
	v_cvt_f32_f16_sdwa v123, v123 dst_sel:DWORD dst_unused:UNUSED_PAD src0_sel:WORD_1
	v_pk_fma_f32 v[118:119], v[126:127], s[34:35], v[118:119] op_sel_hi:[1,0,1]
	s_nop 0
	v_cvt_pk_f16_f32 v118, v118, v119
	v_pk_fma_f32 v[120:121], v[122:123], s[34:35], v[120:121] op_sel_hi:[1,0,1]
	s_nop 0
	v_cvt_pk_f16_f32 v119, v120, v121
	v_cvt_f32_f16_e32 v120, v124
	v_cvt_f32_f16_sdwa v121, v124 dst_sel:DWORD dst_unused:UNUSED_PAD src0_sel:WORD_1
	v_pk_fma_f32 v[114:115], v[120:121], s[34:35], v[114:115] op_sel_hi:[1,0,1]
	s_nop 0
	v_cvt_pk_f16_f32 v120, v114, v115
	v_cvt_f32_f16_e32 v114, v125
	v_cvt_f32_f16_sdwa v115, v125 dst_sel:DWORD dst_unused:UNUSED_PAD src0_sel:WORD_1
	v_pk_fma_f32 v[114:115], v[114:115], s[34:35], v[116:117] op_sel_hi:[1,0,1]
	s_nop 0
	v_cvt_pk_f16_f32 v121, v114, v115
	v_or_b32_e32 v114, 16, v144
	v_ashrrev_i32_e32 v115, 31, v114
	v_lshlrev_b64 v[114:115], 11, v[114:115]
	v_lshl_add_u64 v[114:115], v[114:115], 0, v[142:143]
	global_store_dwordx4 v[150:151], v[118:121], off offset:256
	s_nop 1
	v_lshlrev_b64 v[118:119], 1, v[114:115]
	v_lshl_add_u64 v[120:121], s[94:95], 0, v[118:119]
	s_waitcnt vmcnt(15)
	v_mov_b64_e32 v[114:115], v[166:167]
	v_mov_b64_e32 v[116:117], v[168:169]
	v_cvt_f32_f16_e32 v122, v114
	v_cvt_f32_f16_sdwa v123, v114 dst_sel:DWORD dst_unused:UNUSED_PAD src0_sel:WORD_1
	v_cvt_f32_f16_e32 v114, v115
	v_cvt_f32_f16_sdwa v115, v115 dst_sel:DWORD dst_unused:UNUSED_PAD src0_sel:WORD_1
	v_pk_fma_f32 v[110:111], v[122:123], s[34:35], v[110:111] op_sel_hi:[1,0,1]
	s_nop 0
	v_cvt_pk_f16_f32 v110, v110, v111
	v_pk_fma_f32 v[112:113], v[114:115], s[34:35], v[112:113] op_sel_hi:[1,0,1]
	v_lshl_add_u64 v[114:115], s[4:5], 0, v[118:119]
	v_cvt_pk_f16_f32 v111, v112, v113
	v_cvt_f32_f16_e32 v112, v116
	v_cvt_f32_f16_sdwa v113, v116 dst_sel:DWORD dst_unused:UNUSED_PAD src0_sel:WORD_1
	v_pk_fma_f32 v[106:107], v[112:113], s[34:35], v[106:107] op_sel_hi:[1,0,1]
	s_nop 0
	v_cvt_pk_f16_f32 v112, v106, v107
	v_cvt_f32_f16_e32 v106, v117
	v_cvt_f32_f16_sdwa v107, v117 dst_sel:DWORD dst_unused:UNUSED_PAD src0_sel:WORD_1
	v_pk_fma_f32 v[106:107], v[106:107], s[34:35], v[108:109] op_sel_hi:[1,0,1]
	s_nop 0
	v_cvt_pk_f16_f32 v113, v106, v107
	s_nop 0
	global_store_dwordx4 v[114:115], v[110:113], off
	s_waitcnt vmcnt(15)
	v_mov_b64_e32 v[106:107], v[170:171]
	v_mov_b64_e32 v[108:109], v[172:173]
	s_nop 0
	v_cvt_f32_f16_e32 v110, v106
	v_cvt_f32_f16_sdwa v111, v106 dst_sel:DWORD dst_unused:UNUSED_PAD src0_sel:WORD_1
	v_cvt_f32_f16_e32 v106, v107
	v_cvt_f32_f16_sdwa v107, v107 dst_sel:DWORD dst_unused:UNUSED_PAD src0_sel:WORD_1
	v_pk_fma_f32 v[102:103], v[110:111], s[34:35], v[102:103] op_sel_hi:[1,0,1]
	s_nop 0
	v_cvt_pk_f16_f32 v102, v102, v103
	v_pk_fma_f32 v[104:105], v[106:107], s[34:35], v[104:105] op_sel_hi:[1,0,1]
	s_nop 0
	v_cvt_pk_f16_f32 v103, v104, v105
	v_cvt_f32_f16_e32 v104, v108
	v_cvt_f32_f16_sdwa v105, v108 dst_sel:DWORD dst_unused:UNUSED_PAD src0_sel:WORD_1
	v_pk_fma_f32 v[98:99], v[104:105], s[34:35], v[98:99] op_sel_hi:[1,0,1]
	s_nop 0
	v_cvt_pk_f16_f32 v104, v98, v99
	v_cvt_f32_f16_e32 v98, v109
	v_cvt_f32_f16_sdwa v99, v109 dst_sel:DWORD dst_unused:UNUSED_PAD src0_sel:WORD_1
	v_pk_fma_f32 v[98:99], v[98:99], s[34:35], v[100:101] op_sel_hi:[1,0,1]
	s_nop 0
	v_cvt_pk_f16_f32 v105, v98, v99
	v_or_b32_e32 v98, 32, v144
	v_ashrrev_i32_e32 v99, 31, v98
	v_lshlrev_b64 v[98:99], 11, v[98:99]
	v_lshl_add_u64 v[98:99], v[98:99], 0, v[142:143]
	global_store_dwordx4 v[114:115], v[102:105], off offset:256
	s_nop 1
	v_lshlrev_b64 v[102:103], 1, v[98:99]
	v_lshl_add_u64 v[104:105], s[94:95], 0, v[102:103]
	s_waitcnt vmcnt(15)
	v_mov_b64_e32 v[98:99], v[174:175]
	v_mov_b64_e32 v[100:101], v[176:177]
	v_cvt_f32_f16_e32 v106, v98
	v_cvt_f32_f16_sdwa v107, v98 dst_sel:DWORD dst_unused:UNUSED_PAD src0_sel:WORD_1
	v_cvt_f32_f16_e32 v98, v99
	v_cvt_f32_f16_sdwa v99, v99 dst_sel:DWORD dst_unused:UNUSED_PAD src0_sel:WORD_1
	v_pk_fma_f32 v[94:95], v[106:107], s[34:35], v[94:95] op_sel_hi:[1,0,1]
	s_nop 0
	v_cvt_pk_f16_f32 v94, v94, v95
	v_pk_fma_f32 v[96:97], v[98:99], s[34:35], v[96:97] op_sel_hi:[1,0,1]
	v_lshl_add_u64 v[98:99], s[4:5], 0, v[102:103]
	v_cvt_pk_f16_f32 v95, v96, v97
	v_cvt_f32_f16_e32 v96, v100
	v_cvt_f32_f16_sdwa v97, v100 dst_sel:DWORD dst_unused:UNUSED_PAD src0_sel:WORD_1
	v_pk_fma_f32 v[90:91], v[96:97], s[34:35], v[90:91] op_sel_hi:[1,0,1]
	s_nop 0
	v_cvt_pk_f16_f32 v96, v90, v91
	v_cvt_f32_f16_e32 v90, v101
	v_cvt_f32_f16_sdwa v91, v101 dst_sel:DWORD dst_unused:UNUSED_PAD src0_sel:WORD_1
	v_pk_fma_f32 v[90:91], v[90:91], s[34:35], v[92:93] op_sel_hi:[1,0,1]
	s_nop 0
	v_cvt_pk_f16_f32 v97, v90, v91
	s_nop 0
	global_store_dwordx4 v[98:99], v[94:97], off
	s_waitcnt vmcnt(15)
;     __device__ __forceinline__ void operator()(const f32x4 (&acc)[2][2][4][2], const Unit& u, int wr, int wc, int fr, int fq) const {
;     ...
;             for (int m = 0; m < 4; ++m) { const size_t off = (size_t)(row0 + ai * 128 + m * 16) * DM + colt;
; #pragma unroll
;                 for (int bj = 0; bj < 2; ++bj) {
;                     const h16x8 x = *(const h16x8*)(X + off + bj * 128);
;                     f32x4 o0, o1;
; #pragma unroll
;                     for (int e = 0; e < 4; ++e) { o0[e] = (float)x[e] * ALPHA + acc[ai][bj][m][0][e]; o1[e] = (float)x[4 + e] * ALPHA + acc[ai][bj][m][1][e]; }
;                     *(u32x4*)(PRE + off + bj * 128) = pack8(o0, o1); } }
	v_mov_b64_e32 v[90:91], v[178:179]
	v_mov_b64_e32 v[92:93], v[180:181]
	s_nop 0
	v_cvt_f32_f16_e32 v94, v90
	v_cvt_f32_f16_sdwa v95, v90 dst_sel:DWORD dst_unused:UNUSED_PAD src0_sel:WORD_1
	v_cvt_f32_f16_e32 v90, v91
	v_cvt_f32_f16_sdwa v91, v91 dst_sel:DWORD dst_unused:UNUSED_PAD src0_sel:WORD_1
	v_pk_fma_f32 v[86:87], v[94:95], s[34:35], v[86:87] op_sel_hi:[1,0,1]
	s_nop 0
	v_cvt_pk_f16_f32 v86, v86, v87
	v_pk_fma_f32 v[88:89], v[90:91], s[34:35], v[88:89] op_sel_hi:[1,0,1]
	s_nop 0
	v_cvt_pk_f16_f32 v87, v88, v89
	v_cvt_f32_f16_e32 v88, v92
	v_cvt_f32_f16_sdwa v89, v92 dst_sel:DWORD dst_unused:UNUSED_PAD src0_sel:WORD_1
	v_pk_fma_f32 v[82:83], v[88:89], s[34:35], v[82:83] op_sel_hi:[1,0,1]
	s_nop 0
	v_cvt_pk_f16_f32 v88, v82, v83
	v_cvt_f32_f16_e32 v82, v93
	v_cvt_f32_f16_sdwa v83, v93 dst_sel:DWORD dst_unused:UNUSED_PAD src0_sel:WORD_1
	v_pk_fma_f32 v[82:83], v[82:83], s[34:35], v[84:85] op_sel_hi:[1,0,1]
	s_nop 0
	v_cvt_pk_f16_f32 v89, v82, v83
	v_or_b32_e32 v82, 48, v144
	v_ashrrev_i32_e32 v83, 31, v82
	v_lshlrev_b64 v[82:83], 11, v[82:83]
	v_lshl_add_u64 v[82:83], v[82:83], 0, v[142:143]
	global_store_dwordx4 v[98:99], v[86:89], off offset:256
	s_nop 1
	v_lshlrev_b64 v[86:87], 1, v[82:83]
	v_lshl_add_u64 v[88:89], s[94:95], 0, v[86:87]
	s_waitcnt vmcnt(15)
	v_mov_b64_e32 v[82:83], v[182:183]
	v_mov_b64_e32 v[84:85], v[184:185]
	v_cvt_f32_f16_e32 v90, v82
	v_cvt_f32_f16_sdwa v91, v82 dst_sel:DWORD dst_unused:UNUSED_PAD src0_sel:WORD_1
	v_cvt_f32_f16_e32 v82, v83
	v_cvt_f32_f16_sdwa v83, v83 dst_sel:DWORD dst_unused:UNUSED_PAD src0_sel:WORD_1
	v_pk_fma_f32 v[78:79], v[90:91], s[34:35], v[78:79] op_sel_hi:[1,0,1]
	s_nop 0
	v_cvt_pk_f16_f32 v78, v78, v79
	v_pk_fma_f32 v[80:81], v[82:83], s[34:35], v[80:81] op_sel_hi:[1,0,1]
	v_lshl_add_u64 v[82:83], s[4:5], 0, v[86:87]
	v_cvt_pk_f16_f32 v79, v80, v81
	v_cvt_f32_f16_e32 v80, v84
	v_cvt_f32_f16_sdwa v81, v84 dst_sel:DWORD dst_unused:UNUSED_PAD src0_sel:WORD_1
	v_pk_fma_f32 v[74:75], v[80:81], s[34:35], v[74:75] op_sel_hi:[1,0,1]
	s_nop 0
	v_cvt_pk_f16_f32 v80, v74, v75
	v_cvt_f32_f16_e32 v74, v85
	v_cvt_f32_f16_sdwa v75, v85 dst_sel:DWORD dst_unused:UNUSED_PAD src0_sel:WORD_1
	v_pk_fma_f32 v[74:75], v[74:75], s[34:35], v[76:77] op_sel_hi:[1,0,1]
	s_nop 0
	v_cvt_pk_f16_f32 v81, v74, v75
	s_nop 0
	global_store_dwordx4 v[82:83], v[78:81], off
	s_waitcnt vmcnt(15)
	v_mov_b64_e32 v[74:75], v[186:187]
	v_mov_b64_e32 v[76:77], v[188:189]
	s_nop 0
	v_cvt_f32_f16_e32 v78, v74
	v_cvt_f32_f16_sdwa v79, v74 dst_sel:DWORD dst_unused:UNUSED_PAD src0_sel:WORD_1
	v_cvt_f32_f16_e32 v74, v75
	v_cvt_f32_f16_sdwa v75, v75 dst_sel:DWORD dst_unused:UNUSED_PAD src0_sel:WORD_1
	v_pk_fma_f32 v[70:71], v[78:79], s[34:35], v[70:71] op_sel_hi:[1,0,1]
	s_nop 0
	v_cvt_pk_f16_f32 v70, v70, v71
	v_pk_fma_f32 v[72:73], v[74:75], s[34:35], v[72:73] op_sel_hi:[1,0,1]
	s_nop 0
	v_cvt_pk_f16_f32 v71, v72, v73
	v_cvt_f32_f16_e32 v72, v76
	v_cvt_f32_f16_sdwa v73, v76 dst_sel:DWORD dst_unused:UNUSED_PAD src0_sel:WORD_1
	v_pk_fma_f32 v[66:67], v[72:73], s[34:35], v[66:67] op_sel_hi:[1,0,1]
	s_nop 0
	v_cvt_pk_f16_f32 v72, v66, v67
	v_cvt_f32_f16_e32 v66, v77
	v_cvt_f32_f16_sdwa v67, v77 dst_sel:DWORD dst_unused:UNUSED_PAD src0_sel:WORD_1
	v_pk_fma_f32 v[66:67], v[66:67], s[34:35], v[68:69] op_sel_hi:[1,0,1]
	s_nop 0
	v_cvt_pk_f16_f32 v73, v66, v67
	global_store_dwordx4 v[82:83], v[70:73], off offset:256
	s_nop 1
	v_lshl_add_u64 v[70:71], v[140:141], 0, s[16:17]
	v_lshl_add_u64 v[72:73], s[94:95], 0, v[70:71]
	s_waitcnt vmcnt(15)
	v_mov_b64_e32 v[66:67], v[190:191]
	v_mov_b64_e32 v[68:69], v[192:193]
	v_cvt_f32_f16_e32 v74, v66
	v_cvt_f32_f16_sdwa v75, v66 dst_sel:DWORD dst_unused:UNUSED_PAD src0_sel:WORD_1
	v_cvt_f32_f16_e32 v66, v67
	v_cvt_f32_f16_sdwa v67, v67 dst_sel:DWORD dst_unused:UNUSED_PAD src0_sel:WORD_1
	v_pk_fma_f32 v[62:63], v[74:75], s[34:35], v[62:63] op_sel_hi:[1,0,1]
	s_nop 0
	v_cvt_pk_f16_f32 v62, v62, v63
	v_pk_fma_f32 v[64:65], v[66:67], s[34:35], v[64:65] op_sel_hi:[1,0,1]
	v_lshl_add_u64 v[66:67], s[4:5], 0, v[70:71]
	v_cvt_pk_f16_f32 v63, v64, v65
	v_cvt_f32_f16_e32 v64, v68
	v_cvt_f32_f16_sdwa v65, v68 dst_sel:DWORD dst_unused:UNUSED_PAD src0_sel:WORD_1
	v_pk_fma_f32 v[58:59], v[64:65], s[34:35], v[58:59] op_sel_hi:[1,0,1]
	s_nop 0
	v_cvt_pk_f16_f32 v64, v58, v59
	v_cvt_f32_f16_e32 v58, v69
	v_cvt_f32_f16_sdwa v59, v69 dst_sel:DWORD dst_unused:UNUSED_PAD src0_sel:WORD_1
	v_pk_fma_f32 v[58:59], v[58:59], s[34:35], v[60:61] op_sel_hi:[1,0,1]
	s_nop 0
	v_cvt_pk_f16_f32 v65, v58, v59
	s_nop 0
	global_store_dwordx4 v[66:67], v[62:65], off
	s_waitcnt vmcnt(15)
	v_mov_b64_e32 v[58:59], v[194:195]
	v_mov_b64_e32 v[60:61], v[196:197]
	s_nop 0
	v_cvt_f32_f16_e32 v62, v58
	v_cvt_f32_f16_sdwa v63, v58 dst_sel:DWORD dst_unused:UNUSED_PAD src0_sel:WORD_1
	v_cvt_f32_f16_e32 v58, v59
	v_cvt_f32_f16_sdwa v59, v59 dst_sel:DWORD dst_unused:UNUSED_PAD src0_sel:WORD_1
	v_pk_fma_f32 v[54:55], v[62:63], s[34:35], v[54:55] op_sel_hi:[1,0,1]
	s_nop 0
	v_cvt_pk_f16_f32 v54, v54, v55
	v_pk_fma_f32 v[56:57], v[58:59], s[34:35], v[56:57] op_sel_hi:[1,0,1]
	s_nop 0
	v_cvt_pk_f16_f32 v55, v56, v57
	v_cvt_f32_f16_e32 v56, v60
	v_cvt_f32_f16_sdwa v57, v60 dst_sel:DWORD dst_unused:UNUSED_PAD src0_sel:WORD_1
	v_pk_fma_f32 v[50:51], v[56:57], s[34:35], v[50:51] op_sel_hi:[1,0,1]
	s_nop 0
	v_cvt_pk_f16_f32 v56, v50, v51
	v_cvt_f32_f16_e32 v50, v61
	v_cvt_f32_f16_sdwa v51, v61 dst_sel:DWORD dst_unused:UNUSED_PAD src0_sel:WORD_1
	v_pk_fma_f32 v[50:51], v[50:51], s[34:35], v[52:53] op_sel_hi:[1,0,1]
	s_nop 0
	v_cvt_pk_f16_f32 v57, v50, v51
	global_store_dwordx4 v[66:67], v[54:57], off offset:256
	s_nop 1
	v_lshl_add_u64 v[54:55], v[140:141], 0, s[18:19]
	v_lshl_add_u64 v[56:57], s[94:95], 0, v[54:55]
	s_waitcnt vmcnt(15)
; template <class Epi, class AMap>
; __device__ __forceinline__ void gemm_phase(LAS unsigned char* lds, const AMap am, const int lda, const h16* Bt, const int ldb, const int M, const int N, const int K, const Epi& E) {
;     ...
;         if (!has_next) break;
; #pragma unroll
;         for (int a = 0; a < 2; ++a)
; #pragma unroll
;             for (int b = 0; b < 2; ++b)
; #pragma unroll
;                 for (int m = 0; m < 4; ++m)
; #pragma unroll
;                     for (int n = 0; n < 2; ++n) acc[a][b][m][n] = (f32x4){0.f, 0.f, 0.f, 0.f};
;         cur = nxt; cA = nA; cB = nB; ++ui;
;     __device__ __forceinline__ void operator()(const f32x4 (&acc)[2][2][4][2], const Unit& u, int wr, int wc, int fr, int fq) const {
;     ...
;             for (int m = 0; m < 4; ++m) { const size_t off = (size_t)(row0 + ai * 128 + m * 16) * DM + colt;
; #pragma unroll
;                 for (int bj = 0; bj < 2; ++bj) {
;                     const h16x8 x = *(const h16x8*)(X + off + bj * 128);
;                     f32x4 o0, o1;
; #pragma unroll
;                     for (int e = 0; e < 4; ++e) { o0[e] = (float)x[e] * ALPHA + acc[ai][bj][m][0][e]; o1[e] = (float)x[4 + e] * ALPHA + acc[ai][bj][m][1][e]; }
;                     *(u32x4*)(PRE + off + bj * 128) = pack8(o0, o1); } }
	v_mov_b64_e32 v[50:51], v[198:199]
	v_mov_b64_e32 v[52:53], v[200:201]
	v_cvt_f32_f16_e32 v58, v50
	v_cvt_f32_f16_sdwa v59, v50 dst_sel:DWORD dst_unused:UNUSED_PAD src0_sel:WORD_1
	v_cvt_f32_f16_e32 v50, v51
	v_cvt_f32_f16_sdwa v51, v51 dst_sel:DWORD dst_unused:UNUSED_PAD src0_sel:WORD_1
	v_pk_fma_f32 v[46:47], v[58:59], s[34:35], v[46:47] op_sel_hi:[1,0,1]
	s_nop 0
	v_cvt_pk_f16_f32 v46, v46, v47
	v_pk_fma_f32 v[48:49], v[50:51], s[34:35], v[48:49] op_sel_hi:[1,0,1]
	v_lshl_add_u64 v[50:51], s[4:5], 0, v[54:55]
	v_cvt_pk_f16_f32 v47, v48, v49
	v_cvt_f32_f16_e32 v48, v52
	v_cvt_f32_f16_sdwa v49, v52 dst_sel:DWORD dst_unused:UNUSED_PAD src0_sel:WORD_1
	v_pk_fma_f32 v[42:43], v[48:49], s[34:35], v[42:43] op_sel_hi:[1,0,1]
	s_nop 0
	v_cvt_pk_f16_f32 v48, v42, v43
	v_cvt_f32_f16_e32 v42, v53
	v_cvt_f32_f16_sdwa v43, v53 dst_sel:DWORD dst_unused:UNUSED_PAD src0_sel:WORD_1
	v_pk_fma_f32 v[42:43], v[42:43], s[34:35], v[44:45] op_sel_hi:[1,0,1]
	s_nop 0
	v_cvt_pk_f16_f32 v49, v42, v43
	s_nop 0
	global_store_dwordx4 v[50:51], v[46:49], off
	s_waitcnt vmcnt(15)
	v_mov_b64_e32 v[42:43], v[202:203]
	v_mov_b64_e32 v[44:45], v[204:205]
	s_nop 0
	v_cvt_f32_f16_e32 v46, v42
	v_cvt_f32_f16_sdwa v47, v42 dst_sel:DWORD dst_unused:UNUSED_PAD src0_sel:WORD_1
	v_cvt_f32_f16_e32 v42, v43
	v_cvt_f32_f16_sdwa v43, v43 dst_sel:DWORD dst_unused:UNUSED_PAD src0_sel:WORD_1
	v_pk_fma_f32 v[38:39], v[46:47], s[34:35], v[38:39] op_sel_hi:[1,0,1]
	s_nop 0
	v_cvt_pk_f16_f32 v38, v38, v39
	v_pk_fma_f32 v[40:41], v[42:43], s[34:35], v[40:41] op_sel_hi:[1,0,1]
	s_nop 0
	v_cvt_pk_f16_f32 v39, v40, v41
	v_cvt_f32_f16_e32 v40, v44
	v_cvt_f32_f16_sdwa v41, v44 dst_sel:DWORD dst_unused:UNUSED_PAD src0_sel:WORD_1
	v_pk_fma_f32 v[34:35], v[40:41], s[34:35], v[34:35] op_sel_hi:[1,0,1]
	s_nop 0
	v_cvt_pk_f16_f32 v40, v34, v35
	v_cvt_f32_f16_e32 v34, v45
	v_cvt_f32_f16_sdwa v35, v45 dst_sel:DWORD dst_unused:UNUSED_PAD src0_sel:WORD_1
	v_pk_fma_f32 v[34:35], v[34:35], s[34:35], v[36:37] op_sel_hi:[1,0,1]
	s_nop 0
	v_cvt_pk_f16_f32 v41, v34, v35
	global_store_dwordx4 v[50:51], v[38:41], off offset:256
	s_nop 1
	v_lshl_add_u64 v[38:39], v[140:141], 0, s[8:9]
	v_lshl_add_u64 v[40:41], s[94:95], 0, v[38:39]
	s_waitcnt vmcnt(15)
	v_mov_b64_e32 v[34:35], v[212:213]
	v_mov_b64_e32 v[36:37], v[214:215]
	v_cvt_f32_f16_e32 v42, v34
	v_cvt_f32_f16_sdwa v43, v34 dst_sel:DWORD dst_unused:UNUSED_PAD src0_sel:WORD_1
	v_cvt_f32_f16_e32 v34, v35
	v_cvt_f32_f16_sdwa v35, v35 dst_sel:DWORD dst_unused:UNUSED_PAD src0_sel:WORD_1
	v_pk_fma_f32 v[30:31], v[42:43], s[34:35], v[30:31] op_sel_hi:[1,0,1]
	s_nop 0
	v_cvt_pk_f16_f32 v30, v30, v31
	v_pk_fma_f32 v[32:33], v[34:35], s[34:35], v[32:33] op_sel_hi:[1,0,1]
	v_lshl_add_u64 v[34:35], s[4:5], 0, v[38:39]
	v_cvt_pk_f16_f32 v31, v32, v33
	v_cvt_f32_f16_e32 v32, v36
	v_cvt_f32_f16_sdwa v33, v36 dst_sel:DWORD dst_unused:UNUSED_PAD src0_sel:WORD_1
	v_pk_fma_f32 v[26:27], v[32:33], s[34:35], v[26:27] op_sel_hi:[1,0,1]
	s_nop 0
	v_cvt_pk_f16_f32 v32, v26, v27
	v_cvt_f32_f16_e32 v26, v37
	v_cvt_f32_f16_sdwa v27, v37 dst_sel:DWORD dst_unused:UNUSED_PAD src0_sel:WORD_1
	v_pk_fma_f32 v[26:27], v[26:27], s[34:35], v[28:29] op_sel_hi:[1,0,1]
	s_nop 0
	v_cvt_pk_f16_f32 v33, v26, v27
	s_nop 0
	global_store_dwordx4 v[34:35], v[30:33], off
	s_waitcnt vmcnt(15)
	v_mov_b64_e32 v[26:27], v[220:221]
	v_mov_b64_e32 v[28:29], v[222:223]
	s_nop 0
	v_cvt_f32_f16_e32 v30, v26
	v_cvt_f32_f16_sdwa v31, v26 dst_sel:DWORD dst_unused:UNUSED_PAD src0_sel:WORD_1
	v_cvt_f32_f16_e32 v26, v27
	v_cvt_f32_f16_sdwa v27, v27 dst_sel:DWORD dst_unused:UNUSED_PAD src0_sel:WORD_1
	v_pk_fma_f32 v[22:23], v[30:31], s[34:35], v[22:23] op_sel_hi:[1,0,1]
	s_nop 0
	v_cvt_pk_f16_f32 v22, v22, v23
	v_pk_fma_f32 v[24:25], v[26:27], s[34:35], v[24:25] op_sel_hi:[1,0,1]
	s_nop 0
	v_cvt_pk_f16_f32 v23, v24, v25
	v_cvt_f32_f16_e32 v24, v28
	v_cvt_f32_f16_sdwa v25, v28 dst_sel:DWORD dst_unused:UNUSED_PAD src0_sel:WORD_1
	v_pk_fma_f32 v[18:19], v[24:25], s[34:35], v[18:19] op_sel_hi:[1,0,1]
	s_nop 0
	v_cvt_pk_f16_f32 v24, v18, v19
	v_cvt_f32_f16_e32 v18, v29
	v_cvt_f32_f16_sdwa v19, v29 dst_sel:DWORD dst_unused:UNUSED_PAD src0_sel:WORD_1
	v_pk_fma_f32 v[18:19], v[18:19], s[34:35], v[20:21] op_sel_hi:[1,0,1]
	s_nop 0
	v_cvt_pk_f16_f32 v25, v18, v19
	global_store_dwordx4 v[34:35], v[22:25], off offset:256
	s_nop 1
	v_lshl_add_u64 v[22:23], v[140:141], 0, s[2:3]
	v_lshl_add_u64 v[24:25], s[94:95], 0, v[22:23]
	s_waitcnt vmcnt(15)
	v_mov_b64_e32 v[18:19], v[224:225]
	v_mov_b64_e32 v[20:21], v[226:227]
	v_cvt_f32_f16_e32 v26, v18
	v_cvt_f32_f16_sdwa v27, v18 dst_sel:DWORD dst_unused:UNUSED_PAD src0_sel:WORD_1
	v_cvt_f32_f16_e32 v18, v19
	v_cvt_f32_f16_sdwa v19, v19 dst_sel:DWORD dst_unused:UNUSED_PAD src0_sel:WORD_1
	v_pk_fma_f32 v[14:15], v[26:27], s[34:35], v[14:15] op_sel_hi:[1,0,1]
	s_nop 0
	v_cvt_pk_f16_f32 v14, v14, v15
	v_pk_fma_f32 v[16:17], v[18:19], s[34:35], v[16:17] op_sel_hi:[1,0,1]
	v_lshl_add_u64 v[18:19], s[4:5], 0, v[22:23]
	v_cvt_pk_f16_f32 v15, v16, v17
	v_cvt_f32_f16_e32 v16, v20
	v_cvt_f32_f16_sdwa v17, v20 dst_sel:DWORD dst_unused:UNUSED_PAD src0_sel:WORD_1
	v_pk_fma_f32 v[10:11], v[16:17], s[34:35], v[10:11] op_sel_hi:[1,0,1]
	s_nop 0
	v_cvt_pk_f16_f32 v16, v10, v11
	v_cvt_f32_f16_e32 v10, v21
	v_cvt_f32_f16_sdwa v11, v21 dst_sel:DWORD dst_unused:UNUSED_PAD src0_sel:WORD_1
	v_pk_fma_f32 v[10:11], v[10:11], s[34:35], v[12:13] op_sel_hi:[1,0,1]
	s_nop 0
	v_cvt_pk_f16_f32 v17, v10, v11
	s_nop 0
	global_store_dwordx4 v[18:19], v[14:17], off
	s_waitcnt vmcnt(15)
	v_mov_b64_e32 v[10:11], v[228:229]
	v_mov_b64_e32 v[12:13], v[230:231]
	s_nop 0
	v_cvt_f32_f16_e32 v14, v10
	v_cvt_f32_f16_sdwa v15, v10 dst_sel:DWORD dst_unused:UNUSED_PAD src0_sel:WORD_1
	v_cvt_f32_f16_e32 v10, v11
	v_cvt_f32_f16_sdwa v11, v11 dst_sel:DWORD dst_unused:UNUSED_PAD src0_sel:WORD_1
	v_pk_fma_f32 v[6:7], v[14:15], s[34:35], v[6:7] op_sel_hi:[1,0,1]
	s_nop 0
	v_cvt_pk_f16_f32 v6, v6, v7
	v_pk_fma_f32 v[8:9], v[10:11], s[34:35], v[8:9] op_sel_hi:[1,0,1]
	s_nop 0
	v_cvt_pk_f16_f32 v7, v8, v9
	v_cvt_f32_f16_e32 v8, v12
	v_cvt_f32_f16_sdwa v9, v12 dst_sel:DWORD dst_unused:UNUSED_PAD src0_sel:WORD_1
	v_pk_fma_f32 v[2:3], v[8:9], s[34:35], v[2:3] op_sel_hi:[1,0,1]
	s_nop 0
	v_cvt_pk_f16_f32 v8, v2, v3
	v_cvt_f32_f16_e32 v2, v13
	v_cvt_f32_f16_sdwa v3, v13 dst_sel:DWORD dst_unused:UNUSED_PAD src0_sel:WORD_1
	v_pk_fma_f32 v[2:3], v[2:3], s[34:35], v[4:5] op_sel_hi:[1,0,1]
	s_nop 0
	v_cvt_pk_f16_f32 v9, v2, v3
	s_mov_b32 s35, s0
	global_store_dwordx4 v[18:19], v[6:9], off offset:256
	s_cmpk_lt_u32 s62, 0x100
	s_cbranch_scc1 .Lgy2
	s_barrier

; #define PG8_STAGE(bufoff, gbase, voff) do { _Pragma("unroll") for (int _i = 0; _i < 2; ++_i) \
;         __builtin_amdgcn_global_load_lds((const unsigned*)((const char*)(gbase) + (voff)[_i]), (LAS unsigned*)(lds + (bufoff) + ldsw + _i * 8192), 16, 0, 0); } while (0)
; #define PG8_LDA(dst, b, h) do { _Pragma("unroll") for (int m = 0; m < 4; ++m) _Pragma("unroll") for (int k = 0; k < 2; ++k) dst[m][k] = *(const LAS h16x8*)(lds + PG8_SA(b, h) + aoff + m * 2048 + k * 1024); } while (0)
; #define PG8_LDB(dst, b, h) do { _Pragma("unroll") for (int n = 0; n < 2; ++n) _Pragma("unroll") for (int k = 0; k < 2; ++k) dst[n][k] = *(const LAS h16x8*)(lds + PG8_SB(b, h) + boff + n * 2048 + k * 1024); } while (0)
; #define PG8_MMA(ai, bj, At, Bt_) do { __builtin_amdgcn_s_setprio(1); _Pragma("unroll") for (int m = 0; m < 4; ++m) _Pragma("unroll") for (int n = 0; n < 2; ++n) _Pragma("unroll") for (int k = 0; k < 2; ++k) \
;         acc[ai][bj][m][n] = __builtin_amdgcn_mfma_f32_16x16x32_f16(Bt_[n][k], At[m][k], acc[ai][bj][m][n], 0, 0, 0); __builtin_amdgcn_s_setprio(0); } while (0)
; #define PG8_WAIT_V(n) asm volatile("s_waitcnt vmcnt(" #n ")" ::: "memory")
; template <class Epi, class AMap>
; __device__ __forceinline__ void gemm_phase(LAS unsigned char* lds, const AMap am, const int lda, const h16* Bt, const int ldb, const int M, const int N, const int K, const Epi& E) {
;     ...
;         for (int t = 0; t < nt; t += 2) {
;             const bool last = (t == nt - 2);
;             const char* a1 = cA + (size_t)(t + 1) * kstep;
;             const char* a2 = last ? nA : cA + (size_t)(t + 2) * kstep; const char* b2 = last ? nB : cB + (size_t)(t + 2) * kstep;
;             const char* a3 = a2 + kstep; const char* b3 = b2 + kstep;
;             PG8_LDB(B0, 0, 0); PG8_SCHED; PG8_LDA(At, 0, 0); PG8_STAGE(PG8_SA(1, 1), a1 + hstepA, voffA);
;             PG8_WAIT_L(8); PG8_BAR; PG8_WAIT_L(0); PG8_MMA(0, 0, At, B0); PG8_BAR; PG8_SCHED;
;             PG8_LDB(B1, 0, 1); PG8_STAGE(PG8_SB(0, 0), b2, voffB);
;             PG8_BAR; PG8_WAIT_L(0); PG8_MMA(0, 1, At, B1); PG8_BAR;
;             PG8_LDA(At, 0, 1); PG8_STAGE(PG8_SA(0, 0), a2, voffA);
;             PG8_BAR; PG8_WAIT_L(0); PG8_MMA(1, 0, At, B0); PG8_BAR; PG8_SCHED;
;             PG8_STAGE(PG8_SB(0, 1), b2 + hstepB, voffB);
;             PG8_WAIT_V(6); PG8_BAR; PG8_MMA(1, 1, At, B1); PG8_BAR;
.LBB0_268:
	s_add_u32 s42, s40, 0xfff80080
	s_addc_u32 s43, s41, -1
	s_add_i32 s45, 0, 0x10000
	v_add_u32_e32 v0, s45, v149
	ds_read_b128 v[142:145], v0
	ds_read_b128 v[154:157], v0 offset:1024
	ds_read_b128 v[158:161], v0 offset:2048
	ds_read_b128 v[162:165], v0 offset:3072
	s_cmp_eq_u32 s35, 28
	s_cselect_b32 s49, s23, s43
	s_cselect_b32 s48, s27, s42
	s_cselect_b32 s43, s1, s29
	s_cselect_b32 s42, s20, s21
	v_lshl_add_u64 v[146:147], s[40:41], 0, v[138:139]
	s_add_i32 m0, s72, 0xc000
	ds_read_b128 v[166:169], v153
	ds_read_b128 v[170:173], v153 offset:1024
	ds_read_b128 v[174:177], v153 offset:2048
	ds_read_b128 v[178:181], v153 offset:3072
	ds_read_b128 v[182:185], v153 offset:4096
	ds_read_b128 v[186:189], v153 offset:5120
	ds_read_b128 v[190:193], v153 offset:6144
	ds_read_b128 v[194:197], v153 offset:7168
	global_load_lds_dwordx4 v[146:147], off
	v_lshl_add_u64 v[146:147], s[40:41], 0, v[140:141]
	s_add_i32 m0, s72, 0xe000
	s_nop 0
	global_load_lds_dwordx4 v[146:147], off
	s_waitcnt lgkmcnt(11)
	s_add_i32 s60, 0, 0x14000
	s_add_i32 s45, s45, s65
	v_add_u32_e32 v0, s60, v149
	v_lshl_add_u64 v[146:147], s[42:43], 0, v[132:133]
	s_mov_b32 m0, s45
	ds_read_b128 v[198:201], v0
	ds_read_b128 v[202:205], v0 offset:1024
	ds_read_b128 v[220:223], v0 offset:2048
	ds_read_b128 v[224:227], v0 offset:3072
	s_waitcnt vmcnt(8) lgkmcnt(0)
	s_barrier
	v_mfma_f32_16x16x32_f16 v[126:129], v[142:145], v[166:169], v[126:129]
	v_mfma_f32_16x16x32_f16 v[122:125], v[158:161], v[166:169], v[122:125]
	v_mfma_f32_16x16x32_f16 v[110:113], v[142:145], v[174:177], v[110:113]
	v_mfma_f32_16x16x32_f16 v[106:109], v[158:161], v[174:177], v[106:109]
	v_mfma_f32_16x16x32_f16 v[94:97], v[142:145], v[182:185], v[94:97]
	v_mfma_f32_16x16x32_f16 v[90:93], v[158:161], v[182:185], v[90:93]
	v_mfma_f32_16x16x32_f16 v[78:81], v[142:145], v[190:193], v[78:81]
	v_mfma_f32_16x16x32_f16 v[74:77], v[158:161], v[190:193], v[74:77]
	v_mfma_f32_16x16x32_f16 v[126:129], v[154:157], v[170:173], v[126:129]
	v_mfma_f32_16x16x32_f16 v[122:125], v[162:165], v[170:173], v[122:125]
	v_mfma_f32_16x16x32_f16 v[110:113], v[154:157], v[178:181], v[110:113]
	v_mfma_f32_16x16x32_f16 v[106:109], v[162:165], v[178:181], v[106:109]
	v_mfma_f32_16x16x32_f16 v[94:97], v[154:157], v[186:189], v[94:97]
	v_mfma_f32_16x16x32_f16 v[90:93], v[162:165], v[186:189], v[90:93]
	v_mfma_f32_16x16x32_f16 v[78:81], v[154:157], v[194:197], v[78:81]
	v_mfma_f32_16x16x32_f16 v[74:77], v[162:165], v[194:197], v[74:77]
	v_mfma_f32_16x16x32_f16 v[118:121], v[198:201], v[166:169], v[118:121]
	v_mfma_f32_16x16x32_f16 v[114:117], v[220:223], v[166:169], v[114:117]
	v_mfma_f32_16x16x32_f16 v[102:105], v[198:201], v[174:177], v[102:105]
	v_mfma_f32_16x16x32_f16 v[98:101], v[220:223], v[174:177], v[98:101]
	v_mfma_f32_16x16x32_f16 v[86:89], v[198:201], v[182:185], v[86:89]
	v_mfma_f32_16x16x32_f16 v[82:85], v[220:223], v[182:185], v[82:85]
	v_mfma_f32_16x16x32_f16 v[70:73], v[198:201], v[190:193], v[70:73]
	v_mfma_f32_16x16x32_f16 v[66:69], v[220:223], v[190:193], v[66:69]
	v_mfma_f32_16x16x32_f16 v[118:121], v[202:205], v[170:173], v[118:121]
	v_mfma_f32_16x16x32_f16 v[114:117], v[224:227], v[170:173], v[114:117]
	v_mfma_f32_16x16x32_f16 v[102:105], v[202:205], v[178:181], v[102:105]
	v_mfma_f32_16x16x32_f16 v[98:101], v[224:227], v[178:181], v[98:101]
	v_mfma_f32_16x16x32_f16 v[86:89], v[202:205], v[186:189], v[86:89]
	v_mfma_f32_16x16x32_f16 v[82:85], v[224:227], v[186:189], v[82:85]
	v_mfma_f32_16x16x32_f16 v[70:73], v[202:205], v[194:197], v[70:73]
	v_mfma_f32_16x16x32_f16 v[66:69], v[224:227], v[194:197], v[66:69]
	s_barrier
	global_load_lds_dwordx4 v[146:147], off
	v_lshl_add_u64 v[206:207], s[42:43], 0, v[136:137]
	s_add_i32 m0, s45, 0x2000
	s_nop 0
	global_load_lds_dwordx4 v[206:207], off
	s_mov_b32 m0, s72
	v_lshl_add_u64 v[212:213], s[48:49], 0, v[130:131]
	ds_read_b128 v[166:169], v153 offset:16384
	ds_read_b128 v[170:173], v153 offset:17408
	ds_read_b128 v[174:177], v153 offset:18432
	ds_read_b128 v[178:181], v153 offset:19456
	ds_read_b128 v[182:185], v153 offset:20480
	ds_read_b128 v[186:189], v153 offset:21504
	ds_read_b128 v[190:193], v153 offset:22528
	ds_read_b128 v[194:197], v153 offset:23552
	global_load_lds_dwordx4 v[212:213], off
	v_lshl_add_u64 v[228:229], s[48:49], 0, v[134:135]
	s_mov_b32 m0, s73
	s_nop 0
	global_load_lds_dwordx4 v[228:229], off
	s_add_u32 s50, s42, 0x80000
	s_addc_u32 s51, s43, 0
	s_add_i32 s45, s60, s65
	v_lshl_add_u64 v[232:233], s[50:51], 0, v[132:133]
	s_mov_b32 m0, s45
	s_nop 0
	global_load_lds_dwordx4 v[232:233], off
	v_lshl_add_u64 v[232:233], s[50:51], 0, v[136:137]
	s_add_i32 m0, s45, 0x2000
	s_nop 0
	global_load_lds_dwordx4 v[232:233], off
	s_waitcnt vmcnt(8) lgkmcnt(0)
	s_barrier
; #define PG8_STAGE(bufoff, gbase, voff) do { _Pragma("unroll") for (int _i = 0; _i < 2; ++_i) \
;         __builtin_amdgcn_global_load_lds((const unsigned*)((const char*)(gbase) + (voff)[_i]), (LAS unsigned*)(lds + (bufoff) + ldsw + _i * 8192), 16, 0, 0); } while (0)
; #define PG8_LDA(dst, b, h) do { _Pragma("unroll") for (int m = 0; m < 4; ++m) _Pragma("unroll") for (int k = 0; k < 2; ++k) dst[m][k] = *(const LAS h16x8*)(lds + PG8_SA(b, h) + aoff + m * 2048 + k * 1024); } while (0)
; #define PG8_LDB(dst, b, h) do { _Pragma("unroll") for (int n = 0; n < 2; ++n) _Pragma("unroll") for (int k = 0; k < 2; ++k) dst[n][k] = *(const LAS h16x8*)(lds + PG8_SB(b, h) + boff + n * 2048 + k * 1024); } while (0)
; #define PG8_MMA(ai, bj, At, Bt_) do { __builtin_amdgcn_s_setprio(1); _Pragma("unroll") for (int m = 0; m < 4; ++m) _Pragma("unroll") for (int n = 0; n < 2; ++n) _Pragma("unroll") for (int k = 0; k < 2; ++k) \
;         acc[ai][bj][m][n] = __builtin_amdgcn_mfma_f32_16x16x32_f16(Bt_[n][k], At[m][k], acc[ai][bj][m][n], 0, 0, 0); __builtin_amdgcn_s_setprio(0); } while (0)
; #define PG8_WAIT_V(n) asm volatile("s_waitcnt vmcnt(" #n ")" ::: "memory")
; #define PG8_WAIT_L(n) asm volatile("s_waitcnt lgkmcnt(" #n ")" ::: "memory")
; #define PG8_BAR __builtin_amdgcn_s_barrier()
; #define PG8_SCHED __builtin_amdgcn_sched_barrier(0)
; template <class Epi, class AMap>
; __device__ __forceinline__ void gemm_phase(LAS unsigned char* lds, const AMap am, const int lda, const h16* Bt, const int ldb, const int M, const int N, const int K, const Epi& E) {
;     ...
;             PG8_WAIT_V(6); PG8_BAR; PG8_MMA(1, 1, At, B1); PG8_BAR;
;             PG8_LDB(B0, 1, 0); PG8_SCHED; PG8_LDA(At, 1, 0); PG8_STAGE(PG8_SA(0, 1), a2 + hstepA, voffA);
;             PG8_WAIT_L(8); PG8_BAR; PG8_WAIT_L(0); PG8_MMA(0, 0, At, B0); PG8_BAR; PG8_SCHED;
;             PG8_LDB(B1, 1, 1); PG8_STAGE(PG8_SB(1, 0), b3, voffB);
;             PG8_BAR; PG8_WAIT_L(0); PG8_MMA(0, 1, At, B1); PG8_BAR;
	v_mfma_f32_16x16x32_f16 v[62:65], v[142:145], v[166:169], v[62:65]
	v_mfma_f32_16x16x32_f16 v[58:61], v[158:161], v[166:169], v[58:61]
	v_mfma_f32_16x16x32_f16 v[46:49], v[142:145], v[174:177], v[46:49]
	v_mfma_f32_16x16x32_f16 v[42:45], v[158:161], v[174:177], v[42:45]
	v_mfma_f32_16x16x32_f16 v[30:33], v[142:145], v[182:185], v[30:33]
	v_mfma_f32_16x16x32_f16 v[26:29], v[158:161], v[182:185], v[26:29]
	v_mfma_f32_16x16x32_f16 v[14:17], v[142:145], v[190:193], v[14:17]
	v_mfma_f32_16x16x32_f16 v[10:13], v[158:161], v[190:193], v[10:13]
	v_mfma_f32_16x16x32_f16 v[62:65], v[154:157], v[170:173], v[62:65]
	v_mfma_f32_16x16x32_f16 v[58:61], v[162:165], v[170:173], v[58:61]
	v_mfma_f32_16x16x32_f16 v[46:49], v[154:157], v[178:181], v[46:49]
	v_mfma_f32_16x16x32_f16 v[42:45], v[162:165], v[178:181], v[42:45]
	v_mfma_f32_16x16x32_f16 v[30:33], v[154:157], v[186:189], v[30:33]
	v_mfma_f32_16x16x32_f16 v[26:29], v[162:165], v[186:189], v[26:29]
	v_mfma_f32_16x16x32_f16 v[14:17], v[154:157], v[194:197], v[14:17]
	v_mfma_f32_16x16x32_f16 v[10:13], v[162:165], v[194:197], v[10:13]
	v_mfma_f32_16x16x32_f16 v[54:57], v[198:201], v[166:169], v[54:57]
	v_mfma_f32_16x16x32_f16 v[50:53], v[220:223], v[166:169], v[50:53]
	v_mfma_f32_16x16x32_f16 v[38:41], v[198:201], v[174:177], v[38:41]
	v_mfma_f32_16x16x32_f16 v[34:37], v[220:223], v[174:177], v[34:37]
	v_mfma_f32_16x16x32_f16 v[22:25], v[198:201], v[182:185], v[22:25]
	v_mfma_f32_16x16x32_f16 v[18:21], v[220:223], v[182:185], v[18:21]
	v_mfma_f32_16x16x32_f16 v[6:9], v[198:201], v[190:193], v[6:9]
	v_mfma_f32_16x16x32_f16 v[2:5], v[220:223], v[190:193], v[2:5]
	v_mfma_f32_16x16x32_f16 v[54:57], v[202:205], v[170:173], v[54:57]
	v_mfma_f32_16x16x32_f16 v[50:53], v[224:227], v[170:173], v[50:53]
	v_mfma_f32_16x16x32_f16 v[38:41], v[202:205], v[178:181], v[38:41]
	v_mfma_f32_16x16x32_f16 v[34:37], v[224:227], v[178:181], v[34:37]
	v_mfma_f32_16x16x32_f16 v[22:25], v[202:205], v[186:189], v[22:25]
	v_mfma_f32_16x16x32_f16 v[18:21], v[224:227], v[186:189], v[18:21]
	v_mfma_f32_16x16x32_f16 v[6:9], v[202:205], v[194:197], v[6:9]
	v_mfma_f32_16x16x32_f16 v[2:5], v[224:227], v[194:197], v[2:5]
	s_barrier
	s_add_i32 s45, 0, 0x18000
	v_add_u32_e32 v0, s45, v149
	ds_read_b128 v[142:145], v0
	ds_read_b128 v[154:157], v0 offset:1024
	ds_read_b128 v[158:161], v0 offset:2048
	ds_read_b128 v[162:165], v0 offset:3072
	s_add_u32 s48, s48, 0x80000
	s_addc_u32 s49, s49, 0
	s_mov_b32 m0, s74
	v_lshl_add_u64 v[232:233], s[48:49], 0, v[130:131]
	ds_read_b128 v[166:169], v153 offset:32768
	ds_read_b128 v[170:173], v153 offset:33792
	ds_read_b128 v[174:177], v153 offset:34816
	ds_read_b128 v[178:181], v153 offset:35840
	ds_read_b128 v[182:185], v153 offset:36864
	ds_read_b128 v[186:189], v153 offset:37888
	ds_read_b128 v[190:193], v153 offset:38912
	ds_read_b128 v[194:197], v153 offset:39936
	global_load_lds_dwordx4 v[232:233], off
	v_lshl_add_u64 v[232:233], s[48:49], 0, v[134:135]
	s_mov_b32 m0, s75
	s_nop 0
	global_load_lds_dwordx4 v[232:233], off
	s_waitcnt lgkmcnt(11)
	s_add_i32 s48, 0, 0x1c000
	s_add_i32 s45, s45, s65
	v_add_u32_e32 v0, s48, v149
	v_lshl_add_u64 v[146:147], v[146:147], 0, s[92:93]
	s_mov_b32 m0, s45
	ds_read_b128 v[198:201], v0
	ds_read_b128 v[202:205], v0 offset:1024
	ds_read_b128 v[220:223], v0 offset:2048
	ds_read_b128 v[224:227], v0 offset:3072
	s_waitcnt vmcnt(8) lgkmcnt(0)
	s_barrier
	v_mfma_f32_16x16x32_f16 v[126:129], v[142:145], v[166:169], v[126:129]
	v_mfma_f32_16x16x32_f16 v[122:125], v[158:161], v[166:169], v[122:125]
	v_mfma_f32_16x16x32_f16 v[110:113], v[142:145], v[174:177], v[110:113]
	v_mfma_f32_16x16x32_f16 v[106:109], v[158:161], v[174:177], v[106:109]
	v_mfma_f32_16x16x32_f16 v[94:97], v[142:145], v[182:185], v[94:97]
	v_mfma_f32_16x16x32_f16 v[90:93], v[158:161], v[182:185], v[90:93]
	v_mfma_f32_16x16x32_f16 v[78:81], v[142:145], v[190:193], v[78:81]
	v_mfma_f32_16x16x32_f16 v[74:77], v[158:161], v[190:193], v[74:77]
	v_mfma_f32_16x16x32_f16 v[126:129], v[154:157], v[170:173], v[126:129]
	v_mfma_f32_16x16x32_f16 v[122:125], v[162:165], v[170:173], v[122:125]
	v_mfma_f32_16x16x32_f16 v[110:113], v[154:157], v[178:181], v[110:113]
	v_mfma_f32_16x16x32_f16 v[106:109], v[162:165], v[178:181], v[106:109]
	v_mfma_f32_16x16x32_f16 v[94:97], v[154:157], v[186:189], v[94:97]
	v_mfma_f32_16x16x32_f16 v[90:93], v[162:165], v[186:189], v[90:93]
	v_mfma_f32_16x16x32_f16 v[78:81], v[154:157], v[194:197], v[78:81]
	v_mfma_f32_16x16x32_f16 v[74:77], v[162:165], v[194:197], v[74:77]
	v_mfma_f32_16x16x32_f16 v[118:121], v[198:201], v[166:169], v[118:121]
	v_mfma_f32_16x16x32_f16 v[114:117], v[220:223], v[166:169], v[114:117]
	v_mfma_f32_16x16x32_f16 v[102:105], v[198:201], v[174:177], v[102:105]
	v_mfma_f32_16x16x32_f16 v[98:101], v[220:223], v[174:177], v[98:101]
	v_mfma_f32_16x16x32_f16 v[86:89], v[198:201], v[182:185], v[86:89]
	v_mfma_f32_16x16x32_f16 v[82:85], v[220:223], v[182:185], v[82:85]
	v_mfma_f32_16x16x32_f16 v[70:73], v[198:201], v[190:193], v[70:73]
	v_mfma_f32_16x16x32_f16 v[66:69], v[220:223], v[190:193], v[66:69]
	v_mfma_f32_16x16x32_f16 v[118:121], v[202:205], v[170:173], v[118:121]
	v_mfma_f32_16x16x32_f16 v[114:117], v[224:227], v[170:173], v[114:117]
	v_mfma_f32_16x16x32_f16 v[102:105], v[202:205], v[178:181], v[102:105]
	v_mfma_f32_16x16x32_f16 v[98:101], v[224:227], v[178:181], v[98:101]
	v_mfma_f32_16x16x32_f16 v[86:89], v[202:205], v[186:189], v[86:89]
	v_mfma_f32_16x16x32_f16 v[82:85], v[224:227], v[186:189], v[82:85]
	v_mfma_f32_16x16x32_f16 v[70:73], v[202:205], v[194:197], v[70:73]
	v_mfma_f32_16x16x32_f16 v[66:69], v[224:227], v[194:197], v[66:69]
	s_barrier
; #define PG8_STAGE(bufoff, gbase, voff) do { _Pragma("unroll") for (int _i = 0; _i < 2; ++_i) \
;         __builtin_amdgcn_global_load_lds((const unsigned*)((const char*)(gbase) + (voff)[_i]), (LAS unsigned*)(lds + (bufoff) + ldsw + _i * 8192), 16, 0, 0); } while (0)
; #define PG8_LDA(dst, b, h) do { _Pragma("unroll") for (int m = 0; m < 4; ++m) _Pragma("unroll") for (int k = 0; k < 2; ++k) dst[m][k] = *(const LAS h16x8*)(lds + PG8_SA(b, h) + aoff + m * 2048 + k * 1024); } while (0)
; #define PG8_MMA(ai, bj, At, Bt_) do { __builtin_amdgcn_s_setprio(1); _Pragma("unroll") for (int m = 0; m < 4; ++m) _Pragma("unroll") for (int n = 0; n < 2; ++n) _Pragma("unroll") for (int k = 0; k < 2; ++k) \
;         acc[ai][bj][m][n] = __builtin_amdgcn_mfma_f32_16x16x32_f16(Bt_[n][k], At[m][k], acc[ai][bj][m][n], 0, 0, 0); __builtin_amdgcn_s_setprio(0); } while (0)
; #define PG8_WAIT_V(n) asm volatile("s_waitcnt vmcnt(" #n ")" ::: "memory")
; #define PG8_WAIT_L(n) asm volatile("s_waitcnt lgkmcnt(" #n ")" ::: "memory")
; #define PG8_BAR __builtin_amdgcn_s_barrier()
; #define PG8_SCHED __builtin_amdgcn_sched_barrier(0)
; template <class Epi, class AMap>
; __device__ __forceinline__ void gemm_phase(LAS unsigned char* lds, const AMap am, const int lda, const h16* Bt, const int ldb, const int M, const int N, const int K, const Epi& E) {
;     ...
;             PG8_LDA(At, 1, 1); PG8_STAGE(PG8_SA(1, 0), a3, voffA);
;             PG8_BAR; PG8_WAIT_L(0); PG8_MMA(1, 0, At, B0); PG8_BAR; PG8_SCHED;
;             PG8_STAGE(PG8_SB(1, 1), b3 + hstepB, voffB);
;             PG8_WAIT_V(6); PG8_BAR; PG8_MMA(1, 1, At, B1); PG8_BAR;
;         }
	global_load_lds_dwordx4 v[146:147], off
	v_lshl_add_u64 v[146:147], v[206:207], 0, s[92:93]
	s_add_i32 m0, s45, 0x2000
	s_nop 0
	global_load_lds_dwordx4 v[146:147], off
	s_mov_b32 m0, s77
	v_lshl_add_u64 v[146:147], v[212:213], 0, s[92:93]
	ds_read_b128 v[166:169], v153 offset:49152
	ds_read_b128 v[170:173], v153 offset:50176
	ds_read_b128 v[174:177], v153 offset:51200
	ds_read_b128 v[178:181], v153 offset:52224
	ds_read_b128 v[182:185], v153 offset:53248
	ds_read_b128 v[186:189], v153 offset:54272
	ds_read_b128 v[190:193], v153 offset:55296
	ds_read_b128 v[194:197], v153 offset:56320
	global_load_lds_dwordx4 v[146:147], off
	v_lshl_add_u64 v[146:147], v[228:229], 0, s[92:93]
	s_mov_b32 m0, s78
	s_nop 0
	global_load_lds_dwordx4 v[146:147], off
	s_add_u32 s42, s42, 0x80080
	s_addc_u32 s43, s43, 0
	s_add_i32 s45, s48, s65
	v_lshl_add_u64 v[232:233], s[42:43], 0, v[132:133]
	s_mov_b32 m0, s45
	s_nop 0
	global_load_lds_dwordx4 v[232:233], off
	v_lshl_add_u64 v[232:233], s[42:43], 0, v[136:137]
	s_add_i32 m0, s45, 0x2000
	s_nop 0
	global_load_lds_dwordx4 v[232:233], off
	s_add_i32 s35, s35, 2
	s_add_u32 s40, s40, 0x100
	s_addc_u32 s41, s41, 0
	s_add_u32 s21, s21, 0x100
	s_addc_u32 s29, s29, 0
	s_cmp_gt_u32 s35, 29
	s_waitcnt vmcnt(8) lgkmcnt(0)
	s_barrier
	v_mfma_f32_16x16x32_f16 v[62:65], v[142:145], v[166:169], v[62:65]
	v_mfma_f32_16x16x32_f16 v[58:61], v[158:161], v[166:169], v[58:61]
	v_mfma_f32_16x16x32_f16 v[46:49], v[142:145], v[174:177], v[46:49]
	v_mfma_f32_16x16x32_f16 v[42:45], v[158:161], v[174:177], v[42:45]
	v_mfma_f32_16x16x32_f16 v[30:33], v[142:145], v[182:185], v[30:33]
	v_mfma_f32_16x16x32_f16 v[26:29], v[158:161], v[182:185], v[26:29]
	v_mfma_f32_16x16x32_f16 v[14:17], v[142:145], v[190:193], v[14:17]
	v_mfma_f32_16x16x32_f16 v[10:13], v[158:161], v[190:193], v[10:13]
	v_mfma_f32_16x16x32_f16 v[62:65], v[154:157], v[170:173], v[62:65]
	v_mfma_f32_16x16x32_f16 v[58:61], v[162:165], v[170:173], v[58:61]
	v_mfma_f32_16x16x32_f16 v[46:49], v[154:157], v[178:181], v[46:49]
	v_mfma_f32_16x16x32_f16 v[42:45], v[162:165], v[178:181], v[42:45]
	v_mfma_f32_16x16x32_f16 v[30:33], v[154:157], v[186:189], v[30:33]
	v_mfma_f32_16x16x32_f16 v[26:29], v[162:165], v[186:189], v[26:29]
	v_mfma_f32_16x16x32_f16 v[14:17], v[154:157], v[194:197], v[14:17]
	v_mfma_f32_16x16x32_f16 v[10:13], v[162:165], v[194:197], v[10:13]
	v_mfma_f32_16x16x32_f16 v[54:57], v[198:201], v[166:169], v[54:57]
	v_mfma_f32_16x16x32_f16 v[50:53], v[220:223], v[166:169], v[50:53]
	v_mfma_f32_16x16x32_f16 v[38:41], v[198:201], v[174:177], v[38:41]
	v_mfma_f32_16x16x32_f16 v[34:37], v[220:223], v[174:177], v[34:37]
	v_mfma_f32_16x16x32_f16 v[22:25], v[198:201], v[182:185], v[22:25]
	v_mfma_f32_16x16x32_f16 v[18:21], v[220:223], v[182:185], v[18:21]
	v_mfma_f32_16x16x32_f16 v[6:9], v[198:201], v[190:193], v[6:9]
	v_mfma_f32_16x16x32_f16 v[2:5], v[220:223], v[190:193], v[2:5]
	v_mfma_f32_16x16x32_f16 v[54:57], v[202:205], v[170:173], v[54:57]
	v_mfma_f32_16x16x32_f16 v[50:53], v[224:227], v[170:173], v[50:53]
	v_mfma_f32_16x16x32_f16 v[38:41], v[202:205], v[178:181], v[38:41]
	v_mfma_f32_16x16x32_f16 v[34:37], v[224:227], v[178:181], v[34:37]
	v_mfma_f32_16x16x32_f16 v[22:25], v[202:205], v[186:189], v[22:25]
	v_mfma_f32_16x16x32_f16 v[18:21], v[224:227], v[186:189], v[18:21]
	v_mfma_f32_16x16x32_f16 v[6:9], v[202:205], v[194:197], v[6:9]
	v_mfma_f32_16x16x32_f16 v[2:5], v[224:227], v[194:197], v[2:5]
	s_barrier
	s_cbranch_scc0 .LBB0_268
	s_cmpk_gt_u32 s64, 0xff
	s_cbranch_scc1 .Lgx3
	s_barrier

; __device__ __forceinline__ float sigmoidf_(float x) { return 1.0f / (1.0f + __expf(-x)); }
;     template <int GI>
;     __device__ __forceinline__ void body(const f32x4 (&acc)[2][2][4][2], int row0, int colt) const {
; #pragma unroll
;         for (int bj = 0; bj < 2; ++bj) {
;             const int c = colt + bj * 128;
;             f32x4 b0 = (f32x4){0.f, 0.f, 0.f, 0.f}, b1 = b0;
;             if (GI == 0) { b0 = *(const f32x4*)(w0 + c); b1 = *(const f32x4*)(w0 + c + 4); }
;             else if (GI == 1) { b0 = *(const f32x4*)(a0 + c); b1 = *(const f32x4*)(a0 + c + 4); }
;             else if (GI == 3) { b0 = *(const f32x4*)(v0 + c); b1 = *(const f32x4*)(v0 + c + 4); }
; #pragma unroll
;             for (int ai = 0; ai < 2; ++ai)
; #pragma unroll
;                 for (int m = 0; m < 4; ++m) {
;                     const size_t row = (size_t)(row0 + ai * 128 + m * 16);
;                     f32x4 x0 = acc[ai][bj][m][0] + b0, x1 = acc[ai][bj][m][1] + b1;
;                     if (GI == 0) {
; #pragma unroll
;                         for (int j = 0; j < 4; ++j) {
;                             x0[j] = 0.6065306597126334f * sigmoidf_(x0[j]); x1[j] = 0.6065306597126334f * sigmoidf_(x1[j]); }
;                         *(u32x4*)(DEC + row * DM + c) = pack8(x0, x1);
.LBB0_610:
	v_lshl_or_b32 v152, s50, 8, v156
	v_ashrrev_i32_e32 v153, 31, v152
	v_lshl_add_u64 v[148:149], v[152:153], 2, s[40:41]
	global_load_dwordx4 v[90:93], v[148:149], off offset:16
	global_load_dwordx4 v[94:97], v[148:149], off
	s_mov_b32 s4, 0x3f1b4598
	v_lshl_add_u32 v150, s35, 8, v154
	v_ashrrev_i32_e32 v151, 31, v150
	v_readlane_b32 s6, v254, 56
	v_readlane_b32 s7, v254, 57
	s_cmpk_gt_u32 s71, 0xff
	s_cbranch_scc1 .Lgx4
	s_barrier
.Lgx4:
	s_waitcnt vmcnt(0)
	v_pk_add_f32 v[160:161], v[136:137], v[92:93]
	v_pk_add_f32 v[130:131], v[130:131], v[94:95]
	v_pk_add_f32 v[158:159], v[132:133], v[96:97]
	v_mul_f32_e32 v130, 0xbfb8aa3b, v130
	v_mul_f32_e32 v131, 0xbfb8aa3b, v131
	v_exp_f32_e32 v130, v130
	v_exp_f32_e32 v131, v131
	v_pk_add_f32 v[132:133], v[134:135], v[90:91]
	v_mul_f32_e32 v134, 0xbfb8aa3b, v158
	v_mul_f32_e32 v135, 0xbfb8aa3b, v159
	v_pk_add_f32 v[130:131], v[130:131], 1.0 op_sel_hi:[1,0]
	v_exp_f32_e32 v136, v134
	v_div_scale_f32 v158, s[0:1], v131, v131, 1.0
	v_rcp_f32_e32 v159, v158
	v_mul_f32_e32 v134, 0xbfb8aa3b, v160
	v_exp_f32_e32 v137, v135
	v_mul_f32_e32 v135, 0xbfb8aa3b, v161
	v_fma_f32 v160, -v158, v159, 1.0
	v_fmac_f32_e32 v159, v160, v159
	v_div_scale_f32 v160, vcc, 1.0, v131, 1.0
	v_mul_f32_e32 v161, v160, v159
	v_fma_f32 v162, -v158, v161, v160
	v_fmac_f32_e32 v161, v162, v159
	v_fma_f32 v158, -v158, v161, v160
	v_div_fmas_f32 v158, v158, v159, v161
	v_div_fixup_f32 v131, v158, v131, 1.0
	v_div_scale_f32 v158, s[0:1], v130, v130, 1.0
	v_rcp_f32_e32 v159, v158
	v_pk_add_f32 v[136:137], v[136:137], 1.0 op_sel_hi:[1,0]
	v_mul_f32_e32 v132, 0xbfb8aa3b, v132
	v_mul_f32_e32 v133, 0xbfb8aa3b, v133
	v_fma_f32 v160, -v158, v159, 1.0
	v_fmac_f32_e32 v159, v160, v159
	v_div_scale_f32 v160, vcc, 1.0, v130, 1.0
	v_mul_f32_e32 v161, v160, v159
	v_fma_f32 v162, -v158, v161, v160
	v_fmac_f32_e32 v161, v162, v159
	v_fma_f32 v158, -v158, v161, v160
	v_div_fmas_f32 v158, v158, v159, v161
	v_div_fixup_f32 v130, v158, v130, 1.0
	v_pk_mul_f32 v[130:131], v[130:131], s[4:5] op_sel_hi:[1,0]
	v_exp_f32_e32 v132, v132
	v_cvt_pk_f16_f32 v130, v130, v131
	v_div_scale_f32 v131, s[0:1], v137, v137, 1.0
	v_rcp_f32_e32 v158, v131
	v_exp_f32_e32 v133, v133
	v_exp_f32_e32 v134, v134
	v_exp_f32_e32 v135, v135
	v_fma_f32 v159, -v131, v158, 1.0
	v_fmac_f32_e32 v158, v159, v158
	v_div_scale_f32 v159, vcc, 1.0, v137, 1.0
	v_mul_f32_e32 v160, v159, v158
	v_fma_f32 v161, -v131, v160, v159
	v_fmac_f32_e32 v160, v161, v158
	v_fma_f32 v131, -v131, v160, v159
	v_div_fmas_f32 v131, v131, v158, v160
	v_div_fixup_f32 v137, v131, v137, 1.0
	v_div_scale_f32 v131, s[0:1], v136, v136, 1.0
	v_rcp_f32_e32 v158, v131
	v_pk_add_f32 v[132:133], v[132:133], 1.0 op_sel_hi:[1,0]
	v_pk_add_f32 v[134:135], v[134:135], 1.0 op_sel_hi:[1,0]
	v_fma_f32 v159, -v131, v158, 1.0
	v_fmac_f32_e32 v158, v159, v158
	v_div_scale_f32 v159, vcc, 1.0, v136, 1.0
	v_mul_f32_e32 v160, v159, v158
	v_fma_f32 v161, -v131, v160, v159
	v_fmac_f32_e32 v160, v161, v158
	v_fma_f32 v131, -v131, v160, v159
	v_div_fmas_f32 v131, v131, v158, v160
	v_div_fixup_f32 v136, v131, v136, 1.0
	v_pk_mul_f32 v[136:137], v[136:137], s[4:5] op_sel_hi:[1,0]
	s_nop 0
	v_cvt_pk_f16_f32 v131, v136, v137
	v_div_scale_f32 v136, s[0:1], v133, v133, 1.0
	v_rcp_f32_e32 v137, v136
	s_nop 0
	v_fma_f32 v158, -v136, v137, 1.0
	v_fmac_f32_e32 v137, v158, v137
	v_div_scale_f32 v158, vcc, 1.0, v133, 1.0
	v_mul_f32_e32 v159, v158, v137
	v_fma_f32 v160, -v136, v159, v158
	v_fmac_f32_e32 v159, v160, v137
	v_fma_f32 v136, -v136, v159, v158
	v_div_fmas_f32 v136, v136, v137, v159
	v_div_fixup_f32 v133, v136, v133, 1.0
	v_div_scale_f32 v136, s[0:1], v132, v132, 1.0
	v_rcp_f32_e32 v137, v136
	s_nop 0
	v_fma_f32 v158, -v136, v137, 1.0
	v_fmac_f32_e32 v137, v158, v137
	v_div_scale_f32 v158, vcc, 1.0, v132, 1.0
	v_mul_f32_e32 v159, v158, v137
	v_fma_f32 v160, -v136, v159, v158
	v_fmac_f32_e32 v159, v160, v137
	v_fma_f32 v136, -v136, v159, v158
	v_div_fmas_f32 v136, v136, v137, v159
	v_div_fixup_f32 v132, v136, v132, 1.0
	v_pk_mul_f32 v[132:133], v[132:133], s[4:5] op_sel_hi:[1,0]
	s_nop 0
	v_cvt_pk_f16_f32 v132, v132, v133
	v_div_scale_f32 v133, s[0:1], v135, v135, 1.0
	v_rcp_f32_e32 v136, v133
	s_nop 0
	v_fma_f32 v137, -v133, v136, 1.0
	v_fmac_f32_e32 v136, v137, v136
	v_div_scale_f32 v137, vcc, 1.0, v135, 1.0
	v_mul_f32_e32 v158, v137, v136
	v_fma_f32 v159, -v133, v158, v137
	v_fmac_f32_e32 v158, v159, v136
	v_fma_f32 v133, -v133, v158, v137
	v_div_fmas_f32 v133, v133, v136, v158
	v_div_fixup_f32 v135, v133, v135, 1.0
	v_div_scale_f32 v133, s[0:1], v134, v134, 1.0
	v_rcp_f32_e32 v136, v133
	s_nop 0
	v_fma_f32 v137, -v133, v136, 1.0
	v_fmac_f32_e32 v136, v137, v136
	v_div_scale_f32 v137, vcc, 1.0, v134, 1.0
	v_mul_f32_e32 v158, v137, v136
	v_fma_f32 v159, -v133, v158, v137
	v_fmac_f32_e32 v158, v159, v136
	v_fma_f32 v133, -v133, v158, v137
	v_div_fmas_f32 v133, v133, v136, v158
	v_div_fixup_f32 v134, v133, v134, 1.0
	v_pk_mul_f32 v[134:135], v[134:135], s[4:5] op_sel_hi:[1,0]
	v_lshlrev_b64 v[136:137], 1, v[152:153]
	v_cvt_pk_f16_f32 v133, v134, v135
	v_lshlrev_b64 v[134:135], 12, v[150:151]
	v_lshl_add_u64 v[134:135], s[6:7], 0, v[134:135]
	v_lshl_add_u64 v[134:135], v[134:135], 0, v[136:137]
	global_store_dwordx4 v[134:135], v[130:133], off
	v_pk_add_f32 v[122:123], v[122:123], v[90:91]
	v_pk_add_f32 v[126:127], v[126:127], v[94:95]
	v_mul_f32_e32 v122, 0xbfb8aa3b, v122
	v_exp_f32_e32 v152, v122
	v_mul_f32_e32 v122, 0xbfb8aa3b, v127
	v_pk_add_f32 v[128:129], v[128:129], v[96:97]
	v_mul_f32_e32 v126, 0xbfb8aa3b, v126
	v_exp_f32_e32 v133, v122
	v_mul_f32_e32 v122, 0xbfb8aa3b, v123
	v_pk_add_f32 v[124:125], v[124:125], v[92:93]
; __device__ __forceinline__ float sigmoidf_(float x) { return 1.0f / (1.0f + __expf(-x)); }
;     template <int GI>
;     __device__ __forceinline__ void body(const f32x4 (&acc)[2][2][4][2], int row0, int colt) const {
;     ...
;             for (int ai = 0; ai < 2; ++ai)
; #pragma unroll
;                 for (int m = 0; m < 4; ++m) {
;                     const size_t row = (size_t)(row0 + ai * 128 + m * 16);
;                     f32x4 x0 = acc[ai][bj][m][0] + b0, x1 = acc[ai][bj][m][1] + b1;
;                     if (GI == 0) {
; #pragma unroll
;                         for (int j = 0; j < 4; ++j) {
;                             x0[j] = 0.6065306597126334f * sigmoidf_(x0[j]); x1[j] = 0.6065306597126334f * sigmoidf_(x1[j]); }
;                         *(u32x4*)(DEC + row * DM + c) = pack8(x0, x1);
	v_exp_f32_e32 v132, v126
	v_exp_f32_e32 v153, v122
	v_mul_f32_e32 v122, 0xbfb8aa3b, v128
	v_exp_f32_e32 v128, v122
	v_mul_f32_e32 v122, 0xbfb8aa3b, v124
	v_exp_f32_e32 v126, v122
	v_mul_f32_e32 v122, 0xbfb8aa3b, v129
	v_exp_f32_e32 v129, v122
	v_mul_f32_e32 v122, 0xbfb8aa3b, v125
	v_exp_f32_e32 v127, v122
	v_pk_add_f32 v[122:123], v[132:133], 1.0 op_sel_hi:[1,0]
	v_or_b32_e32 v130, 16, v150
	v_div_scale_f32 v124, s[0:1], v123, v123, 1.0
	v_rcp_f32_e32 v125, v124
	v_pk_add_f32 v[126:127], v[126:127], 1.0 op_sel_hi:[1,0]
	v_ashrrev_i32_e32 v131, 31, v130
	v_fma_f32 v132, -v124, v125, 1.0
	v_fmac_f32_e32 v125, v132, v125
	v_div_scale_f32 v132, vcc, 1.0, v123, 1.0
	v_mul_f32_e32 v133, v132, v125
	v_fma_f32 v151, -v124, v133, v132
	v_fmac_f32_e32 v133, v151, v125
	v_fma_f32 v124, -v124, v133, v132
	v_div_fmas_f32 v124, v124, v125, v133
	v_div_fixup_f32 v123, v124, v123, 1.0
	v_div_scale_f32 v124, s[0:1], v122, v122, 1.0
	v_rcp_f32_e32 v125, v124
	s_nop 0
	v_fma_f32 v132, -v124, v125, 1.0
	v_fmac_f32_e32 v125, v132, v125
	v_div_scale_f32 v132, vcc, 1.0, v122, 1.0
	v_mul_f32_e32 v133, v132, v125
	v_fma_f32 v151, -v124, v133, v132
	v_fmac_f32_e32 v133, v151, v125
	v_fma_f32 v124, -v124, v133, v132
	v_div_fmas_f32 v124, v124, v125, v133
	v_div_fixup_f32 v122, v124, v122, 1.0
	v_pk_mul_f32 v[122:123], v[122:123], s[4:5] op_sel_hi:[1,0]
	v_pk_add_f32 v[124:125], v[128:129], 1.0 op_sel_hi:[1,0]
	v_cvt_pk_f16_f32 v122, v122, v123
	v_div_scale_f32 v123, s[0:1], v125, v125, 1.0
	v_rcp_f32_e32 v128, v123
	s_nop 0
	v_fma_f32 v129, -v123, v128, 1.0
	v_fmac_f32_e32 v128, v129, v128
	v_div_scale_f32 v129, vcc, 1.0, v125, 1.0
	v_mul_f32_e32 v132, v129, v128
	v_fma_f32 v133, -v123, v132, v129
	v_fmac_f32_e32 v132, v133, v128
	v_fma_f32 v123, -v123, v132, v129
	v_div_fmas_f32 v123, v123, v128, v132
	v_div_fixup_f32 v125, v123, v125, 1.0
	v_div_scale_f32 v123, s[0:1], v124, v124, 1.0
	v_rcp_f32_e32 v128, v123
	s_nop 0
	v_fma_f32 v129, -v123, v128, 1.0
	v_fmac_f32_e32 v128, v129, v128
	v_div_scale_f32 v129, vcc, 1.0, v124, 1.0
	v_mul_f32_e32 v132, v129, v128
	v_fma_f32 v133, -v123, v132, v129
	v_fmac_f32_e32 v132, v133, v128
	v_fma_f32 v123, -v123, v132, v129
	v_div_fmas_f32 v123, v123, v128, v132
	v_div_fixup_f32 v124, v123, v124, 1.0
	v_pk_mul_f32 v[124:125], v[124:125], s[4:5] op_sel_hi:[1,0]
	s_nop 0
	v_cvt_pk_f16_f32 v123, v124, v125
	v_pk_add_f32 v[124:125], v[152:153], 1.0 op_sel_hi:[1,0]
	s_nop 0
	v_div_scale_f32 v128, s[0:1], v125, v125, 1.0
	v_rcp_f32_e32 v129, v128
	s_nop 0
	v_fma_f32 v132, -v128, v129, 1.0
	v_fmac_f32_e32 v129, v132, v129
	v_div_scale_f32 v132, vcc, 1.0, v125, 1.0
	v_mul_f32_e32 v133, v132, v129
	v_fma_f32 v151, -v128, v133, v132
	v_fmac_f32_e32 v133, v151, v129
	v_fma_f32 v128, -v128, v133, v132
	v_div_fmas_f32 v128, v128, v129, v133
	v_div_fixup_f32 v125, v128, v125, 1.0
	v_div_scale_f32 v128, s[0:1], v124, v124, 1.0
	v_rcp_f32_e32 v129, v128
	s_nop 0
	v_fma_f32 v132, -v128, v129, 1.0
	v_fmac_f32_e32 v129, v132, v129
	v_div_scale_f32 v132, vcc, 1.0, v124, 1.0
	v_mul_f32_e32 v133, v132, v129
	v_fma_f32 v151, -v128, v133, v132
	v_fmac_f32_e32 v133, v151, v129
	v_fma_f32 v128, -v128, v133, v132
	v_div_fmas_f32 v128, v128, v129, v133
	v_div_fixup_f32 v124, v128, v124, 1.0
	v_pk_mul_f32 v[124:125], v[124:125], s[4:5] op_sel_hi:[1,0]
	s_nop 0
	v_cvt_pk_f16_f32 v124, v124, v125
	v_div_scale_f32 v125, s[0:1], v127, v127, 1.0
	v_rcp_f32_e32 v128, v125
	s_nop 0
	v_fma_f32 v129, -v125, v128, 1.0
	v_fmac_f32_e32 v128, v129, v128
	v_div_scale_f32 v129, vcc, 1.0, v127, 1.0
	v_mul_f32_e32 v132, v129, v128
	v_fma_f32 v133, -v125, v132, v129
	v_fmac_f32_e32 v132, v133, v128
	v_fma_f32 v125, -v125, v132, v129
	v_div_fmas_f32 v125, v125, v128, v132
	v_div_fixup_f32 v127, v125, v127, 1.0
	v_div_scale_f32 v125, s[0:1], v126, v126, 1.0
	v_rcp_f32_e32 v128, v125
	s_nop 0
	v_fma_f32 v129, -v125, v128, 1.0
	v_fmac_f32_e32 v128, v129, v128
	v_div_scale_f32 v129, vcc, 1.0, v126, 1.0
	v_mul_f32_e32 v132, v129, v128
	v_fma_f32 v133, -v125, v132, v129
	v_fmac_f32_e32 v132, v133, v128
	v_fma_f32 v125, -v125, v132, v129
	v_div_fmas_f32 v125, v125, v128, v132
	v_div_fixup_f32 v126, v125, v126, 1.0
	v_pk_mul_f32 v[126:127], v[126:127], s[4:5] op_sel_hi:[1,0]
	s_nop 0
	v_cvt_pk_f16_f32 v125, v126, v127
	v_lshlrev_b64 v[126:127], 12, v[130:131]
	v_lshl_add_u64 v[126:127], s[6:7], 0, v[126:127]
	v_lshl_add_u64 v[126:127], v[126:127], 0, v[136:137]
	global_store_dwordx4 v[126:127], v[122:125], off
	v_pk_add_f32 v[114:115], v[114:115], v[90:91]
	v_pk_add_f32 v[118:119], v[118:119], v[94:95]
	v_mul_f32_e32 v114, 0xbfb8aa3b, v114
	v_exp_f32_e32 v128, v114
	v_mul_f32_e32 v114, 0xbfb8aa3b, v119
	v_pk_add_f32 v[120:121], v[120:121], v[96:97]
	v_mul_f32_e32 v118, 0xbfb8aa3b, v118
	v_exp_f32_e32 v125, v114
	v_mul_f32_e32 v114, 0xbfb8aa3b, v115
	v_pk_add_f32 v[116:117], v[116:117], v[92:93]
	v_exp_f32_e32 v124, v118
	v_exp_f32_e32 v129, v114
	v_mul_f32_e32 v114, 0xbfb8aa3b, v120
	v_exp_f32_e32 v120, v114
	v_mul_f32_e32 v114, 0xbfb8aa3b, v116
	v_exp_f32_e32 v118, v114
	v_mul_f32_e32 v114, 0xbfb8aa3b, v121
	v_exp_f32_e32 v121, v114
	v_mul_f32_e32 v114, 0xbfb8aa3b, v117
	v_exp_f32_e32 v119, v114
	v_pk_add_f32 v[114:115], v[124:125], 1.0 op_sel_hi:[1,0]
	v_or_b32_e32 v122, 32, v150
	v_div_scale_f32 v116, s[0:1], v115, v115, 1.0
	v_rcp_f32_e32 v117, v116
	v_pk_add_f32 v[118:119], v[118:119], 1.0 op_sel_hi:[1,0]
	v_ashrrev_i32_e32 v123, 31, v122
	v_fma_f32 v124, -v116, v117, 1.0
	v_fmac_f32_e32 v117, v124, v117
	v_div_scale_f32 v124, vcc, 1.0, v115, 1.0
	v_mul_f32_e32 v125, v124, v117
	v_fma_f32 v130, -v116, v125, v124
	v_fmac_f32_e32 v125, v130, v117
	v_fma_f32 v116, -v116, v125, v124
; __device__ __forceinline__ float sigmoidf_(float x) { return 1.0f / (1.0f + __expf(-x)); }
;     template <int GI>
;     __device__ __forceinline__ void body(const f32x4 (&acc)[2][2][4][2], int row0, int colt) const {
;     ...
;             for (int ai = 0; ai < 2; ++ai)
; #pragma unroll
;                 for (int m = 0; m < 4; ++m) {
;                     const size_t row = (size_t)(row0 + ai * 128 + m * 16);
;                     f32x4 x0 = acc[ai][bj][m][0] + b0, x1 = acc[ai][bj][m][1] + b1;
;                     if (GI == 0) {
; #pragma unroll
;                         for (int j = 0; j < 4; ++j) {
;                             x0[j] = 0.6065306597126334f * sigmoidf_(x0[j]); x1[j] = 0.6065306597126334f * sigmoidf_(x1[j]); }
;                         *(u32x4*)(DEC + row * DM + c) = pack8(x0, x1);
	v_div_fmas_f32 v116, v116, v117, v125
	v_div_fixup_f32 v115, v116, v115, 1.0
	v_div_scale_f32 v116, s[0:1], v114, v114, 1.0
	v_rcp_f32_e32 v117, v116
	s_nop 0
	v_fma_f32 v124, -v116, v117, 1.0
	v_fmac_f32_e32 v117, v124, v117
	v_div_scale_f32 v124, vcc, 1.0, v114, 1.0
	v_mul_f32_e32 v125, v124, v117
	v_fma_f32 v130, -v116, v125, v124
	v_fmac_f32_e32 v125, v130, v117
	v_fma_f32 v116, -v116, v125, v124
	v_div_fmas_f32 v116, v116, v117, v125
	v_div_fixup_f32 v114, v116, v114, 1.0
	v_pk_mul_f32 v[114:115], v[114:115], s[4:5] op_sel_hi:[1,0]
	v_pk_add_f32 v[116:117], v[120:121], 1.0 op_sel_hi:[1,0]
	v_cvt_pk_f16_f32 v114, v114, v115
	v_div_scale_f32 v115, s[0:1], v117, v117, 1.0
	v_rcp_f32_e32 v120, v115
	s_nop 0
	v_fma_f32 v121, -v115, v120, 1.0
	v_fmac_f32_e32 v120, v121, v120
	v_div_scale_f32 v121, vcc, 1.0, v117, 1.0
	v_mul_f32_e32 v124, v121, v120
	v_fma_f32 v125, -v115, v124, v121
	v_fmac_f32_e32 v124, v125, v120
	v_fma_f32 v115, -v115, v124, v121
	v_div_fmas_f32 v115, v115, v120, v124
	v_div_fixup_f32 v117, v115, v117, 1.0
	v_div_scale_f32 v115, s[0:1], v116, v116, 1.0
	v_rcp_f32_e32 v120, v115
	s_nop 0
	v_fma_f32 v121, -v115, v120, 1.0
	v_fmac_f32_e32 v120, v121, v120
	v_div_scale_f32 v121, vcc, 1.0, v116, 1.0
	v_mul_f32_e32 v124, v121, v120
	v_fma_f32 v125, -v115, v124, v121
	v_fmac_f32_e32 v124, v125, v120
	v_fma_f32 v115, -v115, v124, v121
	v_div_fmas_f32 v115, v115, v120, v124
	v_div_fixup_f32 v116, v115, v116, 1.0
	v_pk_mul_f32 v[116:117], v[116:117], s[4:5] op_sel_hi:[1,0]
	s_nop 0
	v_cvt_pk_f16_f32 v115, v116, v117
	v_pk_add_f32 v[116:117], v[128:129], 1.0 op_sel_hi:[1,0]
	s_nop 0
	v_div_scale_f32 v120, s[0:1], v117, v117, 1.0
	v_rcp_f32_e32 v121, v120
	s_nop 0
	v_fma_f32 v124, -v120, v121, 1.0
	v_fmac_f32_e32 v121, v124, v121
	v_div_scale_f32 v124, vcc, 1.0, v117, 1.0
	v_mul_f32_e32 v125, v124, v121
	v_fma_f32 v128, -v120, v125, v124
	v_fmac_f32_e32 v125, v128, v121
	v_fma_f32 v120, -v120, v125, v124
	v_div_fmas_f32 v120, v120, v121, v125
	v_div_fixup_f32 v117, v120, v117, 1.0
	v_div_scale_f32 v120, s[0:1], v116, v116, 1.0
	v_rcp_f32_e32 v121, v120
	s_nop 0
	v_fma_f32 v124, -v120, v121, 1.0
	v_fmac_f32_e32 v121, v124, v121
	v_div_scale_f32 v124, vcc, 1.0, v116, 1.0
	v_mul_f32_e32 v125, v124, v121
	v_fma_f32 v128, -v120, v125, v124
	v_fmac_f32_e32 v125, v128, v121
	v_fma_f32 v120, -v120, v125, v124
	v_div_fmas_f32 v120, v120, v121, v125
	v_div_fixup_f32 v116, v120, v116, 1.0
	v_pk_mul_f32 v[116:117], v[116:117], s[4:5] op_sel_hi:[1,0]
	s_nop 0
	v_cvt_pk_f16_f32 v116, v116, v117
	v_div_scale_f32 v117, s[0:1], v119, v119, 1.0
	v_rcp_f32_e32 v120, v117
	s_nop 0
	v_fma_f32 v121, -v117, v120, 1.0
	v_fmac_f32_e32 v120, v121, v120
	v_div_scale_f32 v121, vcc, 1.0, v119, 1.0
	v_mul_f32_e32 v124, v121, v120
	v_fma_f32 v125, -v117, v124, v121
	v_fmac_f32_e32 v124, v125, v120
	v_fma_f32 v117, -v117, v124, v121
	v_div_fmas_f32 v117, v117, v120, v124
	v_div_fixup_f32 v119, v117, v119, 1.0
	v_div_scale_f32 v117, s[0:1], v118, v118, 1.0
	v_rcp_f32_e32 v120, v117
	s_nop 0
	v_fma_f32 v121, -v117, v120, 1.0
	v_fmac_f32_e32 v120, v121, v120
	v_div_scale_f32 v121, vcc, 1.0, v118, 1.0
	v_mul_f32_e32 v124, v121, v120
	v_fma_f32 v125, -v117, v124, v121
	v_fmac_f32_e32 v124, v125, v120
	v_fma_f32 v117, -v117, v124, v121
	v_div_fmas_f32 v117, v117, v120, v124
	v_div_fixup_f32 v118, v117, v118, 1.0
	v_pk_mul_f32 v[118:119], v[118:119], s[4:5] op_sel_hi:[1,0]
	s_nop 0
	v_cvt_pk_f16_f32 v117, v118, v119
	v_lshlrev_b64 v[118:119], 12, v[122:123]
	v_lshl_add_u64 v[118:119], s[6:7], 0, v[118:119]
	v_lshl_add_u64 v[118:119], v[118:119], 0, v[136:137]
	global_store_dwordx4 v[118:119], v[114:117], off
	v_pk_add_f32 v[106:107], v[106:107], v[90:91]
	v_pk_add_f32 v[110:111], v[110:111], v[94:95]
	v_mul_f32_e32 v106, 0xbfb8aa3b, v106
	v_exp_f32_e32 v120, v106
	v_mul_f32_e32 v106, 0xbfb8aa3b, v111
	v_pk_add_f32 v[112:113], v[112:113], v[96:97]
	v_mul_f32_e32 v110, 0xbfb8aa3b, v110
	v_exp_f32_e32 v117, v106
	v_mul_f32_e32 v106, 0xbfb8aa3b, v107
	v_pk_add_f32 v[108:109], v[108:109], v[92:93]
	v_exp_f32_e32 v116, v110
	v_exp_f32_e32 v121, v106
	v_mul_f32_e32 v106, 0xbfb8aa3b, v112
	v_exp_f32_e32 v112, v106
	v_mul_f32_e32 v106, 0xbfb8aa3b, v108
	v_exp_f32_e32 v110, v106
	v_mul_f32_e32 v106, 0xbfb8aa3b, v113
	v_exp_f32_e32 v113, v106
	v_mul_f32_e32 v106, 0xbfb8aa3b, v109
	v_exp_f32_e32 v111, v106
	v_pk_add_f32 v[106:107], v[116:117], 1.0 op_sel_hi:[1,0]
	v_or_b32_e32 v114, 48, v150
	v_div_scale_f32 v108, s[0:1], v107, v107, 1.0
	v_rcp_f32_e32 v109, v108
	v_pk_add_f32 v[110:111], v[110:111], 1.0 op_sel_hi:[1,0]
	v_ashrrev_i32_e32 v115, 31, v114
	v_fma_f32 v116, -v108, v109, 1.0
	v_fmac_f32_e32 v109, v116, v109
	v_div_scale_f32 v116, vcc, 1.0, v107, 1.0
	v_mul_f32_e32 v117, v116, v109
	v_fma_f32 v122, -v108, v117, v116
	v_fmac_f32_e32 v117, v122, v109
	v_fma_f32 v108, -v108, v117, v116
	v_div_fmas_f32 v108, v108, v109, v117
	v_div_fixup_f32 v107, v108, v107, 1.0
	v_div_scale_f32 v108, s[0:1], v106, v106, 1.0
	v_rcp_f32_e32 v109, v108
	s_nop 0
	v_fma_f32 v116, -v108, v109, 1.0
	v_fmac_f32_e32 v109, v116, v109
	v_div_scale_f32 v116, vcc, 1.0, v106, 1.0
	v_mul_f32_e32 v117, v116, v109
	v_fma_f32 v122, -v108, v117, v116
	v_fmac_f32_e32 v117, v122, v109
	v_fma_f32 v108, -v108, v117, v116
	v_div_fmas_f32 v108, v108, v109, v117
	v_div_fixup_f32 v106, v108, v106, 1.0
	v_pk_mul_f32 v[106:107], v[106:107], s[4:5] op_sel_hi:[1,0]
	v_pk_add_f32 v[108:109], v[112:113], 1.0 op_sel_hi:[1,0]
	v_cvt_pk_f16_f32 v106, v106, v107
	v_div_scale_f32 v107, s[0:1], v109, v109, 1.0
	v_rcp_f32_e32 v112, v107
	s_nop 0
	v_fma_f32 v113, -v107, v112, 1.0
	v_fmac_f32_e32 v112, v113, v112
; __device__ __forceinline__ float sigmoidf_(float x) { return 1.0f / (1.0f + __expf(-x)); }
;     template <int GI>
;     __device__ __forceinline__ void body(const f32x4 (&acc)[2][2][4][2], int row0, int colt) const {
;     ...
;             for (int ai = 0; ai < 2; ++ai)
; #pragma unroll
;                 for (int m = 0; m < 4; ++m) {
;                     const size_t row = (size_t)(row0 + ai * 128 + m * 16);
;                     f32x4 x0 = acc[ai][bj][m][0] + b0, x1 = acc[ai][bj][m][1] + b1;
;                     if (GI == 0) {
; #pragma unroll
;                         for (int j = 0; j < 4; ++j) {
;                             x0[j] = 0.6065306597126334f * sigmoidf_(x0[j]); x1[j] = 0.6065306597126334f * sigmoidf_(x1[j]); }
;                         *(u32x4*)(DEC + row * DM + c) = pack8(x0, x1);
	v_div_scale_f32 v113, vcc, 1.0, v109, 1.0
	v_mul_f32_e32 v116, v113, v112
	v_fma_f32 v117, -v107, v116, v113
	v_fmac_f32_e32 v116, v117, v112
	v_fma_f32 v107, -v107, v116, v113
	v_div_fmas_f32 v107, v107, v112, v116
	v_div_fixup_f32 v109, v107, v109, 1.0
	v_div_scale_f32 v107, s[0:1], v108, v108, 1.0
	v_rcp_f32_e32 v112, v107
	s_nop 0
	v_fma_f32 v113, -v107, v112, 1.0
	v_fmac_f32_e32 v112, v113, v112
	v_div_scale_f32 v113, vcc, 1.0, v108, 1.0
	v_mul_f32_e32 v116, v113, v112
	v_fma_f32 v117, -v107, v116, v113
	v_fmac_f32_e32 v116, v117, v112
	v_fma_f32 v107, -v107, v116, v113
	v_div_fmas_f32 v107, v107, v112, v116
	v_div_fixup_f32 v108, v107, v108, 1.0
	v_pk_mul_f32 v[108:109], v[108:109], s[4:5] op_sel_hi:[1,0]
	s_nop 0
	v_cvt_pk_f16_f32 v107, v108, v109
	v_pk_add_f32 v[108:109], v[120:121], 1.0 op_sel_hi:[1,0]
	s_nop 0
	v_div_scale_f32 v112, s[0:1], v109, v109, 1.0
	v_rcp_f32_e32 v113, v112
	s_nop 0
	v_fma_f32 v116, -v112, v113, 1.0
	v_fmac_f32_e32 v113, v116, v113
	v_div_scale_f32 v116, vcc, 1.0, v109, 1.0
	v_mul_f32_e32 v117, v116, v113
	v_fma_f32 v120, -v112, v117, v116
	v_fmac_f32_e32 v117, v120, v113
	v_fma_f32 v112, -v112, v117, v116
	v_div_fmas_f32 v112, v112, v113, v117
	v_div_fixup_f32 v109, v112, v109, 1.0
	v_div_scale_f32 v112, s[0:1], v108, v108, 1.0
	v_rcp_f32_e32 v113, v112
	s_nop 0
	v_fma_f32 v116, -v112, v113, 1.0
	v_fmac_f32_e32 v113, v116, v113
	v_div_scale_f32 v116, vcc, 1.0, v108, 1.0
	v_mul_f32_e32 v117, v116, v113
	v_fma_f32 v120, -v112, v117, v116
	v_fmac_f32_e32 v117, v120, v113
	v_fma_f32 v112, -v112, v117, v116
	v_div_fmas_f32 v112, v112, v113, v117
	v_div_fixup_f32 v108, v112, v108, 1.0
	v_pk_mul_f32 v[108:109], v[108:109], s[4:5] op_sel_hi:[1,0]
	s_nop 0
	v_cvt_pk_f16_f32 v108, v108, v109
	v_div_scale_f32 v109, s[0:1], v111, v111, 1.0
	v_rcp_f32_e32 v112, v109
	s_nop 0
	v_fma_f32 v113, -v109, v112, 1.0
	v_fmac_f32_e32 v112, v113, v112
	v_div_scale_f32 v113, vcc, 1.0, v111, 1.0
	v_mul_f32_e32 v116, v113, v112
	v_fma_f32 v117, -v109, v116, v113
	v_fmac_f32_e32 v116, v117, v112
	v_fma_f32 v109, -v109, v116, v113
	v_div_fmas_f32 v109, v109, v112, v116
	v_div_fixup_f32 v111, v109, v111, 1.0
	v_div_scale_f32 v109, s[0:1], v110, v110, 1.0
	v_rcp_f32_e32 v112, v109
	s_nop 0
	v_fma_f32 v113, -v109, v112, 1.0
	v_fmac_f32_e32 v112, v113, v112
	v_div_scale_f32 v113, vcc, 1.0, v110, 1.0
	v_mul_f32_e32 v116, v113, v112
	v_fma_f32 v117, -v109, v116, v113
	v_fmac_f32_e32 v116, v117, v112
	v_fma_f32 v109, -v109, v116, v113
	v_div_fmas_f32 v109, v109, v112, v116
	v_div_fixup_f32 v110, v109, v110, 1.0
	v_pk_mul_f32 v[110:111], v[110:111], s[4:5] op_sel_hi:[1,0]
	s_nop 0
	v_cvt_pk_f16_f32 v109, v110, v111
	v_lshlrev_b64 v[110:111], 12, v[114:115]
	v_lshl_add_u64 v[110:111], s[6:7], 0, v[110:111]
	v_lshl_add_u64 v[110:111], v[110:111], 0, v[136:137]
	global_store_dwordx4 v[110:111], v[106:109], off
	v_pk_add_f32 v[98:99], v[98:99], v[90:91]
	v_pk_add_f32 v[102:103], v[102:103], v[94:95]
	v_mul_f32_e32 v98, 0xbfb8aa3b, v98
	v_exp_f32_e32 v108, v98
	v_mul_f32_e32 v98, 0xbfb8aa3b, v103
	v_pk_add_f32 v[104:105], v[104:105], v[96:97]
	v_mul_f32_e32 v102, 0xbfb8aa3b, v102
	v_exp_f32_e32 v107, v98
	v_mul_f32_e32 v98, 0xbfb8aa3b, v99
	v_pk_add_f32 v[100:101], v[100:101], v[92:93]
	v_exp_f32_e32 v106, v102
	v_exp_f32_e32 v109, v98
	v_mul_f32_e32 v98, 0xbfb8aa3b, v104
	v_exp_f32_e32 v104, v98
	v_mul_f32_e32 v98, 0xbfb8aa3b, v100
	v_exp_f32_e32 v102, v98
	v_mul_f32_e32 v98, 0xbfb8aa3b, v105
	v_exp_f32_e32 v105, v98
	v_mul_f32_e32 v98, 0xbfb8aa3b, v101
	v_exp_f32_e32 v103, v98
	v_pk_add_f32 v[98:99], v[106:107], 1.0 op_sel_hi:[1,0]
	v_pk_add_f32 v[102:103], v[102:103], 1.0 op_sel_hi:[1,0]
	v_div_scale_f32 v100, s[0:1], v99, v99, 1.0
	v_rcp_f32_e32 v101, v100
	s_nop 0
	v_fma_f32 v106, -v100, v101, 1.0
	v_fmac_f32_e32 v101, v106, v101
	v_div_scale_f32 v106, vcc, 1.0, v99, 1.0
	v_mul_f32_e32 v107, v106, v101
	v_fma_f32 v112, -v100, v107, v106
	v_fmac_f32_e32 v107, v112, v101
	v_fma_f32 v100, -v100, v107, v106
	v_div_fmas_f32 v100, v100, v101, v107
	v_div_fixup_f32 v99, v100, v99, 1.0
	v_div_scale_f32 v100, s[0:1], v98, v98, 1.0
	v_rcp_f32_e32 v101, v100
	s_nop 0
	v_fma_f32 v106, -v100, v101, 1.0
	v_fmac_f32_e32 v101, v106, v101
	v_div_scale_f32 v106, vcc, 1.0, v98, 1.0
	v_mul_f32_e32 v107, v106, v101
	v_fma_f32 v112, -v100, v107, v106
	v_fmac_f32_e32 v107, v112, v101
	v_fma_f32 v100, -v100, v107, v106
	v_div_fmas_f32 v100, v100, v101, v107
	v_div_fixup_f32 v98, v100, v98, 1.0
	v_pk_mul_f32 v[98:99], v[98:99], s[4:5] op_sel_hi:[1,0]
	v_pk_add_f32 v[100:101], v[104:105], 1.0 op_sel_hi:[1,0]
	v_cvt_pk_f16_f32 v98, v98, v99
	v_div_scale_f32 v99, s[0:1], v101, v101, 1.0
	v_rcp_f32_e32 v104, v99
	s_nop 0
	v_fma_f32 v105, -v99, v104, 1.0
	v_fmac_f32_e32 v104, v105, v104
	v_div_scale_f32 v105, vcc, 1.0, v101, 1.0
	v_mul_f32_e32 v106, v105, v104
	v_fma_f32 v107, -v99, v106, v105
	v_fmac_f32_e32 v106, v107, v104
	v_fma_f32 v99, -v99, v106, v105
	v_div_fmas_f32 v99, v99, v104, v106
	v_div_fixup_f32 v101, v99, v101, 1.0
	v_div_scale_f32 v99, s[0:1], v100, v100, 1.0
	v_rcp_f32_e32 v104, v99
	s_nop 0
	v_fma_f32 v105, -v99, v104, 1.0
	v_fmac_f32_e32 v104, v105, v104
	v_div_scale_f32 v105, vcc, 1.0, v100, 1.0
	v_mul_f32_e32 v106, v105, v104
	v_fma_f32 v107, -v99, v106, v105
	v_fmac_f32_e32 v106, v107, v104
	v_fma_f32 v99, -v99, v106, v105
	v_div_fmas_f32 v99, v99, v104, v106
	v_div_fixup_f32 v100, v99, v100, 1.0
	v_pk_mul_f32 v[100:101], v[100:101], s[4:5] op_sel_hi:[1,0]
	s_nop 0
	v_cvt_pk_f16_f32 v99, v100, v101
	v_pk_add_f32 v[100:101], v[108:109], 1.0 op_sel_hi:[1,0]
	s_nop 0
	v_div_scale_f32 v104, s[0:1], v101, v101, 1.0
	v_rcp_f32_e32 v105, v104
; __device__ __forceinline__ float sigmoidf_(float x) { return 1.0f / (1.0f + __expf(-x)); }
;     template <int GI>
;     __device__ __forceinline__ void body(const f32x4 (&acc)[2][2][4][2], int row0, int colt) const {
;     ...
;             for (int ai = 0; ai < 2; ++ai)
; #pragma unroll
;                 for (int m = 0; m < 4; ++m) {
;                     const size_t row = (size_t)(row0 + ai * 128 + m * 16);
;                     f32x4 x0 = acc[ai][bj][m][0] + b0, x1 = acc[ai][bj][m][1] + b1;
;                     if (GI == 0) {
; #pragma unroll
;                         for (int j = 0; j < 4; ++j) {
;                             x0[j] = 0.6065306597126334f * sigmoidf_(x0[j]); x1[j] = 0.6065306597126334f * sigmoidf_(x1[j]); }
;                         *(u32x4*)(DEC + row * DM + c) = pack8(x0, x1);
	s_nop 0
	v_fma_f32 v106, -v104, v105, 1.0
	v_fmac_f32_e32 v105, v106, v105
	v_div_scale_f32 v106, vcc, 1.0, v101, 1.0
	v_mul_f32_e32 v107, v106, v105
	v_fma_f32 v108, -v104, v107, v106
	v_fmac_f32_e32 v107, v108, v105
	v_fma_f32 v104, -v104, v107, v106
	v_div_fmas_f32 v104, v104, v105, v107
	v_div_fixup_f32 v101, v104, v101, 1.0
	v_div_scale_f32 v104, s[0:1], v100, v100, 1.0
	v_rcp_f32_e32 v105, v104
	s_nop 0
	v_fma_f32 v106, -v104, v105, 1.0
	v_fmac_f32_e32 v105, v106, v105
	v_div_scale_f32 v106, vcc, 1.0, v100, 1.0
	v_mul_f32_e32 v107, v106, v105
	v_fma_f32 v108, -v104, v107, v106
	v_fmac_f32_e32 v107, v108, v105
	v_fma_f32 v104, -v104, v107, v106
	v_div_fmas_f32 v104, v104, v105, v107
	v_div_fixup_f32 v100, v104, v100, 1.0
	v_pk_mul_f32 v[100:101], v[100:101], s[4:5] op_sel_hi:[1,0]
	s_nop 0
	v_cvt_pk_f16_f32 v100, v100, v101
	v_div_scale_f32 v101, s[0:1], v103, v103, 1.0
	v_rcp_f32_e32 v104, v101
	s_nop 0
	v_fma_f32 v105, -v101, v104, 1.0
	v_fmac_f32_e32 v104, v105, v104
	v_div_scale_f32 v105, vcc, 1.0, v103, 1.0
	v_mul_f32_e32 v106, v105, v104
	v_fma_f32 v107, -v101, v106, v105
	v_fmac_f32_e32 v106, v107, v104
	v_fma_f32 v101, -v101, v106, v105
	v_div_fmas_f32 v101, v101, v104, v106
	v_div_fixup_f32 v103, v101, v103, 1.0
	v_div_scale_f32 v101, s[0:1], v102, v102, 1.0
	v_rcp_f32_e32 v104, v101
	s_mov_b32 s0, 0x80000
	v_fma_f32 v105, -v101, v104, 1.0
	v_fmac_f32_e32 v104, v105, v104
	v_div_scale_f32 v105, vcc, 1.0, v102, 1.0
	v_mul_f32_e32 v106, v105, v104
	v_fma_f32 v107, -v101, v106, v105
	v_fmac_f32_e32 v106, v107, v104
	v_fma_f32 v101, -v101, v106, v105
	v_div_fmas_f32 v101, v101, v104, v106
	v_div_fixup_f32 v102, v101, v102, 1.0
	v_pk_mul_f32 v[102:103], v[102:103], s[4:5] op_sel_hi:[1,0]
	v_add_co_u32_e32 v104, vcc, s0, v134
	v_cvt_pk_f16_f32 v101, v102, v103
	s_nop 0
	v_addc_co_u32_e32 v105, vcc, 0, v135, vcc
	v_lshl_add_u64 v[102:103], v[134:135], 0, s[10:11]
	global_store_dwordx4 v[104:105], v[98:101], off
	v_pk_add_f32 v[82:83], v[82:83], v[90:91]
	v_pk_add_f32 v[86:87], v[86:87], v[94:95]
	v_mul_f32_e32 v82, 0xbfb8aa3b, v82
	v_exp_f32_e32 v100, v82
	v_mul_f32_e32 v82, 0xbfb8aa3b, v87
	v_pk_add_f32 v[88:89], v[88:89], v[96:97]
	v_mul_f32_e32 v86, 0xbfb8aa3b, v86
	v_exp_f32_e32 v99, v82
	v_mul_f32_e32 v82, 0xbfb8aa3b, v83
	v_pk_add_f32 v[84:85], v[84:85], v[92:93]
	v_exp_f32_e32 v98, v86
	v_exp_f32_e32 v101, v82
	v_mul_f32_e32 v82, 0xbfb8aa3b, v88
	v_exp_f32_e32 v88, v82
	v_mul_f32_e32 v82, 0xbfb8aa3b, v84
	v_exp_f32_e32 v86, v82
	v_mul_f32_e32 v82, 0xbfb8aa3b, v89
	v_exp_f32_e32 v89, v82
	v_mul_f32_e32 v82, 0xbfb8aa3b, v85
	v_exp_f32_e32 v87, v82
	v_pk_add_f32 v[82:83], v[98:99], 1.0 op_sel_hi:[1,0]
	v_pk_add_f32 v[86:87], v[86:87], 1.0 op_sel_hi:[1,0]
	v_div_scale_f32 v84, s[0:1], v83, v83, 1.0
	v_rcp_f32_e32 v85, v84
	s_nop 0
	v_fma_f32 v98, -v84, v85, 1.0
	v_fmac_f32_e32 v85, v98, v85
	v_div_scale_f32 v98, vcc, 1.0, v83, 1.0
	v_mul_f32_e32 v99, v98, v85
	v_fma_f32 v104, -v84, v99, v98
	v_fmac_f32_e32 v99, v104, v85
	v_fma_f32 v84, -v84, v99, v98
	v_div_fmas_f32 v84, v84, v85, v99
	v_div_fixup_f32 v83, v84, v83, 1.0
	v_div_scale_f32 v84, s[0:1], v82, v82, 1.0
	v_rcp_f32_e32 v85, v84
	s_nop 0
	v_fma_f32 v98, -v84, v85, 1.0
	v_fmac_f32_e32 v85, v98, v85
	v_div_scale_f32 v98, vcc, 1.0, v82, 1.0
	v_mul_f32_e32 v99, v98, v85
	v_fma_f32 v104, -v84, v99, v98
	v_fmac_f32_e32 v99, v104, v85
	v_fma_f32 v84, -v84, v99, v98
	v_div_fmas_f32 v84, v84, v85, v99
	v_div_fixup_f32 v82, v84, v82, 1.0
	v_pk_mul_f32 v[82:83], v[82:83], s[4:5] op_sel_hi:[1,0]
	v_pk_add_f32 v[84:85], v[88:89], 1.0 op_sel_hi:[1,0]
	v_cvt_pk_f16_f32 v82, v82, v83
	v_div_scale_f32 v83, s[0:1], v85, v85, 1.0
	v_rcp_f32_e32 v88, v83
	s_nop 0
	v_fma_f32 v89, -v83, v88, 1.0
	v_fmac_f32_e32 v88, v89, v88
	v_div_scale_f32 v89, vcc, 1.0, v85, 1.0
	v_mul_f32_e32 v98, v89, v88
	v_fma_f32 v99, -v83, v98, v89
	v_fmac_f32_e32 v98, v99, v88
	v_fma_f32 v83, -v83, v98, v89
	v_div_fmas_f32 v83, v83, v88, v98
	v_div_fixup_f32 v85, v83, v85, 1.0
	v_div_scale_f32 v83, s[0:1], v84, v84, 1.0
	v_rcp_f32_e32 v88, v83
	s_nop 0
	v_fma_f32 v89, -v83, v88, 1.0
	v_fmac_f32_e32 v88, v89, v88
	v_div_scale_f32 v89, vcc, 1.0, v84, 1.0
	v_mul_f32_e32 v98, v89, v88
	v_fma_f32 v99, -v83, v98, v89
	v_fmac_f32_e32 v98, v99, v88
	v_fma_f32 v83, -v83, v98, v89
	v_div_fmas_f32 v83, v83, v88, v98
	v_div_fixup_f32 v84, v83, v84, 1.0
	v_pk_mul_f32 v[84:85], v[84:85], s[4:5] op_sel_hi:[1,0]
	s_nop 0
	v_cvt_pk_f16_f32 v83, v84, v85
	v_pk_add_f32 v[84:85], v[100:101], 1.0 op_sel_hi:[1,0]
	s_nop 0
	v_div_scale_f32 v88, s[0:1], v85, v85, 1.0
	v_rcp_f32_e32 v89, v88
	s_nop 0
	v_fma_f32 v98, -v88, v89, 1.0
	v_fmac_f32_e32 v89, v98, v89
	v_div_scale_f32 v98, vcc, 1.0, v85, 1.0
	v_mul_f32_e32 v99, v98, v89
	v_fma_f32 v100, -v88, v99, v98
	v_fmac_f32_e32 v99, v100, v89
	v_fma_f32 v88, -v88, v99, v98
	v_div_fmas_f32 v88, v88, v89, v99
	v_div_fixup_f32 v85, v88, v85, 1.0
	v_div_scale_f32 v88, s[0:1], v84, v84, 1.0
	v_rcp_f32_e32 v89, v88
	s_nop 0
	v_fma_f32 v98, -v88, v89, 1.0
	v_fmac_f32_e32 v89, v98, v89
	v_div_scale_f32 v98, vcc, 1.0, v84, 1.0
	v_mul_f32_e32 v99, v98, v89
	v_fma_f32 v100, -v88, v99, v98
	v_fmac_f32_e32 v99, v100, v89
	v_fma_f32 v88, -v88, v99, v98
	v_div_fmas_f32 v88, v88, v89, v99
	v_div_fixup_f32 v84, v88, v84, 1.0
	v_pk_mul_f32 v[84:85], v[84:85], s[4:5] op_sel_hi:[1,0]
	s_nop 0
	v_cvt_pk_f16_f32 v84, v84, v85
	v_div_scale_f32 v85, s[0:1], v87, v87, 1.0
	v_rcp_f32_e32 v88, v85
	s_nop 0
	v_fma_f32 v89, -v85, v88, 1.0
	v_fmac_f32_e32 v88, v89, v88
	v_div_scale_f32 v89, vcc, 1.0, v87, 1.0
	v_mul_f32_e32 v98, v89, v88
	v_fma_f32 v99, -v85, v98, v89
	v_fmac_f32_e32 v98, v99, v88
	v_fma_f32 v85, -v85, v98, v89
; __device__ __forceinline__ float sigmoidf_(float x) { return 1.0f / (1.0f + __expf(-x)); }
;     template <int GI>
;     __device__ __forceinline__ void body(const f32x4 (&acc)[2][2][4][2], int row0, int colt) const {
;     ...
;             for (int ai = 0; ai < 2; ++ai)
; #pragma unroll
;                 for (int m = 0; m < 4; ++m) {
;                     const size_t row = (size_t)(row0 + ai * 128 + m * 16);
;                     f32x4 x0 = acc[ai][bj][m][0] + b0, x1 = acc[ai][bj][m][1] + b1;
;                     if (GI == 0) {
; #pragma unroll
;                         for (int j = 0; j < 4; ++j) {
;                             x0[j] = 0.6065306597126334f * sigmoidf_(x0[j]); x1[j] = 0.6065306597126334f * sigmoidf_(x1[j]); }
;                         *(u32x4*)(DEC + row * DM + c) = pack8(x0, x1);
	v_div_fmas_f32 v85, v85, v88, v98
	v_div_fixup_f32 v87, v85, v87, 1.0
	v_div_scale_f32 v85, s[0:1], v86, v86, 1.0
	v_rcp_f32_e32 v88, v85
	s_mov_b32 s0, 0x90000
	v_fma_f32 v89, -v85, v88, 1.0
	v_fmac_f32_e32 v88, v89, v88
	v_div_scale_f32 v89, vcc, 1.0, v86, 1.0
	v_mul_f32_e32 v98, v89, v88
	v_fma_f32 v99, -v85, v98, v89
	v_fmac_f32_e32 v98, v99, v88
	v_fma_f32 v85, -v85, v98, v89
	v_div_fmas_f32 v85, v85, v88, v98
	v_div_fixup_f32 v86, v85, v86, 1.0
	v_pk_mul_f32 v[86:87], v[86:87], s[4:5] op_sel_hi:[1,0]
	v_add_co_u32_e32 v88, vcc, s0, v134
	v_cvt_pk_f16_f32 v85, v86, v87
	s_nop 0
	v_addc_co_u32_e32 v89, vcc, 0, v135, vcc
	v_lshl_add_u64 v[86:87], v[134:135], 0, s[18:19]
	global_store_dwordx4 v[88:89], v[82:85], off
	v_pk_add_f32 v[74:75], v[74:75], v[90:91]
	v_pk_add_f32 v[78:79], v[78:79], v[94:95]
	v_mul_f32_e32 v74, 0xbfb8aa3b, v74
	v_exp_f32_e32 v84, v74
	v_mul_f32_e32 v74, 0xbfb8aa3b, v79
	v_pk_add_f32 v[80:81], v[80:81], v[96:97]
	v_mul_f32_e32 v78, 0xbfb8aa3b, v78
	v_exp_f32_e32 v83, v74
	v_mul_f32_e32 v74, 0xbfb8aa3b, v75
	v_pk_add_f32 v[76:77], v[76:77], v[92:93]
	v_exp_f32_e32 v82, v78
	v_exp_f32_e32 v85, v74
	v_mul_f32_e32 v74, 0xbfb8aa3b, v80
	v_exp_f32_e32 v80, v74
	v_mul_f32_e32 v74, 0xbfb8aa3b, v76
	v_exp_f32_e32 v78, v74
	v_mul_f32_e32 v74, 0xbfb8aa3b, v81
	v_exp_f32_e32 v81, v74
	v_mul_f32_e32 v74, 0xbfb8aa3b, v77
	v_exp_f32_e32 v79, v74
	v_pk_add_f32 v[74:75], v[82:83], 1.0 op_sel_hi:[1,0]
	v_pk_add_f32 v[78:79], v[78:79], 1.0 op_sel_hi:[1,0]
	v_div_scale_f32 v76, s[0:1], v75, v75, 1.0
	v_rcp_f32_e32 v77, v76
	s_nop 0
	v_fma_f32 v82, -v76, v77, 1.0
	v_fmac_f32_e32 v77, v82, v77
	v_div_scale_f32 v82, vcc, 1.0, v75, 1.0
	v_mul_f32_e32 v83, v82, v77
	v_fma_f32 v88, -v76, v83, v82
	v_fmac_f32_e32 v83, v88, v77
	v_fma_f32 v76, -v76, v83, v82
	v_div_fmas_f32 v76, v76, v77, v83
	v_div_fixup_f32 v75, v76, v75, 1.0
	v_div_scale_f32 v76, s[0:1], v74, v74, 1.0
	v_rcp_f32_e32 v77, v76
	s_nop 0
	v_fma_f32 v82, -v76, v77, 1.0
	v_fmac_f32_e32 v77, v82, v77
	v_div_scale_f32 v82, vcc, 1.0, v74, 1.0
	v_mul_f32_e32 v83, v82, v77
	v_fma_f32 v88, -v76, v83, v82
	v_fmac_f32_e32 v83, v88, v77
	v_fma_f32 v76, -v76, v83, v82
	v_div_fmas_f32 v76, v76, v77, v83
	v_div_fixup_f32 v74, v76, v74, 1.0
	v_pk_mul_f32 v[74:75], v[74:75], s[4:5] op_sel_hi:[1,0]
	v_pk_add_f32 v[76:77], v[80:81], 1.0 op_sel_hi:[1,0]
	v_cvt_pk_f16_f32 v74, v74, v75
	v_div_scale_f32 v75, s[0:1], v77, v77, 1.0
	v_rcp_f32_e32 v80, v75
	s_nop 0
	v_fma_f32 v81, -v75, v80, 1.0
	v_fmac_f32_e32 v80, v81, v80
	v_div_scale_f32 v81, vcc, 1.0, v77, 1.0
	v_mul_f32_e32 v82, v81, v80
	v_fma_f32 v83, -v75, v82, v81
	v_fmac_f32_e32 v82, v83, v80
	v_fma_f32 v75, -v75, v82, v81
	v_div_fmas_f32 v75, v75, v80, v82
	v_div_fixup_f32 v77, v75, v77, 1.0
	v_div_scale_f32 v75, s[0:1], v76, v76, 1.0
	v_rcp_f32_e32 v80, v75
	s_nop 0
	v_fma_f32 v81, -v75, v80, 1.0
	v_fmac_f32_e32 v80, v81, v80
	v_div_scale_f32 v81, vcc, 1.0, v76, 1.0
	v_mul_f32_e32 v82, v81, v80
	v_fma_f32 v83, -v75, v82, v81
	v_fmac_f32_e32 v82, v83, v80
	v_fma_f32 v75, -v75, v82, v81
	v_div_fmas_f32 v75, v75, v80, v82
	v_div_fixup_f32 v76, v75, v76, 1.0
	v_pk_mul_f32 v[76:77], v[76:77], s[4:5] op_sel_hi:[1,0]
	s_nop 0
	v_cvt_pk_f16_f32 v75, v76, v77
	v_pk_add_f32 v[76:77], v[84:85], 1.0 op_sel_hi:[1,0]
	s_nop 0
	v_div_scale_f32 v80, s[0:1], v77, v77, 1.0
	v_rcp_f32_e32 v81, v80
	s_nop 0
	v_fma_f32 v82, -v80, v81, 1.0
	v_fmac_f32_e32 v81, v82, v81
	v_div_scale_f32 v82, vcc, 1.0, v77, 1.0
	v_mul_f32_e32 v83, v82, v81
	v_fma_f32 v84, -v80, v83, v82
	v_fmac_f32_e32 v83, v84, v81
	v_fma_f32 v80, -v80, v83, v82
	v_div_fmas_f32 v80, v80, v81, v83
	v_div_fixup_f32 v77, v80, v77, 1.0
	v_div_scale_f32 v80, s[0:1], v76, v76, 1.0
	v_rcp_f32_e32 v81, v80
	s_nop 0
	v_fma_f32 v82, -v80, v81, 1.0
	v_fmac_f32_e32 v81, v82, v81
	v_div_scale_f32 v82, vcc, 1.0, v76, 1.0
	v_mul_f32_e32 v83, v82, v81
	v_fma_f32 v84, -v80, v83, v82
	v_fmac_f32_e32 v83, v84, v81
	v_fma_f32 v80, -v80, v83, v82
	v_div_fmas_f32 v80, v80, v81, v83
	v_div_fixup_f32 v76, v80, v76, 1.0
	v_pk_mul_f32 v[76:77], v[76:77], s[4:5] op_sel_hi:[1,0]
	s_nop 0
	v_cvt_pk_f16_f32 v76, v76, v77
	v_div_scale_f32 v77, s[0:1], v79, v79, 1.0
	v_rcp_f32_e32 v80, v77
	s_nop 0
	v_fma_f32 v81, -v77, v80, 1.0
	v_fmac_f32_e32 v80, v81, v80
	v_div_scale_f32 v81, vcc, 1.0, v79, 1.0
	v_mul_f32_e32 v82, v81, v80
	v_fma_f32 v83, -v77, v82, v81
	v_fmac_f32_e32 v82, v83, v80
	v_fma_f32 v77, -v77, v82, v81
	v_div_fmas_f32 v77, v77, v80, v82
	v_div_fixup_f32 v79, v77, v79, 1.0
	v_div_scale_f32 v77, s[0:1], v78, v78, 1.0
	v_rcp_f32_e32 v80, v77
	s_mov_b32 s0, 0xa0000
	v_fma_f32 v81, -v77, v80, 1.0
	v_fmac_f32_e32 v80, v81, v80
	v_div_scale_f32 v81, vcc, 1.0, v78, 1.0
	v_mul_f32_e32 v82, v81, v80
	v_fma_f32 v83, -v77, v82, v81
	v_fmac_f32_e32 v82, v83, v80
	v_fma_f32 v77, -v77, v82, v81
	v_div_fmas_f32 v77, v77, v80, v82
	v_div_fixup_f32 v78, v77, v78, 1.0
	v_pk_mul_f32 v[78:79], v[78:79], s[4:5] op_sel_hi:[1,0]
	v_add_co_u32_e32 v80, vcc, s0, v134
	v_cvt_pk_f16_f32 v77, v78, v79
	s_nop 0
	v_addc_co_u32_e32 v81, vcc, 0, v135, vcc
	v_lshl_add_u64 v[78:79], v[134:135], 0, s[14:15]
	global_store_dwordx4 v[80:81], v[74:77], off
	v_pk_add_f32 v[66:67], v[66:67], v[90:91]
	v_pk_add_f32 v[70:71], v[70:71], v[94:95]
	v_mul_f32_e32 v66, 0xbfb8aa3b, v66
	v_mul_f32_e32 v70, 0xbfb8aa3b, v70
	v_exp_f32_e32 v74, v66
	v_mul_f32_e32 v66, 0xbfb8aa3b, v71
	v_exp_f32_e32 v70, v70
	v_exp_f32_e32 v71, v66
	v_pk_add_f32 v[72:73], v[72:73], v[96:97]
	v_pk_add_f32 v[68:69], v[68:69], v[92:93]
	v_mul_f32_e32 v66, 0xbfb8aa3b, v67
	v_pk_add_f32 v[70:71], v[70:71], 1.0 op_sel_hi:[1,0]
	v_exp_f32_e32 v75, v66
	v_mul_f32_e32 v66, 0xbfb8aa3b, v72
; __device__ __forceinline__ float sigmoidf_(float x) { return 1.0f / (1.0f + __expf(-x)); }
;     template <int GI>
;     __device__ __forceinline__ void body(const f32x4 (&acc)[2][2][4][2], int row0, int colt) const {
;     ...
;         for (int bj = 0; bj < 2; ++bj) {
;             const int c = colt + bj * 128;
;             f32x4 b0 = (f32x4){0.f, 0.f, 0.f, 0.f}, b1 = b0;
;             if (GI == 0) { b0 = *(const f32x4*)(w0 + c); b1 = *(const f32x4*)(w0 + c + 4); }
;             else if (GI == 1) { b0 = *(const f32x4*)(a0 + c); b1 = *(const f32x4*)(a0 + c + 4); }
;             else if (GI == 3) { b0 = *(const f32x4*)(v0 + c); b1 = *(const f32x4*)(v0 + c + 4); }
; #pragma unroll
;             for (int ai = 0; ai < 2; ++ai)
; #pragma unroll
;                 for (int m = 0; m < 4; ++m) {
;                     const size_t row = (size_t)(row0 + ai * 128 + m * 16);
;                     f32x4 x0 = acc[ai][bj][m][0] + b0, x1 = acc[ai][bj][m][1] + b1;
;                     if (GI == 0) {
; #pragma unroll
;                         for (int j = 0; j < 4; ++j) {
;                             x0[j] = 0.6065306597126334f * sigmoidf_(x0[j]); x1[j] = 0.6065306597126334f * sigmoidf_(x1[j]); }
;                         *(u32x4*)(DEC + row * DM + c) = pack8(x0, x1);
	v_mul_f32_e32 v67, 0xbfb8aa3b, v68
	v_div_scale_f32 v72, s[0:1], v71, v71, 1.0
	v_exp_f32_e32 v68, v67
	v_mul_f32_e32 v67, 0xbfb8aa3b, v73
	v_rcp_f32_e32 v73, v72
	v_exp_f32_e32 v66, v66
	v_exp_f32_e32 v67, v67
	v_pk_add_f32 v[74:75], v[74:75], 1.0 op_sel_hi:[1,0]
	v_fma_f32 v76, -v72, v73, 1.0
	v_fmac_f32_e32 v73, v76, v73
	v_div_scale_f32 v76, vcc, 1.0, v71, 1.0
	v_mul_f32_e32 v77, v76, v73
	v_fma_f32 v80, -v72, v77, v76
	v_fmac_f32_e32 v77, v80, v73
	v_fma_f32 v72, -v72, v77, v76
	v_div_scale_f32 v76, s[0:1], v70, v70, 1.0
	v_rcp_f32_e32 v80, v76
	v_div_fmas_f32 v72, v72, v73, v77
	v_div_fixup_f32 v71, v72, v71, 1.0
	v_mul_f32_e32 v69, 0xbfb8aa3b, v69
	v_fma_f32 v72, -v76, v80, 1.0
	v_fmac_f32_e32 v80, v72, v80
	v_div_scale_f32 v72, vcc, 1.0, v70, 1.0
	v_mul_f32_e32 v73, v72, v80
	v_fma_f32 v77, -v76, v73, v72
	v_fmac_f32_e32 v73, v77, v80
	v_fma_f32 v72, -v76, v73, v72
	v_div_fmas_f32 v76, v72, v80, v73
	v_pk_add_f32 v[72:73], v[66:67], 1.0 op_sel_hi:[1,0]
	v_div_fixup_f32 v70, v76, v70, 1.0
	v_div_scale_f32 v77, s[0:1], v73, v73, 1.0
	v_rcp_f32_e32 v80, v77
	v_pk_mul_f32 v[66:67], v[70:71], s[4:5] op_sel_hi:[1,0]
	v_div_scale_f32 v76, s[0:1], v72, v72, 1.0
	v_cvt_pk_f16_f32 v66, v66, v67
	v_fma_f32 v67, -v77, v80, 1.0
	v_fmac_f32_e32 v80, v67, v80
	v_div_scale_f32 v67, vcc, 1.0, v73, 1.0
	v_mul_f32_e32 v70, v67, v80
	v_fma_f32 v71, -v77, v70, v67
	v_fmac_f32_e32 v70, v71, v80
	v_fma_f32 v67, -v77, v70, v67
	v_rcp_f32_e32 v77, v76
	v_div_fmas_f32 v67, v67, v80, v70
	v_div_fixup_f32 v71, v67, v73, 1.0
	v_exp_f32_e32 v69, v69
	v_fma_f32 v67, -v76, v77, 1.0
	v_fmac_f32_e32 v77, v67, v77
	v_div_scale_f32 v67, vcc, 1.0, v72, 1.0
	v_mul_f32_e32 v70, v67, v77
	v_fma_f32 v73, -v76, v70, v67
	v_fmac_f32_e32 v70, v73, v77
	v_div_scale_f32 v73, s[0:1], v75, v75, 1.0
	v_fma_f32 v67, -v76, v70, v67
	v_rcp_f32_e32 v76, v73
	v_div_fmas_f32 v67, v67, v77, v70
	v_div_fixup_f32 v70, v67, v72, 1.0
	v_pk_mul_f32 v[70:71], v[70:71], s[4:5] op_sel_hi:[1,0]
	s_nop 0
	v_cvt_pk_f16_f32 v67, v70, v71
	v_fma_f32 v70, -v73, v76, 1.0
	v_fmac_f32_e32 v76, v70, v76
	v_div_scale_f32 v70, vcc, 1.0, v75, 1.0
	v_mul_f32_e32 v71, v70, v76
	v_fma_f32 v72, -v73, v71, v70
	v_fmac_f32_e32 v71, v72, v76
	v_div_scale_f32 v72, s[0:1], v74, v74, 1.0
	v_fma_f32 v70, -v73, v71, v70
	v_rcp_f32_e32 v73, v72
	v_div_fmas_f32 v70, v70, v76, v71
	v_div_fixup_f32 v71, v70, v75, 1.0
	v_fma_f32 v70, -v72, v73, 1.0
	v_fmac_f32_e32 v73, v70, v73
	v_div_scale_f32 v70, vcc, 1.0, v74, 1.0
	v_mul_f32_e32 v75, v70, v73
	v_fma_f32 v76, -v72, v75, v70
	v_fmac_f32_e32 v75, v76, v73
	v_fma_f32 v70, -v72, v75, v70
	v_div_fmas_f32 v70, v70, v73, v75
	v_pk_add_f32 v[72:73], v[68:69], 1.0 op_sel_hi:[1,0]
	v_div_fixup_f32 v70, v70, v74, 1.0
	v_div_scale_f32 v75, s[0:1], v73, v73, 1.0
	v_rcp_f32_e32 v76, v75
	v_pk_mul_f32 v[68:69], v[70:71], s[4:5] op_sel_hi:[1,0]
	v_div_scale_f32 v74, s[0:1], v72, v72, 1.0
	v_cvt_pk_f16_f32 v68, v68, v69
	v_fma_f32 v69, -v75, v76, 1.0
	v_fmac_f32_e32 v76, v69, v76
	v_div_scale_f32 v69, vcc, 1.0, v73, 1.0
	v_mul_f32_e32 v70, v69, v76
	v_fma_f32 v71, -v75, v70, v69
	v_fmac_f32_e32 v70, v71, v76
	v_fma_f32 v69, -v75, v70, v69
	v_rcp_f32_e32 v75, v74
	v_div_fmas_f32 v69, v69, v76, v70
	v_div_fixup_f32 v71, v69, v73, 1.0
	s_mov_b32 s0, 0xb0000
	v_fma_f32 v69, -v74, v75, 1.0
	v_fmac_f32_e32 v75, v69, v75
	v_div_scale_f32 v69, vcc, 1.0, v72, 1.0
	v_mul_f32_e32 v70, v69, v75
	v_fma_f32 v73, -v74, v70, v69
	v_fmac_f32_e32 v70, v73, v75
	v_fma_f32 v69, -v74, v70, v69
	v_div_fmas_f32 v69, v69, v75, v70
	v_div_fixup_f32 v70, v69, v72, 1.0
	v_pk_mul_f32 v[70:71], v[70:71], s[4:5] op_sel_hi:[1,0]
	v_lshl_add_u64 v[74:75], v[134:135], 0, s[16:17]
	v_cvt_pk_f16_f32 v69, v70, v71
	v_add_co_u32_e32 v70, vcc, s0, v134
	s_nop 1
	v_addc_co_u32_e32 v71, vcc, 0, v135, vcc
	global_store_dwordx4 v[70:71], v[66:69], off
	global_load_dwordx4 v[66:69], v[148:149], off offset:528
	s_nop 0
	global_load_dwordx4 v[70:73], v[148:149], off offset:512
	s_waitcnt vmcnt(0)
	v_pk_add_f32 v[58:59], v[58:59], v[66:67]
	v_pk_add_f32 v[62:63], v[62:63], v[70:71]
	v_pk_add_f32 v[76:77], v[60:61], v[68:69]
	v_mul_f32_e32 v60, 0xbfb8aa3b, v62
	v_mul_f32_e32 v58, 0xbfb8aa3b, v58
	v_exp_f32_e32 v80, v60
	v_exp_f32_e32 v60, v58
	v_mul_f32_e32 v58, 0xbfb8aa3b, v63
	v_pk_add_f32 v[64:65], v[64:65], v[72:73]
	v_exp_f32_e32 v81, v58
	v_mul_f32_e32 v58, 0xbfb8aa3b, v59
	v_exp_f32_e32 v61, v58
	v_mul_f32_e32 v58, 0xbfb8aa3b, v64
	v_exp_f32_e32 v64, v58
	v_mul_f32_e32 v58, 0xbfb8aa3b, v76
	v_exp_f32_e32 v62, v58
	v_mul_f32_e32 v58, 0xbfb8aa3b, v65
	v_exp_f32_e32 v65, v58
	v_mul_f32_e32 v58, 0xbfb8aa3b, v77
	v_exp_f32_e32 v63, v58
	v_pk_add_f32 v[58:59], v[80:81], 1.0 op_sel_hi:[1,0]
	v_pk_add_f32 v[64:65], v[64:65], 1.0 op_sel_hi:[1,0]
	v_div_scale_f32 v76, s[0:1], v59, v59, 1.0
	v_rcp_f32_e32 v77, v76
	v_pk_add_f32 v[60:61], v[60:61], 1.0 op_sel_hi:[1,0]
	v_pk_add_f32 v[62:63], v[62:63], 1.0 op_sel_hi:[1,0]
	v_fma_f32 v80, -v76, v77, 1.0
	v_fmac_f32_e32 v77, v80, v77
	v_div_scale_f32 v80, vcc, 1.0, v59, 1.0
	v_mul_f32_e32 v81, v80, v77
	v_fma_f32 v82, -v76, v81, v80
	v_fmac_f32_e32 v81, v82, v77
	v_fma_f32 v76, -v76, v81, v80
	v_div_fmas_f32 v76, v76, v77, v81
	v_div_fixup_f32 v59, v76, v59, 1.0
	v_div_scale_f32 v76, s[0:1], v58, v58, 1.0
	v_rcp_f32_e32 v77, v76
	s_nop 0
	v_fma_f32 v80, -v76, v77, 1.0
	v_fmac_f32_e32 v77, v80, v77
	v_div_scale_f32 v80, vcc, 1.0, v58, 1.0
	v_mul_f32_e32 v81, v80, v77
	v_fma_f32 v82, -v76, v81, v80
	v_fmac_f32_e32 v81, v82, v77
	v_fma_f32 v76, -v76, v81, v80
	v_div_fmas_f32 v76, v76, v77, v81
	v_div_fixup_f32 v58, v76, v58, 1.0
	v_pk_mul_f32 v[58:59], v[58:59], s[4:5] op_sel_hi:[1,0]
; __device__ __forceinline__ float sigmoidf_(float x) { return 1.0f / (1.0f + __expf(-x)); }
;     template <int GI>
;     __device__ __forceinline__ void body(const f32x4 (&acc)[2][2][4][2], int row0, int colt) const {
;     ...
;             for (int ai = 0; ai < 2; ++ai)
; #pragma unroll
;                 for (int m = 0; m < 4; ++m) {
;                     const size_t row = (size_t)(row0 + ai * 128 + m * 16);
;                     f32x4 x0 = acc[ai][bj][m][0] + b0, x1 = acc[ai][bj][m][1] + b1;
;                     if (GI == 0) {
; #pragma unroll
;                         for (int j = 0; j < 4; ++j) {
;                             x0[j] = 0.6065306597126334f * sigmoidf_(x0[j]); x1[j] = 0.6065306597126334f * sigmoidf_(x1[j]); }
;                         *(u32x4*)(DEC + row * DM + c) = pack8(x0, x1);
	s_nop 0
	v_cvt_pk_f16_f32 v58, v58, v59
	v_div_scale_f32 v59, s[0:1], v65, v65, 1.0
	v_rcp_f32_e32 v76, v59
	s_nop 0
	v_fma_f32 v77, -v59, v76, 1.0
	v_fmac_f32_e32 v76, v77, v76
	v_div_scale_f32 v77, vcc, 1.0, v65, 1.0
	v_mul_f32_e32 v80, v77, v76
	v_fma_f32 v81, -v59, v80, v77
	v_fmac_f32_e32 v80, v81, v76
	v_fma_f32 v59, -v59, v80, v77
	v_div_fmas_f32 v59, v59, v76, v80
	v_div_fixup_f32 v65, v59, v65, 1.0
	v_div_scale_f32 v59, s[0:1], v64, v64, 1.0
	v_rcp_f32_e32 v76, v59
	s_nop 0
	v_fma_f32 v77, -v59, v76, 1.0
	v_fmac_f32_e32 v76, v77, v76
	v_div_scale_f32 v77, vcc, 1.0, v64, 1.0
	v_mul_f32_e32 v80, v77, v76
	v_fma_f32 v81, -v59, v80, v77
	v_fmac_f32_e32 v80, v81, v76
	v_fma_f32 v59, -v59, v80, v77
	v_div_fmas_f32 v59, v59, v76, v80
	v_div_fixup_f32 v64, v59, v64, 1.0
	v_pk_mul_f32 v[64:65], v[64:65], s[4:5] op_sel_hi:[1,0]
	s_nop 0
	v_cvt_pk_f16_f32 v59, v64, v65
	v_div_scale_f32 v64, s[0:1], v61, v61, 1.0
	v_rcp_f32_e32 v65, v64
	s_nop 0
	v_fma_f32 v76, -v64, v65, 1.0
	v_fmac_f32_e32 v65, v76, v65
	v_div_scale_f32 v76, vcc, 1.0, v61, 1.0
	v_mul_f32_e32 v77, v76, v65
	v_fma_f32 v80, -v64, v77, v76
	v_fmac_f32_e32 v77, v80, v65
	v_fma_f32 v64, -v64, v77, v76
	v_div_fmas_f32 v64, v64, v65, v77
	v_div_fixup_f32 v61, v64, v61, 1.0
	v_div_scale_f32 v64, s[0:1], v60, v60, 1.0
	v_rcp_f32_e32 v65, v64
	s_nop 0
	v_fma_f32 v76, -v64, v65, 1.0
	v_fmac_f32_e32 v65, v76, v65
	v_div_scale_f32 v76, vcc, 1.0, v60, 1.0
	v_mul_f32_e32 v77, v76, v65
	v_fma_f32 v80, -v64, v77, v76
	v_fmac_f32_e32 v77, v80, v65
	v_fma_f32 v64, -v64, v77, v76
	v_div_fmas_f32 v64, v64, v65, v77
	v_div_fixup_f32 v60, v64, v60, 1.0
	v_pk_mul_f32 v[60:61], v[60:61], s[4:5] op_sel_hi:[1,0]
	s_nop 0
	v_cvt_pk_f16_f32 v60, v60, v61
	v_div_scale_f32 v61, s[0:1], v63, v63, 1.0
	v_rcp_f32_e32 v64, v61
	s_nop 0
	v_fma_f32 v65, -v61, v64, 1.0
	v_fmac_f32_e32 v64, v65, v64
	v_div_scale_f32 v65, vcc, 1.0, v63, 1.0
	v_mul_f32_e32 v76, v65, v64
	v_fma_f32 v77, -v61, v76, v65
	v_fmac_f32_e32 v76, v77, v64
	v_fma_f32 v61, -v61, v76, v65
	v_div_fmas_f32 v61, v61, v64, v76
	v_div_fixup_f32 v63, v61, v63, 1.0
	v_div_scale_f32 v61, s[0:1], v62, v62, 1.0
	v_rcp_f32_e32 v64, v61
	s_nop 0
	v_fma_f32 v65, -v61, v64, 1.0
	v_fmac_f32_e32 v64, v65, v64
	v_div_scale_f32 v65, vcc, 1.0, v62, 1.0
	v_mul_f32_e32 v76, v65, v64
	v_fma_f32 v77, -v61, v76, v65
	v_fmac_f32_e32 v76, v77, v64
	v_fma_f32 v61, -v61, v76, v65
	v_div_fmas_f32 v61, v61, v64, v76
	v_div_fixup_f32 v62, v61, v62, 1.0
	v_pk_mul_f32 v[62:63], v[62:63], s[4:5] op_sel_hi:[1,0]
	s_nop 0
	v_cvt_pk_f16_f32 v61, v62, v63
	global_store_dwordx4 v[134:135], v[58:61], off offset:256
	v_pk_add_f32 v[50:51], v[50:51], v[66:67]
	v_pk_add_f32 v[54:55], v[54:55], v[70:71]
	v_mul_f32_e32 v50, 0xbfb8aa3b, v50
	v_exp_f32_e32 v60, v50
	v_mul_f32_e32 v50, 0xbfb8aa3b, v55
	v_pk_add_f32 v[56:57], v[56:57], v[72:73]
	v_mul_f32_e32 v54, 0xbfb8aa3b, v54
	v_exp_f32_e32 v59, v50
	v_mul_f32_e32 v50, 0xbfb8aa3b, v51
	v_pk_add_f32 v[52:53], v[52:53], v[68:69]
	v_exp_f32_e32 v58, v54
	v_exp_f32_e32 v61, v50
	v_mul_f32_e32 v50, 0xbfb8aa3b, v56
	v_exp_f32_e32 v56, v50
	v_mul_f32_e32 v50, 0xbfb8aa3b, v52
	v_exp_f32_e32 v54, v50
	v_mul_f32_e32 v50, 0xbfb8aa3b, v57
	v_exp_f32_e32 v57, v50
	v_mul_f32_e32 v50, 0xbfb8aa3b, v53
	v_exp_f32_e32 v55, v50
	v_pk_add_f32 v[50:51], v[58:59], 1.0 op_sel_hi:[1,0]
	v_pk_add_f32 v[54:55], v[54:55], 1.0 op_sel_hi:[1,0]
	v_div_scale_f32 v52, s[0:1], v51, v51, 1.0
	v_rcp_f32_e32 v53, v52
	s_nop 0
	v_fma_f32 v58, -v52, v53, 1.0
	v_fmac_f32_e32 v53, v58, v53
	v_div_scale_f32 v58, vcc, 1.0, v51, 1.0
	v_mul_f32_e32 v59, v58, v53
	v_fma_f32 v62, -v52, v59, v58
	v_fmac_f32_e32 v59, v62, v53
	v_fma_f32 v52, -v52, v59, v58
	v_div_fmas_f32 v52, v52, v53, v59
	v_div_fixup_f32 v51, v52, v51, 1.0
	v_div_scale_f32 v52, s[0:1], v50, v50, 1.0
	v_rcp_f32_e32 v53, v52
	s_nop 0
	v_fma_f32 v58, -v52, v53, 1.0
	v_fmac_f32_e32 v53, v58, v53
	v_div_scale_f32 v58, vcc, 1.0, v50, 1.0
	v_mul_f32_e32 v59, v58, v53
	v_fma_f32 v62, -v52, v59, v58
	v_fmac_f32_e32 v59, v62, v53
	v_fma_f32 v52, -v52, v59, v58
	v_div_fmas_f32 v52, v52, v53, v59
	v_div_fixup_f32 v50, v52, v50, 1.0
	v_pk_mul_f32 v[50:51], v[50:51], s[4:5] op_sel_hi:[1,0]
	v_pk_add_f32 v[52:53], v[56:57], 1.0 op_sel_hi:[1,0]
	v_cvt_pk_f16_f32 v50, v50, v51
	v_div_scale_f32 v51, s[0:1], v53, v53, 1.0
	v_rcp_f32_e32 v56, v51
	s_nop 0
	v_fma_f32 v57, -v51, v56, 1.0
	v_fmac_f32_e32 v56, v57, v56
	v_div_scale_f32 v57, vcc, 1.0, v53, 1.0
	v_mul_f32_e32 v58, v57, v56
	v_fma_f32 v59, -v51, v58, v57
	v_fmac_f32_e32 v58, v59, v56
	v_fma_f32 v51, -v51, v58, v57
	v_div_fmas_f32 v51, v51, v56, v58
	v_div_fixup_f32 v53, v51, v53, 1.0
	v_div_scale_f32 v51, s[0:1], v52, v52, 1.0
	v_rcp_f32_e32 v56, v51
	s_nop 0
	v_fma_f32 v57, -v51, v56, 1.0
	v_fmac_f32_e32 v56, v57, v56
	v_div_scale_f32 v57, vcc, 1.0, v52, 1.0
	v_mul_f32_e32 v58, v57, v56
	v_fma_f32 v59, -v51, v58, v57
	v_fmac_f32_e32 v58, v59, v56
	v_fma_f32 v51, -v51, v58, v57
	v_div_fmas_f32 v51, v51, v56, v58
	v_div_fixup_f32 v52, v51, v52, 1.0
	v_pk_mul_f32 v[52:53], v[52:53], s[4:5] op_sel_hi:[1,0]
	s_nop 0
	v_cvt_pk_f16_f32 v51, v52, v53
	v_pk_add_f32 v[52:53], v[60:61], 1.0 op_sel_hi:[1,0]
	s_nop 0
	v_div_scale_f32 v56, s[0:1], v53, v53, 1.0
	v_rcp_f32_e32 v57, v56
	s_nop 0
	v_fma_f32 v58, -v56, v57, 1.0
	v_fmac_f32_e32 v57, v58, v57
	v_div_scale_f32 v58, vcc, 1.0, v53, 1.0
	v_mul_f32_e32 v59, v58, v57
	v_fma_f32 v60, -v56, v59, v58
	v_fmac_f32_e32 v59, v60, v57
	v_fma_f32 v56, -v56, v59, v58
	v_div_fmas_f32 v56, v56, v57, v59
	v_div_fixup_f32 v53, v56, v53, 1.0
	v_div_scale_f32 v56, s[0:1], v52, v52, 1.0
	v_rcp_f32_e32 v57, v56
	s_nop 0
	v_fma_f32 v58, -v56, v57, 1.0
; __device__ __forceinline__ float sigmoidf_(float x) { return 1.0f / (1.0f + __expf(-x)); }
;     template <int GI>
;     __device__ __forceinline__ void body(const f32x4 (&acc)[2][2][4][2], int row0, int colt) const {
;     ...
;             for (int ai = 0; ai < 2; ++ai)
; #pragma unroll
;                 for (int m = 0; m < 4; ++m) {
;                     const size_t row = (size_t)(row0 + ai * 128 + m * 16);
;                     f32x4 x0 = acc[ai][bj][m][0] + b0, x1 = acc[ai][bj][m][1] + b1;
;                     if (GI == 0) {
; #pragma unroll
;                         for (int j = 0; j < 4; ++j) {
;                             x0[j] = 0.6065306597126334f * sigmoidf_(x0[j]); x1[j] = 0.6065306597126334f * sigmoidf_(x1[j]); }
;                         *(u32x4*)(DEC + row * DM + c) = pack8(x0, x1);
	v_fmac_f32_e32 v57, v58, v57
	v_div_scale_f32 v58, vcc, 1.0, v52, 1.0
	v_mul_f32_e32 v59, v58, v57
	v_fma_f32 v60, -v56, v59, v58
	v_fmac_f32_e32 v59, v60, v57
	v_fma_f32 v56, -v56, v59, v58
	v_div_fmas_f32 v56, v56, v57, v59
	v_div_fixup_f32 v52, v56, v52, 1.0
	v_pk_mul_f32 v[52:53], v[52:53], s[4:5] op_sel_hi:[1,0]
	s_nop 0
	v_cvt_pk_f16_f32 v52, v52, v53
	v_div_scale_f32 v53, s[0:1], v55, v55, 1.0
	v_rcp_f32_e32 v56, v53
	s_nop 0
	v_fma_f32 v57, -v53, v56, 1.0
	v_fmac_f32_e32 v56, v57, v56
	v_div_scale_f32 v57, vcc, 1.0, v55, 1.0
	v_mul_f32_e32 v58, v57, v56
	v_fma_f32 v59, -v53, v58, v57
	v_fmac_f32_e32 v58, v59, v56
	v_fma_f32 v53, -v53, v58, v57
	v_div_fmas_f32 v53, v53, v56, v58
	v_div_fixup_f32 v55, v53, v55, 1.0
	v_div_scale_f32 v53, s[0:1], v54, v54, 1.0
	v_rcp_f32_e32 v56, v53
	s_nop 0
	v_fma_f32 v57, -v53, v56, 1.0
	v_fmac_f32_e32 v56, v57, v56
	v_div_scale_f32 v57, vcc, 1.0, v54, 1.0
	v_mul_f32_e32 v58, v57, v56
	v_fma_f32 v59, -v53, v58, v57
	v_fmac_f32_e32 v58, v59, v56
	v_fma_f32 v53, -v53, v58, v57
	v_div_fmas_f32 v53, v53, v56, v58
	v_div_fixup_f32 v54, v53, v54, 1.0
	v_pk_mul_f32 v[54:55], v[54:55], s[4:5] op_sel_hi:[1,0]
	s_nop 0
	v_cvt_pk_f16_f32 v53, v54, v55
	global_store_dwordx4 v[126:127], v[50:53], off offset:256
	v_pk_add_f32 v[42:43], v[42:43], v[66:67]
	v_pk_add_f32 v[46:47], v[46:47], v[70:71]
	v_mul_f32_e32 v42, 0xbfb8aa3b, v42
	v_exp_f32_e32 v52, v42
	v_mul_f32_e32 v42, 0xbfb8aa3b, v47
	v_pk_add_f32 v[48:49], v[48:49], v[72:73]
	v_mul_f32_e32 v46, 0xbfb8aa3b, v46
	v_exp_f32_e32 v51, v42
	v_mul_f32_e32 v42, 0xbfb8aa3b, v43
	v_pk_add_f32 v[44:45], v[44:45], v[68:69]
	v_exp_f32_e32 v50, v46
	v_exp_f32_e32 v53, v42
	v_mul_f32_e32 v42, 0xbfb8aa3b, v48
	v_exp_f32_e32 v48, v42
	v_mul_f32_e32 v42, 0xbfb8aa3b, v44
	v_exp_f32_e32 v46, v42
	v_mul_f32_e32 v42, 0xbfb8aa3b, v49
	v_exp_f32_e32 v49, v42
	v_mul_f32_e32 v42, 0xbfb8aa3b, v45
	v_exp_f32_e32 v47, v42
	v_pk_add_f32 v[42:43], v[50:51], 1.0 op_sel_hi:[1,0]
	v_pk_add_f32 v[46:47], v[46:47], 1.0 op_sel_hi:[1,0]
	v_div_scale_f32 v44, s[0:1], v43, v43, 1.0
	v_rcp_f32_e32 v45, v44
	s_nop 0
	v_fma_f32 v50, -v44, v45, 1.0
	v_fmac_f32_e32 v45, v50, v45
	v_div_scale_f32 v50, vcc, 1.0, v43, 1.0
	v_mul_f32_e32 v51, v50, v45
	v_fma_f32 v54, -v44, v51, v50
	v_fmac_f32_e32 v51, v54, v45
	v_fma_f32 v44, -v44, v51, v50
	v_div_fmas_f32 v44, v44, v45, v51
	v_div_fixup_f32 v43, v44, v43, 1.0
	v_div_scale_f32 v44, s[0:1], v42, v42, 1.0
	v_rcp_f32_e32 v45, v44
	s_nop 0
	v_fma_f32 v50, -v44, v45, 1.0
	v_fmac_f32_e32 v45, v50, v45
	v_div_scale_f32 v50, vcc, 1.0, v42, 1.0
	v_mul_f32_e32 v51, v50, v45
	v_fma_f32 v54, -v44, v51, v50
	v_fmac_f32_e32 v51, v54, v45
	v_fma_f32 v44, -v44, v51, v50
	v_div_fmas_f32 v44, v44, v45, v51
	v_div_fixup_f32 v42, v44, v42, 1.0
	v_pk_mul_f32 v[42:43], v[42:43], s[4:5] op_sel_hi:[1,0]
	v_pk_add_f32 v[44:45], v[48:49], 1.0 op_sel_hi:[1,0]
	v_cvt_pk_f16_f32 v42, v42, v43
	v_div_scale_f32 v43, s[0:1], v45, v45, 1.0
	v_rcp_f32_e32 v48, v43
	s_nop 0
	v_fma_f32 v49, -v43, v48, 1.0
	v_fmac_f32_e32 v48, v49, v48
	v_div_scale_f32 v49, vcc, 1.0, v45, 1.0
	v_mul_f32_e32 v50, v49, v48
	v_fma_f32 v51, -v43, v50, v49
	v_fmac_f32_e32 v50, v51, v48
	v_fma_f32 v43, -v43, v50, v49
	v_div_fmas_f32 v43, v43, v48, v50
	v_div_fixup_f32 v45, v43, v45, 1.0
	v_div_scale_f32 v43, s[0:1], v44, v44, 1.0
	v_rcp_f32_e32 v48, v43
	s_nop 0
	v_fma_f32 v49, -v43, v48, 1.0
	v_fmac_f32_e32 v48, v49, v48
	v_div_scale_f32 v49, vcc, 1.0, v44, 1.0
	v_mul_f32_e32 v50, v49, v48
	v_fma_f32 v51, -v43, v50, v49
	v_fmac_f32_e32 v50, v51, v48
	v_fma_f32 v43, -v43, v50, v49
	v_div_fmas_f32 v43, v43, v48, v50
	v_div_fixup_f32 v44, v43, v44, 1.0
	v_pk_mul_f32 v[44:45], v[44:45], s[4:5] op_sel_hi:[1,0]
	s_nop 0
	v_cvt_pk_f16_f32 v43, v44, v45
	v_pk_add_f32 v[44:45], v[52:53], 1.0 op_sel_hi:[1,0]
	s_nop 0
	v_div_scale_f32 v48, s[0:1], v45, v45, 1.0
	v_rcp_f32_e32 v49, v48
	s_nop 0
	v_fma_f32 v50, -v48, v49, 1.0
	v_fmac_f32_e32 v49, v50, v49
	v_div_scale_f32 v50, vcc, 1.0, v45, 1.0
	v_mul_f32_e32 v51, v50, v49
	v_fma_f32 v52, -v48, v51, v50
	v_fmac_f32_e32 v51, v52, v49
	v_fma_f32 v48, -v48, v51, v50
	v_div_fmas_f32 v48, v48, v49, v51
	v_div_fixup_f32 v45, v48, v45, 1.0
	v_div_scale_f32 v48, s[0:1], v44, v44, 1.0
	v_rcp_f32_e32 v49, v48
	s_nop 0
	v_fma_f32 v50, -v48, v49, 1.0
	v_fmac_f32_e32 v49, v50, v49
	v_div_scale_f32 v50, vcc, 1.0, v44, 1.0
	v_mul_f32_e32 v51, v50, v49
	v_fma_f32 v52, -v48, v51, v50
	v_fmac_f32_e32 v51, v52, v49
	v_fma_f32 v48, -v48, v51, v50
	v_div_fmas_f32 v48, v48, v49, v51
	v_div_fixup_f32 v44, v48, v44, 1.0
	v_pk_mul_f32 v[44:45], v[44:45], s[4:5] op_sel_hi:[1,0]
	s_nop 0
	v_cvt_pk_f16_f32 v44, v44, v45
	v_div_scale_f32 v45, s[0:1], v47, v47, 1.0
	v_rcp_f32_e32 v48, v45
	s_nop 0
	v_fma_f32 v49, -v45, v48, 1.0
	v_fmac_f32_e32 v48, v49, v48
	v_div_scale_f32 v49, vcc, 1.0, v47, 1.0
	v_mul_f32_e32 v50, v49, v48
	v_fma_f32 v51, -v45, v50, v49
	v_fmac_f32_e32 v50, v51, v48
	v_fma_f32 v45, -v45, v50, v49
	v_div_fmas_f32 v45, v45, v48, v50
	v_div_fixup_f32 v47, v45, v47, 1.0
	v_div_scale_f32 v45, s[0:1], v46, v46, 1.0
	v_rcp_f32_e32 v48, v45
	s_nop 0
	v_fma_f32 v49, -v45, v48, 1.0
	v_fmac_f32_e32 v48, v49, v48
	v_div_scale_f32 v49, vcc, 1.0, v46, 1.0
	v_mul_f32_e32 v50, v49, v48
	v_fma_f32 v51, -v45, v50, v49
	v_fmac_f32_e32 v50, v51, v48
	v_fma_f32 v45, -v45, v50, v49
	v_div_fmas_f32 v45, v45, v48, v50
	v_div_fixup_f32 v46, v45, v46, 1.0
	v_pk_mul_f32 v[46:47], v[46:47], s[4:5] op_sel_hi:[1,0]
	s_nop 0
	v_cvt_pk_f16_f32 v45, v46, v47
	global_store_dwordx4 v[118:119], v[42:45], off offset:256
	v_pk_add_f32 v[34:35], v[34:35], v[66:67]
	v_pk_add_f32 v[38:39], v[38:39], v[70:71]
; __device__ __forceinline__ float sigmoidf_(float x) { return 1.0f / (1.0f + __expf(-x)); }
;     template <int GI>
;     __device__ __forceinline__ void body(const f32x4 (&acc)[2][2][4][2], int row0, int colt) const {
;     ...
;             for (int ai = 0; ai < 2; ++ai)
; #pragma unroll
;                 for (int m = 0; m < 4; ++m) {
;                     const size_t row = (size_t)(row0 + ai * 128 + m * 16);
;                     f32x4 x0 = acc[ai][bj][m][0] + b0, x1 = acc[ai][bj][m][1] + b1;
;                     if (GI == 0) {
; #pragma unroll
;                         for (int j = 0; j < 4; ++j) {
;                             x0[j] = 0.6065306597126334f * sigmoidf_(x0[j]); x1[j] = 0.6065306597126334f * sigmoidf_(x1[j]); }
;                         *(u32x4*)(DEC + row * DM + c) = pack8(x0, x1);
	v_mul_f32_e32 v34, 0xbfb8aa3b, v34
	v_exp_f32_e32 v44, v34
	v_mul_f32_e32 v34, 0xbfb8aa3b, v39
	v_pk_add_f32 v[40:41], v[40:41], v[72:73]
	v_mul_f32_e32 v38, 0xbfb8aa3b, v38
	v_exp_f32_e32 v43, v34
	v_mul_f32_e32 v34, 0xbfb8aa3b, v35
	v_pk_add_f32 v[36:37], v[36:37], v[68:69]
	v_exp_f32_e32 v42, v38
	v_exp_f32_e32 v45, v34
	v_mul_f32_e32 v34, 0xbfb8aa3b, v40
	v_exp_f32_e32 v40, v34
	v_mul_f32_e32 v34, 0xbfb8aa3b, v36
	v_exp_f32_e32 v38, v34
	v_mul_f32_e32 v34, 0xbfb8aa3b, v41
	v_exp_f32_e32 v41, v34
	v_mul_f32_e32 v34, 0xbfb8aa3b, v37
	v_exp_f32_e32 v39, v34
	v_pk_add_f32 v[34:35], v[42:43], 1.0 op_sel_hi:[1,0]
	v_pk_add_f32 v[38:39], v[38:39], 1.0 op_sel_hi:[1,0]
	v_div_scale_f32 v36, s[0:1], v35, v35, 1.0
	v_rcp_f32_e32 v37, v36
	s_nop 0
	v_fma_f32 v42, -v36, v37, 1.0
	v_fmac_f32_e32 v37, v42, v37
	v_div_scale_f32 v42, vcc, 1.0, v35, 1.0
	v_mul_f32_e32 v43, v42, v37
	v_fma_f32 v46, -v36, v43, v42
	v_fmac_f32_e32 v43, v46, v37
	v_fma_f32 v36, -v36, v43, v42
	v_div_fmas_f32 v36, v36, v37, v43
	v_div_fixup_f32 v35, v36, v35, 1.0
	v_div_scale_f32 v36, s[0:1], v34, v34, 1.0
	v_rcp_f32_e32 v37, v36
	s_nop 0
	v_fma_f32 v42, -v36, v37, 1.0
	v_fmac_f32_e32 v37, v42, v37
	v_div_scale_f32 v42, vcc, 1.0, v34, 1.0
	v_mul_f32_e32 v43, v42, v37
	v_fma_f32 v46, -v36, v43, v42
	v_fmac_f32_e32 v43, v46, v37
	v_fma_f32 v36, -v36, v43, v42
	v_div_fmas_f32 v36, v36, v37, v43
	v_div_fixup_f32 v34, v36, v34, 1.0
	v_pk_mul_f32 v[34:35], v[34:35], s[4:5] op_sel_hi:[1,0]
	v_pk_add_f32 v[36:37], v[40:41], 1.0 op_sel_hi:[1,0]
	v_cvt_pk_f16_f32 v34, v34, v35
	v_div_scale_f32 v35, s[0:1], v37, v37, 1.0
	v_rcp_f32_e32 v40, v35
	s_nop 0
	v_fma_f32 v41, -v35, v40, 1.0
	v_fmac_f32_e32 v40, v41, v40
	v_div_scale_f32 v41, vcc, 1.0, v37, 1.0
	v_mul_f32_e32 v42, v41, v40
	v_fma_f32 v43, -v35, v42, v41
	v_fmac_f32_e32 v42, v43, v40
	v_fma_f32 v35, -v35, v42, v41
	v_div_fmas_f32 v35, v35, v40, v42
	v_div_fixup_f32 v37, v35, v37, 1.0
	v_div_scale_f32 v35, s[0:1], v36, v36, 1.0
	v_rcp_f32_e32 v40, v35
	s_nop 0
	v_fma_f32 v41, -v35, v40, 1.0
	v_fmac_f32_e32 v40, v41, v40
	v_div_scale_f32 v41, vcc, 1.0, v36, 1.0
	v_mul_f32_e32 v42, v41, v40
	v_fma_f32 v43, -v35, v42, v41
	v_fmac_f32_e32 v42, v43, v40
	v_fma_f32 v35, -v35, v42, v41
	v_div_fmas_f32 v35, v35, v40, v42
	v_div_fixup_f32 v36, v35, v36, 1.0
	v_pk_mul_f32 v[36:37], v[36:37], s[4:5] op_sel_hi:[1,0]
	s_nop 0
	v_cvt_pk_f16_f32 v35, v36, v37
	v_pk_add_f32 v[36:37], v[44:45], 1.0 op_sel_hi:[1,0]
	s_nop 0
	v_div_scale_f32 v40, s[0:1], v37, v37, 1.0
	v_rcp_f32_e32 v41, v40
	s_nop 0
	v_fma_f32 v42, -v40, v41, 1.0
	v_fmac_f32_e32 v41, v42, v41
	v_div_scale_f32 v42, vcc, 1.0, v37, 1.0
	v_mul_f32_e32 v43, v42, v41
	v_fma_f32 v44, -v40, v43, v42
	v_fmac_f32_e32 v43, v44, v41
	v_fma_f32 v40, -v40, v43, v42
	v_div_fmas_f32 v40, v40, v41, v43
	v_div_fixup_f32 v37, v40, v37, 1.0
	v_div_scale_f32 v40, s[0:1], v36, v36, 1.0
	v_rcp_f32_e32 v41, v40
	s_nop 0
	v_fma_f32 v42, -v40, v41, 1.0
	v_fmac_f32_e32 v41, v42, v41
	v_div_scale_f32 v42, vcc, 1.0, v36, 1.0
	v_mul_f32_e32 v43, v42, v41
	v_fma_f32 v44, -v40, v43, v42
	v_fmac_f32_e32 v43, v44, v41
	v_fma_f32 v40, -v40, v43, v42
	v_div_fmas_f32 v40, v40, v41, v43
	v_div_fixup_f32 v36, v40, v36, 1.0
	v_pk_mul_f32 v[36:37], v[36:37], s[4:5] op_sel_hi:[1,0]
	s_nop 0
	v_cvt_pk_f16_f32 v36, v36, v37
	v_div_scale_f32 v37, s[0:1], v39, v39, 1.0
	v_rcp_f32_e32 v40, v37
	s_nop 0
	v_fma_f32 v41, -v37, v40, 1.0
	v_fmac_f32_e32 v40, v41, v40
	v_div_scale_f32 v41, vcc, 1.0, v39, 1.0
	v_mul_f32_e32 v42, v41, v40
	v_fma_f32 v43, -v37, v42, v41
	v_fmac_f32_e32 v42, v43, v40
	v_fma_f32 v37, -v37, v42, v41
	v_div_fmas_f32 v37, v37, v40, v42
	v_div_fixup_f32 v39, v37, v39, 1.0
	v_div_scale_f32 v37, s[0:1], v38, v38, 1.0
	v_rcp_f32_e32 v40, v37
	s_nop 0
	v_fma_f32 v41, -v37, v40, 1.0
	v_fmac_f32_e32 v40, v41, v40
	v_div_scale_f32 v41, vcc, 1.0, v38, 1.0
	v_mul_f32_e32 v42, v41, v40
	v_fma_f32 v43, -v37, v42, v41
	v_fmac_f32_e32 v42, v43, v40
	v_fma_f32 v37, -v37, v42, v41
	v_div_fmas_f32 v37, v37, v40, v42
	v_div_fixup_f32 v38, v37, v38, 1.0
	v_pk_mul_f32 v[38:39], v[38:39], s[4:5] op_sel_hi:[1,0]
	s_nop 0
	v_cvt_pk_f16_f32 v37, v38, v39
	global_store_dwordx4 v[110:111], v[34:37], off offset:256
	v_pk_add_f32 v[26:27], v[26:27], v[66:67]
	v_pk_add_f32 v[30:31], v[30:31], v[70:71]
	v_mul_f32_e32 v26, 0xbfb8aa3b, v26
	v_exp_f32_e32 v36, v26
	v_mul_f32_e32 v26, 0xbfb8aa3b, v31
	v_pk_add_f32 v[32:33], v[32:33], v[72:73]
	v_mul_f32_e32 v30, 0xbfb8aa3b, v30
	v_exp_f32_e32 v35, v26
	v_mul_f32_e32 v26, 0xbfb8aa3b, v27
	v_pk_add_f32 v[28:29], v[28:29], v[68:69]
	v_exp_f32_e32 v34, v30
	v_exp_f32_e32 v37, v26
	v_mul_f32_e32 v26, 0xbfb8aa3b, v32
	v_exp_f32_e32 v32, v26
	v_mul_f32_e32 v26, 0xbfb8aa3b, v28
	v_exp_f32_e32 v30, v26
	v_mul_f32_e32 v26, 0xbfb8aa3b, v33
	v_exp_f32_e32 v33, v26
	v_mul_f32_e32 v26, 0xbfb8aa3b, v29
	v_exp_f32_e32 v31, v26
	v_pk_add_f32 v[26:27], v[34:35], 1.0 op_sel_hi:[1,0]
	v_pk_add_f32 v[30:31], v[30:31], 1.0 op_sel_hi:[1,0]
	v_div_scale_f32 v28, s[0:1], v27, v27, 1.0
	v_rcp_f32_e32 v29, v28
	s_nop 0
	v_fma_f32 v34, -v28, v29, 1.0
	v_fmac_f32_e32 v29, v34, v29
	v_div_scale_f32 v34, vcc, 1.0, v27, 1.0
	v_mul_f32_e32 v35, v34, v29
	v_fma_f32 v38, -v28, v35, v34
	v_fmac_f32_e32 v35, v38, v29
	v_fma_f32 v28, -v28, v35, v34
	v_div_fmas_f32 v28, v28, v29, v35
	v_div_fixup_f32 v27, v28, v27, 1.0
	v_div_scale_f32 v28, s[0:1], v26, v26, 1.0
	v_rcp_f32_e32 v29, v28
	s_nop 0
	v_fma_f32 v34, -v28, v29, 1.0
	v_fmac_f32_e32 v29, v34, v29
	v_div_scale_f32 v34, vcc, 1.0, v26, 1.0
	v_mul_f32_e32 v35, v34, v29
	v_fma_f32 v38, -v28, v35, v34
	v_fmac_f32_e32 v35, v38, v29
	v_fma_f32 v28, -v28, v35, v34
; __device__ __forceinline__ float sigmoidf_(float x) { return 1.0f / (1.0f + __expf(-x)); }
;     template <int GI>
;     __device__ __forceinline__ void body(const f32x4 (&acc)[2][2][4][2], int row0, int colt) const {
;     ...
;             for (int ai = 0; ai < 2; ++ai)
; #pragma unroll
;                 for (int m = 0; m < 4; ++m) {
;                     const size_t row = (size_t)(row0 + ai * 128 + m * 16);
;                     f32x4 x0 = acc[ai][bj][m][0] + b0, x1 = acc[ai][bj][m][1] + b1;
;                     if (GI == 0) {
; #pragma unroll
;                         for (int j = 0; j < 4; ++j) {
;                             x0[j] = 0.6065306597126334f * sigmoidf_(x0[j]); x1[j] = 0.6065306597126334f * sigmoidf_(x1[j]); }
;                         *(u32x4*)(DEC + row * DM + c) = pack8(x0, x1);
	v_div_fmas_f32 v28, v28, v29, v35
	v_div_fixup_f32 v26, v28, v26, 1.0
	v_pk_mul_f32 v[26:27], v[26:27], s[4:5] op_sel_hi:[1,0]
	v_pk_add_f32 v[28:29], v[32:33], 1.0 op_sel_hi:[1,0]
	v_cvt_pk_f16_f32 v26, v26, v27
	v_div_scale_f32 v27, s[0:1], v29, v29, 1.0
	v_rcp_f32_e32 v32, v27
	s_nop 0
	v_fma_f32 v33, -v27, v32, 1.0
	v_fmac_f32_e32 v32, v33, v32
	v_div_scale_f32 v33, vcc, 1.0, v29, 1.0
	v_mul_f32_e32 v34, v33, v32
	v_fma_f32 v35, -v27, v34, v33
	v_fmac_f32_e32 v34, v35, v32
	v_fma_f32 v27, -v27, v34, v33
	v_div_fmas_f32 v27, v27, v32, v34
	v_div_fixup_f32 v29, v27, v29, 1.0
	v_div_scale_f32 v27, s[0:1], v28, v28, 1.0
	v_rcp_f32_e32 v32, v27
	s_nop 0
	v_fma_f32 v33, -v27, v32, 1.0
	v_fmac_f32_e32 v32, v33, v32
	v_div_scale_f32 v33, vcc, 1.0, v28, 1.0
	v_mul_f32_e32 v34, v33, v32
	v_fma_f32 v35, -v27, v34, v33
	v_fmac_f32_e32 v34, v35, v32
	v_fma_f32 v27, -v27, v34, v33
	v_div_fmas_f32 v27, v27, v32, v34
	v_div_fixup_f32 v28, v27, v28, 1.0
	v_pk_mul_f32 v[28:29], v[28:29], s[4:5] op_sel_hi:[1,0]
	s_nop 0
	v_cvt_pk_f16_f32 v27, v28, v29
	v_pk_add_f32 v[28:29], v[36:37], 1.0 op_sel_hi:[1,0]
	s_nop 0
	v_div_scale_f32 v32, s[0:1], v29, v29, 1.0
	v_rcp_f32_e32 v33, v32
	s_nop 0
	v_fma_f32 v34, -v32, v33, 1.0
	v_fmac_f32_e32 v33, v34, v33
	v_div_scale_f32 v34, vcc, 1.0, v29, 1.0
	v_mul_f32_e32 v35, v34, v33
	v_fma_f32 v36, -v32, v35, v34
	v_fmac_f32_e32 v35, v36, v33
	v_fma_f32 v32, -v32, v35, v34
	v_div_fmas_f32 v32, v32, v33, v35
	v_div_fixup_f32 v29, v32, v29, 1.0
	v_div_scale_f32 v32, s[0:1], v28, v28, 1.0
	v_rcp_f32_e32 v33, v32
	s_nop 0
	v_fma_f32 v34, -v32, v33, 1.0
	v_fmac_f32_e32 v33, v34, v33
	v_div_scale_f32 v34, vcc, 1.0, v28, 1.0
	v_mul_f32_e32 v35, v34, v33
	v_fma_f32 v36, -v32, v35, v34
	v_fmac_f32_e32 v35, v36, v33
	v_fma_f32 v32, -v32, v35, v34
	v_div_fmas_f32 v32, v32, v33, v35
	v_div_fixup_f32 v28, v32, v28, 1.0
	v_pk_mul_f32 v[28:29], v[28:29], s[4:5] op_sel_hi:[1,0]
	s_nop 0
	v_cvt_pk_f16_f32 v28, v28, v29
	v_div_scale_f32 v29, s[0:1], v31, v31, 1.0
	v_rcp_f32_e32 v32, v29
	s_nop 0
	v_fma_f32 v33, -v29, v32, 1.0
	v_fmac_f32_e32 v32, v33, v32
	v_div_scale_f32 v33, vcc, 1.0, v31, 1.0
	v_mul_f32_e32 v34, v33, v32
	v_fma_f32 v35, -v29, v34, v33
	v_fmac_f32_e32 v34, v35, v32
	v_fma_f32 v29, -v29, v34, v33
	v_div_fmas_f32 v29, v29, v32, v34
	v_div_fixup_f32 v31, v29, v31, 1.0
	v_div_scale_f32 v29, s[0:1], v30, v30, 1.0
	v_rcp_f32_e32 v32, v29
	s_nop 0
	v_fma_f32 v33, -v29, v32, 1.0
	v_fmac_f32_e32 v32, v33, v32
	v_div_scale_f32 v33, vcc, 1.0, v30, 1.0
	v_mul_f32_e32 v34, v33, v32
	v_fma_f32 v35, -v29, v34, v33
	v_fmac_f32_e32 v34, v35, v32
	v_fma_f32 v29, -v29, v34, v33
	v_div_fmas_f32 v29, v29, v32, v34
	v_div_fixup_f32 v30, v29, v30, 1.0
	v_pk_mul_f32 v[30:31], v[30:31], s[4:5] op_sel_hi:[1,0]
	s_nop 0
	v_cvt_pk_f16_f32 v29, v30, v31
	global_store_dwordx4 v[102:103], v[26:29], off offset:256
	v_pk_add_f32 v[18:19], v[18:19], v[66:67]
	v_pk_add_f32 v[22:23], v[22:23], v[70:71]
	v_mul_f32_e32 v18, 0xbfb8aa3b, v18
	v_exp_f32_e32 v28, v18
	v_mul_f32_e32 v18, 0xbfb8aa3b, v23
	v_pk_add_f32 v[24:25], v[24:25], v[72:73]
	v_mul_f32_e32 v22, 0xbfb8aa3b, v22
	v_exp_f32_e32 v27, v18
	v_mul_f32_e32 v18, 0xbfb8aa3b, v19
	v_pk_add_f32 v[20:21], v[20:21], v[68:69]
	v_exp_f32_e32 v26, v22
	v_exp_f32_e32 v29, v18
	v_mul_f32_e32 v18, 0xbfb8aa3b, v24
	v_exp_f32_e32 v24, v18
	v_mul_f32_e32 v18, 0xbfb8aa3b, v20
	v_exp_f32_e32 v22, v18
	v_mul_f32_e32 v18, 0xbfb8aa3b, v25
	v_exp_f32_e32 v25, v18
	v_mul_f32_e32 v18, 0xbfb8aa3b, v21
	v_exp_f32_e32 v23, v18
	v_pk_add_f32 v[18:19], v[26:27], 1.0 op_sel_hi:[1,0]
	v_pk_add_f32 v[22:23], v[22:23], 1.0 op_sel_hi:[1,0]
	v_div_scale_f32 v20, s[0:1], v19, v19, 1.0
	v_rcp_f32_e32 v21, v20
	s_nop 0
	v_fma_f32 v26, -v20, v21, 1.0
	v_fmac_f32_e32 v21, v26, v21
	v_div_scale_f32 v26, vcc, 1.0, v19, 1.0
	v_mul_f32_e32 v27, v26, v21
	v_fma_f32 v30, -v20, v27, v26
	v_fmac_f32_e32 v27, v30, v21
	v_fma_f32 v20, -v20, v27, v26
	v_div_fmas_f32 v20, v20, v21, v27
	v_div_fixup_f32 v19, v20, v19, 1.0
	v_div_scale_f32 v20, s[0:1], v18, v18, 1.0
	v_rcp_f32_e32 v21, v20
	s_nop 0
	v_fma_f32 v26, -v20, v21, 1.0
	v_fmac_f32_e32 v21, v26, v21
	v_div_scale_f32 v26, vcc, 1.0, v18, 1.0
	v_mul_f32_e32 v27, v26, v21
	v_fma_f32 v30, -v20, v27, v26
	v_fmac_f32_e32 v27, v30, v21
	v_fma_f32 v20, -v20, v27, v26
	v_div_fmas_f32 v20, v20, v21, v27
	v_div_fixup_f32 v18, v20, v18, 1.0
	v_pk_mul_f32 v[18:19], v[18:19], s[4:5] op_sel_hi:[1,0]
	v_pk_add_f32 v[20:21], v[24:25], 1.0 op_sel_hi:[1,0]
	v_cvt_pk_f16_f32 v18, v18, v19
	v_div_scale_f32 v19, s[0:1], v21, v21, 1.0
	v_rcp_f32_e32 v24, v19
	s_nop 0
	v_fma_f32 v25, -v19, v24, 1.0
	v_fmac_f32_e32 v24, v25, v24
	v_div_scale_f32 v25, vcc, 1.0, v21, 1.0
	v_mul_f32_e32 v26, v25, v24
	v_fma_f32 v27, -v19, v26, v25
	v_fmac_f32_e32 v26, v27, v24
	v_fma_f32 v19, -v19, v26, v25
	v_div_fmas_f32 v19, v19, v24, v26
	v_div_fixup_f32 v21, v19, v21, 1.0
	v_div_scale_f32 v19, s[0:1], v20, v20, 1.0
	v_rcp_f32_e32 v24, v19
	s_nop 0
	v_fma_f32 v25, -v19, v24, 1.0
	v_fmac_f32_e32 v24, v25, v24
	v_div_scale_f32 v25, vcc, 1.0, v20, 1.0
	v_mul_f32_e32 v26, v25, v24
	v_fma_f32 v27, -v19, v26, v25
	v_fmac_f32_e32 v26, v27, v24
	v_fma_f32 v19, -v19, v26, v25
	v_div_fmas_f32 v19, v19, v24, v26
	v_div_fixup_f32 v20, v19, v20, 1.0
	v_pk_mul_f32 v[20:21], v[20:21], s[4:5] op_sel_hi:[1,0]
	s_nop 0
	v_cvt_pk_f16_f32 v19, v20, v21
	v_pk_add_f32 v[20:21], v[28:29], 1.0 op_sel_hi:[1,0]
	s_nop 0
	v_div_scale_f32 v24, s[0:1], v21, v21, 1.0
	v_rcp_f32_e32 v25, v24
	s_nop 0
	v_fma_f32 v26, -v24, v25, 1.0
	v_fmac_f32_e32 v25, v26, v25
	v_div_scale_f32 v26, vcc, 1.0, v21, 1.0
	v_mul_f32_e32 v27, v26, v25
	v_fma_f32 v28, -v24, v27, v26
; __device__ __forceinline__ float sigmoidf_(float x) { return 1.0f / (1.0f + __expf(-x)); }
;     template <int GI>
;     __device__ __forceinline__ void body(const f32x4 (&acc)[2][2][4][2], int row0, int colt) const {
;     ...
;             for (int ai = 0; ai < 2; ++ai)
; #pragma unroll
;                 for (int m = 0; m < 4; ++m) {
;                     const size_t row = (size_t)(row0 + ai * 128 + m * 16);
;                     f32x4 x0 = acc[ai][bj][m][0] + b0, x1 = acc[ai][bj][m][1] + b1;
;                     if (GI == 0) {
; #pragma unroll
;                         for (int j = 0; j < 4; ++j) {
;                             x0[j] = 0.6065306597126334f * sigmoidf_(x0[j]); x1[j] = 0.6065306597126334f * sigmoidf_(x1[j]); }
;                         *(u32x4*)(DEC + row * DM + c) = pack8(x0, x1);
	v_fmac_f32_e32 v27, v28, v25
	v_fma_f32 v24, -v24, v27, v26
	v_div_fmas_f32 v24, v24, v25, v27
	v_div_fixup_f32 v21, v24, v21, 1.0
	v_div_scale_f32 v24, s[0:1], v20, v20, 1.0
	v_rcp_f32_e32 v25, v24
	s_nop 0
	v_fma_f32 v26, -v24, v25, 1.0
	v_fmac_f32_e32 v25, v26, v25
	v_div_scale_f32 v26, vcc, 1.0, v20, 1.0
	v_mul_f32_e32 v27, v26, v25
	v_fma_f32 v28, -v24, v27, v26
	v_fmac_f32_e32 v27, v28, v25
	v_fma_f32 v24, -v24, v27, v26
	v_div_fmas_f32 v24, v24, v25, v27
	v_div_fixup_f32 v20, v24, v20, 1.0
	v_pk_mul_f32 v[20:21], v[20:21], s[4:5] op_sel_hi:[1,0]
	s_nop 0
	v_cvt_pk_f16_f32 v20, v20, v21
	v_div_scale_f32 v21, s[0:1], v23, v23, 1.0
	v_rcp_f32_e32 v24, v21
	s_nop 0
	v_fma_f32 v25, -v21, v24, 1.0
	v_fmac_f32_e32 v24, v25, v24
	v_div_scale_f32 v25, vcc, 1.0, v23, 1.0
	v_mul_f32_e32 v26, v25, v24
	v_fma_f32 v27, -v21, v26, v25
	v_fmac_f32_e32 v26, v27, v24
	v_fma_f32 v21, -v21, v26, v25
	v_div_fmas_f32 v21, v21, v24, v26
	v_div_fixup_f32 v23, v21, v23, 1.0
	v_div_scale_f32 v21, s[0:1], v22, v22, 1.0
	v_rcp_f32_e32 v24, v21
	s_nop 0
	v_fma_f32 v25, -v21, v24, 1.0
	v_fmac_f32_e32 v24, v25, v24
	v_div_scale_f32 v25, vcc, 1.0, v22, 1.0
	v_mul_f32_e32 v26, v25, v24
	v_fma_f32 v27, -v21, v26, v25
	v_fmac_f32_e32 v26, v27, v24
	v_fma_f32 v21, -v21, v26, v25
	v_div_fmas_f32 v21, v21, v24, v26
	v_div_fixup_f32 v22, v21, v22, 1.0
	v_pk_mul_f32 v[22:23], v[22:23], s[4:5] op_sel_hi:[1,0]
	s_nop 0
	v_cvt_pk_f16_f32 v21, v22, v23
	global_store_dwordx4 v[86:87], v[18:21], off offset:256
	v_pk_add_f32 v[10:11], v[10:11], v[66:67]
	v_pk_add_f32 v[14:15], v[14:15], v[70:71]
	v_mul_f32_e32 v10, 0xbfb8aa3b, v10
	v_exp_f32_e32 v20, v10
	v_mul_f32_e32 v10, 0xbfb8aa3b, v15
	v_pk_add_f32 v[16:17], v[16:17], v[72:73]
	v_mul_f32_e32 v14, 0xbfb8aa3b, v14
	v_exp_f32_e32 v19, v10
	v_mul_f32_e32 v10, 0xbfb8aa3b, v11
	v_pk_add_f32 v[12:13], v[12:13], v[68:69]
	v_exp_f32_e32 v18, v14
	v_exp_f32_e32 v21, v10
	v_mul_f32_e32 v10, 0xbfb8aa3b, v16
	v_exp_f32_e32 v16, v10
	v_mul_f32_e32 v10, 0xbfb8aa3b, v12
	v_exp_f32_e32 v14, v10
	v_mul_f32_e32 v10, 0xbfb8aa3b, v17
	v_exp_f32_e32 v17, v10
	v_mul_f32_e32 v10, 0xbfb8aa3b, v13
	v_exp_f32_e32 v15, v10
	v_pk_add_f32 v[10:11], v[18:19], 1.0 op_sel_hi:[1,0]
	v_pk_add_f32 v[14:15], v[14:15], 1.0 op_sel_hi:[1,0]
	v_div_scale_f32 v12, s[0:1], v11, v11, 1.0
	v_rcp_f32_e32 v13, v12
	s_nop 0
	v_fma_f32 v18, -v12, v13, 1.0
	v_fmac_f32_e32 v13, v18, v13
	v_div_scale_f32 v18, vcc, 1.0, v11, 1.0
	v_mul_f32_e32 v19, v18, v13
	v_fma_f32 v22, -v12, v19, v18
	v_fmac_f32_e32 v19, v22, v13
	v_fma_f32 v12, -v12, v19, v18
	v_div_fmas_f32 v12, v12, v13, v19
	v_div_fixup_f32 v11, v12, v11, 1.0
	v_div_scale_f32 v12, s[0:1], v10, v10, 1.0
	v_rcp_f32_e32 v13, v12
	s_nop 0
	v_fma_f32 v18, -v12, v13, 1.0
	v_fmac_f32_e32 v13, v18, v13
	v_div_scale_f32 v18, vcc, 1.0, v10, 1.0
	v_mul_f32_e32 v19, v18, v13
	v_fma_f32 v22, -v12, v19, v18
	v_fmac_f32_e32 v19, v22, v13
	v_fma_f32 v12, -v12, v19, v18
	v_div_fmas_f32 v12, v12, v13, v19
	v_div_fixup_f32 v10, v12, v10, 1.0
	v_pk_mul_f32 v[10:11], v[10:11], s[4:5] op_sel_hi:[1,0]
	v_pk_add_f32 v[12:13], v[16:17], 1.0 op_sel_hi:[1,0]
	v_cvt_pk_f16_f32 v10, v10, v11
	v_div_scale_f32 v11, s[0:1], v13, v13, 1.0
	v_rcp_f32_e32 v16, v11
	s_nop 0
	v_fma_f32 v17, -v11, v16, 1.0
	v_fmac_f32_e32 v16, v17, v16
	v_div_scale_f32 v17, vcc, 1.0, v13, 1.0
	v_mul_f32_e32 v18, v17, v16
	v_fma_f32 v19, -v11, v18, v17
	v_fmac_f32_e32 v18, v19, v16
	v_fma_f32 v11, -v11, v18, v17
	v_div_fmas_f32 v11, v11, v16, v18
	v_div_fixup_f32 v13, v11, v13, 1.0
	v_div_scale_f32 v11, s[0:1], v12, v12, 1.0
	v_rcp_f32_e32 v16, v11
	s_nop 0
	v_fma_f32 v17, -v11, v16, 1.0
	v_fmac_f32_e32 v16, v17, v16
	v_div_scale_f32 v17, vcc, 1.0, v12, 1.0
	v_mul_f32_e32 v18, v17, v16
	v_fma_f32 v19, -v11, v18, v17
	v_fmac_f32_e32 v18, v19, v16
	v_fma_f32 v11, -v11, v18, v17
	v_div_fmas_f32 v11, v11, v16, v18
	v_div_fixup_f32 v12, v11, v12, 1.0
	v_pk_mul_f32 v[12:13], v[12:13], s[4:5] op_sel_hi:[1,0]
	s_nop 0
	v_cvt_pk_f16_f32 v11, v12, v13
	v_pk_add_f32 v[12:13], v[20:21], 1.0 op_sel_hi:[1,0]
	s_nop 0
	v_div_scale_f32 v16, s[0:1], v13, v13, 1.0
	v_rcp_f32_e32 v17, v16
	s_nop 0
	v_fma_f32 v18, -v16, v17, 1.0
	v_fmac_f32_e32 v17, v18, v17
	v_div_scale_f32 v18, vcc, 1.0, v13, 1.0
	v_mul_f32_e32 v19, v18, v17
	v_fma_f32 v20, -v16, v19, v18
	v_fmac_f32_e32 v19, v20, v17
	v_fma_f32 v16, -v16, v19, v18
	v_div_fmas_f32 v16, v16, v17, v19
	v_div_fixup_f32 v13, v16, v13, 1.0
	v_div_scale_f32 v16, s[0:1], v12, v12, 1.0
	v_rcp_f32_e32 v17, v16
	s_nop 0
	v_fma_f32 v18, -v16, v17, 1.0
	v_fmac_f32_e32 v17, v18, v17
	v_div_scale_f32 v18, vcc, 1.0, v12, 1.0
	v_mul_f32_e32 v19, v18, v17
	v_fma_f32 v20, -v16, v19, v18
	v_fmac_f32_e32 v19, v20, v17
	v_fma_f32 v16, -v16, v19, v18
	v_div_fmas_f32 v16, v16, v17, v19
	v_div_fixup_f32 v12, v16, v12, 1.0
	v_pk_mul_f32 v[12:13], v[12:13], s[4:5] op_sel_hi:[1,0]
	s_nop 0
	v_cvt_pk_f16_f32 v12, v12, v13
	v_div_scale_f32 v13, s[0:1], v15, v15, 1.0
	v_rcp_f32_e32 v16, v13
	s_nop 0
	v_fma_f32 v17, -v13, v16, 1.0
; __device__ __forceinline__ float sigmoidf_(float x) { return 1.0f / (1.0f + __expf(-x)); }
; template <class Epi, class AMap>
; __device__ __forceinline__ void gemm_phase(LAS unsigned char* lds, const AMap am, const int lda, const h16* Bt, const int ldb, const int M, const int N, const int K, const Epi& E) {
;     ...
;         if (!has_next) break;
; #pragma unroll
;         for (int a = 0; a < 2; ++a)
; #pragma unroll
;             for (int b = 0; b < 2; ++b)
; #pragma unroll
;                 for (int m = 0; m < 4; ++m)
; #pragma unroll
;                     for (int n = 0; n < 2; ++n) acc[a][b][m][n] = (f32x4){0.f, 0.f, 0.f, 0.f};
;         cur = nxt; cA = nA; cB = nB; ++ui;
;     template <int GI>
;     __device__ __forceinline__ void body(const f32x4 (&acc)[2][2][4][2], int row0, int colt) const {
;     ...
;             for (int ai = 0; ai < 2; ++ai)
; #pragma unroll
;                 for (int m = 0; m < 4; ++m) {
;                     const size_t row = (size_t)(row0 + ai * 128 + m * 16);
;                     f32x4 x0 = acc[ai][bj][m][0] + b0, x1 = acc[ai][bj][m][1] + b1;
;                     if (GI == 0) {
; #pragma unroll
;                         for (int j = 0; j < 4; ++j) {
;                             x0[j] = 0.6065306597126334f * sigmoidf_(x0[j]); x1[j] = 0.6065306597126334f * sigmoidf_(x1[j]); }
;                         *(u32x4*)(DEC + row * DM + c) = pack8(x0, x1);
	v_fmac_f32_e32 v16, v17, v16
	v_div_scale_f32 v17, vcc, 1.0, v15, 1.0
	v_mul_f32_e32 v18, v17, v16
	v_fma_f32 v19, -v13, v18, v17
	v_fmac_f32_e32 v18, v19, v16
	v_fma_f32 v13, -v13, v18, v17
	v_div_fmas_f32 v13, v13, v16, v18
	v_div_fixup_f32 v15, v13, v15, 1.0
	v_div_scale_f32 v13, s[0:1], v14, v14, 1.0
	v_rcp_f32_e32 v16, v13
	s_nop 0
	v_fma_f32 v17, -v13, v16, 1.0
	v_fmac_f32_e32 v16, v17, v16
	v_div_scale_f32 v17, vcc, 1.0, v14, 1.0
	v_mul_f32_e32 v18, v17, v16
	v_fma_f32 v19, -v13, v18, v17
	v_fmac_f32_e32 v18, v19, v16
	v_fma_f32 v13, -v13, v18, v17
	v_div_fmas_f32 v13, v13, v16, v18
	v_div_fixup_f32 v14, v13, v14, 1.0
	v_pk_mul_f32 v[14:15], v[14:15], s[4:5] op_sel_hi:[1,0]
	s_nop 0
	v_cvt_pk_f16_f32 v13, v14, v15
	global_store_dwordx4 v[78:79], v[10:13], off offset:256
	v_pk_add_f32 v[2:3], v[2:3], v[66:67]
	v_pk_add_f32 v[6:7], v[6:7], v[70:71]
	v_mul_f32_e32 v2, 0xbfb8aa3b, v2
	v_exp_f32_e32 v12, v2
	v_mul_f32_e32 v2, 0xbfb8aa3b, v7
	v_pk_add_f32 v[8:9], v[8:9], v[72:73]
	v_mul_f32_e32 v6, 0xbfb8aa3b, v6
	v_exp_f32_e32 v11, v2
	v_mul_f32_e32 v2, 0xbfb8aa3b, v3
	v_pk_add_f32 v[4:5], v[4:5], v[68:69]
	v_exp_f32_e32 v10, v6
	v_exp_f32_e32 v13, v2
	v_mul_f32_e32 v2, 0xbfb8aa3b, v8
	v_exp_f32_e32 v8, v2
	v_mul_f32_e32 v2, 0xbfb8aa3b, v4
	v_exp_f32_e32 v6, v2
	v_mul_f32_e32 v2, 0xbfb8aa3b, v9
	v_exp_f32_e32 v9, v2
	v_mul_f32_e32 v2, 0xbfb8aa3b, v5
	v_exp_f32_e32 v7, v2
	v_pk_add_f32 v[2:3], v[10:11], 1.0 op_sel_hi:[1,0]
	v_pk_add_f32 v[6:7], v[6:7], 1.0 op_sel_hi:[1,0]
	v_div_scale_f32 v4, s[0:1], v3, v3, 1.0
	v_rcp_f32_e32 v5, v4
	s_nop 0
	v_fma_f32 v10, -v4, v5, 1.0
	v_fmac_f32_e32 v5, v10, v5
	v_div_scale_f32 v10, vcc, 1.0, v3, 1.0
	v_mul_f32_e32 v11, v10, v5
	v_fma_f32 v14, -v4, v11, v10
	v_fmac_f32_e32 v11, v14, v5
	v_fma_f32 v4, -v4, v11, v10
	v_div_fmas_f32 v4, v4, v5, v11
	v_div_fixup_f32 v3, v4, v3, 1.0
	v_div_scale_f32 v4, s[0:1], v2, v2, 1.0
	v_rcp_f32_e32 v5, v4
	s_nop 0
	v_fma_f32 v10, -v4, v5, 1.0
	v_fmac_f32_e32 v5, v10, v5
	v_div_scale_f32 v10, vcc, 1.0, v2, 1.0
	v_mul_f32_e32 v11, v10, v5
	v_fma_f32 v14, -v4, v11, v10
	v_fmac_f32_e32 v11, v14, v5
	v_fma_f32 v4, -v4, v11, v10
	v_div_fmas_f32 v4, v4, v5, v11
	v_div_fixup_f32 v2, v4, v2, 1.0
	v_pk_mul_f32 v[2:3], v[2:3], s[4:5] op_sel_hi:[1,0]
	v_pk_add_f32 v[4:5], v[8:9], 1.0 op_sel_hi:[1,0]
	v_cvt_pk_f16_f32 v2, v2, v3
	v_div_scale_f32 v3, s[0:1], v5, v5, 1.0
	v_rcp_f32_e32 v8, v3
	s_nop 0
	v_fma_f32 v9, -v3, v8, 1.0
	v_fmac_f32_e32 v8, v9, v8
	v_div_scale_f32 v9, vcc, 1.0, v5, 1.0
	v_mul_f32_e32 v10, v9, v8
	v_fma_f32 v11, -v3, v10, v9
	v_fmac_f32_e32 v10, v11, v8
	v_fma_f32 v3, -v3, v10, v9
	v_div_fmas_f32 v3, v3, v8, v10
	v_div_fixup_f32 v5, v3, v5, 1.0
	v_div_scale_f32 v3, s[0:1], v4, v4, 1.0
	v_rcp_f32_e32 v8, v3
	s_nop 0
	v_fma_f32 v9, -v3, v8, 1.0
	v_fmac_f32_e32 v8, v9, v8
	v_div_scale_f32 v9, vcc, 1.0, v4, 1.0
	v_mul_f32_e32 v10, v9, v8
	v_fma_f32 v11, -v3, v10, v9
	v_fmac_f32_e32 v10, v11, v8
	v_fma_f32 v3, -v3, v10, v9
	v_div_fmas_f32 v3, v3, v8, v10
	v_div_fixup_f32 v4, v3, v4, 1.0
	v_pk_mul_f32 v[4:5], v[4:5], s[4:5] op_sel_hi:[1,0]
	s_nop 0
	v_cvt_pk_f16_f32 v3, v4, v5
	v_pk_add_f32 v[4:5], v[12:13], 1.0 op_sel_hi:[1,0]
	s_nop 0
	v_div_scale_f32 v8, s[0:1], v5, v5, 1.0
	v_rcp_f32_e32 v9, v8
	s_nop 0
	v_fma_f32 v10, -v8, v9, 1.0
	v_fmac_f32_e32 v9, v10, v9
	v_div_scale_f32 v10, vcc, 1.0, v5, 1.0
	v_mul_f32_e32 v11, v10, v9
	v_fma_f32 v12, -v8, v11, v10
	v_fmac_f32_e32 v11, v12, v9
	v_fma_f32 v8, -v8, v11, v10
	v_div_fmas_f32 v8, v8, v9, v11
	v_div_fixup_f32 v5, v8, v5, 1.0
	v_div_scale_f32 v8, s[0:1], v4, v4, 1.0
	v_rcp_f32_e32 v9, v8
	s_nop 0
	v_fma_f32 v10, -v8, v9, 1.0
	v_fmac_f32_e32 v9, v10, v9
	v_div_scale_f32 v10, vcc, 1.0, v4, 1.0
	v_mul_f32_e32 v11, v10, v9
	v_fma_f32 v12, -v8, v11, v10
	v_fmac_f32_e32 v11, v12, v9
	v_fma_f32 v8, -v8, v11, v10
	v_div_fmas_f32 v8, v8, v9, v11
	v_div_fixup_f32 v4, v8, v4, 1.0
	v_pk_mul_f32 v[4:5], v[4:5], s[4:5] op_sel_hi:[1,0]
	s_nop 0
	v_cvt_pk_f16_f32 v4, v4, v5
	v_div_scale_f32 v5, s[0:1], v7, v7, 1.0
	v_rcp_f32_e32 v8, v5
	s_nop 0
	v_fma_f32 v9, -v5, v8, 1.0
	v_fmac_f32_e32 v8, v9, v8
	v_div_scale_f32 v9, vcc, 1.0, v7, 1.0
	v_mul_f32_e32 v10, v9, v8
	v_fma_f32 v11, -v5, v10, v9
	v_fmac_f32_e32 v10, v11, v8
	v_fma_f32 v5, -v5, v10, v9
	v_div_fmas_f32 v5, v5, v8, v10
	v_div_fixup_f32 v7, v5, v7, 1.0
	v_div_scale_f32 v5, s[0:1], v6, v6, 1.0
	v_rcp_f32_e32 v8, v5
	s_nop 0
	v_fma_f32 v9, -v5, v8, 1.0
	v_fmac_f32_e32 v8, v9, v8
	v_div_scale_f32 v9, vcc, 1.0, v6, 1.0
	v_mul_f32_e32 v10, v9, v8
	v_fma_f32 v11, -v5, v10, v9
	v_fmac_f32_e32 v10, v11, v8
	v_fma_f32 v5, -v5, v10, v9
	v_div_fmas_f32 v5, v5, v8, v10
	v_div_fixup_f32 v6, v5, v6, 1.0
	v_pk_mul_f32 v[6:7], v[6:7], s[4:5] op_sel_hi:[1,0]
	s_nop 0
	v_cvt_pk_f16_f32 v5, v6, v7
	global_store_dwordx4 v[74:75], v[2:5], off offset:256
	s_and_b64 vcc, exec, s[38:39]
	s_mov_b32 s50, s44
	s_mov_b32 s35, s96
	s_mov_b64 s[26:27], s[68:69]
	s_mov_b64 s[22:23], s[64:65]
	s_cmpk_lt_u32 s71, 0x100
	s_cbranch_scc1 .Lgy4
	s_barrier

; #define PG8_STAGE(bufoff, gbase, voff) do { _Pragma("unroll") for (int _i = 0; _i < 2; ++_i) \
;         __builtin_amdgcn_global_load_lds((const unsigned*)((const char*)(gbase) + (voff)[_i]), (LAS unsigned*)(lds + (bufoff) + ldsw + _i * 8192), 16, 0, 0); } while (0)
; #define PG8_LDA(dst, b, h) do { _Pragma("unroll") for (int m = 0; m < 4; ++m) _Pragma("unroll") for (int k = 0; k < 2; ++k) dst[m][k] = *(const LAS h16x8*)(lds + PG8_SA(b, h) + aoff + m * 2048 + k * 1024); } while (0)
; #define PG8_LDB(dst, b, h) do { _Pragma("unroll") for (int n = 0; n < 2; ++n) _Pragma("unroll") for (int k = 0; k < 2; ++k) dst[n][k] = *(const LAS h16x8*)(lds + PG8_SB(b, h) + boff + n * 2048 + k * 1024); } while (0)
; #define PG8_MMA(ai, bj, At, Bt_) do { __builtin_amdgcn_s_setprio(1); _Pragma("unroll") for (int m = 0; m < 4; ++m) _Pragma("unroll") for (int n = 0; n < 2; ++n) _Pragma("unroll") for (int k = 0; k < 2; ++k) \
;         acc[ai][bj][m][n] = __builtin_amdgcn_mfma_f32_16x16x32_f16(Bt_[n][k], At[m][k], acc[ai][bj][m][n], 0, 0, 0); __builtin_amdgcn_s_setprio(0); } while (0)
; #define PG8_WAIT_L(n) asm volatile("s_waitcnt lgkmcnt(" #n ")" ::: "memory")
; #define PG8_BAR __builtin_amdgcn_s_barrier()
; #define PG8_SCHED __builtin_amdgcn_sched_barrier(0)
; template <class Epi, class AMap>
; __device__ __forceinline__ void gemm_phase(LAS unsigned char* lds, const AMap am, const int lda, const h16* Bt, const int ldb, const int M, const int N, const int K, const Epi& E) {
;     ...
;         for (int t = 0; t < nt; t += 2) {
;             const bool last = (t == nt - 2);
;             const char* a1 = cA + (size_t)(t + 1) * kstep;
;             const char* a2 = last ? nA : cA + (size_t)(t + 2) * kstep; const char* b2 = last ? nB : cB + (size_t)(t + 2) * kstep;
;             const char* a3 = a2 + kstep; const char* b3 = b2 + kstep;
;             PG8_LDB(B0, 0, 0); PG8_SCHED; PG8_LDA(At, 0, 0); PG8_STAGE(PG8_SA(1, 1), a1 + hstepA, voffA);
;             PG8_WAIT_L(8); PG8_BAR; PG8_WAIT_L(0); PG8_MMA(0, 0, At, B0); PG8_BAR; PG8_SCHED;
;             PG8_LDB(B1, 0, 1); PG8_STAGE(PG8_SB(0, 0), b2, voffB);
;             PG8_BAR; PG8_WAIT_L(0); PG8_MMA(0, 1, At, B1); PG8_BAR;
;             PG8_LDA(At, 0, 1); PG8_STAGE(PG8_SA(0, 0), a2, voffA);
;             PG8_BAR; PG8_WAIT_L(0); PG8_MMA(1, 0, At, B0); PG8_BAR; PG8_SCHED;
.LBB0_621:
	s_add_i32 s51, s26, 2
	s_add_u32 s0, s22, 0x100
	s_addc_u32 s1, s23, 0
	s_add_i32 s60, 0, 0x10000
	v_add_u32_e32 v152, s60, v155
	ds_read_b128 v[90:93], v152
	ds_read_b128 v[94:97], v152 offset:1024
	ds_read_b128 v[148:151], v152 offset:2048
	ds_read_b128 v[158:161], v152 offset:3072
	s_cmp_eq_u32 s82, s26
	s_cselect_b32 s26, s21, s29
	s_cselect_b32 s49, s65, s1
	s_cselect_b32 s48, s64, s0
	s_cselect_b32 s27, s20, s45
	v_lshl_add_u64 v[152:153], s[22:23], 0, v[144:145]
	s_add_i32 m0, s76, 0xc000
	ds_read_b128 v[162:165], v157
	ds_read_b128 v[166:169], v157 offset:1024
	ds_read_b128 v[170:173], v157 offset:2048
	ds_read_b128 v[174:177], v157 offset:3072
	ds_read_b128 v[178:181], v157 offset:4096
	ds_read_b128 v[182:185], v157 offset:5120
	ds_read_b128 v[186:189], v157 offset:6144
	ds_read_b128 v[190:193], v157 offset:7168
	global_load_lds_dwordx4 v[152:153], off
	v_lshl_add_u64 v[152:153], s[22:23], 0, v[146:147]
	s_add_i32 m0, s76, 0xe000
	s_nop 0
	global_load_lds_dwordx4 v[152:153], off
	s_waitcnt lgkmcnt(11)
	s_add_i32 s62, 0, 0x14000
	v_add_u32_e32 v152, s62, v155
	s_add_i32 s22, s60, s73
	ds_read_b128 v[194:197], v152
	ds_read_b128 v[198:201], v152 offset:1024
	ds_read_b128 v[202:205], v152 offset:2048
	ds_read_b128 v[220:223], v152 offset:3072
	s_waitcnt vmcnt(8) lgkmcnt(0)
	s_barrier
	v_mfma_f32_16x16x32_f16 v[130:133], v[90:93], v[162:165], v[130:133]
	v_mfma_f32_16x16x32_f16 v[134:137], v[148:151], v[162:165], v[134:137]
	v_mfma_f32_16x16x32_f16 v[126:129], v[90:93], v[170:173], v[126:129]
	v_mfma_f32_16x16x32_f16 v[122:125], v[148:151], v[170:173], v[122:125]
	v_mfma_f32_16x16x32_f16 v[118:121], v[90:93], v[178:181], v[118:121]
	v_mfma_f32_16x16x32_f16 v[114:117], v[148:151], v[178:181], v[114:117]
	v_mfma_f32_16x16x32_f16 v[110:113], v[90:93], v[186:189], v[110:113]
	v_mfma_f32_16x16x32_f16 v[106:109], v[148:151], v[186:189], v[106:109]
	v_mfma_f32_16x16x32_f16 v[130:133], v[94:97], v[166:169], v[130:133]
	v_mfma_f32_16x16x32_f16 v[134:137], v[158:161], v[166:169], v[134:137]
	v_mfma_f32_16x16x32_f16 v[126:129], v[94:97], v[174:177], v[126:129]
	v_mfma_f32_16x16x32_f16 v[122:125], v[158:161], v[174:177], v[122:125]
	v_mfma_f32_16x16x32_f16 v[118:121], v[94:97], v[182:185], v[118:121]
	v_mfma_f32_16x16x32_f16 v[114:117], v[158:161], v[182:185], v[114:117]
	v_mfma_f32_16x16x32_f16 v[110:113], v[94:97], v[190:193], v[110:113]
	v_mfma_f32_16x16x32_f16 v[106:109], v[158:161], v[190:193], v[106:109]
	v_mfma_f32_16x16x32_f16 v[62:65], v[194:197], v[162:165], v[62:65]
	v_mfma_f32_16x16x32_f16 v[58:61], v[202:205], v[162:165], v[58:61]
	v_mfma_f32_16x16x32_f16 v[54:57], v[194:197], v[170:173], v[54:57]
	v_mfma_f32_16x16x32_f16 v[50:53], v[202:205], v[170:173], v[50:53]
	v_mfma_f32_16x16x32_f16 v[46:49], v[194:197], v[178:181], v[46:49]
	v_mfma_f32_16x16x32_f16 v[42:45], v[202:205], v[178:181], v[42:45]
	v_mfma_f32_16x16x32_f16 v[38:41], v[194:197], v[186:189], v[38:41]
	v_mfma_f32_16x16x32_f16 v[34:37], v[202:205], v[186:189], v[34:37]
	v_mfma_f32_16x16x32_f16 v[62:65], v[198:201], v[166:169], v[62:65]
	v_mfma_f32_16x16x32_f16 v[58:61], v[220:223], v[166:169], v[58:61]
	v_mfma_f32_16x16x32_f16 v[54:57], v[198:201], v[174:177], v[54:57]
	v_mfma_f32_16x16x32_f16 v[50:53], v[220:223], v[174:177], v[50:53]
	v_mfma_f32_16x16x32_f16 v[46:49], v[198:201], v[182:185], v[46:49]
	v_mfma_f32_16x16x32_f16 v[42:45], v[220:223], v[182:185], v[42:45]
	v_mfma_f32_16x16x32_f16 v[38:41], v[198:201], v[190:193], v[38:41]
	v_mfma_f32_16x16x32_f16 v[34:37], v[220:223], v[190:193], v[34:37]
	s_barrier
	v_lshl_add_u64 v[152:153], s[26:27], 0, v[0:1]
	s_mov_b32 m0, s22
	v_lshl_add_u64 v[206:207], s[26:27], 0, v[142:143]
	global_load_lds_dwordx4 v[152:153], off
	s_add_i32 m0, s22, 0x2000
	s_nop 0
	global_load_lds_dwordx4 v[206:207], off
	s_mov_b32 m0, s76
	v_lshl_add_u64 v[212:213], s[48:49], 0, v[138:139]
	ds_read_b128 v[162:165], v157 offset:16384
	ds_read_b128 v[166:169], v157 offset:17408
	ds_read_b128 v[170:173], v157 offset:18432
	ds_read_b128 v[174:177], v157 offset:19456
	ds_read_b128 v[178:181], v157 offset:20480
	ds_read_b128 v[182:185], v157 offset:21504
	ds_read_b128 v[186:189], v157 offset:22528
	ds_read_b128 v[190:193], v157 offset:23552
	global_load_lds_dwordx4 v[212:213], off
	v_lshl_add_u64 v[224:225], s[48:49], 0, v[140:141]
	s_mov_b32 m0, s77
	s_nop 0
	global_load_lds_dwordx4 v[224:225], off
	s_add_u32 s22, s26, 0x10000
	s_addc_u32 s23, s27, 0
	s_add_i32 s60, s62, s73
	v_lshl_add_u64 v[232:233], s[22:23], 0, v[0:1]
	s_mov_b32 m0, s60
	s_nop 0
	global_load_lds_dwordx4 v[232:233], off
	v_lshl_add_u64 v[232:233], s[22:23], 0, v[142:143]
	s_add_i32 m0, s60, 0x2000
	s_nop 0
	global_load_lds_dwordx4 v[232:233], off
	s_waitcnt vmcnt(8) lgkmcnt(0)
	s_barrier
; #define PG8_STAGE(bufoff, gbase, voff) do { _Pragma("unroll") for (int _i = 0; _i < 2; ++_i) \
;         __builtin_amdgcn_global_load_lds((const unsigned*)((const char*)(gbase) + (voff)[_i]), (LAS unsigned*)(lds + (bufoff) + ldsw + _i * 8192), 16, 0, 0); } while (0)
; #define PG8_LDA(dst, b, h) do { _Pragma("unroll") for (int m = 0; m < 4; ++m) _Pragma("unroll") for (int k = 0; k < 2; ++k) dst[m][k] = *(const LAS h16x8*)(lds + PG8_SA(b, h) + aoff + m * 2048 + k * 1024); } while (0)
; #define PG8_LDB(dst, b, h) do { _Pragma("unroll") for (int n = 0; n < 2; ++n) _Pragma("unroll") for (int k = 0; k < 2; ++k) dst[n][k] = *(const LAS h16x8*)(lds + PG8_SB(b, h) + boff + n * 2048 + k * 1024); } while (0)
; #define PG8_MMA(ai, bj, At, Bt_) do { __builtin_amdgcn_s_setprio(1); _Pragma("unroll") for (int m = 0; m < 4; ++m) _Pragma("unroll") for (int n = 0; n < 2; ++n) _Pragma("unroll") for (int k = 0; k < 2; ++k) \
;         acc[ai][bj][m][n] = __builtin_amdgcn_mfma_f32_16x16x32_f16(Bt_[n][k], At[m][k], acc[ai][bj][m][n], 0, 0, 0); __builtin_amdgcn_s_setprio(0); } while (0)
; #define PG8_WAIT_V(n) asm volatile("s_waitcnt vmcnt(" #n ")" ::: "memory")
; #define PG8_WAIT_L(n) asm volatile("s_waitcnt lgkmcnt(" #n ")" ::: "memory")
; #define PG8_BAR __builtin_amdgcn_s_barrier()
; #define PG8_SCHED __builtin_amdgcn_sched_barrier(0)
; template <class Epi, class AMap>
; __device__ __forceinline__ void gemm_phase(LAS unsigned char* lds, const AMap am, const int lda, const h16* Bt, const int ldb, const int M, const int N, const int K, const Epi& E) {
;     ...
;             PG8_BAR; PG8_WAIT_L(0); PG8_MMA(1, 0, At, B0); PG8_BAR; PG8_SCHED;
;             PG8_STAGE(PG8_SB(0, 1), b2 + hstepB, voffB);
;             PG8_WAIT_V(6); PG8_BAR; PG8_MMA(1, 1, At, B1); PG8_BAR;
;             PG8_LDB(B0, 1, 0); PG8_SCHED; PG8_LDA(At, 1, 0); PG8_STAGE(PG8_SA(0, 1), a2 + hstepA, voffA);
;             PG8_WAIT_L(8); PG8_BAR; PG8_WAIT_L(0); PG8_MMA(0, 0, At, B0); PG8_BAR; PG8_SCHED;
;             PG8_LDB(B1, 1, 1); PG8_STAGE(PG8_SB(1, 0), b3, voffB);
;             PG8_BAR; PG8_WAIT_L(0); PG8_MMA(0, 1, At, B1); PG8_BAR;
	v_mfma_f32_16x16x32_f16 v[102:105], v[90:93], v[162:165], v[102:105]
	v_mfma_f32_16x16x32_f16 v[98:101], v[148:151], v[162:165], v[98:101]
	v_mfma_f32_16x16x32_f16 v[86:89], v[90:93], v[170:173], v[86:89]
	v_mfma_f32_16x16x32_f16 v[82:85], v[148:151], v[170:173], v[82:85]
	v_mfma_f32_16x16x32_f16 v[78:81], v[90:93], v[178:181], v[78:81]
	v_mfma_f32_16x16x32_f16 v[74:77], v[148:151], v[178:181], v[74:77]
	v_mfma_f32_16x16x32_f16 v[70:73], v[90:93], v[186:189], v[70:73]
	v_mfma_f32_16x16x32_f16 v[66:69], v[148:151], v[186:189], v[66:69]
	v_mfma_f32_16x16x32_f16 v[102:105], v[94:97], v[166:169], v[102:105]
	v_mfma_f32_16x16x32_f16 v[98:101], v[158:161], v[166:169], v[98:101]
	v_mfma_f32_16x16x32_f16 v[86:89], v[94:97], v[174:177], v[86:89]
	v_mfma_f32_16x16x32_f16 v[82:85], v[158:161], v[174:177], v[82:85]
	v_mfma_f32_16x16x32_f16 v[78:81], v[94:97], v[182:185], v[78:81]
	v_mfma_f32_16x16x32_f16 v[74:77], v[158:161], v[182:185], v[74:77]
	v_mfma_f32_16x16x32_f16 v[70:73], v[94:97], v[190:193], v[70:73]
	v_mfma_f32_16x16x32_f16 v[66:69], v[158:161], v[190:193], v[66:69]
	v_mfma_f32_16x16x32_f16 v[30:33], v[194:197], v[162:165], v[30:33]
	v_mfma_f32_16x16x32_f16 v[26:29], v[202:205], v[162:165], v[26:29]
	v_mfma_f32_16x16x32_f16 v[22:25], v[194:197], v[170:173], v[22:25]
	v_mfma_f32_16x16x32_f16 v[18:21], v[202:205], v[170:173], v[18:21]
	v_mfma_f32_16x16x32_f16 v[14:17], v[194:197], v[178:181], v[14:17]
	v_mfma_f32_16x16x32_f16 v[10:13], v[202:205], v[178:181], v[10:13]
	v_mfma_f32_16x16x32_f16 v[6:9], v[194:197], v[186:189], v[6:9]
	v_mfma_f32_16x16x32_f16 v[2:5], v[202:205], v[186:189], v[2:5]
	v_mfma_f32_16x16x32_f16 v[30:33], v[198:201], v[166:169], v[30:33]
	v_mfma_f32_16x16x32_f16 v[26:29], v[220:223], v[166:169], v[26:29]
	v_mfma_f32_16x16x32_f16 v[22:25], v[198:201], v[174:177], v[22:25]
	v_mfma_f32_16x16x32_f16 v[18:21], v[220:223], v[174:177], v[18:21]
	v_mfma_f32_16x16x32_f16 v[14:17], v[198:201], v[182:185], v[14:17]
	v_mfma_f32_16x16x32_f16 v[10:13], v[220:223], v[182:185], v[10:13]
	v_mfma_f32_16x16x32_f16 v[6:9], v[198:201], v[190:193], v[6:9]
	v_mfma_f32_16x16x32_f16 v[2:5], v[220:223], v[190:193], v[2:5]
	s_barrier
	s_add_i32 s60, 0, 0x18000
	v_add_u32_e32 v234, s60, v155
	ds_read_b128 v[90:93], v234
	ds_read_b128 v[94:97], v234 offset:1024
	ds_read_b128 v[148:151], v234 offset:2048
	ds_read_b128 v[158:161], v234 offset:3072
	s_add_u32 s22, s48, 0x1c0000
	s_addc_u32 s23, s49, 0
	s_mov_b32 m0, s78
	v_lshl_add_u64 v[232:233], s[22:23], 0, v[138:139]
	ds_read_b128 v[162:165], v157 offset:32768
	ds_read_b128 v[166:169], v157 offset:33792
	ds_read_b128 v[170:173], v157 offset:34816
	ds_read_b128 v[174:177], v157 offset:35840
	ds_read_b128 v[178:181], v157 offset:36864
	ds_read_b128 v[182:185], v157 offset:37888
	ds_read_b128 v[186:189], v157 offset:38912
	ds_read_b128 v[190:193], v157 offset:39936
	global_load_lds_dwordx4 v[232:233], off
	v_lshl_add_u64 v[232:233], s[22:23], 0, v[140:141]
	s_mov_b32 m0, s79
	s_nop 0
	global_load_lds_dwordx4 v[232:233], off
	s_waitcnt lgkmcnt(11)
	s_add_i32 s48, 0, 0x1c000
	s_add_i32 s22, s60, s73
	v_add_u32_e32 v214, s48, v155
	v_lshl_add_u64 v[152:153], v[152:153], 0, s[92:93]
	s_mov_b32 m0, s22
	ds_read_b128 v[194:197], v214
	ds_read_b128 v[198:201], v214 offset:1024
	ds_read_b128 v[202:205], v214 offset:2048
	ds_read_b128 v[220:223], v214 offset:3072
	s_waitcnt vmcnt(8) lgkmcnt(0)
	s_barrier
	v_mfma_f32_16x16x32_f16 v[130:133], v[90:93], v[162:165], v[130:133]
	v_mfma_f32_16x16x32_f16 v[134:137], v[148:151], v[162:165], v[134:137]
	v_mfma_f32_16x16x32_f16 v[126:129], v[90:93], v[170:173], v[126:129]
	v_mfma_f32_16x16x32_f16 v[122:125], v[148:151], v[170:173], v[122:125]
	v_mfma_f32_16x16x32_f16 v[118:121], v[90:93], v[178:181], v[118:121]
	v_mfma_f32_16x16x32_f16 v[114:117], v[148:151], v[178:181], v[114:117]
	v_mfma_f32_16x16x32_f16 v[110:113], v[90:93], v[186:189], v[110:113]
	v_mfma_f32_16x16x32_f16 v[106:109], v[148:151], v[186:189], v[106:109]
	v_mfma_f32_16x16x32_f16 v[130:133], v[94:97], v[166:169], v[130:133]
	v_mfma_f32_16x16x32_f16 v[134:137], v[158:161], v[166:169], v[134:137]
	v_mfma_f32_16x16x32_f16 v[126:129], v[94:97], v[174:177], v[126:129]
	v_mfma_f32_16x16x32_f16 v[122:125], v[158:161], v[174:177], v[122:125]
	v_mfma_f32_16x16x32_f16 v[118:121], v[94:97], v[182:185], v[118:121]
	v_mfma_f32_16x16x32_f16 v[114:117], v[158:161], v[182:185], v[114:117]
	v_mfma_f32_16x16x32_f16 v[110:113], v[94:97], v[190:193], v[110:113]
	v_mfma_f32_16x16x32_f16 v[106:109], v[158:161], v[190:193], v[106:109]
	v_mfma_f32_16x16x32_f16 v[62:65], v[194:197], v[162:165], v[62:65]
	v_mfma_f32_16x16x32_f16 v[58:61], v[202:205], v[162:165], v[58:61]
	v_mfma_f32_16x16x32_f16 v[54:57], v[194:197], v[170:173], v[54:57]
	v_mfma_f32_16x16x32_f16 v[50:53], v[202:205], v[170:173], v[50:53]
	v_mfma_f32_16x16x32_f16 v[46:49], v[194:197], v[178:181], v[46:49]
	v_mfma_f32_16x16x32_f16 v[42:45], v[202:205], v[178:181], v[42:45]
	v_mfma_f32_16x16x32_f16 v[38:41], v[194:197], v[186:189], v[38:41]
	v_mfma_f32_16x16x32_f16 v[34:37], v[202:205], v[186:189], v[34:37]
	v_mfma_f32_16x16x32_f16 v[62:65], v[198:201], v[166:169], v[62:65]
	v_mfma_f32_16x16x32_f16 v[58:61], v[220:223], v[166:169], v[58:61]
	v_mfma_f32_16x16x32_f16 v[54:57], v[198:201], v[174:177], v[54:57]
	v_mfma_f32_16x16x32_f16 v[50:53], v[220:223], v[174:177], v[50:53]
	v_mfma_f32_16x16x32_f16 v[46:49], v[198:201], v[182:185], v[46:49]
	v_mfma_f32_16x16x32_f16 v[42:45], v[220:223], v[182:185], v[42:45]
	v_mfma_f32_16x16x32_f16 v[38:41], v[198:201], v[190:193], v[38:41]
	v_mfma_f32_16x16x32_f16 v[34:37], v[220:223], v[190:193], v[34:37]
	s_barrier
; #define PG8_STAGE(bufoff, gbase, voff) do { _Pragma("unroll") for (int _i = 0; _i < 2; ++_i) \
;         __builtin_amdgcn_global_load_lds((const unsigned*)((const char*)(gbase) + (voff)[_i]), (LAS unsigned*)(lds + (bufoff) + ldsw + _i * 8192), 16, 0, 0); } while (0)
; #define PG8_LDA(dst, b, h) do { _Pragma("unroll") for (int m = 0; m < 4; ++m) _Pragma("unroll") for (int k = 0; k < 2; ++k) dst[m][k] = *(const LAS h16x8*)(lds + PG8_SA(b, h) + aoff + m * 2048 + k * 1024); } while (0)
; #define PG8_MMA(ai, bj, At, Bt_) do { __builtin_amdgcn_s_setprio(1); _Pragma("unroll") for (int m = 0; m < 4; ++m) _Pragma("unroll") for (int n = 0; n < 2; ++n) _Pragma("unroll") for (int k = 0; k < 2; ++k) \
;         acc[ai][bj][m][n] = __builtin_amdgcn_mfma_f32_16x16x32_f16(Bt_[n][k], At[m][k], acc[ai][bj][m][n], 0, 0, 0); __builtin_amdgcn_s_setprio(0); } while (0)
; #define PG8_WAIT_V(n) asm volatile("s_waitcnt vmcnt(" #n ")" ::: "memory")
; #define PG8_WAIT_L(n) asm volatile("s_waitcnt lgkmcnt(" #n ")" ::: "memory")
; #define PG8_BAR __builtin_amdgcn_s_barrier()
; #define PG8_SCHED __builtin_amdgcn_sched_barrier(0)
; template <class Epi, class AMap>
; __device__ __forceinline__ void gemm_phase(LAS unsigned char* lds, const AMap am, const int lda, const h16* Bt, const int ldb, const int M, const int N, const int K, const Epi& E) {
;     ...
;             PG8_LDA(At, 1, 1); PG8_STAGE(PG8_SA(1, 0), a3, voffA);
;             PG8_BAR; PG8_WAIT_L(0); PG8_MMA(1, 0, At, B0); PG8_BAR; PG8_SCHED;
;             PG8_STAGE(PG8_SB(1, 1), b3 + hstepB, voffB);
;             PG8_WAIT_V(6); PG8_BAR; PG8_MMA(1, 1, At, B1); PG8_BAR;
;         }
	global_load_lds_dwordx4 v[152:153], off
	v_lshl_add_u64 v[152:153], v[206:207], 0, s[92:93]
	s_add_i32 m0, s22, 0x2000
	s_nop 0
	global_load_lds_dwordx4 v[152:153], off
	s_mov_b32 m0, s80
	v_lshl_add_u64 v[152:153], v[212:213], 0, s[92:93]
	ds_read_b128 v[162:165], v157 offset:49152
	ds_read_b128 v[166:169], v157 offset:50176
	ds_read_b128 v[170:173], v157 offset:51200
	ds_read_b128 v[174:177], v157 offset:52224
	ds_read_b128 v[178:181], v157 offset:53248
	ds_read_b128 v[182:185], v157 offset:54272
	ds_read_b128 v[186:189], v157 offset:55296
	ds_read_b128 v[190:193], v157 offset:56320
	global_load_lds_dwordx4 v[152:153], off
	v_lshl_add_u64 v[152:153], v[224:225], 0, s[92:93]
	s_mov_b32 m0, s81
	s_nop 0
	global_load_lds_dwordx4 v[152:153], off
	s_add_u32 s22, s26, 0x10080
	s_addc_u32 s23, s27, 0
	s_add_i32 s26, s48, s73
	v_lshl_add_u64 v[232:233], s[22:23], 0, v[0:1]
	s_mov_b32 m0, s26
	s_nop 0
	global_load_lds_dwordx4 v[232:233], off
	v_lshl_add_u64 v[232:233], s[22:23], 0, v[142:143]
	s_add_i32 m0, s26, 0x2000
	s_nop 0
	global_load_lds_dwordx4 v[232:233], off
	s_add_u32 s29, s29, 0x100
	s_addc_u32 s45, s45, 0
	s_cmp_ge_i32 s51, s24
	s_mov_b64 s[22:23], s[0:1]
	s_mov_b32 s26, s51
	s_waitcnt vmcnt(8) lgkmcnt(0)
	s_barrier
	v_mfma_f32_16x16x32_f16 v[102:105], v[90:93], v[162:165], v[102:105]
	v_mfma_f32_16x16x32_f16 v[98:101], v[148:151], v[162:165], v[98:101]
	v_mfma_f32_16x16x32_f16 v[86:89], v[90:93], v[170:173], v[86:89]
	v_mfma_f32_16x16x32_f16 v[82:85], v[148:151], v[170:173], v[82:85]
	v_mfma_f32_16x16x32_f16 v[78:81], v[90:93], v[178:181], v[78:81]
	v_mfma_f32_16x16x32_f16 v[74:77], v[148:151], v[178:181], v[74:77]
	v_mfma_f32_16x16x32_f16 v[70:73], v[90:93], v[186:189], v[70:73]
	v_mfma_f32_16x16x32_f16 v[66:69], v[148:151], v[186:189], v[66:69]
	v_mfma_f32_16x16x32_f16 v[102:105], v[94:97], v[166:169], v[102:105]
	v_mfma_f32_16x16x32_f16 v[98:101], v[158:161], v[166:169], v[98:101]
	v_mfma_f32_16x16x32_f16 v[86:89], v[94:97], v[174:177], v[86:89]
	v_mfma_f32_16x16x32_f16 v[82:85], v[158:161], v[174:177], v[82:85]
	v_mfma_f32_16x16x32_f16 v[78:81], v[94:97], v[182:185], v[78:81]
	v_mfma_f32_16x16x32_f16 v[74:77], v[158:161], v[182:185], v[74:77]
	v_mfma_f32_16x16x32_f16 v[70:73], v[94:97], v[190:193], v[70:73]
	v_mfma_f32_16x16x32_f16 v[66:69], v[158:161], v[190:193], v[66:69]
	v_mfma_f32_16x16x32_f16 v[30:33], v[194:197], v[162:165], v[30:33]
	v_mfma_f32_16x16x32_f16 v[26:29], v[202:205], v[162:165], v[26:29]
	v_mfma_f32_16x16x32_f16 v[22:25], v[194:197], v[170:173], v[22:25]
	v_mfma_f32_16x16x32_f16 v[18:21], v[202:205], v[170:173], v[18:21]
	v_mfma_f32_16x16x32_f16 v[14:17], v[194:197], v[178:181], v[14:17]
	v_mfma_f32_16x16x32_f16 v[10:13], v[202:205], v[178:181], v[10:13]
	v_mfma_f32_16x16x32_f16 v[6:9], v[194:197], v[186:189], v[6:9]
	v_mfma_f32_16x16x32_f16 v[2:5], v[202:205], v[186:189], v[2:5]
	v_mfma_f32_16x16x32_f16 v[30:33], v[198:201], v[166:169], v[30:33]
	v_mfma_f32_16x16x32_f16 v[26:29], v[220:223], v[166:169], v[26:29]
	v_mfma_f32_16x16x32_f16 v[22:25], v[198:201], v[174:177], v[22:25]
	v_mfma_f32_16x16x32_f16 v[18:21], v[220:223], v[174:177], v[18:21]
	v_mfma_f32_16x16x32_f16 v[14:17], v[198:201], v[182:185], v[14:17]
	v_mfma_f32_16x16x32_f16 v[10:13], v[220:223], v[182:185], v[10:13]
	v_mfma_f32_16x16x32_f16 v[6:9], v[198:201], v[190:193], v[6:9]
	v_mfma_f32_16x16x32_f16 v[2:5], v[220:223], v[190:193], v[2:5]
	s_barrier
	s_cbranch_scc0 .LBB0_621
	s_branch .LBB0_610

; __device__ __forceinline__ float sigmoidf_(float x) { return 1.0f / (1.0f + __expf(-x)); }
;     __device__ __forceinline__ void body_a(const f32x4 (&acc)[2][2][4][2], int row0, int cb0) const {
; #pragma unroll
;         for (int ai = 0; ai < 2; ++ai)
; #pragma unroll
;             for (int m = 0; m < 4; ++m) {
;                 const size_t row = (size_t)(row0 + ai * 128 + m * 16);
;                 asm volatile("" ::: "memory");
;                 float a[2][8], kv[2][8], kk[2][8]; float ss = 0.f;
; #pragma unroll
;                 for (int bj = 0; bj < 2; ++bj) {
;                     const int c = cb0 + 32 * bj;
;                     const f32x4 b0 = *(const f32x4*)(a0 + c), b1 = *(const f32x4*)(a0 + c + 4), q0 = *(const f32x4*)(k_k + c), q1 = *(const f32x4*)(k_k + c + 4);
;                     const h16x8 kh = *(const h16x8*)(C1 + row * LDC1 + 2048 + c);
; #pragma unroll
;                     for (int e = 0; e < 4; ++e) {
;                         a[bj][e] = sigmoidf_(acc[ai][bj][m][0][e] + b0[e]); a[bj][4 + e] = sigmoidf_(acc[ai][bj][m][1][e] + b1[e]);
;                         kv[bj][e] = (float)kh[e]; kv[bj][4 + e] = (float)kh[4 + e];
;                         kk[bj][e] = kv[bj][e] * q0[e]; kk[bj][4 + e] = kv[bj][4 + e] * q1[e];
;                         ss += kk[bj][e] * kk[bj][e] + kk[bj][4 + e] * kk[bj][4 + e];
;                     }
;                 }
.LBB0_633:
	v_lshl_or_b32 v170, s50, 8, v204
	v_ashrrev_i32_e32 v171, 31, v170
	v_lshlrev_b64 v[198:199], 2, v[170:171]
	v_lshl_add_u64 v[154:155], s[40:41], 0, v[198:199]
	global_load_dwordx4 v[162:165], v[154:155], off offset:16
	global_load_dwordx4 v[166:169], v[154:155], off
	v_lshl_add_u32 v158, s35, 8, v202
	v_mov_b64_e32 v[160:161], s[8:9]
	v_mad_i64_i32 v[130:131], s[0:1], v158, s5, v[160:161]
	s_mov_b64 s[6:7], 0x1000
	v_readlane_b32 s0, v255, 15
	v_lshl_add_u64 v[172:173], v[130:131], 0, s[6:7]
	v_readlane_b32 s1, v255, 16
	v_lshlrev_b64 v[152:153], 1, v[170:171]
	v_lshl_add_u64 v[184:185], v[172:173], 0, v[152:153]
	v_lshl_add_u64 v[156:157], s[0:1], 0, v[198:199]
	global_load_dwordx4 v[130:133], v[156:157], off offset:16
	global_load_dwordx4 v[134:137], v[156:157], off
	global_load_dwordx4 v[138:141], v[184:185], off
	v_readlane_b32 s0, v255, 13
	v_readlane_b32 s1, v255, 14
	s_mov_b32 s4, 0xf800000
	v_ashrrev_i32_e32 v159, 31, v158
	v_readlane_b32 s10, v254, 60
	v_readlane_b32 s11, v254, 61
	s_cmpk_gt_u32 s69, 0xff
	s_cbranch_scc1 .Lgx5
	s_barrier
.Lgx5:
	s_waitcnt vmcnt(0)
	v_add_f32_e32 v122, v122, v166
	v_mul_f32_e32 v122, 0xbfb8aa3b, v122
	v_exp_f32_e32 v196, v122
	v_add_f32_e32 v122, v126, v162
	v_mul_f32_e32 v122, 0xbfb8aa3b, v122
	v_exp_f32_e32 v192, v122
	v_add_f32_e32 v122, v123, v167
	v_mul_f32_e32 v122, 0xbfb8aa3b, v122
	v_exp_f32_e32 v197, v122
	v_add_f32_e32 v122, v127, v163
	v_mul_f32_e32 v122, 0xbfb8aa3b, v122
	v_exp_f32_e32 v193, v122
	v_add_f32_e32 v122, v124, v168
	v_mul_f32_e32 v122, 0xbfb8aa3b, v122
	v_exp_f32_e32 v194, v122
	v_add_f32_e32 v122, v128, v164
	v_mul_f32_e32 v122, 0xbfb8aa3b, v122
	v_exp_f32_e32 v186, v122
	v_add_f32_e32 v122, v125, v169
	v_mul_f32_e32 v122, 0xbfb8aa3b, v122
	v_exp_f32_e32 v195, v122
	v_add_f32_e32 v122, v129, v165
	v_mul_f32_e32 v122, 0xbfb8aa3b, v122
	v_exp_f32_e32 v187, v122
	v_or_b32_e32 v122, 32, v170
	v_ashrrev_i32_e32 v123, 31, v122
	v_lshlrev_b64 v[128:129], 1, v[122:123]
	v_lshl_add_u64 v[122:123], v[172:173], 0, v[128:129]
	global_load_dwordx4 v[124:127], v[154:155], off offset:144
	global_load_dwordx4 v[162:165], v[154:155], off offset:128
	global_load_dwordx4 v[188:191], v[156:157], off offset:144
	global_load_dwordx4 v[220:223], v[156:157], off offset:128
	global_load_dwordx4 v[166:169], v[122:123], off
	v_pk_add_f32 v[196:197], v[196:197], 1.0 op_sel_hi:[1,0]
	s_waitcnt vmcnt(0)
	v_add_f32_e32 v114, v114, v124
	v_mul_f32_e32 v114, 0xbfb8aa3b, v114
	v_exp_f32_e32 v174, v114
	v_add_f32_e32 v114, v119, v163
	v_cvt_f32_f16_e32 v172, v168
	v_cvt_f32_f16_sdwa v173, v168 dst_sel:DWORD dst_unused:UNUSED_PAD src0_sel:WORD_1
	v_cvt_f32_f16_e32 v180, v166
	v_cvt_f32_f16_sdwa v181, v166 dst_sel:DWORD dst_unused:UNUSED_PAD src0_sel:WORD_1
	v_mul_f32_e32 v114, 0xbfb8aa3b, v114
	v_exp_f32_e32 v183, v114
	v_add_f32_e32 v114, v115, v125
	v_mul_f32_e32 v114, 0xbfb8aa3b, v114
	v_pk_mul_f32 v[124:125], v[188:189], v[172:173]
	v_add_f32_e32 v118, v118, v162
	v_exp_f32_e32 v175, v114
	v_pk_mul_f32 v[162:163], v[220:221], v[180:181]
	v_pk_mul_f32 v[114:115], v[124:125], v[124:125]
	v_cvt_f32_f16_e32 v168, v169
	v_pk_fma_f32 v[188:189], v[162:163], v[162:163], v[114:115]
	v_add_f32_e32 v114, v120, v164
	v_mul_f32_e32 v114, 0xbfb8aa3b, v114
	v_exp_f32_e32 v178, v114
	v_add_f32_e32 v114, v116, v126
	v_mul_f32_e32 v114, 0xbfb8aa3b, v114
	v_cvt_f32_f16_sdwa v169, v169 dst_sel:DWORD dst_unused:UNUSED_PAD src0_sel:WORD_1
	v_exp_f32_e32 v170, v114
	v_add_f32_e32 v114, v121, v165
	v_cvt_f32_f16_e32 v176, v167
	v_cvt_f32_f16_sdwa v177, v167 dst_sel:DWORD dst_unused:UNUSED_PAD src0_sel:WORD_1
	v_mul_f32_e32 v114, 0xbfb8aa3b, v114
	v_exp_f32_e32 v179, v114
	v_add_f32_e32 v114, v117, v127
	v_mul_f32_e32 v114, 0xbfb8aa3b, v114
	v_pk_mul_f32 v[164:165], v[190:191], v[168:169]
	v_exp_f32_e32 v171, v114
	v_pk_mul_f32 v[166:167], v[222:223], v[176:177]
	v_pk_mul_f32 v[114:115], v[164:165], v[164:165]
	v_mul_f32_e32 v118, 0xbfb8aa3b, v118
	v_pk_fma_f32 v[190:191], v[166:167], v[166:167], v[114:115]
	v_and_b32_e32 v115, 64, v246
	v_xor_b32_e32 v114, 16, v246
	v_add_u32_e32 v115, 64, v115
	v_cmp_lt_i32_e32 vcc, v114, v115
	v_lshl_add_u64 v[126:127], s[0:1], 0, v[198:199]
	v_exp_f32_e32 v182, v118
	v_cndmask_b32_e32 v114, v246, v114, vcc
	v_lshlrev_b32_e32 v206, 2, v114
	v_xor_b32_e32 v114, 32, v246
	v_cmp_lt_i32_e32 vcc, v114, v115
	v_cvt_f32_f16_e32 v198, v138
	v_cvt_f32_f16_sdwa v199, v138 dst_sel:DWORD dst_unused:UNUSED_PAD src0_sel:WORD_1
	v_cndmask_b32_e32 v114, v246, v114, vcc
	v_lshlrev_b32_e32 v207, 2, v114
	global_load_dwordx4 v[114:117], v[126:127], off offset:16
	global_load_dwordx4 v[118:121], v[126:127], off
	v_div_scale_f32 v138, s[0:1], v197, v197, 1.0
	v_rcp_f32_e32 v200, v138
	s_nop 0
	v_fma_f32 v201, -v138, v200, 1.0
	v_fmac_f32_e32 v200, v201, v200
	v_div_scale_f32 v201, vcc, 1.0, v197, 1.0
	v_mul_f32_e32 v212, v201, v200
	v_fma_f32 v213, -v138, v212, v201
	v_fmac_f32_e32 v212, v213, v200
	v_fma_f32 v138, -v138, v212, v201
	v_div_fmas_f32 v138, v138, v200, v212
	v_div_fixup_f32 v197, v138, v197, 1.0
	v_div_scale_f32 v138, s[0:1], v196, v196, 1.0
	v_rcp_f32_e32 v200, v138
	s_nop 0
	v_fma_f32 v201, -v138, v200, 1.0
	v_fmac_f32_e32 v200, v201, v200
	v_div_scale_f32 v201, vcc, 1.0, v196, 1.0
	v_mul_f32_e32 v212, v201, v200
	v_fma_f32 v213, -v138, v212, v201
	v_fmac_f32_e32 v212, v213, v200
	v_fma_f32 v138, -v138, v212, v201
	v_div_fmas_f32 v138, v138, v200, v212
	v_div_fixup_f32 v196, v138, v196, 1.0
	v_pk_add_f32 v[200:201], v[196:197], -1.0 op_sel_hi:[1,0]
	s_waitcnt vmcnt(0)
; __device__ __forceinline__ float sigmoidf_(float x) { return 1.0f / (1.0f + __expf(-x)); }
;     __device__ __forceinline__ void body_a(const f32x4 (&acc)[2][2][4][2], int row0, int cb0) const {
;     ...
;                 for (int bj = 0; bj < 2; ++bj) {
;                     const int c = cb0 + 32 * bj;
;                     const f32x4 b0 = *(const f32x4*)(a0 + c), b1 = *(const f32x4*)(a0 + c + 4), q0 = *(const f32x4*)(k_k + c), q1 = *(const f32x4*)(k_k + c + 4);
;                     const h16x8 kh = *(const h16x8*)(C1 + row * LDC1 + 2048 + c);
; #pragma unroll
;                     for (int e = 0; e < 4; ++e) {
;                         a[bj][e] = sigmoidf_(acc[ai][bj][m][0][e] + b0[e]); a[bj][4 + e] = sigmoidf_(acc[ai][bj][m][1][e] + b1[e]);
;                         kv[bj][e] = (float)kh[e]; kv[bj][4 + e] = (float)kh[4 + e];
;                         kk[bj][e] = kv[bj][e] * q0[e]; kk[bj][4 + e] = kv[bj][4 + e] * q1[e];
;                         ss += kk[bj][e] * kk[bj][e] + kk[bj][4 + e] * kk[bj][4 + e];
;                     }
;                 }
;                 ss += __shfl_xor(ss, 16); ss += __shfl_xor(ss, 32);
;                 const float inv = 1.0f / fmaxf(sqrtf(ss), 1e-12f);
; #pragma unroll
;                 for (int bj = 0; bj < 2; ++bj) {
;                     const int c = cb0 + 32 * bj;
;                     const f32x4 p0 = *(const f32x4*)(k_a + c), p1 = *(const f32x4*)(k_a + c + 4);
;                     f32x4 ko0, ko1, ao0, ao1, bo0, bo1;
; #pragma unroll
;                     for (int e = 0; e < 4; ++e) {
;                         ko0[e] = kv[bj][e] * (1.0f + (a[bj][e] - 1.0f) * p0[e]); ko1[e] = kv[bj][4 + e] * (1.0f + (a[bj][4 + e] - 1.0f) * p1[e]);
;                         const float n0_ = kk[bj][e] * inv, n1_ = kk[bj][4 + e] * inv;
;                         ao0[e] = -n0_; ao1[e] = -n1_; bo0[e] = n0_ * a[bj][e]; bo1[e] = n1_ * a[bj][4 + e];
;                     }
;                     *(u32x4*)(C1 + row * LDC1 + 2048 + c) = pack8(ko0, ko1);
;                     *(u32x4*)(AA + row * DM + c) = pack8(ao0, ao1);
;                     *(u32x4*)(Ab + row * DM + c) = pack8(bo0, bo1);
;                 }
	v_pk_fma_f32 v[118:119], v[200:201], v[118:119], 1.0 op_sel_hi:[1,1,0]
	s_nop 0
	v_pk_mul_f32 v[118:119], v[118:119], v[198:199]
	v_cvt_f32_f16_e32 v200, v139
	v_cvt_f32_f16_sdwa v201, v139 dst_sel:DWORD dst_unused:UNUSED_PAD src0_sel:WORD_1
	v_pk_add_f32 v[138:139], v[194:195], 1.0 op_sel_hi:[1,0]
	v_cvt_pk_f16_f32 v118, v118, v119
	v_div_scale_f32 v119, s[0:1], v139, v139, 1.0
	v_rcp_f32_e32 v194, v119
	s_nop 0
	v_fma_f32 v195, -v119, v194, 1.0
	v_fmac_f32_e32 v194, v195, v194
	v_div_scale_f32 v195, vcc, 1.0, v139, 1.0
	v_mul_f32_e32 v212, v195, v194
	v_fma_f32 v213, -v119, v212, v195
	v_fmac_f32_e32 v212, v213, v194
	v_fma_f32 v119, -v119, v212, v195
	v_div_fmas_f32 v119, v119, v194, v212
	v_div_fixup_f32 v139, v119, v139, 1.0
	v_div_scale_f32 v119, s[0:1], v138, v138, 1.0
	v_rcp_f32_e32 v194, v119
	s_nop 0
	v_fma_f32 v195, -v119, v194, 1.0
	v_fmac_f32_e32 v194, v195, v194
	v_div_scale_f32 v195, vcc, 1.0, v138, 1.0
	v_mul_f32_e32 v212, v195, v194
	v_fma_f32 v213, -v119, v212, v195
	v_fmac_f32_e32 v212, v213, v194
	v_fma_f32 v119, -v119, v212, v195
	v_div_fmas_f32 v119, v119, v194, v212
	v_div_fixup_f32 v138, v119, v138, 1.0
	v_pk_add_f32 v[194:195], v[138:139], -1.0 op_sel_hi:[1,0]
	s_nop 0
	v_pk_fma_f32 v[120:121], v[194:195], v[120:121], 1.0 op_sel_hi:[1,1,0]
	v_cvt_f32_f16_e32 v194, v140
	v_pk_mul_f32 v[120:121], v[120:121], v[200:201]
	v_cvt_f32_f16_sdwa v195, v140 dst_sel:DWORD dst_unused:UNUSED_PAD src0_sel:WORD_1
	v_cvt_pk_f16_f32 v119, v120, v121
	v_pk_add_f32 v[120:121], v[192:193], 1.0 op_sel_hi:[1,0]
	s_nop 0
	v_div_scale_f32 v140, s[0:1], v121, v121, 1.0
	v_rcp_f32_e32 v192, v140
	s_nop 0
	v_fma_f32 v193, -v140, v192, 1.0
	v_fmac_f32_e32 v192, v193, v192
	v_div_scale_f32 v193, vcc, 1.0, v121, 1.0
	v_mul_f32_e32 v212, v193, v192
	v_fma_f32 v213, -v140, v212, v193
	v_fmac_f32_e32 v212, v213, v192
	v_fma_f32 v140, -v140, v212, v193
	v_div_fmas_f32 v140, v140, v192, v212
	v_div_fixup_f32 v193, v140, v121, 1.0
	v_div_scale_f32 v121, s[0:1], v120, v120, 1.0
	v_rcp_f32_e32 v140, v121
	s_nop 0
	v_fma_f32 v192, -v121, v140, 1.0
	v_fmac_f32_e32 v140, v192, v140
	v_div_scale_f32 v192, vcc, 1.0, v120, 1.0
	v_mul_f32_e32 v212, v192, v140
	v_fma_f32 v213, -v121, v212, v192
	v_fmac_f32_e32 v212, v213, v140
	v_fma_f32 v121, -v121, v212, v192
	v_div_fmas_f32 v121, v121, v140, v212
	v_div_fixup_f32 v192, v121, v120, 1.0
	v_pk_add_f32 v[120:121], v[192:193], -1.0 op_sel_hi:[1,0]
	v_cvt_f32_f16_e32 v140, v141
	v_pk_fma_f32 v[114:115], v[120:121], v[114:115], 1.0 op_sel_hi:[1,1,0]
	v_cvt_f32_f16_sdwa v141, v141 dst_sel:DWORD dst_unused:UNUSED_PAD src0_sel:WORD_1
	v_pk_mul_f32 v[114:115], v[114:115], v[194:195]
	v_pk_mul_f32 v[132:133], v[132:133], v[140:141]
	v_cvt_pk_f16_f32 v120, v114, v115
	v_pk_add_f32 v[114:115], v[186:187], 1.0 op_sel_hi:[1,0]
	s_nop 0
	v_div_scale_f32 v121, s[0:1], v115, v115, 1.0
	v_rcp_f32_e32 v186, v121
	s_nop 0
	v_fma_f32 v187, -v121, v186, 1.0
	v_fmac_f32_e32 v186, v187, v186
	v_div_scale_f32 v187, vcc, 1.0, v115, 1.0
	v_mul_f32_e32 v212, v187, v186
	v_fma_f32 v213, -v121, v212, v187
	v_fmac_f32_e32 v212, v213, v186
	v_fma_f32 v121, -v121, v212, v187
	v_div_fmas_f32 v121, v121, v186, v212
	v_div_fixup_f32 v115, v121, v115, 1.0
	v_div_scale_f32 v121, s[0:1], v114, v114, 1.0
	v_rcp_f32_e32 v186, v121
	s_nop 0
	v_fma_f32 v187, -v121, v186, 1.0
	v_fmac_f32_e32 v186, v187, v186
	v_div_scale_f32 v187, vcc, 1.0, v114, 1.0
	v_mul_f32_e32 v212, v187, v186
	v_fma_f32 v213, -v121, v212, v187
	v_fmac_f32_e32 v212, v213, v186
	v_fma_f32 v121, -v121, v212, v187
	v_div_fmas_f32 v121, v121, v186, v212
	v_div_fixup_f32 v114, v121, v114, 1.0
	v_pk_add_f32 v[186:187], v[114:115], -1.0 op_sel_hi:[1,0]
	s_nop 0
	v_pk_fma_f32 v[116:117], v[186:187], v[116:117], 1.0 op_sel_hi:[1,1,0]
	s_nop 0
	v_pk_mul_f32 v[116:117], v[116:117], v[140:141]
	s_nop 0
	v_cvt_pk_f16_f32 v121, v116, v117
	global_store_dwordx4 v[184:185], v[118:121], off
	v_pk_mul_f32 v[116:117], v[134:135], v[198:199]
	v_pk_mul_f32 v[134:135], v[132:133], v[132:133]
	v_pk_mul_f32 v[120:121], v[130:131], v[194:195]
	v_pk_mul_f32 v[118:119], v[136:137], v[200:201]
	v_pk_mul_f32 v[130:131], v[120:121], v[120:121]
	v_pk_fma_f32 v[134:135], v[118:119], v[118:119], v[134:135]
	v_pk_fma_f32 v[130:131], v[116:117], v[116:117], v[130:131]
	v_lshlrev_b64 v[184:185], 12, v[158:159]
	v_add_f32_e32 v130, v130, v131
	v_add_f32_e32 v130, v134, v130
	v_add_f32_e32 v130, v135, v130
	v_add_f32_e32 v130, v130, v188
	v_add_f32_e32 v130, v189, v130
	v_add_f32_e32 v130, v190, v130
	v_add_f32_e32 v130, v191, v130
	ds_bpermute_b32 v131, v206, v130
	s_waitcnt lgkmcnt(0)
	v_add_f32_e32 v130, v130, v131
	ds_bpermute_b32 v131, v207, v130
	s_waitcnt lgkmcnt(0)
;     __device__ __forceinline__ void body_a(const f32x4 (&acc)[2][2][4][2], int row0, int cb0) const {
;     ...
;                 ss += __shfl_xor(ss, 16); ss += __shfl_xor(ss, 32);
;                 const float inv = 1.0f / fmaxf(sqrtf(ss), 1e-12f);
; #pragma unroll
;                 for (int bj = 0; bj < 2; ++bj) {
;                     const int c = cb0 + 32 * bj;
;                     const f32x4 p0 = *(const f32x4*)(k_a + c), p1 = *(const f32x4*)(k_a + c + 4);
;                     f32x4 ko0, ko1, ao0, ao1, bo0, bo1;
; #pragma unroll
;                     for (int e = 0; e < 4; ++e) {
;                         ko0[e] = kv[bj][e] * (1.0f + (a[bj][e] - 1.0f) * p0[e]); ko1[e] = kv[bj][4 + e] * (1.0f + (a[bj][4 + e] - 1.0f) * p1[e]);
;                         const float n0_ = kk[bj][e] * inv, n1_ = kk[bj][4 + e] * inv;
;                         ao0[e] = -n0_; ao1[e] = -n1_; bo0[e] = n0_ * a[bj][e]; bo1[e] = n1_ * a[bj][4 + e];
;                     }
;                     *(u32x4*)(C1 + row * LDC1 + 2048 + c) = pack8(ko0, ko1);
;                     *(u32x4*)(AA + row * DM + c) = pack8(ao0, ao1);
;                     *(u32x4*)(Ab + row * DM + c) = pack8(bo0, bo1);
;                 }
	v_add_f32_e32 v130, v130, v131
	v_cmp_gt_f32_e32 vcc, s4, v130
	v_mul_f32_e32 v131, 0x4f800000, v130
	s_nop 0
	v_cndmask_b32_e32 v130, v130, v131, vcc
	v_sqrt_f32_e32 v131, v130
	s_nop 0
	v_add_u32_e32 v134, -1, v131
	v_fma_f32 v135, -v134, v131, v130
	v_cmp_ge_f32_e64 s[0:1], 0, v135
	v_add_u32_e32 v135, 1, v131
	s_nop 0
	v_cndmask_b32_e64 v134, v131, v134, s[0:1]
	v_fma_f32 v131, -v135, v131, v130
	v_cmp_lt_f32_e64 s[0:1], 0, v131
	s_nop 1
	v_cndmask_b32_e64 v131, v134, v135, s[0:1]
	v_mul_f32_e32 v134, 0x37800000, v131
	v_cndmask_b32_e32 v131, v131, v134, vcc
	v_cmp_class_f32_e32 vcc, v130, v244
	s_nop 1
	v_cndmask_b32_e32 v130, v131, v130, vcc
	v_max_f32_e32 v130, 0x2b8cbccc, v130
	v_div_scale_f32 v131, s[0:1], v130, v130, 1.0
	v_rcp_f32_e32 v134, v131
	s_nop 0
	v_fma_f32 v135, -v131, v134, 1.0
	v_fmac_f32_e32 v134, v135, v134
	v_div_scale_f32 v135, vcc, 1.0, v130, 1.0
	v_mul_f32_e32 v136, v135, v134
	v_fma_f32 v137, -v131, v136, v135
	v_fmac_f32_e32 v136, v137, v134
	v_fma_f32 v131, -v131, v136, v135
	v_div_fmas_f32 v131, v131, v134, v136
	v_div_fixup_f32 v134, v131, v130, 1.0
	v_pk_mul_f32 v[140:141], v[118:119], v[134:135] op_sel_hi:[1,0]
	v_pk_mul_f32 v[136:137], v[116:117], v[134:135] op_sel_hi:[1,0]
	v_cvt_pk_f16_f32 v117, v140, v141
	v_cvt_pk_f16_f32 v116, v136, v137
	v_xor_b32_e32 v118, 0x8000, v117
	v_xor_b32_sdwa v117, s63, v117 dst_sel:DWORD dst_unused:UNUSED_PAD src0_sel:DWORD src1_sel:WORD_1
	v_pk_mul_f32 v[120:121], v[120:121], v[134:135] op_sel_hi:[1,0]
	v_pk_mul_f32 v[132:133], v[132:133], v[134:135] op_sel_hi:[1,0]
	v_perm_b32 v117, v117, v118, s33
	v_xor_b32_e32 v118, 0x8000, v116
	v_xor_b32_sdwa v116, s63, v116 dst_sel:DWORD dst_unused:UNUSED_PAD src0_sel:DWORD src1_sel:WORD_1
	v_perm_b32 v116, v116, v118, s33
	v_pk_add_f32 v[118:119], v[120:121], 0 neg_lo:[1,1] neg_hi:[1,1]
	v_pk_add_f32 v[130:131], v[132:133], 0 neg_lo:[1,1] neg_hi:[1,1]
	v_cvt_pk_f16_f32 v118, v118, v119
	v_cvt_pk_f16_f32 v119, v130, v131
	v_lshl_add_u64 v[130:131], s[10:11], 0, v[184:185]
	v_lshl_add_u64 v[130:131], v[130:131], 0, v[152:153]
	global_store_dwordx4 v[130:131], v[116:119], off
	v_fma_mixlo_f16 v135, v196, v136, 0
	v_mul_f32_e32 v159, v162, v134
	v_pk_mov_b32 v[116:117], v[196:197], v[138:139] op_sel:[1,0]
	v_pk_mov_b32 v[118:119], v[136:137], v[140:141] op_sel:[1,0]
	v_pk_mov_b32 v[136:137], v[140:141], v[120:121] op_sel:[1,0]
	v_pk_mul_f32 v[116:117], v[116:117], v[118:119]
	v_pk_mov_b32 v[118:119], v[138:139], v[192:193] op_sel:[1,0]
	v_cvt_pk_f16_f32 v117, v116, v117
	v_pk_mul_f32 v[118:119], v[118:119], v[136:137]
	v_pack_b32_f16 v116, v135, v117
	v_cvt_pk_f16_f32 v135, v118, v119
	v_pk_mov_b32 v[118:119], v[192:193], v[114:115] op_sel:[1,0]
	v_pk_mov_b32 v[120:121], v[120:121], v[132:133] op_sel:[1,0]
	v_alignbit_b32 v117, v135, v117, 16
	v_pk_mul_f32 v[118:119], v[118:119], v[120:121]
	v_pk_add_f32 v[136:137], v[182:183], 1.0 op_sel_hi:[1,0]
	v_cvt_pk_f16_f32 v114, v118, v119
	v_lshrrev_b32_e32 v119, 16, v114
	v_alignbit_b32 v118, v114, v135, 16
	v_fma_mixhi_f16 v119, v115, v133, 0
	v_lshl_add_u64 v[114:115], s[2:3], 0, v[184:185]
	v_lshl_add_u64 v[132:133], v[114:115], 0, v[152:153]
	global_store_dwordx4 v[132:133], v[116:119], off
	global_load_dwordx4 v[114:117], v[126:127], off offset:144
	s_nop 0
	global_load_dwordx4 v[118:121], v[126:127], off offset:128
	v_div_scale_f32 v138, s[0:1], v137, v137, 1.0
	v_rcp_f32_e32 v139, v138
	v_mul_f32_e32 v135, v165, v134
	v_fma_f32 v140, -v138, v139, 1.0
	v_fmac_f32_e32 v139, v140, v139
	v_div_scale_f32 v140, vcc, 1.0, v137, 1.0
	v_mul_f32_e32 v141, v140, v139
	v_fma_f32 v182, -v138, v141, v140
	v_fmac_f32_e32 v141, v182, v139
	v_fma_f32 v138, -v138, v141, v140
	v_div_fmas_f32 v138, v138, v139, v141
	v_div_fixup_f32 v137, v138, v137, 1.0
	v_div_scale_f32 v138, s[0:1], v136, v136, 1.0
	v_rcp_f32_e32 v139, v138
	s_nop 0
	v_fma_f32 v140, -v138, v139, 1.0
	v_fmac_f32_e32 v139, v140, v139
	v_div_scale_f32 v140, vcc, 1.0, v136, 1.0
	v_mul_f32_e32 v141, v140, v139
	v_fma_f32 v182, -v138, v141, v140
	v_fmac_f32_e32 v141, v182, v139
	v_fma_f32 v138, -v138, v141, v140
	v_div_fmas_f32 v138, v138, v139, v141
	v_div_fixup_f32 v136, v138, v136, 1.0
	v_pk_add_f32 v[138:139], v[136:137], -1.0 op_sel_hi:[1,0]
	s_waitcnt vmcnt(0)
;     __device__ __forceinline__ void body_a(const f32x4 (&acc)[2][2][4][2], int row0, int cb0) const {
;     ...
;             for (int m = 0; m < 4; ++m) {
;                 const size_t row = (size_t)(row0 + ai * 128 + m * 16);
;                 asm volatile("" ::: "memory");
;                 float a[2][8], kv[2][8], kk[2][8]; float ss = 0.f;
; #pragma unroll
;                 for (int bj = 0; bj < 2; ++bj) {
;                     const int c = cb0 + 32 * bj;
;                     const f32x4 b0 = *(const f32x4*)(a0 + c), b1 = *(const f32x4*)(a0 + c + 4), q0 = *(const f32x4*)(k_k + c), q1 = *(const f32x4*)(k_k + c + 4);
;                     const h16x8 kh = *(const h16x8*)(C1 + row * LDC1 + 2048 + c);
; #pragma unroll
;                     for (int e = 0; e < 4; ++e) {
;                         a[bj][e] = sigmoidf_(acc[ai][bj][m][0][e] + b0[e]); a[bj][4 + e] = sigmoidf_(acc[ai][bj][m][1][e] + b1[e]);
;                         kv[bj][e] = (float)kh[e]; kv[bj][4 + e] = (float)kh[4 + e];
;                         kk[bj][e] = kv[bj][e] * q0[e]; kk[bj][4 + e] = kv[bj][4 + e] * q1[e];
;                         ss += kk[bj][e] * kk[bj][e] + kk[bj][4 + e] * kk[bj][4 + e];
;                     }
;                 }
;                 ss += __shfl_xor(ss, 16); ss += __shfl_xor(ss, 32);
;                 const float inv = 1.0f / fmaxf(sqrtf(ss), 1e-12f);
; #pragma unroll
;                 for (int bj = 0; bj < 2; ++bj) {
;                     const int c = cb0 + 32 * bj;
;                     const f32x4 p0 = *(const f32x4*)(k_a + c), p1 = *(const f32x4*)(k_a + c + 4);
;                     f32x4 ko0, ko1, ao0, ao1, bo0, bo1;
; #pragma unroll
;                     for (int e = 0; e < 4; ++e) {
;                         ko0[e] = kv[bj][e] * (1.0f + (a[bj][e] - 1.0f) * p0[e]); ko1[e] = kv[bj][4 + e] * (1.0f + (a[bj][4 + e] - 1.0f) * p1[e]);
;                         const float n0_ = kk[bj][e] * inv, n1_ = kk[bj][4 + e] * inv;
;                         ao0[e] = -n0_; ao1[e] = -n1_; bo0[e] = n0_ * a[bj][e]; bo1[e] = n1_ * a[bj][4 + e];
;                     }
;                     *(u32x4*)(C1 + row * LDC1 + 2048 + c) = pack8(ko0, ko1);
;                     *(u32x4*)(AA + row * DM + c) = pack8(ao0, ao1);
;                     *(u32x4*)(Ab + row * DM + c) = pack8(bo0, bo1);
;                 }
	v_pk_fma_f32 v[118:119], v[138:139], v[118:119], 1.0 op_sel_hi:[1,1,0]
	s_nop 0
	v_pk_mul_f32 v[118:119], v[118:119], v[180:181]
	v_pk_add_f32 v[138:139], v[178:179], 1.0 op_sel_hi:[1,0]
	v_cvt_pk_f16_f32 v118, v118, v119
	v_div_scale_f32 v119, s[0:1], v139, v139, 1.0
	v_rcp_f32_e32 v140, v119
	s_nop 0
	v_fma_f32 v141, -v119, v140, 1.0
	v_fmac_f32_e32 v140, v141, v140
	v_div_scale_f32 v141, vcc, 1.0, v139, 1.0
	v_mul_f32_e32 v178, v141, v140
	v_fma_f32 v179, -v119, v178, v141
	v_fmac_f32_e32 v178, v179, v140
	v_fma_f32 v119, -v119, v178, v141
	v_div_fmas_f32 v119, v119, v140, v178
	v_div_fixup_f32 v139, v119, v139, 1.0
	v_div_scale_f32 v119, s[0:1], v138, v138, 1.0
	v_rcp_f32_e32 v140, v119
	s_nop 0
	v_fma_f32 v141, -v119, v140, 1.0
	v_fmac_f32_e32 v140, v141, v140
	v_div_scale_f32 v141, vcc, 1.0, v138, 1.0
	v_mul_f32_e32 v178, v141, v140
	v_fma_f32 v179, -v119, v178, v141
	v_fmac_f32_e32 v178, v179, v140
	v_fma_f32 v119, -v119, v178, v141
	v_div_fmas_f32 v119, v119, v140, v178
	v_div_fixup_f32 v138, v119, v138, 1.0
	v_pk_add_f32 v[140:141], v[138:139], -1.0 op_sel_hi:[1,0]
	s_nop 0
	v_pk_fma_f32 v[120:121], v[140:141], v[120:121], 1.0 op_sel_hi:[1,1,0]
	s_nop 0
	v_pk_mul_f32 v[120:121], v[120:121], v[176:177]
	s_nop 0
	v_cvt_pk_f16_f32 v119, v120, v121
	v_pk_add_f32 v[120:121], v[174:175], 1.0 op_sel_hi:[1,0]
	s_nop 0
	v_div_scale_f32 v140, s[0:1], v121, v121, 1.0
	v_rcp_f32_e32 v141, v140
	s_nop 0
	v_fma_f32 v174, -v140, v141, 1.0
	v_fmac_f32_e32 v141, v174, v141
	v_div_scale_f32 v174, vcc, 1.0, v121, 1.0
	v_mul_f32_e32 v175, v174, v141
	v_fma_f32 v176, -v140, v175, v174
	v_fmac_f32_e32 v175, v176, v141
	v_fma_f32 v140, -v140, v175, v174
	v_div_fmas_f32 v140, v140, v141, v175
	v_div_fixup_f32 v141, v140, v121, 1.0
	v_div_scale_f32 v121, s[0:1], v120, v120, 1.0
	v_rcp_f32_e32 v140, v121
	s_nop 0
	v_fma_f32 v174, -v121, v140, 1.0
	v_fmac_f32_e32 v140, v174, v140
	v_div_scale_f32 v174, vcc, 1.0, v120, 1.0
	v_mul_f32_e32 v175, v174, v140
	v_fma_f32 v176, -v121, v175, v174
	v_fmac_f32_e32 v175, v176, v140
	v_fma_f32 v121, -v121, v175, v174
	v_div_fmas_f32 v121, v121, v140, v175
	v_div_fixup_f32 v140, v121, v120, 1.0
	v_pk_add_f32 v[120:121], v[140:141], -1.0 op_sel_hi:[1,0]
	s_nop 0
	v_pk_fma_f32 v[114:115], v[120:121], v[114:115], 1.0 op_sel_hi:[1,1,0]
	s_nop 0
	v_pk_mul_f32 v[114:115], v[114:115], v[172:173]
	s_nop 0
	v_cvt_pk_f16_f32 v120, v114, v115
	v_pk_add_f32 v[114:115], v[170:171], 1.0 op_sel_hi:[1,0]
	s_nop 0
	v_div_scale_f32 v121, s[0:1], v115, v115, 1.0
	v_rcp_f32_e32 v170, v121
	s_nop 0
	v_fma_f32 v171, -v121, v170, 1.0
	v_fmac_f32_e32 v170, v171, v170
	v_div_scale_f32 v171, vcc, 1.0, v115, 1.0
	v_mul_f32_e32 v172, v171, v170
	v_fma_f32 v173, -v121, v172, v171
	v_fmac_f32_e32 v172, v173, v170
	v_fma_f32 v121, -v121, v172, v171
	v_div_fmas_f32 v121, v121, v170, v172
	v_div_fixup_f32 v171, v121, v115, 1.0
	v_div_scale_f32 v115, s[0:1], v114, v114, 1.0
	v_rcp_f32_e32 v121, v115
	s_nop 0
	v_fma_f32 v170, -v115, v121, 1.0
	v_fmac_f32_e32 v121, v170, v121
	v_div_scale_f32 v170, vcc, 1.0, v114, 1.0
	v_mul_f32_e32 v172, v170, v121
	v_fma_f32 v173, -v115, v172, v170
	v_fmac_f32_e32 v172, v173, v121
	v_fma_f32 v115, -v115, v172, v170
	v_div_fmas_f32 v115, v115, v121, v172
	v_div_fixup_f32 v170, v115, v114, 1.0
	v_pk_add_f32 v[114:115], v[170:171], -1.0 op_sel_hi:[1,0]
	s_nop 0
	v_pk_fma_f32 v[114:115], v[114:115], v[116:117], 1.0 op_sel_hi:[1,1,0]
	v_cvt_f16_f32_e64 v116, -v159
	v_pk_mul_f32 v[114:115], v[114:115], v[168:169]
	s_nop 0
	v_cvt_pk_f16_f32 v121, v114, v115
	v_pk_mov_b32 v[114:115], v[162:163], v[166:167] op_sel:[1,0]
	global_store_dwordx4 v[122:123], v[118:121], off
	s_nop 1
	v_pk_mul_f32 v[118:119], v[114:115], v[134:135] op_sel_hi:[1,0]
	s_nop 0
	v_cvt_pk_f16_f32 v115, v118, v119
	v_pack_b32_f16 v114, v116, -v115
	v_pk_mov_b32 v[116:117], v[166:167], v[124:125] op_sel:[1,0]
	v_xor_b32_sdwa v115, s63, v115 dst_sel:DWORD dst_unused:UNUSED_PAD src0_sel:DWORD src1_sel:WORD_1
	v_pk_mul_f32 v[120:121], v[116:117], v[134:135] op_sel_hi:[1,0]
	s_nop 0
	v_cvt_pk_f16_f32 v116, v120, v121
	v_xor_b32_e32 v117, 0x8000, v116
	v_perm_b32 v115, v117, v115, s33
	v_xor_b32_sdwa v162, s63, v116 dst_sel:DWORD dst_unused:UNUSED_PAD src0_sel:DWORD src1_sel:WORD_1
	v_pk_mov_b32 v[116:117], v[124:125], v[164:165] op_sel:[1,0]
	v_cvt_f16_f32_e64 v124, -v135
	v_pk_mul_f32 v[122:123], v[116:117], v[134:135] op_sel_hi:[1,0]
	s_nop 0
	v_cvt_pk_f16_f32 v117, v122, v123
	v_xor_b32_e32 v116, 0x8000, v117
	v_xor_b32_sdwa v117, s63, v117 dst_sel:DWORD dst_unused:UNUSED_PAD src0_sel:DWORD src1_sel:WORD_1
	v_perm_b32 v116, v116, v162, s33
	v_perm_b32 v117, v124, v117, s33
	global_store_dwordx4 v[130:131], v[114:117], off offset:64
	s_nop 1
	v_pk_mov_b32 v[114:115], v[136:137], v[138:139] op_sel:[1,0]
	v_fma_mixlo_f16 v116, v136, v159, 0
	v_pk_mul_f32 v[114:115], v[114:115], v[118:119]
	s_nop 0
	v_cvt_pk_f16_f32 v115, v114, v115
	v_pack_b32_f16 v114, v116, v115
	v_pk_mov_b32 v[116:117], v[138:139], v[140:141] op_sel:[1,0]
	s_nop 0
	v_pk_mul_f32 v[116:117], v[116:117], v[120:121]
	s_nop 0
	v_cvt_pk_f16_f32 v118, v116, v117
	v_pk_mov_b32 v[116:117], v[140:141], v[170:171] op_sel:[1,0]
	v_alignbit_b32 v115, v118, v115, 16
	v_pk_mul_f32 v[116:117], v[116:117], v[122:123]
	s_nop 0
	v_cvt_pk_f16_f32 v117, v116, v117
	v_alignbit_b32 v116, v117, v118, 16
	v_lshrrev_b32_e32 v117, 16, v117
	v_fma_mixhi_f16 v117, v171, v135, 0
	global_store_dwordx4 v[132:133], v[114:117], off offset:64
	v_or_b32_e32 v162, 16, v158
	s_nop 0
	v_mad_i64_i32 v[114:115], s[0:1], v162, s5, v[160:161]
	v_lshl_add_u64 v[138:139], v[114:115], 0, s[6:7]
	global_load_dwordx4 v[130:133], v[154:155], off offset:16
	global_load_dwordx4 v[134:137], v[154:155], off
	global_load_dwordx4 v[114:117], v[156:157], off offset:16
	global_load_dwordx4 v[118:121], v[156:157], off
	v_lshl_add_u64 v[170:171], v[138:139], 0, v[152:153]
	global_load_dwordx4 v[122:125], v[170:171], off
	v_ashrrev_i32_e32 v163, 31, v162
	s_waitcnt vmcnt(4)
; __device__ __forceinline__ float sigmoidf_(float x) { return 1.0f / (1.0f + __expf(-x)); }
;     __device__ __forceinline__ void body_a(const f32x4 (&acc)[2][2][4][2], int row0, int cb0) const {
;     ...
;                 for (int bj = 0; bj < 2; ++bj) {
;                     const int c = cb0 + 32 * bj;
;                     const f32x4 b0 = *(const f32x4*)(a0 + c), b1 = *(const f32x4*)(a0 + c + 4), q0 = *(const f32x4*)(k_k + c), q1 = *(const f32x4*)(k_k + c + 4);
;                     const h16x8 kh = *(const h16x8*)(C1 + row * LDC1 + 2048 + c);
; #pragma unroll
;                     for (int e = 0; e < 4; ++e) {
;                         a[bj][e] = sigmoidf_(acc[ai][bj][m][0][e] + b0[e]); a[bj][4 + e] = sigmoidf_(acc[ai][bj][m][1][e] + b1[e]);
;                         kv[bj][e] = (float)kh[e]; kv[bj][4 + e] = (float)kh[4 + e];
;                         kk[bj][e] = kv[bj][e] * q0[e]; kk[bj][4 + e] = kv[bj][4 + e] * q1[e];
;                         ss += kk[bj][e] * kk[bj][e] + kk[bj][4 + e] * kk[bj][4 + e];
;                     }
;                 }
;                 ss += __shfl_xor(ss, 16); ss += __shfl_xor(ss, 32);
;                 const float inv = 1.0f / fmaxf(sqrtf(ss), 1e-12f);
; #pragma unroll
;                 for (int bj = 0; bj < 2; ++bj) {
;                     const int c = cb0 + 32 * bj;
;                     const f32x4 p0 = *(const f32x4*)(k_a + c), p1 = *(const f32x4*)(k_a + c + 4);
;                     f32x4 ko0, ko1, ao0, ao1, bo0, bo1;
; #pragma unroll
;                     for (int e = 0; e < 4; ++e) {
;                         ko0[e] = kv[bj][e] * (1.0f + (a[bj][e] - 1.0f) * p0[e]); ko1[e] = kv[bj][4 + e] * (1.0f + (a[bj][4 + e] - 1.0f) * p1[e]);
;                         const float n0_ = kk[bj][e] * inv, n1_ = kk[bj][4 + e] * inv;
;                         ao0[e] = -n0_; ao1[e] = -n1_; bo0[e] = n0_ * a[bj][e]; bo1[e] = n1_ * a[bj][4 + e];
;                     }
;                     *(u32x4*)(C1 + row * LDC1 + 2048 + c) = pack8(ko0, ko1);
;                     *(u32x4*)(AA + row * DM + c) = pack8(ao0, ao1);
;                     *(u32x4*)(Ab + row * DM + c) = pack8(bo0, bo1);
;                 }
	v_add_f32_e32 v106, v106, v130
	v_mul_f32_e32 v106, 0xbfb8aa3b, v106
	v_exp_f32_e32 v178, v106
	s_waitcnt vmcnt(3)
	v_add_f32_e32 v106, v111, v135
	v_mul_f32_e32 v106, 0xbfb8aa3b, v106
	v_exp_f32_e32 v181, v106
	v_add_f32_e32 v106, v107, v131
	v_mul_f32_e32 v106, 0xbfb8aa3b, v106
	v_exp_f32_e32 v179, v106
	v_add_f32_e32 v106, v112, v136
	v_mul_f32_e32 v106, 0xbfb8aa3b, v106
	v_exp_f32_e32 v182, v106
	v_add_f32_e32 v106, v108, v132
	v_mul_f32_e32 v106, 0xbfb8aa3b, v106
	v_exp_f32_e32 v172, v106
	v_add_f32_e32 v106, v113, v137
	v_mul_f32_e32 v106, 0xbfb8aa3b, v106
	v_exp_f32_e32 v183, v106
	v_add_f32_e32 v106, v109, v133
	v_add_f32_e32 v110, v110, v134
	v_mul_f32_e32 v106, 0xbfb8aa3b, v106
	v_mul_f32_e32 v110, 0xbfb8aa3b, v110
	v_exp_f32_e32 v173, v106
	v_lshl_add_u64 v[106:107], v[138:139], 0, v[128:129]
	v_exp_f32_e32 v180, v110
	global_load_dwordx4 v[110:113], v[154:155], off offset:144
	global_load_dwordx4 v[130:133], v[154:155], off offset:128
	global_load_dwordx4 v[174:177], v[156:157], off offset:144
	global_load_dwordx4 v[184:187], v[156:157], off offset:128
	global_load_dwordx4 v[188:191], v[106:107], off
	v_pk_add_f32 v[182:183], v[182:183], 1.0 op_sel_hi:[1,0]
	v_pk_add_f32 v[180:181], v[180:181], 1.0 op_sel_hi:[1,0]
	s_waitcnt vmcnt(4)
	v_add_f32_e32 v98, v98, v110
	v_mul_f32_e32 v98, 0xbfb8aa3b, v98
	v_exp_f32_e32 v138, v98
	s_waitcnt vmcnt(3)
	v_add_f32_e32 v98, v103, v131
	s_waitcnt vmcnt(0)
	v_cvt_f32_f16_e32 v136, v190
	v_cvt_f32_f16_sdwa v137, v190 dst_sel:DWORD dst_unused:UNUSED_PAD src0_sel:WORD_1
	v_cvt_f32_f16_e32 v166, v188
	v_cvt_f32_f16_sdwa v167, v188 dst_sel:DWORD dst_unused:UNUSED_PAD src0_sel:WORD_1
	v_mul_f32_e32 v98, 0xbfb8aa3b, v98
	v_exp_f32_e32 v169, v98
	v_add_f32_e32 v98, v99, v111
	v_mul_f32_e32 v98, 0xbfb8aa3b, v98
	v_pk_mul_f32 v[108:109], v[174:175], v[136:137]
	v_exp_f32_e32 v139, v98
	v_pk_mul_f32 v[110:111], v[184:185], v[166:167]
	v_pk_mul_f32 v[98:99], v[108:109], v[108:109]
	v_cvt_f32_f16_e32 v140, v189
	v_pk_fma_f32 v[174:175], v[110:111], v[110:111], v[98:99]
	v_add_f32_e32 v98, v104, v132
	v_mul_f32_e32 v98, 0xbfb8aa3b, v98
	v_exp_f32_e32 v164, v98
	v_add_f32_e32 v98, v100, v112
	v_mul_f32_e32 v98, 0xbfb8aa3b, v98
	v_exp_f32_e32 v134, v98
	v_add_f32_e32 v98, v105, v133
	v_cvt_f32_f16_e32 v132, v191
	v_cvt_f32_f16_sdwa v133, v191 dst_sel:DWORD dst_unused:UNUSED_PAD src0_sel:WORD_1
	v_cvt_f32_f16_sdwa v141, v189 dst_sel:DWORD dst_unused:UNUSED_PAD src0_sel:WORD_1
	v_mul_f32_e32 v98, 0xbfb8aa3b, v98
	v_exp_f32_e32 v165, v98
	v_add_f32_e32 v98, v101, v113
	v_add_f32_e32 v102, v102, v130
	v_mul_f32_e32 v98, 0xbfb8aa3b, v98
	v_pk_mul_f32 v[112:113], v[176:177], v[132:133]
	v_mul_f32_e32 v102, 0xbfb8aa3b, v102
	v_exp_f32_e32 v135, v98
	v_pk_mul_f32 v[130:131], v[186:187], v[140:141]
	v_pk_mul_f32 v[98:99], v[112:113], v[112:113]
	v_exp_f32_e32 v168, v102
	v_pk_fma_f32 v[176:177], v[130:131], v[130:131], v[98:99]
	global_load_dwordx4 v[98:101], v[126:127], off offset:16
	global_load_dwordx4 v[102:105], v[126:127], off
	v_cvt_f32_f16_e32 v184, v122
	v_cvt_f32_f16_sdwa v185, v122 dst_sel:DWORD dst_unused:UNUSED_PAD src0_sel:WORD_1
	v_div_scale_f32 v122, s[0:1], v181, v181, 1.0
	v_rcp_f32_e32 v159, v122
	s_nop 0
	v_fma_f32 v186, -v122, v159, 1.0
	v_fmac_f32_e32 v159, v186, v159
	v_div_scale_f32 v186, vcc, 1.0, v181, 1.0
	v_mul_f32_e32 v187, v186, v159
	v_fma_f32 v188, -v122, v187, v186
	v_fmac_f32_e32 v187, v188, v159
	v_fma_f32 v122, -v122, v187, v186
	v_div_fmas_f32 v122, v122, v159, v187
	v_div_fixup_f32 v181, v122, v181, 1.0
	v_div_scale_f32 v122, s[0:1], v180, v180, 1.0
	v_rcp_f32_e32 v159, v122
	s_nop 0
	v_fma_f32 v186, -v122, v159, 1.0
	v_fmac_f32_e32 v159, v186, v159
	v_div_scale_f32 v186, vcc, 1.0, v180, 1.0
	v_mul_f32_e32 v187, v186, v159
	v_fma_f32 v188, -v122, v187, v186
	v_fmac_f32_e32 v187, v188, v159
	v_fma_f32 v122, -v122, v187, v186
	v_div_fmas_f32 v122, v122, v159, v187
	v_div_fixup_f32 v180, v122, v180, 1.0
	v_pk_add_f32 v[186:187], v[180:181], -1.0 op_sel_hi:[1,0]
	v_cvt_f32_f16_e32 v122, v123
	v_cvt_f32_f16_sdwa v123, v123 dst_sel:DWORD dst_unused:UNUSED_PAD src0_sel:WORD_1
	s_waitcnt vmcnt(0)
	v_pk_fma_f32 v[102:103], v[186:187], v[102:103], 1.0 op_sel_hi:[1,1,0]
	s_nop 0
	v_pk_mul_f32 v[102:103], v[102:103], v[184:185]
	s_nop 0
	v_cvt_pk_f16_f32 v102, v102, v103
	v_div_scale_f32 v103, s[0:1], v183, v183, 1.0
	v_rcp_f32_e32 v159, v103
	s_nop 0
	v_fma_f32 v186, -v103, v159, 1.0
	v_fmac_f32_e32 v159, v186, v159
	v_div_scale_f32 v186, vcc, 1.0, v183, 1.0
	v_mul_f32_e32 v187, v186, v159
	v_fma_f32 v188, -v103, v187, v186
	v_fmac_f32_e32 v187, v188, v159
	v_fma_f32 v103, -v103, v187, v186
	v_div_fmas_f32 v103, v103, v159, v187
	v_div_fixup_f32 v183, v103, v183, 1.0
	v_div_scale_f32 v103, s[0:1], v182, v182, 1.0
	v_rcp_f32_e32 v159, v103
	s_nop 0
	v_fma_f32 v186, -v103, v159, 1.0
	v_fmac_f32_e32 v159, v186, v159
	v_div_scale_f32 v186, vcc, 1.0, v182, 1.0
	v_mul_f32_e32 v187, v186, v159
	v_fma_f32 v188, -v103, v187, v186
	v_fmac_f32_e32 v187, v188, v159
	v_fma_f32 v103, -v103, v187, v186
	v_div_fmas_f32 v103, v103, v159, v187
	v_div_fixup_f32 v182, v103, v182, 1.0
	v_pk_add_f32 v[186:187], v[182:183], -1.0 op_sel_hi:[1,0]
	s_nop 0
	v_pk_fma_f32 v[104:105], v[186:187], v[104:105], 1.0 op_sel_hi:[1,1,0]
	v_cvt_f32_f16_e32 v186, v124
	v_pk_mul_f32 v[104:105], v[104:105], v[122:123]
	v_cvt_f32_f16_sdwa v187, v124 dst_sel:DWORD dst_unused:UNUSED_PAD src0_sel:WORD_1
	v_cvt_pk_f16_f32 v103, v104, v105
	v_pk_add_f32 v[104:105], v[178:179], 1.0 op_sel_hi:[1,0]
	s_nop 0
	v_div_scale_f32 v124, s[0:1], v105, v105, 1.0
	v_rcp_f32_e32 v159, v124
	s_nop 0
	v_fma_f32 v178, -v124, v159, 1.0
; __device__ __forceinline__ float sigmoidf_(float x) { return 1.0f / (1.0f + __expf(-x)); }
;     __device__ __forceinline__ void body_a(const f32x4 (&acc)[2][2][4][2], int row0, int cb0) const {
;     ...
;                         a[bj][e] = sigmoidf_(acc[ai][bj][m][0][e] + b0[e]); a[bj][4 + e] = sigmoidf_(acc[ai][bj][m][1][e] + b1[e]);
;                         kv[bj][e] = (float)kh[e]; kv[bj][4 + e] = (float)kh[4 + e];
;                         kk[bj][e] = kv[bj][e] * q0[e]; kk[bj][4 + e] = kv[bj][4 + e] * q1[e];
;                         ss += kk[bj][e] * kk[bj][e] + kk[bj][4 + e] * kk[bj][4 + e];
;                     }
;                 }
;                 ss += __shfl_xor(ss, 16); ss += __shfl_xor(ss, 32);
;                 const float inv = 1.0f / fmaxf(sqrtf(ss), 1e-12f);
; #pragma unroll
;                 for (int bj = 0; bj < 2; ++bj) {
;                     const int c = cb0 + 32 * bj;
;                     const f32x4 p0 = *(const f32x4*)(k_a + c), p1 = *(const f32x4*)(k_a + c + 4);
;                     f32x4 ko0, ko1, ao0, ao1, bo0, bo1;
; #pragma unroll
;                     for (int e = 0; e < 4; ++e) {
;                         ko0[e] = kv[bj][e] * (1.0f + (a[bj][e] - 1.0f) * p0[e]); ko1[e] = kv[bj][4 + e] * (1.0f + (a[bj][4 + e] - 1.0f) * p1[e]);
;                         const float n0_ = kk[bj][e] * inv, n1_ = kk[bj][4 + e] * inv;
;                         ao0[e] = -n0_; ao1[e] = -n1_; bo0[e] = n0_ * a[bj][e]; bo1[e] = n1_ * a[bj][4 + e];
;                     }
;                     *(u32x4*)(C1 + row * LDC1 + 2048 + c) = pack8(ko0, ko1);
;                     *(u32x4*)(AA + row * DM + c) = pack8(ao0, ao1);
;                     *(u32x4*)(Ab + row * DM + c) = pack8(bo0, bo1);
	v_fmac_f32_e32 v159, v178, v159
	v_div_scale_f32 v178, vcc, 1.0, v105, 1.0
	v_mul_f32_e32 v179, v178, v159
	v_fma_f32 v188, -v124, v179, v178
	v_fmac_f32_e32 v179, v188, v159
	v_fma_f32 v124, -v124, v179, v178
	v_div_fmas_f32 v124, v124, v159, v179
	v_div_fixup_f32 v179, v124, v105, 1.0
	v_div_scale_f32 v105, s[0:1], v104, v104, 1.0
	v_rcp_f32_e32 v124, v105
	s_nop 0
	v_fma_f32 v159, -v105, v124, 1.0
	v_fmac_f32_e32 v124, v159, v124
	v_div_scale_f32 v159, vcc, 1.0, v104, 1.0
	v_mul_f32_e32 v178, v159, v124
	v_fma_f32 v188, -v105, v178, v159
	v_fmac_f32_e32 v178, v188, v124
	v_fma_f32 v105, -v105, v178, v159
	v_div_fmas_f32 v105, v105, v124, v178
	v_div_fixup_f32 v178, v105, v104, 1.0
	v_pk_add_f32 v[104:105], v[178:179], -1.0 op_sel_hi:[1,0]
	v_cvt_f32_f16_e32 v124, v125
	v_pk_fma_f32 v[98:99], v[104:105], v[98:99], 1.0 op_sel_hi:[1,1,0]
	v_cvt_f32_f16_sdwa v125, v125 dst_sel:DWORD dst_unused:UNUSED_PAD src0_sel:WORD_1
	v_pk_mul_f32 v[98:99], v[98:99], v[186:187]
	v_pk_mul_f32 v[116:117], v[116:117], v[124:125]
	v_cvt_pk_f16_f32 v104, v98, v99
	v_pk_add_f32 v[98:99], v[172:173], 1.0 op_sel_hi:[1,0]
	s_nop 0
	v_div_scale_f32 v105, s[0:1], v99, v99, 1.0
	v_rcp_f32_e32 v159, v105
	s_nop 0
	v_fma_f32 v172, -v105, v159, 1.0
	v_fmac_f32_e32 v159, v172, v159
	v_div_scale_f32 v172, vcc, 1.0, v99, 1.0
	v_mul_f32_e32 v173, v172, v159
	v_fma_f32 v188, -v105, v173, v172
	v_fmac_f32_e32 v173, v188, v159
	v_fma_f32 v105, -v105, v173, v172
	v_div_fmas_f32 v105, v105, v159, v173
	v_div_fixup_f32 v99, v105, v99, 1.0
	v_div_scale_f32 v105, s[0:1], v98, v98, 1.0
	v_rcp_f32_e32 v159, v105
	s_nop 0
	v_fma_f32 v172, -v105, v159, 1.0
	v_fmac_f32_e32 v159, v172, v159
	v_div_scale_f32 v172, vcc, 1.0, v98, 1.0
	v_mul_f32_e32 v173, v172, v159
	v_fma_f32 v188, -v105, v173, v172
	v_fmac_f32_e32 v173, v188, v159
	v_fma_f32 v105, -v105, v173, v172
	v_div_fmas_f32 v105, v105, v159, v173
	v_div_fixup_f32 v98, v105, v98, 1.0
	v_pk_add_f32 v[172:173], v[98:99], -1.0 op_sel_hi:[1,0]
	s_nop 0
	v_pk_fma_f32 v[100:101], v[172:173], v[100:101], 1.0 op_sel_hi:[1,1,0]
	s_nop 0
	v_pk_mul_f32 v[100:101], v[100:101], v[124:125]
	v_lshlrev_b64 v[124:125], 12, v[162:163]
	v_cvt_pk_f16_f32 v105, v100, v101
	global_store_dwordx4 v[170:171], v[102:105], off
	v_pk_mul_f32 v[100:101], v[118:119], v[184:185]
	v_pk_mul_f32 v[118:119], v[116:117], v[116:117]
	v_pk_mul_f32 v[104:105], v[114:115], v[186:187]
	v_pk_mul_f32 v[102:103], v[120:121], v[122:123]
	v_pk_mul_f32 v[114:115], v[104:105], v[104:105]
	v_pk_fma_f32 v[118:119], v[102:103], v[102:103], v[118:119]
	v_pk_fma_f32 v[114:115], v[100:101], v[100:101], v[114:115]
	s_nop 0
	v_add_f32_e32 v114, v114, v115
	v_add_f32_e32 v114, v118, v114
	v_add_f32_e32 v114, v119, v114
	v_add_f32_e32 v114, v114, v174
	v_add_f32_e32 v114, v175, v114
	v_add_f32_e32 v114, v176, v114
	v_add_f32_e32 v114, v177, v114
	ds_bpermute_b32 v115, v206, v114
	s_waitcnt lgkmcnt(0)
	v_add_f32_e32 v114, v114, v115
	ds_bpermute_b32 v115, v207, v114
	s_waitcnt lgkmcnt(0)
	v_add_f32_e32 v114, v114, v115
	v_cmp_gt_f32_e32 vcc, s4, v114
	v_mul_f32_e32 v115, 0x4f800000, v114
	s_nop 0
	v_cndmask_b32_e32 v114, v114, v115, vcc
	v_sqrt_f32_e32 v115, v114
	s_nop 0
	v_add_u32_e32 v118, -1, v115
	v_fma_f32 v119, -v118, v115, v114
	v_cmp_ge_f32_e64 s[0:1], 0, v119
	v_add_u32_e32 v119, 1, v115
	s_nop 0
	v_cndmask_b32_e64 v118, v115, v118, s[0:1]
	v_fma_f32 v115, -v119, v115, v114
	v_cmp_lt_f32_e64 s[0:1], 0, v115
	s_nop 1
	v_cndmask_b32_e64 v115, v118, v119, s[0:1]
	v_mul_f32_e32 v118, 0x37800000, v115
	v_cndmask_b32_e32 v115, v115, v118, vcc
	v_cmp_class_f32_e32 vcc, v114, v244
	s_nop 1
	v_cndmask_b32_e32 v114, v115, v114, vcc
	v_max_f32_e32 v114, 0x2b8cbccc, v114
	v_div_scale_f32 v115, s[0:1], v114, v114, 1.0
	v_rcp_f32_e32 v118, v115
	s_nop 0
	v_fma_f32 v119, -v115, v118, 1.0
	v_fmac_f32_e32 v118, v119, v118
	v_div_scale_f32 v119, vcc, 1.0, v114, 1.0
	v_mul_f32_e32 v120, v119, v118
	v_fma_f32 v121, -v115, v120, v119
	v_fmac_f32_e32 v120, v121, v118
	v_fma_f32 v115, -v115, v120, v119
	v_div_fmas_f32 v115, v115, v118, v120
	v_div_fixup_f32 v118, v115, v114, 1.0
	v_pk_mul_f32 v[122:123], v[102:103], v[118:119] op_sel_hi:[1,0]
	v_pk_mul_f32 v[120:121], v[100:101], v[118:119] op_sel_hi:[1,0]
	v_cvt_pk_f16_f32 v101, v122, v123
	v_cvt_pk_f16_f32 v100, v120, v121
	v_xor_b32_e32 v102, 0x8000, v101
	v_xor_b32_sdwa v101, s63, v101 dst_sel:DWORD dst_unused:UNUSED_PAD src0_sel:DWORD src1_sel:WORD_1
	v_pk_mul_f32 v[104:105], v[104:105], v[118:119] op_sel_hi:[1,0]
	v_pk_mul_f32 v[116:117], v[116:117], v[118:119] op_sel_hi:[1,0]
	v_perm_b32 v101, v101, v102, s33
	v_xor_b32_e32 v102, 0x8000, v100
	v_xor_b32_sdwa v100, s63, v100 dst_sel:DWORD dst_unused:UNUSED_PAD src0_sel:DWORD src1_sel:WORD_1
	v_perm_b32 v100, v100, v102, s33
	v_pk_add_f32 v[102:103], v[104:105], 0 neg_lo:[1,1] neg_hi:[1,1]
	v_pk_add_f32 v[114:115], v[116:117], 0 neg_lo:[1,1] neg_hi:[1,1]
	v_cvt_pk_f16_f32 v102, v102, v103
	v_cvt_pk_f16_f32 v103, v114, v115
	v_lshl_add_u64 v[114:115], s[10:11], 0, v[124:125]
	v_lshl_add_u64 v[114:115], v[114:115], 0, v[152:153]
	global_store_dwordx4 v[114:115], v[100:103], off
	v_fma_mixlo_f16 v119, v180, v120, 0
	v_mul_f32_e32 v159, v110, v118
	v_pk_mov_b32 v[100:101], v[180:181], v[182:183] op_sel:[1,0]
	v_pk_mov_b32 v[102:103], v[120:121], v[122:123] op_sel:[1,0]
	v_pk_mov_b32 v[120:121], v[122:123], v[104:105] op_sel:[1,0]
	v_pk_mul_f32 v[100:101], v[100:101], v[102:103]
	v_pk_mov_b32 v[102:103], v[182:183], v[178:179] op_sel:[1,0]
	v_cvt_pk_f16_f32 v101, v100, v101
	v_pk_mul_f32 v[102:103], v[102:103], v[120:121]
	v_pack_b32_f16 v100, v119, v101
	v_cvt_pk_f16_f32 v119, v102, v103
;     __device__ __forceinline__ void body_a(const f32x4 (&acc)[2][2][4][2], int row0, int cb0) const {
;     ...
;                 for (int bj = 0; bj < 2; ++bj) {
;                     const int c = cb0 + 32 * bj;
;                     const f32x4 p0 = *(const f32x4*)(k_a + c), p1 = *(const f32x4*)(k_a + c + 4);
;                     f32x4 ko0, ko1, ao0, ao1, bo0, bo1;
; #pragma unroll
;                     for (int e = 0; e < 4; ++e) {
;                         ko0[e] = kv[bj][e] * (1.0f + (a[bj][e] - 1.0f) * p0[e]); ko1[e] = kv[bj][4 + e] * (1.0f + (a[bj][4 + e] - 1.0f) * p1[e]);
;                         const float n0_ = kk[bj][e] * inv, n1_ = kk[bj][4 + e] * inv;
;                         ao0[e] = -n0_; ao1[e] = -n1_; bo0[e] = n0_ * a[bj][e]; bo1[e] = n1_ * a[bj][4 + e];
;                     }
;                     *(u32x4*)(C1 + row * LDC1 + 2048 + c) = pack8(ko0, ko1);
;                     *(u32x4*)(AA + row * DM + c) = pack8(ao0, ao1);
;                     *(u32x4*)(Ab + row * DM + c) = pack8(bo0, bo1);
	v_pk_mov_b32 v[102:103], v[178:179], v[98:99] op_sel:[1,0]
	v_pk_mov_b32 v[104:105], v[104:105], v[116:117] op_sel:[1,0]
	v_alignbit_b32 v101, v119, v101, 16
	v_pk_mul_f32 v[102:103], v[102:103], v[104:105]
	v_pk_add_f32 v[120:121], v[168:169], 1.0 op_sel_hi:[1,0]
	v_cvt_pk_f16_f32 v98, v102, v103
	v_lshrrev_b32_e32 v103, 16, v98
	v_alignbit_b32 v102, v98, v119, 16
	v_fma_mixhi_f16 v103, v99, v117, 0
	v_lshl_add_u64 v[98:99], s[2:3], 0, v[124:125]
	v_lshl_add_u64 v[116:117], v[98:99], 0, v[152:153]
	global_store_dwordx4 v[116:117], v[100:103], off
	global_load_dwordx4 v[98:101], v[126:127], off offset:144
	s_nop 0
	global_load_dwordx4 v[102:105], v[126:127], off offset:128
	v_div_scale_f32 v122, s[0:1], v121, v121, 1.0
	v_rcp_f32_e32 v123, v122
	v_mul_f32_e32 v119, v113, v118
	v_fma_f32 v124, -v122, v123, 1.0
	v_fmac_f32_e32 v123, v124, v123
	v_div_scale_f32 v124, vcc, 1.0, v121, 1.0
	v_mul_f32_e32 v125, v124, v123
	v_fma_f32 v162, -v122, v125, v124
	v_fmac_f32_e32 v125, v162, v123
	v_fma_f32 v122, -v122, v125, v124
	v_div_fmas_f32 v122, v122, v123, v125
	v_div_fixup_f32 v121, v122, v121, 1.0
	v_div_scale_f32 v122, s[0:1], v120, v120, 1.0
	v_rcp_f32_e32 v123, v122
	s_nop 0
	v_fma_f32 v124, -v122, v123, 1.0
	v_fmac_f32_e32 v123, v124, v123
	v_div_scale_f32 v124, vcc, 1.0, v120, 1.0
	v_mul_f32_e32 v125, v124, v123
	v_fma_f32 v162, -v122, v125, v124
	v_fmac_f32_e32 v125, v162, v123
	v_fma_f32 v122, -v122, v125, v124
	v_div_fmas_f32 v122, v122, v123, v125
	v_div_fixup_f32 v120, v122, v120, 1.0
	v_pk_add_f32 v[122:123], v[120:121], -1.0 op_sel_hi:[1,0]
	s_waitcnt vmcnt(0)
	v_pk_fma_f32 v[102:103], v[122:123], v[102:103], 1.0 op_sel_hi:[1,1,0]
	s_nop 0
	v_pk_mul_f32 v[102:103], v[102:103], v[166:167]
	v_pk_add_f32 v[122:123], v[164:165], 1.0 op_sel_hi:[1,0]
	v_cvt_pk_f16_f32 v102, v102, v103
	v_div_scale_f32 v103, s[0:1], v123, v123, 1.0
	v_rcp_f32_e32 v124, v103
	s_nop 0
	v_fma_f32 v125, -v103, v124, 1.0
	v_fmac_f32_e32 v124, v125, v124
	v_div_scale_f32 v125, vcc, 1.0, v123, 1.0
	v_mul_f32_e32 v162, v125, v124
	v_fma_f32 v163, -v103, v162, v125
	v_fmac_f32_e32 v162, v163, v124
	v_fma_f32 v103, -v103, v162, v125
	v_div_fmas_f32 v103, v103, v124, v162
	v_div_fixup_f32 v123, v103, v123, 1.0
	v_div_scale_f32 v103, s[0:1], v122, v122, 1.0
	v_rcp_f32_e32 v124, v103
	s_nop 0
	v_fma_f32 v125, -v103, v124, 1.0
	v_fmac_f32_e32 v124, v125, v124
	v_div_scale_f32 v125, vcc, 1.0, v122, 1.0
	v_mul_f32_e32 v162, v125, v124
	v_fma_f32 v163, -v103, v162, v125
	v_fmac_f32_e32 v162, v163, v124
	v_fma_f32 v103, -v103, v162, v125
	v_div_fmas_f32 v103, v103, v124, v162
	v_div_fixup_f32 v122, v103, v122, 1.0
	v_pk_add_f32 v[124:125], v[122:123], -1.0 op_sel_hi:[1,0]
	s_nop 0
	v_pk_fma_f32 v[104:105], v[124:125], v[104:105], 1.0 op_sel_hi:[1,1,0]
	s_nop 0
	v_pk_mul_f32 v[104:105], v[104:105], v[140:141]
	s_nop 0
	v_cvt_pk_f16_f32 v103, v104, v105
	v_pk_add_f32 v[104:105], v[138:139], 1.0 op_sel_hi:[1,0]
	s_nop 0
	v_div_scale_f32 v124, s[0:1], v105, v105, 1.0
	v_rcp_f32_e32 v125, v124
	s_nop 0
	v_fma_f32 v138, -v124, v125, 1.0
	v_fmac_f32_e32 v125, v138, v125
	v_div_scale_f32 v138, vcc, 1.0, v105, 1.0
	v_mul_f32_e32 v139, v138, v125
	v_fma_f32 v140, -v124, v139, v138
	v_fmac_f32_e32 v139, v140, v125
	v_fma_f32 v124, -v124, v139, v138
	v_div_fmas_f32 v124, v124, v125, v139
	v_div_fixup_f32 v125, v124, v105, 1.0
	v_div_scale_f32 v105, s[0:1], v104, v104, 1.0
	v_rcp_f32_e32 v124, v105
	s_nop 0
	v_fma_f32 v138, -v105, v124, 1.0
	v_fmac_f32_e32 v124, v138, v124
	v_div_scale_f32 v138, vcc, 1.0, v104, 1.0
	v_mul_f32_e32 v139, v138, v124
	v_fma_f32 v140, -v105, v139, v138
	v_fmac_f32_e32 v139, v140, v124
	v_fma_f32 v105, -v105, v139, v138
	v_div_fmas_f32 v105, v105, v124, v139
	v_div_fixup_f32 v124, v105, v104, 1.0
	v_pk_add_f32 v[104:105], v[124:125], -1.0 op_sel_hi:[1,0]
	s_nop 0
	v_pk_fma_f32 v[98:99], v[104:105], v[98:99], 1.0 op_sel_hi:[1,1,0]
	s_nop 0
	v_pk_mul_f32 v[98:99], v[98:99], v[136:137]
	s_nop 0
	v_cvt_pk_f16_f32 v104, v98, v99
	v_pk_add_f32 v[98:99], v[134:135], 1.0 op_sel_hi:[1,0]
	s_nop 0
	v_div_scale_f32 v105, s[0:1], v99, v99, 1.0
	v_rcp_f32_e32 v134, v105
	s_nop 0
	v_fma_f32 v135, -v105, v134, 1.0
	v_fmac_f32_e32 v134, v135, v134
	v_div_scale_f32 v135, vcc, 1.0, v99, 1.0
	v_mul_f32_e32 v136, v135, v134
	v_fma_f32 v137, -v105, v136, v135
	v_fmac_f32_e32 v136, v137, v134
	v_fma_f32 v105, -v105, v136, v135
	v_div_fmas_f32 v105, v105, v134, v136
	v_div_fixup_f32 v135, v105, v99, 1.0
	v_div_scale_f32 v99, s[0:1], v98, v98, 1.0
	v_rcp_f32_e32 v105, v99
	s_nop 0
	v_fma_f32 v134, -v99, v105, 1.0
	v_fmac_f32_e32 v105, v134, v105
	v_div_scale_f32 v134, vcc, 1.0, v98, 1.0
	v_mul_f32_e32 v136, v134, v105
	v_fma_f32 v137, -v99, v136, v134
	v_fmac_f32_e32 v136, v137, v105
	v_fma_f32 v99, -v99, v136, v134
	v_div_fmas_f32 v99, v99, v105, v136
	v_div_fixup_f32 v134, v99, v98, 1.0
	v_pk_add_f32 v[98:99], v[134:135], -1.0 op_sel_hi:[1,0]
	s_nop 0
	v_pk_fma_f32 v[98:99], v[98:99], v[100:101], 1.0 op_sel_hi:[1,1,0]
	v_cvt_f16_f32_e64 v100, -v159
	v_pk_mul_f32 v[98:99], v[98:99], v[132:133]
	s_nop 0
	v_cvt_pk_f16_f32 v105, v98, v99
	v_pk_mov_b32 v[98:99], v[110:111], v[130:131] op_sel:[1,0]
	global_store_dwordx4 v[106:107], v[102:105], off
	s_nop 1
	v_pk_mul_f32 v[102:103], v[98:99], v[118:119] op_sel_hi:[1,0]
	s_nop 0
	v_cvt_pk_f16_f32 v99, v102, v103
	v_pack_b32_f16 v98, v100, -v99
	v_pk_mov_b32 v[100:101], v[130:131], v[108:109] op_sel:[1,0]
	v_xor_b32_sdwa v99, s63, v99 dst_sel:DWORD dst_unused:UNUSED_PAD src0_sel:DWORD src1_sel:WORD_1
	v_pk_mul_f32 v[104:105], v[100:101], v[118:119] op_sel_hi:[1,0]
	s_nop 0
	v_cvt_pk_f16_f32 v100, v104, v105
	v_xor_b32_e32 v101, 0x8000, v100
; __device__ __forceinline__ float sigmoidf_(float x) { return 1.0f / (1.0f + __expf(-x)); }
;     __device__ __forceinline__ void body_a(const f32x4 (&acc)[2][2][4][2], int row0, int cb0) const {
;     ...
;                 const size_t row = (size_t)(row0 + ai * 128 + m * 16);
;                 asm volatile("" ::: "memory");
;                 float a[2][8], kv[2][8], kk[2][8]; float ss = 0.f;
; #pragma unroll
;                 for (int bj = 0; bj < 2; ++bj) {
;                     const int c = cb0 + 32 * bj;
;                     const f32x4 b0 = *(const f32x4*)(a0 + c), b1 = *(const f32x4*)(a0 + c + 4), q0 = *(const f32x4*)(k_k + c), q1 = *(const f32x4*)(k_k + c + 4);
;                     const h16x8 kh = *(const h16x8*)(C1 + row * LDC1 + 2048 + c);
; #pragma unroll
;                     for (int e = 0; e < 4; ++e) {
;                         a[bj][e] = sigmoidf_(acc[ai][bj][m][0][e] + b0[e]); a[bj][4 + e] = sigmoidf_(acc[ai][bj][m][1][e] + b1[e]);
;                         kv[bj][e] = (float)kh[e]; kv[bj][4 + e] = (float)kh[4 + e];
;                         kk[bj][e] = kv[bj][e] * q0[e]; kk[bj][4 + e] = kv[bj][4 + e] * q1[e];
;                         ss += kk[bj][e] * kk[bj][e] + kk[bj][4 + e] * kk[bj][4 + e];
;     ...
;                         ko0[e] = kv[bj][e] * (1.0f + (a[bj][e] - 1.0f) * p0[e]); ko1[e] = kv[bj][4 + e] * (1.0f + (a[bj][4 + e] - 1.0f) * p1[e]);
;                         const float n0_ = kk[bj][e] * inv, n1_ = kk[bj][4 + e] * inv;
;                         ao0[e] = -n0_; ao1[e] = -n1_; bo0[e] = n0_ * a[bj][e]; bo1[e] = n1_ * a[bj][4 + e];
;                     }
;                     *(u32x4*)(C1 + row * LDC1 + 2048 + c) = pack8(ko0, ko1);
;                     *(u32x4*)(AA + row * DM + c) = pack8(ao0, ao1);
;                     *(u32x4*)(Ab + row * DM + c) = pack8(bo0, bo1);
	v_perm_b32 v99, v101, v99, s33
	v_xor_b32_sdwa v110, s63, v100 dst_sel:DWORD dst_unused:UNUSED_PAD src0_sel:DWORD src1_sel:WORD_1
	v_pk_mov_b32 v[100:101], v[108:109], v[112:113] op_sel:[1,0]
	v_cvt_f16_f32_e64 v108, -v119
	v_pk_mul_f32 v[106:107], v[100:101], v[118:119] op_sel_hi:[1,0]
	s_nop 0
	v_cvt_pk_f16_f32 v101, v106, v107
	v_xor_b32_e32 v100, 0x8000, v101
	v_xor_b32_sdwa v101, s63, v101 dst_sel:DWORD dst_unused:UNUSED_PAD src0_sel:DWORD src1_sel:WORD_1
	v_perm_b32 v100, v100, v110, s33
	v_perm_b32 v101, v108, v101, s33
	global_store_dwordx4 v[114:115], v[98:101], off offset:64
	s_nop 1
	v_pk_mov_b32 v[98:99], v[120:121], v[122:123] op_sel:[1,0]
	v_fma_mixlo_f16 v100, v120, v159, 0
	v_pk_mul_f32 v[98:99], v[98:99], v[102:103]
	s_nop 0
	v_cvt_pk_f16_f32 v99, v98, v99
	v_pack_b32_f16 v98, v100, v99
	v_pk_mov_b32 v[100:101], v[122:123], v[124:125] op_sel:[1,0]
	s_nop 0
	v_pk_mul_f32 v[100:101], v[100:101], v[104:105]
	s_nop 0
	v_cvt_pk_f16_f32 v102, v100, v101
	v_pk_mov_b32 v[100:101], v[124:125], v[134:135] op_sel:[1,0]
	v_alignbit_b32 v99, v102, v99, 16
	v_pk_mul_f32 v[100:101], v[100:101], v[106:107]
	s_nop 0
	v_cvt_pk_f16_f32 v101, v100, v101
	v_alignbit_b32 v100, v101, v102, 16
	v_lshrrev_b32_e32 v101, 16, v101
	v_fma_mixhi_f16 v101, v135, v119, 0
	global_store_dwordx4 v[116:117], v[98:101], off offset:64
	v_or_b32_e32 v122, 32, v158
	s_nop 0
	v_mad_i64_i32 v[98:99], s[0:1], v122, s5, v[160:161]
	v_lshl_add_u64 v[118:119], v[98:99], 0, s[6:7]
	global_load_dwordx4 v[110:113], v[154:155], off offset:16
	global_load_dwordx4 v[114:117], v[154:155], off
	global_load_dwordx4 v[98:101], v[156:157], off offset:16
	global_load_dwordx4 v[102:105], v[156:157], off
	v_lshl_add_u64 v[134:135], v[118:119], 0, v[152:153]
	global_load_dwordx4 v[106:109], v[134:135], off
	v_ashrrev_i32_e32 v123, 31, v122
	s_waitcnt vmcnt(4)
	v_add_f32_e32 v90, v90, v110
	v_mul_f32_e32 v90, 0xbfb8aa3b, v90
	v_exp_f32_e32 v162, v90
	s_waitcnt vmcnt(3)
	v_add_f32_e32 v90, v95, v115
	v_mul_f32_e32 v90, 0xbfb8aa3b, v90
	v_exp_f32_e32 v165, v90
	v_add_f32_e32 v90, v91, v111
	v_mul_f32_e32 v90, 0xbfb8aa3b, v90
	v_exp_f32_e32 v163, v90
	v_add_f32_e32 v90, v96, v116
	v_mul_f32_e32 v90, 0xbfb8aa3b, v90
	v_exp_f32_e32 v166, v90
	v_add_f32_e32 v90, v92, v112
	v_mul_f32_e32 v90, 0xbfb8aa3b, v90
	v_exp_f32_e32 v136, v90
	v_add_f32_e32 v90, v97, v117
	v_mul_f32_e32 v90, 0xbfb8aa3b, v90
	v_exp_f32_e32 v167, v90
	v_add_f32_e32 v90, v93, v113
	v_add_f32_e32 v94, v94, v114
	v_mul_f32_e32 v90, 0xbfb8aa3b, v90
	v_mul_f32_e32 v94, 0xbfb8aa3b, v94
	v_exp_f32_e32 v137, v90
	v_lshl_add_u64 v[90:91], v[118:119], 0, v[128:129]
	v_exp_f32_e32 v164, v94
	global_load_dwordx4 v[94:97], v[154:155], off offset:144
	global_load_dwordx4 v[110:113], v[154:155], off offset:128
	global_load_dwordx4 v[138:141], v[156:157], off offset:144
	global_load_dwordx4 v[168:171], v[156:157], off offset:128
	global_load_dwordx4 v[172:175], v[90:91], off
	v_pk_add_f32 v[166:167], v[166:167], 1.0 op_sel_hi:[1,0]
	v_pk_add_f32 v[164:165], v[164:165], 1.0 op_sel_hi:[1,0]
	s_waitcnt vmcnt(4)
	v_add_f32_e32 v82, v82, v94
	v_mul_f32_e32 v82, 0xbfb8aa3b, v82
	v_exp_f32_e32 v118, v82
	s_waitcnt vmcnt(3)
	v_add_f32_e32 v82, v87, v111
	s_waitcnt vmcnt(0)
	v_cvt_f32_f16_e32 v116, v174
	v_cvt_f32_f16_sdwa v117, v174 dst_sel:DWORD dst_unused:UNUSED_PAD src0_sel:WORD_1
	v_cvt_f32_f16_e32 v130, v172
	v_cvt_f32_f16_sdwa v131, v172 dst_sel:DWORD dst_unused:UNUSED_PAD src0_sel:WORD_1
	v_mul_f32_e32 v82, 0xbfb8aa3b, v82
	v_exp_f32_e32 v133, v82
	v_add_f32_e32 v82, v83, v95
	v_mul_f32_e32 v82, 0xbfb8aa3b, v82
	v_pk_mul_f32 v[92:93], v[138:139], v[116:117]
	v_exp_f32_e32 v119, v82
	v_pk_mul_f32 v[94:95], v[168:169], v[130:131]
	v_pk_mul_f32 v[82:83], v[92:93], v[92:93]
	v_cvt_f32_f16_e32 v120, v173
	v_pk_fma_f32 v[138:139], v[94:95], v[94:95], v[82:83]
	v_add_f32_e32 v82, v88, v112
	v_mul_f32_e32 v82, 0xbfb8aa3b, v82
	v_exp_f32_e32 v124, v82
	v_add_f32_e32 v82, v84, v96
	v_mul_f32_e32 v82, 0xbfb8aa3b, v82
	v_exp_f32_e32 v114, v82
	v_add_f32_e32 v82, v89, v113
	v_cvt_f32_f16_e32 v112, v175
	v_cvt_f32_f16_sdwa v113, v175 dst_sel:DWORD dst_unused:UNUSED_PAD src0_sel:WORD_1
	v_cvt_f32_f16_sdwa v121, v173 dst_sel:DWORD dst_unused:UNUSED_PAD src0_sel:WORD_1
	v_mul_f32_e32 v82, 0xbfb8aa3b, v82
	v_exp_f32_e32 v125, v82
	v_add_f32_e32 v82, v85, v97
	v_add_f32_e32 v86, v86, v110
	v_mul_f32_e32 v82, 0xbfb8aa3b, v82
	v_pk_mul_f32 v[96:97], v[140:141], v[112:113]
	v_mul_f32_e32 v86, 0xbfb8aa3b, v86
	v_exp_f32_e32 v115, v82
	v_pk_mul_f32 v[110:111], v[170:171], v[120:121]
	v_pk_mul_f32 v[82:83], v[96:97], v[96:97]
	v_exp_f32_e32 v132, v86
	v_pk_fma_f32 v[140:141], v[110:111], v[110:111], v[82:83]
	global_load_dwordx4 v[82:85], v[126:127], off offset:16
	global_load_dwordx4 v[86:89], v[126:127], off
	v_cvt_f32_f16_e32 v168, v106
	v_cvt_f32_f16_sdwa v169, v106 dst_sel:DWORD dst_unused:UNUSED_PAD src0_sel:WORD_1
	v_div_scale_f32 v106, s[0:1], v165, v165, 1.0
	v_rcp_f32_e32 v159, v106
	s_nop 0
	v_fma_f32 v170, -v106, v159, 1.0
	v_fmac_f32_e32 v159, v170, v159
	v_div_scale_f32 v170, vcc, 1.0, v165, 1.0
	v_mul_f32_e32 v171, v170, v159
	v_fma_f32 v172, -v106, v171, v170
	v_fmac_f32_e32 v171, v172, v159
	v_fma_f32 v106, -v106, v171, v170
	v_div_fmas_f32 v106, v106, v159, v171
	v_div_fixup_f32 v165, v106, v165, 1.0
	v_div_scale_f32 v106, s[0:1], v164, v164, 1.0
	v_rcp_f32_e32 v159, v106
	s_nop 0
	v_fma_f32 v170, -v106, v159, 1.0
	v_fmac_f32_e32 v159, v170, v159
	v_div_scale_f32 v170, vcc, 1.0, v164, 1.0
	v_mul_f32_e32 v171, v170, v159
	v_fma_f32 v172, -v106, v171, v170
	v_fmac_f32_e32 v171, v172, v159
	v_fma_f32 v106, -v106, v171, v170
	v_div_fmas_f32 v106, v106, v159, v171
	v_div_fixup_f32 v164, v106, v164, 1.0
	v_pk_add_f32 v[170:171], v[164:165], -1.0 op_sel_hi:[1,0]
	v_cvt_f32_f16_e32 v106, v107
	v_cvt_f32_f16_sdwa v107, v107 dst_sel:DWORD dst_unused:UNUSED_PAD src0_sel:WORD_1
	s_waitcnt vmcnt(0)
; __device__ __forceinline__ float sigmoidf_(float x) { return 1.0f / (1.0f + __expf(-x)); }
;     __device__ __forceinline__ void body_a(const f32x4 (&acc)[2][2][4][2], int row0, int cb0) const {
;     ...
;                         a[bj][e] = sigmoidf_(acc[ai][bj][m][0][e] + b0[e]); a[bj][4 + e] = sigmoidf_(acc[ai][bj][m][1][e] + b1[e]);
;                         kv[bj][e] = (float)kh[e]; kv[bj][4 + e] = (float)kh[4 + e];
;                         kk[bj][e] = kv[bj][e] * q0[e]; kk[bj][4 + e] = kv[bj][4 + e] * q1[e];
;                         ss += kk[bj][e] * kk[bj][e] + kk[bj][4 + e] * kk[bj][4 + e];
;                     }
;                 }
;                 ss += __shfl_xor(ss, 16); ss += __shfl_xor(ss, 32);
;     ...
;                         ko0[e] = kv[bj][e] * (1.0f + (a[bj][e] - 1.0f) * p0[e]); ko1[e] = kv[bj][4 + e] * (1.0f + (a[bj][4 + e] - 1.0f) * p1[e]);
;                         const float n0_ = kk[bj][e] * inv, n1_ = kk[bj][4 + e] * inv;
;                         ao0[e] = -n0_; ao1[e] = -n1_; bo0[e] = n0_ * a[bj][e]; bo1[e] = n1_ * a[bj][4 + e];
;                     }
;                     *(u32x4*)(C1 + row * LDC1 + 2048 + c) = pack8(ko0, ko1);
	v_pk_fma_f32 v[86:87], v[170:171], v[86:87], 1.0 op_sel_hi:[1,1,0]
	s_nop 0
	v_pk_mul_f32 v[86:87], v[86:87], v[168:169]
	s_nop 0
	v_cvt_pk_f16_f32 v86, v86, v87
	v_div_scale_f32 v87, s[0:1], v167, v167, 1.0
	v_rcp_f32_e32 v159, v87
	s_nop 0
	v_fma_f32 v170, -v87, v159, 1.0
	v_fmac_f32_e32 v159, v170, v159
	v_div_scale_f32 v170, vcc, 1.0, v167, 1.0
	v_mul_f32_e32 v171, v170, v159
	v_fma_f32 v172, -v87, v171, v170
	v_fmac_f32_e32 v171, v172, v159
	v_fma_f32 v87, -v87, v171, v170
	v_div_fmas_f32 v87, v87, v159, v171
	v_div_fixup_f32 v167, v87, v167, 1.0
	v_div_scale_f32 v87, s[0:1], v166, v166, 1.0
	v_rcp_f32_e32 v159, v87
	s_nop 0
	v_fma_f32 v170, -v87, v159, 1.0
	v_fmac_f32_e32 v159, v170, v159
	v_div_scale_f32 v170, vcc, 1.0, v166, 1.0
	v_mul_f32_e32 v171, v170, v159
	v_fma_f32 v172, -v87, v171, v170
	v_fmac_f32_e32 v171, v172, v159
	v_fma_f32 v87, -v87, v171, v170
	v_div_fmas_f32 v87, v87, v159, v171
	v_div_fixup_f32 v166, v87, v166, 1.0
	v_pk_add_f32 v[170:171], v[166:167], -1.0 op_sel_hi:[1,0]
	s_nop 0
	v_pk_fma_f32 v[88:89], v[170:171], v[88:89], 1.0 op_sel_hi:[1,1,0]
	v_cvt_f32_f16_e32 v170, v108
	v_pk_mul_f32 v[88:89], v[88:89], v[106:107]
	v_cvt_f32_f16_sdwa v171, v108 dst_sel:DWORD dst_unused:UNUSED_PAD src0_sel:WORD_1
	v_cvt_pk_f16_f32 v87, v88, v89
	v_pk_add_f32 v[88:89], v[162:163], 1.0 op_sel_hi:[1,0]
	s_nop 0
	v_div_scale_f32 v108, s[0:1], v89, v89, 1.0
	v_rcp_f32_e32 v159, v108
	s_nop 0
	v_fma_f32 v162, -v108, v159, 1.0
	v_fmac_f32_e32 v159, v162, v159
	v_div_scale_f32 v162, vcc, 1.0, v89, 1.0
	v_mul_f32_e32 v163, v162, v159
	v_fma_f32 v172, -v108, v163, v162
	v_fmac_f32_e32 v163, v172, v159
	v_fma_f32 v108, -v108, v163, v162
	v_div_fmas_f32 v108, v108, v159, v163
	v_div_fixup_f32 v163, v108, v89, 1.0
	v_div_scale_f32 v89, s[0:1], v88, v88, 1.0
	v_rcp_f32_e32 v108, v89
	s_nop 0
	v_fma_f32 v159, -v89, v108, 1.0
	v_fmac_f32_e32 v108, v159, v108
	v_div_scale_f32 v159, vcc, 1.0, v88, 1.0
	v_mul_f32_e32 v162, v159, v108
	v_fma_f32 v172, -v89, v162, v159
	v_fmac_f32_e32 v162, v172, v108
	v_fma_f32 v89, -v89, v162, v159
	v_div_fmas_f32 v89, v89, v108, v162
	v_div_fixup_f32 v162, v89, v88, 1.0
	v_pk_add_f32 v[88:89], v[162:163], -1.0 op_sel_hi:[1,0]
	v_cvt_f32_f16_e32 v108, v109
	v_pk_fma_f32 v[82:83], v[88:89], v[82:83], 1.0 op_sel_hi:[1,1,0]
	v_cvt_f32_f16_sdwa v109, v109 dst_sel:DWORD dst_unused:UNUSED_PAD src0_sel:WORD_1
	v_pk_mul_f32 v[82:83], v[82:83], v[170:171]
	v_pk_mul_f32 v[100:101], v[100:101], v[108:109]
	v_cvt_pk_f16_f32 v88, v82, v83
	v_pk_add_f32 v[82:83], v[136:137], 1.0 op_sel_hi:[1,0]
	s_nop 0
	v_div_scale_f32 v89, s[0:1], v83, v83, 1.0
	v_rcp_f32_e32 v136, v89
	s_nop 0
	v_fma_f32 v137, -v89, v136, 1.0
	v_fmac_f32_e32 v136, v137, v136
	v_div_scale_f32 v137, vcc, 1.0, v83, 1.0
	v_mul_f32_e32 v159, v137, v136
	v_fma_f32 v172, -v89, v159, v137
	v_fmac_f32_e32 v159, v172, v136
	v_fma_f32 v89, -v89, v159, v137
	v_div_fmas_f32 v89, v89, v136, v159
	v_div_fixup_f32 v83, v89, v83, 1.0
	v_div_scale_f32 v89, s[0:1], v82, v82, 1.0
	v_rcp_f32_e32 v136, v89
	s_nop 0
	v_fma_f32 v137, -v89, v136, 1.0
	v_fmac_f32_e32 v136, v137, v136
	v_div_scale_f32 v137, vcc, 1.0, v82, 1.0
	v_mul_f32_e32 v159, v137, v136
	v_fma_f32 v172, -v89, v159, v137
	v_fmac_f32_e32 v159, v172, v136
	v_fma_f32 v89, -v89, v159, v137
	v_div_fmas_f32 v89, v89, v136, v159
	v_div_fixup_f32 v82, v89, v82, 1.0
	v_pk_add_f32 v[136:137], v[82:83], -1.0 op_sel_hi:[1,0]
	s_nop 0
	v_pk_fma_f32 v[84:85], v[136:137], v[84:85], 1.0 op_sel_hi:[1,1,0]
	s_nop 0
	v_pk_mul_f32 v[84:85], v[84:85], v[108:109]
	v_lshlrev_b64 v[108:109], 12, v[122:123]
	v_cvt_pk_f16_f32 v89, v84, v85
	global_store_dwordx4 v[134:135], v[86:89], off
	v_pk_mul_f32 v[84:85], v[102:103], v[168:169]
	v_pk_mul_f32 v[102:103], v[100:101], v[100:101]
	v_pk_mul_f32 v[88:89], v[98:99], v[170:171]
	v_pk_mul_f32 v[86:87], v[104:105], v[106:107]
	v_pk_mul_f32 v[98:99], v[88:89], v[88:89]
	v_pk_fma_f32 v[102:103], v[86:87], v[86:87], v[102:103]
	v_pk_fma_f32 v[98:99], v[84:85], v[84:85], v[98:99]
	s_nop 0
	v_add_f32_e32 v98, v98, v99
	v_add_f32_e32 v98, v102, v98
	v_add_f32_e32 v98, v103, v98
	v_add_f32_e32 v98, v98, v138
	v_add_f32_e32 v98, v139, v98
	v_add_f32_e32 v98, v140, v98
	v_add_f32_e32 v98, v141, v98
	ds_bpermute_b32 v99, v206, v98
	s_waitcnt lgkmcnt(0)
	v_add_f32_e32 v98, v98, v99
	ds_bpermute_b32 v99, v207, v98
	s_waitcnt lgkmcnt(0)
;     __device__ __forceinline__ void body_a(const f32x4 (&acc)[2][2][4][2], int row0, int cb0) const {
;     ...
;                 ss += __shfl_xor(ss, 16); ss += __shfl_xor(ss, 32);
;                 const float inv = 1.0f / fmaxf(sqrtf(ss), 1e-12f);
; #pragma unroll
;                 for (int bj = 0; bj < 2; ++bj) {
;                     const int c = cb0 + 32 * bj;
;                     const f32x4 p0 = *(const f32x4*)(k_a + c), p1 = *(const f32x4*)(k_a + c + 4);
;                     f32x4 ko0, ko1, ao0, ao1, bo0, bo1;
; #pragma unroll
;                     for (int e = 0; e < 4; ++e) {
;                         ko0[e] = kv[bj][e] * (1.0f + (a[bj][e] - 1.0f) * p0[e]); ko1[e] = kv[bj][4 + e] * (1.0f + (a[bj][4 + e] - 1.0f) * p1[e]);
;                         const float n0_ = kk[bj][e] * inv, n1_ = kk[bj][4 + e] * inv;
;                         ao0[e] = -n0_; ao1[e] = -n1_; bo0[e] = n0_ * a[bj][e]; bo1[e] = n1_ * a[bj][4 + e];
;                     }
;                     *(u32x4*)(C1 + row * LDC1 + 2048 + c) = pack8(ko0, ko1);
;                     *(u32x4*)(AA + row * DM + c) = pack8(ao0, ao1);
;                     *(u32x4*)(Ab + row * DM + c) = pack8(bo0, bo1);
	v_add_f32_e32 v98, v98, v99
	v_cmp_gt_f32_e32 vcc, s4, v98
	v_mul_f32_e32 v99, 0x4f800000, v98
	s_nop 0
	v_cndmask_b32_e32 v98, v98, v99, vcc
	v_sqrt_f32_e32 v99, v98
	s_nop 0
	v_add_u32_e32 v102, -1, v99
	v_fma_f32 v103, -v102, v99, v98
	v_cmp_ge_f32_e64 s[0:1], 0, v103
	v_add_u32_e32 v103, 1, v99
	s_nop 0
	v_cndmask_b32_e64 v102, v99, v102, s[0:1]
	v_fma_f32 v99, -v103, v99, v98
	v_cmp_lt_f32_e64 s[0:1], 0, v99
	s_nop 1
	v_cndmask_b32_e64 v99, v102, v103, s[0:1]
	v_mul_f32_e32 v102, 0x37800000, v99
	v_cndmask_b32_e32 v99, v99, v102, vcc
	v_cmp_class_f32_e32 vcc, v98, v244
	s_nop 1
	v_cndmask_b32_e32 v98, v99, v98, vcc
	v_max_f32_e32 v98, 0x2b8cbccc, v98
	v_div_scale_f32 v99, s[0:1], v98, v98, 1.0
	v_rcp_f32_e32 v102, v99
	s_nop 0
	v_fma_f32 v103, -v99, v102, 1.0
	v_fmac_f32_e32 v102, v103, v102
	v_div_scale_f32 v103, vcc, 1.0, v98, 1.0
	v_mul_f32_e32 v104, v103, v102
	v_fma_f32 v105, -v99, v104, v103
	v_fmac_f32_e32 v104, v105, v102
	v_fma_f32 v99, -v99, v104, v103
	v_div_fmas_f32 v99, v99, v102, v104
	v_div_fixup_f32 v102, v99, v98, 1.0
	v_pk_mul_f32 v[106:107], v[86:87], v[102:103] op_sel_hi:[1,0]
	v_pk_mul_f32 v[104:105], v[84:85], v[102:103] op_sel_hi:[1,0]
	v_cvt_pk_f16_f32 v85, v106, v107
	v_cvt_pk_f16_f32 v84, v104, v105
	v_xor_b32_e32 v86, 0x8000, v85
	v_xor_b32_sdwa v85, s63, v85 dst_sel:DWORD dst_unused:UNUSED_PAD src0_sel:DWORD src1_sel:WORD_1
	v_pk_mul_f32 v[88:89], v[88:89], v[102:103] op_sel_hi:[1,0]
	v_pk_mul_f32 v[100:101], v[100:101], v[102:103] op_sel_hi:[1,0]
	v_perm_b32 v85, v85, v86, s33
	v_xor_b32_e32 v86, 0x8000, v84
	v_xor_b32_sdwa v84, s63, v84 dst_sel:DWORD dst_unused:UNUSED_PAD src0_sel:DWORD src1_sel:WORD_1
	v_perm_b32 v84, v84, v86, s33
	v_pk_add_f32 v[86:87], v[88:89], 0 neg_lo:[1,1] neg_hi:[1,1]
	v_pk_add_f32 v[98:99], v[100:101], 0 neg_lo:[1,1] neg_hi:[1,1]
	v_cvt_pk_f16_f32 v86, v86, v87
	v_cvt_pk_f16_f32 v87, v98, v99
	v_lshl_add_u64 v[98:99], s[10:11], 0, v[108:109]
	v_lshl_add_u64 v[98:99], v[98:99], 0, v[152:153]
	global_store_dwordx4 v[98:99], v[84:87], off
	v_fma_mixlo_f16 v103, v164, v104, 0
	v_mul_f32_e32 v122, v94, v102
	v_pk_mov_b32 v[84:85], v[164:165], v[166:167] op_sel:[1,0]
	v_pk_mov_b32 v[86:87], v[104:105], v[106:107] op_sel:[1,0]
	v_pk_mov_b32 v[104:105], v[106:107], v[88:89] op_sel:[1,0]
	v_pk_mul_f32 v[84:85], v[84:85], v[86:87]
	v_pk_mov_b32 v[86:87], v[166:167], v[162:163] op_sel:[1,0]
	v_cvt_pk_f16_f32 v85, v84, v85
	v_pk_mul_f32 v[86:87], v[86:87], v[104:105]
	v_pack_b32_f16 v84, v103, v85
	v_cvt_pk_f16_f32 v103, v86, v87
	v_pk_mov_b32 v[86:87], v[162:163], v[82:83] op_sel:[1,0]
	v_pk_mov_b32 v[88:89], v[88:89], v[100:101] op_sel:[1,0]
	v_alignbit_b32 v85, v103, v85, 16
	v_pk_mul_f32 v[86:87], v[86:87], v[88:89]
	v_pk_add_f32 v[104:105], v[132:133], 1.0 op_sel_hi:[1,0]
	v_cvt_pk_f16_f32 v82, v86, v87
	v_lshrrev_b32_e32 v87, 16, v82
	v_alignbit_b32 v86, v82, v103, 16
	v_fma_mixhi_f16 v87, v83, v101, 0
	v_lshl_add_u64 v[82:83], s[2:3], 0, v[108:109]
	v_lshl_add_u64 v[100:101], v[82:83], 0, v[152:153]
	global_store_dwordx4 v[100:101], v[84:87], off
	global_load_dwordx4 v[82:85], v[126:127], off offset:144
	s_nop 0
	global_load_dwordx4 v[86:89], v[126:127], off offset:128
	v_div_scale_f32 v106, s[0:1], v105, v105, 1.0
	v_rcp_f32_e32 v107, v106
	v_mul_f32_e32 v103, v97, v102
	v_fma_f32 v108, -v106, v107, 1.0
	v_fmac_f32_e32 v107, v108, v107
	v_div_scale_f32 v108, vcc, 1.0, v105, 1.0
	v_mul_f32_e32 v109, v108, v107
	v_fma_f32 v123, -v106, v109, v108
	v_fmac_f32_e32 v109, v123, v107
	v_fma_f32 v106, -v106, v109, v108
	v_div_fmas_f32 v106, v106, v107, v109
	v_div_fixup_f32 v105, v106, v105, 1.0
	v_div_scale_f32 v106, s[0:1], v104, v104, 1.0
	v_rcp_f32_e32 v107, v106
	s_nop 0
	v_fma_f32 v108, -v106, v107, 1.0
	v_fmac_f32_e32 v107, v108, v107
	v_div_scale_f32 v108, vcc, 1.0, v104, 1.0
	v_mul_f32_e32 v109, v108, v107
	v_fma_f32 v123, -v106, v109, v108
	v_fmac_f32_e32 v109, v123, v107
	v_fma_f32 v106, -v106, v109, v108
	v_div_fmas_f32 v106, v106, v107, v109
	v_div_fixup_f32 v104, v106, v104, 1.0
	v_pk_add_f32 v[106:107], v[104:105], -1.0 op_sel_hi:[1,0]
	s_waitcnt vmcnt(0)
	v_pk_fma_f32 v[86:87], v[106:107], v[86:87], 1.0 op_sel_hi:[1,1,0]
	s_nop 0
	v_pk_mul_f32 v[86:87], v[86:87], v[130:131]
	v_pk_add_f32 v[106:107], v[124:125], 1.0 op_sel_hi:[1,0]
	v_cvt_pk_f16_f32 v86, v86, v87
	v_div_scale_f32 v87, s[0:1], v107, v107, 1.0
	v_rcp_f32_e32 v108, v87
	s_nop 0
	v_fma_f32 v109, -v87, v108, 1.0
	v_fmac_f32_e32 v108, v109, v108
	v_div_scale_f32 v109, vcc, 1.0, v107, 1.0
	v_mul_f32_e32 v123, v109, v108
	v_fma_f32 v124, -v87, v123, v109
	v_fmac_f32_e32 v123, v124, v108
	v_fma_f32 v87, -v87, v123, v109
	v_div_fmas_f32 v87, v87, v108, v123
	v_div_fixup_f32 v107, v87, v107, 1.0
	v_div_scale_f32 v87, s[0:1], v106, v106, 1.0
	v_rcp_f32_e32 v108, v87
	s_nop 0
	v_fma_f32 v109, -v87, v108, 1.0
	v_fmac_f32_e32 v108, v109, v108
	v_div_scale_f32 v109, vcc, 1.0, v106, 1.0
	v_mul_f32_e32 v123, v109, v108
	v_fma_f32 v124, -v87, v123, v109
	v_fmac_f32_e32 v123, v124, v108
	v_fma_f32 v87, -v87, v123, v109
	v_div_fmas_f32 v87, v87, v108, v123
	v_div_fixup_f32 v106, v87, v106, 1.0
	v_pk_add_f32 v[108:109], v[106:107], -1.0 op_sel_hi:[1,0]
	s_nop 0
	v_pk_fma_f32 v[88:89], v[108:109], v[88:89], 1.0 op_sel_hi:[1,1,0]
	s_nop 0
	v_pk_mul_f32 v[88:89], v[88:89], v[120:121]
	s_nop 0
	v_cvt_pk_f16_f32 v87, v88, v89
	v_pk_add_f32 v[88:89], v[118:119], 1.0 op_sel_hi:[1,0]
	s_nop 0
	v_div_scale_f32 v108, s[0:1], v89, v89, 1.0
	v_rcp_f32_e32 v109, v108
	s_nop 0
	v_fma_f32 v118, -v108, v109, 1.0
	v_fmac_f32_e32 v109, v118, v109
	v_div_scale_f32 v118, vcc, 1.0, v89, 1.0
	v_mul_f32_e32 v119, v118, v109
	v_fma_f32 v120, -v108, v119, v118
; __device__ __forceinline__ float sigmoidf_(float x) { return 1.0f / (1.0f + __expf(-x)); }
;     __device__ __forceinline__ void body_a(const f32x4 (&acc)[2][2][4][2], int row0, int cb0) const {
;     ...
;                 const size_t row = (size_t)(row0 + ai * 128 + m * 16);
;                 asm volatile("" ::: "memory");
;                 float a[2][8], kv[2][8], kk[2][8]; float ss = 0.f;
; #pragma unroll
;                 for (int bj = 0; bj < 2; ++bj) {
;                     const int c = cb0 + 32 * bj;
;                     const f32x4 b0 = *(const f32x4*)(a0 + c), b1 = *(const f32x4*)(a0 + c + 4), q0 = *(const f32x4*)(k_k + c), q1 = *(const f32x4*)(k_k + c + 4);
;                     const h16x8 kh = *(const h16x8*)(C1 + row * LDC1 + 2048 + c);
; #pragma unroll
;                     for (int e = 0; e < 4; ++e) {
;                         a[bj][e] = sigmoidf_(acc[ai][bj][m][0][e] + b0[e]); a[bj][4 + e] = sigmoidf_(acc[ai][bj][m][1][e] + b1[e]);
;                         kv[bj][e] = (float)kh[e]; kv[bj][4 + e] = (float)kh[4 + e];
;                         kk[bj][e] = kv[bj][e] * q0[e]; kk[bj][4 + e] = kv[bj][4 + e] * q1[e];
;                         ss += kk[bj][e] * kk[bj][e] + kk[bj][4 + e] * kk[bj][4 + e];
;     ...
;                 for (int bj = 0; bj < 2; ++bj) {
;                     const int c = cb0 + 32 * bj;
;                     const f32x4 p0 = *(const f32x4*)(k_a + c), p1 = *(const f32x4*)(k_a + c + 4);
;                     f32x4 ko0, ko1, ao0, ao1, bo0, bo1;
; #pragma unroll
;                     for (int e = 0; e < 4; ++e) {
;                         ko0[e] = kv[bj][e] * (1.0f + (a[bj][e] - 1.0f) * p0[e]); ko1[e] = kv[bj][4 + e] * (1.0f + (a[bj][4 + e] - 1.0f) * p1[e]);
;                         const float n0_ = kk[bj][e] * inv, n1_ = kk[bj][4 + e] * inv;
;                         ao0[e] = -n0_; ao1[e] = -n1_; bo0[e] = n0_ * a[bj][e]; bo1[e] = n1_ * a[bj][4 + e];
;                     }
;                     *(u32x4*)(C1 + row * LDC1 + 2048 + c) = pack8(ko0, ko1);
;                     *(u32x4*)(AA + row * DM + c) = pack8(ao0, ao1);
;                     *(u32x4*)(Ab + row * DM + c) = pack8(bo0, bo1);
	v_fmac_f32_e32 v119, v120, v109
	v_fma_f32 v108, -v108, v119, v118
	v_div_fmas_f32 v108, v108, v109, v119
	v_div_fixup_f32 v109, v108, v89, 1.0
	v_div_scale_f32 v89, s[0:1], v88, v88, 1.0
	v_rcp_f32_e32 v108, v89
	s_nop 0
	v_fma_f32 v118, -v89, v108, 1.0
	v_fmac_f32_e32 v108, v118, v108
	v_div_scale_f32 v118, vcc, 1.0, v88, 1.0
	v_mul_f32_e32 v119, v118, v108
	v_fma_f32 v120, -v89, v119, v118
	v_fmac_f32_e32 v119, v120, v108
	v_fma_f32 v89, -v89, v119, v118
	v_div_fmas_f32 v89, v89, v108, v119
	v_div_fixup_f32 v108, v89, v88, 1.0
	v_pk_add_f32 v[88:89], v[108:109], -1.0 op_sel_hi:[1,0]
	s_nop 0
	v_pk_fma_f32 v[82:83], v[88:89], v[82:83], 1.0 op_sel_hi:[1,1,0]
	s_nop 0
	v_pk_mul_f32 v[82:83], v[82:83], v[116:117]
	s_nop 0
	v_cvt_pk_f16_f32 v88, v82, v83
	v_pk_add_f32 v[82:83], v[114:115], 1.0 op_sel_hi:[1,0]
	s_nop 0
	v_div_scale_f32 v89, s[0:1], v83, v83, 1.0
	v_rcp_f32_e32 v114, v89
	s_nop 0
	v_fma_f32 v115, -v89, v114, 1.0
	v_fmac_f32_e32 v114, v115, v114
	v_div_scale_f32 v115, vcc, 1.0, v83, 1.0
	v_mul_f32_e32 v116, v115, v114
	v_fma_f32 v117, -v89, v116, v115
	v_fmac_f32_e32 v116, v117, v114
	v_fma_f32 v89, -v89, v116, v115
	v_div_fmas_f32 v89, v89, v114, v116
	v_div_fixup_f32 v115, v89, v83, 1.0
	v_div_scale_f32 v83, s[0:1], v82, v82, 1.0
	v_rcp_f32_e32 v89, v83
	s_nop 0
	v_fma_f32 v114, -v83, v89, 1.0
	v_fmac_f32_e32 v89, v114, v89
	v_div_scale_f32 v114, vcc, 1.0, v82, 1.0
	v_mul_f32_e32 v116, v114, v89
	v_fma_f32 v117, -v83, v116, v114
	v_fmac_f32_e32 v116, v117, v89
	v_fma_f32 v83, -v83, v116, v114
	v_div_fmas_f32 v83, v83, v89, v116
	v_div_fixup_f32 v114, v83, v82, 1.0
	v_pk_add_f32 v[82:83], v[114:115], -1.0 op_sel_hi:[1,0]
	s_nop 0
	v_pk_fma_f32 v[82:83], v[82:83], v[84:85], 1.0 op_sel_hi:[1,1,0]
	v_cvt_f16_f32_e64 v84, -v122
	v_pk_mul_f32 v[82:83], v[82:83], v[112:113]
	s_nop 0
	v_cvt_pk_f16_f32 v89, v82, v83
	v_pk_mov_b32 v[82:83], v[94:95], v[110:111] op_sel:[1,0]
	global_store_dwordx4 v[90:91], v[86:89], off
	s_nop 1
	v_pk_mul_f32 v[86:87], v[82:83], v[102:103] op_sel_hi:[1,0]
	s_nop 0
	v_cvt_pk_f16_f32 v83, v86, v87
	v_pack_b32_f16 v82, v84, -v83
	v_pk_mov_b32 v[84:85], v[110:111], v[92:93] op_sel:[1,0]
	v_xor_b32_sdwa v83, s63, v83 dst_sel:DWORD dst_unused:UNUSED_PAD src0_sel:DWORD src1_sel:WORD_1
	v_pk_mul_f32 v[88:89], v[84:85], v[102:103] op_sel_hi:[1,0]
	s_nop 0
	v_cvt_pk_f16_f32 v84, v88, v89
	v_xor_b32_e32 v85, 0x8000, v84
	v_perm_b32 v83, v85, v83, s33
	v_xor_b32_sdwa v94, s63, v84 dst_sel:DWORD dst_unused:UNUSED_PAD src0_sel:DWORD src1_sel:WORD_1
	v_pk_mov_b32 v[84:85], v[92:93], v[96:97] op_sel:[1,0]
	v_cvt_f16_f32_e64 v92, -v103
	v_pk_mul_f32 v[90:91], v[84:85], v[102:103] op_sel_hi:[1,0]
	s_nop 0
	v_cvt_pk_f16_f32 v85, v90, v91
	v_xor_b32_e32 v84, 0x8000, v85
	v_xor_b32_sdwa v85, s63, v85 dst_sel:DWORD dst_unused:UNUSED_PAD src0_sel:DWORD src1_sel:WORD_1
	v_perm_b32 v84, v84, v94, s33
	v_perm_b32 v85, v92, v85, s33
	global_store_dwordx4 v[98:99], v[82:85], off offset:64
	s_nop 1
	v_pk_mov_b32 v[82:83], v[104:105], v[106:107] op_sel:[1,0]
	v_fma_mixlo_f16 v84, v104, v122, 0
	v_pk_mul_f32 v[82:83], v[82:83], v[86:87]
	s_nop 0
	v_cvt_pk_f16_f32 v83, v82, v83
	v_pack_b32_f16 v82, v84, v83
	v_pk_mov_b32 v[84:85], v[106:107], v[108:109] op_sel:[1,0]
	s_nop 0
	v_pk_mul_f32 v[84:85], v[84:85], v[88:89]
	s_nop 0
	v_cvt_pk_f16_f32 v86, v84, v85
	v_pk_mov_b32 v[84:85], v[108:109], v[114:115] op_sel:[1,0]
	v_alignbit_b32 v83, v86, v83, 16
	v_pk_mul_f32 v[84:85], v[84:85], v[90:91]
	s_nop 0
	v_cvt_pk_f16_f32 v85, v84, v85
	v_alignbit_b32 v84, v85, v86, 16
	v_lshrrev_b32_e32 v85, 16, v85
	v_fma_mixhi_f16 v85, v115, v103, 0
	global_store_dwordx4 v[100:101], v[82:85], off offset:64
	v_or_b32_e32 v106, 48, v158
	s_nop 0
	v_mad_i64_i32 v[82:83], s[0:1], v106, s5, v[160:161]
	v_lshl_add_u64 v[102:103], v[82:83], 0, s[6:7]
	global_load_dwordx4 v[94:97], v[154:155], off offset:16
	global_load_dwordx4 v[98:101], v[154:155], off
	global_load_dwordx4 v[82:85], v[156:157], off offset:16
	global_load_dwordx4 v[86:89], v[156:157], off
	v_lshl_add_u64 v[114:115], v[102:103], 0, v[152:153]
	global_load_dwordx4 v[90:93], v[114:115], off
	v_ashrrev_i32_e32 v107, 31, v106
	s_waitcnt vmcnt(4)
	v_add_f32_e32 v74, v74, v94
	v_mul_f32_e32 v74, 0xbfb8aa3b, v74
	v_exp_f32_e32 v122, v74
	s_waitcnt vmcnt(3)
	v_add_f32_e32 v74, v79, v99
	v_mul_f32_e32 v74, 0xbfb8aa3b, v74
	v_exp_f32_e32 v125, v74
	v_add_f32_e32 v74, v75, v95
	v_mul_f32_e32 v74, 0xbfb8aa3b, v74
	v_exp_f32_e32 v123, v74
	v_add_f32_e32 v74, v80, v100
	v_mul_f32_e32 v74, 0xbfb8aa3b, v74
	v_exp_f32_e32 v130, v74
	v_add_f32_e32 v74, v76, v96
	v_mul_f32_e32 v74, 0xbfb8aa3b, v74
	v_exp_f32_e32 v116, v74
	v_add_f32_e32 v74, v81, v101
	v_mul_f32_e32 v74, 0xbfb8aa3b, v74
	v_exp_f32_e32 v131, v74
	v_add_f32_e32 v74, v77, v97
	v_add_f32_e32 v78, v78, v98
	v_mul_f32_e32 v74, 0xbfb8aa3b, v74
	v_mul_f32_e32 v78, 0xbfb8aa3b, v78
	v_exp_f32_e32 v117, v74
	v_lshl_add_u64 v[74:75], v[102:103], 0, v[128:129]
	v_exp_f32_e32 v124, v78
	global_load_dwordx4 v[78:81], v[154:155], off offset:144
	global_load_dwordx4 v[94:97], v[154:155], off offset:128
	global_load_dwordx4 v[118:121], v[156:157], off offset:144
	global_load_dwordx4 v[132:135], v[156:157], off offset:128
	global_load_dwordx4 v[136:139], v[74:75], off
	v_pk_add_f32 v[130:131], v[130:131], 1.0 op_sel_hi:[1,0]
	v_pk_add_f32 v[124:125], v[124:125], 1.0 op_sel_hi:[1,0]
	s_waitcnt vmcnt(4)
	v_add_f32_e32 v66, v66, v78
	v_mul_f32_e32 v66, 0xbfb8aa3b, v66
	v_exp_f32_e32 v102, v66
	s_waitcnt vmcnt(3)
	v_add_f32_e32 v66, v71, v95
	s_waitcnt vmcnt(0)
; __device__ __forceinline__ float sigmoidf_(float x) { return 1.0f / (1.0f + __expf(-x)); }
;     __device__ __forceinline__ void body_a(const f32x4 (&acc)[2][2][4][2], int row0, int cb0) const {
;     ...
;                     const f32x4 b0 = *(const f32x4*)(a0 + c), b1 = *(const f32x4*)(a0 + c + 4), q0 = *(const f32x4*)(k_k + c), q1 = *(const f32x4*)(k_k + c + 4);
;                     const h16x8 kh = *(const h16x8*)(C1 + row * LDC1 + 2048 + c);
; #pragma unroll
;                     for (int e = 0; e < 4; ++e) {
;                         a[bj][e] = sigmoidf_(acc[ai][bj][m][0][e] + b0[e]); a[bj][4 + e] = sigmoidf_(acc[ai][bj][m][1][e] + b1[e]);
;                         kv[bj][e] = (float)kh[e]; kv[bj][4 + e] = (float)kh[4 + e];
;                         kk[bj][e] = kv[bj][e] * q0[e]; kk[bj][4 + e] = kv[bj][4 + e] * q1[e];
;                         ss += kk[bj][e] * kk[bj][e] + kk[bj][4 + e] * kk[bj][4 + e];
;                     }
;                 }
;                 ss += __shfl_xor(ss, 16); ss += __shfl_xor(ss, 32);
;     ...
;                         ko0[e] = kv[bj][e] * (1.0f + (a[bj][e] - 1.0f) * p0[e]); ko1[e] = kv[bj][4 + e] * (1.0f + (a[bj][4 + e] - 1.0f) * p1[e]);
;                         const float n0_ = kk[bj][e] * inv, n1_ = kk[bj][4 + e] * inv;
;                         ao0[e] = -n0_; ao1[e] = -n1_; bo0[e] = n0_ * a[bj][e]; bo1[e] = n1_ * a[bj][4 + e];
;                     }
;                     *(u32x4*)(C1 + row * LDC1 + 2048 + c) = pack8(ko0, ko1);
	v_cvt_f32_f16_e32 v100, v138
	v_cvt_f32_f16_sdwa v101, v138 dst_sel:DWORD dst_unused:UNUSED_PAD src0_sel:WORD_1
	v_cvt_f32_f16_e32 v110, v136
	v_cvt_f32_f16_sdwa v111, v136 dst_sel:DWORD dst_unused:UNUSED_PAD src0_sel:WORD_1
	v_mul_f32_e32 v66, 0xbfb8aa3b, v66
	v_exp_f32_e32 v113, v66
	v_add_f32_e32 v66, v67, v79
	v_mul_f32_e32 v66, 0xbfb8aa3b, v66
	v_pk_mul_f32 v[76:77], v[118:119], v[100:101]
	v_exp_f32_e32 v103, v66
	v_pk_mul_f32 v[78:79], v[132:133], v[110:111]
	v_pk_mul_f32 v[66:67], v[76:77], v[76:77]
	v_cvt_f32_f16_e32 v104, v137
	v_pk_fma_f32 v[118:119], v[78:79], v[78:79], v[66:67]
	v_add_f32_e32 v66, v72, v96
	v_mul_f32_e32 v66, 0xbfb8aa3b, v66
	v_exp_f32_e32 v108, v66
	v_add_f32_e32 v66, v68, v80
	v_mul_f32_e32 v66, 0xbfb8aa3b, v66
	v_exp_f32_e32 v98, v66
	v_add_f32_e32 v66, v73, v97
	v_cvt_f32_f16_e32 v96, v139
	v_cvt_f32_f16_sdwa v97, v139 dst_sel:DWORD dst_unused:UNUSED_PAD src0_sel:WORD_1
	v_cvt_f32_f16_sdwa v105, v137 dst_sel:DWORD dst_unused:UNUSED_PAD src0_sel:WORD_1
	v_mul_f32_e32 v66, 0xbfb8aa3b, v66
	v_exp_f32_e32 v109, v66
	v_add_f32_e32 v66, v69, v81
	v_add_f32_e32 v70, v70, v94
	v_mul_f32_e32 v66, 0xbfb8aa3b, v66
	v_pk_mul_f32 v[80:81], v[120:121], v[96:97]
	v_mul_f32_e32 v70, 0xbfb8aa3b, v70
	v_exp_f32_e32 v99, v66
	v_pk_mul_f32 v[94:95], v[134:135], v[104:105]
	v_pk_mul_f32 v[66:67], v[80:81], v[80:81]
	v_exp_f32_e32 v112, v70
	v_pk_fma_f32 v[120:121], v[94:95], v[94:95], v[66:67]
	global_load_dwordx4 v[66:69], v[126:127], off offset:16
	global_load_dwordx4 v[70:73], v[126:127], off
	v_cvt_f32_f16_e32 v132, v90
	v_cvt_f32_f16_sdwa v133, v90 dst_sel:DWORD dst_unused:UNUSED_PAD src0_sel:WORD_1
	v_div_scale_f32 v90, s[0:1], v125, v125, 1.0
	v_rcp_f32_e32 v134, v90
	s_nop 0
	v_fma_f32 v135, -v90, v134, 1.0
	v_fmac_f32_e32 v134, v135, v134
	v_div_scale_f32 v135, vcc, 1.0, v125, 1.0
	v_mul_f32_e32 v136, v135, v134
	v_fma_f32 v137, -v90, v136, v135
	v_fmac_f32_e32 v136, v137, v134
	v_fma_f32 v90, -v90, v136, v135
	v_div_fmas_f32 v90, v90, v134, v136
	v_div_fixup_f32 v125, v90, v125, 1.0
	v_div_scale_f32 v90, s[0:1], v124, v124, 1.0
	v_rcp_f32_e32 v134, v90
	s_nop 0
	v_fma_f32 v135, -v90, v134, 1.0
	v_fmac_f32_e32 v134, v135, v134
	v_div_scale_f32 v135, vcc, 1.0, v124, 1.0
	v_mul_f32_e32 v136, v135, v134
	v_fma_f32 v137, -v90, v136, v135
	v_fmac_f32_e32 v136, v137, v134
	v_fma_f32 v90, -v90, v136, v135
	v_div_fmas_f32 v90, v90, v134, v136
	v_div_fixup_f32 v124, v90, v124, 1.0
	v_pk_add_f32 v[134:135], v[124:125], -1.0 op_sel_hi:[1,0]
	v_cvt_f32_f16_e32 v90, v91
	v_cvt_f32_f16_sdwa v91, v91 dst_sel:DWORD dst_unused:UNUSED_PAD src0_sel:WORD_1
	s_waitcnt vmcnt(0)
	v_pk_fma_f32 v[70:71], v[134:135], v[70:71], 1.0 op_sel_hi:[1,1,0]
	s_nop 0
	v_pk_mul_f32 v[70:71], v[70:71], v[132:133]
	s_nop 0
	v_cvt_pk_f16_f32 v70, v70, v71
	v_div_scale_f32 v71, s[0:1], v131, v131, 1.0
	v_rcp_f32_e32 v134, v71
	s_nop 0
	v_fma_f32 v135, -v71, v134, 1.0
	v_fmac_f32_e32 v134, v135, v134
	v_div_scale_f32 v135, vcc, 1.0, v131, 1.0
	v_mul_f32_e32 v136, v135, v134
	v_fma_f32 v137, -v71, v136, v135
	v_fmac_f32_e32 v136, v137, v134
	v_fma_f32 v71, -v71, v136, v135
	v_div_fmas_f32 v71, v71, v134, v136
	v_div_fixup_f32 v131, v71, v131, 1.0
	v_div_scale_f32 v71, s[0:1], v130, v130, 1.0
	v_rcp_f32_e32 v134, v71
	s_nop 0
	v_fma_f32 v135, -v71, v134, 1.0
	v_fmac_f32_e32 v134, v135, v134
	v_div_scale_f32 v135, vcc, 1.0, v130, 1.0
	v_mul_f32_e32 v136, v135, v134
	v_fma_f32 v137, -v71, v136, v135
	v_fmac_f32_e32 v136, v137, v134
	v_fma_f32 v71, -v71, v136, v135
	v_div_fmas_f32 v71, v71, v134, v136
	v_div_fixup_f32 v130, v71, v130, 1.0
	v_pk_add_f32 v[134:135], v[130:131], -1.0 op_sel_hi:[1,0]
	s_nop 0
	v_pk_fma_f32 v[72:73], v[134:135], v[72:73], 1.0 op_sel_hi:[1,1,0]
	v_cvt_f32_f16_e32 v134, v92
	v_pk_mul_f32 v[72:73], v[72:73], v[90:91]
	v_cvt_f32_f16_sdwa v135, v92 dst_sel:DWORD dst_unused:UNUSED_PAD src0_sel:WORD_1
	v_cvt_pk_f16_f32 v71, v72, v73
	v_pk_add_f32 v[72:73], v[122:123], 1.0 op_sel_hi:[1,0]
	s_nop 0
	v_div_scale_f32 v92, s[0:1], v73, v73, 1.0
	v_rcp_f32_e32 v122, v92
	s_nop 0
	v_fma_f32 v123, -v92, v122, 1.0
	v_fmac_f32_e32 v122, v123, v122
	v_div_scale_f32 v123, vcc, 1.0, v73, 1.0
	v_mul_f32_e32 v136, v123, v122
	v_fma_f32 v137, -v92, v136, v123
	v_fmac_f32_e32 v136, v137, v122
	v_fma_f32 v92, -v92, v136, v123
	v_div_fmas_f32 v92, v92, v122, v136
	v_div_fixup_f32 v123, v92, v73, 1.0
	v_div_scale_f32 v73, s[0:1], v72, v72, 1.0
	v_rcp_f32_e32 v92, v73
	s_nop 0
	v_fma_f32 v122, -v73, v92, 1.0
	v_fmac_f32_e32 v92, v122, v92
	v_div_scale_f32 v122, vcc, 1.0, v72, 1.0
	v_mul_f32_e32 v136, v122, v92
	v_fma_f32 v137, -v73, v136, v122
	v_fmac_f32_e32 v136, v137, v92
	v_fma_f32 v73, -v73, v136, v122
	v_div_fmas_f32 v73, v73, v92, v136
	v_div_fixup_f32 v122, v73, v72, 1.0
	v_pk_add_f32 v[72:73], v[122:123], -1.0 op_sel_hi:[1,0]
	v_cvt_f32_f16_e32 v92, v93
	v_pk_fma_f32 v[66:67], v[72:73], v[66:67], 1.0 op_sel_hi:[1,1,0]
	v_cvt_f32_f16_sdwa v93, v93 dst_sel:DWORD dst_unused:UNUSED_PAD src0_sel:WORD_1
	v_pk_mul_f32 v[66:67], v[66:67], v[134:135]
	v_pk_mul_f32 v[84:85], v[84:85], v[92:93]
	v_cvt_pk_f16_f32 v72, v66, v67
	v_pk_add_f32 v[66:67], v[116:117], 1.0 op_sel_hi:[1,0]
	s_nop 0
	v_div_scale_f32 v73, s[0:1], v67, v67, 1.0
	v_rcp_f32_e32 v116, v73
	s_nop 0
	v_fma_f32 v117, -v73, v116, 1.0
	v_fmac_f32_e32 v116, v117, v116
	v_div_scale_f32 v117, vcc, 1.0, v67, 1.0
	v_mul_f32_e32 v136, v117, v116
	v_fma_f32 v137, -v73, v136, v117
	v_fmac_f32_e32 v136, v137, v116
	v_fma_f32 v73, -v73, v136, v117
	v_div_fmas_f32 v73, v73, v116, v136
	v_div_fixup_f32 v67, v73, v67, 1.0
	v_div_scale_f32 v73, s[0:1], v66, v66, 1.0
	v_rcp_f32_e32 v116, v73
	s_nop 0
	v_fma_f32 v117, -v73, v116, 1.0
	v_fmac_f32_e32 v116, v117, v116
	v_div_scale_f32 v117, vcc, 1.0, v66, 1.0
	v_mul_f32_e32 v136, v117, v116
	v_fma_f32 v137, -v73, v136, v117
	v_fmac_f32_e32 v136, v137, v116
	v_fma_f32 v73, -v73, v136, v117
	v_div_fmas_f32 v73, v73, v116, v136
	v_div_fixup_f32 v66, v73, v66, 1.0
	v_pk_add_f32 v[116:117], v[66:67], -1.0 op_sel_hi:[1,0]
	s_nop 0
	v_pk_fma_f32 v[68:69], v[116:117], v[68:69], 1.0 op_sel_hi:[1,1,0]
	s_nop 0
	v_pk_mul_f32 v[68:69], v[68:69], v[92:93]
	v_lshlrev_b64 v[92:93], 12, v[106:107]
	v_cvt_pk_f16_f32 v73, v68, v69
	global_store_dwordx4 v[114:115], v[70:73], off
	v_pk_mul_f32 v[68:69], v[86:87], v[132:133]
	v_pk_mul_f32 v[86:87], v[84:85], v[84:85]
	v_pk_mul_f32 v[72:73], v[82:83], v[134:135]
	v_pk_mul_f32 v[70:71], v[88:89], v[90:91]
	v_pk_mul_f32 v[82:83], v[72:73], v[72:73]
	v_pk_fma_f32 v[86:87], v[70:71], v[70:71], v[86:87]
	v_pk_fma_f32 v[82:83], v[68:69], v[68:69], v[82:83]
	s_nop 0
	v_add_f32_e32 v82, v82, v83
	v_add_f32_e32 v82, v86, v82
	v_add_f32_e32 v82, v87, v82
	v_add_f32_e32 v82, v82, v118
	v_add_f32_e32 v82, v119, v82
	v_add_f32_e32 v82, v120, v82
	v_add_f32_e32 v82, v121, v82
	ds_bpermute_b32 v83, v206, v82
	s_waitcnt lgkmcnt(0)
;     __device__ __forceinline__ void body_a(const f32x4 (&acc)[2][2][4][2], int row0, int cb0) const {
;     ...
;                 ss += __shfl_xor(ss, 16); ss += __shfl_xor(ss, 32);
;                 const float inv = 1.0f / fmaxf(sqrtf(ss), 1e-12f);
; #pragma unroll
;                 for (int bj = 0; bj < 2; ++bj) {
;                     const int c = cb0 + 32 * bj;
;                     const f32x4 p0 = *(const f32x4*)(k_a + c), p1 = *(const f32x4*)(k_a + c + 4);
;                     f32x4 ko0, ko1, ao0, ao1, bo0, bo1;
; #pragma unroll
;                     for (int e = 0; e < 4; ++e) {
;                         ko0[e] = kv[bj][e] * (1.0f + (a[bj][e] - 1.0f) * p0[e]); ko1[e] = kv[bj][4 + e] * (1.0f + (a[bj][4 + e] - 1.0f) * p1[e]);
;                         const float n0_ = kk[bj][e] * inv, n1_ = kk[bj][4 + e] * inv;
;                         ao0[e] = -n0_; ao1[e] = -n1_; bo0[e] = n0_ * a[bj][e]; bo1[e] = n1_ * a[bj][4 + e];
;                     }
;                     *(u32x4*)(C1 + row * LDC1 + 2048 + c) = pack8(ko0, ko1);
;                     *(u32x4*)(AA + row * DM + c) = pack8(ao0, ao1);
;                     *(u32x4*)(Ab + row * DM + c) = pack8(bo0, bo1);
	v_add_f32_e32 v82, v82, v83
	ds_bpermute_b32 v83, v207, v82
	s_waitcnt lgkmcnt(0)
	v_add_f32_e32 v82, v82, v83
	v_cmp_gt_f32_e32 vcc, s4, v82
	v_mul_f32_e32 v83, 0x4f800000, v82
	s_nop 0
	v_cndmask_b32_e32 v82, v82, v83, vcc
	v_sqrt_f32_e32 v83, v82
	s_nop 0
	v_add_u32_e32 v86, -1, v83
	v_fma_f32 v87, -v86, v83, v82
	v_cmp_ge_f32_e64 s[0:1], 0, v87
	v_add_u32_e32 v87, 1, v83
	s_nop 0
	v_cndmask_b32_e64 v86, v83, v86, s[0:1]
	v_fma_f32 v83, -v87, v83, v82
	v_cmp_lt_f32_e64 s[0:1], 0, v83
	s_nop 1
	v_cndmask_b32_e64 v83, v86, v87, s[0:1]
	v_mul_f32_e32 v86, 0x37800000, v83
	v_cndmask_b32_e32 v83, v83, v86, vcc
	v_cmp_class_f32_e32 vcc, v82, v244
	s_nop 1
	v_cndmask_b32_e32 v82, v83, v82, vcc
	v_max_f32_e32 v82, 0x2b8cbccc, v82
	v_div_scale_f32 v83, s[0:1], v82, v82, 1.0
	v_rcp_f32_e32 v86, v83
	s_nop 0
	v_fma_f32 v87, -v83, v86, 1.0
	v_fmac_f32_e32 v86, v87, v86
	v_div_scale_f32 v87, vcc, 1.0, v82, 1.0
	v_mul_f32_e32 v88, v87, v86
	v_fma_f32 v89, -v83, v88, v87
	v_fmac_f32_e32 v88, v89, v86
	v_fma_f32 v83, -v83, v88, v87
	v_div_fmas_f32 v83, v83, v86, v88
	v_div_fixup_f32 v86, v83, v82, 1.0
	v_pk_mul_f32 v[90:91], v[70:71], v[86:87] op_sel_hi:[1,0]
	v_pk_mul_f32 v[88:89], v[68:69], v[86:87] op_sel_hi:[1,0]
	v_cvt_pk_f16_f32 v69, v90, v91
	v_cvt_pk_f16_f32 v68, v88, v89
	v_xor_b32_e32 v70, 0x8000, v69
	v_xor_b32_sdwa v69, s63, v69 dst_sel:DWORD dst_unused:UNUSED_PAD src0_sel:DWORD src1_sel:WORD_1
	v_pk_mul_f32 v[72:73], v[72:73], v[86:87] op_sel_hi:[1,0]
	v_pk_mul_f32 v[84:85], v[84:85], v[86:87] op_sel_hi:[1,0]
	v_perm_b32 v69, v69, v70, s33
	v_xor_b32_e32 v70, 0x8000, v68
	v_xor_b32_sdwa v68, s63, v68 dst_sel:DWORD dst_unused:UNUSED_PAD src0_sel:DWORD src1_sel:WORD_1
	v_perm_b32 v68, v68, v70, s33
	v_pk_add_f32 v[70:71], v[72:73], 0 neg_lo:[1,1] neg_hi:[1,1]
	v_pk_add_f32 v[82:83], v[84:85], 0 neg_lo:[1,1] neg_hi:[1,1]
	v_cvt_pk_f16_f32 v70, v70, v71
	v_cvt_pk_f16_f32 v71, v82, v83
	v_lshl_add_u64 v[82:83], s[10:11], 0, v[92:93]
	v_lshl_add_u64 v[82:83], v[82:83], 0, v[152:153]
	global_store_dwordx4 v[82:83], v[68:71], off
	v_fma_mixlo_f16 v87, v124, v88, 0
	v_mul_f32_e32 v106, v78, v86
	v_pk_mov_b32 v[68:69], v[124:125], v[130:131] op_sel:[1,0]
	v_pk_mov_b32 v[70:71], v[88:89], v[90:91] op_sel:[1,0]
	v_pk_mov_b32 v[88:89], v[90:91], v[72:73] op_sel:[1,0]
	v_pk_mul_f32 v[68:69], v[68:69], v[70:71]
	v_pk_mov_b32 v[70:71], v[130:131], v[122:123] op_sel:[1,0]
	v_cvt_pk_f16_f32 v69, v68, v69
	v_pk_mul_f32 v[70:71], v[70:71], v[88:89]
	v_pack_b32_f16 v68, v87, v69
	v_cvt_pk_f16_f32 v87, v70, v71
	v_pk_mov_b32 v[70:71], v[122:123], v[66:67] op_sel:[1,0]
	v_pk_mov_b32 v[72:73], v[72:73], v[84:85] op_sel:[1,0]
	v_alignbit_b32 v69, v87, v69, 16
	v_pk_mul_f32 v[70:71], v[70:71], v[72:73]
	v_pk_add_f32 v[88:89], v[112:113], 1.0 op_sel_hi:[1,0]
	v_cvt_pk_f16_f32 v66, v70, v71
	v_lshrrev_b32_e32 v71, 16, v66
	v_alignbit_b32 v70, v66, v87, 16
	v_fma_mixhi_f16 v71, v67, v85, 0
	v_lshl_add_u64 v[66:67], s[2:3], 0, v[92:93]
	v_lshl_add_u64 v[84:85], v[66:67], 0, v[152:153]
	global_store_dwordx4 v[84:85], v[68:71], off
	global_load_dwordx4 v[66:69], v[126:127], off offset:144
	s_nop 0
	global_load_dwordx4 v[70:73], v[126:127], off offset:128
	v_div_scale_f32 v90, s[0:1], v89, v89, 1.0
	v_rcp_f32_e32 v91, v90
	v_mul_f32_e32 v87, v81, v86
	v_fma_f32 v92, -v90, v91, 1.0
	v_fmac_f32_e32 v91, v92, v91
	v_div_scale_f32 v92, vcc, 1.0, v89, 1.0
	v_mul_f32_e32 v93, v92, v91
	v_fma_f32 v107, -v90, v93, v92
	v_fmac_f32_e32 v93, v107, v91
	v_fma_f32 v90, -v90, v93, v92
	v_div_fmas_f32 v90, v90, v91, v93
	v_div_fixup_f32 v89, v90, v89, 1.0
	v_div_scale_f32 v90, s[0:1], v88, v88, 1.0
	v_rcp_f32_e32 v91, v90
	s_nop 0
	v_fma_f32 v92, -v90, v91, 1.0
	v_fmac_f32_e32 v91, v92, v91
	v_div_scale_f32 v92, vcc, 1.0, v88, 1.0
	v_mul_f32_e32 v93, v92, v91
	v_fma_f32 v107, -v90, v93, v92
	v_fmac_f32_e32 v93, v107, v91
	v_fma_f32 v90, -v90, v93, v92
	v_div_fmas_f32 v90, v90, v91, v93
	v_div_fixup_f32 v88, v90, v88, 1.0
	v_pk_add_f32 v[90:91], v[88:89], -1.0 op_sel_hi:[1,0]
	s_waitcnt vmcnt(0)
	v_pk_fma_f32 v[70:71], v[90:91], v[70:71], 1.0 op_sel_hi:[1,1,0]
	s_nop 0
	v_pk_mul_f32 v[70:71], v[70:71], v[110:111]
	v_pk_add_f32 v[90:91], v[108:109], 1.0 op_sel_hi:[1,0]
	v_cvt_pk_f16_f32 v70, v70, v71
	v_div_scale_f32 v71, s[0:1], v91, v91, 1.0
	v_rcp_f32_e32 v92, v71
	s_nop 0
	v_fma_f32 v93, -v71, v92, 1.0
	v_fmac_f32_e32 v92, v93, v92
	v_div_scale_f32 v93, vcc, 1.0, v91, 1.0
	v_mul_f32_e32 v107, v93, v92
	v_fma_f32 v108, -v71, v107, v93
	v_fmac_f32_e32 v107, v108, v92
	v_fma_f32 v71, -v71, v107, v93
	v_div_fmas_f32 v71, v71, v92, v107
	v_div_fixup_f32 v91, v71, v91, 1.0
	v_div_scale_f32 v71, s[0:1], v90, v90, 1.0
	v_rcp_f32_e32 v92, v71
	s_nop 0
	v_fma_f32 v93, -v71, v92, 1.0
	v_fmac_f32_e32 v92, v93, v92
	v_div_scale_f32 v93, vcc, 1.0, v90, 1.0
	v_mul_f32_e32 v107, v93, v92
	v_fma_f32 v108, -v71, v107, v93
	v_fmac_f32_e32 v107, v108, v92
	v_fma_f32 v71, -v71, v107, v93
	v_div_fmas_f32 v71, v71, v92, v107
	v_div_fixup_f32 v90, v71, v90, 1.0
	v_pk_add_f32 v[92:93], v[90:91], -1.0 op_sel_hi:[1,0]
	s_nop 0
	v_pk_fma_f32 v[72:73], v[92:93], v[72:73], 1.0 op_sel_hi:[1,1,0]
	s_nop 0
	v_pk_mul_f32 v[72:73], v[72:73], v[104:105]
	s_nop 0
	v_cvt_pk_f16_f32 v71, v72, v73
	v_pk_add_f32 v[72:73], v[102:103], 1.0 op_sel_hi:[1,0]
	s_nop 0
	v_div_scale_f32 v92, s[0:1], v73, v73, 1.0
	v_rcp_f32_e32 v93, v92
	s_nop 0
	v_fma_f32 v102, -v92, v93, 1.0
	v_fmac_f32_e32 v93, v102, v93
	v_div_scale_f32 v102, vcc, 1.0, v73, 1.0
	v_mul_f32_e32 v103, v102, v93
	v_fma_f32 v104, -v92, v103, v102
	v_fmac_f32_e32 v103, v104, v93
	v_fma_f32 v92, -v92, v103, v102
	v_div_fmas_f32 v92, v92, v93, v103
; __device__ __forceinline__ float sigmoidf_(float x) { return 1.0f / (1.0f + __expf(-x)); }
;     __device__ __forceinline__ void body_a(const f32x4 (&acc)[2][2][4][2], int row0, int cb0) const {
;     ...
;                 const size_t row = (size_t)(row0 + ai * 128 + m * 16);
;                 asm volatile("" ::: "memory");
;                 float a[2][8], kv[2][8], kk[2][8]; float ss = 0.f;
; #pragma unroll
;                 for (int bj = 0; bj < 2; ++bj) {
;                     const int c = cb0 + 32 * bj;
;                     const f32x4 b0 = *(const f32x4*)(a0 + c), b1 = *(const f32x4*)(a0 + c + 4), q0 = *(const f32x4*)(k_k + c), q1 = *(const f32x4*)(k_k + c + 4);
;                     const h16x8 kh = *(const h16x8*)(C1 + row * LDC1 + 2048 + c);
; #pragma unroll
;                     for (int e = 0; e < 4; ++e) {
;                         a[bj][e] = sigmoidf_(acc[ai][bj][m][0][e] + b0[e]); a[bj][4 + e] = sigmoidf_(acc[ai][bj][m][1][e] + b1[e]);
;                         kv[bj][e] = (float)kh[e]; kv[bj][4 + e] = (float)kh[4 + e];
;                         kk[bj][e] = kv[bj][e] * q0[e]; kk[bj][4 + e] = kv[bj][4 + e] * q1[e];
;                         ss += kk[bj][e] * kk[bj][e] + kk[bj][4 + e] * kk[bj][4 + e];
;     ...
;                 for (int bj = 0; bj < 2; ++bj) {
;                     const int c = cb0 + 32 * bj;
;                     const f32x4 p0 = *(const f32x4*)(k_a + c), p1 = *(const f32x4*)(k_a + c + 4);
;                     f32x4 ko0, ko1, ao0, ao1, bo0, bo1;
; #pragma unroll
;                     for (int e = 0; e < 4; ++e) {
;                         ko0[e] = kv[bj][e] * (1.0f + (a[bj][e] - 1.0f) * p0[e]); ko1[e] = kv[bj][4 + e] * (1.0f + (a[bj][4 + e] - 1.0f) * p1[e]);
;                         const float n0_ = kk[bj][e] * inv, n1_ = kk[bj][4 + e] * inv;
;                         ao0[e] = -n0_; ao1[e] = -n1_; bo0[e] = n0_ * a[bj][e]; bo1[e] = n1_ * a[bj][4 + e];
;                     }
;                     *(u32x4*)(C1 + row * LDC1 + 2048 + c) = pack8(ko0, ko1);
;                     *(u32x4*)(AA + row * DM + c) = pack8(ao0, ao1);
;                     *(u32x4*)(Ab + row * DM + c) = pack8(bo0, bo1);
	v_div_fixup_f32 v93, v92, v73, 1.0
	v_div_scale_f32 v73, s[0:1], v72, v72, 1.0
	v_rcp_f32_e32 v92, v73
	s_nop 0
	v_fma_f32 v102, -v73, v92, 1.0
	v_fmac_f32_e32 v92, v102, v92
	v_div_scale_f32 v102, vcc, 1.0, v72, 1.0
	v_mul_f32_e32 v103, v102, v92
	v_fma_f32 v104, -v73, v103, v102
	v_fmac_f32_e32 v103, v104, v92
	v_fma_f32 v73, -v73, v103, v102
	v_div_fmas_f32 v73, v73, v92, v103
	v_div_fixup_f32 v92, v73, v72, 1.0
	v_pk_add_f32 v[72:73], v[92:93], -1.0 op_sel_hi:[1,0]
	s_nop 0
	v_pk_fma_f32 v[66:67], v[72:73], v[66:67], 1.0 op_sel_hi:[1,1,0]
	s_nop 0
	v_pk_mul_f32 v[66:67], v[66:67], v[100:101]
	s_nop 0
	v_cvt_pk_f16_f32 v72, v66, v67
	v_pk_add_f32 v[66:67], v[98:99], 1.0 op_sel_hi:[1,0]
	s_nop 0
	v_div_scale_f32 v73, s[0:1], v67, v67, 1.0
	v_rcp_f32_e32 v98, v73
	s_nop 0
	v_fma_f32 v99, -v73, v98, 1.0
	v_fmac_f32_e32 v98, v99, v98
	v_div_scale_f32 v99, vcc, 1.0, v67, 1.0
	v_mul_f32_e32 v100, v99, v98
	v_fma_f32 v101, -v73, v100, v99
	v_fmac_f32_e32 v100, v101, v98
	v_fma_f32 v73, -v73, v100, v99
	v_div_fmas_f32 v73, v73, v98, v100
	v_div_fixup_f32 v99, v73, v67, 1.0
	v_div_scale_f32 v67, s[0:1], v66, v66, 1.0
	v_rcp_f32_e32 v73, v67
	s_nop 0
	v_fma_f32 v98, -v67, v73, 1.0
	v_fmac_f32_e32 v73, v98, v73
	v_div_scale_f32 v98, vcc, 1.0, v66, 1.0
	v_mul_f32_e32 v100, v98, v73
	v_fma_f32 v101, -v67, v100, v98
	v_fmac_f32_e32 v100, v101, v73
	v_fma_f32 v67, -v67, v100, v98
	v_div_fmas_f32 v67, v67, v73, v100
	v_div_fixup_f32 v98, v67, v66, 1.0
	v_pk_add_f32 v[66:67], v[98:99], -1.0 op_sel_hi:[1,0]
	s_nop 0
	v_pk_fma_f32 v[66:67], v[66:67], v[68:69], 1.0 op_sel_hi:[1,1,0]
	v_cvt_f16_f32_e64 v68, -v106
	v_pk_mul_f32 v[66:67], v[66:67], v[96:97]
	s_nop 0
	v_cvt_pk_f16_f32 v73, v66, v67
	v_pk_mov_b32 v[66:67], v[78:79], v[94:95] op_sel:[1,0]
	global_store_dwordx4 v[74:75], v[70:73], off
	s_nop 1
	v_pk_mul_f32 v[70:71], v[66:67], v[86:87] op_sel_hi:[1,0]
	s_nop 0
	v_cvt_pk_f16_f32 v67, v70, v71
	v_pack_b32_f16 v66, v68, -v67
	v_pk_mov_b32 v[68:69], v[94:95], v[76:77] op_sel:[1,0]
	v_xor_b32_sdwa v67, s63, v67 dst_sel:DWORD dst_unused:UNUSED_PAD src0_sel:DWORD src1_sel:WORD_1
	v_pk_mul_f32 v[72:73], v[68:69], v[86:87] op_sel_hi:[1,0]
	s_nop 0
	v_cvt_pk_f16_f32 v68, v72, v73
	v_xor_b32_e32 v69, 0x8000, v68
	v_perm_b32 v67, v69, v67, s33
	v_xor_b32_sdwa v78, s63, v68 dst_sel:DWORD dst_unused:UNUSED_PAD src0_sel:DWORD src1_sel:WORD_1
	v_pk_mov_b32 v[68:69], v[76:77], v[80:81] op_sel:[1,0]
	v_cvt_f16_f32_e64 v76, -v87
	v_pk_mul_f32 v[74:75], v[68:69], v[86:87] op_sel_hi:[1,0]
	s_nop 0
	v_cvt_pk_f16_f32 v69, v74, v75
	v_xor_b32_e32 v68, 0x8000, v69
	v_xor_b32_sdwa v69, s63, v69 dst_sel:DWORD dst_unused:UNUSED_PAD src0_sel:DWORD src1_sel:WORD_1
	v_perm_b32 v68, v68, v78, s33
	v_perm_b32 v69, v76, v69, s33
	global_store_dwordx4 v[82:83], v[66:69], off offset:64
	s_nop 1
	v_pk_mov_b32 v[66:67], v[88:89], v[90:91] op_sel:[1,0]
	v_fma_mixlo_f16 v68, v88, v106, 0
	v_pk_mul_f32 v[66:67], v[66:67], v[70:71]
	s_nop 0
	v_cvt_pk_f16_f32 v67, v66, v67
	v_pack_b32_f16 v66, v68, v67
	v_pk_mov_b32 v[68:69], v[90:91], v[92:93] op_sel:[1,0]
	s_nop 0
	v_pk_mul_f32 v[68:69], v[68:69], v[72:73]
	s_nop 0
	v_cvt_pk_f16_f32 v70, v68, v69
	v_pk_mov_b32 v[68:69], v[92:93], v[98:99] op_sel:[1,0]
	v_alignbit_b32 v67, v70, v67, 16
	v_pk_mul_f32 v[68:69], v[68:69], v[74:75]
	s_nop 0
	v_cvt_pk_f16_f32 v69, v68, v69
	v_alignbit_b32 v68, v69, v70, 16
	v_lshrrev_b32_e32 v69, 16, v69
	v_fma_mixhi_f16 v69, v99, v87, 0
	global_store_dwordx4 v[84:85], v[66:69], off offset:64
	v_add_u32_e32 v90, 0x80, v158
	s_nop 0
	v_mad_i64_i32 v[66:67], s[0:1], v90, s5, v[160:161]
	v_lshl_add_u64 v[86:87], v[66:67], 0, s[6:7]
	global_load_dwordx4 v[78:81], v[154:155], off offset:16
	global_load_dwordx4 v[82:85], v[154:155], off
	global_load_dwordx4 v[66:69], v[156:157], off offset:16
	global_load_dwordx4 v[70:73], v[156:157], off
	v_lshl_add_u64 v[98:99], v[86:87], 0, v[152:153]
	global_load_dwordx4 v[74:77], v[98:99], off
	v_ashrrev_i32_e32 v91, 31, v90
	s_waitcnt vmcnt(4)
	v_add_f32_e32 v58, v58, v78
	v_mul_f32_e32 v58, 0xbfb8aa3b, v58
	v_exp_f32_e32 v106, v58
	s_waitcnt vmcnt(3)
	v_add_f32_e32 v58, v63, v83
	v_mul_f32_e32 v58, 0xbfb8aa3b, v58
	v_exp_f32_e32 v109, v58
	v_add_f32_e32 v58, v59, v79
	v_mul_f32_e32 v58, 0xbfb8aa3b, v58
	v_exp_f32_e32 v107, v58
	v_add_f32_e32 v58, v64, v84
	v_mul_f32_e32 v58, 0xbfb8aa3b, v58
	v_exp_f32_e32 v110, v58
	v_add_f32_e32 v58, v60, v80
	v_mul_f32_e32 v58, 0xbfb8aa3b, v58
	v_exp_f32_e32 v100, v58
	v_add_f32_e32 v58, v65, v85
	v_mul_f32_e32 v58, 0xbfb8aa3b, v58
	v_exp_f32_e32 v111, v58
	v_add_f32_e32 v58, v61, v81
	v_add_f32_e32 v62, v62, v82
	v_mul_f32_e32 v58, 0xbfb8aa3b, v58
	v_mul_f32_e32 v62, 0xbfb8aa3b, v62
	v_exp_f32_e32 v101, v58
	v_lshl_add_u64 v[58:59], v[86:87], 0, v[128:129]
	v_exp_f32_e32 v108, v62
	global_load_dwordx4 v[62:65], v[154:155], off offset:144
	global_load_dwordx4 v[78:81], v[154:155], off offset:128
	global_load_dwordx4 v[102:105], v[156:157], off offset:144
	global_load_dwordx4 v[112:115], v[156:157], off offset:128
	global_load_dwordx4 v[116:119], v[58:59], off
	v_pk_add_f32 v[110:111], v[110:111], 1.0 op_sel_hi:[1,0]
	v_pk_add_f32 v[108:109], v[108:109], 1.0 op_sel_hi:[1,0]
	s_waitcnt vmcnt(4)
	v_add_f32_e32 v50, v50, v62
	v_mul_f32_e32 v50, 0xbfb8aa3b, v50
	v_exp_f32_e32 v86, v50
	s_waitcnt vmcnt(3)
	v_add_f32_e32 v50, v55, v79
	s_waitcnt vmcnt(0)
; __device__ __forceinline__ float sigmoidf_(float x) { return 1.0f / (1.0f + __expf(-x)); }
;     __device__ __forceinline__ void body_a(const f32x4 (&acc)[2][2][4][2], int row0, int cb0) const {
;     ...
;                     const f32x4 b0 = *(const f32x4*)(a0 + c), b1 = *(const f32x4*)(a0 + c + 4), q0 = *(const f32x4*)(k_k + c), q1 = *(const f32x4*)(k_k + c + 4);
;                     const h16x8 kh = *(const h16x8*)(C1 + row * LDC1 + 2048 + c);
; #pragma unroll
;                     for (int e = 0; e < 4; ++e) {
;                         a[bj][e] = sigmoidf_(acc[ai][bj][m][0][e] + b0[e]); a[bj][4 + e] = sigmoidf_(acc[ai][bj][m][1][e] + b1[e]);
;                         kv[bj][e] = (float)kh[e]; kv[bj][4 + e] = (float)kh[4 + e];
;                         kk[bj][e] = kv[bj][e] * q0[e]; kk[bj][4 + e] = kv[bj][4 + e] * q1[e];
;                         ss += kk[bj][e] * kk[bj][e] + kk[bj][4 + e] * kk[bj][4 + e];
;                     }
;                 }
;                 ss += __shfl_xor(ss, 16); ss += __shfl_xor(ss, 32);
;     ...
;                         ko0[e] = kv[bj][e] * (1.0f + (a[bj][e] - 1.0f) * p0[e]); ko1[e] = kv[bj][4 + e] * (1.0f + (a[bj][4 + e] - 1.0f) * p1[e]);
;                         const float n0_ = kk[bj][e] * inv, n1_ = kk[bj][4 + e] * inv;
;                         ao0[e] = -n0_; ao1[e] = -n1_; bo0[e] = n0_ * a[bj][e]; bo1[e] = n1_ * a[bj][4 + e];
;                     }
;                     *(u32x4*)(C1 + row * LDC1 + 2048 + c) = pack8(ko0, ko1);
	v_cvt_f32_f16_e32 v84, v118
	v_cvt_f32_f16_sdwa v85, v118 dst_sel:DWORD dst_unused:UNUSED_PAD src0_sel:WORD_1
	v_cvt_f32_f16_e32 v94, v116
	v_cvt_f32_f16_sdwa v95, v116 dst_sel:DWORD dst_unused:UNUSED_PAD src0_sel:WORD_1
	v_mul_f32_e32 v50, 0xbfb8aa3b, v50
	v_exp_f32_e32 v97, v50
	v_add_f32_e32 v50, v51, v63
	v_mul_f32_e32 v50, 0xbfb8aa3b, v50
	v_pk_mul_f32 v[60:61], v[102:103], v[84:85]
	v_exp_f32_e32 v87, v50
	v_pk_mul_f32 v[62:63], v[112:113], v[94:95]
	v_pk_mul_f32 v[50:51], v[60:61], v[60:61]
	v_cvt_f32_f16_e32 v88, v117
	v_pk_fma_f32 v[102:103], v[62:63], v[62:63], v[50:51]
	v_add_f32_e32 v50, v56, v80
	v_mul_f32_e32 v50, 0xbfb8aa3b, v50
	v_exp_f32_e32 v92, v50
	v_add_f32_e32 v50, v52, v64
	v_mul_f32_e32 v50, 0xbfb8aa3b, v50
	v_exp_f32_e32 v82, v50
	v_add_f32_e32 v50, v57, v81
	v_cvt_f32_f16_e32 v80, v119
	v_cvt_f32_f16_sdwa v81, v119 dst_sel:DWORD dst_unused:UNUSED_PAD src0_sel:WORD_1
	v_cvt_f32_f16_sdwa v89, v117 dst_sel:DWORD dst_unused:UNUSED_PAD src0_sel:WORD_1
	v_mul_f32_e32 v50, 0xbfb8aa3b, v50
	v_exp_f32_e32 v93, v50
	v_add_f32_e32 v50, v53, v65
	v_add_f32_e32 v54, v54, v78
	v_mul_f32_e32 v50, 0xbfb8aa3b, v50
	v_pk_mul_f32 v[64:65], v[104:105], v[80:81]
	v_mul_f32_e32 v54, 0xbfb8aa3b, v54
	v_exp_f32_e32 v83, v50
	v_pk_mul_f32 v[78:79], v[114:115], v[88:89]
	v_pk_mul_f32 v[50:51], v[64:65], v[64:65]
	v_exp_f32_e32 v96, v54
	v_pk_fma_f32 v[104:105], v[78:79], v[78:79], v[50:51]
	global_load_dwordx4 v[50:53], v[126:127], off offset:16
	global_load_dwordx4 v[54:57], v[126:127], off
	v_cvt_f32_f16_e32 v112, v74
	v_cvt_f32_f16_sdwa v113, v74 dst_sel:DWORD dst_unused:UNUSED_PAD src0_sel:WORD_1
	v_div_scale_f32 v74, s[0:1], v109, v109, 1.0
	v_rcp_f32_e32 v114, v74
	s_nop 0
	v_fma_f32 v115, -v74, v114, 1.0
	v_fmac_f32_e32 v114, v115, v114
	v_div_scale_f32 v115, vcc, 1.0, v109, 1.0
	v_mul_f32_e32 v116, v115, v114
	v_fma_f32 v117, -v74, v116, v115
	v_fmac_f32_e32 v116, v117, v114
	v_fma_f32 v74, -v74, v116, v115
	v_div_fmas_f32 v74, v74, v114, v116
	v_div_fixup_f32 v109, v74, v109, 1.0
	v_div_scale_f32 v74, s[0:1], v108, v108, 1.0
	v_rcp_f32_e32 v114, v74
	s_nop 0
	v_fma_f32 v115, -v74, v114, 1.0
	v_fmac_f32_e32 v114, v115, v114
	v_div_scale_f32 v115, vcc, 1.0, v108, 1.0
	v_mul_f32_e32 v116, v115, v114
	v_fma_f32 v117, -v74, v116, v115
	v_fmac_f32_e32 v116, v117, v114
	v_fma_f32 v74, -v74, v116, v115
	v_div_fmas_f32 v74, v74, v114, v116
	v_div_fixup_f32 v108, v74, v108, 1.0
	v_pk_add_f32 v[114:115], v[108:109], -1.0 op_sel_hi:[1,0]
	v_cvt_f32_f16_e32 v74, v75
	v_cvt_f32_f16_sdwa v75, v75 dst_sel:DWORD dst_unused:UNUSED_PAD src0_sel:WORD_1
	s_waitcnt vmcnt(0)
	v_pk_fma_f32 v[54:55], v[114:115], v[54:55], 1.0 op_sel_hi:[1,1,0]
	s_nop 0
	v_pk_mul_f32 v[54:55], v[54:55], v[112:113]
	s_nop 0
	v_cvt_pk_f16_f32 v54, v54, v55
	v_div_scale_f32 v55, s[0:1], v111, v111, 1.0
	v_rcp_f32_e32 v114, v55
	s_nop 0
	v_fma_f32 v115, -v55, v114, 1.0
	v_fmac_f32_e32 v114, v115, v114
	v_div_scale_f32 v115, vcc, 1.0, v111, 1.0
	v_mul_f32_e32 v116, v115, v114
	v_fma_f32 v117, -v55, v116, v115
	v_fmac_f32_e32 v116, v117, v114
	v_fma_f32 v55, -v55, v116, v115
	v_div_fmas_f32 v55, v55, v114, v116
	v_div_fixup_f32 v111, v55, v111, 1.0
	v_div_scale_f32 v55, s[0:1], v110, v110, 1.0
	v_rcp_f32_e32 v114, v55
	s_nop 0
	v_fma_f32 v115, -v55, v114, 1.0
	v_fmac_f32_e32 v114, v115, v114
	v_div_scale_f32 v115, vcc, 1.0, v110, 1.0
	v_mul_f32_e32 v116, v115, v114
	v_fma_f32 v117, -v55, v116, v115
	v_fmac_f32_e32 v116, v117, v114
	v_fma_f32 v55, -v55, v116, v115
	v_div_fmas_f32 v55, v55, v114, v116
	v_div_fixup_f32 v110, v55, v110, 1.0
	v_pk_add_f32 v[114:115], v[110:111], -1.0 op_sel_hi:[1,0]
	s_nop 0
	v_pk_fma_f32 v[56:57], v[114:115], v[56:57], 1.0 op_sel_hi:[1,1,0]
	v_cvt_f32_f16_e32 v114, v76
	v_pk_mul_f32 v[56:57], v[56:57], v[74:75]
	v_cvt_f32_f16_sdwa v115, v76 dst_sel:DWORD dst_unused:UNUSED_PAD src0_sel:WORD_1
	v_cvt_pk_f16_f32 v55, v56, v57
	v_pk_add_f32 v[56:57], v[106:107], 1.0 op_sel_hi:[1,0]
	s_nop 0
	v_div_scale_f32 v76, s[0:1], v57, v57, 1.0
	v_rcp_f32_e32 v106, v76
	s_nop 0
	v_fma_f32 v107, -v76, v106, 1.0
	v_fmac_f32_e32 v106, v107, v106
	v_div_scale_f32 v107, vcc, 1.0, v57, 1.0
	v_mul_f32_e32 v116, v107, v106
	v_fma_f32 v117, -v76, v116, v107
	v_fmac_f32_e32 v116, v117, v106
	v_fma_f32 v76, -v76, v116, v107
	v_div_fmas_f32 v76, v76, v106, v116
	v_div_fixup_f32 v107, v76, v57, 1.0
	v_div_scale_f32 v57, s[0:1], v56, v56, 1.0
	v_rcp_f32_e32 v76, v57
	s_nop 0
	v_fma_f32 v106, -v57, v76, 1.0
	v_fmac_f32_e32 v76, v106, v76
	v_div_scale_f32 v106, vcc, 1.0, v56, 1.0
	v_mul_f32_e32 v116, v106, v76
	v_fma_f32 v117, -v57, v116, v106
	v_fmac_f32_e32 v116, v117, v76
	v_fma_f32 v57, -v57, v116, v106
	v_div_fmas_f32 v57, v57, v76, v116
	v_div_fixup_f32 v106, v57, v56, 1.0
	v_pk_add_f32 v[56:57], v[106:107], -1.0 op_sel_hi:[1,0]
	v_cvt_f32_f16_e32 v76, v77
	v_pk_fma_f32 v[50:51], v[56:57], v[50:51], 1.0 op_sel_hi:[1,1,0]
	v_cvt_f32_f16_sdwa v77, v77 dst_sel:DWORD dst_unused:UNUSED_PAD src0_sel:WORD_1
	v_pk_mul_f32 v[50:51], v[50:51], v[114:115]
	v_pk_mul_f32 v[68:69], v[68:69], v[76:77]
	v_cvt_pk_f16_f32 v56, v50, v51
	v_pk_add_f32 v[50:51], v[100:101], 1.0 op_sel_hi:[1,0]
	s_nop 0
	v_div_scale_f32 v57, s[0:1], v51, v51, 1.0
	v_rcp_f32_e32 v100, v57
	s_nop 0
	v_fma_f32 v101, -v57, v100, 1.0
	v_fmac_f32_e32 v100, v101, v100
	v_div_scale_f32 v101, vcc, 1.0, v51, 1.0
	v_mul_f32_e32 v116, v101, v100
	v_fma_f32 v117, -v57, v116, v101
	v_fmac_f32_e32 v116, v117, v100
	v_fma_f32 v57, -v57, v116, v101
	v_div_fmas_f32 v57, v57, v100, v116
	v_div_fixup_f32 v51, v57, v51, 1.0
	v_div_scale_f32 v57, s[0:1], v50, v50, 1.0
	v_rcp_f32_e32 v100, v57
	s_nop 0
	v_fma_f32 v101, -v57, v100, 1.0
	v_fmac_f32_e32 v100, v101, v100
	v_div_scale_f32 v101, vcc, 1.0, v50, 1.0
	v_mul_f32_e32 v116, v101, v100
	v_fma_f32 v117, -v57, v116, v101
	v_fmac_f32_e32 v116, v117, v100
	v_fma_f32 v57, -v57, v116, v101
	v_div_fmas_f32 v57, v57, v100, v116
	v_div_fixup_f32 v50, v57, v50, 1.0
	v_pk_add_f32 v[100:101], v[50:51], -1.0 op_sel_hi:[1,0]
	s_nop 0
	v_pk_fma_f32 v[52:53], v[100:101], v[52:53], 1.0 op_sel_hi:[1,1,0]
	s_nop 0
	v_pk_mul_f32 v[52:53], v[52:53], v[76:77]
	v_lshlrev_b64 v[76:77], 12, v[90:91]
	v_cvt_pk_f16_f32 v57, v52, v53
	global_store_dwordx4 v[98:99], v[54:57], off
	v_pk_mul_f32 v[52:53], v[70:71], v[112:113]
	v_pk_mul_f32 v[70:71], v[68:69], v[68:69]
	v_pk_mul_f32 v[56:57], v[66:67], v[114:115]
	v_pk_mul_f32 v[54:55], v[72:73], v[74:75]
	v_pk_mul_f32 v[66:67], v[56:57], v[56:57]
	v_pk_fma_f32 v[70:71], v[54:55], v[54:55], v[70:71]
	v_pk_fma_f32 v[66:67], v[52:53], v[52:53], v[66:67]
	s_nop 0
	v_add_f32_e32 v66, v66, v67
	v_add_f32_e32 v66, v70, v66
	v_add_f32_e32 v66, v71, v66
	v_add_f32_e32 v66, v66, v102
	v_add_f32_e32 v66, v103, v66
	v_add_f32_e32 v66, v104, v66
	v_add_f32_e32 v66, v105, v66
	ds_bpermute_b32 v67, v206, v66
	s_waitcnt lgkmcnt(0)
;     __device__ __forceinline__ void body_a(const f32x4 (&acc)[2][2][4][2], int row0, int cb0) const {
;     ...
;                 ss += __shfl_xor(ss, 16); ss += __shfl_xor(ss, 32);
;                 const float inv = 1.0f / fmaxf(sqrtf(ss), 1e-12f);
; #pragma unroll
;                 for (int bj = 0; bj < 2; ++bj) {
;                     const int c = cb0 + 32 * bj;
;                     const f32x4 p0 = *(const f32x4*)(k_a + c), p1 = *(const f32x4*)(k_a + c + 4);
;                     f32x4 ko0, ko1, ao0, ao1, bo0, bo1;
; #pragma unroll
;                     for (int e = 0; e < 4; ++e) {
;                         ko0[e] = kv[bj][e] * (1.0f + (a[bj][e] - 1.0f) * p0[e]); ko1[e] = kv[bj][4 + e] * (1.0f + (a[bj][4 + e] - 1.0f) * p1[e]);
;                         const float n0_ = kk[bj][e] * inv, n1_ = kk[bj][4 + e] * inv;
;                         ao0[e] = -n0_; ao1[e] = -n1_; bo0[e] = n0_ * a[bj][e]; bo1[e] = n1_ * a[bj][4 + e];
;                     }
;                     *(u32x4*)(C1 + row * LDC1 + 2048 + c) = pack8(ko0, ko1);
;                     *(u32x4*)(AA + row * DM + c) = pack8(ao0, ao1);
;                     *(u32x4*)(Ab + row * DM + c) = pack8(bo0, bo1);
	v_add_f32_e32 v66, v66, v67
	ds_bpermute_b32 v67, v207, v66
	s_waitcnt lgkmcnt(0)
	v_add_f32_e32 v66, v66, v67
	v_cmp_gt_f32_e32 vcc, s4, v66
	v_mul_f32_e32 v67, 0x4f800000, v66
	s_nop 0
	v_cndmask_b32_e32 v66, v66, v67, vcc
	v_sqrt_f32_e32 v67, v66
	s_nop 0
	v_add_u32_e32 v70, -1, v67
	v_fma_f32 v71, -v70, v67, v66
	v_cmp_ge_f32_e64 s[0:1], 0, v71
	v_add_u32_e32 v71, 1, v67
	s_nop 0
	v_cndmask_b32_e64 v70, v67, v70, s[0:1]
	v_fma_f32 v67, -v71, v67, v66
	v_cmp_lt_f32_e64 s[0:1], 0, v67
	s_nop 1
	v_cndmask_b32_e64 v67, v70, v71, s[0:1]
	v_mul_f32_e32 v70, 0x37800000, v67
	v_cndmask_b32_e32 v67, v67, v70, vcc
	v_cmp_class_f32_e32 vcc, v66, v244
	s_nop 1
	v_cndmask_b32_e32 v66, v67, v66, vcc
	v_max_f32_e32 v66, 0x2b8cbccc, v66
	v_div_scale_f32 v67, s[0:1], v66, v66, 1.0
	v_rcp_f32_e32 v70, v67
	s_nop 0
	v_fma_f32 v71, -v67, v70, 1.0
	v_fmac_f32_e32 v70, v71, v70
	v_div_scale_f32 v71, vcc, 1.0, v66, 1.0
	v_mul_f32_e32 v72, v71, v70
	v_fma_f32 v73, -v67, v72, v71
	v_fmac_f32_e32 v72, v73, v70
	v_fma_f32 v67, -v67, v72, v71
	v_div_fmas_f32 v67, v67, v70, v72
	v_div_fixup_f32 v70, v67, v66, 1.0
	v_pk_mul_f32 v[74:75], v[54:55], v[70:71] op_sel_hi:[1,0]
	v_pk_mul_f32 v[72:73], v[52:53], v[70:71] op_sel_hi:[1,0]
	v_cvt_pk_f16_f32 v53, v74, v75
	v_cvt_pk_f16_f32 v52, v72, v73
	v_xor_b32_e32 v54, 0x8000, v53
	v_xor_b32_sdwa v53, s63, v53 dst_sel:DWORD dst_unused:UNUSED_PAD src0_sel:DWORD src1_sel:WORD_1
	v_pk_mul_f32 v[56:57], v[56:57], v[70:71] op_sel_hi:[1,0]
	v_pk_mul_f32 v[68:69], v[68:69], v[70:71] op_sel_hi:[1,0]
	v_perm_b32 v53, v53, v54, s33
	v_xor_b32_e32 v54, 0x8000, v52
	v_xor_b32_sdwa v52, s63, v52 dst_sel:DWORD dst_unused:UNUSED_PAD src0_sel:DWORD src1_sel:WORD_1
	v_perm_b32 v52, v52, v54, s33
	v_pk_add_f32 v[54:55], v[56:57], 0 neg_lo:[1,1] neg_hi:[1,1]
	v_pk_add_f32 v[66:67], v[68:69], 0 neg_lo:[1,1] neg_hi:[1,1]
	v_cvt_pk_f16_f32 v54, v54, v55
	v_cvt_pk_f16_f32 v55, v66, v67
	v_lshl_add_u64 v[66:67], s[10:11], 0, v[76:77]
	v_lshl_add_u64 v[66:67], v[66:67], 0, v[152:153]
	global_store_dwordx4 v[66:67], v[52:55], off
	v_fma_mixlo_f16 v71, v108, v72, 0
	v_mul_f32_e32 v90, v62, v70
	v_pk_mov_b32 v[52:53], v[108:109], v[110:111] op_sel:[1,0]
	v_pk_mov_b32 v[54:55], v[72:73], v[74:75] op_sel:[1,0]
	v_pk_mov_b32 v[72:73], v[74:75], v[56:57] op_sel:[1,0]
	v_pk_mul_f32 v[52:53], v[52:53], v[54:55]
	v_pk_mov_b32 v[54:55], v[110:111], v[106:107] op_sel:[1,0]
	v_cvt_pk_f16_f32 v53, v52, v53
	v_pk_mul_f32 v[54:55], v[54:55], v[72:73]
	v_pack_b32_f16 v52, v71, v53
	v_cvt_pk_f16_f32 v71, v54, v55
	v_pk_mov_b32 v[54:55], v[106:107], v[50:51] op_sel:[1,0]
	v_pk_mov_b32 v[56:57], v[56:57], v[68:69] op_sel:[1,0]
	v_alignbit_b32 v53, v71, v53, 16
	v_pk_mul_f32 v[54:55], v[54:55], v[56:57]
	v_pk_add_f32 v[72:73], v[96:97], 1.0 op_sel_hi:[1,0]
	v_cvt_pk_f16_f32 v50, v54, v55
	v_lshrrev_b32_e32 v55, 16, v50
	v_alignbit_b32 v54, v50, v71, 16
	v_fma_mixhi_f16 v55, v51, v69, 0
	v_lshl_add_u64 v[50:51], s[2:3], 0, v[76:77]
	v_lshl_add_u64 v[68:69], v[50:51], 0, v[152:153]
	global_store_dwordx4 v[68:69], v[52:55], off
	global_load_dwordx4 v[50:53], v[126:127], off offset:144
	s_nop 0
	global_load_dwordx4 v[54:57], v[126:127], off offset:128
	v_div_scale_f32 v74, s[0:1], v73, v73, 1.0
	v_rcp_f32_e32 v75, v74
	v_mul_f32_e32 v71, v65, v70
	v_fma_f32 v76, -v74, v75, 1.0
	v_fmac_f32_e32 v75, v76, v75
	v_div_scale_f32 v76, vcc, 1.0, v73, 1.0
	v_mul_f32_e32 v77, v76, v75
	v_fma_f32 v91, -v74, v77, v76
	v_fmac_f32_e32 v77, v91, v75
	v_fma_f32 v74, -v74, v77, v76
	v_div_fmas_f32 v74, v74, v75, v77
	v_div_fixup_f32 v73, v74, v73, 1.0
	v_div_scale_f32 v74, s[0:1], v72, v72, 1.0
	v_rcp_f32_e32 v75, v74
	s_nop 0
	v_fma_f32 v76, -v74, v75, 1.0
	v_fmac_f32_e32 v75, v76, v75
	v_div_scale_f32 v76, vcc, 1.0, v72, 1.0
	v_mul_f32_e32 v77, v76, v75
	v_fma_f32 v91, -v74, v77, v76
	v_fmac_f32_e32 v77, v91, v75
	v_fma_f32 v74, -v74, v77, v76
	v_div_fmas_f32 v74, v74, v75, v77
	v_div_fixup_f32 v72, v74, v72, 1.0
	v_pk_add_f32 v[74:75], v[72:73], -1.0 op_sel_hi:[1,0]
	s_waitcnt vmcnt(0)
	v_pk_fma_f32 v[54:55], v[74:75], v[54:55], 1.0 op_sel_hi:[1,1,0]
	s_nop 0
	v_pk_mul_f32 v[54:55], v[54:55], v[94:95]
	v_pk_add_f32 v[74:75], v[92:93], 1.0 op_sel_hi:[1,0]
	v_cvt_pk_f16_f32 v54, v54, v55
	v_div_scale_f32 v55, s[0:1], v75, v75, 1.0
	v_rcp_f32_e32 v76, v55
	s_nop 0
	v_fma_f32 v77, -v55, v76, 1.0
	v_fmac_f32_e32 v76, v77, v76
	v_div_scale_f32 v77, vcc, 1.0, v75, 1.0
	v_mul_f32_e32 v91, v77, v76
	v_fma_f32 v92, -v55, v91, v77
	v_fmac_f32_e32 v91, v92, v76
	v_fma_f32 v55, -v55, v91, v77
	v_div_fmas_f32 v55, v55, v76, v91
	v_div_fixup_f32 v75, v55, v75, 1.0
	v_div_scale_f32 v55, s[0:1], v74, v74, 1.0
	v_rcp_f32_e32 v76, v55
	s_nop 0
	v_fma_f32 v77, -v55, v76, 1.0
	v_fmac_f32_e32 v76, v77, v76
	v_div_scale_f32 v77, vcc, 1.0, v74, 1.0
	v_mul_f32_e32 v91, v77, v76
	v_fma_f32 v92, -v55, v91, v77
	v_fmac_f32_e32 v91, v92, v76
	v_fma_f32 v55, -v55, v91, v77
	v_div_fmas_f32 v55, v55, v76, v91
	v_div_fixup_f32 v74, v55, v74, 1.0
	v_pk_add_f32 v[76:77], v[74:75], -1.0 op_sel_hi:[1,0]
	s_nop 0
	v_pk_fma_f32 v[56:57], v[76:77], v[56:57], 1.0 op_sel_hi:[1,1,0]
	s_nop 0
	v_pk_mul_f32 v[56:57], v[56:57], v[88:89]
	s_nop 0
	v_cvt_pk_f16_f32 v55, v56, v57
	v_pk_add_f32 v[56:57], v[86:87], 1.0 op_sel_hi:[1,0]
	s_nop 0
	v_div_scale_f32 v76, s[0:1], v57, v57, 1.0
	v_rcp_f32_e32 v77, v76
	s_nop 0
	v_fma_f32 v86, -v76, v77, 1.0
	v_fmac_f32_e32 v77, v86, v77
	v_div_scale_f32 v86, vcc, 1.0, v57, 1.0
	v_mul_f32_e32 v87, v86, v77
	v_fma_f32 v88, -v76, v87, v86
	v_fmac_f32_e32 v87, v88, v77
	v_fma_f32 v76, -v76, v87, v86
	v_div_fmas_f32 v76, v76, v77, v87
	v_div_fixup_f32 v77, v76, v57, 1.0
; __device__ __forceinline__ float sigmoidf_(float x) { return 1.0f / (1.0f + __expf(-x)); }
;     __device__ __forceinline__ void body_a(const f32x4 (&acc)[2][2][4][2], int row0, int cb0) const {
;     ...
;                 const size_t row = (size_t)(row0 + ai * 128 + m * 16);
;                 asm volatile("" ::: "memory");
;                 float a[2][8], kv[2][8], kk[2][8]; float ss = 0.f;
; #pragma unroll
;                 for (int bj = 0; bj < 2; ++bj) {
;                     const int c = cb0 + 32 * bj;
;                     const f32x4 b0 = *(const f32x4*)(a0 + c), b1 = *(const f32x4*)(a0 + c + 4), q0 = *(const f32x4*)(k_k + c), q1 = *(const f32x4*)(k_k + c + 4);
;                     const h16x8 kh = *(const h16x8*)(C1 + row * LDC1 + 2048 + c);
; #pragma unroll
;                     for (int e = 0; e < 4; ++e) {
;                         a[bj][e] = sigmoidf_(acc[ai][bj][m][0][e] + b0[e]); a[bj][4 + e] = sigmoidf_(acc[ai][bj][m][1][e] + b1[e]);
;                         kv[bj][e] = (float)kh[e]; kv[bj][4 + e] = (float)kh[4 + e];
;                         kk[bj][e] = kv[bj][e] * q0[e]; kk[bj][4 + e] = kv[bj][4 + e] * q1[e];
;                         ss += kk[bj][e] * kk[bj][e] + kk[bj][4 + e] * kk[bj][4 + e];
;     ...
;                 for (int bj = 0; bj < 2; ++bj) {
;                     const int c = cb0 + 32 * bj;
;                     const f32x4 p0 = *(const f32x4*)(k_a + c), p1 = *(const f32x4*)(k_a + c + 4);
;                     f32x4 ko0, ko1, ao0, ao1, bo0, bo1;
; #pragma unroll
;                     for (int e = 0; e < 4; ++e) {
;                         ko0[e] = kv[bj][e] * (1.0f + (a[bj][e] - 1.0f) * p0[e]); ko1[e] = kv[bj][4 + e] * (1.0f + (a[bj][4 + e] - 1.0f) * p1[e]);
;                         const float n0_ = kk[bj][e] * inv, n1_ = kk[bj][4 + e] * inv;
;                         ao0[e] = -n0_; ao1[e] = -n1_; bo0[e] = n0_ * a[bj][e]; bo1[e] = n1_ * a[bj][4 + e];
;                     }
;                     *(u32x4*)(C1 + row * LDC1 + 2048 + c) = pack8(ko0, ko1);
;                     *(u32x4*)(AA + row * DM + c) = pack8(ao0, ao1);
;                     *(u32x4*)(Ab + row * DM + c) = pack8(bo0, bo1);
	v_div_scale_f32 v57, s[0:1], v56, v56, 1.0
	v_rcp_f32_e32 v76, v57
	s_nop 0
	v_fma_f32 v86, -v57, v76, 1.0
	v_fmac_f32_e32 v76, v86, v76
	v_div_scale_f32 v86, vcc, 1.0, v56, 1.0
	v_mul_f32_e32 v87, v86, v76
	v_fma_f32 v88, -v57, v87, v86
	v_fmac_f32_e32 v87, v88, v76
	v_fma_f32 v57, -v57, v87, v86
	v_div_fmas_f32 v57, v57, v76, v87
	v_div_fixup_f32 v76, v57, v56, 1.0
	v_pk_add_f32 v[56:57], v[76:77], -1.0 op_sel_hi:[1,0]
	s_nop 0
	v_pk_fma_f32 v[50:51], v[56:57], v[50:51], 1.0 op_sel_hi:[1,1,0]
	s_nop 0
	v_pk_mul_f32 v[50:51], v[50:51], v[84:85]
	s_nop 0
	v_cvt_pk_f16_f32 v56, v50, v51
	v_pk_add_f32 v[50:51], v[82:83], 1.0 op_sel_hi:[1,0]
	s_nop 0
	v_div_scale_f32 v57, s[0:1], v51, v51, 1.0
	v_rcp_f32_e32 v82, v57
	s_nop 0
	v_fma_f32 v83, -v57, v82, 1.0
	v_fmac_f32_e32 v82, v83, v82
	v_div_scale_f32 v83, vcc, 1.0, v51, 1.0
	v_mul_f32_e32 v84, v83, v82
	v_fma_f32 v85, -v57, v84, v83
	v_fmac_f32_e32 v84, v85, v82
	v_fma_f32 v57, -v57, v84, v83
	v_div_fmas_f32 v57, v57, v82, v84
	v_div_fixup_f32 v83, v57, v51, 1.0
	v_div_scale_f32 v51, s[0:1], v50, v50, 1.0
	v_rcp_f32_e32 v57, v51
	s_nop 0
	v_fma_f32 v82, -v51, v57, 1.0
	v_fmac_f32_e32 v57, v82, v57
	v_div_scale_f32 v82, vcc, 1.0, v50, 1.0
	v_mul_f32_e32 v84, v82, v57
	v_fma_f32 v85, -v51, v84, v82
	v_fmac_f32_e32 v84, v85, v57
	v_fma_f32 v51, -v51, v84, v82
	v_div_fmas_f32 v51, v51, v57, v84
	v_div_fixup_f32 v82, v51, v50, 1.0
	v_pk_add_f32 v[50:51], v[82:83], -1.0 op_sel_hi:[1,0]
	s_nop 0
	v_pk_fma_f32 v[50:51], v[50:51], v[52:53], 1.0 op_sel_hi:[1,1,0]
	v_cvt_f16_f32_e64 v52, -v90
	v_pk_mul_f32 v[50:51], v[50:51], v[80:81]
	s_nop 0
	v_cvt_pk_f16_f32 v57, v50, v51
	v_pk_mov_b32 v[50:51], v[62:63], v[78:79] op_sel:[1,0]
	global_store_dwordx4 v[58:59], v[54:57], off
	s_nop 1
	v_pk_mul_f32 v[54:55], v[50:51], v[70:71] op_sel_hi:[1,0]
	s_nop 0
	v_cvt_pk_f16_f32 v51, v54, v55
	v_pack_b32_f16 v50, v52, -v51
	v_pk_mov_b32 v[52:53], v[78:79], v[60:61] op_sel:[1,0]
	v_xor_b32_sdwa v51, s63, v51 dst_sel:DWORD dst_unused:UNUSED_PAD src0_sel:DWORD src1_sel:WORD_1
	v_pk_mul_f32 v[56:57], v[52:53], v[70:71] op_sel_hi:[1,0]
	s_nop 0
	v_cvt_pk_f16_f32 v52, v56, v57
	v_xor_b32_e32 v53, 0x8000, v52
	v_perm_b32 v51, v53, v51, s33
	v_xor_b32_sdwa v62, s63, v52 dst_sel:DWORD dst_unused:UNUSED_PAD src0_sel:DWORD src1_sel:WORD_1
	v_pk_mov_b32 v[52:53], v[60:61], v[64:65] op_sel:[1,0]
	v_cvt_f16_f32_e64 v60, -v71
	v_pk_mul_f32 v[58:59], v[52:53], v[70:71] op_sel_hi:[1,0]
	s_nop 0
	v_cvt_pk_f16_f32 v53, v58, v59
	v_xor_b32_e32 v52, 0x8000, v53
	v_xor_b32_sdwa v53, s63, v53 dst_sel:DWORD dst_unused:UNUSED_PAD src0_sel:DWORD src1_sel:WORD_1
	v_perm_b32 v52, v52, v62, s33
	v_perm_b32 v53, v60, v53, s33
	global_store_dwordx4 v[66:67], v[50:53], off offset:64
	s_nop 1
	v_pk_mov_b32 v[50:51], v[72:73], v[74:75] op_sel:[1,0]
	v_fma_mixlo_f16 v52, v72, v90, 0
	v_pk_mul_f32 v[50:51], v[50:51], v[54:55]
	s_nop 0
	v_cvt_pk_f16_f32 v51, v50, v51
	v_pack_b32_f16 v50, v52, v51
	v_pk_mov_b32 v[52:53], v[74:75], v[76:77] op_sel:[1,0]
	s_nop 0
	v_pk_mul_f32 v[52:53], v[52:53], v[56:57]
	s_nop 0
	v_cvt_pk_f16_f32 v54, v52, v53
	v_pk_mov_b32 v[52:53], v[76:77], v[82:83] op_sel:[1,0]
	v_alignbit_b32 v51, v54, v51, 16
	v_pk_mul_f32 v[52:53], v[52:53], v[58:59]
	s_nop 0
	v_cvt_pk_f16_f32 v53, v52, v53
	v_alignbit_b32 v52, v53, v54, 16
	v_lshrrev_b32_e32 v53, 16, v53
	v_fma_mixhi_f16 v53, v83, v71, 0
	global_store_dwordx4 v[68:69], v[50:53], off offset:64
	v_add_u32_e32 v74, 0x90, v158
	s_nop 0
	v_mad_i64_i32 v[50:51], s[0:1], v74, s5, v[160:161]
	v_lshl_add_u64 v[70:71], v[50:51], 0, s[6:7]
	global_load_dwordx4 v[62:65], v[154:155], off offset:16
	global_load_dwordx4 v[66:69], v[154:155], off
	global_load_dwordx4 v[50:53], v[156:157], off offset:16
	global_load_dwordx4 v[54:57], v[156:157], off
	v_lshl_add_u64 v[82:83], v[70:71], 0, v[152:153]
	global_load_dwordx4 v[58:61], v[82:83], off
	v_ashrrev_i32_e32 v75, 31, v74
	s_waitcnt vmcnt(4)
	v_add_f32_e32 v42, v42, v62
	v_mul_f32_e32 v42, 0xbfb8aa3b, v42
	v_exp_f32_e32 v90, v42
	s_waitcnt vmcnt(3)
	v_add_f32_e32 v42, v47, v67
	v_mul_f32_e32 v42, 0xbfb8aa3b, v42
	v_exp_f32_e32 v93, v42
	v_add_f32_e32 v42, v43, v63
	v_mul_f32_e32 v42, 0xbfb8aa3b, v42
	v_exp_f32_e32 v91, v42
	v_add_f32_e32 v42, v48, v68
	v_mul_f32_e32 v42, 0xbfb8aa3b, v42
	v_exp_f32_e32 v94, v42
	v_add_f32_e32 v42, v44, v64
	v_mul_f32_e32 v42, 0xbfb8aa3b, v42
	v_exp_f32_e32 v84, v42
	v_add_f32_e32 v42, v49, v69
	v_mul_f32_e32 v42, 0xbfb8aa3b, v42
	v_exp_f32_e32 v95, v42
	v_add_f32_e32 v42, v45, v65
	v_add_f32_e32 v46, v46, v66
	v_mul_f32_e32 v42, 0xbfb8aa3b, v42
	v_mul_f32_e32 v46, 0xbfb8aa3b, v46
	v_exp_f32_e32 v85, v42
	v_lshl_add_u64 v[42:43], v[70:71], 0, v[128:129]
	v_exp_f32_e32 v92, v46
	global_load_dwordx4 v[46:49], v[154:155], off offset:144
	global_load_dwordx4 v[62:65], v[154:155], off offset:128
	global_load_dwordx4 v[86:89], v[156:157], off offset:144
	global_load_dwordx4 v[96:99], v[156:157], off offset:128
	global_load_dwordx4 v[100:103], v[42:43], off
	v_pk_add_f32 v[94:95], v[94:95], 1.0 op_sel_hi:[1,0]
	v_pk_add_f32 v[92:93], v[92:93], 1.0 op_sel_hi:[1,0]
	s_waitcnt vmcnt(4)
	v_add_f32_e32 v34, v34, v46
	v_mul_f32_e32 v34, 0xbfb8aa3b, v34
	v_exp_f32_e32 v70, v34
	s_waitcnt vmcnt(3)
	v_add_f32_e32 v34, v39, v63
	s_waitcnt vmcnt(0)
; __device__ __forceinline__ float sigmoidf_(float x) { return 1.0f / (1.0f + __expf(-x)); }
;     __device__ __forceinline__ void body_a(const f32x4 (&acc)[2][2][4][2], int row0, int cb0) const {
;     ...
;                     const f32x4 b0 = *(const f32x4*)(a0 + c), b1 = *(const f32x4*)(a0 + c + 4), q0 = *(const f32x4*)(k_k + c), q1 = *(const f32x4*)(k_k + c + 4);
;                     const h16x8 kh = *(const h16x8*)(C1 + row * LDC1 + 2048 + c);
; #pragma unroll
;                     for (int e = 0; e < 4; ++e) {
;                         a[bj][e] = sigmoidf_(acc[ai][bj][m][0][e] + b0[e]); a[bj][4 + e] = sigmoidf_(acc[ai][bj][m][1][e] + b1[e]);
;                         kv[bj][e] = (float)kh[e]; kv[bj][4 + e] = (float)kh[4 + e];
;                         kk[bj][e] = kv[bj][e] * q0[e]; kk[bj][4 + e] = kv[bj][4 + e] * q1[e];
;                         ss += kk[bj][e] * kk[bj][e] + kk[bj][4 + e] * kk[bj][4 + e];
;                     }
;                 }
;                 ss += __shfl_xor(ss, 16); ss += __shfl_xor(ss, 32);
;     ...
;                         ko0[e] = kv[bj][e] * (1.0f + (a[bj][e] - 1.0f) * p0[e]); ko1[e] = kv[bj][4 + e] * (1.0f + (a[bj][4 + e] - 1.0f) * p1[e]);
;                         const float n0_ = kk[bj][e] * inv, n1_ = kk[bj][4 + e] * inv;
;                         ao0[e] = -n0_; ao1[e] = -n1_; bo0[e] = n0_ * a[bj][e]; bo1[e] = n1_ * a[bj][4 + e];
;                     }
;                     *(u32x4*)(C1 + row * LDC1 + 2048 + c) = pack8(ko0, ko1);
	v_cvt_f32_f16_e32 v68, v102
	v_cvt_f32_f16_sdwa v69, v102 dst_sel:DWORD dst_unused:UNUSED_PAD src0_sel:WORD_1
	v_cvt_f32_f16_e32 v78, v100
	v_cvt_f32_f16_sdwa v79, v100 dst_sel:DWORD dst_unused:UNUSED_PAD src0_sel:WORD_1
	v_mul_f32_e32 v34, 0xbfb8aa3b, v34
	v_exp_f32_e32 v81, v34
	v_add_f32_e32 v34, v35, v47
	v_mul_f32_e32 v34, 0xbfb8aa3b, v34
	v_pk_mul_f32 v[44:45], v[86:87], v[68:69]
	v_exp_f32_e32 v71, v34
	v_pk_mul_f32 v[46:47], v[96:97], v[78:79]
	v_pk_mul_f32 v[34:35], v[44:45], v[44:45]
	v_cvt_f32_f16_e32 v72, v101
	v_pk_fma_f32 v[86:87], v[46:47], v[46:47], v[34:35]
	v_add_f32_e32 v34, v40, v64
	v_mul_f32_e32 v34, 0xbfb8aa3b, v34
	v_exp_f32_e32 v76, v34
	v_add_f32_e32 v34, v36, v48
	v_mul_f32_e32 v34, 0xbfb8aa3b, v34
	v_exp_f32_e32 v66, v34
	v_add_f32_e32 v34, v41, v65
	v_cvt_f32_f16_e32 v64, v103
	v_cvt_f32_f16_sdwa v65, v103 dst_sel:DWORD dst_unused:UNUSED_PAD src0_sel:WORD_1
	v_cvt_f32_f16_sdwa v73, v101 dst_sel:DWORD dst_unused:UNUSED_PAD src0_sel:WORD_1
	v_mul_f32_e32 v34, 0xbfb8aa3b, v34
	v_exp_f32_e32 v77, v34
	v_add_f32_e32 v34, v37, v49
	v_add_f32_e32 v38, v38, v62
	v_mul_f32_e32 v34, 0xbfb8aa3b, v34
	v_pk_mul_f32 v[48:49], v[88:89], v[64:65]
	v_mul_f32_e32 v38, 0xbfb8aa3b, v38
	v_exp_f32_e32 v67, v34
	v_pk_mul_f32 v[62:63], v[98:99], v[72:73]
	v_pk_mul_f32 v[34:35], v[48:49], v[48:49]
	v_exp_f32_e32 v80, v38
	v_pk_fma_f32 v[88:89], v[62:63], v[62:63], v[34:35]
	global_load_dwordx4 v[34:37], v[126:127], off offset:16
	global_load_dwordx4 v[38:41], v[126:127], off
	v_cvt_f32_f16_e32 v96, v58
	v_cvt_f32_f16_sdwa v97, v58 dst_sel:DWORD dst_unused:UNUSED_PAD src0_sel:WORD_1
	v_div_scale_f32 v58, s[0:1], v93, v93, 1.0
	v_rcp_f32_e32 v98, v58
	s_nop 0
	v_fma_f32 v99, -v58, v98, 1.0
	v_fmac_f32_e32 v98, v99, v98
	v_div_scale_f32 v99, vcc, 1.0, v93, 1.0
	v_mul_f32_e32 v100, v99, v98
	v_fma_f32 v101, -v58, v100, v99
	v_fmac_f32_e32 v100, v101, v98
	v_fma_f32 v58, -v58, v100, v99
	v_div_fmas_f32 v58, v58, v98, v100
	v_div_fixup_f32 v93, v58, v93, 1.0
	v_div_scale_f32 v58, s[0:1], v92, v92, 1.0
	v_rcp_f32_e32 v98, v58
	s_nop 0
	v_fma_f32 v99, -v58, v98, 1.0
	v_fmac_f32_e32 v98, v99, v98
	v_div_scale_f32 v99, vcc, 1.0, v92, 1.0
	v_mul_f32_e32 v100, v99, v98
	v_fma_f32 v101, -v58, v100, v99
	v_fmac_f32_e32 v100, v101, v98
	v_fma_f32 v58, -v58, v100, v99
	v_div_fmas_f32 v58, v58, v98, v100
	v_div_fixup_f32 v92, v58, v92, 1.0
	v_pk_add_f32 v[98:99], v[92:93], -1.0 op_sel_hi:[1,0]
	v_cvt_f32_f16_e32 v58, v59
	v_cvt_f32_f16_sdwa v59, v59 dst_sel:DWORD dst_unused:UNUSED_PAD src0_sel:WORD_1
	s_waitcnt vmcnt(0)
	v_pk_fma_f32 v[38:39], v[98:99], v[38:39], 1.0 op_sel_hi:[1,1,0]
	s_nop 0
	v_pk_mul_f32 v[38:39], v[38:39], v[96:97]
	s_nop 0
	v_cvt_pk_f16_f32 v38, v38, v39
	v_div_scale_f32 v39, s[0:1], v95, v95, 1.0
	v_rcp_f32_e32 v98, v39
	s_nop 0
	v_fma_f32 v99, -v39, v98, 1.0
	v_fmac_f32_e32 v98, v99, v98
	v_div_scale_f32 v99, vcc, 1.0, v95, 1.0
	v_mul_f32_e32 v100, v99, v98
	v_fma_f32 v101, -v39, v100, v99
	v_fmac_f32_e32 v100, v101, v98
	v_fma_f32 v39, -v39, v100, v99
	v_div_fmas_f32 v39, v39, v98, v100
	v_div_fixup_f32 v95, v39, v95, 1.0
	v_div_scale_f32 v39, s[0:1], v94, v94, 1.0
	v_rcp_f32_e32 v98, v39
	s_nop 0
	v_fma_f32 v99, -v39, v98, 1.0
	v_fmac_f32_e32 v98, v99, v98
	v_div_scale_f32 v99, vcc, 1.0, v94, 1.0
	v_mul_f32_e32 v100, v99, v98
	v_fma_f32 v101, -v39, v100, v99
	v_fmac_f32_e32 v100, v101, v98
	v_fma_f32 v39, -v39, v100, v99
	v_div_fmas_f32 v39, v39, v98, v100
	v_div_fixup_f32 v94, v39, v94, 1.0
	v_pk_add_f32 v[98:99], v[94:95], -1.0 op_sel_hi:[1,0]
	s_nop 0
	v_pk_fma_f32 v[40:41], v[98:99], v[40:41], 1.0 op_sel_hi:[1,1,0]
	v_cvt_f32_f16_e32 v98, v60
	v_pk_mul_f32 v[40:41], v[40:41], v[58:59]
	v_cvt_f32_f16_sdwa v99, v60 dst_sel:DWORD dst_unused:UNUSED_PAD src0_sel:WORD_1
	v_cvt_pk_f16_f32 v39, v40, v41
	v_pk_add_f32 v[40:41], v[90:91], 1.0 op_sel_hi:[1,0]
	s_nop 0
	v_div_scale_f32 v60, s[0:1], v41, v41, 1.0
	v_rcp_f32_e32 v90, v60
	s_nop 0
	v_fma_f32 v91, -v60, v90, 1.0
	v_fmac_f32_e32 v90, v91, v90
	v_div_scale_f32 v91, vcc, 1.0, v41, 1.0
	v_mul_f32_e32 v100, v91, v90
	v_fma_f32 v101, -v60, v100, v91
	v_fmac_f32_e32 v100, v101, v90
	v_fma_f32 v60, -v60, v100, v91
	v_div_fmas_f32 v60, v60, v90, v100
	v_div_fixup_f32 v91, v60, v41, 1.0
	v_div_scale_f32 v41, s[0:1], v40, v40, 1.0
	v_rcp_f32_e32 v60, v41
	s_nop 0
	v_fma_f32 v90, -v41, v60, 1.0
	v_fmac_f32_e32 v60, v90, v60
	v_div_scale_f32 v90, vcc, 1.0, v40, 1.0
	v_mul_f32_e32 v100, v90, v60
	v_fma_f32 v101, -v41, v100, v90
	v_fmac_f32_e32 v100, v101, v60
	v_fma_f32 v41, -v41, v100, v90
	v_div_fmas_f32 v41, v41, v60, v100
	v_div_fixup_f32 v90, v41, v40, 1.0
	v_pk_add_f32 v[40:41], v[90:91], -1.0 op_sel_hi:[1,0]
	v_cvt_f32_f16_e32 v60, v61
	v_pk_fma_f32 v[34:35], v[40:41], v[34:35], 1.0 op_sel_hi:[1,1,0]
	v_cvt_f32_f16_sdwa v61, v61 dst_sel:DWORD dst_unused:UNUSED_PAD src0_sel:WORD_1
	v_pk_mul_f32 v[34:35], v[34:35], v[98:99]
	v_pk_mul_f32 v[52:53], v[52:53], v[60:61]
	v_cvt_pk_f16_f32 v40, v34, v35
	v_pk_add_f32 v[34:35], v[84:85], 1.0 op_sel_hi:[1,0]
	s_nop 0
	v_div_scale_f32 v41, s[0:1], v35, v35, 1.0
	v_rcp_f32_e32 v84, v41
	s_nop 0
	v_fma_f32 v85, -v41, v84, 1.0
	v_fmac_f32_e32 v84, v85, v84
	v_div_scale_f32 v85, vcc, 1.0, v35, 1.0
	v_mul_f32_e32 v100, v85, v84
	v_fma_f32 v101, -v41, v100, v85
	v_fmac_f32_e32 v100, v101, v84
	v_fma_f32 v41, -v41, v100, v85
	v_div_fmas_f32 v41, v41, v84, v100
	v_div_fixup_f32 v35, v41, v35, 1.0
	v_div_scale_f32 v41, s[0:1], v34, v34, 1.0
	v_rcp_f32_e32 v84, v41
	s_nop 0
	v_fma_f32 v85, -v41, v84, 1.0
	v_fmac_f32_e32 v84, v85, v84
	v_div_scale_f32 v85, vcc, 1.0, v34, 1.0
	v_mul_f32_e32 v100, v85, v84
	v_fma_f32 v101, -v41, v100, v85
	v_fmac_f32_e32 v100, v101, v84
	v_fma_f32 v41, -v41, v100, v85
	v_div_fmas_f32 v41, v41, v84, v100
	v_div_fixup_f32 v34, v41, v34, 1.0
	v_pk_add_f32 v[84:85], v[34:35], -1.0 op_sel_hi:[1,0]
	s_nop 0
	v_pk_fma_f32 v[36:37], v[84:85], v[36:37], 1.0 op_sel_hi:[1,1,0]
	s_nop 0
	v_pk_mul_f32 v[36:37], v[36:37], v[60:61]
	v_lshlrev_b64 v[60:61], 12, v[74:75]
	v_cvt_pk_f16_f32 v41, v36, v37
	global_store_dwordx4 v[82:83], v[38:41], off
	v_pk_mul_f32 v[36:37], v[54:55], v[96:97]
	v_pk_mul_f32 v[54:55], v[52:53], v[52:53]
	v_pk_mul_f32 v[40:41], v[50:51], v[98:99]
	v_pk_mul_f32 v[38:39], v[56:57], v[58:59]
	v_pk_mul_f32 v[50:51], v[40:41], v[40:41]
	v_pk_fma_f32 v[54:55], v[38:39], v[38:39], v[54:55]
	v_pk_fma_f32 v[50:51], v[36:37], v[36:37], v[50:51]
	s_nop 0
	v_add_f32_e32 v50, v50, v51
	v_add_f32_e32 v50, v54, v50
	v_add_f32_e32 v50, v55, v50
	v_add_f32_e32 v50, v50, v86
	v_add_f32_e32 v50, v87, v50
	v_add_f32_e32 v50, v88, v50
	v_add_f32_e32 v50, v89, v50
	ds_bpermute_b32 v51, v206, v50
	s_waitcnt lgkmcnt(0)
;     __device__ __forceinline__ void body_a(const f32x4 (&acc)[2][2][4][2], int row0, int cb0) const {
;     ...
;                 ss += __shfl_xor(ss, 16); ss += __shfl_xor(ss, 32);
;                 const float inv = 1.0f / fmaxf(sqrtf(ss), 1e-12f);
; #pragma unroll
;                 for (int bj = 0; bj < 2; ++bj) {
;                     const int c = cb0 + 32 * bj;
;                     const f32x4 p0 = *(const f32x4*)(k_a + c), p1 = *(const f32x4*)(k_a + c + 4);
;                     f32x4 ko0, ko1, ao0, ao1, bo0, bo1;
; #pragma unroll
;                     for (int e = 0; e < 4; ++e) {
;                         ko0[e] = kv[bj][e] * (1.0f + (a[bj][e] - 1.0f) * p0[e]); ko1[e] = kv[bj][4 + e] * (1.0f + (a[bj][4 + e] - 1.0f) * p1[e]);
;                         const float n0_ = kk[bj][e] * inv, n1_ = kk[bj][4 + e] * inv;
;                         ao0[e] = -n0_; ao1[e] = -n1_; bo0[e] = n0_ * a[bj][e]; bo1[e] = n1_ * a[bj][4 + e];
;                     }
;                     *(u32x4*)(C1 + row * LDC1 + 2048 + c) = pack8(ko0, ko1);
;                     *(u32x4*)(AA + row * DM + c) = pack8(ao0, ao1);
;                     *(u32x4*)(Ab + row * DM + c) = pack8(bo0, bo1);
	v_add_f32_e32 v50, v50, v51
	ds_bpermute_b32 v51, v207, v50
	s_waitcnt lgkmcnt(0)
	v_add_f32_e32 v50, v50, v51
	v_cmp_gt_f32_e32 vcc, s4, v50
	v_mul_f32_e32 v51, 0x4f800000, v50
	s_nop 0
	v_cndmask_b32_e32 v50, v50, v51, vcc
	v_sqrt_f32_e32 v51, v50
	s_nop 0
	v_add_u32_e32 v54, -1, v51
	v_fma_f32 v55, -v54, v51, v50
	v_cmp_ge_f32_e64 s[0:1], 0, v55
	v_add_u32_e32 v55, 1, v51
	s_nop 0
	v_cndmask_b32_e64 v54, v51, v54, s[0:1]
	v_fma_f32 v51, -v55, v51, v50
	v_cmp_lt_f32_e64 s[0:1], 0, v51
	s_nop 1
	v_cndmask_b32_e64 v51, v54, v55, s[0:1]
	v_mul_f32_e32 v54, 0x37800000, v51
	v_cndmask_b32_e32 v51, v51, v54, vcc
	v_cmp_class_f32_e32 vcc, v50, v244
	s_nop 1
	v_cndmask_b32_e32 v50, v51, v50, vcc
	v_max_f32_e32 v50, 0x2b8cbccc, v50
	v_div_scale_f32 v51, s[0:1], v50, v50, 1.0
	v_rcp_f32_e32 v54, v51
	s_nop 0
	v_fma_f32 v55, -v51, v54, 1.0
	v_fmac_f32_e32 v54, v55, v54
	v_div_scale_f32 v55, vcc, 1.0, v50, 1.0
	v_mul_f32_e32 v56, v55, v54
	v_fma_f32 v57, -v51, v56, v55
	v_fmac_f32_e32 v56, v57, v54
	v_fma_f32 v51, -v51, v56, v55
	v_div_fmas_f32 v51, v51, v54, v56
	v_div_fixup_f32 v54, v51, v50, 1.0
	v_pk_mul_f32 v[58:59], v[38:39], v[54:55] op_sel_hi:[1,0]
	v_pk_mul_f32 v[56:57], v[36:37], v[54:55] op_sel_hi:[1,0]
	v_cvt_pk_f16_f32 v37, v58, v59
	v_cvt_pk_f16_f32 v36, v56, v57
	v_xor_b32_e32 v38, 0x8000, v37
	v_xor_b32_sdwa v37, s63, v37 dst_sel:DWORD dst_unused:UNUSED_PAD src0_sel:DWORD src1_sel:WORD_1
	v_pk_mul_f32 v[40:41], v[40:41], v[54:55] op_sel_hi:[1,0]
	v_pk_mul_f32 v[52:53], v[52:53], v[54:55] op_sel_hi:[1,0]
	v_perm_b32 v37, v37, v38, s33
	v_xor_b32_e32 v38, 0x8000, v36
	v_xor_b32_sdwa v36, s63, v36 dst_sel:DWORD dst_unused:UNUSED_PAD src0_sel:DWORD src1_sel:WORD_1
	v_perm_b32 v36, v36, v38, s33
	v_pk_add_f32 v[38:39], v[40:41], 0 neg_lo:[1,1] neg_hi:[1,1]
	v_pk_add_f32 v[50:51], v[52:53], 0 neg_lo:[1,1] neg_hi:[1,1]
	v_cvt_pk_f16_f32 v38, v38, v39
	v_cvt_pk_f16_f32 v39, v50, v51
	v_lshl_add_u64 v[50:51], s[10:11], 0, v[60:61]
	v_lshl_add_u64 v[50:51], v[50:51], 0, v[152:153]
	global_store_dwordx4 v[50:51], v[36:39], off
	v_fma_mixlo_f16 v55, v92, v56, 0
	v_mul_f32_e32 v74, v46, v54
	v_pk_mov_b32 v[36:37], v[92:93], v[94:95] op_sel:[1,0]
	v_pk_mov_b32 v[38:39], v[56:57], v[58:59] op_sel:[1,0]
	v_pk_mov_b32 v[56:57], v[58:59], v[40:41] op_sel:[1,0]
	v_pk_mul_f32 v[36:37], v[36:37], v[38:39]
	v_pk_mov_b32 v[38:39], v[94:95], v[90:91] op_sel:[1,0]
	v_cvt_pk_f16_f32 v37, v36, v37
	v_pk_mul_f32 v[38:39], v[38:39], v[56:57]
	v_pack_b32_f16 v36, v55, v37
	v_cvt_pk_f16_f32 v55, v38, v39
	v_pk_mov_b32 v[38:39], v[90:91], v[34:35] op_sel:[1,0]
	v_pk_mov_b32 v[40:41], v[40:41], v[52:53] op_sel:[1,0]
	v_alignbit_b32 v37, v55, v37, 16
	v_pk_mul_f32 v[38:39], v[38:39], v[40:41]
	v_pk_add_f32 v[56:57], v[80:81], 1.0 op_sel_hi:[1,0]
	v_cvt_pk_f16_f32 v34, v38, v39
	v_lshrrev_b32_e32 v39, 16, v34
	v_alignbit_b32 v38, v34, v55, 16
	v_fma_mixhi_f16 v39, v35, v53, 0
	v_lshl_add_u64 v[34:35], s[2:3], 0, v[60:61]
	v_lshl_add_u64 v[52:53], v[34:35], 0, v[152:153]
	global_store_dwordx4 v[52:53], v[36:39], off
	global_load_dwordx4 v[34:37], v[126:127], off offset:144
	s_nop 0
	global_load_dwordx4 v[38:41], v[126:127], off offset:128
	v_div_scale_f32 v58, s[0:1], v57, v57, 1.0
	v_rcp_f32_e32 v59, v58
	v_mul_f32_e32 v55, v49, v54
	v_fma_f32 v60, -v58, v59, 1.0
	v_fmac_f32_e32 v59, v60, v59
	v_div_scale_f32 v60, vcc, 1.0, v57, 1.0
	v_mul_f32_e32 v61, v60, v59
	v_fma_f32 v75, -v58, v61, v60
	v_fmac_f32_e32 v61, v75, v59
	v_fma_f32 v58, -v58, v61, v60
	v_div_fmas_f32 v58, v58, v59, v61
	v_div_fixup_f32 v57, v58, v57, 1.0
	v_div_scale_f32 v58, s[0:1], v56, v56, 1.0
	v_rcp_f32_e32 v59, v58
	s_nop 0
	v_fma_f32 v60, -v58, v59, 1.0
	v_fmac_f32_e32 v59, v60, v59
	v_div_scale_f32 v60, vcc, 1.0, v56, 1.0
	v_mul_f32_e32 v61, v60, v59
	v_fma_f32 v75, -v58, v61, v60
	v_fmac_f32_e32 v61, v75, v59
	v_fma_f32 v58, -v58, v61, v60
	v_div_fmas_f32 v58, v58, v59, v61
	v_div_fixup_f32 v56, v58, v56, 1.0
	v_pk_add_f32 v[58:59], v[56:57], -1.0 op_sel_hi:[1,0]
	s_waitcnt vmcnt(0)
	v_pk_fma_f32 v[38:39], v[58:59], v[38:39], 1.0 op_sel_hi:[1,1,0]
	s_nop 0
	v_pk_mul_f32 v[38:39], v[38:39], v[78:79]
	v_pk_add_f32 v[58:59], v[76:77], 1.0 op_sel_hi:[1,0]
	v_cvt_pk_f16_f32 v38, v38, v39
	v_div_scale_f32 v39, s[0:1], v59, v59, 1.0
	v_rcp_f32_e32 v60, v39
	s_nop 0
	v_fma_f32 v61, -v39, v60, 1.0
	v_fmac_f32_e32 v60, v61, v60
	v_div_scale_f32 v61, vcc, 1.0, v59, 1.0
	v_mul_f32_e32 v75, v61, v60
	v_fma_f32 v76, -v39, v75, v61
	v_fmac_f32_e32 v75, v76, v60
	v_fma_f32 v39, -v39, v75, v61
	v_div_fmas_f32 v39, v39, v60, v75
	v_div_fixup_f32 v59, v39, v59, 1.0
	v_div_scale_f32 v39, s[0:1], v58, v58, 1.0
	v_rcp_f32_e32 v60, v39
	s_nop 0
	v_fma_f32 v61, -v39, v60, 1.0
	v_fmac_f32_e32 v60, v61, v60
	v_div_scale_f32 v61, vcc, 1.0, v58, 1.0
	v_mul_f32_e32 v75, v61, v60
	v_fma_f32 v76, -v39, v75, v61
	v_fmac_f32_e32 v75, v76, v60
	v_fma_f32 v39, -v39, v75, v61
	v_div_fmas_f32 v39, v39, v60, v75
	v_div_fixup_f32 v58, v39, v58, 1.0
	v_pk_add_f32 v[60:61], v[58:59], -1.0 op_sel_hi:[1,0]
	s_nop 0
	v_pk_fma_f32 v[40:41], v[60:61], v[40:41], 1.0 op_sel_hi:[1,1,0]
	s_nop 0
	v_pk_mul_f32 v[40:41], v[40:41], v[72:73]
	s_nop 0
	v_cvt_pk_f16_f32 v39, v40, v41
	v_pk_add_f32 v[40:41], v[70:71], 1.0 op_sel_hi:[1,0]
	s_nop 0
	v_div_scale_f32 v60, s[0:1], v41, v41, 1.0
	v_rcp_f32_e32 v61, v60
	s_nop 0
	v_fma_f32 v70, -v60, v61, 1.0
	v_fmac_f32_e32 v61, v70, v61
	v_div_scale_f32 v70, vcc, 1.0, v41, 1.0
	v_mul_f32_e32 v71, v70, v61
	v_fma_f32 v72, -v60, v71, v70
	v_fmac_f32_e32 v71, v72, v61
	v_fma_f32 v60, -v60, v71, v70
	v_div_fmas_f32 v60, v60, v61, v71
	v_div_fixup_f32 v61, v60, v41, 1.0
	v_div_scale_f32 v41, s[0:1], v40, v40, 1.0
; __device__ __forceinline__ float sigmoidf_(float x) { return 1.0f / (1.0f + __expf(-x)); }
;     __device__ __forceinline__ void body_a(const f32x4 (&acc)[2][2][4][2], int row0, int cb0) const {
;     ...
;                 const size_t row = (size_t)(row0 + ai * 128 + m * 16);
;                 asm volatile("" ::: "memory");
;                 float a[2][8], kv[2][8], kk[2][8]; float ss = 0.f;
; #pragma unroll
;                 for (int bj = 0; bj < 2; ++bj) {
;                     const int c = cb0 + 32 * bj;
;                     const f32x4 b0 = *(const f32x4*)(a0 + c), b1 = *(const f32x4*)(a0 + c + 4), q0 = *(const f32x4*)(k_k + c), q1 = *(const f32x4*)(k_k + c + 4);
;                     const h16x8 kh = *(const h16x8*)(C1 + row * LDC1 + 2048 + c);
; #pragma unroll
;                     for (int e = 0; e < 4; ++e) {
;                         a[bj][e] = sigmoidf_(acc[ai][bj][m][0][e] + b0[e]); a[bj][4 + e] = sigmoidf_(acc[ai][bj][m][1][e] + b1[e]);
;                         kv[bj][e] = (float)kh[e]; kv[bj][4 + e] = (float)kh[4 + e];
;                         kk[bj][e] = kv[bj][e] * q0[e]; kk[bj][4 + e] = kv[bj][4 + e] * q1[e];
;                         ss += kk[bj][e] * kk[bj][e] + kk[bj][4 + e] * kk[bj][4 + e];
;     ...
;                 for (int bj = 0; bj < 2; ++bj) {
;                     const int c = cb0 + 32 * bj;
;                     const f32x4 p0 = *(const f32x4*)(k_a + c), p1 = *(const f32x4*)(k_a + c + 4);
;                     f32x4 ko0, ko1, ao0, ao1, bo0, bo1;
; #pragma unroll
;                     for (int e = 0; e < 4; ++e) {
;                         ko0[e] = kv[bj][e] * (1.0f + (a[bj][e] - 1.0f) * p0[e]); ko1[e] = kv[bj][4 + e] * (1.0f + (a[bj][4 + e] - 1.0f) * p1[e]);
;                         const float n0_ = kk[bj][e] * inv, n1_ = kk[bj][4 + e] * inv;
;                         ao0[e] = -n0_; ao1[e] = -n1_; bo0[e] = n0_ * a[bj][e]; bo1[e] = n1_ * a[bj][4 + e];
;                     }
;                     *(u32x4*)(C1 + row * LDC1 + 2048 + c) = pack8(ko0, ko1);
;                     *(u32x4*)(AA + row * DM + c) = pack8(ao0, ao1);
;                     *(u32x4*)(Ab + row * DM + c) = pack8(bo0, bo1);
	v_rcp_f32_e32 v60, v41
	s_nop 0
	v_fma_f32 v70, -v41, v60, 1.0
	v_fmac_f32_e32 v60, v70, v60
	v_div_scale_f32 v70, vcc, 1.0, v40, 1.0
	v_mul_f32_e32 v71, v70, v60
	v_fma_f32 v72, -v41, v71, v70
	v_fmac_f32_e32 v71, v72, v60
	v_fma_f32 v41, -v41, v71, v70
	v_div_fmas_f32 v41, v41, v60, v71
	v_div_fixup_f32 v60, v41, v40, 1.0
	v_pk_add_f32 v[40:41], v[60:61], -1.0 op_sel_hi:[1,0]
	s_nop 0
	v_pk_fma_f32 v[34:35], v[40:41], v[34:35], 1.0 op_sel_hi:[1,1,0]
	s_nop 0
	v_pk_mul_f32 v[34:35], v[34:35], v[68:69]
	s_nop 0
	v_cvt_pk_f16_f32 v40, v34, v35
	v_pk_add_f32 v[34:35], v[66:67], 1.0 op_sel_hi:[1,0]
	s_nop 0
	v_div_scale_f32 v41, s[0:1], v35, v35, 1.0
	v_rcp_f32_e32 v66, v41
	s_nop 0
	v_fma_f32 v67, -v41, v66, 1.0
	v_fmac_f32_e32 v66, v67, v66
	v_div_scale_f32 v67, vcc, 1.0, v35, 1.0
	v_mul_f32_e32 v68, v67, v66
	v_fma_f32 v69, -v41, v68, v67
	v_fmac_f32_e32 v68, v69, v66
	v_fma_f32 v41, -v41, v68, v67
	v_div_fmas_f32 v41, v41, v66, v68
	v_div_fixup_f32 v67, v41, v35, 1.0
	v_div_scale_f32 v35, s[0:1], v34, v34, 1.0
	v_rcp_f32_e32 v41, v35
	s_nop 0
	v_fma_f32 v66, -v35, v41, 1.0
	v_fmac_f32_e32 v41, v66, v41
	v_div_scale_f32 v66, vcc, 1.0, v34, 1.0
	v_mul_f32_e32 v68, v66, v41
	v_fma_f32 v69, -v35, v68, v66
	v_fmac_f32_e32 v68, v69, v41
	v_fma_f32 v35, -v35, v68, v66
	v_div_fmas_f32 v35, v35, v41, v68
	v_div_fixup_f32 v66, v35, v34, 1.0
	v_pk_add_f32 v[34:35], v[66:67], -1.0 op_sel_hi:[1,0]
	s_nop 0
	v_pk_fma_f32 v[34:35], v[34:35], v[36:37], 1.0 op_sel_hi:[1,1,0]
	v_cvt_f16_f32_e64 v36, -v74
	v_pk_mul_f32 v[34:35], v[34:35], v[64:65]
	s_nop 0
	v_cvt_pk_f16_f32 v41, v34, v35
	v_pk_mov_b32 v[34:35], v[46:47], v[62:63] op_sel:[1,0]
	global_store_dwordx4 v[42:43], v[38:41], off
	s_nop 1
	v_pk_mul_f32 v[38:39], v[34:35], v[54:55] op_sel_hi:[1,0]
	s_nop 0
	v_cvt_pk_f16_f32 v35, v38, v39
	v_pack_b32_f16 v34, v36, -v35
	v_pk_mov_b32 v[36:37], v[62:63], v[44:45] op_sel:[1,0]
	v_xor_b32_sdwa v35, s63, v35 dst_sel:DWORD dst_unused:UNUSED_PAD src0_sel:DWORD src1_sel:WORD_1
	v_pk_mul_f32 v[40:41], v[36:37], v[54:55] op_sel_hi:[1,0]
	s_nop 0
	v_cvt_pk_f16_f32 v36, v40, v41
	v_xor_b32_e32 v37, 0x8000, v36
	v_perm_b32 v35, v37, v35, s33
	v_xor_b32_sdwa v46, s63, v36 dst_sel:DWORD dst_unused:UNUSED_PAD src0_sel:DWORD src1_sel:WORD_1
	v_pk_mov_b32 v[36:37], v[44:45], v[48:49] op_sel:[1,0]
	v_cvt_f16_f32_e64 v44, -v55
	v_pk_mul_f32 v[42:43], v[36:37], v[54:55] op_sel_hi:[1,0]
	s_nop 0
	v_cvt_pk_f16_f32 v37, v42, v43
	v_xor_b32_e32 v36, 0x8000, v37
	v_xor_b32_sdwa v37, s63, v37 dst_sel:DWORD dst_unused:UNUSED_PAD src0_sel:DWORD src1_sel:WORD_1
	v_perm_b32 v36, v36, v46, s33
	v_perm_b32 v37, v44, v37, s33
	global_store_dwordx4 v[50:51], v[34:37], off offset:64
	s_nop 1
	v_pk_mov_b32 v[34:35], v[56:57], v[58:59] op_sel:[1,0]
	v_fma_mixlo_f16 v36, v56, v74, 0
	v_pk_mul_f32 v[34:35], v[34:35], v[38:39]
	s_nop 0
	v_cvt_pk_f16_f32 v35, v34, v35
	v_pack_b32_f16 v34, v36, v35
	v_pk_mov_b32 v[36:37], v[58:59], v[60:61] op_sel:[1,0]
	s_nop 0
	v_pk_mul_f32 v[36:37], v[36:37], v[40:41]
	s_nop 0
	v_cvt_pk_f16_f32 v38, v36, v37
	v_pk_mov_b32 v[36:37], v[60:61], v[66:67] op_sel:[1,0]
	v_alignbit_b32 v35, v38, v35, 16
	v_pk_mul_f32 v[36:37], v[36:37], v[42:43]
	s_nop 0
	v_cvt_pk_f16_f32 v37, v36, v37
	v_alignbit_b32 v36, v37, v38, 16
	v_lshrrev_b32_e32 v37, 16, v37
	v_fma_mixhi_f16 v37, v67, v55, 0
	global_store_dwordx4 v[52:53], v[34:37], off offset:64
	v_add_u32_e32 v58, 0xa0, v158
	s_nop 0
	v_mad_i64_i32 v[34:35], s[0:1], v58, s5, v[160:161]
	v_lshl_add_u64 v[54:55], v[34:35], 0, s[6:7]
	global_load_dwordx4 v[46:49], v[154:155], off offset:16
	global_load_dwordx4 v[50:53], v[154:155], off
	global_load_dwordx4 v[34:37], v[156:157], off offset:16
	global_load_dwordx4 v[38:41], v[156:157], off
	v_lshl_add_u64 v[66:67], v[54:55], 0, v[152:153]
	global_load_dwordx4 v[42:45], v[66:67], off
	v_ashrrev_i32_e32 v59, 31, v58
	s_waitcnt vmcnt(4)
	v_add_f32_e32 v26, v26, v46
	v_mul_f32_e32 v26, 0xbfb8aa3b, v26
	v_exp_f32_e32 v74, v26
	s_waitcnt vmcnt(3)
	v_add_f32_e32 v26, v31, v51
	v_mul_f32_e32 v26, 0xbfb8aa3b, v26
	v_exp_f32_e32 v77, v26
	v_add_f32_e32 v26, v27, v47
	v_mul_f32_e32 v26, 0xbfb8aa3b, v26
	v_exp_f32_e32 v75, v26
	v_add_f32_e32 v26, v32, v52
	v_mul_f32_e32 v26, 0xbfb8aa3b, v26
	v_exp_f32_e32 v78, v26
	v_add_f32_e32 v26, v28, v48
	v_mul_f32_e32 v26, 0xbfb8aa3b, v26
	v_exp_f32_e32 v68, v26
	v_add_f32_e32 v26, v33, v53
	v_mul_f32_e32 v26, 0xbfb8aa3b, v26
	v_exp_f32_e32 v79, v26
	v_add_f32_e32 v26, v29, v49
	v_add_f32_e32 v30, v30, v50
	v_mul_f32_e32 v26, 0xbfb8aa3b, v26
	v_mul_f32_e32 v30, 0xbfb8aa3b, v30
	v_exp_f32_e32 v69, v26
	v_lshl_add_u64 v[26:27], v[54:55], 0, v[128:129]
	v_exp_f32_e32 v76, v30
	global_load_dwordx4 v[30:33], v[154:155], off offset:144
	global_load_dwordx4 v[46:49], v[154:155], off offset:128
	global_load_dwordx4 v[70:73], v[156:157], off offset:144
	global_load_dwordx4 v[80:83], v[156:157], off offset:128
	global_load_dwordx4 v[84:87], v[26:27], off
	v_pk_add_f32 v[78:79], v[78:79], 1.0 op_sel_hi:[1,0]
	v_pk_add_f32 v[76:77], v[76:77], 1.0 op_sel_hi:[1,0]
	s_waitcnt vmcnt(4)
	v_add_f32_e32 v18, v18, v30
	v_mul_f32_e32 v18, 0xbfb8aa3b, v18
	v_exp_f32_e32 v54, v18
	s_waitcnt vmcnt(3)
	v_add_f32_e32 v18, v23, v47
	s_waitcnt vmcnt(0)
; __device__ __forceinline__ float sigmoidf_(float x) { return 1.0f / (1.0f + __expf(-x)); }
;     __device__ __forceinline__ void body_a(const f32x4 (&acc)[2][2][4][2], int row0, int cb0) const {
;     ...
;                     const f32x4 b0 = *(const f32x4*)(a0 + c), b1 = *(const f32x4*)(a0 + c + 4), q0 = *(const f32x4*)(k_k + c), q1 = *(const f32x4*)(k_k + c + 4);
;                     const h16x8 kh = *(const h16x8*)(C1 + row * LDC1 + 2048 + c);
; #pragma unroll
;                     for (int e = 0; e < 4; ++e) {
;                         a[bj][e] = sigmoidf_(acc[ai][bj][m][0][e] + b0[e]); a[bj][4 + e] = sigmoidf_(acc[ai][bj][m][1][e] + b1[e]);
;                         kv[bj][e] = (float)kh[e]; kv[bj][4 + e] = (float)kh[4 + e];
;                         kk[bj][e] = kv[bj][e] * q0[e]; kk[bj][4 + e] = kv[bj][4 + e] * q1[e];
;                         ss += kk[bj][e] * kk[bj][e] + kk[bj][4 + e] * kk[bj][4 + e];
;                     }
;                 }
;                 ss += __shfl_xor(ss, 16); ss += __shfl_xor(ss, 32);
;     ...
;                         ko0[e] = kv[bj][e] * (1.0f + (a[bj][e] - 1.0f) * p0[e]); ko1[e] = kv[bj][4 + e] * (1.0f + (a[bj][4 + e] - 1.0f) * p1[e]);
;                         const float n0_ = kk[bj][e] * inv, n1_ = kk[bj][4 + e] * inv;
;                         ao0[e] = -n0_; ao1[e] = -n1_; bo0[e] = n0_ * a[bj][e]; bo1[e] = n1_ * a[bj][4 + e];
;                     }
;                     *(u32x4*)(C1 + row * LDC1 + 2048 + c) = pack8(ko0, ko1);
	v_cvt_f32_f16_e32 v52, v86
	v_cvt_f32_f16_sdwa v53, v86 dst_sel:DWORD dst_unused:UNUSED_PAD src0_sel:WORD_1
	v_cvt_f32_f16_e32 v62, v84
	v_cvt_f32_f16_sdwa v63, v84 dst_sel:DWORD dst_unused:UNUSED_PAD src0_sel:WORD_1
	v_mul_f32_e32 v18, 0xbfb8aa3b, v18
	v_exp_f32_e32 v65, v18
	v_add_f32_e32 v18, v19, v31
	v_mul_f32_e32 v18, 0xbfb8aa3b, v18
	v_pk_mul_f32 v[28:29], v[70:71], v[52:53]
	v_exp_f32_e32 v55, v18
	v_pk_mul_f32 v[30:31], v[80:81], v[62:63]
	v_pk_mul_f32 v[18:19], v[28:29], v[28:29]
	v_cvt_f32_f16_e32 v56, v85
	v_pk_fma_f32 v[70:71], v[30:31], v[30:31], v[18:19]
	v_add_f32_e32 v18, v24, v48
	v_mul_f32_e32 v18, 0xbfb8aa3b, v18
	v_exp_f32_e32 v60, v18
	v_add_f32_e32 v18, v20, v32
	v_mul_f32_e32 v18, 0xbfb8aa3b, v18
	v_exp_f32_e32 v50, v18
	v_add_f32_e32 v18, v25, v49
	v_cvt_f32_f16_e32 v48, v87
	v_cvt_f32_f16_sdwa v49, v87 dst_sel:DWORD dst_unused:UNUSED_PAD src0_sel:WORD_1
	v_cvt_f32_f16_sdwa v57, v85 dst_sel:DWORD dst_unused:UNUSED_PAD src0_sel:WORD_1
	v_mul_f32_e32 v18, 0xbfb8aa3b, v18
	v_exp_f32_e32 v61, v18
	v_add_f32_e32 v18, v21, v33
	v_add_f32_e32 v22, v22, v46
	v_mul_f32_e32 v18, 0xbfb8aa3b, v18
	v_pk_mul_f32 v[32:33], v[72:73], v[48:49]
	v_mul_f32_e32 v22, 0xbfb8aa3b, v22
	v_exp_f32_e32 v51, v18
	v_pk_mul_f32 v[46:47], v[82:83], v[56:57]
	v_pk_mul_f32 v[18:19], v[32:33], v[32:33]
	v_exp_f32_e32 v64, v22
	v_pk_fma_f32 v[72:73], v[46:47], v[46:47], v[18:19]
	global_load_dwordx4 v[18:21], v[126:127], off offset:16
	global_load_dwordx4 v[22:25], v[126:127], off
	v_cvt_f32_f16_e32 v80, v42
	v_cvt_f32_f16_sdwa v81, v42 dst_sel:DWORD dst_unused:UNUSED_PAD src0_sel:WORD_1
	v_div_scale_f32 v42, s[0:1], v77, v77, 1.0
	v_rcp_f32_e32 v82, v42
	s_nop 0
	v_fma_f32 v83, -v42, v82, 1.0
	v_fmac_f32_e32 v82, v83, v82
	v_div_scale_f32 v83, vcc, 1.0, v77, 1.0
	v_mul_f32_e32 v84, v83, v82
	v_fma_f32 v85, -v42, v84, v83
	v_fmac_f32_e32 v84, v85, v82
	v_fma_f32 v42, -v42, v84, v83
	v_div_fmas_f32 v42, v42, v82, v84
	v_div_fixup_f32 v77, v42, v77, 1.0
	v_div_scale_f32 v42, s[0:1], v76, v76, 1.0
	v_rcp_f32_e32 v82, v42
	s_nop 0
	v_fma_f32 v83, -v42, v82, 1.0
	v_fmac_f32_e32 v82, v83, v82
	v_div_scale_f32 v83, vcc, 1.0, v76, 1.0
	v_mul_f32_e32 v84, v83, v82
	v_fma_f32 v85, -v42, v84, v83
	v_fmac_f32_e32 v84, v85, v82
	v_fma_f32 v42, -v42, v84, v83
	v_div_fmas_f32 v42, v42, v82, v84
	v_div_fixup_f32 v76, v42, v76, 1.0
	v_pk_add_f32 v[82:83], v[76:77], -1.0 op_sel_hi:[1,0]
	v_cvt_f32_f16_e32 v42, v43
	v_cvt_f32_f16_sdwa v43, v43 dst_sel:DWORD dst_unused:UNUSED_PAD src0_sel:WORD_1
	s_waitcnt vmcnt(0)
	v_pk_fma_f32 v[22:23], v[82:83], v[22:23], 1.0 op_sel_hi:[1,1,0]
	s_nop 0
	v_pk_mul_f32 v[22:23], v[22:23], v[80:81]
	s_nop 0
	v_cvt_pk_f16_f32 v22, v22, v23
	v_div_scale_f32 v23, s[0:1], v79, v79, 1.0
	v_rcp_f32_e32 v82, v23
	s_nop 0
	v_fma_f32 v83, -v23, v82, 1.0
	v_fmac_f32_e32 v82, v83, v82
	v_div_scale_f32 v83, vcc, 1.0, v79, 1.0
	v_mul_f32_e32 v84, v83, v82
	v_fma_f32 v85, -v23, v84, v83
	v_fmac_f32_e32 v84, v85, v82
	v_fma_f32 v23, -v23, v84, v83
	v_div_fmas_f32 v23, v23, v82, v84
	v_div_fixup_f32 v79, v23, v79, 1.0
	v_div_scale_f32 v23, s[0:1], v78, v78, 1.0
	v_rcp_f32_e32 v82, v23
	s_nop 0
	v_fma_f32 v83, -v23, v82, 1.0
	v_fmac_f32_e32 v82, v83, v82
	v_div_scale_f32 v83, vcc, 1.0, v78, 1.0
	v_mul_f32_e32 v84, v83, v82
	v_fma_f32 v85, -v23, v84, v83
	v_fmac_f32_e32 v84, v85, v82
	v_fma_f32 v23, -v23, v84, v83
	v_div_fmas_f32 v23, v23, v82, v84
	v_div_fixup_f32 v78, v23, v78, 1.0
	v_pk_add_f32 v[82:83], v[78:79], -1.0 op_sel_hi:[1,0]
	s_nop 0
	v_pk_fma_f32 v[24:25], v[82:83], v[24:25], 1.0 op_sel_hi:[1,1,0]
	v_cvt_f32_f16_e32 v82, v44
	v_pk_mul_f32 v[24:25], v[24:25], v[42:43]
	v_cvt_f32_f16_sdwa v83, v44 dst_sel:DWORD dst_unused:UNUSED_PAD src0_sel:WORD_1
	v_cvt_pk_f16_f32 v23, v24, v25
	v_pk_add_f32 v[24:25], v[74:75], 1.0 op_sel_hi:[1,0]
	s_nop 0
	v_div_scale_f32 v44, s[0:1], v25, v25, 1.0
	v_rcp_f32_e32 v74, v44
	s_nop 0
	v_fma_f32 v75, -v44, v74, 1.0
	v_fmac_f32_e32 v74, v75, v74
	v_div_scale_f32 v75, vcc, 1.0, v25, 1.0
	v_mul_f32_e32 v84, v75, v74
	v_fma_f32 v85, -v44, v84, v75
	v_fmac_f32_e32 v84, v85, v74
	v_fma_f32 v44, -v44, v84, v75
	v_div_fmas_f32 v44, v44, v74, v84
	v_div_fixup_f32 v75, v44, v25, 1.0
	v_div_scale_f32 v25, s[0:1], v24, v24, 1.0
	v_rcp_f32_e32 v44, v25
	s_nop 0
	v_fma_f32 v74, -v25, v44, 1.0
	v_fmac_f32_e32 v44, v74, v44
	v_div_scale_f32 v74, vcc, 1.0, v24, 1.0
	v_mul_f32_e32 v84, v74, v44
	v_fma_f32 v85, -v25, v84, v74
	v_fmac_f32_e32 v84, v85, v44
	v_fma_f32 v25, -v25, v84, v74
	v_div_fmas_f32 v25, v25, v44, v84
	v_div_fixup_f32 v74, v25, v24, 1.0
	v_pk_add_f32 v[24:25], v[74:75], -1.0 op_sel_hi:[1,0]
	v_cvt_f32_f16_e32 v44, v45
	v_pk_fma_f32 v[18:19], v[24:25], v[18:19], 1.0 op_sel_hi:[1,1,0]
	v_cvt_f32_f16_sdwa v45, v45 dst_sel:DWORD dst_unused:UNUSED_PAD src0_sel:WORD_1
	v_pk_mul_f32 v[18:19], v[18:19], v[82:83]
	v_pk_mul_f32 v[36:37], v[36:37], v[44:45]
	v_cvt_pk_f16_f32 v24, v18, v19
	v_pk_add_f32 v[18:19], v[68:69], 1.0 op_sel_hi:[1,0]
	s_nop 0
	v_div_scale_f32 v25, s[0:1], v19, v19, 1.0
	v_rcp_f32_e32 v68, v25
	s_nop 0
	v_fma_f32 v69, -v25, v68, 1.0
	v_fmac_f32_e32 v68, v69, v68
	v_div_scale_f32 v69, vcc, 1.0, v19, 1.0
	v_mul_f32_e32 v84, v69, v68
	v_fma_f32 v85, -v25, v84, v69
	v_fmac_f32_e32 v84, v85, v68
	v_fma_f32 v25, -v25, v84, v69
	v_div_fmas_f32 v25, v25, v68, v84
	v_div_fixup_f32 v19, v25, v19, 1.0
	v_div_scale_f32 v25, s[0:1], v18, v18, 1.0
	v_rcp_f32_e32 v68, v25
	s_nop 0
	v_fma_f32 v69, -v25, v68, 1.0
	v_fmac_f32_e32 v68, v69, v68
	v_div_scale_f32 v69, vcc, 1.0, v18, 1.0
	v_mul_f32_e32 v84, v69, v68
	v_fma_f32 v85, -v25, v84, v69
	v_fmac_f32_e32 v84, v85, v68
	v_fma_f32 v25, -v25, v84, v69
	v_div_fmas_f32 v25, v25, v68, v84
	v_div_fixup_f32 v18, v25, v18, 1.0
	v_pk_add_f32 v[68:69], v[18:19], -1.0 op_sel_hi:[1,0]
	s_nop 0
	v_pk_fma_f32 v[20:21], v[68:69], v[20:21], 1.0 op_sel_hi:[1,1,0]
	s_nop 0
	v_pk_mul_f32 v[20:21], v[20:21], v[44:45]
	v_lshlrev_b64 v[44:45], 12, v[58:59]
	v_cvt_pk_f16_f32 v25, v20, v21
	global_store_dwordx4 v[66:67], v[22:25], off
	v_pk_mul_f32 v[20:21], v[38:39], v[80:81]
	v_pk_mul_f32 v[38:39], v[36:37], v[36:37]
	v_pk_mul_f32 v[24:25], v[34:35], v[82:83]
	v_pk_mul_f32 v[22:23], v[40:41], v[42:43]
	v_pk_mul_f32 v[34:35], v[24:25], v[24:25]
	v_pk_fma_f32 v[38:39], v[22:23], v[22:23], v[38:39]
	v_pk_fma_f32 v[34:35], v[20:21], v[20:21], v[34:35]
	s_nop 0
	v_add_f32_e32 v34, v34, v35
	v_add_f32_e32 v34, v38, v34
	v_add_f32_e32 v34, v39, v34
	v_add_f32_e32 v34, v34, v70
	v_add_f32_e32 v34, v71, v34
	v_add_f32_e32 v34, v72, v34
	v_add_f32_e32 v34, v73, v34
	ds_bpermute_b32 v35, v206, v34
	s_waitcnt lgkmcnt(0)
;     __device__ __forceinline__ void body_a(const f32x4 (&acc)[2][2][4][2], int row0, int cb0) const {
;     ...
;                 ss += __shfl_xor(ss, 16); ss += __shfl_xor(ss, 32);
;                 const float inv = 1.0f / fmaxf(sqrtf(ss), 1e-12f);
; #pragma unroll
;                 for (int bj = 0; bj < 2; ++bj) {
;                     const int c = cb0 + 32 * bj;
;                     const f32x4 p0 = *(const f32x4*)(k_a + c), p1 = *(const f32x4*)(k_a + c + 4);
;                     f32x4 ko0, ko1, ao0, ao1, bo0, bo1;
; #pragma unroll
;                     for (int e = 0; e < 4; ++e) {
;                         ko0[e] = kv[bj][e] * (1.0f + (a[bj][e] - 1.0f) * p0[e]); ko1[e] = kv[bj][4 + e] * (1.0f + (a[bj][4 + e] - 1.0f) * p1[e]);
;                         const float n0_ = kk[bj][e] * inv, n1_ = kk[bj][4 + e] * inv;
;                         ao0[e] = -n0_; ao1[e] = -n1_; bo0[e] = n0_ * a[bj][e]; bo1[e] = n1_ * a[bj][4 + e];
;                     }
;                     *(u32x4*)(C1 + row * LDC1 + 2048 + c) = pack8(ko0, ko1);
;                     *(u32x4*)(AA + row * DM + c) = pack8(ao0, ao1);
;                     *(u32x4*)(Ab + row * DM + c) = pack8(bo0, bo1);
	v_add_f32_e32 v34, v34, v35
	ds_bpermute_b32 v35, v207, v34
	s_waitcnt lgkmcnt(0)
	v_add_f32_e32 v34, v34, v35
	v_cmp_gt_f32_e32 vcc, s4, v34
	v_mul_f32_e32 v35, 0x4f800000, v34
	s_nop 0
	v_cndmask_b32_e32 v34, v34, v35, vcc
	v_sqrt_f32_e32 v35, v34
	s_nop 0
	v_add_u32_e32 v38, -1, v35
	v_fma_f32 v39, -v38, v35, v34
	v_cmp_ge_f32_e64 s[0:1], 0, v39
	v_add_u32_e32 v39, 1, v35
	s_nop 0
	v_cndmask_b32_e64 v38, v35, v38, s[0:1]
	v_fma_f32 v35, -v39, v35, v34
	v_cmp_lt_f32_e64 s[0:1], 0, v35
	s_nop 1
	v_cndmask_b32_e64 v35, v38, v39, s[0:1]
	v_mul_f32_e32 v38, 0x37800000, v35
	v_cndmask_b32_e32 v35, v35, v38, vcc
	v_cmp_class_f32_e32 vcc, v34, v244
	s_nop 1
	v_cndmask_b32_e32 v34, v35, v34, vcc
	v_max_f32_e32 v34, 0x2b8cbccc, v34
	v_div_scale_f32 v35, s[0:1], v34, v34, 1.0
	v_rcp_f32_e32 v38, v35
	s_nop 0
	v_fma_f32 v39, -v35, v38, 1.0
	v_fmac_f32_e32 v38, v39, v38
	v_div_scale_f32 v39, vcc, 1.0, v34, 1.0
	v_mul_f32_e32 v40, v39, v38
	v_fma_f32 v41, -v35, v40, v39
	v_fmac_f32_e32 v40, v41, v38
	v_fma_f32 v35, -v35, v40, v39
	v_div_fmas_f32 v35, v35, v38, v40
	v_div_fixup_f32 v38, v35, v34, 1.0
	v_pk_mul_f32 v[42:43], v[22:23], v[38:39] op_sel_hi:[1,0]
	v_pk_mul_f32 v[40:41], v[20:21], v[38:39] op_sel_hi:[1,0]
	v_cvt_pk_f16_f32 v21, v42, v43
	v_cvt_pk_f16_f32 v20, v40, v41
	v_xor_b32_e32 v22, 0x8000, v21
	v_xor_b32_sdwa v21, s63, v21 dst_sel:DWORD dst_unused:UNUSED_PAD src0_sel:DWORD src1_sel:WORD_1
	v_pk_mul_f32 v[24:25], v[24:25], v[38:39] op_sel_hi:[1,0]
	v_pk_mul_f32 v[36:37], v[36:37], v[38:39] op_sel_hi:[1,0]
	v_perm_b32 v21, v21, v22, s33
	v_xor_b32_e32 v22, 0x8000, v20
	v_xor_b32_sdwa v20, s63, v20 dst_sel:DWORD dst_unused:UNUSED_PAD src0_sel:DWORD src1_sel:WORD_1
	v_perm_b32 v20, v20, v22, s33
	v_pk_add_f32 v[22:23], v[24:25], 0 neg_lo:[1,1] neg_hi:[1,1]
	v_pk_add_f32 v[34:35], v[36:37], 0 neg_lo:[1,1] neg_hi:[1,1]
	v_cvt_pk_f16_f32 v22, v22, v23
	v_cvt_pk_f16_f32 v23, v34, v35
	v_lshl_add_u64 v[34:35], s[10:11], 0, v[44:45]
	v_lshl_add_u64 v[34:35], v[34:35], 0, v[152:153]
	global_store_dwordx4 v[34:35], v[20:23], off
	v_fma_mixlo_f16 v39, v76, v40, 0
	v_mul_f32_e32 v58, v30, v38
	v_pk_mov_b32 v[20:21], v[76:77], v[78:79] op_sel:[1,0]
	v_pk_mov_b32 v[22:23], v[40:41], v[42:43] op_sel:[1,0]
	v_pk_mov_b32 v[40:41], v[42:43], v[24:25] op_sel:[1,0]
	v_pk_mul_f32 v[20:21], v[20:21], v[22:23]
	v_pk_mov_b32 v[22:23], v[78:79], v[74:75] op_sel:[1,0]
	v_cvt_pk_f16_f32 v21, v20, v21
	v_pk_mul_f32 v[22:23], v[22:23], v[40:41]
	v_pack_b32_f16 v20, v39, v21
	v_cvt_pk_f16_f32 v39, v22, v23
	v_pk_mov_b32 v[22:23], v[74:75], v[18:19] op_sel:[1,0]
	v_pk_mov_b32 v[24:25], v[24:25], v[36:37] op_sel:[1,0]
	v_alignbit_b32 v21, v39, v21, 16
	v_pk_mul_f32 v[22:23], v[22:23], v[24:25]
	v_pk_add_f32 v[40:41], v[64:65], 1.0 op_sel_hi:[1,0]
	v_cvt_pk_f16_f32 v18, v22, v23
	v_lshrrev_b32_e32 v23, 16, v18
	v_alignbit_b32 v22, v18, v39, 16
	v_fma_mixhi_f16 v23, v19, v37, 0
	v_lshl_add_u64 v[18:19], s[2:3], 0, v[44:45]
	v_lshl_add_u64 v[36:37], v[18:19], 0, v[152:153]
	global_store_dwordx4 v[36:37], v[20:23], off
	global_load_dwordx4 v[18:21], v[126:127], off offset:144
	s_nop 0
	global_load_dwordx4 v[22:25], v[126:127], off offset:128
	v_div_scale_f32 v42, s[0:1], v41, v41, 1.0
	v_rcp_f32_e32 v43, v42
	v_mul_f32_e32 v39, v33, v38
	v_fma_f32 v44, -v42, v43, 1.0
	v_fmac_f32_e32 v43, v44, v43
	v_div_scale_f32 v44, vcc, 1.0, v41, 1.0
	v_mul_f32_e32 v45, v44, v43
	v_fma_f32 v59, -v42, v45, v44
	v_fmac_f32_e32 v45, v59, v43
	v_fma_f32 v42, -v42, v45, v44
	v_div_fmas_f32 v42, v42, v43, v45
	v_div_fixup_f32 v41, v42, v41, 1.0
	v_div_scale_f32 v42, s[0:1], v40, v40, 1.0
	v_rcp_f32_e32 v43, v42
	s_nop 0
	v_fma_f32 v44, -v42, v43, 1.0
	v_fmac_f32_e32 v43, v44, v43
	v_div_scale_f32 v44, vcc, 1.0, v40, 1.0
	v_mul_f32_e32 v45, v44, v43
	v_fma_f32 v59, -v42, v45, v44
	v_fmac_f32_e32 v45, v59, v43
	v_fma_f32 v42, -v42, v45, v44
	v_div_fmas_f32 v42, v42, v43, v45
	v_div_fixup_f32 v40, v42, v40, 1.0
	v_pk_add_f32 v[42:43], v[40:41], -1.0 op_sel_hi:[1,0]
	s_waitcnt vmcnt(0)
	v_pk_fma_f32 v[22:23], v[42:43], v[22:23], 1.0 op_sel_hi:[1,1,0]
	s_nop 0
	v_pk_mul_f32 v[22:23], v[22:23], v[62:63]
	v_pk_add_f32 v[42:43], v[60:61], 1.0 op_sel_hi:[1,0]
	v_cvt_pk_f16_f32 v22, v22, v23
	v_div_scale_f32 v23, s[0:1], v43, v43, 1.0
	v_rcp_f32_e32 v44, v23
	s_nop 0
	v_fma_f32 v45, -v23, v44, 1.0
	v_fmac_f32_e32 v44, v45, v44
	v_div_scale_f32 v45, vcc, 1.0, v43, 1.0
	v_mul_f32_e32 v59, v45, v44
	v_fma_f32 v60, -v23, v59, v45
	v_fmac_f32_e32 v59, v60, v44
	v_fma_f32 v23, -v23, v59, v45
	v_div_fmas_f32 v23, v23, v44, v59
	v_div_fixup_f32 v43, v23, v43, 1.0
	v_div_scale_f32 v23, s[0:1], v42, v42, 1.0
	v_rcp_f32_e32 v44, v23
	s_nop 0
	v_fma_f32 v45, -v23, v44, 1.0
	v_fmac_f32_e32 v44, v45, v44
	v_div_scale_f32 v45, vcc, 1.0, v42, 1.0
	v_mul_f32_e32 v59, v45, v44
	v_fma_f32 v60, -v23, v59, v45
	v_fmac_f32_e32 v59, v60, v44
	v_fma_f32 v23, -v23, v59, v45
	v_div_fmas_f32 v23, v23, v44, v59
	v_div_fixup_f32 v42, v23, v42, 1.0
	v_pk_add_f32 v[44:45], v[42:43], -1.0 op_sel_hi:[1,0]
	s_nop 0
	v_pk_fma_f32 v[24:25], v[44:45], v[24:25], 1.0 op_sel_hi:[1,1,0]
	s_nop 0
	v_pk_mul_f32 v[24:25], v[24:25], v[56:57]
	s_nop 0
	v_cvt_pk_f16_f32 v23, v24, v25
	v_pk_add_f32 v[24:25], v[54:55], 1.0 op_sel_hi:[1,0]
	s_nop 0
	v_div_scale_f32 v44, s[0:1], v25, v25, 1.0
	v_rcp_f32_e32 v45, v44
	s_nop 0
	v_fma_f32 v54, -v44, v45, 1.0
	v_fmac_f32_e32 v45, v54, v45
	v_div_scale_f32 v54, vcc, 1.0, v25, 1.0
	v_mul_f32_e32 v55, v54, v45
	v_fma_f32 v56, -v44, v55, v54
	v_fmac_f32_e32 v55, v56, v45
	v_fma_f32 v44, -v44, v55, v54
	v_div_fmas_f32 v44, v44, v45, v55
	v_div_fixup_f32 v45, v44, v25, 1.0
	v_div_scale_f32 v25, s[0:1], v24, v24, 1.0
; __device__ __forceinline__ float sigmoidf_(float x) { return 1.0f / (1.0f + __expf(-x)); }
;     __device__ __forceinline__ void body_a(const f32x4 (&acc)[2][2][4][2], int row0, int cb0) const {
;     ...
;                 const size_t row = (size_t)(row0 + ai * 128 + m * 16);
;                 asm volatile("" ::: "memory");
;                 float a[2][8], kv[2][8], kk[2][8]; float ss = 0.f;
; #pragma unroll
;                 for (int bj = 0; bj < 2; ++bj) {
;                     const int c = cb0 + 32 * bj;
;                     const f32x4 b0 = *(const f32x4*)(a0 + c), b1 = *(const f32x4*)(a0 + c + 4), q0 = *(const f32x4*)(k_k + c), q1 = *(const f32x4*)(k_k + c + 4);
;                     const h16x8 kh = *(const h16x8*)(C1 + row * LDC1 + 2048 + c);
; #pragma unroll
;                     for (int e = 0; e < 4; ++e) {
;                         a[bj][e] = sigmoidf_(acc[ai][bj][m][0][e] + b0[e]); a[bj][4 + e] = sigmoidf_(acc[ai][bj][m][1][e] + b1[e]);
;                         kv[bj][e] = (float)kh[e]; kv[bj][4 + e] = (float)kh[4 + e];
;                         kk[bj][e] = kv[bj][e] * q0[e]; kk[bj][4 + e] = kv[bj][4 + e] * q1[e];
;                         ss += kk[bj][e] * kk[bj][e] + kk[bj][4 + e] * kk[bj][4 + e];
;     ...
;                 for (int bj = 0; bj < 2; ++bj) {
;                     const int c = cb0 + 32 * bj;
;                     const f32x4 p0 = *(const f32x4*)(k_a + c), p1 = *(const f32x4*)(k_a + c + 4);
;                     f32x4 ko0, ko1, ao0, ao1, bo0, bo1;
; #pragma unroll
;                     for (int e = 0; e < 4; ++e) {
;                         ko0[e] = kv[bj][e] * (1.0f + (a[bj][e] - 1.0f) * p0[e]); ko1[e] = kv[bj][4 + e] * (1.0f + (a[bj][4 + e] - 1.0f) * p1[e]);
;                         const float n0_ = kk[bj][e] * inv, n1_ = kk[bj][4 + e] * inv;
;                         ao0[e] = -n0_; ao1[e] = -n1_; bo0[e] = n0_ * a[bj][e]; bo1[e] = n1_ * a[bj][4 + e];
;                     }
;                     *(u32x4*)(C1 + row * LDC1 + 2048 + c) = pack8(ko0, ko1);
;                     *(u32x4*)(AA + row * DM + c) = pack8(ao0, ao1);
;                     *(u32x4*)(Ab + row * DM + c) = pack8(bo0, bo1);
	v_rcp_f32_e32 v44, v25
	s_nop 0
	v_fma_f32 v54, -v25, v44, 1.0
	v_fmac_f32_e32 v44, v54, v44
	v_div_scale_f32 v54, vcc, 1.0, v24, 1.0
	v_mul_f32_e32 v55, v54, v44
	v_fma_f32 v56, -v25, v55, v54
	v_fmac_f32_e32 v55, v56, v44
	v_fma_f32 v25, -v25, v55, v54
	v_div_fmas_f32 v25, v25, v44, v55
	v_div_fixup_f32 v44, v25, v24, 1.0
	v_pk_add_f32 v[24:25], v[44:45], -1.0 op_sel_hi:[1,0]
	s_nop 0
	v_pk_fma_f32 v[18:19], v[24:25], v[18:19], 1.0 op_sel_hi:[1,1,0]
	s_nop 0
	v_pk_mul_f32 v[18:19], v[18:19], v[52:53]
	s_nop 0
	v_cvt_pk_f16_f32 v24, v18, v19
	v_pk_add_f32 v[18:19], v[50:51], 1.0 op_sel_hi:[1,0]
	s_nop 0
	v_div_scale_f32 v25, s[0:1], v19, v19, 1.0
	v_rcp_f32_e32 v50, v25
	s_nop 0
	v_fma_f32 v51, -v25, v50, 1.0
	v_fmac_f32_e32 v50, v51, v50
	v_div_scale_f32 v51, vcc, 1.0, v19, 1.0
	v_mul_f32_e32 v52, v51, v50
	v_fma_f32 v53, -v25, v52, v51
	v_fmac_f32_e32 v52, v53, v50
	v_fma_f32 v25, -v25, v52, v51
	v_div_fmas_f32 v25, v25, v50, v52
	v_div_fixup_f32 v51, v25, v19, 1.0
	v_div_scale_f32 v19, s[0:1], v18, v18, 1.0
	v_rcp_f32_e32 v25, v19
	s_nop 0
	v_fma_f32 v50, -v19, v25, 1.0
	v_fmac_f32_e32 v25, v50, v25
	v_div_scale_f32 v50, vcc, 1.0, v18, 1.0
	v_mul_f32_e32 v52, v50, v25
	v_fma_f32 v53, -v19, v52, v50
	v_fmac_f32_e32 v52, v53, v25
	v_fma_f32 v19, -v19, v52, v50
	v_div_fmas_f32 v19, v19, v25, v52
	v_div_fixup_f32 v50, v19, v18, 1.0
	v_pk_add_f32 v[18:19], v[50:51], -1.0 op_sel_hi:[1,0]
	s_nop 0
	v_pk_fma_f32 v[18:19], v[18:19], v[20:21], 1.0 op_sel_hi:[1,1,0]
	v_cvt_f16_f32_e64 v20, -v58
	v_pk_mul_f32 v[18:19], v[18:19], v[48:49]
	s_nop 0
	v_cvt_pk_f16_f32 v25, v18, v19
	v_pk_mov_b32 v[18:19], v[30:31], v[46:47] op_sel:[1,0]
	global_store_dwordx4 v[26:27], v[22:25], off
	s_nop 1
	v_pk_mul_f32 v[22:23], v[18:19], v[38:39] op_sel_hi:[1,0]
	s_nop 0
	v_cvt_pk_f16_f32 v19, v22, v23
	v_pack_b32_f16 v18, v20, -v19
	v_pk_mov_b32 v[20:21], v[46:47], v[28:29] op_sel:[1,0]
	v_xor_b32_sdwa v19, s63, v19 dst_sel:DWORD dst_unused:UNUSED_PAD src0_sel:DWORD src1_sel:WORD_1
	v_pk_mul_f32 v[24:25], v[20:21], v[38:39] op_sel_hi:[1,0]
	s_nop 0
	v_cvt_pk_f16_f32 v20, v24, v25
	v_xor_b32_e32 v21, 0x8000, v20
	v_perm_b32 v19, v21, v19, s33
	v_xor_b32_sdwa v30, s63, v20 dst_sel:DWORD dst_unused:UNUSED_PAD src0_sel:DWORD src1_sel:WORD_1
	v_pk_mov_b32 v[20:21], v[28:29], v[32:33] op_sel:[1,0]
	v_cvt_f16_f32_e64 v28, -v39
	v_pk_mul_f32 v[26:27], v[20:21], v[38:39] op_sel_hi:[1,0]
	s_nop 0
	v_cvt_pk_f16_f32 v21, v26, v27
	v_xor_b32_e32 v20, 0x8000, v21
	v_xor_b32_sdwa v21, s63, v21 dst_sel:DWORD dst_unused:UNUSED_PAD src0_sel:DWORD src1_sel:WORD_1
	v_perm_b32 v20, v20, v30, s33
	v_perm_b32 v21, v28, v21, s33
	global_store_dwordx4 v[34:35], v[18:21], off offset:64
	s_nop 1
	v_pk_mov_b32 v[18:19], v[40:41], v[42:43] op_sel:[1,0]
	v_fma_mixlo_f16 v20, v40, v58, 0
	v_pk_mul_f32 v[18:19], v[18:19], v[22:23]
	s_nop 0
	v_cvt_pk_f16_f32 v19, v18, v19
	v_pack_b32_f16 v18, v20, v19
	v_pk_mov_b32 v[20:21], v[42:43], v[44:45] op_sel:[1,0]
	s_nop 0
	v_pk_mul_f32 v[20:21], v[20:21], v[24:25]
	s_nop 0
	v_cvt_pk_f16_f32 v22, v20, v21
	v_pk_mov_b32 v[20:21], v[44:45], v[50:51] op_sel:[1,0]
	v_alignbit_b32 v19, v22, v19, 16
	v_pk_mul_f32 v[20:21], v[20:21], v[26:27]
	s_nop 0
	v_cvt_pk_f16_f32 v21, v20, v21
	v_alignbit_b32 v20, v21, v22, 16
	v_lshrrev_b32_e32 v21, 16, v21
	v_fma_mixhi_f16 v21, v51, v39, 0
	global_store_dwordx4 v[36:37], v[18:21], off offset:64
	v_add_u32_e32 v42, 0xb0, v158
	s_nop 0
	v_mad_i64_i32 v[18:19], s[0:1], v42, s5, v[160:161]
	v_lshl_add_u64 v[38:39], v[18:19], 0, s[6:7]
	global_load_dwordx4 v[30:33], v[154:155], off offset:16
	global_load_dwordx4 v[34:37], v[154:155], off
	global_load_dwordx4 v[18:21], v[156:157], off offset:16
	global_load_dwordx4 v[22:25], v[156:157], off
	v_lshl_add_u64 v[50:51], v[38:39], 0, v[152:153]
	global_load_dwordx4 v[26:29], v[50:51], off
	v_ashrrev_i32_e32 v43, 31, v42
	s_waitcnt vmcnt(4)
	v_add_f32_e32 v10, v10, v30
	v_mul_f32_e32 v10, 0xbfb8aa3b, v10
	v_exp_f32_e32 v58, v10
	s_waitcnt vmcnt(3)
	v_add_f32_e32 v10, v15, v35
	v_mul_f32_e32 v10, 0xbfb8aa3b, v10
	v_exp_f32_e32 v61, v10
	v_add_f32_e32 v10, v11, v31
	v_mul_f32_e32 v10, 0xbfb8aa3b, v10
	v_exp_f32_e32 v59, v10
	v_add_f32_e32 v10, v16, v36
	v_mul_f32_e32 v10, 0xbfb8aa3b, v10
	v_exp_f32_e32 v62, v10
	v_add_f32_e32 v10, v12, v32
	v_mul_f32_e32 v10, 0xbfb8aa3b, v10
	v_exp_f32_e32 v52, v10
	v_add_f32_e32 v10, v17, v37
	v_mul_f32_e32 v10, 0xbfb8aa3b, v10
	v_exp_f32_e32 v63, v10
	v_add_f32_e32 v10, v13, v33
	v_add_f32_e32 v14, v14, v34
	v_mul_f32_e32 v10, 0xbfb8aa3b, v10
	v_mul_f32_e32 v14, 0xbfb8aa3b, v14
	v_exp_f32_e32 v53, v10
	v_lshl_add_u64 v[10:11], v[38:39], 0, v[128:129]
	v_exp_f32_e32 v60, v14
	global_load_dwordx4 v[14:17], v[154:155], off offset:144
	global_load_dwordx4 v[30:33], v[154:155], off offset:128
	global_load_dwordx4 v[54:57], v[156:157], off offset:144
	global_load_dwordx4 v[64:67], v[156:157], off offset:128
	global_load_dwordx4 v[68:71], v[10:11], off
	v_pk_add_f32 v[62:63], v[62:63], 1.0 op_sel_hi:[1,0]
	v_pk_add_f32 v[60:61], v[60:61], 1.0 op_sel_hi:[1,0]
	s_waitcnt vmcnt(4)
	v_add_f32_e32 v2, v2, v14
	v_mul_f32_e32 v2, 0xbfb8aa3b, v2
	v_exp_f32_e32 v38, v2
	s_waitcnt vmcnt(3)
	v_add_f32_e32 v2, v7, v31
	s_waitcnt vmcnt(0)
; __device__ __forceinline__ float sigmoidf_(float x) { return 1.0f / (1.0f + __expf(-x)); }
;     __device__ __forceinline__ void body_a(const f32x4 (&acc)[2][2][4][2], int row0, int cb0) const {
;     ...
;                     const f32x4 b0 = *(const f32x4*)(a0 + c), b1 = *(const f32x4*)(a0 + c + 4), q0 = *(const f32x4*)(k_k + c), q1 = *(const f32x4*)(k_k + c + 4);
;                     const h16x8 kh = *(const h16x8*)(C1 + row * LDC1 + 2048 + c);
; #pragma unroll
;                     for (int e = 0; e < 4; ++e) {
;                         a[bj][e] = sigmoidf_(acc[ai][bj][m][0][e] + b0[e]); a[bj][4 + e] = sigmoidf_(acc[ai][bj][m][1][e] + b1[e]);
;                         kv[bj][e] = (float)kh[e]; kv[bj][4 + e] = (float)kh[4 + e];
;                         kk[bj][e] = kv[bj][e] * q0[e]; kk[bj][4 + e] = kv[bj][4 + e] * q1[e];
;                         ss += kk[bj][e] * kk[bj][e] + kk[bj][4 + e] * kk[bj][4 + e];
;                     }
;                 }
;                 ss += __shfl_xor(ss, 16); ss += __shfl_xor(ss, 32);
;     ...
;                         ko0[e] = kv[bj][e] * (1.0f + (a[bj][e] - 1.0f) * p0[e]); ko1[e] = kv[bj][4 + e] * (1.0f + (a[bj][4 + e] - 1.0f) * p1[e]);
;                         const float n0_ = kk[bj][e] * inv, n1_ = kk[bj][4 + e] * inv;
;                         ao0[e] = -n0_; ao1[e] = -n1_; bo0[e] = n0_ * a[bj][e]; bo1[e] = n1_ * a[bj][4 + e];
;                     }
;                     *(u32x4*)(C1 + row * LDC1 + 2048 + c) = pack8(ko0, ko1);
	v_cvt_f32_f16_e32 v36, v70
	v_cvt_f32_f16_sdwa v37, v70 dst_sel:DWORD dst_unused:UNUSED_PAD src0_sel:WORD_1
	v_cvt_f32_f16_e32 v46, v68
	v_cvt_f32_f16_sdwa v47, v68 dst_sel:DWORD dst_unused:UNUSED_PAD src0_sel:WORD_1
	v_mul_f32_e32 v2, 0xbfb8aa3b, v2
	v_exp_f32_e32 v49, v2
	v_add_f32_e32 v2, v3, v15
	v_mul_f32_e32 v2, 0xbfb8aa3b, v2
	v_pk_mul_f32 v[12:13], v[54:55], v[36:37]
	v_exp_f32_e32 v39, v2
	v_pk_mul_f32 v[14:15], v[64:65], v[46:47]
	v_pk_mul_f32 v[2:3], v[12:13], v[12:13]
	v_cvt_f32_f16_e32 v40, v69
	v_pk_fma_f32 v[54:55], v[14:15], v[14:15], v[2:3]
	v_add_f32_e32 v2, v8, v32
	v_mul_f32_e32 v2, 0xbfb8aa3b, v2
	v_exp_f32_e32 v44, v2
	v_add_f32_e32 v2, v4, v16
	v_mul_f32_e32 v2, 0xbfb8aa3b, v2
	v_exp_f32_e32 v34, v2
	v_add_f32_e32 v2, v9, v33
	v_cvt_f32_f16_e32 v32, v71
	v_cvt_f32_f16_sdwa v33, v71 dst_sel:DWORD dst_unused:UNUSED_PAD src0_sel:WORD_1
	v_cvt_f32_f16_sdwa v41, v69 dst_sel:DWORD dst_unused:UNUSED_PAD src0_sel:WORD_1
	v_mul_f32_e32 v2, 0xbfb8aa3b, v2
	v_exp_f32_e32 v45, v2
	v_add_f32_e32 v2, v5, v17
	v_add_f32_e32 v6, v6, v30
	v_mul_f32_e32 v2, 0xbfb8aa3b, v2
	v_pk_mul_f32 v[16:17], v[56:57], v[32:33]
	v_mul_f32_e32 v6, 0xbfb8aa3b, v6
	v_exp_f32_e32 v35, v2
	v_pk_mul_f32 v[30:31], v[66:67], v[40:41]
	v_pk_mul_f32 v[2:3], v[16:17], v[16:17]
	v_exp_f32_e32 v48, v6
	v_pk_fma_f32 v[56:57], v[30:31], v[30:31], v[2:3]
	global_load_dwordx4 v[2:5], v[126:127], off offset:16
	global_load_dwordx4 v[6:9], v[126:127], off
	v_cvt_f32_f16_e32 v64, v26
	v_cvt_f32_f16_sdwa v65, v26 dst_sel:DWORD dst_unused:UNUSED_PAD src0_sel:WORD_1
	v_div_scale_f32 v26, s[0:1], v61, v61, 1.0
	v_rcp_f32_e32 v66, v26
	s_nop 0
	v_fma_f32 v67, -v26, v66, 1.0
	v_fmac_f32_e32 v66, v67, v66
	v_div_scale_f32 v67, vcc, 1.0, v61, 1.0
	v_mul_f32_e32 v68, v67, v66
	v_fma_f32 v69, -v26, v68, v67
	v_fmac_f32_e32 v68, v69, v66
	v_fma_f32 v26, -v26, v68, v67
	v_div_fmas_f32 v26, v26, v66, v68
	v_div_fixup_f32 v61, v26, v61, 1.0
	v_div_scale_f32 v26, s[0:1], v60, v60, 1.0
	v_rcp_f32_e32 v66, v26
	s_nop 0
	v_fma_f32 v67, -v26, v66, 1.0
	v_fmac_f32_e32 v66, v67, v66
	v_div_scale_f32 v67, vcc, 1.0, v60, 1.0
	v_mul_f32_e32 v68, v67, v66
	v_fma_f32 v69, -v26, v68, v67
	v_fmac_f32_e32 v68, v69, v66
	v_fma_f32 v26, -v26, v68, v67
	v_div_fmas_f32 v26, v26, v66, v68
	v_div_fixup_f32 v60, v26, v60, 1.0
	v_pk_add_f32 v[66:67], v[60:61], -1.0 op_sel_hi:[1,0]
	v_cvt_f32_f16_e32 v26, v27
	v_cvt_f32_f16_sdwa v27, v27 dst_sel:DWORD dst_unused:UNUSED_PAD src0_sel:WORD_1
	s_waitcnt vmcnt(0)
	v_pk_fma_f32 v[6:7], v[66:67], v[6:7], 1.0 op_sel_hi:[1,1,0]
	s_nop 0
	v_pk_mul_f32 v[6:7], v[6:7], v[64:65]
	s_nop 0
	v_cvt_pk_f16_f32 v6, v6, v7
	v_div_scale_f32 v7, s[0:1], v63, v63, 1.0
	v_rcp_f32_e32 v66, v7
	s_nop 0
	v_fma_f32 v67, -v7, v66, 1.0
	v_fmac_f32_e32 v66, v67, v66
	v_div_scale_f32 v67, vcc, 1.0, v63, 1.0
	v_mul_f32_e32 v68, v67, v66
	v_fma_f32 v69, -v7, v68, v67
	v_fmac_f32_e32 v68, v69, v66
	v_fma_f32 v7, -v7, v68, v67
	v_div_fmas_f32 v7, v7, v66, v68
	v_div_fixup_f32 v63, v7, v63, 1.0
	v_div_scale_f32 v7, s[0:1], v62, v62, 1.0
	v_rcp_f32_e32 v66, v7
	s_nop 0
	v_fma_f32 v67, -v7, v66, 1.0
	v_fmac_f32_e32 v66, v67, v66
	v_div_scale_f32 v67, vcc, 1.0, v62, 1.0
	v_mul_f32_e32 v68, v67, v66
	v_fma_f32 v69, -v7, v68, v67
	v_fmac_f32_e32 v68, v69, v66
	v_fma_f32 v7, -v7, v68, v67
	v_div_fmas_f32 v7, v7, v66, v68
	v_div_fixup_f32 v62, v7, v62, 1.0
	v_pk_add_f32 v[66:67], v[62:63], -1.0 op_sel_hi:[1,0]
	s_nop 0
	v_pk_fma_f32 v[8:9], v[66:67], v[8:9], 1.0 op_sel_hi:[1,1,0]
	v_cvt_f32_f16_e32 v66, v28
	v_pk_mul_f32 v[8:9], v[8:9], v[26:27]
	v_cvt_f32_f16_sdwa v67, v28 dst_sel:DWORD dst_unused:UNUSED_PAD src0_sel:WORD_1
	v_cvt_pk_f16_f32 v7, v8, v9
	v_pk_add_f32 v[8:9], v[58:59], 1.0 op_sel_hi:[1,0]
	s_nop 0
	v_div_scale_f32 v28, s[0:1], v9, v9, 1.0
	v_rcp_f32_e32 v58, v28
	s_nop 0
	v_fma_f32 v59, -v28, v58, 1.0
	v_fmac_f32_e32 v58, v59, v58
	v_div_scale_f32 v59, vcc, 1.0, v9, 1.0
	v_mul_f32_e32 v68, v59, v58
	v_fma_f32 v69, -v28, v68, v59
	v_fmac_f32_e32 v68, v69, v58
	v_fma_f32 v28, -v28, v68, v59
	v_div_fmas_f32 v28, v28, v58, v68
	v_div_fixup_f32 v59, v28, v9, 1.0
	v_div_scale_f32 v9, s[0:1], v8, v8, 1.0
	v_rcp_f32_e32 v28, v9
	s_nop 0
	v_fma_f32 v58, -v9, v28, 1.0
	v_fmac_f32_e32 v28, v58, v28
	v_div_scale_f32 v58, vcc, 1.0, v8, 1.0
	v_mul_f32_e32 v68, v58, v28
	v_fma_f32 v69, -v9, v68, v58
	v_fmac_f32_e32 v68, v69, v28
	v_fma_f32 v9, -v9, v68, v58
	v_div_fmas_f32 v9, v9, v28, v68
	v_div_fixup_f32 v58, v9, v8, 1.0
	v_pk_add_f32 v[8:9], v[58:59], -1.0 op_sel_hi:[1,0]
	v_cvt_f32_f16_e32 v28, v29
	v_pk_fma_f32 v[2:3], v[8:9], v[2:3], 1.0 op_sel_hi:[1,1,0]
	v_cvt_f32_f16_sdwa v29, v29 dst_sel:DWORD dst_unused:UNUSED_PAD src0_sel:WORD_1
	v_pk_mul_f32 v[2:3], v[2:3], v[66:67]
	v_pk_mul_f32 v[20:21], v[20:21], v[28:29]
	v_cvt_pk_f16_f32 v8, v2, v3
	v_pk_add_f32 v[2:3], v[52:53], 1.0 op_sel_hi:[1,0]
	s_nop 0
	v_div_scale_f32 v9, s[0:1], v3, v3, 1.0
	v_rcp_f32_e32 v52, v9
	s_nop 0
	v_fma_f32 v53, -v9, v52, 1.0
	v_fmac_f32_e32 v52, v53, v52
	v_div_scale_f32 v53, vcc, 1.0, v3, 1.0
	v_mul_f32_e32 v68, v53, v52
	v_fma_f32 v69, -v9, v68, v53
	v_fmac_f32_e32 v68, v69, v52
	v_fma_f32 v9, -v9, v68, v53
	v_div_fmas_f32 v9, v9, v52, v68
	v_div_fixup_f32 v3, v9, v3, 1.0
	v_div_scale_f32 v9, s[0:1], v2, v2, 1.0
	v_rcp_f32_e32 v52, v9
	s_nop 0
	v_fma_f32 v53, -v9, v52, 1.0
	v_fmac_f32_e32 v52, v53, v52
	v_div_scale_f32 v53, vcc, 1.0, v2, 1.0
	v_mul_f32_e32 v68, v53, v52
	v_fma_f32 v69, -v9, v68, v53
	v_fmac_f32_e32 v68, v69, v52
	v_fma_f32 v9, -v9, v68, v53
	v_div_fmas_f32 v9, v9, v52, v68
	v_div_fixup_f32 v2, v9, v2, 1.0
	v_pk_add_f32 v[52:53], v[2:3], -1.0 op_sel_hi:[1,0]
	s_nop 0
	v_pk_fma_f32 v[4:5], v[52:53], v[4:5], 1.0 op_sel_hi:[1,1,0]
	s_nop 0
	v_pk_mul_f32 v[4:5], v[4:5], v[28:29]
	v_lshlrev_b64 v[28:29], 12, v[42:43]
	v_cvt_pk_f16_f32 v9, v4, v5
	global_store_dwordx4 v[50:51], v[6:9], off
	v_pk_mul_f32 v[4:5], v[22:23], v[64:65]
	v_pk_mul_f32 v[22:23], v[20:21], v[20:21]
	v_pk_mul_f32 v[8:9], v[18:19], v[66:67]
	v_pk_mul_f32 v[6:7], v[24:25], v[26:27]
	v_pk_mul_f32 v[18:19], v[8:9], v[8:9]
	v_pk_fma_f32 v[22:23], v[6:7], v[6:7], v[22:23]
	v_pk_fma_f32 v[18:19], v[4:5], v[4:5], v[18:19]
	s_nop 0
	v_add_f32_e32 v18, v18, v19
	v_add_f32_e32 v18, v22, v18
	v_add_f32_e32 v18, v23, v18
	v_add_f32_e32 v18, v18, v54
	v_add_f32_e32 v18, v55, v18
	v_add_f32_e32 v18, v56, v18
	v_add_f32_e32 v18, v57, v18
	ds_bpermute_b32 v19, v206, v18
	s_waitcnt lgkmcnt(0)
;     __device__ __forceinline__ void body_a(const f32x4 (&acc)[2][2][4][2], int row0, int cb0) const {
;     ...
;                 ss += __shfl_xor(ss, 16); ss += __shfl_xor(ss, 32);
;                 const float inv = 1.0f / fmaxf(sqrtf(ss), 1e-12f);
; #pragma unroll
;                 for (int bj = 0; bj < 2; ++bj) {
;                     const int c = cb0 + 32 * bj;
;                     const f32x4 p0 = *(const f32x4*)(k_a + c), p1 = *(const f32x4*)(k_a + c + 4);
;                     f32x4 ko0, ko1, ao0, ao1, bo0, bo1;
; #pragma unroll
;                     for (int e = 0; e < 4; ++e) {
;                         ko0[e] = kv[bj][e] * (1.0f + (a[bj][e] - 1.0f) * p0[e]); ko1[e] = kv[bj][4 + e] * (1.0f + (a[bj][4 + e] - 1.0f) * p1[e]);
;                         const float n0_ = kk[bj][e] * inv, n1_ = kk[bj][4 + e] * inv;
;                         ao0[e] = -n0_; ao1[e] = -n1_; bo0[e] = n0_ * a[bj][e]; bo1[e] = n1_ * a[bj][4 + e];
;                     }
;                     *(u32x4*)(C1 + row * LDC1 + 2048 + c) = pack8(ko0, ko1);
;                     *(u32x4*)(AA + row * DM + c) = pack8(ao0, ao1);
;                     *(u32x4*)(Ab + row * DM + c) = pack8(bo0, bo1);
	v_add_f32_e32 v18, v18, v19
	ds_bpermute_b32 v19, v207, v18
	s_waitcnt lgkmcnt(0)
	v_add_f32_e32 v18, v18, v19
	v_cmp_gt_f32_e32 vcc, s4, v18
	v_mul_f32_e32 v19, 0x4f800000, v18
	s_nop 0
	v_cndmask_b32_e32 v18, v18, v19, vcc
	v_sqrt_f32_e32 v19, v18
	s_nop 0
	v_add_u32_e32 v22, -1, v19
	v_fma_f32 v23, -v22, v19, v18
	v_cmp_ge_f32_e64 s[0:1], 0, v23
	v_add_u32_e32 v23, 1, v19
	s_nop 0
	v_cndmask_b32_e64 v22, v19, v22, s[0:1]
	v_fma_f32 v19, -v23, v19, v18
	v_cmp_lt_f32_e64 s[0:1], 0, v19
	s_nop 1
	v_cndmask_b32_e64 v19, v22, v23, s[0:1]
	v_mul_f32_e32 v22, 0x37800000, v19
	v_cndmask_b32_e32 v19, v19, v22, vcc
	v_cmp_class_f32_e32 vcc, v18, v244
	s_nop 1
	v_cndmask_b32_e32 v18, v19, v18, vcc
	v_max_f32_e32 v18, 0x2b8cbccc, v18
	v_div_scale_f32 v19, s[0:1], v18, v18, 1.0
	v_rcp_f32_e32 v22, v19
	s_nop 0
	v_fma_f32 v23, -v19, v22, 1.0
	v_fmac_f32_e32 v22, v23, v22
	v_div_scale_f32 v23, vcc, 1.0, v18, 1.0
	v_mul_f32_e32 v24, v23, v22
	v_fma_f32 v25, -v19, v24, v23
	v_fmac_f32_e32 v24, v25, v22
	v_fma_f32 v19, -v19, v24, v23
	v_div_fmas_f32 v19, v19, v22, v24
	v_div_fixup_f32 v22, v19, v18, 1.0
	v_pk_mul_f32 v[26:27], v[6:7], v[22:23] op_sel_hi:[1,0]
	v_pk_mul_f32 v[24:25], v[4:5], v[22:23] op_sel_hi:[1,0]
	v_cvt_pk_f16_f32 v5, v26, v27
	v_cvt_pk_f16_f32 v4, v24, v25
	v_xor_b32_e32 v6, 0x8000, v5
	v_xor_b32_sdwa v5, s63, v5 dst_sel:DWORD dst_unused:UNUSED_PAD src0_sel:DWORD src1_sel:WORD_1
	v_pk_mul_f32 v[8:9], v[8:9], v[22:23] op_sel_hi:[1,0]
	v_pk_mul_f32 v[20:21], v[20:21], v[22:23] op_sel_hi:[1,0]
	v_perm_b32 v5, v5, v6, s33
	v_xor_b32_e32 v6, 0x8000, v4
	v_xor_b32_sdwa v4, s63, v4 dst_sel:DWORD dst_unused:UNUSED_PAD src0_sel:DWORD src1_sel:WORD_1
	v_perm_b32 v4, v4, v6, s33
	v_pk_add_f32 v[6:7], v[8:9], 0 neg_lo:[1,1] neg_hi:[1,1]
	v_pk_add_f32 v[18:19], v[20:21], 0 neg_lo:[1,1] neg_hi:[1,1]
	v_cvt_pk_f16_f32 v6, v6, v7
	v_cvt_pk_f16_f32 v7, v18, v19
	v_lshl_add_u64 v[18:19], s[10:11], 0, v[28:29]
	v_lshl_add_u64 v[18:19], v[18:19], 0, v[152:153]
	global_store_dwordx4 v[18:19], v[4:7], off
	v_fma_mixlo_f16 v23, v60, v24, 0
	v_mul_f32_e32 v42, v14, v22
	v_pk_mov_b32 v[4:5], v[60:61], v[62:63] op_sel:[1,0]
	v_pk_mov_b32 v[6:7], v[24:25], v[26:27] op_sel:[1,0]
	v_pk_mov_b32 v[24:25], v[26:27], v[8:9] op_sel:[1,0]
	v_pk_mul_f32 v[4:5], v[4:5], v[6:7]
	v_pk_mov_b32 v[6:7], v[62:63], v[58:59] op_sel:[1,0]
	v_cvt_pk_f16_f32 v5, v4, v5
	v_pk_mul_f32 v[6:7], v[6:7], v[24:25]
	v_pack_b32_f16 v4, v23, v5
	v_cvt_pk_f16_f32 v23, v6, v7
	v_pk_mov_b32 v[6:7], v[58:59], v[2:3] op_sel:[1,0]
	v_pk_mov_b32 v[8:9], v[8:9], v[20:21] op_sel:[1,0]
	v_alignbit_b32 v5, v23, v5, 16
	v_pk_mul_f32 v[6:7], v[6:7], v[8:9]
	v_pk_add_f32 v[24:25], v[48:49], 1.0 op_sel_hi:[1,0]
	v_cvt_pk_f16_f32 v2, v6, v7
	v_lshrrev_b32_e32 v7, 16, v2
	v_alignbit_b32 v6, v2, v23, 16
	v_fma_mixhi_f16 v7, v3, v21, 0
	v_lshl_add_u64 v[2:3], s[2:3], 0, v[28:29]
	v_lshl_add_u64 v[20:21], v[2:3], 0, v[152:153]
	global_store_dwordx4 v[20:21], v[4:7], off
	global_load_dwordx4 v[2:5], v[126:127], off offset:144
	s_nop 0
	global_load_dwordx4 v[6:9], v[126:127], off offset:128
	v_div_scale_f32 v26, s[0:1], v25, v25, 1.0
	v_rcp_f32_e32 v27, v26
	v_mul_f32_e32 v23, v17, v22
	v_fma_f32 v28, -v26, v27, 1.0
	v_fmac_f32_e32 v27, v28, v27
	v_div_scale_f32 v28, vcc, 1.0, v25, 1.0
	v_mul_f32_e32 v29, v28, v27
	v_fma_f32 v43, -v26, v29, v28
	v_fmac_f32_e32 v29, v43, v27
	v_fma_f32 v26, -v26, v29, v28
	v_div_fmas_f32 v26, v26, v27, v29
	v_div_fixup_f32 v25, v26, v25, 1.0
	v_div_scale_f32 v26, s[0:1], v24, v24, 1.0
	v_rcp_f32_e32 v27, v26
	s_nop 0
	v_fma_f32 v28, -v26, v27, 1.0
	v_fmac_f32_e32 v27, v28, v27
	v_div_scale_f32 v28, vcc, 1.0, v24, 1.0
	v_mul_f32_e32 v29, v28, v27
	v_fma_f32 v43, -v26, v29, v28
	v_fmac_f32_e32 v29, v43, v27
	v_fma_f32 v26, -v26, v29, v28
	v_div_fmas_f32 v26, v26, v27, v29
	v_div_fixup_f32 v24, v26, v24, 1.0
	v_pk_add_f32 v[26:27], v[24:25], -1.0 op_sel_hi:[1,0]
	s_waitcnt vmcnt(0)
; template <class Epi, class AMap>
; __device__ __forceinline__ void gemm_phase(LAS unsigned char* lds, const AMap am, const int lda, const h16* Bt, const int ldb, const int M, const int N, const int K, const Epi& E) {
;     ...
;         E(acc, cur, wr, wc, fr, fq);
;         if (!has_next) break;
; #pragma unroll
;         for (int a = 0; a < 2; ++a)
; #pragma unroll
;             for (int b = 0; b < 2; ++b)
; #pragma unroll
;                 for (int m = 0; m < 4; ++m)
; #pragma unroll
;                     for (int n = 0; n < 2; ++n) acc[a][b][m][n] = (f32x4){0.f, 0.f, 0.f, 0.f};
;         cur = nxt; cA = nA; cB = nB; ++ui;
;     }
;     __device__ __forceinline__ void body_a(const f32x4 (&acc)[2][2][4][2], int row0, int cb0) const {
;     ...
;                         ko0[e] = kv[bj][e] * (1.0f + (a[bj][e] - 1.0f) * p0[e]); ko1[e] = kv[bj][4 + e] * (1.0f + (a[bj][4 + e] - 1.0f) * p1[e]);
;                         const float n0_ = kk[bj][e] * inv, n1_ = kk[bj][4 + e] * inv;
;                         ao0[e] = -n0_; ao1[e] = -n1_; bo0[e] = n0_ * a[bj][e]; bo1[e] = n1_ * a[bj][4 + e];
;                     }
;                     *(u32x4*)(C1 + row * LDC1 + 2048 + c) = pack8(ko0, ko1);
;                     *(u32x4*)(AA + row * DM + c) = pack8(ao0, ao1);
;                     *(u32x4*)(Ab + row * DM + c) = pack8(bo0, bo1);
	v_pk_fma_f32 v[6:7], v[26:27], v[6:7], 1.0 op_sel_hi:[1,1,0]
	s_nop 0
	v_pk_mul_f32 v[6:7], v[6:7], v[46:47]
	v_pk_add_f32 v[26:27], v[44:45], 1.0 op_sel_hi:[1,0]
	v_cvt_pk_f16_f32 v6, v6, v7
	v_div_scale_f32 v7, s[0:1], v27, v27, 1.0
	v_rcp_f32_e32 v28, v7
	s_nop 0
	v_fma_f32 v29, -v7, v28, 1.0
	v_fmac_f32_e32 v28, v29, v28
	v_div_scale_f32 v29, vcc, 1.0, v27, 1.0
	v_mul_f32_e32 v43, v29, v28
	v_fma_f32 v44, -v7, v43, v29
	v_fmac_f32_e32 v43, v44, v28
	v_fma_f32 v7, -v7, v43, v29
	v_div_fmas_f32 v7, v7, v28, v43
	v_div_fixup_f32 v27, v7, v27, 1.0
	v_div_scale_f32 v7, s[0:1], v26, v26, 1.0
	v_rcp_f32_e32 v28, v7
	s_nop 0
	v_fma_f32 v29, -v7, v28, 1.0
	v_fmac_f32_e32 v28, v29, v28
	v_div_scale_f32 v29, vcc, 1.0, v26, 1.0
	v_mul_f32_e32 v43, v29, v28
	v_fma_f32 v44, -v7, v43, v29
	v_fmac_f32_e32 v43, v44, v28
	v_fma_f32 v7, -v7, v43, v29
	v_div_fmas_f32 v7, v7, v28, v43
	v_div_fixup_f32 v26, v7, v26, 1.0
	v_pk_add_f32 v[28:29], v[26:27], -1.0 op_sel_hi:[1,0]
	s_nop 0
	v_pk_fma_f32 v[8:9], v[28:29], v[8:9], 1.0 op_sel_hi:[1,1,0]
	s_nop 0
	v_pk_mul_f32 v[8:9], v[8:9], v[40:41]
	s_nop 0
	v_cvt_pk_f16_f32 v7, v8, v9
	v_pk_add_f32 v[8:9], v[38:39], 1.0 op_sel_hi:[1,0]
	s_nop 0
	v_div_scale_f32 v28, s[0:1], v9, v9, 1.0
	v_rcp_f32_e32 v29, v28
	s_nop 0
	v_fma_f32 v38, -v28, v29, 1.0
	v_fmac_f32_e32 v29, v38, v29
	v_div_scale_f32 v38, vcc, 1.0, v9, 1.0
	v_mul_f32_e32 v39, v38, v29
	v_fma_f32 v40, -v28, v39, v38
	v_fmac_f32_e32 v39, v40, v29
	v_fma_f32 v28, -v28, v39, v38
	v_div_fmas_f32 v28, v28, v29, v39
	v_div_fixup_f32 v29, v28, v9, 1.0
	v_div_scale_f32 v9, s[0:1], v8, v8, 1.0
	v_rcp_f32_e32 v28, v9
	s_nop 0
	v_fma_f32 v38, -v9, v28, 1.0
	v_fmac_f32_e32 v28, v38, v28
	v_div_scale_f32 v38, vcc, 1.0, v8, 1.0
	v_mul_f32_e32 v39, v38, v28
	v_fma_f32 v40, -v9, v39, v38
	v_fmac_f32_e32 v39, v40, v28
	v_fma_f32 v9, -v9, v39, v38
	v_div_fmas_f32 v9, v9, v28, v39
	v_div_fixup_f32 v28, v9, v8, 1.0
	v_pk_add_f32 v[8:9], v[28:29], -1.0 op_sel_hi:[1,0]
	s_nop 0
	v_pk_fma_f32 v[2:3], v[8:9], v[2:3], 1.0 op_sel_hi:[1,1,0]
	s_nop 0
	v_pk_mul_f32 v[2:3], v[2:3], v[36:37]
	s_nop 0
	v_cvt_pk_f16_f32 v8, v2, v3
	v_pk_add_f32 v[2:3], v[34:35], 1.0 op_sel_hi:[1,0]
	s_nop 0
	v_div_scale_f32 v9, s[0:1], v3, v3, 1.0
	v_rcp_f32_e32 v34, v9
	s_nop 0
	v_fma_f32 v35, -v9, v34, 1.0
	v_fmac_f32_e32 v34, v35, v34
	v_div_scale_f32 v35, vcc, 1.0, v3, 1.0
	v_mul_f32_e32 v36, v35, v34
	v_fma_f32 v37, -v9, v36, v35
	v_fmac_f32_e32 v36, v37, v34
	v_fma_f32 v9, -v9, v36, v35
	v_div_fmas_f32 v9, v9, v34, v36
	v_div_fixup_f32 v35, v9, v3, 1.0
	v_div_scale_f32 v3, s[0:1], v2, v2, 1.0
	v_rcp_f32_e32 v9, v3
	s_nop 0
	v_fma_f32 v34, -v3, v9, 1.0
	v_fmac_f32_e32 v9, v34, v9
	v_div_scale_f32 v34, vcc, 1.0, v2, 1.0
	v_mul_f32_e32 v36, v34, v9
	v_fma_f32 v37, -v3, v36, v34
	v_fmac_f32_e32 v36, v37, v9
	v_fma_f32 v3, -v3, v36, v34
	v_div_fmas_f32 v3, v3, v9, v36
	v_div_fixup_f32 v34, v3, v2, 1.0
	v_pk_add_f32 v[2:3], v[34:35], -1.0 op_sel_hi:[1,0]
	s_nop 0
	v_pk_fma_f32 v[2:3], v[2:3], v[4:5], 1.0 op_sel_hi:[1,1,0]
	v_cvt_f16_f32_e64 v4, -v42
	v_pk_mul_f32 v[2:3], v[2:3], v[32:33]
	s_nop 0
	v_cvt_pk_f16_f32 v9, v2, v3
	v_pk_mov_b32 v[2:3], v[14:15], v[30:31] op_sel:[1,0]
	global_store_dwordx4 v[10:11], v[6:9], off
	s_nop 1
	v_pk_mul_f32 v[6:7], v[2:3], v[22:23] op_sel_hi:[1,0]
	s_nop 0
	v_cvt_pk_f16_f32 v3, v6, v7
	v_pack_b32_f16 v2, v4, -v3
	v_pk_mov_b32 v[4:5], v[30:31], v[12:13] op_sel:[1,0]
	v_xor_b32_sdwa v3, s63, v3 dst_sel:DWORD dst_unused:UNUSED_PAD src0_sel:DWORD src1_sel:WORD_1
	v_pk_mul_f32 v[8:9], v[4:5], v[22:23] op_sel_hi:[1,0]
	s_nop 0
	v_cvt_pk_f16_f32 v4, v8, v9
	v_xor_b32_e32 v5, 0x8000, v4
	v_perm_b32 v3, v5, v3, s33
	v_xor_b32_sdwa v14, s63, v4 dst_sel:DWORD dst_unused:UNUSED_PAD src0_sel:DWORD src1_sel:WORD_1
	v_pk_mov_b32 v[4:5], v[12:13], v[16:17] op_sel:[1,0]
	v_cvt_f16_f32_e64 v12, -v23
	v_pk_mul_f32 v[10:11], v[4:5], v[22:23] op_sel_hi:[1,0]
	s_nop 0
	v_cvt_pk_f16_f32 v5, v10, v11
	v_xor_b32_e32 v4, 0x8000, v5
	v_xor_b32_sdwa v5, s63, v5 dst_sel:DWORD dst_unused:UNUSED_PAD src0_sel:DWORD src1_sel:WORD_1
	v_perm_b32 v4, v4, v14, s33
	v_perm_b32 v5, v12, v5, s33
	global_store_dwordx4 v[18:19], v[2:5], off offset:64
	s_nop 1
	v_pk_mov_b32 v[2:3], v[24:25], v[26:27] op_sel:[1,0]
	v_fma_mixlo_f16 v4, v24, v42, 0
	v_pk_mul_f32 v[2:3], v[2:3], v[6:7]
	s_nop 0
	v_cvt_pk_f16_f32 v3, v2, v3
	v_pack_b32_f16 v2, v4, v3
	v_pk_mov_b32 v[4:5], v[26:27], v[28:29] op_sel:[1,0]
	s_nop 0
	v_pk_mul_f32 v[4:5], v[4:5], v[8:9]
	s_nop 0
	v_cvt_pk_f16_f32 v6, v4, v5
	v_pk_mov_b32 v[4:5], v[28:29], v[34:35] op_sel:[1,0]
	v_alignbit_b32 v3, v6, v3, 16
	v_pk_mul_f32 v[4:5], v[4:5], v[10:11]
	s_nop 0
	v_cvt_pk_f16_f32 v5, v4, v5
	v_alignbit_b32 v4, v5, v6, 16
	v_lshrrev_b32_e32 v5, 16, v5
	v_fma_mixhi_f16 v5, v35, v23, 0
	global_store_dwordx4 v[20:21], v[2:5], off offset:64
	s_and_b64 vcc, exec, s[38:39]
	s_mov_b32 s50, s44
	s_mov_b32 s35, s82
	s_mov_b64 s[26:27], s[64:65]
	s_mov_b64 s[22:23], s[46:47]
	s_cmpk_lt_u32 s69, 0x100
	s_cbranch_scc1 .Lgy5
	s_barrier

; #define PG8_STAGE(bufoff, gbase, voff) do { _Pragma("unroll") for (int _i = 0; _i < 2; ++_i) \
;         __builtin_amdgcn_global_load_lds((const unsigned*)((const char*)(gbase) + (voff)[_i]), (LAS unsigned*)(lds + (bufoff) + ldsw + _i * 8192), 16, 0, 0); } while (0)
; #define PG8_LDA(dst, b, h) do { _Pragma("unroll") for (int m = 0; m < 4; ++m) _Pragma("unroll") for (int k = 0; k < 2; ++k) dst[m][k] = *(const LAS h16x8*)(lds + PG8_SA(b, h) + aoff + m * 2048 + k * 1024); } while (0)
; #define PG8_LDB(dst, b, h) do { _Pragma("unroll") for (int n = 0; n < 2; ++n) _Pragma("unroll") for (int k = 0; k < 2; ++k) dst[n][k] = *(const LAS h16x8*)(lds + PG8_SB(b, h) + boff + n * 2048 + k * 1024); } while (0)
; #define PG8_MMA(ai, bj, At, Bt_) do { __builtin_amdgcn_s_setprio(1); _Pragma("unroll") for (int m = 0; m < 4; ++m) _Pragma("unroll") for (int n = 0; n < 2; ++n) _Pragma("unroll") for (int k = 0; k < 2; ++k) \
;         acc[ai][bj][m][n] = __builtin_amdgcn_mfma_f32_16x16x32_f16(Bt_[n][k], At[m][k], acc[ai][bj][m][n], 0, 0, 0); __builtin_amdgcn_s_setprio(0); } while (0)
; #define PG8_WAIT_V(n) asm volatile("s_waitcnt vmcnt(" #n ")" ::: "memory")
; template <class Epi, class AMap>
; __device__ __forceinline__ void gemm_phase(LAS unsigned char* lds, const AMap am, const int lda, const h16* Bt, const int ldb, const int M, const int N, const int K, const Epi& E) {
;     ...
;         for (int t = 0; t < nt; t += 2) {
;             const bool last = (t == nt - 2);
;             const char* a1 = cA + (size_t)(t + 1) * kstep;
;             const char* a2 = last ? nA : cA + (size_t)(t + 2) * kstep; const char* b2 = last ? nB : cB + (size_t)(t + 2) * kstep;
;             const char* a3 = a2 + kstep; const char* b3 = b2 + kstep;
;             PG8_LDB(B0, 0, 0); PG8_SCHED; PG8_LDA(At, 0, 0); PG8_STAGE(PG8_SA(1, 1), a1 + hstepA, voffA);
;             PG8_WAIT_L(8); PG8_BAR; PG8_WAIT_L(0); PG8_MMA(0, 0, At, B0); PG8_BAR; PG8_SCHED;
;             PG8_LDB(B1, 0, 1); PG8_STAGE(PG8_SB(0, 0), b2, voffB);
;             PG8_BAR; PG8_WAIT_L(0); PG8_MMA(0, 1, At, B1); PG8_BAR;
;             PG8_LDA(At, 0, 1); PG8_STAGE(PG8_SA(0, 0), a2, voffA);
;             PG8_BAR; PG8_WAIT_L(0); PG8_MMA(1, 0, At, B0); PG8_BAR; PG8_SCHED;
;             PG8_STAGE(PG8_SB(0, 1), b2 + hstepB, voffB);
;             PG8_WAIT_V(6); PG8_BAR; PG8_MMA(1, 1, At, B1); PG8_BAR;
.LBB0_644:
	s_add_i32 s51, s26, 2
	s_add_u32 s0, s22, 0x100
	s_addc_u32 s1, s23, 0
	s_add_i32 s60, 0, 0x10000
	v_add_u32_e32 v234, s60, v203
	ds_read_b128 v[130:133], v234
	ds_read_b128 v[134:137], v234 offset:1024
	ds_read_b128 v[138:141], v234 offset:2048
	ds_read_b128 v[152:155], v234 offset:3072
	s_cmp_eq_u32 s80, s26
	s_cselect_b32 s26, s21, s29
	s_cselect_b32 s49, s47, s1
	s_cselect_b32 s48, s46, s0
	s_cselect_b32 s27, s20, s45
	v_lshl_add_u64 v[232:233], s[22:23], 0, v[148:149]
	s_add_i32 m0, s74, 0xc000
	ds_read_b128 v[156:159], v205
	ds_read_b128 v[160:163], v205 offset:1024
	ds_read_b128 v[164:167], v205 offset:2048
	ds_read_b128 v[168:171], v205 offset:3072
	ds_read_b128 v[172:175], v205 offset:4096
	ds_read_b128 v[176:179], v205 offset:5120
	ds_read_b128 v[180:183], v205 offset:6144
	ds_read_b128 v[184:187], v205 offset:7168
	global_load_lds_dwordx4 v[232:233], off
	v_lshl_add_u64 v[232:233], s[22:23], 0, v[150:151]
	s_add_i32 m0, s74, 0xe000
	s_nop 0
	global_load_lds_dwordx4 v[232:233], off
	s_waitcnt lgkmcnt(11)
	s_add_i32 s62, 0, 0x14000
	v_add_u32_e32 v200, s62, v203
	s_add_i32 s22, s60, s71
	ds_read_b128 v[188:191], v200
	ds_read_b128 v[192:195], v200 offset:1024
	ds_read_b128 v[196:199], v200 offset:2048
	ds_read_b128 v[220:223], v200 offset:3072
	s_waitcnt vmcnt(8) lgkmcnt(0)
	s_barrier
	v_mfma_f32_16x16x32_f16 v[122:125], v[130:133], v[156:159], v[122:125]
	v_mfma_f32_16x16x32_f16 v[126:129], v[138:141], v[156:159], v[126:129]
	v_mfma_f32_16x16x32_f16 v[110:113], v[130:133], v[164:167], v[110:113]
	v_mfma_f32_16x16x32_f16 v[106:109], v[138:141], v[164:167], v[106:109]
	v_mfma_f32_16x16x32_f16 v[94:97], v[130:133], v[172:175], v[94:97]
	v_mfma_f32_16x16x32_f16 v[90:93], v[138:141], v[172:175], v[90:93]
	v_mfma_f32_16x16x32_f16 v[78:81], v[130:133], v[180:183], v[78:81]
	v_mfma_f32_16x16x32_f16 v[74:77], v[138:141], v[180:183], v[74:77]
	v_mfma_f32_16x16x32_f16 v[122:125], v[134:137], v[160:163], v[122:125]
	v_mfma_f32_16x16x32_f16 v[126:129], v[152:155], v[160:163], v[126:129]
	v_mfma_f32_16x16x32_f16 v[110:113], v[134:137], v[168:171], v[110:113]
	v_mfma_f32_16x16x32_f16 v[106:109], v[152:155], v[168:171], v[106:109]
	v_mfma_f32_16x16x32_f16 v[94:97], v[134:137], v[176:179], v[94:97]
	v_mfma_f32_16x16x32_f16 v[90:93], v[152:155], v[176:179], v[90:93]
	v_mfma_f32_16x16x32_f16 v[78:81], v[134:137], v[184:187], v[78:81]
	v_mfma_f32_16x16x32_f16 v[74:77], v[152:155], v[184:187], v[74:77]
	v_mfma_f32_16x16x32_f16 v[118:121], v[188:191], v[156:159], v[118:121]
	v_mfma_f32_16x16x32_f16 v[114:117], v[196:199], v[156:159], v[114:117]
	v_mfma_f32_16x16x32_f16 v[102:105], v[188:191], v[164:167], v[102:105]
	v_mfma_f32_16x16x32_f16 v[98:101], v[196:199], v[164:167], v[98:101]
	v_mfma_f32_16x16x32_f16 v[86:89], v[188:191], v[172:175], v[86:89]
	v_mfma_f32_16x16x32_f16 v[82:85], v[196:199], v[172:175], v[82:85]
	v_mfma_f32_16x16x32_f16 v[70:73], v[188:191], v[180:183], v[70:73]
	v_mfma_f32_16x16x32_f16 v[66:69], v[196:199], v[180:183], v[66:69]
	v_mfma_f32_16x16x32_f16 v[118:121], v[192:195], v[160:163], v[118:121]
	v_mfma_f32_16x16x32_f16 v[114:117], v[220:223], v[160:163], v[114:117]
	v_mfma_f32_16x16x32_f16 v[102:105], v[192:195], v[168:171], v[102:105]
	v_mfma_f32_16x16x32_f16 v[98:101], v[220:223], v[168:171], v[98:101]
	v_mfma_f32_16x16x32_f16 v[86:89], v[192:195], v[176:179], v[86:89]
	v_mfma_f32_16x16x32_f16 v[82:85], v[220:223], v[176:179], v[82:85]
	v_mfma_f32_16x16x32_f16 v[70:73], v[192:195], v[184:187], v[70:73]
	v_mfma_f32_16x16x32_f16 v[66:69], v[220:223], v[184:187], v[66:69]
	s_barrier
	v_lshl_add_u64 v[200:201], s[26:27], 0, v[0:1]
	s_mov_b32 m0, s22
	v_lshl_add_u64 v[206:207], s[26:27], 0, v[146:147]
	global_load_lds_dwordx4 v[200:201], off
	s_add_i32 m0, s22, 0x2000
	s_nop 0
	global_load_lds_dwordx4 v[206:207], off
	s_mov_b32 m0, s74
	v_lshl_add_u64 v[212:213], s[48:49], 0, v[142:143]
	ds_read_b128 v[156:159], v205 offset:16384
	ds_read_b128 v[160:163], v205 offset:17408
	ds_read_b128 v[164:167], v205 offset:18432
	ds_read_b128 v[168:171], v205 offset:19456
	ds_read_b128 v[172:175], v205 offset:20480
	ds_read_b128 v[176:179], v205 offset:21504
	ds_read_b128 v[180:183], v205 offset:22528
	ds_read_b128 v[184:187], v205 offset:23552
	global_load_lds_dwordx4 v[212:213], off
	v_lshl_add_u64 v[224:225], s[48:49], 0, v[144:145]
	s_mov_b32 m0, s75
	s_nop 0
	global_load_lds_dwordx4 v[224:225], off
	s_add_u32 s22, s26, 0x10000
	s_addc_u32 s23, s27, 0
	s_add_i32 s60, s62, s71
	v_lshl_add_u64 v[232:233], s[22:23], 0, v[0:1]
	s_mov_b32 m0, s60
	s_nop 0
	global_load_lds_dwordx4 v[232:233], off
	v_lshl_add_u64 v[232:233], s[22:23], 0, v[146:147]
	s_add_i32 m0, s60, 0x2000
	s_nop 0
	global_load_lds_dwordx4 v[232:233], off
	s_waitcnt vmcnt(8) lgkmcnt(0)
	s_barrier
; #define PG8_STAGE(bufoff, gbase, voff) do { _Pragma("unroll") for (int _i = 0; _i < 2; ++_i) \
;         __builtin_amdgcn_global_load_lds((const unsigned*)((const char*)(gbase) + (voff)[_i]), (LAS unsigned*)(lds + (bufoff) + ldsw + _i * 8192), 16, 0, 0); } while (0)
; #define PG8_LDA(dst, b, h) do { _Pragma("unroll") for (int m = 0; m < 4; ++m) _Pragma("unroll") for (int k = 0; k < 2; ++k) dst[m][k] = *(const LAS h16x8*)(lds + PG8_SA(b, h) + aoff + m * 2048 + k * 1024); } while (0)
; #define PG8_LDB(dst, b, h) do { _Pragma("unroll") for (int n = 0; n < 2; ++n) _Pragma("unroll") for (int k = 0; k < 2; ++k) dst[n][k] = *(const LAS h16x8*)(lds + PG8_SB(b, h) + boff + n * 2048 + k * 1024); } while (0)
; #define PG8_MMA(ai, bj, At, Bt_) do { __builtin_amdgcn_s_setprio(1); _Pragma("unroll") for (int m = 0; m < 4; ++m) _Pragma("unroll") for (int n = 0; n < 2; ++n) _Pragma("unroll") for (int k = 0; k < 2; ++k) \
;         acc[ai][bj][m][n] = __builtin_amdgcn_mfma_f32_16x16x32_f16(Bt_[n][k], At[m][k], acc[ai][bj][m][n], 0, 0, 0); __builtin_amdgcn_s_setprio(0); } while (0)
; #define PG8_WAIT_V(n) asm volatile("s_waitcnt vmcnt(" #n ")" ::: "memory")
; #define PG8_WAIT_L(n) asm volatile("s_waitcnt lgkmcnt(" #n ")" ::: "memory")
; #define PG8_BAR __builtin_amdgcn_s_barrier()
; #define PG8_SCHED __builtin_amdgcn_sched_barrier(0)
; template <class Epi, class AMap>
; __device__ __forceinline__ void gemm_phase(LAS unsigned char* lds, const AMap am, const int lda, const h16* Bt, const int ldb, const int M, const int N, const int K, const Epi& E) {
;     ...
;             PG8_WAIT_V(6); PG8_BAR; PG8_MMA(1, 1, At, B1); PG8_BAR;
;             PG8_LDB(B0, 1, 0); PG8_SCHED; PG8_LDA(At, 1, 0); PG8_STAGE(PG8_SA(0, 1), a2 + hstepA, voffA);
;             PG8_WAIT_L(8); PG8_BAR; PG8_WAIT_L(0); PG8_MMA(0, 0, At, B0); PG8_BAR; PG8_SCHED;
;             PG8_LDB(B1, 1, 1); PG8_STAGE(PG8_SB(1, 0), b3, voffB);
;             PG8_BAR; PG8_WAIT_L(0); PG8_MMA(0, 1, At, B1); PG8_BAR;
;             PG8_LDA(At, 1, 1); PG8_STAGE(PG8_SA(1, 0), a3, voffA);
;             PG8_BAR; PG8_WAIT_L(0); PG8_MMA(1, 0, At, B0); PG8_BAR; PG8_SCHED;
	v_mfma_f32_16x16x32_f16 v[62:65], v[130:133], v[156:159], v[62:65]
	v_mfma_f32_16x16x32_f16 v[58:61], v[138:141], v[156:159], v[58:61]
	v_mfma_f32_16x16x32_f16 v[46:49], v[130:133], v[164:167], v[46:49]
	v_mfma_f32_16x16x32_f16 v[42:45], v[138:141], v[164:167], v[42:45]
	v_mfma_f32_16x16x32_f16 v[30:33], v[130:133], v[172:175], v[30:33]
	v_mfma_f32_16x16x32_f16 v[26:29], v[138:141], v[172:175], v[26:29]
	v_mfma_f32_16x16x32_f16 v[14:17], v[130:133], v[180:183], v[14:17]
	v_mfma_f32_16x16x32_f16 v[10:13], v[138:141], v[180:183], v[10:13]
	v_mfma_f32_16x16x32_f16 v[62:65], v[134:137], v[160:163], v[62:65]
	v_mfma_f32_16x16x32_f16 v[58:61], v[152:155], v[160:163], v[58:61]
	v_mfma_f32_16x16x32_f16 v[46:49], v[134:137], v[168:171], v[46:49]
	v_mfma_f32_16x16x32_f16 v[42:45], v[152:155], v[168:171], v[42:45]
	v_mfma_f32_16x16x32_f16 v[30:33], v[134:137], v[176:179], v[30:33]
	v_mfma_f32_16x16x32_f16 v[26:29], v[152:155], v[176:179], v[26:29]
	v_mfma_f32_16x16x32_f16 v[14:17], v[134:137], v[184:187], v[14:17]
	v_mfma_f32_16x16x32_f16 v[10:13], v[152:155], v[184:187], v[10:13]
	v_mfma_f32_16x16x32_f16 v[54:57], v[188:191], v[156:159], v[54:57]
	v_mfma_f32_16x16x32_f16 v[50:53], v[196:199], v[156:159], v[50:53]
	v_mfma_f32_16x16x32_f16 v[38:41], v[188:191], v[164:167], v[38:41]
	v_mfma_f32_16x16x32_f16 v[34:37], v[196:199], v[164:167], v[34:37]
	v_mfma_f32_16x16x32_f16 v[22:25], v[188:191], v[172:175], v[22:25]
	v_mfma_f32_16x16x32_f16 v[18:21], v[196:199], v[172:175], v[18:21]
	v_mfma_f32_16x16x32_f16 v[6:9], v[188:191], v[180:183], v[6:9]
	v_mfma_f32_16x16x32_f16 v[2:5], v[196:199], v[180:183], v[2:5]
	v_mfma_f32_16x16x32_f16 v[54:57], v[192:195], v[160:163], v[54:57]
	v_mfma_f32_16x16x32_f16 v[50:53], v[220:223], v[160:163], v[50:53]
	v_mfma_f32_16x16x32_f16 v[38:41], v[192:195], v[168:171], v[38:41]
	v_mfma_f32_16x16x32_f16 v[34:37], v[220:223], v[168:171], v[34:37]
	v_mfma_f32_16x16x32_f16 v[22:25], v[192:195], v[176:179], v[22:25]
	v_mfma_f32_16x16x32_f16 v[18:21], v[220:223], v[176:179], v[18:21]
	v_mfma_f32_16x16x32_f16 v[6:9], v[192:195], v[184:187], v[6:9]
	v_mfma_f32_16x16x32_f16 v[2:5], v[220:223], v[184:187], v[2:5]
	s_barrier
	s_add_i32 s60, 0, 0x18000
	v_add_u32_e32 v234, s60, v203
	ds_read_b128 v[130:133], v234
	ds_read_b128 v[134:137], v234 offset:1024
	ds_read_b128 v[138:141], v234 offset:2048
	ds_read_b128 v[152:155], v234 offset:3072
	s_add_u32 s22, s48, 0x1c0000
	s_addc_u32 s23, s49, 0
	s_mov_b32 m0, s76
	v_lshl_add_u64 v[232:233], s[22:23], 0, v[142:143]
	ds_read_b128 v[156:159], v205 offset:32768
	ds_read_b128 v[160:163], v205 offset:33792
	ds_read_b128 v[164:167], v205 offset:34816
	ds_read_b128 v[168:171], v205 offset:35840
	ds_read_b128 v[172:175], v205 offset:36864
	ds_read_b128 v[176:179], v205 offset:37888
	ds_read_b128 v[180:183], v205 offset:38912
	ds_read_b128 v[184:187], v205 offset:39936
	global_load_lds_dwordx4 v[232:233], off
	v_lshl_add_u64 v[232:233], s[22:23], 0, v[144:145]
	s_mov_b32 m0, s77
	s_nop 0
	global_load_lds_dwordx4 v[232:233], off
	s_waitcnt lgkmcnt(11)
	s_add_i32 s48, 0, 0x1c000
	s_add_i32 s22, s60, s71
	v_add_u32_e32 v214, s48, v203
	v_lshl_add_u64 v[200:201], v[200:201], 0, s[92:93]
	s_mov_b32 m0, s22
	ds_read_b128 v[188:191], v214
	ds_read_b128 v[192:195], v214 offset:1024
	ds_read_b128 v[196:199], v214 offset:2048
	ds_read_b128 v[220:223], v214 offset:3072
	s_waitcnt vmcnt(8) lgkmcnt(0)
	s_barrier
	v_mfma_f32_16x16x32_f16 v[122:125], v[130:133], v[156:159], v[122:125]
	v_mfma_f32_16x16x32_f16 v[126:129], v[138:141], v[156:159], v[126:129]
	v_mfma_f32_16x16x32_f16 v[110:113], v[130:133], v[164:167], v[110:113]
	v_mfma_f32_16x16x32_f16 v[106:109], v[138:141], v[164:167], v[106:109]
	v_mfma_f32_16x16x32_f16 v[94:97], v[130:133], v[172:175], v[94:97]
	v_mfma_f32_16x16x32_f16 v[90:93], v[138:141], v[172:175], v[90:93]
	v_mfma_f32_16x16x32_f16 v[78:81], v[130:133], v[180:183], v[78:81]
	v_mfma_f32_16x16x32_f16 v[74:77], v[138:141], v[180:183], v[74:77]
	v_mfma_f32_16x16x32_f16 v[122:125], v[134:137], v[160:163], v[122:125]
	v_mfma_f32_16x16x32_f16 v[126:129], v[152:155], v[160:163], v[126:129]
	v_mfma_f32_16x16x32_f16 v[110:113], v[134:137], v[168:171], v[110:113]
	v_mfma_f32_16x16x32_f16 v[106:109], v[152:155], v[168:171], v[106:109]
	v_mfma_f32_16x16x32_f16 v[94:97], v[134:137], v[176:179], v[94:97]
	v_mfma_f32_16x16x32_f16 v[90:93], v[152:155], v[176:179], v[90:93]
	v_mfma_f32_16x16x32_f16 v[78:81], v[134:137], v[184:187], v[78:81]
	v_mfma_f32_16x16x32_f16 v[74:77], v[152:155], v[184:187], v[74:77]
	v_mfma_f32_16x16x32_f16 v[118:121], v[188:191], v[156:159], v[118:121]
	v_mfma_f32_16x16x32_f16 v[114:117], v[196:199], v[156:159], v[114:117]
	v_mfma_f32_16x16x32_f16 v[102:105], v[188:191], v[164:167], v[102:105]
	v_mfma_f32_16x16x32_f16 v[98:101], v[196:199], v[164:167], v[98:101]
	v_mfma_f32_16x16x32_f16 v[86:89], v[188:191], v[172:175], v[86:89]
	v_mfma_f32_16x16x32_f16 v[82:85], v[196:199], v[172:175], v[82:85]
	v_mfma_f32_16x16x32_f16 v[70:73], v[188:191], v[180:183], v[70:73]
	v_mfma_f32_16x16x32_f16 v[66:69], v[196:199], v[180:183], v[66:69]
	v_mfma_f32_16x16x32_f16 v[118:121], v[192:195], v[160:163], v[118:121]
	v_mfma_f32_16x16x32_f16 v[114:117], v[220:223], v[160:163], v[114:117]
	v_mfma_f32_16x16x32_f16 v[102:105], v[192:195], v[168:171], v[102:105]
	v_mfma_f32_16x16x32_f16 v[98:101], v[220:223], v[168:171], v[98:101]
	v_mfma_f32_16x16x32_f16 v[86:89], v[192:195], v[176:179], v[86:89]
	v_mfma_f32_16x16x32_f16 v[82:85], v[220:223], v[176:179], v[82:85]
	v_mfma_f32_16x16x32_f16 v[70:73], v[192:195], v[184:187], v[70:73]
	v_mfma_f32_16x16x32_f16 v[66:69], v[220:223], v[184:187], v[66:69]
	s_barrier
; #define PG8_STAGE(bufoff, gbase, voff) do { _Pragma("unroll") for (int _i = 0; _i < 2; ++_i) \
;         __builtin_amdgcn_global_load_lds((const unsigned*)((const char*)(gbase) + (voff)[_i]), (LAS unsigned*)(lds + (bufoff) + ldsw + _i * 8192), 16, 0, 0); } while (0)
; #define PG8_LDA(dst, b, h) do { _Pragma("unroll") for (int m = 0; m < 4; ++m) _Pragma("unroll") for (int k = 0; k < 2; ++k) dst[m][k] = *(const LAS h16x8*)(lds + PG8_SA(b, h) + aoff + m * 2048 + k * 1024); } while (0)
; #define PG8_MMA(ai, bj, At, Bt_) do { __builtin_amdgcn_s_setprio(1); _Pragma("unroll") for (int m = 0; m < 4; ++m) _Pragma("unroll") for (int n = 0; n < 2; ++n) _Pragma("unroll") for (int k = 0; k < 2; ++k) \
;         acc[ai][bj][m][n] = __builtin_amdgcn_mfma_f32_16x16x32_f16(Bt_[n][k], At[m][k], acc[ai][bj][m][n], 0, 0, 0); __builtin_amdgcn_s_setprio(0); } while (0)
; #define PG8_WAIT_V(n) asm volatile("s_waitcnt vmcnt(" #n ")" ::: "memory")
; #define PG8_WAIT_L(n) asm volatile("s_waitcnt lgkmcnt(" #n ")" ::: "memory")
; #define PG8_BAR __builtin_amdgcn_s_barrier()
; #define PG8_SCHED __builtin_amdgcn_sched_barrier(0)
; template <class Epi, class AMap>
; __device__ __forceinline__ void gemm_phase(LAS unsigned char* lds, const AMap am, const int lda, const h16* Bt, const int ldb, const int M, const int N, const int K, const Epi& E) {
;     ...
;         for (int t = 0; t < nt; t += 2) {
;     ...
;             PG8_LDA(At, 1, 1); PG8_STAGE(PG8_SA(1, 0), a3, voffA);
;             PG8_BAR; PG8_WAIT_L(0); PG8_MMA(1, 0, At, B0); PG8_BAR; PG8_SCHED;
;             PG8_STAGE(PG8_SB(1, 1), b3 + hstepB, voffB);
;             PG8_WAIT_V(6); PG8_BAR; PG8_MMA(1, 1, At, B1); PG8_BAR;
;         }
	global_load_lds_dwordx4 v[200:201], off
	v_lshl_add_u64 v[200:201], v[206:207], 0, s[92:93]
	s_add_i32 m0, s22, 0x2000
	s_nop 0
	global_load_lds_dwordx4 v[200:201], off
	s_mov_b32 m0, s78
	v_lshl_add_u64 v[200:201], v[212:213], 0, s[92:93]
	ds_read_b128 v[156:159], v205 offset:49152
	ds_read_b128 v[160:163], v205 offset:50176
	ds_read_b128 v[164:167], v205 offset:51200
	ds_read_b128 v[168:171], v205 offset:52224
	ds_read_b128 v[172:175], v205 offset:53248
	ds_read_b128 v[176:179], v205 offset:54272
	ds_read_b128 v[180:183], v205 offset:55296
	ds_read_b128 v[184:187], v205 offset:56320
	global_load_lds_dwordx4 v[200:201], off
	v_lshl_add_u64 v[200:201], v[224:225], 0, s[92:93]
	s_mov_b32 m0, s79
	s_nop 0
	global_load_lds_dwordx4 v[200:201], off
	s_add_u32 s22, s26, 0x10080
	s_addc_u32 s23, s27, 0
	s_add_i32 s26, s48, s71
	v_lshl_add_u64 v[232:233], s[22:23], 0, v[0:1]
	s_mov_b32 m0, s26
	s_nop 0
	global_load_lds_dwordx4 v[232:233], off
	v_lshl_add_u64 v[232:233], s[22:23], 0, v[146:147]
	s_add_i32 m0, s26, 0x2000
	s_nop 0
	global_load_lds_dwordx4 v[232:233], off
	s_add_u32 s29, s29, 0x100
	s_addc_u32 s45, s45, 0
	s_cmp_ge_i32 s51, s24
	s_mov_b64 s[22:23], s[0:1]
	s_mov_b32 s26, s51
	s_waitcnt vmcnt(8) lgkmcnt(0)
	s_barrier
	v_mfma_f32_16x16x32_f16 v[62:65], v[130:133], v[156:159], v[62:65]
	v_mfma_f32_16x16x32_f16 v[58:61], v[138:141], v[156:159], v[58:61]
	v_mfma_f32_16x16x32_f16 v[46:49], v[130:133], v[164:167], v[46:49]
	v_mfma_f32_16x16x32_f16 v[42:45], v[138:141], v[164:167], v[42:45]
	v_mfma_f32_16x16x32_f16 v[30:33], v[130:133], v[172:175], v[30:33]
	v_mfma_f32_16x16x32_f16 v[26:29], v[138:141], v[172:175], v[26:29]
	v_mfma_f32_16x16x32_f16 v[14:17], v[130:133], v[180:183], v[14:17]
	v_mfma_f32_16x16x32_f16 v[10:13], v[138:141], v[180:183], v[10:13]
	v_mfma_f32_16x16x32_f16 v[62:65], v[134:137], v[160:163], v[62:65]
	v_mfma_f32_16x16x32_f16 v[58:61], v[152:155], v[160:163], v[58:61]
	v_mfma_f32_16x16x32_f16 v[46:49], v[134:137], v[168:171], v[46:49]
	v_mfma_f32_16x16x32_f16 v[42:45], v[152:155], v[168:171], v[42:45]
	v_mfma_f32_16x16x32_f16 v[30:33], v[134:137], v[176:179], v[30:33]
	v_mfma_f32_16x16x32_f16 v[26:29], v[152:155], v[176:179], v[26:29]
	v_mfma_f32_16x16x32_f16 v[14:17], v[134:137], v[184:187], v[14:17]
	v_mfma_f32_16x16x32_f16 v[10:13], v[152:155], v[184:187], v[10:13]
	v_mfma_f32_16x16x32_f16 v[54:57], v[188:191], v[156:159], v[54:57]
	v_mfma_f32_16x16x32_f16 v[50:53], v[196:199], v[156:159], v[50:53]
	v_mfma_f32_16x16x32_f16 v[38:41], v[188:191], v[164:167], v[38:41]
	v_mfma_f32_16x16x32_f16 v[34:37], v[196:199], v[164:167], v[34:37]
	v_mfma_f32_16x16x32_f16 v[22:25], v[188:191], v[172:175], v[22:25]
	v_mfma_f32_16x16x32_f16 v[18:21], v[196:199], v[172:175], v[18:21]
	v_mfma_f32_16x16x32_f16 v[6:9], v[188:191], v[180:183], v[6:9]
	v_mfma_f32_16x16x32_f16 v[2:5], v[196:199], v[180:183], v[2:5]
	v_mfma_f32_16x16x32_f16 v[54:57], v[192:195], v[160:163], v[54:57]
	v_mfma_f32_16x16x32_f16 v[50:53], v[220:223], v[160:163], v[50:53]
	v_mfma_f32_16x16x32_f16 v[38:41], v[192:195], v[168:171], v[38:41]
	v_mfma_f32_16x16x32_f16 v[34:37], v[220:223], v[168:171], v[34:37]
	v_mfma_f32_16x16x32_f16 v[22:25], v[192:195], v[176:179], v[22:25]
	v_mfma_f32_16x16x32_f16 v[18:21], v[220:223], v[176:179], v[18:21]
	v_mfma_f32_16x16x32_f16 v[6:9], v[192:195], v[184:187], v[6:9]
	v_mfma_f32_16x16x32_f16 v[2:5], v[220:223], v[184:187], v[2:5]
	s_barrier
	s_cbranch_scc0 .LBB0_644
	s_branch .LBB0_633

; #define PG8_STAGE(bufoff, gbase, voff) do { _Pragma("unroll") for (int _i = 0; _i < 2; ++_i) \
;         __builtin_amdgcn_global_load_lds((const unsigned*)((const char*)(gbase) + (voff)[_i]), (LAS unsigned*)(lds + (bufoff) + ldsw + _i * 8192), 16, 0, 0); } while (0)
; #define PG8_LDA(dst, b, h) do { _Pragma("unroll") for (int m = 0; m < 4; ++m) _Pragma("unroll") for (int k = 0; k < 2; ++k) dst[m][k] = *(const LAS h16x8*)(lds + PG8_SA(b, h) + aoff + m * 2048 + k * 1024); } while (0)
; #define PG8_LDB(dst, b, h) do { _Pragma("unroll") for (int n = 0; n < 2; ++n) _Pragma("unroll") for (int k = 0; k < 2; ++k) dst[n][k] = *(const LAS h16x8*)(lds + PG8_SB(b, h) + boff + n * 2048 + k * 1024); } while (0)
; #define PG8_WAIT_L(n) asm volatile("s_waitcnt lgkmcnt(" #n ")" ::: "memory")
; #define PG8_BAR __builtin_amdgcn_s_barrier()
; #define PG8_SCHED __builtin_amdgcn_sched_barrier(0)
; template <class Epi, class AMap>
; __device__ __forceinline__ void gemm_phase(LAS unsigned char* lds, const AMap am, const int lda, const h16* Bt, const int ldb, const int M, const int N, const int K, const Epi& E) {
;     ...
;         const bool has_next = S.next(ui + 1, nxt);
;         const char* nA = has_next ? am(nxt.pn) + (size_t)nxt.pm * tstepA : cA; const char* nB = has_next ? (const char*)Bt + (size_t)nxt.pn * tstepB : cB;
; #pragma unroll 1
;         for (int t = 0; t < nt; t += 2) {
;             const bool last = (t == nt - 2);
;             const char* a1 = cA + (size_t)(t + 1) * kstep;
;             const char* a2 = last ? nA : cA + (size_t)(t + 2) * kstep; const char* b2 = last ? nB : cB + (size_t)(t + 2) * kstep;
;             const char* a3 = a2 + kstep; const char* b3 = b2 + kstep;
;             PG8_LDB(B0, 0, 0); PG8_SCHED; PG8_LDA(At, 0, 0); PG8_STAGE(PG8_SA(1, 1), a1 + hstepA, voffA);
;             PG8_WAIT_L(8); PG8_BAR; PG8_WAIT_L(0); PG8_MMA(0, 0, At, B0); PG8_BAR; PG8_SCHED;
;             PG8_LDB(B1, 0, 1); PG8_STAGE(PG8_SB(0, 0), b2, voffB);
;             PG8_BAR; PG8_WAIT_L(0); PG8_MMA(0, 1, At, B1); PG8_BAR;
;             PG8_LDA(At, 0, 1); PG8_STAGE(PG8_SA(0, 0), a2, voffA);
;             PG8_BAR; PG8_WAIT_L(0); PG8_MMA(1, 0, At, B0); PG8_BAR; PG8_SCHED;
;             PG8_STAGE(PG8_SB(0, 1), b2 + hstepB, voffB);
.LBB0_667:
	s_add_i32 s60, s46, 2
	s_add_u32 s0, s44, 0x100
	s_addc_u32 s1, s45, 0
	s_add_i32 s66, 0, 0x10000
	v_add_u32_e32 v234, s66, v161
	ds_read_b128 v[140:143], v234
	ds_read_b128 v[144:147], v234 offset:1024
	ds_read_b128 v[148:151], v234 offset:2048
	ds_read_b128 v[152:155], v234 offset:3072
	s_cmp_eq_u32 s73, s46
	s_cselect_b32 s46, s21, s27
	s_cselect_b32 s49, s41, s1
	s_cselect_b32 s48, s40, s0
	s_cselect_b32 s47, s20, s29
	v_lshl_add_u64 v[232:233], s[44:45], 0, v[136:137]
	s_add_i32 m0, s65, 0xc000
	ds_read_b128 v[156:159], v163
	ds_read_b128 v[164:167], v163 offset:1024
	ds_read_b128 v[168:171], v163 offset:2048
	ds_read_b128 v[172:175], v163 offset:3072
	ds_read_b128 v[176:179], v163 offset:4096
	ds_read_b128 v[180:183], v163 offset:5120
	ds_read_b128 v[184:187], v163 offset:6144
	ds_read_b128 v[188:191], v163 offset:7168
	global_load_lds_dwordx4 v[232:233], off
	v_lshl_add_u64 v[232:233], s[44:45], 0, v[138:139]
	s_add_i32 m0, s65, 0xe000
	s_nop 0
	global_load_lds_dwordx4 v[232:233], off
	s_waitcnt lgkmcnt(11)
	s_add_i32 s78, 0, 0x14000
	s_add_i32 s44, s66, s62
	v_add_u32_e32 v234, s78, v161
	v_lshl_add_u64 v[212:213], s[46:47], 0, v[0:1]
	s_mov_b32 m0, s44
	ds_read_b128 v[192:195], v234
	ds_read_b128 v[196:199], v234 offset:1024
	ds_read_b128 v[200:203], v234 offset:2048
	ds_read_b128 v[204:207], v234 offset:3072
	s_waitcnt vmcnt(8) lgkmcnt(0)
	s_barrier
	v_mfma_f32_16x16x32_f16 v[126:129], v[140:143], v[156:159], v[126:129]
	v_mfma_f32_16x16x32_f16 v[122:125], v[148:151], v[156:159], v[122:125]
	v_mfma_f32_16x16x32_f16 v[118:121], v[140:143], v[168:171], v[118:121]
	v_mfma_f32_16x16x32_f16 v[114:117], v[148:151], v[168:171], v[114:117]
	v_mfma_f32_16x16x32_f16 v[110:113], v[140:143], v[176:179], v[110:113]
	v_mfma_f32_16x16x32_f16 v[106:109], v[148:151], v[176:179], v[106:109]
	v_mfma_f32_16x16x32_f16 v[102:105], v[140:143], v[184:187], v[102:105]
	v_mfma_f32_16x16x32_f16 v[98:101], v[148:151], v[184:187], v[98:101]
	v_mfma_f32_16x16x32_f16 v[126:129], v[144:147], v[164:167], v[126:129]
	v_mfma_f32_16x16x32_f16 v[122:125], v[152:155], v[164:167], v[122:125]
	v_mfma_f32_16x16x32_f16 v[118:121], v[144:147], v[172:175], v[118:121]
	v_mfma_f32_16x16x32_f16 v[114:117], v[152:155], v[172:175], v[114:117]
	v_mfma_f32_16x16x32_f16 v[110:113], v[144:147], v[180:183], v[110:113]
	v_mfma_f32_16x16x32_f16 v[106:109], v[152:155], v[180:183], v[106:109]
	v_mfma_f32_16x16x32_f16 v[102:105], v[144:147], v[188:191], v[102:105]
	v_mfma_f32_16x16x32_f16 v[98:101], v[152:155], v[188:191], v[98:101]
	v_mfma_f32_16x16x32_f16 v[94:97], v[192:195], v[156:159], v[94:97]
	v_mfma_f32_16x16x32_f16 v[86:89], v[200:203], v[156:159], v[86:89]
	v_mfma_f32_16x16x32_f16 v[78:81], v[192:195], v[168:171], v[78:81]
	v_mfma_f32_16x16x32_f16 v[70:73], v[200:203], v[168:171], v[70:73]
	v_mfma_f32_16x16x32_f16 v[62:65], v[192:195], v[176:179], v[62:65]
	v_mfma_f32_16x16x32_f16 v[54:57], v[200:203], v[176:179], v[54:57]
	v_mfma_f32_16x16x32_f16 v[46:49], v[192:195], v[184:187], v[46:49]
	v_mfma_f32_16x16x32_f16 v[38:41], v[200:203], v[184:187], v[38:41]
	v_mfma_f32_16x16x32_f16 v[94:97], v[196:199], v[164:167], v[94:97]
	v_mfma_f32_16x16x32_f16 v[86:89], v[204:207], v[164:167], v[86:89]
	v_mfma_f32_16x16x32_f16 v[78:81], v[196:199], v[172:175], v[78:81]
	v_mfma_f32_16x16x32_f16 v[70:73], v[204:207], v[172:175], v[70:73]
	v_mfma_f32_16x16x32_f16 v[62:65], v[196:199], v[180:183], v[62:65]
	v_mfma_f32_16x16x32_f16 v[54:57], v[204:207], v[180:183], v[54:57]
	v_mfma_f32_16x16x32_f16 v[46:49], v[196:199], v[188:191], v[46:49]
	v_mfma_f32_16x16x32_f16 v[38:41], v[204:207], v[188:191], v[38:41]
	s_barrier
	global_load_lds_dwordx4 v[212:213], off
	v_lshl_add_u64 v[220:221], s[46:47], 0, v[134:135]
	s_add_i32 m0, s44, 0x2000
	s_nop 0
	global_load_lds_dwordx4 v[220:221], off
	s_mov_b32 m0, s65
	v_lshl_add_u64 v[222:223], s[48:49], 0, v[130:131]
	ds_read_b128 v[156:159], v163 offset:16384
	ds_read_b128 v[164:167], v163 offset:17408
	ds_read_b128 v[168:171], v163 offset:18432
	ds_read_b128 v[172:175], v163 offset:19456
	ds_read_b128 v[176:179], v163 offset:20480
	ds_read_b128 v[180:183], v163 offset:21504
	ds_read_b128 v[184:187], v163 offset:22528
	ds_read_b128 v[188:191], v163 offset:23552
	global_load_lds_dwordx4 v[222:223], off
	v_lshl_add_u64 v[224:225], s[48:49], 0, v[132:133]
	s_mov_b32 m0, s68
	s_nop 0
	global_load_lds_dwordx4 v[224:225], off
	s_add_u32 s44, s46, 0x10000
	s_addc_u32 s45, s47, 0
	s_add_i32 s66, s78, s62
	v_lshl_add_u64 v[232:233], s[44:45], 0, v[0:1]
	s_mov_b32 m0, s66
	s_nop 0
	global_load_lds_dwordx4 v[232:233], off
	v_lshl_add_u64 v[232:233], s[44:45], 0, v[134:135]
	s_add_i32 m0, s66, 0x2000
	s_nop 0
	global_load_lds_dwordx4 v[232:233], off
	s_waitcnt vmcnt(8) lgkmcnt(0)
	s_barrier
; #define PG8_STAGE(bufoff, gbase, voff) do { _Pragma("unroll") for (int _i = 0; _i < 2; ++_i) \
;         __builtin_amdgcn_global_load_lds((const unsigned*)((const char*)(gbase) + (voff)[_i]), (LAS unsigned*)(lds + (bufoff) + ldsw + _i * 8192), 16, 0, 0); } while (0)
; #define PG8_LDA(dst, b, h) do { _Pragma("unroll") for (int m = 0; m < 4; ++m) _Pragma("unroll") for (int k = 0; k < 2; ++k) dst[m][k] = *(const LAS h16x8*)(lds + PG8_SA(b, h) + aoff + m * 2048 + k * 1024); } while (0)
; #define PG8_LDB(dst, b, h) do { _Pragma("unroll") for (int n = 0; n < 2; ++n) _Pragma("unroll") for (int k = 0; k < 2; ++k) dst[n][k] = *(const LAS h16x8*)(lds + PG8_SB(b, h) + boff + n * 2048 + k * 1024); } while (0)
; #define PG8_MMA(ai, bj, At, Bt_) do { __builtin_amdgcn_s_setprio(1); _Pragma("unroll") for (int m = 0; m < 4; ++m) _Pragma("unroll") for (int n = 0; n < 2; ++n) _Pragma("unroll") for (int k = 0; k < 2; ++k) \
;         acc[ai][bj][m][n] = __builtin_amdgcn_mfma_f32_16x16x32_f16(Bt_[n][k], At[m][k], acc[ai][bj][m][n], 0, 0, 0); __builtin_amdgcn_s_setprio(0); } while (0)
; #define PG8_WAIT_V(n) asm volatile("s_waitcnt vmcnt(" #n ")" ::: "memory")
; #define PG8_WAIT_L(n) asm volatile("s_waitcnt lgkmcnt(" #n ")" ::: "memory")
; #define PG8_BAR __builtin_amdgcn_s_barrier()
; #define PG8_SCHED __builtin_amdgcn_sched_barrier(0)
; template <class Epi, class AMap>
; __device__ __forceinline__ void gemm_phase(LAS unsigned char* lds, const AMap am, const int lda, const h16* Bt, const int ldb, const int M, const int N, const int K, const Epi& E) {
;     ...
;             PG8_BAR; PG8_WAIT_L(0); PG8_MMA(1, 0, At, B0); PG8_BAR; PG8_SCHED;
;             PG8_STAGE(PG8_SB(0, 1), b2 + hstepB, voffB);
;             PG8_WAIT_V(6); PG8_BAR; PG8_MMA(1, 1, At, B1); PG8_BAR;
;             PG8_LDB(B0, 1, 0); PG8_SCHED; PG8_LDA(At, 1, 0); PG8_STAGE(PG8_SA(0, 1), a2 + hstepA, voffA);
;             PG8_WAIT_L(8); PG8_BAR; PG8_WAIT_L(0); PG8_MMA(0, 0, At, B0); PG8_BAR; PG8_SCHED;
;             PG8_LDB(B1, 1, 1); PG8_STAGE(PG8_SB(1, 0), b3, voffB);
;             PG8_BAR; PG8_WAIT_L(0); PG8_MMA(0, 1, At, B1); PG8_BAR;
	v_mfma_f32_16x16x32_f16 v[90:93], v[140:143], v[156:159], v[90:93]
	v_mfma_f32_16x16x32_f16 v[82:85], v[148:151], v[156:159], v[82:85]
	v_mfma_f32_16x16x32_f16 v[74:77], v[140:143], v[168:171], v[74:77]
	v_mfma_f32_16x16x32_f16 v[66:69], v[148:151], v[168:171], v[66:69]
	v_mfma_f32_16x16x32_f16 v[58:61], v[140:143], v[176:179], v[58:61]
	v_mfma_f32_16x16x32_f16 v[50:53], v[148:151], v[176:179], v[50:53]
	v_mfma_f32_16x16x32_f16 v[42:45], v[140:143], v[184:187], v[42:45]
	v_mfma_f32_16x16x32_f16 v[34:37], v[148:151], v[184:187], v[34:37]
	v_mfma_f32_16x16x32_f16 v[90:93], v[144:147], v[164:167], v[90:93]
	v_mfma_f32_16x16x32_f16 v[82:85], v[152:155], v[164:167], v[82:85]
	v_mfma_f32_16x16x32_f16 v[74:77], v[144:147], v[172:175], v[74:77]
	v_mfma_f32_16x16x32_f16 v[66:69], v[152:155], v[172:175], v[66:69]
	v_mfma_f32_16x16x32_f16 v[58:61], v[144:147], v[180:183], v[58:61]
	v_mfma_f32_16x16x32_f16 v[50:53], v[152:155], v[180:183], v[50:53]
	v_mfma_f32_16x16x32_f16 v[42:45], v[144:147], v[188:191], v[42:45]
	v_mfma_f32_16x16x32_f16 v[34:37], v[152:155], v[188:191], v[34:37]
	v_mfma_f32_16x16x32_f16 v[30:33], v[192:195], v[156:159], v[30:33]
	v_mfma_f32_16x16x32_f16 v[26:29], v[200:203], v[156:159], v[26:29]
	v_mfma_f32_16x16x32_f16 v[22:25], v[192:195], v[168:171], v[22:25]
	v_mfma_f32_16x16x32_f16 v[18:21], v[200:203], v[168:171], v[18:21]
	v_mfma_f32_16x16x32_f16 v[14:17], v[192:195], v[176:179], v[14:17]
	v_mfma_f32_16x16x32_f16 v[10:13], v[200:203], v[176:179], v[10:13]
	v_mfma_f32_16x16x32_f16 v[6:9], v[192:195], v[184:187], v[6:9]
	v_mfma_f32_16x16x32_f16 v[2:5], v[200:203], v[184:187], v[2:5]
	v_mfma_f32_16x16x32_f16 v[30:33], v[196:199], v[164:167], v[30:33]
	v_mfma_f32_16x16x32_f16 v[26:29], v[204:207], v[164:167], v[26:29]
	v_mfma_f32_16x16x32_f16 v[22:25], v[196:199], v[172:175], v[22:25]
	v_mfma_f32_16x16x32_f16 v[18:21], v[204:207], v[172:175], v[18:21]
	v_mfma_f32_16x16x32_f16 v[14:17], v[196:199], v[180:183], v[14:17]
	v_mfma_f32_16x16x32_f16 v[10:13], v[204:207], v[180:183], v[10:13]
	v_mfma_f32_16x16x32_f16 v[6:9], v[196:199], v[188:191], v[6:9]
	v_mfma_f32_16x16x32_f16 v[2:5], v[204:207], v[188:191], v[2:5]
	s_barrier
	s_add_i32 s66, 0, 0x18000
	v_add_u32_e32 v234, s66, v161
	ds_read_b128 v[140:143], v234
	ds_read_b128 v[144:147], v234 offset:1024
	ds_read_b128 v[148:151], v234 offset:2048
	ds_read_b128 v[152:155], v234 offset:3072
	s_add_u32 s44, s48, 0x1c0000
	s_addc_u32 s45, s49, 0
	s_mov_b32 m0, s69
	v_lshl_add_u64 v[232:233], s[44:45], 0, v[130:131]
	ds_read_b128 v[156:159], v163 offset:32768
	ds_read_b128 v[164:167], v163 offset:33792
	ds_read_b128 v[168:171], v163 offset:34816
	ds_read_b128 v[172:175], v163 offset:35840
	ds_read_b128 v[176:179], v163 offset:36864
	ds_read_b128 v[180:183], v163 offset:37888
	ds_read_b128 v[184:187], v163 offset:38912
	ds_read_b128 v[188:191], v163 offset:39936
	global_load_lds_dwordx4 v[232:233], off
	v_lshl_add_u64 v[232:233], s[44:45], 0, v[132:133]
	s_mov_b32 m0, s70
	s_nop 0
	global_load_lds_dwordx4 v[232:233], off
	s_waitcnt lgkmcnt(11)
	s_add_i32 s48, 0, 0x1c000
	s_add_i32 s44, s66, s62
	v_add_u32_e32 v234, s48, v161
	v_lshl_add_u64 v[212:213], v[212:213], 0, s[92:93]
	s_mov_b32 m0, s44
	ds_read_b128 v[192:195], v234
	ds_read_b128 v[196:199], v234 offset:1024
	ds_read_b128 v[200:203], v234 offset:2048
	ds_read_b128 v[204:207], v234 offset:3072
	s_waitcnt vmcnt(8) lgkmcnt(0)
	s_barrier
	v_mfma_f32_16x16x32_f16 v[126:129], v[140:143], v[156:159], v[126:129]
	v_mfma_f32_16x16x32_f16 v[122:125], v[148:151], v[156:159], v[122:125]
	v_mfma_f32_16x16x32_f16 v[118:121], v[140:143], v[168:171], v[118:121]
	v_mfma_f32_16x16x32_f16 v[114:117], v[148:151], v[168:171], v[114:117]
	v_mfma_f32_16x16x32_f16 v[110:113], v[140:143], v[176:179], v[110:113]
	v_mfma_f32_16x16x32_f16 v[106:109], v[148:151], v[176:179], v[106:109]
	v_mfma_f32_16x16x32_f16 v[102:105], v[140:143], v[184:187], v[102:105]
	v_mfma_f32_16x16x32_f16 v[98:101], v[148:151], v[184:187], v[98:101]
	v_mfma_f32_16x16x32_f16 v[126:129], v[144:147], v[164:167], v[126:129]
	v_mfma_f32_16x16x32_f16 v[122:125], v[152:155], v[164:167], v[122:125]
	v_mfma_f32_16x16x32_f16 v[118:121], v[144:147], v[172:175], v[118:121]
	v_mfma_f32_16x16x32_f16 v[114:117], v[152:155], v[172:175], v[114:117]
	v_mfma_f32_16x16x32_f16 v[110:113], v[144:147], v[180:183], v[110:113]
	v_mfma_f32_16x16x32_f16 v[106:109], v[152:155], v[180:183], v[106:109]
	v_mfma_f32_16x16x32_f16 v[102:105], v[144:147], v[188:191], v[102:105]
	v_mfma_f32_16x16x32_f16 v[98:101], v[152:155], v[188:191], v[98:101]
	v_mfma_f32_16x16x32_f16 v[94:97], v[192:195], v[156:159], v[94:97]
	v_mfma_f32_16x16x32_f16 v[86:89], v[200:203], v[156:159], v[86:89]
	v_mfma_f32_16x16x32_f16 v[78:81], v[192:195], v[168:171], v[78:81]
	v_mfma_f32_16x16x32_f16 v[70:73], v[200:203], v[168:171], v[70:73]
	v_mfma_f32_16x16x32_f16 v[62:65], v[192:195], v[176:179], v[62:65]
	v_mfma_f32_16x16x32_f16 v[54:57], v[200:203], v[176:179], v[54:57]
	v_mfma_f32_16x16x32_f16 v[46:49], v[192:195], v[184:187], v[46:49]
	v_mfma_f32_16x16x32_f16 v[38:41], v[200:203], v[184:187], v[38:41]
	v_mfma_f32_16x16x32_f16 v[94:97], v[196:199], v[164:167], v[94:97]
	v_mfma_f32_16x16x32_f16 v[86:89], v[204:207], v[164:167], v[86:89]
	v_mfma_f32_16x16x32_f16 v[78:81], v[196:199], v[172:175], v[78:81]
	v_mfma_f32_16x16x32_f16 v[70:73], v[204:207], v[172:175], v[70:73]
	v_mfma_f32_16x16x32_f16 v[62:65], v[196:199], v[180:183], v[62:65]
	v_mfma_f32_16x16x32_f16 v[54:57], v[204:207], v[180:183], v[54:57]
	v_mfma_f32_16x16x32_f16 v[46:49], v[196:199], v[188:191], v[46:49]
	v_mfma_f32_16x16x32_f16 v[38:41], v[204:207], v[188:191], v[38:41]
	s_barrier
; #define PG8_STAGE(bufoff, gbase, voff) do { _Pragma("unroll") for (int _i = 0; _i < 2; ++_i) \
;         __builtin_amdgcn_global_load_lds((const unsigned*)((const char*)(gbase) + (voff)[_i]), (LAS unsigned*)(lds + (bufoff) + ldsw + _i * 8192), 16, 0, 0); } while (0)
; #define PG8_LDA(dst, b, h) do { _Pragma("unroll") for (int m = 0; m < 4; ++m) _Pragma("unroll") for (int k = 0; k < 2; ++k) dst[m][k] = *(const LAS h16x8*)(lds + PG8_SA(b, h) + aoff + m * 2048 + k * 1024); } while (0)
; #define PG8_MMA(ai, bj, At, Bt_) do { __builtin_amdgcn_s_setprio(1); _Pragma("unroll") for (int m = 0; m < 4; ++m) _Pragma("unroll") for (int n = 0; n < 2; ++n) _Pragma("unroll") for (int k = 0; k < 2; ++k) \
;         acc[ai][bj][m][n] = __builtin_amdgcn_mfma_f32_16x16x32_f16(Bt_[n][k], At[m][k], acc[ai][bj][m][n], 0, 0, 0); __builtin_amdgcn_s_setprio(0); } while (0)
; #define PG8_WAIT_V(n) asm volatile("s_waitcnt vmcnt(" #n ")" ::: "memory")
; #define PG8_WAIT_L(n) asm volatile("s_waitcnt lgkmcnt(" #n ")" ::: "memory")
; #define PG8_BAR __builtin_amdgcn_s_barrier()
; #define PG8_SCHED __builtin_amdgcn_sched_barrier(0)
; template <class Epi, class AMap>
; __device__ __forceinline__ void gemm_phase(LAS unsigned char* lds, const AMap am, const int lda, const h16* Bt, const int ldb, const int M, const int N, const int K, const Epi& E) {
;     ...
;         for (int t = 0; t < nt; t += 2) {
;     ...
;             PG8_LDA(At, 1, 1); PG8_STAGE(PG8_SA(1, 0), a3, voffA);
;             PG8_BAR; PG8_WAIT_L(0); PG8_MMA(1, 0, At, B0); PG8_BAR; PG8_SCHED;
;             PG8_STAGE(PG8_SB(1, 1), b3 + hstepB, voffB);
;             PG8_WAIT_V(6); PG8_BAR; PG8_MMA(1, 1, At, B1); PG8_BAR;
;         }
	global_load_lds_dwordx4 v[212:213], off
	v_lshl_add_u64 v[212:213], v[220:221], 0, s[92:93]
	s_add_i32 m0, s44, 0x2000
	s_nop 0
	global_load_lds_dwordx4 v[212:213], off
	s_mov_b32 m0, s71
	v_lshl_add_u64 v[212:213], v[222:223], 0, s[92:93]
	ds_read_b128 v[156:159], v163 offset:49152
	ds_read_b128 v[164:167], v163 offset:50176
	ds_read_b128 v[168:171], v163 offset:51200
	ds_read_b128 v[172:175], v163 offset:52224
	ds_read_b128 v[176:179], v163 offset:53248
	ds_read_b128 v[180:183], v163 offset:54272
	ds_read_b128 v[184:187], v163 offset:55296
	ds_read_b128 v[188:191], v163 offset:56320
	global_load_lds_dwordx4 v[212:213], off
	v_lshl_add_u64 v[212:213], v[224:225], 0, s[92:93]
	s_mov_b32 m0, s72
	s_nop 0
	global_load_lds_dwordx4 v[212:213], off
	s_add_u32 s44, s46, 0x10080
	s_addc_u32 s45, s47, 0
	s_add_i32 s46, s48, s62
	v_lshl_add_u64 v[232:233], s[44:45], 0, v[0:1]
	s_mov_b32 m0, s46
	s_nop 0
	global_load_lds_dwordx4 v[232:233], off
	v_lshl_add_u64 v[232:233], s[44:45], 0, v[134:135]
	s_add_i32 m0, s46, 0x2000
	s_nop 0
	global_load_lds_dwordx4 v[232:233], off
	s_add_u32 s27, s27, 0x100
	s_addc_u32 s29, s29, 0
	s_cmp_ge_i32 s60, s24
	s_mov_b64 s[44:45], s[0:1]
	s_mov_b32 s46, s60
	s_waitcnt vmcnt(8) lgkmcnt(0)
	s_barrier
	v_mfma_f32_16x16x32_f16 v[90:93], v[140:143], v[156:159], v[90:93]
	v_mfma_f32_16x16x32_f16 v[82:85], v[148:151], v[156:159], v[82:85]
	v_mfma_f32_16x16x32_f16 v[74:77], v[140:143], v[168:171], v[74:77]
	v_mfma_f32_16x16x32_f16 v[66:69], v[148:151], v[168:171], v[66:69]
	v_mfma_f32_16x16x32_f16 v[58:61], v[140:143], v[176:179], v[58:61]
	v_mfma_f32_16x16x32_f16 v[50:53], v[148:151], v[176:179], v[50:53]
	v_mfma_f32_16x16x32_f16 v[42:45], v[140:143], v[184:187], v[42:45]
	v_mfma_f32_16x16x32_f16 v[34:37], v[148:151], v[184:187], v[34:37]
	v_mfma_f32_16x16x32_f16 v[90:93], v[144:147], v[164:167], v[90:93]
	v_mfma_f32_16x16x32_f16 v[82:85], v[152:155], v[164:167], v[82:85]
	v_mfma_f32_16x16x32_f16 v[74:77], v[144:147], v[172:175], v[74:77]
	v_mfma_f32_16x16x32_f16 v[66:69], v[152:155], v[172:175], v[66:69]
	v_mfma_f32_16x16x32_f16 v[58:61], v[144:147], v[180:183], v[58:61]
	v_mfma_f32_16x16x32_f16 v[50:53], v[152:155], v[180:183], v[50:53]
	v_mfma_f32_16x16x32_f16 v[42:45], v[144:147], v[188:191], v[42:45]
	v_mfma_f32_16x16x32_f16 v[34:37], v[152:155], v[188:191], v[34:37]
	v_mfma_f32_16x16x32_f16 v[30:33], v[192:195], v[156:159], v[30:33]
	v_mfma_f32_16x16x32_f16 v[26:29], v[200:203], v[156:159], v[26:29]
	v_mfma_f32_16x16x32_f16 v[22:25], v[192:195], v[168:171], v[22:25]
	v_mfma_f32_16x16x32_f16 v[18:21], v[200:203], v[168:171], v[18:21]
	v_mfma_f32_16x16x32_f16 v[14:17], v[192:195], v[176:179], v[14:17]
	v_mfma_f32_16x16x32_f16 v[10:13], v[200:203], v[176:179], v[10:13]
	v_mfma_f32_16x16x32_f16 v[6:9], v[192:195], v[184:187], v[6:9]
	v_mfma_f32_16x16x32_f16 v[2:5], v[200:203], v[184:187], v[2:5]
	v_mfma_f32_16x16x32_f16 v[30:33], v[196:199], v[164:167], v[30:33]
	v_mfma_f32_16x16x32_f16 v[26:29], v[204:207], v[164:167], v[26:29]
	v_mfma_f32_16x16x32_f16 v[22:25], v[196:199], v[172:175], v[22:25]
	v_mfma_f32_16x16x32_f16 v[18:21], v[204:207], v[172:175], v[18:21]
	v_mfma_f32_16x16x32_f16 v[14:17], v[196:199], v[180:183], v[14:17]
	v_mfma_f32_16x16x32_f16 v[10:13], v[204:207], v[180:183], v[10:13]
	v_mfma_f32_16x16x32_f16 v[6:9], v[196:199], v[188:191], v[6:9]
	v_mfma_f32_16x16x32_f16 v[2:5], v[204:207], v[188:191], v[2:5]
	s_barrier
	s_cbranch_scc0 .LBB0_667
	s_cmpk_gt_u32 s50, 0xff
	s_cbranch_scc1 .Lgx6
	s_barrier

; __device__ __forceinline__ float sigmoidf_(float x) { return 1.0f / (1.0f + __expf(-x)); }
; #define PG8_BAR __builtin_amdgcn_s_barrier()
; template <class Epi, class AMap>
; __device__ __forceinline__ void gemm_phase(LAS unsigned char* lds, const AMap am, const int lda, const h16* Bt, const int ldb, const int M, const int N, const int K, const Epi& E) {
;     ...
;     if (wr == 0) PG8_BAR;
;     template <int GI>
;     __device__ __forceinline__ void body(const f32x4 (&acc)[2][2][4][2], int row0, int colt) const {
;     ...
;             if (GI == 0) { b0 = *(const f32x4*)(w0 + c); b1 = *(const f32x4*)(w0 + c + 4); }
;             else if (GI == 1) { b0 = *(const f32x4*)(a0 + c); b1 = *(const f32x4*)(a0 + c + 4); }
;             else if (GI == 3) { b0 = *(const f32x4*)(v0 + c); b1 = *(const f32x4*)(v0 + c + 4); }
; #pragma unroll
;             for (int ai = 0; ai < 2; ++ai)
; #pragma unroll
;                 for (int m = 0; m < 4; ++m) {
;                     const size_t row = (size_t)(row0 + ai * 128 + m * 16);
;                     f32x4 x0 = acc[ai][bj][m][0] + b0, x1 = acc[ai][bj][m][1] + b1;
;                     if (GI == 0) {
; #pragma unroll
;                         for (int j = 0; j < 4; ++j) {
;                             x0[j] = 0.6065306597126334f * sigmoidf_(x0[j]); x1[j] = 0.6065306597126334f * sigmoidf_(x1[j]); }
;                         *(u32x4*)(DEC + row * DM + c) = pack8(x0, x1);
;                     } else if (GI == 1) {
; #pragma unroll
;                         for (int j = 0; j < 4; ++j) { x0[j] = sigmoidf_(x0[j]); x1[j] = sigmoidf_(x1[j]); }
;                         *(u32x4*)(Ab + row * DM + c) = pack8(x0, x1);
;                     } else if (GI == 2) {
;                         *(u32x4*)(Gb + row * DM + c) = pack8(x0, x1);
;                     } else {
;                         h16* vp = C1 + row * LDC1 + 4096 + c;
;                         const h16x8 vv = *(const h16x8*)vp; const h16x8 vf = *(const h16x8*)(VF + row * DM + c);
;                         f32x4 o0, o1;
; #pragma unroll
;                         for (int j = 0; j < 4; ++j) { float v = (float)vv[j], f = (float)vf[j]; o0[j] = v + (f - v) * sigmoidf_(x0[j]); v = (float)vv[4 + j]; f = (float)vf[4 + j]; o1[j] = v + (f - v) * sigmoidf_(x1[j]); }
;                         *(u32x4*)vp = pack8(o0, o1);
.LBB0_681:
	v_lshl_or_b32 v158, s50, 8, v176
	v_ashrrev_i32_e32 v159, 31, v158
	v_lshl_add_u64 v[156:157], v[158:159], 2, s[40:41]
	global_load_dwordx4 v[82:85], v[156:157], off offset:16
	global_load_dwordx4 v[86:89], v[156:157], off
	v_lshl_add_u32 v164, s35, 8, v174
	v_mov_b64_e32 v[168:169], s[8:9]
	v_ashrrev_i32_e32 v165, 31, v164
	v_mad_i64_i32 v[138:139], s[0:1], v164, s5, v[168:169]
	v_lshl_add_u64 v[160:161], v[138:139], 0, s[90:91]
	v_lshlrev_b64 v[166:167], 1, v[158:159]
	v_lshlrev_b64 v[142:143], 12, v[164:165]
	v_lshl_add_u64 v[170:171], v[160:161], 0, v[166:167]
	v_lshl_add_u64 v[142:143], s[2:3], 0, v[142:143]
	global_load_dwordx4 v[138:141], v[170:171], off
	v_lshl_add_u64 v[162:163], v[142:143], 0, v[166:167]
	global_load_dwordx4 v[142:145], v[162:163], off
	s_cmpk_gt_u32 s69, 0xff
	s_cbranch_scc1 .Lgx7
	s_barrier
.Lgx7:
	s_waitcnt vmcnt(0)
	v_add_f32_e32 v130, v130, v82
	v_mul_f32_e32 v130, 0xbfb8aa3b, v130
	v_exp_f32_e32 v172, v130
	v_add_f32_e32 v130, v135, v87
	v_mul_f32_e32 v130, 0xbfb8aa3b, v130
	v_exp_f32_e32 v179, v130
	v_add_f32_e32 v130, v131, v83
	v_mul_f32_e32 v130, 0xbfb8aa3b, v130
	v_exp_f32_e32 v173, v130
	v_add_f32_e32 v130, v136, v88
	v_add_f32_e32 v134, v134, v86
	v_mul_f32_e32 v130, 0xbfb8aa3b, v130
	v_mul_f32_e32 v134, 0xbfb8aa3b, v134
	v_exp_f32_e32 v136, v130
	v_add_f32_e32 v130, v132, v84
	v_exp_f32_e32 v178, v134
	v_mul_f32_e32 v130, 0xbfb8aa3b, v130
	v_exp_f32_e32 v134, v130
	v_add_f32_e32 v130, v137, v89
	v_mul_f32_e32 v130, 0xbfb8aa3b, v130
	v_exp_f32_e32 v137, v130
	v_add_f32_e32 v130, v133, v85
	v_mul_f32_e32 v130, 0xbfb8aa3b, v130
	v_pk_add_f32 v[178:179], v[178:179], 1.0 op_sel_hi:[1,0]
	v_exp_f32_e32 v135, v130
	v_cvt_f32_f16_e32 v130, v138
	v_cvt_f32_f16_sdwa v131, v138 dst_sel:DWORD dst_unused:UNUSED_PAD src0_sel:WORD_1
	v_div_scale_f32 v138, s[0:1], v179, v179, 1.0
	v_cvt_f32_f16_e32 v132, v142
	v_cvt_f32_f16_sdwa v133, v142 dst_sel:DWORD dst_unused:UNUSED_PAD src0_sel:WORD_1
	v_rcp_f32_e32 v142, v138
	v_pk_add_f32 v[136:137], v[136:137], 1.0 op_sel_hi:[1,0]
	v_pk_add_f32 v[134:135], v[134:135], 1.0 op_sel_hi:[1,0]
	v_pk_add_f32 v[132:133], v[132:133], v[130:131] neg_lo:[0,1] neg_hi:[0,1]
	v_fma_f32 v159, -v138, v142, 1.0
	v_fmac_f32_e32 v142, v159, v142
	v_div_scale_f32 v159, vcc, 1.0, v179, 1.0
	v_mul_f32_e32 v165, v159, v142
	v_fma_f32 v180, -v138, v165, v159
	v_fmac_f32_e32 v165, v180, v142
	v_fma_f32 v138, -v138, v165, v159
	v_div_fmas_f32 v138, v138, v142, v165
	v_div_fixup_f32 v179, v138, v179, 1.0
	v_div_scale_f32 v138, s[0:1], v178, v178, 1.0
	v_rcp_f32_e32 v142, v138
	s_nop 0
	v_fma_f32 v159, -v138, v142, 1.0
	v_fmac_f32_e32 v142, v159, v142
	v_div_scale_f32 v159, vcc, 1.0, v178, 1.0
	v_mul_f32_e32 v165, v159, v142
	v_fma_f32 v180, -v138, v165, v159
	v_fmac_f32_e32 v165, v180, v142
	v_fma_f32 v138, -v138, v165, v159
	v_div_fmas_f32 v138, v138, v142, v165
	v_div_fixup_f32 v178, v138, v178, 1.0
	v_pk_fma_f32 v[130:131], v[178:179], v[132:133], v[130:131]
	v_cvt_f32_f16_e32 v132, v139
	v_cvt_pk_f16_f32 v130, v130, v131
	v_div_scale_f32 v131, s[0:1], v137, v137, 1.0
	v_rcp_f32_e32 v142, v131
	v_cvt_f32_f16_sdwa v133, v139 dst_sel:DWORD dst_unused:UNUSED_PAD src0_sel:WORD_1
	v_cvt_f32_f16_e32 v138, v143
	v_cvt_f32_f16_sdwa v139, v143 dst_sel:DWORD dst_unused:UNUSED_PAD src0_sel:WORD_1
	v_fma_f32 v143, -v131, v142, 1.0
	v_fmac_f32_e32 v142, v143, v142
	v_div_scale_f32 v143, vcc, 1.0, v137, 1.0
	v_mul_f32_e32 v159, v143, v142
	v_fma_f32 v165, -v131, v159, v143
	v_fmac_f32_e32 v159, v165, v142
	v_fma_f32 v131, -v131, v159, v143
	v_div_fmas_f32 v131, v131, v142, v159
	v_div_fixup_f32 v137, v131, v137, 1.0
	v_div_scale_f32 v131, s[0:1], v136, v136, 1.0
	v_rcp_f32_e32 v142, v131
	v_pk_add_f32 v[138:139], v[138:139], v[132:133] neg_lo:[0,1] neg_hi:[0,1]
	v_fma_f32 v143, -v131, v142, 1.0
	v_fmac_f32_e32 v142, v143, v142
	v_div_scale_f32 v143, vcc, 1.0, v136, 1.0
	v_mul_f32_e32 v159, v143, v142
	v_fma_f32 v165, -v131, v159, v143
	v_fmac_f32_e32 v159, v165, v142
	v_fma_f32 v131, -v131, v159, v143
	v_div_fmas_f32 v131, v131, v142, v159
	v_div_fixup_f32 v136, v131, v136, 1.0
	v_pk_fma_f32 v[132:133], v[136:137], v[138:139], v[132:133]
	v_pk_add_f32 v[138:139], v[172:173], 1.0 op_sel_hi:[1,0]
	v_cvt_pk_f16_f32 v131, v132, v133
	v_cvt_f32_f16_e32 v132, v140
	v_cvt_f32_f16_sdwa v133, v140 dst_sel:DWORD dst_unused:UNUSED_PAD src0_sel:WORD_1
	v_div_scale_f32 v140, s[0:1], v139, v139, 1.0
	v_rcp_f32_e32 v142, v140
	v_cvt_f32_f16_e32 v136, v144
	v_cvt_f32_f16_sdwa v137, v144 dst_sel:DWORD dst_unused:UNUSED_PAD src0_sel:WORD_1
	v_fma_f32 v143, -v140, v142, 1.0
	v_fmac_f32_e32 v142, v143, v142
	v_div_scale_f32 v143, vcc, 1.0, v139, 1.0
	v_mul_f32_e32 v144, v143, v142
	v_fma_f32 v159, -v140, v144, v143
	v_fmac_f32_e32 v144, v159, v142
	v_fma_f32 v140, -v140, v144, v143
	v_div_fmas_f32 v140, v140, v142, v144
	v_div_fixup_f32 v139, v140, v139, 1.0
	v_div_scale_f32 v140, s[0:1], v138, v138, 1.0
	v_rcp_f32_e32 v142, v140
	v_pk_add_f32 v[136:137], v[136:137], v[132:133] neg_lo:[0,1] neg_hi:[0,1]
	v_fma_f32 v143, -v140, v142, 1.0
	v_fmac_f32_e32 v142, v143, v142
	v_div_scale_f32 v143, vcc, 1.0, v138, 1.0
	v_mul_f32_e32 v144, v143, v142
	v_fma_f32 v159, -v140, v144, v143
	v_fmac_f32_e32 v144, v159, v142
	v_fma_f32 v140, -v140, v144, v143
	v_div_fmas_f32 v140, v140, v142, v144
	v_div_fixup_f32 v138, v140, v138, 1.0
	v_pk_fma_f32 v[132:133], v[136:137], v[138:139], v[132:133]
	v_cvt_f32_f16_e32 v136, v141
	v_cvt_pk_f16_f32 v132, v132, v133
	v_div_scale_f32 v133, s[0:1], v135, v135, 1.0
	v_rcp_f32_e32 v140, v133
	v_cvt_f32_f16_sdwa v137, v141 dst_sel:DWORD dst_unused:UNUSED_PAD src0_sel:WORD_1
	v_cvt_f32_f16_e32 v138, v145
; __device__ __forceinline__ float sigmoidf_(float x) { return 1.0f / (1.0f + __expf(-x)); }
;     template <int GI>
;     __device__ __forceinline__ void body(const f32x4 (&acc)[2][2][4][2], int row0, int colt) const {
;     ...
;             for (int ai = 0; ai < 2; ++ai)
; #pragma unroll
;                 for (int m = 0; m < 4; ++m) {
;                     const size_t row = (size_t)(row0 + ai * 128 + m * 16);
;                     f32x4 x0 = acc[ai][bj][m][0] + b0, x1 = acc[ai][bj][m][1] + b1;
;                     if (GI == 0) {
; #pragma unroll
;                         for (int j = 0; j < 4; ++j) {
;                             x0[j] = 0.6065306597126334f * sigmoidf_(x0[j]); x1[j] = 0.6065306597126334f * sigmoidf_(x1[j]); }
;                         *(u32x4*)(DEC + row * DM + c) = pack8(x0, x1);
;                     } else if (GI == 1) {
; #pragma unroll
;                         for (int j = 0; j < 4; ++j) { x0[j] = sigmoidf_(x0[j]); x1[j] = sigmoidf_(x1[j]); }
;                         *(u32x4*)(Ab + row * DM + c) = pack8(x0, x1);
;                     } else if (GI == 2) {
;                         *(u32x4*)(Gb + row * DM + c) = pack8(x0, x1);
;                     } else {
;                         h16* vp = C1 + row * LDC1 + 4096 + c;
;                         const h16x8 vv = *(const h16x8*)vp; const h16x8 vf = *(const h16x8*)(VF + row * DM + c);
;                         f32x4 o0, o1;
; #pragma unroll
;                         for (int j = 0; j < 4; ++j) { float v = (float)vv[j], f = (float)vf[j]; o0[j] = v + (f - v) * sigmoidf_(x0[j]); v = (float)vv[4 + j]; f = (float)vf[4 + j]; o1[j] = v + (f - v) * sigmoidf_(x1[j]); }
;                         *(u32x4*)vp = pack8(o0, o1);
;                     }
;                     __builtin_amdgcn_sched_barrier(0);
	v_cvt_f32_f16_sdwa v139, v145 dst_sel:DWORD dst_unused:UNUSED_PAD src0_sel:WORD_1
	v_fma_f32 v141, -v133, v140, 1.0
	v_fmac_f32_e32 v140, v141, v140
	v_div_scale_f32 v141, vcc, 1.0, v135, 1.0
	v_mul_f32_e32 v142, v141, v140
	v_fma_f32 v143, -v133, v142, v141
	v_fmac_f32_e32 v142, v143, v140
	v_fma_f32 v133, -v133, v142, v141
	v_div_fmas_f32 v133, v133, v140, v142
	v_div_fixup_f32 v135, v133, v135, 1.0
	v_div_scale_f32 v133, s[0:1], v134, v134, 1.0
	v_rcp_f32_e32 v140, v133
	v_pk_add_f32 v[138:139], v[138:139], v[136:137] neg_lo:[0,1] neg_hi:[0,1]
	v_fma_f32 v141, -v133, v140, 1.0
	v_fmac_f32_e32 v140, v141, v140
	v_div_scale_f32 v141, vcc, 1.0, v134, 1.0
	v_mul_f32_e32 v142, v141, v140
	v_fma_f32 v143, -v133, v142, v141
	v_fmac_f32_e32 v142, v143, v140
	v_fma_f32 v133, -v133, v142, v141
	v_div_fmas_f32 v133, v133, v140, v142
	v_div_fixup_f32 v134, v133, v134, 1.0
	v_pk_fma_f32 v[134:135], v[138:139], v[134:135], v[136:137]
	s_nop 0
	v_cvt_pk_f16_f32 v133, v134, v135
	global_store_dwordx4 v[170:171], v[130:133], off
	v_or_b32_e32 v134, 16, v164
	v_ashrrev_i32_e32 v135, 31, v134
	v_mad_i64_i32 v[130:131], s[0:1], v134, s5, v[168:169]
	v_lshl_add_u64 v[138:139], v[130:131], 0, s[90:91]
	v_lshlrev_b64 v[134:135], 12, v[134:135]
	v_lshl_add_u64 v[142:143], v[138:139], 0, v[166:167]
	v_lshl_add_u64 v[134:135], s[2:3], 0, v[134:135]
	global_load_dwordx4 v[130:133], v[142:143], off
	v_lshl_add_u64 v[140:141], v[134:135], 0, v[166:167]
	global_load_dwordx4 v[134:137], v[140:141], off
	v_add_f32_e32 v122, v122, v82
	v_mul_f32_e32 v122, 0xbfb8aa3b, v122
	v_exp_f32_e32 v144, v122
	v_add_f32_e32 v122, v127, v87
	v_mul_f32_e32 v122, 0xbfb8aa3b, v122
	v_exp_f32_e32 v173, v122
	v_add_f32_e32 v122, v123, v83
	v_mul_f32_e32 v122, 0xbfb8aa3b, v122
	v_exp_f32_e32 v145, v122
	v_add_f32_e32 v122, v128, v88
	v_add_f32_e32 v126, v126, v86
	v_mul_f32_e32 v122, 0xbfb8aa3b, v122
	v_mul_f32_e32 v126, 0xbfb8aa3b, v126
	v_exp_f32_e32 v170, v122
	v_add_f32_e32 v122, v124, v84
	v_exp_f32_e32 v172, v126
	v_mul_f32_e32 v122, 0xbfb8aa3b, v122
	v_exp_f32_e32 v126, v122
	v_add_f32_e32 v122, v129, v89
	v_mul_f32_e32 v122, 0xbfb8aa3b, v122
	v_exp_f32_e32 v171, v122
	v_add_f32_e32 v122, v125, v85
	v_mul_f32_e32 v122, 0xbfb8aa3b, v122
	v_pk_add_f32 v[128:129], v[172:173], 1.0 op_sel_hi:[1,0]
	v_exp_f32_e32 v127, v122
	s_waitcnt vmcnt(0)
	v_cvt_f32_f16_e32 v122, v130
	v_cvt_f32_f16_sdwa v123, v130 dst_sel:DWORD dst_unused:UNUSED_PAD src0_sel:WORD_1
	v_div_scale_f32 v130, s[0:1], v129, v129, 1.0
	v_cvt_f32_f16_e32 v124, v134
	v_cvt_f32_f16_sdwa v125, v134 dst_sel:DWORD dst_unused:UNUSED_PAD src0_sel:WORD_1
	v_rcp_f32_e32 v134, v130
	v_pk_add_f32 v[126:127], v[126:127], 1.0 op_sel_hi:[1,0]
	v_pk_add_f32 v[124:125], v[124:125], v[122:123] neg_lo:[0,1] neg_hi:[0,1]
	v_fma_f32 v159, -v130, v134, 1.0
	v_fmac_f32_e32 v134, v159, v134
	v_div_scale_f32 v159, vcc, 1.0, v129, 1.0
	v_mul_f32_e32 v165, v159, v134
	v_fma_f32 v172, -v130, v165, v159
	v_fmac_f32_e32 v165, v172, v134
	v_fma_f32 v130, -v130, v165, v159
	v_div_fmas_f32 v130, v130, v134, v165
	v_div_fixup_f32 v129, v130, v129, 1.0
	v_div_scale_f32 v130, s[0:1], v128, v128, 1.0
	v_rcp_f32_e32 v134, v130
	s_nop 0
	v_fma_f32 v159, -v130, v134, 1.0
	v_fmac_f32_e32 v134, v159, v134
	v_div_scale_f32 v159, vcc, 1.0, v128, 1.0
	v_mul_f32_e32 v165, v159, v134
	v_fma_f32 v172, -v130, v165, v159
	v_fmac_f32_e32 v165, v172, v134
	v_fma_f32 v130, -v130, v165, v159
	v_div_fmas_f32 v130, v130, v134, v165
	v_div_fixup_f32 v128, v130, v128, 1.0
	v_pk_fma_f32 v[122:123], v[128:129], v[124:125], v[122:123]
	v_cvt_f32_f16_e32 v124, v131
	v_cvt_f32_f16_sdwa v125, v131 dst_sel:DWORD dst_unused:UNUSED_PAD src0_sel:WORD_1
	v_pk_add_f32 v[130:131], v[170:171], 1.0 op_sel_hi:[1,0]
	v_cvt_pk_f16_f32 v122, v122, v123
	v_div_scale_f32 v123, s[0:1], v131, v131, 1.0
	v_rcp_f32_e32 v134, v123
	v_cvt_f32_f16_e32 v128, v135
	v_cvt_f32_f16_sdwa v129, v135 dst_sel:DWORD dst_unused:UNUSED_PAD src0_sel:WORD_1
	v_fma_f32 v135, -v123, v134, 1.0
	v_fmac_f32_e32 v134, v135, v134
	v_div_scale_f32 v135, vcc, 1.0, v131, 1.0
	v_mul_f32_e32 v159, v135, v134
	v_fma_f32 v165, -v123, v159, v135
	v_fmac_f32_e32 v159, v165, v134
	v_fma_f32 v123, -v123, v159, v135
	v_div_fmas_f32 v123, v123, v134, v159
	v_div_fixup_f32 v131, v123, v131, 1.0
	v_div_scale_f32 v123, s[0:1], v130, v130, 1.0
	v_rcp_f32_e32 v134, v123
	v_pk_add_f32 v[128:129], v[128:129], v[124:125] neg_lo:[0,1] neg_hi:[0,1]
	v_fma_f32 v135, -v123, v134, 1.0
	v_fmac_f32_e32 v134, v135, v134
	v_div_scale_f32 v135, vcc, 1.0, v130, 1.0
	v_mul_f32_e32 v159, v135, v134
	v_fma_f32 v165, -v123, v159, v135
	v_fmac_f32_e32 v159, v165, v134
	v_fma_f32 v123, -v123, v159, v135
	v_div_fmas_f32 v123, v123, v134, v159
	v_div_fixup_f32 v130, v123, v130, 1.0
	v_pk_fma_f32 v[124:125], v[130:131], v[128:129], v[124:125]
	v_pk_add_f32 v[130:131], v[144:145], 1.0 op_sel_hi:[1,0]
	v_cvt_pk_f16_f32 v123, v124, v125
	v_cvt_f32_f16_e32 v124, v132
	v_cvt_f32_f16_sdwa v125, v132 dst_sel:DWORD dst_unused:UNUSED_PAD src0_sel:WORD_1
	v_div_scale_f32 v132, s[0:1], v131, v131, 1.0
	v_rcp_f32_e32 v134, v132
	v_cvt_f32_f16_e32 v128, v136
	v_cvt_f32_f16_sdwa v129, v136 dst_sel:DWORD dst_unused:UNUSED_PAD src0_sel:WORD_1
	v_fma_f32 v135, -v132, v134, 1.0
	v_fmac_f32_e32 v134, v135, v134
	v_div_scale_f32 v135, vcc, 1.0, v131, 1.0
	v_mul_f32_e32 v136, v135, v134
	v_fma_f32 v144, -v132, v136, v135
	v_fmac_f32_e32 v136, v144, v134
	v_fma_f32 v132, -v132, v136, v135
	v_div_fmas_f32 v132, v132, v134, v136
	v_div_fixup_f32 v131, v132, v131, 1.0
	v_div_scale_f32 v132, s[0:1], v130, v130, 1.0
	v_rcp_f32_e32 v134, v132
	v_pk_add_f32 v[128:129], v[128:129], v[124:125] neg_lo:[0,1] neg_hi:[0,1]
; __device__ __forceinline__ float sigmoidf_(float x) { return 1.0f / (1.0f + __expf(-x)); }
;     template <int GI>
;     __device__ __forceinline__ void body(const f32x4 (&acc)[2][2][4][2], int row0, int colt) const {
;     ...
;             for (int ai = 0; ai < 2; ++ai)
; #pragma unroll
;                 for (int m = 0; m < 4; ++m) {
;                     const size_t row = (size_t)(row0 + ai * 128 + m * 16);
;                     f32x4 x0 = acc[ai][bj][m][0] + b0, x1 = acc[ai][bj][m][1] + b1;
;                     if (GI == 0) {
; #pragma unroll
;                         for (int j = 0; j < 4; ++j) {
;                             x0[j] = 0.6065306597126334f * sigmoidf_(x0[j]); x1[j] = 0.6065306597126334f * sigmoidf_(x1[j]); }
;                         *(u32x4*)(DEC + row * DM + c) = pack8(x0, x1);
;                     } else if (GI == 1) {
; #pragma unroll
;                         for (int j = 0; j < 4; ++j) { x0[j] = sigmoidf_(x0[j]); x1[j] = sigmoidf_(x1[j]); }
;                         *(u32x4*)(Ab + row * DM + c) = pack8(x0, x1);
;                     } else if (GI == 2) {
;                         *(u32x4*)(Gb + row * DM + c) = pack8(x0, x1);
;                     } else {
;                         h16* vp = C1 + row * LDC1 + 4096 + c;
;                         const h16x8 vv = *(const h16x8*)vp; const h16x8 vf = *(const h16x8*)(VF + row * DM + c);
;                         f32x4 o0, o1;
; #pragma unroll
;                         for (int j = 0; j < 4; ++j) { float v = (float)vv[j], f = (float)vf[j]; o0[j] = v + (f - v) * sigmoidf_(x0[j]); v = (float)vv[4 + j]; f = (float)vf[4 + j]; o1[j] = v + (f - v) * sigmoidf_(x1[j]); }
;                         *(u32x4*)vp = pack8(o0, o1);
;                     }
;                     __builtin_amdgcn_sched_barrier(0);
	v_fma_f32 v135, -v132, v134, 1.0
	v_fmac_f32_e32 v134, v135, v134
	v_div_scale_f32 v135, vcc, 1.0, v130, 1.0
	v_mul_f32_e32 v136, v135, v134
	v_fma_f32 v144, -v132, v136, v135
	v_fmac_f32_e32 v136, v144, v134
	v_fma_f32 v132, -v132, v136, v135
	v_div_fmas_f32 v132, v132, v134, v136
	v_div_fixup_f32 v130, v132, v130, 1.0
	v_pk_fma_f32 v[124:125], v[130:131], v[128:129], v[124:125]
	v_cvt_f32_f16_e32 v128, v133
	v_cvt_pk_f16_f32 v124, v124, v125
	v_div_scale_f32 v125, s[0:1], v127, v127, 1.0
	v_rcp_f32_e32 v132, v125
	v_cvt_f32_f16_sdwa v129, v133 dst_sel:DWORD dst_unused:UNUSED_PAD src0_sel:WORD_1
	v_cvt_f32_f16_e32 v130, v137
	v_cvt_f32_f16_sdwa v131, v137 dst_sel:DWORD dst_unused:UNUSED_PAD src0_sel:WORD_1
	v_fma_f32 v133, -v125, v132, 1.0
	v_fmac_f32_e32 v132, v133, v132
	v_div_scale_f32 v133, vcc, 1.0, v127, 1.0
	v_mul_f32_e32 v134, v133, v132
	v_fma_f32 v135, -v125, v134, v133
	v_fmac_f32_e32 v134, v135, v132
	v_fma_f32 v125, -v125, v134, v133
	v_div_fmas_f32 v125, v125, v132, v134
	v_div_fixup_f32 v127, v125, v127, 1.0
	v_div_scale_f32 v125, s[0:1], v126, v126, 1.0
	v_rcp_f32_e32 v132, v125
	v_pk_add_f32 v[130:131], v[130:131], v[128:129] neg_lo:[0,1] neg_hi:[0,1]
	v_fma_f32 v133, -v125, v132, 1.0
	v_fmac_f32_e32 v132, v133, v132
	v_div_scale_f32 v133, vcc, 1.0, v126, 1.0
	v_mul_f32_e32 v134, v133, v132
	v_fma_f32 v135, -v125, v134, v133
	v_fmac_f32_e32 v134, v135, v132
	v_fma_f32 v125, -v125, v134, v133
	v_div_fmas_f32 v125, v125, v132, v134
	v_div_fixup_f32 v126, v125, v126, 1.0
	v_pk_fma_f32 v[126:127], v[126:127], v[130:131], v[128:129]
	s_nop 0
	v_cvt_pk_f16_f32 v125, v126, v127
	global_store_dwordx4 v[142:143], v[122:125], off
	v_or_b32_e32 v126, 32, v164
	v_ashrrev_i32_e32 v127, 31, v126
	v_mad_i64_i32 v[122:123], s[0:1], v126, s5, v[168:169]
	v_lshl_add_u64 v[130:131], v[122:123], 0, s[90:91]
	v_lshlrev_b64 v[126:127], 12, v[126:127]
	v_lshl_add_u64 v[134:135], v[130:131], 0, v[166:167]
	v_lshl_add_u64 v[126:127], s[2:3], 0, v[126:127]
	global_load_dwordx4 v[122:125], v[134:135], off
	v_lshl_add_u64 v[132:133], v[126:127], 0, v[166:167]
	global_load_dwordx4 v[126:129], v[132:133], off
	v_add_f32_e32 v114, v114, v82
	v_mul_f32_e32 v114, 0xbfb8aa3b, v114
	v_exp_f32_e32 v136, v114
	v_add_f32_e32 v114, v119, v87
	v_mul_f32_e32 v114, 0xbfb8aa3b, v114
	v_exp_f32_e32 v145, v114
	v_add_f32_e32 v114, v115, v83
	v_mul_f32_e32 v114, 0xbfb8aa3b, v114
	v_exp_f32_e32 v137, v114
	v_add_f32_e32 v114, v120, v88
	v_add_f32_e32 v118, v118, v86
	v_mul_f32_e32 v114, 0xbfb8aa3b, v114
	v_mul_f32_e32 v118, 0xbfb8aa3b, v118
	v_exp_f32_e32 v142, v114
	v_add_f32_e32 v114, v116, v84
	v_exp_f32_e32 v144, v118
	v_mul_f32_e32 v114, 0xbfb8aa3b, v114
	v_exp_f32_e32 v118, v114
	v_add_f32_e32 v114, v121, v89
	v_mul_f32_e32 v114, 0xbfb8aa3b, v114
	v_exp_f32_e32 v143, v114
	v_add_f32_e32 v114, v117, v85
	v_mul_f32_e32 v114, 0xbfb8aa3b, v114
	v_pk_add_f32 v[120:121], v[144:145], 1.0 op_sel_hi:[1,0]
	v_exp_f32_e32 v119, v114
	s_waitcnt vmcnt(0)
	v_cvt_f32_f16_e32 v114, v122
	v_cvt_f32_f16_sdwa v115, v122 dst_sel:DWORD dst_unused:UNUSED_PAD src0_sel:WORD_1
	v_div_scale_f32 v122, s[0:1], v121, v121, 1.0
	v_cvt_f32_f16_e32 v116, v126
	v_cvt_f32_f16_sdwa v117, v126 dst_sel:DWORD dst_unused:UNUSED_PAD src0_sel:WORD_1
	v_rcp_f32_e32 v126, v122
	v_pk_add_f32 v[118:119], v[118:119], 1.0 op_sel_hi:[1,0]
	v_pk_add_f32 v[116:117], v[116:117], v[114:115] neg_lo:[0,1] neg_hi:[0,1]
	v_fma_f32 v144, -v122, v126, 1.0
	v_fmac_f32_e32 v126, v144, v126
	v_div_scale_f32 v144, vcc, 1.0, v121, 1.0
	v_mul_f32_e32 v145, v144, v126
	v_fma_f32 v159, -v122, v145, v144
	v_fmac_f32_e32 v145, v159, v126
	v_fma_f32 v122, -v122, v145, v144
	v_div_fmas_f32 v122, v122, v126, v145
	v_div_fixup_f32 v121, v122, v121, 1.0
	v_div_scale_f32 v122, s[0:1], v120, v120, 1.0
	v_rcp_f32_e32 v126, v122
	s_nop 0
	v_fma_f32 v144, -v122, v126, 1.0
	v_fmac_f32_e32 v126, v144, v126
	v_div_scale_f32 v144, vcc, 1.0, v120, 1.0
	v_mul_f32_e32 v145, v144, v126
	v_fma_f32 v159, -v122, v145, v144
	v_fmac_f32_e32 v145, v159, v126
	v_fma_f32 v122, -v122, v145, v144
	v_div_fmas_f32 v122, v122, v126, v145
	v_div_fixup_f32 v120, v122, v120, 1.0
	v_pk_fma_f32 v[114:115], v[120:121], v[116:117], v[114:115]
	v_cvt_f32_f16_e32 v116, v123
	v_cvt_f32_f16_sdwa v117, v123 dst_sel:DWORD dst_unused:UNUSED_PAD src0_sel:WORD_1
	v_pk_add_f32 v[122:123], v[142:143], 1.0 op_sel_hi:[1,0]
	v_cvt_pk_f16_f32 v114, v114, v115
	v_div_scale_f32 v115, s[0:1], v123, v123, 1.0
	v_rcp_f32_e32 v126, v115
	v_cvt_f32_f16_e32 v120, v127
	v_cvt_f32_f16_sdwa v121, v127 dst_sel:DWORD dst_unused:UNUSED_PAD src0_sel:WORD_1
	v_fma_f32 v127, -v115, v126, 1.0
	v_fmac_f32_e32 v126, v127, v126
	v_div_scale_f32 v127, vcc, 1.0, v123, 1.0
	v_mul_f32_e32 v142, v127, v126
	v_fma_f32 v143, -v115, v142, v127
	v_fmac_f32_e32 v142, v143, v126
	v_fma_f32 v115, -v115, v142, v127
	v_div_fmas_f32 v115, v115, v126, v142
	v_div_fixup_f32 v123, v115, v123, 1.0
	v_div_scale_f32 v115, s[0:1], v122, v122, 1.0
	v_rcp_f32_e32 v126, v115
	v_pk_add_f32 v[120:121], v[120:121], v[116:117] neg_lo:[0,1] neg_hi:[0,1]
	v_fma_f32 v127, -v115, v126, 1.0
	v_fmac_f32_e32 v126, v127, v126
	v_div_scale_f32 v127, vcc, 1.0, v122, 1.0
	v_mul_f32_e32 v142, v127, v126
	v_fma_f32 v143, -v115, v142, v127
	v_fmac_f32_e32 v142, v143, v126
	v_fma_f32 v115, -v115, v142, v127
	v_div_fmas_f32 v115, v115, v126, v142
	v_div_fixup_f32 v122, v115, v122, 1.0
	v_pk_fma_f32 v[116:117], v[122:123], v[120:121], v[116:117]
	v_pk_add_f32 v[122:123], v[136:137], 1.0 op_sel_hi:[1,0]
	v_cvt_pk_f16_f32 v115, v116, v117
	v_cvt_f32_f16_e32 v116, v124
	v_cvt_f32_f16_sdwa v117, v124 dst_sel:DWORD dst_unused:UNUSED_PAD src0_sel:WORD_1
; __device__ __forceinline__ float sigmoidf_(float x) { return 1.0f / (1.0f + __expf(-x)); }
;     template <int GI>
;     __device__ __forceinline__ void body(const f32x4 (&acc)[2][2][4][2], int row0, int colt) const {
;     ...
;             for (int ai = 0; ai < 2; ++ai)
; #pragma unroll
;                 for (int m = 0; m < 4; ++m) {
;                     const size_t row = (size_t)(row0 + ai * 128 + m * 16);
;                     f32x4 x0 = acc[ai][bj][m][0] + b0, x1 = acc[ai][bj][m][1] + b1;
;                     if (GI == 0) {
; #pragma unroll
;                         for (int j = 0; j < 4; ++j) {
;                             x0[j] = 0.6065306597126334f * sigmoidf_(x0[j]); x1[j] = 0.6065306597126334f * sigmoidf_(x1[j]); }
;                         *(u32x4*)(DEC + row * DM + c) = pack8(x0, x1);
;                     } else if (GI == 1) {
; #pragma unroll
;                         for (int j = 0; j < 4; ++j) { x0[j] = sigmoidf_(x0[j]); x1[j] = sigmoidf_(x1[j]); }
;                         *(u32x4*)(Ab + row * DM + c) = pack8(x0, x1);
;                     } else if (GI == 2) {
;                         *(u32x4*)(Gb + row * DM + c) = pack8(x0, x1);
;                     } else {
;                         h16* vp = C1 + row * LDC1 + 4096 + c;
;                         const h16x8 vv = *(const h16x8*)vp; const h16x8 vf = *(const h16x8*)(VF + row * DM + c);
;                         f32x4 o0, o1;
; #pragma unroll
;                         for (int j = 0; j < 4; ++j) { float v = (float)vv[j], f = (float)vf[j]; o0[j] = v + (f - v) * sigmoidf_(x0[j]); v = (float)vv[4 + j]; f = (float)vf[4 + j]; o1[j] = v + (f - v) * sigmoidf_(x1[j]); }
;                         *(u32x4*)vp = pack8(o0, o1);
;                     }
;                     __builtin_amdgcn_sched_barrier(0);
	v_div_scale_f32 v124, s[0:1], v123, v123, 1.0
	v_rcp_f32_e32 v126, v124
	v_cvt_f32_f16_e32 v120, v128
	v_cvt_f32_f16_sdwa v121, v128 dst_sel:DWORD dst_unused:UNUSED_PAD src0_sel:WORD_1
	v_fma_f32 v127, -v124, v126, 1.0
	v_fmac_f32_e32 v126, v127, v126
	v_div_scale_f32 v127, vcc, 1.0, v123, 1.0
	v_mul_f32_e32 v128, v127, v126
	v_fma_f32 v136, -v124, v128, v127
	v_fmac_f32_e32 v128, v136, v126
	v_fma_f32 v124, -v124, v128, v127
	v_div_fmas_f32 v124, v124, v126, v128
	v_div_fixup_f32 v123, v124, v123, 1.0
	v_div_scale_f32 v124, s[0:1], v122, v122, 1.0
	v_rcp_f32_e32 v126, v124
	v_pk_add_f32 v[120:121], v[120:121], v[116:117] neg_lo:[0,1] neg_hi:[0,1]
	v_fma_f32 v127, -v124, v126, 1.0
	v_fmac_f32_e32 v126, v127, v126
	v_div_scale_f32 v127, vcc, 1.0, v122, 1.0
	v_mul_f32_e32 v128, v127, v126
	v_fma_f32 v136, -v124, v128, v127
	v_fmac_f32_e32 v128, v136, v126
	v_fma_f32 v124, -v124, v128, v127
	v_div_fmas_f32 v124, v124, v126, v128
	v_div_fixup_f32 v122, v124, v122, 1.0
	v_pk_fma_f32 v[116:117], v[122:123], v[120:121], v[116:117]
	v_cvt_f32_f16_e32 v120, v125
	v_cvt_pk_f16_f32 v116, v116, v117
	v_div_scale_f32 v117, s[0:1], v119, v119, 1.0
	v_rcp_f32_e32 v124, v117
	v_cvt_f32_f16_sdwa v121, v125 dst_sel:DWORD dst_unused:UNUSED_PAD src0_sel:WORD_1
	v_cvt_f32_f16_e32 v122, v129
	v_cvt_f32_f16_sdwa v123, v129 dst_sel:DWORD dst_unused:UNUSED_PAD src0_sel:WORD_1
	v_fma_f32 v125, -v117, v124, 1.0
	v_fmac_f32_e32 v124, v125, v124
	v_div_scale_f32 v125, vcc, 1.0, v119, 1.0
	v_mul_f32_e32 v126, v125, v124
	v_fma_f32 v127, -v117, v126, v125
	v_fmac_f32_e32 v126, v127, v124
	v_fma_f32 v117, -v117, v126, v125
	v_div_fmas_f32 v117, v117, v124, v126
	v_div_fixup_f32 v119, v117, v119, 1.0
	v_div_scale_f32 v117, s[0:1], v118, v118, 1.0
	v_rcp_f32_e32 v124, v117
	v_pk_add_f32 v[122:123], v[122:123], v[120:121] neg_lo:[0,1] neg_hi:[0,1]
	v_fma_f32 v125, -v117, v124, 1.0
	v_fmac_f32_e32 v124, v125, v124
	v_div_scale_f32 v125, vcc, 1.0, v118, 1.0
	v_mul_f32_e32 v126, v125, v124
	v_fma_f32 v127, -v117, v126, v125
	v_fmac_f32_e32 v126, v127, v124
	v_fma_f32 v117, -v117, v126, v125
	v_div_fmas_f32 v117, v117, v124, v126
	v_div_fixup_f32 v118, v117, v118, 1.0
	v_pk_fma_f32 v[118:119], v[118:119], v[122:123], v[120:121]
	s_nop 0
	v_cvt_pk_f16_f32 v117, v118, v119
	global_store_dwordx4 v[134:135], v[114:117], off
	v_or_b32_e32 v118, 48, v164
	v_ashrrev_i32_e32 v119, 31, v118
	v_mad_i64_i32 v[114:115], s[0:1], v118, s5, v[168:169]
	v_lshl_add_u64 v[122:123], v[114:115], 0, s[90:91]
	v_lshlrev_b64 v[118:119], 12, v[118:119]
	v_lshl_add_u64 v[126:127], v[122:123], 0, v[166:167]
	v_lshl_add_u64 v[118:119], s[2:3], 0, v[118:119]
	global_load_dwordx4 v[114:117], v[126:127], off
	v_lshl_add_u64 v[124:125], v[118:119], 0, v[166:167]
	global_load_dwordx4 v[118:121], v[124:125], off
	v_add_f32_e32 v106, v106, v82
	v_mul_f32_e32 v106, 0xbfb8aa3b, v106
	v_exp_f32_e32 v128, v106
	v_add_f32_e32 v106, v111, v87
	v_mul_f32_e32 v106, 0xbfb8aa3b, v106
	v_exp_f32_e32 v137, v106
	v_add_f32_e32 v106, v107, v83
	v_mul_f32_e32 v106, 0xbfb8aa3b, v106
	v_exp_f32_e32 v129, v106
	v_add_f32_e32 v106, v112, v88
	v_add_f32_e32 v110, v110, v86
	v_mul_f32_e32 v106, 0xbfb8aa3b, v106
	v_mul_f32_e32 v110, 0xbfb8aa3b, v110
	v_exp_f32_e32 v134, v106
	v_add_f32_e32 v106, v108, v84
	v_exp_f32_e32 v136, v110
	v_mul_f32_e32 v106, 0xbfb8aa3b, v106
	v_exp_f32_e32 v110, v106
	v_add_f32_e32 v106, v113, v89
	v_mul_f32_e32 v106, 0xbfb8aa3b, v106
	v_exp_f32_e32 v135, v106
	v_add_f32_e32 v106, v109, v85
	v_mul_f32_e32 v106, 0xbfb8aa3b, v106
	v_pk_add_f32 v[112:113], v[136:137], 1.0 op_sel_hi:[1,0]
	v_exp_f32_e32 v111, v106
	s_waitcnt vmcnt(0)
	v_cvt_f32_f16_e32 v106, v114
	v_cvt_f32_f16_sdwa v107, v114 dst_sel:DWORD dst_unused:UNUSED_PAD src0_sel:WORD_1
	v_div_scale_f32 v114, s[0:1], v113, v113, 1.0
	v_cvt_f32_f16_e32 v108, v118
	v_cvt_f32_f16_sdwa v109, v118 dst_sel:DWORD dst_unused:UNUSED_PAD src0_sel:WORD_1
	v_rcp_f32_e32 v118, v114
	v_pk_add_f32 v[110:111], v[110:111], 1.0 op_sel_hi:[1,0]
	v_pk_add_f32 v[108:109], v[108:109], v[106:107] neg_lo:[0,1] neg_hi:[0,1]
	v_fma_f32 v136, -v114, v118, 1.0
	v_fmac_f32_e32 v118, v136, v118
	v_div_scale_f32 v136, vcc, 1.0, v113, 1.0
	v_mul_f32_e32 v137, v136, v118
	v_fma_f32 v142, -v114, v137, v136
	v_fmac_f32_e32 v137, v142, v118
	v_fma_f32 v114, -v114, v137, v136
	v_div_fmas_f32 v114, v114, v118, v137
	v_div_fixup_f32 v113, v114, v113, 1.0
	v_div_scale_f32 v114, s[0:1], v112, v112, 1.0
	v_rcp_f32_e32 v118, v114
	s_nop 0
	v_fma_f32 v136, -v114, v118, 1.0
	v_fmac_f32_e32 v118, v136, v118
	v_div_scale_f32 v136, vcc, 1.0, v112, 1.0
	v_mul_f32_e32 v137, v136, v118
	v_fma_f32 v142, -v114, v137, v136
	v_fmac_f32_e32 v137, v142, v118
	v_fma_f32 v114, -v114, v137, v136
	v_div_fmas_f32 v114, v114, v118, v137
	v_div_fixup_f32 v112, v114, v112, 1.0
	v_pk_fma_f32 v[106:107], v[112:113], v[108:109], v[106:107]
	v_cvt_f32_f16_e32 v108, v115
	v_cvt_f32_f16_sdwa v109, v115 dst_sel:DWORD dst_unused:UNUSED_PAD src0_sel:WORD_1
	v_pk_add_f32 v[114:115], v[134:135], 1.0 op_sel_hi:[1,0]
	v_cvt_pk_f16_f32 v106, v106, v107
	v_div_scale_f32 v107, s[0:1], v115, v115, 1.0
	v_rcp_f32_e32 v118, v107
	v_cvt_f32_f16_e32 v112, v119
	v_cvt_f32_f16_sdwa v113, v119 dst_sel:DWORD dst_unused:UNUSED_PAD src0_sel:WORD_1
	v_fma_f32 v119, -v107, v118, 1.0
	v_fmac_f32_e32 v118, v119, v118
	v_div_scale_f32 v119, vcc, 1.0, v115, 1.0
	v_mul_f32_e32 v134, v119, v118
	v_fma_f32 v135, -v107, v134, v119
	v_fmac_f32_e32 v134, v135, v118
	v_fma_f32 v107, -v107, v134, v119
	v_div_fmas_f32 v107, v107, v118, v134
	v_div_fixup_f32 v115, v107, v115, 1.0
	v_div_scale_f32 v107, s[0:1], v114, v114, 1.0
	v_rcp_f32_e32 v118, v107
; __device__ __forceinline__ float sigmoidf_(float x) { return 1.0f / (1.0f + __expf(-x)); }
;     template <int GI>
;     __device__ __forceinline__ void body(const f32x4 (&acc)[2][2][4][2], int row0, int colt) const {
;     ...
;             for (int ai = 0; ai < 2; ++ai)
; #pragma unroll
;                 for (int m = 0; m < 4; ++m) {
;                     const size_t row = (size_t)(row0 + ai * 128 + m * 16);
;                     f32x4 x0 = acc[ai][bj][m][0] + b0, x1 = acc[ai][bj][m][1] + b1;
;                     if (GI == 0) {
; #pragma unroll
;                         for (int j = 0; j < 4; ++j) {
;                             x0[j] = 0.6065306597126334f * sigmoidf_(x0[j]); x1[j] = 0.6065306597126334f * sigmoidf_(x1[j]); }
;                         *(u32x4*)(DEC + row * DM + c) = pack8(x0, x1);
;                     } else if (GI == 1) {
; #pragma unroll
;                         for (int j = 0; j < 4; ++j) { x0[j] = sigmoidf_(x0[j]); x1[j] = sigmoidf_(x1[j]); }
;                         *(u32x4*)(Ab + row * DM + c) = pack8(x0, x1);
;                     } else if (GI == 2) {
;                         *(u32x4*)(Gb + row * DM + c) = pack8(x0, x1);
;                     } else {
;                         h16* vp = C1 + row * LDC1 + 4096 + c;
;                         const h16x8 vv = *(const h16x8*)vp; const h16x8 vf = *(const h16x8*)(VF + row * DM + c);
;                         f32x4 o0, o1;
; #pragma unroll
;                         for (int j = 0; j < 4; ++j) { float v = (float)vv[j], f = (float)vf[j]; o0[j] = v + (f - v) * sigmoidf_(x0[j]); v = (float)vv[4 + j]; f = (float)vf[4 + j]; o1[j] = v + (f - v) * sigmoidf_(x1[j]); }
;                         *(u32x4*)vp = pack8(o0, o1);
;                     }
;                     __builtin_amdgcn_sched_barrier(0);
	v_pk_add_f32 v[112:113], v[112:113], v[108:109] neg_lo:[0,1] neg_hi:[0,1]
	v_fma_f32 v119, -v107, v118, 1.0
	v_fmac_f32_e32 v118, v119, v118
	v_div_scale_f32 v119, vcc, 1.0, v114, 1.0
	v_mul_f32_e32 v134, v119, v118
	v_fma_f32 v135, -v107, v134, v119
	v_fmac_f32_e32 v134, v135, v118
	v_fma_f32 v107, -v107, v134, v119
	v_div_fmas_f32 v107, v107, v118, v134
	v_div_fixup_f32 v114, v107, v114, 1.0
	v_pk_fma_f32 v[108:109], v[114:115], v[112:113], v[108:109]
	v_pk_add_f32 v[114:115], v[128:129], 1.0 op_sel_hi:[1,0]
	v_cvt_pk_f16_f32 v107, v108, v109
	v_cvt_f32_f16_e32 v108, v116
	v_cvt_f32_f16_sdwa v109, v116 dst_sel:DWORD dst_unused:UNUSED_PAD src0_sel:WORD_1
	v_div_scale_f32 v116, s[0:1], v115, v115, 1.0
	v_rcp_f32_e32 v118, v116
	v_cvt_f32_f16_e32 v112, v120
	v_cvt_f32_f16_sdwa v113, v120 dst_sel:DWORD dst_unused:UNUSED_PAD src0_sel:WORD_1
	v_fma_f32 v119, -v116, v118, 1.0
	v_fmac_f32_e32 v118, v119, v118
	v_div_scale_f32 v119, vcc, 1.0, v115, 1.0
	v_mul_f32_e32 v120, v119, v118
	v_fma_f32 v128, -v116, v120, v119
	v_fmac_f32_e32 v120, v128, v118
	v_fma_f32 v116, -v116, v120, v119
	v_div_fmas_f32 v116, v116, v118, v120
	v_div_fixup_f32 v115, v116, v115, 1.0
	v_div_scale_f32 v116, s[0:1], v114, v114, 1.0
	v_rcp_f32_e32 v118, v116
	v_pk_add_f32 v[112:113], v[112:113], v[108:109] neg_lo:[0,1] neg_hi:[0,1]
	v_fma_f32 v119, -v116, v118, 1.0
	v_fmac_f32_e32 v118, v119, v118
	v_div_scale_f32 v119, vcc, 1.0, v114, 1.0
	v_mul_f32_e32 v120, v119, v118
	v_fma_f32 v128, -v116, v120, v119
	v_fmac_f32_e32 v120, v128, v118
	v_fma_f32 v116, -v116, v120, v119
	v_div_fmas_f32 v116, v116, v118, v120
	v_div_fixup_f32 v114, v116, v114, 1.0
	v_pk_fma_f32 v[108:109], v[114:115], v[112:113], v[108:109]
	v_cvt_f32_f16_e32 v112, v117
	v_cvt_pk_f16_f32 v108, v108, v109
	v_div_scale_f32 v109, s[0:1], v111, v111, 1.0
	v_rcp_f32_e32 v116, v109
	v_cvt_f32_f16_sdwa v113, v117 dst_sel:DWORD dst_unused:UNUSED_PAD src0_sel:WORD_1
	v_cvt_f32_f16_e32 v114, v121
	v_cvt_f32_f16_sdwa v115, v121 dst_sel:DWORD dst_unused:UNUSED_PAD src0_sel:WORD_1
	v_fma_f32 v117, -v109, v116, 1.0
	v_fmac_f32_e32 v116, v117, v116
	v_div_scale_f32 v117, vcc, 1.0, v111, 1.0
	v_mul_f32_e32 v118, v117, v116
	v_fma_f32 v119, -v109, v118, v117
	v_fmac_f32_e32 v118, v119, v116
	v_fma_f32 v109, -v109, v118, v117
	v_div_fmas_f32 v109, v109, v116, v118
	v_div_fixup_f32 v111, v109, v111, 1.0
	v_div_scale_f32 v109, s[0:1], v110, v110, 1.0
	v_rcp_f32_e32 v116, v109
	v_pk_add_f32 v[114:115], v[114:115], v[112:113] neg_lo:[0,1] neg_hi:[0,1]
	v_fma_f32 v117, -v109, v116, 1.0
	v_fmac_f32_e32 v116, v117, v116
	v_div_scale_f32 v117, vcc, 1.0, v110, 1.0
	v_mul_f32_e32 v118, v117, v116
	v_fma_f32 v119, -v109, v118, v117
	v_fmac_f32_e32 v118, v119, v116
	v_fma_f32 v109, -v109, v118, v117
	v_div_fmas_f32 v109, v109, v116, v118
	v_div_fixup_f32 v110, v109, v110, 1.0
	v_pk_fma_f32 v[110:111], v[110:111], v[114:115], v[112:113]
	s_nop 0
	v_cvt_pk_f16_f32 v109, v110, v111
	global_store_dwordx4 v[126:127], v[106:109], off
	v_add_u32_e32 v110, 0x80, v164
	v_ashrrev_i32_e32 v111, 31, v110
	v_mad_i64_i32 v[106:107], s[0:1], v110, s5, v[168:169]
	v_lshl_add_u64 v[114:115], v[106:107], 0, s[90:91]
	v_lshlrev_b64 v[110:111], 12, v[110:111]
	v_lshl_add_u64 v[118:119], v[114:115], 0, v[166:167]
	v_lshl_add_u64 v[110:111], s[2:3], 0, v[110:111]
	global_load_dwordx4 v[106:109], v[118:119], off
	v_lshl_add_u64 v[116:117], v[110:111], 0, v[166:167]
	global_load_dwordx4 v[110:113], v[116:117], off
	v_add_f32_e32 v98, v98, v82
	v_mul_f32_e32 v98, 0xbfb8aa3b, v98
	v_exp_f32_e32 v120, v98
	v_add_f32_e32 v98, v103, v87
	v_mul_f32_e32 v98, 0xbfb8aa3b, v98
	v_exp_f32_e32 v129, v98
	v_add_f32_e32 v98, v99, v83
	v_mul_f32_e32 v98, 0xbfb8aa3b, v98
	v_exp_f32_e32 v121, v98
	v_add_f32_e32 v98, v104, v88
	v_add_f32_e32 v102, v102, v86
	v_mul_f32_e32 v98, 0xbfb8aa3b, v98
	v_mul_f32_e32 v102, 0xbfb8aa3b, v102
	v_exp_f32_e32 v126, v98
	v_add_f32_e32 v98, v100, v84
	v_exp_f32_e32 v128, v102
	v_mul_f32_e32 v98, 0xbfb8aa3b, v98
	v_exp_f32_e32 v102, v98
	v_add_f32_e32 v98, v105, v89
	v_mul_f32_e32 v98, 0xbfb8aa3b, v98
	v_exp_f32_e32 v127, v98
	v_add_f32_e32 v98, v101, v85
	v_mul_f32_e32 v98, 0xbfb8aa3b, v98
	v_pk_add_f32 v[104:105], v[128:129], 1.0 op_sel_hi:[1,0]
	v_exp_f32_e32 v103, v98
	s_waitcnt vmcnt(0)
; __device__ __forceinline__ float sigmoidf_(float x) { return 1.0f / (1.0f + __expf(-x)); }
;     template <int GI>
;     __device__ __forceinline__ void body(const f32x4 (&acc)[2][2][4][2], int row0, int colt) const {
;     ...
;             for (int ai = 0; ai < 2; ++ai)
; #pragma unroll
;                 for (int m = 0; m < 4; ++m) {
;                     const size_t row = (size_t)(row0 + ai * 128 + m * 16);
;                     f32x4 x0 = acc[ai][bj][m][0] + b0, x1 = acc[ai][bj][m][1] + b1;
;                     if (GI == 0) {
; #pragma unroll
;                         for (int j = 0; j < 4; ++j) {
;                             x0[j] = 0.6065306597126334f * sigmoidf_(x0[j]); x1[j] = 0.6065306597126334f * sigmoidf_(x1[j]); }
;                         *(u32x4*)(DEC + row * DM + c) = pack8(x0, x1);
;                     } else if (GI == 1) {
; #pragma unroll
;                         for (int j = 0; j < 4; ++j) { x0[j] = sigmoidf_(x0[j]); x1[j] = sigmoidf_(x1[j]); }
;                         *(u32x4*)(Ab + row * DM + c) = pack8(x0, x1);
;                     } else if (GI == 2) {
;                         *(u32x4*)(Gb + row * DM + c) = pack8(x0, x1);
;                     } else {
;                         h16* vp = C1 + row * LDC1 + 4096 + c;
;                         const h16x8 vv = *(const h16x8*)vp; const h16x8 vf = *(const h16x8*)(VF + row * DM + c);
;                         f32x4 o0, o1;
; #pragma unroll
;                         for (int j = 0; j < 4; ++j) { float v = (float)vv[j], f = (float)vf[j]; o0[j] = v + (f - v) * sigmoidf_(x0[j]); v = (float)vv[4 + j]; f = (float)vf[4 + j]; o1[j] = v + (f - v) * sigmoidf_(x1[j]); }
;                         *(u32x4*)vp = pack8(o0, o1);
;                     }
;                     __builtin_amdgcn_sched_barrier(0);
	v_cvt_f32_f16_e32 v98, v106
	v_cvt_f32_f16_sdwa v99, v106 dst_sel:DWORD dst_unused:UNUSED_PAD src0_sel:WORD_1
	v_div_scale_f32 v106, s[0:1], v105, v105, 1.0
	v_cvt_f32_f16_e32 v100, v110
	v_cvt_f32_f16_sdwa v101, v110 dst_sel:DWORD dst_unused:UNUSED_PAD src0_sel:WORD_1
	v_rcp_f32_e32 v110, v106
	v_pk_add_f32 v[102:103], v[102:103], 1.0 op_sel_hi:[1,0]
	v_pk_add_f32 v[100:101], v[100:101], v[98:99] neg_lo:[0,1] neg_hi:[0,1]
	v_fma_f32 v128, -v106, v110, 1.0
	v_fmac_f32_e32 v110, v128, v110
	v_div_scale_f32 v128, vcc, 1.0, v105, 1.0
	v_mul_f32_e32 v129, v128, v110
	v_fma_f32 v134, -v106, v129, v128
	v_fmac_f32_e32 v129, v134, v110
	v_fma_f32 v106, -v106, v129, v128
	v_div_fmas_f32 v106, v106, v110, v129
	v_div_fixup_f32 v105, v106, v105, 1.0
	v_div_scale_f32 v106, s[0:1], v104, v104, 1.0
	v_rcp_f32_e32 v110, v106
	s_nop 0
	v_fma_f32 v128, -v106, v110, 1.0
	v_fmac_f32_e32 v110, v128, v110
	v_div_scale_f32 v128, vcc, 1.0, v104, 1.0
	v_mul_f32_e32 v129, v128, v110
	v_fma_f32 v134, -v106, v129, v128
	v_fmac_f32_e32 v129, v134, v110
	v_fma_f32 v106, -v106, v129, v128
	v_div_fmas_f32 v106, v106, v110, v129
	v_div_fixup_f32 v104, v106, v104, 1.0
	v_pk_fma_f32 v[98:99], v[104:105], v[100:101], v[98:99]
	v_cvt_f32_f16_e32 v100, v107
	v_cvt_f32_f16_sdwa v101, v107 dst_sel:DWORD dst_unused:UNUSED_PAD src0_sel:WORD_1
	v_pk_add_f32 v[106:107], v[126:127], 1.0 op_sel_hi:[1,0]
	v_cvt_pk_f16_f32 v98, v98, v99
	v_div_scale_f32 v99, s[0:1], v107, v107, 1.0
	v_rcp_f32_e32 v110, v99
	v_cvt_f32_f16_e32 v104, v111
	v_cvt_f32_f16_sdwa v105, v111 dst_sel:DWORD dst_unused:UNUSED_PAD src0_sel:WORD_1
	v_fma_f32 v111, -v99, v110, 1.0
	v_fmac_f32_e32 v110, v111, v110
	v_div_scale_f32 v111, vcc, 1.0, v107, 1.0
	v_mul_f32_e32 v126, v111, v110
	v_fma_f32 v127, -v99, v126, v111
	v_fmac_f32_e32 v126, v127, v110
	v_fma_f32 v99, -v99, v126, v111
	v_div_fmas_f32 v99, v99, v110, v126
	v_div_fixup_f32 v107, v99, v107, 1.0
	v_div_scale_f32 v99, s[0:1], v106, v106, 1.0
	v_rcp_f32_e32 v110, v99
	v_pk_add_f32 v[104:105], v[104:105], v[100:101] neg_lo:[0,1] neg_hi:[0,1]
	v_fma_f32 v111, -v99, v110, 1.0
	v_fmac_f32_e32 v110, v111, v110
	v_div_scale_f32 v111, vcc, 1.0, v106, 1.0
	v_mul_f32_e32 v126, v111, v110
	v_fma_f32 v127, -v99, v126, v111
	v_fmac_f32_e32 v126, v127, v110
	v_fma_f32 v99, -v99, v126, v111
	v_div_fmas_f32 v99, v99, v110, v126
	v_div_fixup_f32 v106, v99, v106, 1.0
	v_pk_fma_f32 v[100:101], v[106:107], v[104:105], v[100:101]
	v_pk_add_f32 v[106:107], v[120:121], 1.0 op_sel_hi:[1,0]
	v_cvt_pk_f16_f32 v99, v100, v101
	v_cvt_f32_f16_e32 v100, v108
	v_cvt_f32_f16_sdwa v101, v108 dst_sel:DWORD dst_unused:UNUSED_PAD src0_sel:WORD_1
	v_div_scale_f32 v108, s[0:1], v107, v107, 1.0
	v_rcp_f32_e32 v110, v108
	v_cvt_f32_f16_e32 v104, v112
	v_cvt_f32_f16_sdwa v105, v112 dst_sel:DWORD dst_unused:UNUSED_PAD src0_sel:WORD_1
	v_fma_f32 v111, -v108, v110, 1.0
	v_fmac_f32_e32 v110, v111, v110
	v_div_scale_f32 v111, vcc, 1.0, v107, 1.0
	v_mul_f32_e32 v112, v111, v110
	v_fma_f32 v120, -v108, v112, v111
	v_fmac_f32_e32 v112, v120, v110
	v_fma_f32 v108, -v108, v112, v111
	v_div_fmas_f32 v108, v108, v110, v112
	v_div_fixup_f32 v107, v108, v107, 1.0
	v_div_scale_f32 v108, s[0:1], v106, v106, 1.0
	v_rcp_f32_e32 v110, v108
	v_pk_add_f32 v[104:105], v[104:105], v[100:101] neg_lo:[0,1] neg_hi:[0,1]
	v_fma_f32 v111, -v108, v110, 1.0
	v_fmac_f32_e32 v110, v111, v110
	v_div_scale_f32 v111, vcc, 1.0, v106, 1.0
	v_mul_f32_e32 v112, v111, v110
	v_fma_f32 v120, -v108, v112, v111
	v_fmac_f32_e32 v112, v120, v110
	v_fma_f32 v108, -v108, v112, v111
	v_div_fmas_f32 v108, v108, v110, v112
	v_div_fixup_f32 v106, v108, v106, 1.0
	v_pk_fma_f32 v[100:101], v[106:107], v[104:105], v[100:101]
	v_cvt_f32_f16_e32 v104, v109
	v_cvt_pk_f16_f32 v100, v100, v101
	v_div_scale_f32 v101, s[0:1], v103, v103, 1.0
	v_rcp_f32_e32 v108, v101
	v_cvt_f32_f16_sdwa v105, v109 dst_sel:DWORD dst_unused:UNUSED_PAD src0_sel:WORD_1
	v_cvt_f32_f16_e32 v106, v113
	v_cvt_f32_f16_sdwa v107, v113 dst_sel:DWORD dst_unused:UNUSED_PAD src0_sel:WORD_1
	v_fma_f32 v109, -v101, v108, 1.0
	v_fmac_f32_e32 v108, v109, v108
	v_div_scale_f32 v109, vcc, 1.0, v103, 1.0
	v_mul_f32_e32 v110, v109, v108
	v_fma_f32 v111, -v101, v110, v109
	v_fmac_f32_e32 v110, v111, v108
	v_fma_f32 v101, -v101, v110, v109
	v_div_fmas_f32 v101, v101, v108, v110
	v_div_fixup_f32 v103, v101, v103, 1.0
	v_div_scale_f32 v101, s[0:1], v102, v102, 1.0
	v_rcp_f32_e32 v108, v101
	v_pk_add_f32 v[106:107], v[106:107], v[104:105] neg_lo:[0,1] neg_hi:[0,1]
	v_fma_f32 v109, -v101, v108, 1.0
	v_fmac_f32_e32 v108, v109, v108
	v_div_scale_f32 v109, vcc, 1.0, v102, 1.0
	v_mul_f32_e32 v110, v109, v108
	v_fma_f32 v111, -v101, v110, v109
	v_fmac_f32_e32 v110, v111, v108
	v_fma_f32 v101, -v101, v110, v109
	v_div_fmas_f32 v101, v101, v108, v110
	v_div_fixup_f32 v102, v101, v102, 1.0
	v_pk_fma_f32 v[102:103], v[102:103], v[106:107], v[104:105]
	s_nop 0
	v_cvt_pk_f16_f32 v101, v102, v103
	global_store_dwordx4 v[118:119], v[98:101], off
	v_add_u32_e32 v102, 0x90, v164
	v_ashrrev_i32_e32 v103, 31, v102
	v_mad_i64_i32 v[98:99], s[0:1], v102, s5, v[168:169]
	v_lshl_add_u64 v[106:107], v[98:99], 0, s[90:91]
	v_lshlrev_b64 v[102:103], 12, v[102:103]
	v_lshl_add_u64 v[110:111], v[106:107], 0, v[166:167]
	v_lshl_add_u64 v[102:103], s[2:3], 0, v[102:103]
	global_load_dwordx4 v[98:101], v[110:111], off
	v_lshl_add_u64 v[108:109], v[102:103], 0, v[166:167]
	global_load_dwordx4 v[102:105], v[108:109], off
	v_add_f32_e32 v90, v90, v82
	v_mul_f32_e32 v90, 0xbfb8aa3b, v90
	v_exp_f32_e32 v112, v90
	v_add_f32_e32 v90, v95, v87
	v_mul_f32_e32 v90, 0xbfb8aa3b, v90
	v_exp_f32_e32 v121, v90
	v_add_f32_e32 v90, v91, v83
	v_mul_f32_e32 v90, 0xbfb8aa3b, v90
	v_exp_f32_e32 v113, v90
	v_add_f32_e32 v90, v96, v88
	v_add_f32_e32 v94, v94, v86
	v_mul_f32_e32 v90, 0xbfb8aa3b, v90
	v_mul_f32_e32 v94, 0xbfb8aa3b, v94
	v_exp_f32_e32 v118, v90
	v_add_f32_e32 v90, v92, v84
	v_exp_f32_e32 v120, v94
	v_mul_f32_e32 v90, 0xbfb8aa3b, v90
	v_exp_f32_e32 v94, v90
	v_add_f32_e32 v90, v97, v89
	v_mul_f32_e32 v90, 0xbfb8aa3b, v90
	v_exp_f32_e32 v119, v90
	v_add_f32_e32 v90, v93, v85
	v_mul_f32_e32 v90, 0xbfb8aa3b, v90
	v_pk_add_f32 v[96:97], v[120:121], 1.0 op_sel_hi:[1,0]
	v_exp_f32_e32 v95, v90
	s_waitcnt vmcnt(0)
; __device__ __forceinline__ float sigmoidf_(float x) { return 1.0f / (1.0f + __expf(-x)); }
;     template <int GI>
;     __device__ __forceinline__ void body(const f32x4 (&acc)[2][2][4][2], int row0, int colt) const {
;     ...
;             for (int ai = 0; ai < 2; ++ai)
; #pragma unroll
;                 for (int m = 0; m < 4; ++m) {
;                     const size_t row = (size_t)(row0 + ai * 128 + m * 16);
;                     f32x4 x0 = acc[ai][bj][m][0] + b0, x1 = acc[ai][bj][m][1] + b1;
;                     if (GI == 0) {
; #pragma unroll
;                         for (int j = 0; j < 4; ++j) {
;                             x0[j] = 0.6065306597126334f * sigmoidf_(x0[j]); x1[j] = 0.6065306597126334f * sigmoidf_(x1[j]); }
;                         *(u32x4*)(DEC + row * DM + c) = pack8(x0, x1);
;                     } else if (GI == 1) {
; #pragma unroll
;                         for (int j = 0; j < 4; ++j) { x0[j] = sigmoidf_(x0[j]); x1[j] = sigmoidf_(x1[j]); }
;                         *(u32x4*)(Ab + row * DM + c) = pack8(x0, x1);
;                     } else if (GI == 2) {
;                         *(u32x4*)(Gb + row * DM + c) = pack8(x0, x1);
;                     } else {
;                         h16* vp = C1 + row * LDC1 + 4096 + c;
;                         const h16x8 vv = *(const h16x8*)vp; const h16x8 vf = *(const h16x8*)(VF + row * DM + c);
;                         f32x4 o0, o1;
; #pragma unroll
;                         for (int j = 0; j < 4; ++j) { float v = (float)vv[j], f = (float)vf[j]; o0[j] = v + (f - v) * sigmoidf_(x0[j]); v = (float)vv[4 + j]; f = (float)vf[4 + j]; o1[j] = v + (f - v) * sigmoidf_(x1[j]); }
;                         *(u32x4*)vp = pack8(o0, o1);
;                     }
;                     __builtin_amdgcn_sched_barrier(0);
	v_cvt_f32_f16_e32 v90, v98
	v_cvt_f32_f16_sdwa v91, v98 dst_sel:DWORD dst_unused:UNUSED_PAD src0_sel:WORD_1
	v_div_scale_f32 v98, s[0:1], v97, v97, 1.0
	v_cvt_f32_f16_e32 v92, v102
	v_cvt_f32_f16_sdwa v93, v102 dst_sel:DWORD dst_unused:UNUSED_PAD src0_sel:WORD_1
	v_rcp_f32_e32 v102, v98
	v_pk_add_f32 v[94:95], v[94:95], 1.0 op_sel_hi:[1,0]
	v_pk_add_f32 v[92:93], v[92:93], v[90:91] neg_lo:[0,1] neg_hi:[0,1]
	v_fma_f32 v120, -v98, v102, 1.0
	v_fmac_f32_e32 v102, v120, v102
	v_div_scale_f32 v120, vcc, 1.0, v97, 1.0
	v_mul_f32_e32 v121, v120, v102
	v_fma_f32 v126, -v98, v121, v120
	v_fmac_f32_e32 v121, v126, v102
	v_fma_f32 v98, -v98, v121, v120
	v_div_fmas_f32 v98, v98, v102, v121
	v_div_fixup_f32 v97, v98, v97, 1.0
	v_div_scale_f32 v98, s[0:1], v96, v96, 1.0
	v_rcp_f32_e32 v102, v98
	s_nop 0
	v_fma_f32 v120, -v98, v102, 1.0
	v_fmac_f32_e32 v102, v120, v102
	v_div_scale_f32 v120, vcc, 1.0, v96, 1.0
	v_mul_f32_e32 v121, v120, v102
	v_fma_f32 v126, -v98, v121, v120
	v_fmac_f32_e32 v121, v126, v102
	v_fma_f32 v98, -v98, v121, v120
	v_div_fmas_f32 v98, v98, v102, v121
	v_div_fixup_f32 v96, v98, v96, 1.0
	v_pk_fma_f32 v[90:91], v[96:97], v[92:93], v[90:91]
	v_cvt_f32_f16_e32 v92, v99
	v_cvt_f32_f16_sdwa v93, v99 dst_sel:DWORD dst_unused:UNUSED_PAD src0_sel:WORD_1
	v_pk_add_f32 v[98:99], v[118:119], 1.0 op_sel_hi:[1,0]
	v_cvt_pk_f16_f32 v90, v90, v91
	v_div_scale_f32 v91, s[0:1], v99, v99, 1.0
	v_rcp_f32_e32 v102, v91
	v_cvt_f32_f16_e32 v96, v103
	v_cvt_f32_f16_sdwa v97, v103 dst_sel:DWORD dst_unused:UNUSED_PAD src0_sel:WORD_1
	v_fma_f32 v103, -v91, v102, 1.0
	v_fmac_f32_e32 v102, v103, v102
	v_div_scale_f32 v103, vcc, 1.0, v99, 1.0
	v_mul_f32_e32 v118, v103, v102
	v_fma_f32 v119, -v91, v118, v103
	v_fmac_f32_e32 v118, v119, v102
	v_fma_f32 v91, -v91, v118, v103
	v_div_fmas_f32 v91, v91, v102, v118
	v_div_fixup_f32 v99, v91, v99, 1.0
	v_div_scale_f32 v91, s[0:1], v98, v98, 1.0
	v_rcp_f32_e32 v102, v91
	v_pk_add_f32 v[96:97], v[96:97], v[92:93] neg_lo:[0,1] neg_hi:[0,1]
	v_fma_f32 v103, -v91, v102, 1.0
	v_fmac_f32_e32 v102, v103, v102
	v_div_scale_f32 v103, vcc, 1.0, v98, 1.0
	v_mul_f32_e32 v118, v103, v102
	v_fma_f32 v119, -v91, v118, v103
	v_fmac_f32_e32 v118, v119, v102
	v_fma_f32 v91, -v91, v118, v103
	v_div_fmas_f32 v91, v91, v102, v118
	v_div_fixup_f32 v98, v91, v98, 1.0
	v_pk_fma_f32 v[92:93], v[98:99], v[96:97], v[92:93]
	v_pk_add_f32 v[98:99], v[112:113], 1.0 op_sel_hi:[1,0]
	v_cvt_pk_f16_f32 v91, v92, v93
	v_cvt_f32_f16_e32 v92, v100
	v_cvt_f32_f16_sdwa v93, v100 dst_sel:DWORD dst_unused:UNUSED_PAD src0_sel:WORD_1
	v_div_scale_f32 v100, s[0:1], v99, v99, 1.0
	v_rcp_f32_e32 v102, v100
	v_cvt_f32_f16_e32 v96, v104
	v_cvt_f32_f16_sdwa v97, v104 dst_sel:DWORD dst_unused:UNUSED_PAD src0_sel:WORD_1
	v_fma_f32 v103, -v100, v102, 1.0
	v_fmac_f32_e32 v102, v103, v102
	v_div_scale_f32 v103, vcc, 1.0, v99, 1.0
	v_mul_f32_e32 v104, v103, v102
	v_fma_f32 v112, -v100, v104, v103
	v_fmac_f32_e32 v104, v112, v102
	v_fma_f32 v100, -v100, v104, v103
	v_div_fmas_f32 v100, v100, v102, v104
	v_div_fixup_f32 v99, v100, v99, 1.0
	v_div_scale_f32 v100, s[0:1], v98, v98, 1.0
	v_rcp_f32_e32 v102, v100
	v_pk_add_f32 v[96:97], v[96:97], v[92:93] neg_lo:[0,1] neg_hi:[0,1]
	v_fma_f32 v103, -v100, v102, 1.0
	v_fmac_f32_e32 v102, v103, v102
	v_div_scale_f32 v103, vcc, 1.0, v98, 1.0
	v_mul_f32_e32 v104, v103, v102
	v_fma_f32 v112, -v100, v104, v103
	v_fmac_f32_e32 v104, v112, v102
	v_fma_f32 v100, -v100, v104, v103
	v_div_fmas_f32 v100, v100, v102, v104
	v_div_fixup_f32 v98, v100, v98, 1.0
	v_pk_fma_f32 v[92:93], v[98:99], v[96:97], v[92:93]
	v_cvt_f32_f16_e32 v96, v101
	v_cvt_pk_f16_f32 v92, v92, v93
	v_div_scale_f32 v93, s[0:1], v95, v95, 1.0
	v_rcp_f32_e32 v100, v93
	v_cvt_f32_f16_sdwa v97, v101 dst_sel:DWORD dst_unused:UNUSED_PAD src0_sel:WORD_1
	v_cvt_f32_f16_e32 v98, v105
	v_cvt_f32_f16_sdwa v99, v105 dst_sel:DWORD dst_unused:UNUSED_PAD src0_sel:WORD_1
	v_fma_f32 v101, -v93, v100, 1.0
	v_fmac_f32_e32 v100, v101, v100
	v_div_scale_f32 v101, vcc, 1.0, v95, 1.0
	v_mul_f32_e32 v102, v101, v100
	v_fma_f32 v103, -v93, v102, v101
	v_fmac_f32_e32 v102, v103, v100
	v_fma_f32 v93, -v93, v102, v101
	v_div_fmas_f32 v93, v93, v100, v102
	v_div_fixup_f32 v95, v93, v95, 1.0
	v_div_scale_f32 v93, s[0:1], v94, v94, 1.0
	v_rcp_f32_e32 v100, v93
	v_pk_add_f32 v[98:99], v[98:99], v[96:97] neg_lo:[0,1] neg_hi:[0,1]
	v_fma_f32 v101, -v93, v100, 1.0
	v_fmac_f32_e32 v100, v101, v100
	v_div_scale_f32 v101, vcc, 1.0, v94, 1.0
	v_mul_f32_e32 v102, v101, v100
	v_fma_f32 v103, -v93, v102, v101
	v_fmac_f32_e32 v102, v103, v100
	v_fma_f32 v93, -v93, v102, v101
	v_div_fmas_f32 v93, v93, v100, v102
	v_div_fixup_f32 v94, v93, v94, 1.0
	v_pk_fma_f32 v[94:95], v[94:95], v[98:99], v[96:97]
	s_nop 0
	v_cvt_pk_f16_f32 v93, v94, v95
	global_store_dwordx4 v[110:111], v[90:93], off
	v_add_u32_e32 v94, 0xa0, v164
	v_ashrrev_i32_e32 v95, 31, v94
	v_mad_i64_i32 v[90:91], s[0:1], v94, s5, v[168:169]
	v_lshl_add_u64 v[98:99], v[90:91], 0, s[90:91]
	v_lshlrev_b64 v[94:95], 12, v[94:95]
	v_lshl_add_u64 v[102:103], v[98:99], 0, v[166:167]
	v_lshl_add_u64 v[94:95], s[2:3], 0, v[94:95]
	global_load_dwordx4 v[90:93], v[102:103], off
	v_lshl_add_u64 v[100:101], v[94:95], 0, v[166:167]
	global_load_dwordx4 v[94:97], v[100:101], off
	v_add_f32_e32 v74, v74, v82
	v_mul_f32_e32 v74, 0xbfb8aa3b, v74
	v_exp_f32_e32 v104, v74
	v_add_f32_e32 v74, v79, v87
	v_mul_f32_e32 v74, 0xbfb8aa3b, v74
	v_exp_f32_e32 v113, v74
	v_add_f32_e32 v74, v75, v83
	v_mul_f32_e32 v74, 0xbfb8aa3b, v74
	v_exp_f32_e32 v105, v74
	v_add_f32_e32 v74, v80, v88
	v_add_f32_e32 v78, v78, v86
	v_mul_f32_e32 v74, 0xbfb8aa3b, v74
	v_mul_f32_e32 v78, 0xbfb8aa3b, v78
	v_exp_f32_e32 v110, v74
	v_add_f32_e32 v74, v76, v84
	v_exp_f32_e32 v112, v78
	v_mul_f32_e32 v74, 0xbfb8aa3b, v74
	v_exp_f32_e32 v78, v74
	v_add_f32_e32 v74, v81, v89
	v_mul_f32_e32 v74, 0xbfb8aa3b, v74
	v_exp_f32_e32 v111, v74
	v_add_f32_e32 v74, v77, v85
	v_mul_f32_e32 v74, 0xbfb8aa3b, v74
	v_pk_add_f32 v[80:81], v[112:113], 1.0 op_sel_hi:[1,0]
	v_exp_f32_e32 v79, v74
	s_waitcnt vmcnt(0)
; __device__ __forceinline__ float sigmoidf_(float x) { return 1.0f / (1.0f + __expf(-x)); }
;     template <int GI>
;     __device__ __forceinline__ void body(const f32x4 (&acc)[2][2][4][2], int row0, int colt) const {
;     ...
;             for (int ai = 0; ai < 2; ++ai)
; #pragma unroll
;                 for (int m = 0; m < 4; ++m) {
;                     const size_t row = (size_t)(row0 + ai * 128 + m * 16);
;                     f32x4 x0 = acc[ai][bj][m][0] + b0, x1 = acc[ai][bj][m][1] + b1;
;                     if (GI == 0) {
; #pragma unroll
;                         for (int j = 0; j < 4; ++j) {
;                             x0[j] = 0.6065306597126334f * sigmoidf_(x0[j]); x1[j] = 0.6065306597126334f * sigmoidf_(x1[j]); }
;                         *(u32x4*)(DEC + row * DM + c) = pack8(x0, x1);
;                     } else if (GI == 1) {
; #pragma unroll
;                         for (int j = 0; j < 4; ++j) { x0[j] = sigmoidf_(x0[j]); x1[j] = sigmoidf_(x1[j]); }
;                         *(u32x4*)(Ab + row * DM + c) = pack8(x0, x1);
;                     } else if (GI == 2) {
;                         *(u32x4*)(Gb + row * DM + c) = pack8(x0, x1);
;                     } else {
;                         h16* vp = C1 + row * LDC1 + 4096 + c;
;                         const h16x8 vv = *(const h16x8*)vp; const h16x8 vf = *(const h16x8*)(VF + row * DM + c);
;                         f32x4 o0, o1;
; #pragma unroll
;                         for (int j = 0; j < 4; ++j) { float v = (float)vv[j], f = (float)vf[j]; o0[j] = v + (f - v) * sigmoidf_(x0[j]); v = (float)vv[4 + j]; f = (float)vf[4 + j]; o1[j] = v + (f - v) * sigmoidf_(x1[j]); }
;                         *(u32x4*)vp = pack8(o0, o1);
;                     }
;                     __builtin_amdgcn_sched_barrier(0);
	v_cvt_f32_f16_e32 v74, v90
	v_cvt_f32_f16_sdwa v75, v90 dst_sel:DWORD dst_unused:UNUSED_PAD src0_sel:WORD_1
	v_div_scale_f32 v90, s[0:1], v81, v81, 1.0
	v_cvt_f32_f16_e32 v76, v94
	v_cvt_f32_f16_sdwa v77, v94 dst_sel:DWORD dst_unused:UNUSED_PAD src0_sel:WORD_1
	v_rcp_f32_e32 v94, v90
	v_pk_add_f32 v[78:79], v[78:79], 1.0 op_sel_hi:[1,0]
	v_pk_add_f32 v[76:77], v[76:77], v[74:75] neg_lo:[0,1] neg_hi:[0,1]
	v_fma_f32 v112, -v90, v94, 1.0
	v_fmac_f32_e32 v94, v112, v94
	v_div_scale_f32 v112, vcc, 1.0, v81, 1.0
	v_mul_f32_e32 v113, v112, v94
	v_fma_f32 v118, -v90, v113, v112
	v_fmac_f32_e32 v113, v118, v94
	v_fma_f32 v90, -v90, v113, v112
	v_div_fmas_f32 v90, v90, v94, v113
	v_div_fixup_f32 v81, v90, v81, 1.0
	v_div_scale_f32 v90, s[0:1], v80, v80, 1.0
	v_rcp_f32_e32 v94, v90
	s_nop 0
	v_fma_f32 v112, -v90, v94, 1.0
	v_fmac_f32_e32 v94, v112, v94
	v_div_scale_f32 v112, vcc, 1.0, v80, 1.0
	v_mul_f32_e32 v113, v112, v94
	v_fma_f32 v118, -v90, v113, v112
	v_fmac_f32_e32 v113, v118, v94
	v_fma_f32 v90, -v90, v113, v112
	v_div_fmas_f32 v90, v90, v94, v113
	v_div_fixup_f32 v80, v90, v80, 1.0
	v_pk_fma_f32 v[74:75], v[80:81], v[76:77], v[74:75]
	v_cvt_f32_f16_e32 v76, v91
	v_cvt_f32_f16_sdwa v77, v91 dst_sel:DWORD dst_unused:UNUSED_PAD src0_sel:WORD_1
	v_pk_add_f32 v[90:91], v[110:111], 1.0 op_sel_hi:[1,0]
	v_cvt_pk_f16_f32 v74, v74, v75
	v_div_scale_f32 v75, s[0:1], v91, v91, 1.0
	v_rcp_f32_e32 v94, v75
	v_cvt_f32_f16_e32 v80, v95
	v_cvt_f32_f16_sdwa v81, v95 dst_sel:DWORD dst_unused:UNUSED_PAD src0_sel:WORD_1
	v_fma_f32 v95, -v75, v94, 1.0
	v_fmac_f32_e32 v94, v95, v94
	v_div_scale_f32 v95, vcc, 1.0, v91, 1.0
	v_mul_f32_e32 v110, v95, v94
	v_fma_f32 v111, -v75, v110, v95
	v_fmac_f32_e32 v110, v111, v94
	v_fma_f32 v75, -v75, v110, v95
	v_div_fmas_f32 v75, v75, v94, v110
	v_div_fixup_f32 v91, v75, v91, 1.0
	v_div_scale_f32 v75, s[0:1], v90, v90, 1.0
	v_rcp_f32_e32 v94, v75
	v_pk_add_f32 v[80:81], v[80:81], v[76:77] neg_lo:[0,1] neg_hi:[0,1]
	v_fma_f32 v95, -v75, v94, 1.0
	v_fmac_f32_e32 v94, v95, v94
	v_div_scale_f32 v95, vcc, 1.0, v90, 1.0
	v_mul_f32_e32 v110, v95, v94
	v_fma_f32 v111, -v75, v110, v95
	v_fmac_f32_e32 v110, v111, v94
	v_fma_f32 v75, -v75, v110, v95
	v_div_fmas_f32 v75, v75, v94, v110
	v_div_fixup_f32 v90, v75, v90, 1.0
	v_pk_fma_f32 v[76:77], v[90:91], v[80:81], v[76:77]
	v_pk_add_f32 v[90:91], v[104:105], 1.0 op_sel_hi:[1,0]
	v_cvt_pk_f16_f32 v75, v76, v77
	v_cvt_f32_f16_e32 v76, v92
	v_cvt_f32_f16_sdwa v77, v92 dst_sel:DWORD dst_unused:UNUSED_PAD src0_sel:WORD_1
	v_div_scale_f32 v92, s[0:1], v91, v91, 1.0
	v_rcp_f32_e32 v94, v92
	v_cvt_f32_f16_e32 v80, v96
	v_cvt_f32_f16_sdwa v81, v96 dst_sel:DWORD dst_unused:UNUSED_PAD src0_sel:WORD_1
	v_fma_f32 v95, -v92, v94, 1.0
	v_fmac_f32_e32 v94, v95, v94
	v_div_scale_f32 v95, vcc, 1.0, v91, 1.0
	v_mul_f32_e32 v96, v95, v94
	v_fma_f32 v104, -v92, v96, v95
	v_fmac_f32_e32 v96, v104, v94
	v_fma_f32 v92, -v92, v96, v95
	v_div_fmas_f32 v92, v92, v94, v96
	v_div_fixup_f32 v91, v92, v91, 1.0
	v_div_scale_f32 v92, s[0:1], v90, v90, 1.0
	v_rcp_f32_e32 v94, v92
	v_pk_add_f32 v[80:81], v[80:81], v[76:77] neg_lo:[0,1] neg_hi:[0,1]
	v_fma_f32 v95, -v92, v94, 1.0
	v_fmac_f32_e32 v94, v95, v94
	v_div_scale_f32 v95, vcc, 1.0, v90, 1.0
	v_mul_f32_e32 v96, v95, v94
	v_fma_f32 v104, -v92, v96, v95
	v_fmac_f32_e32 v96, v104, v94
	v_fma_f32 v92, -v92, v96, v95
	v_div_fmas_f32 v92, v92, v94, v96
	v_div_fixup_f32 v90, v92, v90, 1.0
	v_pk_fma_f32 v[76:77], v[90:91], v[80:81], v[76:77]
	v_cvt_f32_f16_e32 v80, v93
	v_cvt_pk_f16_f32 v76, v76, v77
	v_div_scale_f32 v77, s[0:1], v79, v79, 1.0
	v_rcp_f32_e32 v92, v77
	v_cvt_f32_f16_sdwa v81, v93 dst_sel:DWORD dst_unused:UNUSED_PAD src0_sel:WORD_1
	v_cvt_f32_f16_e32 v90, v97
	v_cvt_f32_f16_sdwa v91, v97 dst_sel:DWORD dst_unused:UNUSED_PAD src0_sel:WORD_1
	v_fma_f32 v93, -v77, v92, 1.0
	v_fmac_f32_e32 v92, v93, v92
	v_div_scale_f32 v93, vcc, 1.0, v79, 1.0
	v_mul_f32_e32 v94, v93, v92
	v_fma_f32 v95, -v77, v94, v93
	v_fmac_f32_e32 v94, v95, v92
	v_fma_f32 v77, -v77, v94, v93
	v_div_fmas_f32 v77, v77, v92, v94
	v_div_fixup_f32 v79, v77, v79, 1.0
	v_div_scale_f32 v77, s[0:1], v78, v78, 1.0
	v_rcp_f32_e32 v92, v77
	v_pk_add_f32 v[90:91], v[90:91], v[80:81] neg_lo:[0,1] neg_hi:[0,1]
	v_fma_f32 v93, -v77, v92, 1.0
	v_fmac_f32_e32 v92, v93, v92
	v_div_scale_f32 v93, vcc, 1.0, v78, 1.0
	v_mul_f32_e32 v94, v93, v92
	v_fma_f32 v95, -v77, v94, v93
	v_fmac_f32_e32 v94, v95, v92
	v_fma_f32 v77, -v77, v94, v93
	v_div_fmas_f32 v77, v77, v92, v94
	v_div_fixup_f32 v78, v77, v78, 1.0
	v_pk_fma_f32 v[78:79], v[78:79], v[90:91], v[80:81]
	s_nop 0
	v_cvt_pk_f16_f32 v77, v78, v79
	global_store_dwordx4 v[102:103], v[74:77], off
	v_add_u32_e32 v78, 0xb0, v164
	v_ashrrev_i32_e32 v79, 31, v78
	v_mad_i64_i32 v[74:75], s[0:1], v78, s5, v[168:169]
	v_lshl_add_u64 v[90:91], v[74:75], 0, s[90:91]
	v_lshlrev_b64 v[78:79], 12, v[78:79]
	v_lshl_add_u64 v[94:95], v[90:91], 0, v[166:167]
	v_lshl_add_u64 v[78:79], s[2:3], 0, v[78:79]
	global_load_dwordx4 v[74:77], v[94:95], off
	v_lshl_add_u64 v[92:93], v[78:79], 0, v[166:167]
	global_load_dwordx4 v[78:81], v[92:93], off
	v_add_f32_e32 v66, v66, v82
	v_mul_f32_e32 v66, 0xbfb8aa3b, v66
	v_exp_f32_e32 v82, v66
	v_add_f32_e32 v66, v71, v87
	v_mul_f32_e32 v66, 0xbfb8aa3b, v66
	v_exp_f32_e32 v97, v66
	v_add_f32_e32 v66, v67, v83
	v_mul_f32_e32 v66, 0xbfb8aa3b, v66
	v_exp_f32_e32 v83, v66
	v_add_f32_e32 v66, v72, v88
	v_add_f32_e32 v70, v70, v86
	v_mul_f32_e32 v66, 0xbfb8aa3b, v66
	v_mul_f32_e32 v70, 0xbfb8aa3b, v70
	v_exp_f32_e32 v86, v66
	v_add_f32_e32 v66, v68, v84
	v_exp_f32_e32 v96, v70
	v_mul_f32_e32 v66, 0xbfb8aa3b, v66
	v_exp_f32_e32 v70, v66
	v_add_f32_e32 v66, v73, v89
	v_mul_f32_e32 v66, 0xbfb8aa3b, v66
	v_exp_f32_e32 v87, v66
	v_add_f32_e32 v66, v69, v85
	v_mul_f32_e32 v66, 0xbfb8aa3b, v66
	v_pk_add_f32 v[72:73], v[96:97], 1.0 op_sel_hi:[1,0]
	v_exp_f32_e32 v71, v66
	s_waitcnt vmcnt(0)
; __device__ __forceinline__ float sigmoidf_(float x) { return 1.0f / (1.0f + __expf(-x)); }
;     template <int GI>
;     __device__ __forceinline__ void body(const f32x4 (&acc)[2][2][4][2], int row0, int colt) const {
;     ...
;         for (int bj = 0; bj < 2; ++bj) {
;             const int c = colt + bj * 128;
;             f32x4 b0 = (f32x4){0.f, 0.f, 0.f, 0.f}, b1 = b0;
;             if (GI == 0) { b0 = *(const f32x4*)(w0 + c); b1 = *(const f32x4*)(w0 + c + 4); }
;             else if (GI == 1) { b0 = *(const f32x4*)(a0 + c); b1 = *(const f32x4*)(a0 + c + 4); }
;             else if (GI == 3) { b0 = *(const f32x4*)(v0 + c); b1 = *(const f32x4*)(v0 + c + 4); }
; #pragma unroll
;             for (int ai = 0; ai < 2; ++ai)
; #pragma unroll
;                 for (int m = 0; m < 4; ++m) {
;                     const size_t row = (size_t)(row0 + ai * 128 + m * 16);
;                     f32x4 x0 = acc[ai][bj][m][0] + b0, x1 = acc[ai][bj][m][1] + b1;
;                     if (GI == 0) {
; #pragma unroll
;                         for (int j = 0; j < 4; ++j) {
;                             x0[j] = 0.6065306597126334f * sigmoidf_(x0[j]); x1[j] = 0.6065306597126334f * sigmoidf_(x1[j]); }
;                         *(u32x4*)(DEC + row * DM + c) = pack8(x0, x1);
;                     } else if (GI == 1) {
; #pragma unroll
;                         for (int j = 0; j < 4; ++j) { x0[j] = sigmoidf_(x0[j]); x1[j] = sigmoidf_(x1[j]); }
;                         *(u32x4*)(Ab + row * DM + c) = pack8(x0, x1);
;                     } else if (GI == 2) {
;                         *(u32x4*)(Gb + row * DM + c) = pack8(x0, x1);
;                     } else {
;                         h16* vp = C1 + row * LDC1 + 4096 + c;
;                         const h16x8 vv = *(const h16x8*)vp; const h16x8 vf = *(const h16x8*)(VF + row * DM + c);
;                         f32x4 o0, o1;
; #pragma unroll
;                         for (int j = 0; j < 4; ++j) { float v = (float)vv[j], f = (float)vf[j]; o0[j] = v + (f - v) * sigmoidf_(x0[j]); v = (float)vv[4 + j]; f = (float)vf[4 + j]; o1[j] = v + (f - v) * sigmoidf_(x1[j]); }
;                         *(u32x4*)vp = pack8(o0, o1);
;                     }
;                     __builtin_amdgcn_sched_barrier(0);
	v_cvt_f32_f16_e32 v66, v74
	v_cvt_f32_f16_sdwa v67, v74 dst_sel:DWORD dst_unused:UNUSED_PAD src0_sel:WORD_1
	v_div_scale_f32 v74, s[0:1], v73, v73, 1.0
	v_cvt_f32_f16_e32 v68, v78
	v_cvt_f32_f16_sdwa v69, v78 dst_sel:DWORD dst_unused:UNUSED_PAD src0_sel:WORD_1
	v_rcp_f32_e32 v78, v74
	v_pk_add_f32 v[70:71], v[70:71], 1.0 op_sel_hi:[1,0]
	v_pk_add_f32 v[68:69], v[68:69], v[66:67] neg_lo:[0,1] neg_hi:[0,1]
	v_fma_f32 v84, -v74, v78, 1.0
	v_fmac_f32_e32 v78, v84, v78
	v_div_scale_f32 v84, vcc, 1.0, v73, 1.0
	v_mul_f32_e32 v85, v84, v78
	v_fma_f32 v88, -v74, v85, v84
	v_fmac_f32_e32 v85, v88, v78
	v_fma_f32 v74, -v74, v85, v84
	v_div_fmas_f32 v74, v74, v78, v85
	v_div_fixup_f32 v73, v74, v73, 1.0
	v_div_scale_f32 v74, s[0:1], v72, v72, 1.0
	v_rcp_f32_e32 v78, v74
	s_nop 0
	v_fma_f32 v84, -v74, v78, 1.0
	v_fmac_f32_e32 v78, v84, v78
	v_div_scale_f32 v84, vcc, 1.0, v72, 1.0
	v_mul_f32_e32 v85, v84, v78
	v_fma_f32 v88, -v74, v85, v84
	v_fmac_f32_e32 v85, v88, v78
	v_fma_f32 v74, -v74, v85, v84
	v_div_fmas_f32 v74, v74, v78, v85
	v_div_fixup_f32 v72, v74, v72, 1.0
	v_pk_fma_f32 v[66:67], v[72:73], v[68:69], v[66:67]
	v_cvt_f32_f16_e32 v68, v75
	v_cvt_f32_f16_sdwa v69, v75 dst_sel:DWORD dst_unused:UNUSED_PAD src0_sel:WORD_1
	v_pk_add_f32 v[74:75], v[86:87], 1.0 op_sel_hi:[1,0]
	v_cvt_pk_f16_f32 v66, v66, v67
	v_div_scale_f32 v67, s[0:1], v75, v75, 1.0
	v_rcp_f32_e32 v78, v67
	v_cvt_f32_f16_e32 v72, v79
	v_cvt_f32_f16_sdwa v73, v79 dst_sel:DWORD dst_unused:UNUSED_PAD src0_sel:WORD_1
	v_fma_f32 v79, -v67, v78, 1.0
	v_fmac_f32_e32 v78, v79, v78
	v_div_scale_f32 v79, vcc, 1.0, v75, 1.0
	v_mul_f32_e32 v84, v79, v78
	v_fma_f32 v85, -v67, v84, v79
	v_fmac_f32_e32 v84, v85, v78
	v_fma_f32 v67, -v67, v84, v79
	v_div_fmas_f32 v67, v67, v78, v84
	v_div_fixup_f32 v75, v67, v75, 1.0
	v_div_scale_f32 v67, s[0:1], v74, v74, 1.0
	v_rcp_f32_e32 v78, v67
	v_pk_add_f32 v[72:73], v[72:73], v[68:69] neg_lo:[0,1] neg_hi:[0,1]
	v_fma_f32 v79, -v67, v78, 1.0
	v_fmac_f32_e32 v78, v79, v78
	v_div_scale_f32 v79, vcc, 1.0, v74, 1.0
	v_mul_f32_e32 v84, v79, v78
	v_fma_f32 v85, -v67, v84, v79
	v_fmac_f32_e32 v84, v85, v78
	v_fma_f32 v67, -v67, v84, v79
	v_div_fmas_f32 v67, v67, v78, v84
	v_div_fixup_f32 v74, v67, v74, 1.0
	v_pk_fma_f32 v[68:69], v[74:75], v[72:73], v[68:69]
	v_pk_add_f32 v[74:75], v[82:83], 1.0 op_sel_hi:[1,0]
	v_cvt_pk_f16_f32 v67, v68, v69
	v_cvt_f32_f16_e32 v68, v76
	v_cvt_f32_f16_sdwa v69, v76 dst_sel:DWORD dst_unused:UNUSED_PAD src0_sel:WORD_1
	v_div_scale_f32 v76, s[0:1], v75, v75, 1.0
	v_rcp_f32_e32 v78, v76
	v_cvt_f32_f16_e32 v72, v80
	v_cvt_f32_f16_sdwa v73, v80 dst_sel:DWORD dst_unused:UNUSED_PAD src0_sel:WORD_1
	v_fma_f32 v79, -v76, v78, 1.0
	v_fmac_f32_e32 v78, v79, v78
	v_div_scale_f32 v79, vcc, 1.0, v75, 1.0
	v_mul_f32_e32 v80, v79, v78
	v_fma_f32 v82, -v76, v80, v79
	v_fmac_f32_e32 v80, v82, v78
	v_fma_f32 v76, -v76, v80, v79
	v_div_fmas_f32 v76, v76, v78, v80
	v_div_fixup_f32 v75, v76, v75, 1.0
	v_div_scale_f32 v76, s[0:1], v74, v74, 1.0
	v_rcp_f32_e32 v78, v76
	v_pk_add_f32 v[72:73], v[72:73], v[68:69] neg_lo:[0,1] neg_hi:[0,1]
	v_fma_f32 v79, -v76, v78, 1.0
	v_fmac_f32_e32 v78, v79, v78
	v_div_scale_f32 v79, vcc, 1.0, v74, 1.0
	v_mul_f32_e32 v80, v79, v78
	v_fma_f32 v82, -v76, v80, v79
	v_fmac_f32_e32 v80, v82, v78
	v_fma_f32 v76, -v76, v80, v79
	v_div_fmas_f32 v76, v76, v78, v80
	v_div_fixup_f32 v74, v76, v74, 1.0
	v_pk_fma_f32 v[68:69], v[74:75], v[72:73], v[68:69]
	v_cvt_f32_f16_e32 v72, v77
	v_cvt_pk_f16_f32 v68, v68, v69
	v_div_scale_f32 v69, s[0:1], v71, v71, 1.0
	v_rcp_f32_e32 v76, v69
	v_cvt_f32_f16_sdwa v73, v77 dst_sel:DWORD dst_unused:UNUSED_PAD src0_sel:WORD_1
	v_cvt_f32_f16_e32 v74, v81
	v_cvt_f32_f16_sdwa v75, v81 dst_sel:DWORD dst_unused:UNUSED_PAD src0_sel:WORD_1
	v_fma_f32 v77, -v69, v76, 1.0
	v_fmac_f32_e32 v76, v77, v76
	v_div_scale_f32 v77, vcc, 1.0, v71, 1.0
	v_mul_f32_e32 v78, v77, v76
	v_fma_f32 v79, -v69, v78, v77
	v_fmac_f32_e32 v78, v79, v76
	v_fma_f32 v69, -v69, v78, v77
	v_div_fmas_f32 v69, v69, v76, v78
	v_div_fixup_f32 v71, v69, v71, 1.0
	v_div_scale_f32 v69, s[0:1], v70, v70, 1.0
	v_rcp_f32_e32 v76, v69
	v_pk_add_f32 v[74:75], v[74:75], v[72:73] neg_lo:[0,1] neg_hi:[0,1]
	v_fma_f32 v77, -v69, v76, 1.0
	v_fmac_f32_e32 v76, v77, v76
	v_div_scale_f32 v77, vcc, 1.0, v70, 1.0
	v_mul_f32_e32 v78, v77, v76
	v_fma_f32 v79, -v69, v78, v77
	v_fmac_f32_e32 v78, v79, v76
	v_fma_f32 v69, -v69, v78, v77
	v_div_fmas_f32 v69, v69, v76, v78
	v_div_fixup_f32 v70, v69, v70, 1.0
	v_pk_fma_f32 v[70:71], v[70:71], v[74:75], v[72:73]
	s_nop 0
	v_cvt_pk_f16_f32 v69, v70, v71
	global_store_dwordx4 v[94:95], v[66:69], off
	global_load_dwordx4 v[66:69], v[156:157], off offset:528
	s_nop 0
	global_load_dwordx4 v[70:73], v[156:157], off offset:512
	v_or_b32_e32 v74, 0x80, v158
	v_ashrrev_i32_e32 v75, 31, v74
	v_lshlrev_b64 v[82:83], 1, v[74:75]
	v_lshl_add_u64 v[84:85], v[160:161], 0, v[82:83]
	global_load_dwordx4 v[74:77], v[84:85], off
	global_load_dwordx4 v[78:81], v[162:163], off offset:256
	s_waitcnt vmcnt(0)
; __device__ __forceinline__ float sigmoidf_(float x) { return 1.0f / (1.0f + __expf(-x)); }
;     template <int GI>
;     __device__ __forceinline__ void body(const f32x4 (&acc)[2][2][4][2], int row0, int colt) const {
;     ...
;             for (int ai = 0; ai < 2; ++ai)
; #pragma unroll
;                 for (int m = 0; m < 4; ++m) {
;                     const size_t row = (size_t)(row0 + ai * 128 + m * 16);
;                     f32x4 x0 = acc[ai][bj][m][0] + b0, x1 = acc[ai][bj][m][1] + b1;
;                     if (GI == 0) {
; #pragma unroll
;                         for (int j = 0; j < 4; ++j) {
;                             x0[j] = 0.6065306597126334f * sigmoidf_(x0[j]); x1[j] = 0.6065306597126334f * sigmoidf_(x1[j]); }
;                         *(u32x4*)(DEC + row * DM + c) = pack8(x0, x1);
;                     } else if (GI == 1) {
; #pragma unroll
;                         for (int j = 0; j < 4; ++j) { x0[j] = sigmoidf_(x0[j]); x1[j] = sigmoidf_(x1[j]); }
;                         *(u32x4*)(Ab + row * DM + c) = pack8(x0, x1);
;                     } else if (GI == 2) {
;                         *(u32x4*)(Gb + row * DM + c) = pack8(x0, x1);
;                     } else {
;                         h16* vp = C1 + row * LDC1 + 4096 + c;
;                         const h16x8 vv = *(const h16x8*)vp; const h16x8 vf = *(const h16x8*)(VF + row * DM + c);
;                         f32x4 o0, o1;
; #pragma unroll
;                         for (int j = 0; j < 4; ++j) { float v = (float)vv[j], f = (float)vf[j]; o0[j] = v + (f - v) * sigmoidf_(x0[j]); v = (float)vv[4 + j]; f = (float)vf[4 + j]; o1[j] = v + (f - v) * sigmoidf_(x1[j]); }
;                         *(u32x4*)vp = pack8(o0, o1);
;                     }
;                     __builtin_amdgcn_sched_barrier(0);
	v_add_f32_e32 v58, v58, v66
	v_mul_f32_e32 v58, 0xbfb8aa3b, v58
	v_exp_f32_e32 v86, v58
	v_add_f32_e32 v58, v63, v71
	v_mul_f32_e32 v58, 0xbfb8aa3b, v58
	v_exp_f32_e32 v89, v58
	v_add_f32_e32 v58, v59, v67
	v_mul_f32_e32 v58, 0xbfb8aa3b, v58
	v_exp_f32_e32 v87, v58
	v_add_f32_e32 v58, v64, v72
	v_add_f32_e32 v62, v62, v70
	v_mul_f32_e32 v58, 0xbfb8aa3b, v58
	v_mul_f32_e32 v62, 0xbfb8aa3b, v62
	v_exp_f32_e32 v64, v58
	v_add_f32_e32 v58, v60, v68
	v_exp_f32_e32 v88, v62
	v_mul_f32_e32 v58, 0xbfb8aa3b, v58
	v_exp_f32_e32 v62, v58
	v_add_f32_e32 v58, v65, v73
	v_mul_f32_e32 v58, 0xbfb8aa3b, v58
	v_exp_f32_e32 v65, v58
	v_add_f32_e32 v58, v61, v69
	v_mul_f32_e32 v58, 0xbfb8aa3b, v58
	v_pk_add_f32 v[88:89], v[88:89], 1.0 op_sel_hi:[1,0]
	v_exp_f32_e32 v63, v58
	v_cvt_f32_f16_e32 v58, v74
	v_cvt_f32_f16_sdwa v59, v74 dst_sel:DWORD dst_unused:UNUSED_PAD src0_sel:WORD_1
	v_div_scale_f32 v74, s[0:1], v89, v89, 1.0
	v_cvt_f32_f16_e32 v60, v78
	v_cvt_f32_f16_sdwa v61, v78 dst_sel:DWORD dst_unused:UNUSED_PAD src0_sel:WORD_1
	v_rcp_f32_e32 v78, v74
	v_pk_add_f32 v[64:65], v[64:65], 1.0 op_sel_hi:[1,0]
	v_pk_add_f32 v[62:63], v[62:63], 1.0 op_sel_hi:[1,0]
	v_pk_add_f32 v[60:61], v[60:61], v[58:59] neg_lo:[0,1] neg_hi:[0,1]
	v_fma_f32 v94, -v74, v78, 1.0
	v_fmac_f32_e32 v78, v94, v78
	v_div_scale_f32 v94, vcc, 1.0, v89, 1.0
	v_mul_f32_e32 v95, v94, v78
	v_fma_f32 v96, -v74, v95, v94
	v_fmac_f32_e32 v95, v96, v78
	v_fma_f32 v74, -v74, v95, v94
	v_div_fmas_f32 v74, v74, v78, v95
	v_div_fixup_f32 v89, v74, v89, 1.0
	v_div_scale_f32 v74, s[0:1], v88, v88, 1.0
	v_rcp_f32_e32 v78, v74
	s_nop 0
	v_fma_f32 v94, -v74, v78, 1.0
	v_fmac_f32_e32 v78, v94, v78
	v_div_scale_f32 v94, vcc, 1.0, v88, 1.0
	v_mul_f32_e32 v95, v94, v78
	v_fma_f32 v96, -v74, v95, v94
	v_fmac_f32_e32 v95, v96, v78
	v_fma_f32 v74, -v74, v95, v94
	v_div_fmas_f32 v74, v74, v78, v95
	v_div_fixup_f32 v88, v74, v88, 1.0
	v_pk_fma_f32 v[58:59], v[88:89], v[60:61], v[58:59]
	v_cvt_f32_f16_e32 v60, v75
	v_cvt_pk_f16_f32 v58, v58, v59
	v_div_scale_f32 v59, s[0:1], v65, v65, 1.0
	v_rcp_f32_e32 v78, v59
	v_cvt_f32_f16_sdwa v61, v75 dst_sel:DWORD dst_unused:UNUSED_PAD src0_sel:WORD_1
	v_cvt_f32_f16_e32 v74, v79
	v_cvt_f32_f16_sdwa v75, v79 dst_sel:DWORD dst_unused:UNUSED_PAD src0_sel:WORD_1
	v_fma_f32 v79, -v59, v78, 1.0
	v_fmac_f32_e32 v78, v79, v78
	v_div_scale_f32 v79, vcc, 1.0, v65, 1.0
	v_mul_f32_e32 v88, v79, v78
	v_fma_f32 v89, -v59, v88, v79
	v_fmac_f32_e32 v88, v89, v78
	v_fma_f32 v59, -v59, v88, v79
	v_div_fmas_f32 v59, v59, v78, v88
	v_div_fixup_f32 v65, v59, v65, 1.0
	v_div_scale_f32 v59, s[0:1], v64, v64, 1.0
	v_rcp_f32_e32 v78, v59
	v_pk_add_f32 v[74:75], v[74:75], v[60:61] neg_lo:[0,1] neg_hi:[0,1]
	v_fma_f32 v79, -v59, v78, 1.0
	v_fmac_f32_e32 v78, v79, v78
	v_div_scale_f32 v79, vcc, 1.0, v64, 1.0
	v_mul_f32_e32 v88, v79, v78
	v_fma_f32 v89, -v59, v88, v79
	v_fmac_f32_e32 v88, v89, v78
	v_fma_f32 v59, -v59, v88, v79
	v_div_fmas_f32 v59, v59, v78, v88
	v_div_fixup_f32 v64, v59, v64, 1.0
	v_pk_fma_f32 v[60:61], v[64:65], v[74:75], v[60:61]
	v_pk_add_f32 v[74:75], v[86:87], 1.0 op_sel_hi:[1,0]
	v_cvt_pk_f16_f32 v59, v60, v61
	v_cvt_f32_f16_e32 v60, v76
	v_cvt_f32_f16_sdwa v61, v76 dst_sel:DWORD dst_unused:UNUSED_PAD src0_sel:WORD_1
	v_div_scale_f32 v76, s[0:1], v75, v75, 1.0
	v_rcp_f32_e32 v78, v76
	v_cvt_f32_f16_e32 v64, v80
	v_cvt_f32_f16_sdwa v65, v80 dst_sel:DWORD dst_unused:UNUSED_PAD src0_sel:WORD_1
	v_fma_f32 v79, -v76, v78, 1.0
	v_fmac_f32_e32 v78, v79, v78
	v_div_scale_f32 v79, vcc, 1.0, v75, 1.0
	v_mul_f32_e32 v80, v79, v78
	v_fma_f32 v86, -v76, v80, v79
	v_fmac_f32_e32 v80, v86, v78
	v_fma_f32 v76, -v76, v80, v79
	v_div_fmas_f32 v76, v76, v78, v80
	v_div_fixup_f32 v75, v76, v75, 1.0
	v_div_scale_f32 v76, s[0:1], v74, v74, 1.0
	v_rcp_f32_e32 v78, v76
	v_pk_add_f32 v[64:65], v[64:65], v[60:61] neg_lo:[0,1] neg_hi:[0,1]
	v_fma_f32 v79, -v76, v78, 1.0
	v_fmac_f32_e32 v78, v79, v78
	v_div_scale_f32 v79, vcc, 1.0, v74, 1.0
	v_mul_f32_e32 v80, v79, v78
	v_fma_f32 v86, -v76, v80, v79
	v_fmac_f32_e32 v80, v86, v78
	v_fma_f32 v76, -v76, v80, v79
	v_div_fmas_f32 v76, v76, v78, v80
	v_div_fixup_f32 v74, v76, v74, 1.0
	v_pk_fma_f32 v[60:61], v[64:65], v[74:75], v[60:61]
	v_cvt_f32_f16_e32 v64, v77
	v_cvt_pk_f16_f32 v60, v60, v61
	v_div_scale_f32 v61, s[0:1], v63, v63, 1.0
	v_rcp_f32_e32 v76, v61
	v_cvt_f32_f16_sdwa v65, v77 dst_sel:DWORD dst_unused:UNUSED_PAD src0_sel:WORD_1
	v_cvt_f32_f16_e32 v74, v81
	v_cvt_f32_f16_sdwa v75, v81 dst_sel:DWORD dst_unused:UNUSED_PAD src0_sel:WORD_1
	v_fma_f32 v77, -v61, v76, 1.0
	v_fmac_f32_e32 v76, v77, v76
	v_div_scale_f32 v77, vcc, 1.0, v63, 1.0
	v_mul_f32_e32 v78, v77, v76
	v_fma_f32 v79, -v61, v78, v77
	v_fmac_f32_e32 v78, v79, v76
	v_fma_f32 v61, -v61, v78, v77
	v_div_fmas_f32 v61, v61, v76, v78
	v_div_fixup_f32 v63, v61, v63, 1.0
	v_div_scale_f32 v61, s[0:1], v62, v62, 1.0
	v_rcp_f32_e32 v76, v61
	v_pk_add_f32 v[74:75], v[74:75], v[64:65] neg_lo:[0,1] neg_hi:[0,1]
	v_fma_f32 v77, -v61, v76, 1.0
	v_fmac_f32_e32 v76, v77, v76
	v_div_scale_f32 v77, vcc, 1.0, v62, 1.0
	v_mul_f32_e32 v78, v77, v76
	v_fma_f32 v79, -v61, v78, v77
	v_fmac_f32_e32 v78, v79, v76
	v_fma_f32 v61, -v61, v78, v77
	v_div_fmas_f32 v61, v61, v76, v78
	v_div_fixup_f32 v62, v61, v62, 1.0
	v_pk_fma_f32 v[62:63], v[74:75], v[62:63], v[64:65]
	s_nop 0
	v_cvt_pk_f16_f32 v61, v62, v63
	global_store_dwordx4 v[84:85], v[58:61], off
	v_lshl_add_u64 v[74:75], v[138:139], 0, v[82:83]
	global_load_dwordx4 v[62:65], v[74:75], off
	global_load_dwordx4 v[58:61], v[140:141], off offset:256
	v_add_f32_e32 v50, v50, v66
	v_mul_f32_e32 v50, 0xbfb8aa3b, v50
	v_exp_f32_e32 v76, v50
	v_add_f32_e32 v50, v55, v71
	v_mul_f32_e32 v50, 0xbfb8aa3b, v50
	v_exp_f32_e32 v81, v50
	v_add_f32_e32 v50, v51, v67
	v_mul_f32_e32 v50, 0xbfb8aa3b, v50
	v_add_f32_e32 v54, v54, v70
	v_exp_f32_e32 v77, v50
	v_add_f32_e32 v50, v56, v72
	v_mul_f32_e32 v54, 0xbfb8aa3b, v54
	v_mul_f32_e32 v50, 0xbfb8aa3b, v50
	v_exp_f32_e32 v80, v54
	v_exp_f32_e32 v78, v50
	v_add_f32_e32 v50, v52, v68
	v_mul_f32_e32 v50, 0xbfb8aa3b, v50
	v_exp_f32_e32 v54, v50
	v_add_f32_e32 v50, v57, v73
	v_mul_f32_e32 v50, 0xbfb8aa3b, v50
	v_exp_f32_e32 v79, v50
	v_add_f32_e32 v50, v53, v69
	v_pk_add_f32 v[56:57], v[80:81], 1.0 op_sel_hi:[1,0]
	v_mul_f32_e32 v50, 0xbfb8aa3b, v50
	v_exp_f32_e32 v55, v50
	s_waitcnt vmcnt(0)
; __device__ __forceinline__ float sigmoidf_(float x) { return 1.0f / (1.0f + __expf(-x)); }
;     template <int GI>
;     __device__ __forceinline__ void body(const f32x4 (&acc)[2][2][4][2], int row0, int colt) const {
;     ...
;             for (int ai = 0; ai < 2; ++ai)
; #pragma unroll
;                 for (int m = 0; m < 4; ++m) {
;                     const size_t row = (size_t)(row0 + ai * 128 + m * 16);
;                     f32x4 x0 = acc[ai][bj][m][0] + b0, x1 = acc[ai][bj][m][1] + b1;
;                     if (GI == 0) {
; #pragma unroll
;                         for (int j = 0; j < 4; ++j) {
;                             x0[j] = 0.6065306597126334f * sigmoidf_(x0[j]); x1[j] = 0.6065306597126334f * sigmoidf_(x1[j]); }
;                         *(u32x4*)(DEC + row * DM + c) = pack8(x0, x1);
;                     } else if (GI == 1) {
; #pragma unroll
;                         for (int j = 0; j < 4; ++j) { x0[j] = sigmoidf_(x0[j]); x1[j] = sigmoidf_(x1[j]); }
;                         *(u32x4*)(Ab + row * DM + c) = pack8(x0, x1);
;                     } else if (GI == 2) {
;                         *(u32x4*)(Gb + row * DM + c) = pack8(x0, x1);
;                     } else {
;                         h16* vp = C1 + row * LDC1 + 4096 + c;
;                         const h16x8 vv = *(const h16x8*)vp; const h16x8 vf = *(const h16x8*)(VF + row * DM + c);
;                         f32x4 o0, o1;
; #pragma unroll
;                         for (int j = 0; j < 4; ++j) { float v = (float)vv[j], f = (float)vf[j]; o0[j] = v + (f - v) * sigmoidf_(x0[j]); v = (float)vv[4 + j]; f = (float)vf[4 + j]; o1[j] = v + (f - v) * sigmoidf_(x1[j]); }
;                         *(u32x4*)vp = pack8(o0, o1);
;                     }
;                     __builtin_amdgcn_sched_barrier(0);
	v_cvt_f32_f16_e32 v50, v62
	v_cvt_f32_f16_e32 v52, v58
	v_cvt_f32_f16_sdwa v53, v58 dst_sel:DWORD dst_unused:UNUSED_PAD src0_sel:WORD_1
	v_div_scale_f32 v58, s[0:1], v57, v57, 1.0
	v_cvt_f32_f16_sdwa v51, v62 dst_sel:DWORD dst_unused:UNUSED_PAD src0_sel:WORD_1
	v_rcp_f32_e32 v62, v58
	v_pk_add_f32 v[54:55], v[54:55], 1.0 op_sel_hi:[1,0]
	v_pk_add_f32 v[52:53], v[52:53], v[50:51] neg_lo:[0,1] neg_hi:[0,1]
	v_fma_f32 v80, -v58, v62, 1.0
	v_fmac_f32_e32 v62, v80, v62
	v_div_scale_f32 v80, vcc, 1.0, v57, 1.0
	v_mul_f32_e32 v81, v80, v62
	v_fma_f32 v84, -v58, v81, v80
	v_fmac_f32_e32 v81, v84, v62
	v_fma_f32 v58, -v58, v81, v80
	v_div_fmas_f32 v58, v58, v62, v81
	v_div_fixup_f32 v57, v58, v57, 1.0
	v_div_scale_f32 v58, s[0:1], v56, v56, 1.0
	v_rcp_f32_e32 v62, v58
	s_nop 0
	v_fma_f32 v80, -v58, v62, 1.0
	v_fmac_f32_e32 v62, v80, v62
	v_div_scale_f32 v80, vcc, 1.0, v56, 1.0
	v_mul_f32_e32 v81, v80, v62
	v_fma_f32 v84, -v58, v81, v80
	v_fmac_f32_e32 v81, v84, v62
	v_fma_f32 v58, -v58, v81, v80
	v_div_fmas_f32 v58, v58, v62, v81
	v_div_fixup_f32 v56, v58, v56, 1.0
	v_pk_fma_f32 v[50:51], v[56:57], v[52:53], v[50:51]
	v_cvt_f32_f16_e32 v56, v59
	v_cvt_f32_f16_sdwa v57, v59 dst_sel:DWORD dst_unused:UNUSED_PAD src0_sel:WORD_1
	v_pk_add_f32 v[58:59], v[78:79], 1.0 op_sel_hi:[1,0]
	v_cvt_pk_f16_f32 v50, v50, v51
	v_div_scale_f32 v51, s[0:1], v59, v59, 1.0
	v_rcp_f32_e32 v62, v51
	v_cvt_f32_f16_e32 v52, v63
	v_cvt_f32_f16_sdwa v53, v63 dst_sel:DWORD dst_unused:UNUSED_PAD src0_sel:WORD_1
	v_fma_f32 v63, -v51, v62, 1.0
	v_fmac_f32_e32 v62, v63, v62
	v_div_scale_f32 v63, vcc, 1.0, v59, 1.0
	v_mul_f32_e32 v78, v63, v62
	v_fma_f32 v79, -v51, v78, v63
	v_fmac_f32_e32 v78, v79, v62
	v_fma_f32 v51, -v51, v78, v63
	v_div_fmas_f32 v51, v51, v62, v78
	v_div_fixup_f32 v59, v51, v59, 1.0
	v_div_scale_f32 v51, s[0:1], v58, v58, 1.0
	v_rcp_f32_e32 v62, v51
	v_pk_add_f32 v[56:57], v[56:57], v[52:53] neg_lo:[0,1] neg_hi:[0,1]
	v_fma_f32 v63, -v51, v62, 1.0
	v_fmac_f32_e32 v62, v63, v62
	v_div_scale_f32 v63, vcc, 1.0, v58, 1.0
	v_mul_f32_e32 v78, v63, v62
	v_fma_f32 v79, -v51, v78, v63
	v_fmac_f32_e32 v78, v79, v62
	v_fma_f32 v51, -v51, v78, v63
	v_div_fmas_f32 v51, v51, v62, v78
	v_div_fixup_f32 v58, v51, v58, 1.0
	v_pk_fma_f32 v[52:53], v[58:59], v[56:57], v[52:53]
	v_pk_add_f32 v[58:59], v[76:77], 1.0 op_sel_hi:[1,0]
	v_cvt_f32_f16_e32 v56, v60
	v_cvt_f32_f16_sdwa v57, v60 dst_sel:DWORD dst_unused:UNUSED_PAD src0_sel:WORD_1
	v_div_scale_f32 v60, s[0:1], v59, v59, 1.0
	v_rcp_f32_e32 v62, v60
	v_cvt_pk_f16_f32 v51, v52, v53
	v_cvt_f32_f16_e32 v52, v64
	v_cvt_f32_f16_sdwa v53, v64 dst_sel:DWORD dst_unused:UNUSED_PAD src0_sel:WORD_1
	v_fma_f32 v63, -v60, v62, 1.0
	v_fmac_f32_e32 v62, v63, v62
	v_div_scale_f32 v63, vcc, 1.0, v59, 1.0
	v_mul_f32_e32 v64, v63, v62
	v_fma_f32 v76, -v60, v64, v63
	v_fmac_f32_e32 v64, v76, v62
	v_fma_f32 v60, -v60, v64, v63
	v_div_fmas_f32 v60, v60, v62, v64
	v_div_fixup_f32 v59, v60, v59, 1.0
	v_div_scale_f32 v60, s[0:1], v58, v58, 1.0
	v_rcp_f32_e32 v62, v60
	v_pk_add_f32 v[56:57], v[56:57], v[52:53] neg_lo:[0,1] neg_hi:[0,1]
	v_fma_f32 v63, -v60, v62, 1.0
	v_fmac_f32_e32 v62, v63, v62
	v_div_scale_f32 v63, vcc, 1.0, v58, 1.0
	v_mul_f32_e32 v64, v63, v62
	v_fma_f32 v76, -v60, v64, v63
	v_fmac_f32_e32 v64, v76, v62
	v_fma_f32 v60, -v60, v64, v63
	v_div_fmas_f32 v60, v60, v62, v64
	v_div_fixup_f32 v58, v60, v58, 1.0
	v_pk_fma_f32 v[52:53], v[58:59], v[56:57], v[52:53]
	v_cvt_f32_f16_e32 v58, v61
	v_cvt_pk_f16_f32 v52, v52, v53
	v_div_scale_f32 v53, s[0:1], v55, v55, 1.0
	v_rcp_f32_e32 v60, v53
	v_cvt_f32_f16_sdwa v59, v61 dst_sel:DWORD dst_unused:UNUSED_PAD src0_sel:WORD_1
	v_cvt_f32_f16_e32 v56, v65
	v_cvt_f32_f16_sdwa v57, v65 dst_sel:DWORD dst_unused:UNUSED_PAD src0_sel:WORD_1
	v_fma_f32 v61, -v53, v60, 1.0
	v_fmac_f32_e32 v60, v61, v60
	v_div_scale_f32 v61, vcc, 1.0, v55, 1.0
	v_mul_f32_e32 v62, v61, v60
	v_fma_f32 v63, -v53, v62, v61
	v_fmac_f32_e32 v62, v63, v60
	v_fma_f32 v53, -v53, v62, v61
	v_div_fmas_f32 v53, v53, v60, v62
	v_div_fixup_f32 v55, v53, v55, 1.0
	v_div_scale_f32 v53, s[0:1], v54, v54, 1.0
	v_rcp_f32_e32 v60, v53
	v_pk_add_f32 v[58:59], v[58:59], v[56:57] neg_lo:[0,1] neg_hi:[0,1]
	v_fma_f32 v61, -v53, v60, 1.0
	v_fmac_f32_e32 v60, v61, v60
	v_div_scale_f32 v61, vcc, 1.0, v54, 1.0
	v_mul_f32_e32 v62, v61, v60
	v_fma_f32 v63, -v53, v62, v61
	v_fmac_f32_e32 v62, v63, v60
	v_fma_f32 v53, -v53, v62, v61
	v_div_fmas_f32 v53, v53, v60, v62
	v_div_fixup_f32 v54, v53, v54, 1.0
	v_pk_fma_f32 v[54:55], v[54:55], v[58:59], v[56:57]
	s_nop 0
	v_cvt_pk_f16_f32 v53, v54, v55
	global_store_dwordx4 v[74:75], v[50:53], off
	v_lshl_add_u64 v[58:59], v[130:131], 0, v[82:83]
	global_load_dwordx4 v[54:57], v[58:59], off
	global_load_dwordx4 v[50:53], v[132:133], off offset:256
	v_add_f32_e32 v42, v42, v66
	v_mul_f32_e32 v42, 0xbfb8aa3b, v42
	v_exp_f32_e32 v60, v42
	v_add_f32_e32 v42, v47, v71
	v_mul_f32_e32 v42, 0xbfb8aa3b, v42
	v_exp_f32_e32 v65, v42
	v_add_f32_e32 v42, v43, v67
	v_mul_f32_e32 v42, 0xbfb8aa3b, v42
	v_add_f32_e32 v46, v46, v70
	v_exp_f32_e32 v61, v42
	v_add_f32_e32 v42, v48, v72
	v_mul_f32_e32 v46, 0xbfb8aa3b, v46
	v_mul_f32_e32 v42, 0xbfb8aa3b, v42
	v_exp_f32_e32 v64, v46
	v_exp_f32_e32 v62, v42
	v_add_f32_e32 v42, v44, v68
	v_mul_f32_e32 v42, 0xbfb8aa3b, v42
	v_exp_f32_e32 v46, v42
	v_add_f32_e32 v42, v49, v73
	v_mul_f32_e32 v42, 0xbfb8aa3b, v42
	v_exp_f32_e32 v63, v42
	v_add_f32_e32 v42, v45, v69
	v_pk_add_f32 v[48:49], v[64:65], 1.0 op_sel_hi:[1,0]
	v_mul_f32_e32 v42, 0xbfb8aa3b, v42
	v_exp_f32_e32 v47, v42
	s_waitcnt vmcnt(0)
; __device__ __forceinline__ float sigmoidf_(float x) { return 1.0f / (1.0f + __expf(-x)); }
;     template <int GI>
;     __device__ __forceinline__ void body(const f32x4 (&acc)[2][2][4][2], int row0, int colt) const {
;     ...
;             for (int ai = 0; ai < 2; ++ai)
; #pragma unroll
;                 for (int m = 0; m < 4; ++m) {
;                     const size_t row = (size_t)(row0 + ai * 128 + m * 16);
;                     f32x4 x0 = acc[ai][bj][m][0] + b0, x1 = acc[ai][bj][m][1] + b1;
;                     if (GI == 0) {
; #pragma unroll
;                         for (int j = 0; j < 4; ++j) {
;                             x0[j] = 0.6065306597126334f * sigmoidf_(x0[j]); x1[j] = 0.6065306597126334f * sigmoidf_(x1[j]); }
;                         *(u32x4*)(DEC + row * DM + c) = pack8(x0, x1);
;                     } else if (GI == 1) {
; #pragma unroll
;                         for (int j = 0; j < 4; ++j) { x0[j] = sigmoidf_(x0[j]); x1[j] = sigmoidf_(x1[j]); }
;                         *(u32x4*)(Ab + row * DM + c) = pack8(x0, x1);
;                     } else if (GI == 2) {
;                         *(u32x4*)(Gb + row * DM + c) = pack8(x0, x1);
;                     } else {
;                         h16* vp = C1 + row * LDC1 + 4096 + c;
;                         const h16x8 vv = *(const h16x8*)vp; const h16x8 vf = *(const h16x8*)(VF + row * DM + c);
;                         f32x4 o0, o1;
; #pragma unroll
;                         for (int j = 0; j < 4; ++j) { float v = (float)vv[j], f = (float)vf[j]; o0[j] = v + (f - v) * sigmoidf_(x0[j]); v = (float)vv[4 + j]; f = (float)vf[4 + j]; o1[j] = v + (f - v) * sigmoidf_(x1[j]); }
;                         *(u32x4*)vp = pack8(o0, o1);
;                     }
;                     __builtin_amdgcn_sched_barrier(0);
	v_cvt_f32_f16_e32 v42, v54
	v_cvt_f32_f16_e32 v44, v50
	v_cvt_f32_f16_sdwa v45, v50 dst_sel:DWORD dst_unused:UNUSED_PAD src0_sel:WORD_1
	v_div_scale_f32 v50, s[0:1], v49, v49, 1.0
	v_cvt_f32_f16_sdwa v43, v54 dst_sel:DWORD dst_unused:UNUSED_PAD src0_sel:WORD_1
	v_rcp_f32_e32 v54, v50
	v_pk_add_f32 v[46:47], v[46:47], 1.0 op_sel_hi:[1,0]
	v_pk_add_f32 v[44:45], v[44:45], v[42:43] neg_lo:[0,1] neg_hi:[0,1]
	v_fma_f32 v64, -v50, v54, 1.0
	v_fmac_f32_e32 v54, v64, v54
	v_div_scale_f32 v64, vcc, 1.0, v49, 1.0
	v_mul_f32_e32 v65, v64, v54
	v_fma_f32 v74, -v50, v65, v64
	v_fmac_f32_e32 v65, v74, v54
	v_fma_f32 v50, -v50, v65, v64
	v_div_fmas_f32 v50, v50, v54, v65
	v_div_fixup_f32 v49, v50, v49, 1.0
	v_div_scale_f32 v50, s[0:1], v48, v48, 1.0
	v_rcp_f32_e32 v54, v50
	s_nop 0
	v_fma_f32 v64, -v50, v54, 1.0
	v_fmac_f32_e32 v54, v64, v54
	v_div_scale_f32 v64, vcc, 1.0, v48, 1.0
	v_mul_f32_e32 v65, v64, v54
	v_fma_f32 v74, -v50, v65, v64
	v_fmac_f32_e32 v65, v74, v54
	v_fma_f32 v50, -v50, v65, v64
	v_div_fmas_f32 v50, v50, v54, v65
	v_div_fixup_f32 v48, v50, v48, 1.0
	v_pk_fma_f32 v[42:43], v[48:49], v[44:45], v[42:43]
	v_cvt_f32_f16_e32 v48, v51
	v_cvt_f32_f16_sdwa v49, v51 dst_sel:DWORD dst_unused:UNUSED_PAD src0_sel:WORD_1
	v_pk_add_f32 v[50:51], v[62:63], 1.0 op_sel_hi:[1,0]
	v_cvt_pk_f16_f32 v42, v42, v43
	v_div_scale_f32 v43, s[0:1], v51, v51, 1.0
	v_rcp_f32_e32 v54, v43
	v_cvt_f32_f16_e32 v44, v55
	v_cvt_f32_f16_sdwa v45, v55 dst_sel:DWORD dst_unused:UNUSED_PAD src0_sel:WORD_1
	v_fma_f32 v55, -v43, v54, 1.0
	v_fmac_f32_e32 v54, v55, v54
	v_div_scale_f32 v55, vcc, 1.0, v51, 1.0
	v_mul_f32_e32 v62, v55, v54
	v_fma_f32 v63, -v43, v62, v55
	v_fmac_f32_e32 v62, v63, v54
	v_fma_f32 v43, -v43, v62, v55
	v_div_fmas_f32 v43, v43, v54, v62
	v_div_fixup_f32 v51, v43, v51, 1.0
	v_div_scale_f32 v43, s[0:1], v50, v50, 1.0
	v_rcp_f32_e32 v54, v43
	v_pk_add_f32 v[48:49], v[48:49], v[44:45] neg_lo:[0,1] neg_hi:[0,1]
	v_fma_f32 v55, -v43, v54, 1.0
	v_fmac_f32_e32 v54, v55, v54
	v_div_scale_f32 v55, vcc, 1.0, v50, 1.0
	v_mul_f32_e32 v62, v55, v54
	v_fma_f32 v63, -v43, v62, v55
	v_fmac_f32_e32 v62, v63, v54
	v_fma_f32 v43, -v43, v62, v55
	v_div_fmas_f32 v43, v43, v54, v62
	v_div_fixup_f32 v50, v43, v50, 1.0
	v_pk_fma_f32 v[44:45], v[50:51], v[48:49], v[44:45]
	v_pk_add_f32 v[50:51], v[60:61], 1.0 op_sel_hi:[1,0]
	v_cvt_f32_f16_e32 v48, v52
	v_cvt_f32_f16_sdwa v49, v52 dst_sel:DWORD dst_unused:UNUSED_PAD src0_sel:WORD_1
	v_div_scale_f32 v52, s[0:1], v51, v51, 1.0
	v_rcp_f32_e32 v54, v52
	v_cvt_pk_f16_f32 v43, v44, v45
	v_cvt_f32_f16_e32 v44, v56
	v_cvt_f32_f16_sdwa v45, v56 dst_sel:DWORD dst_unused:UNUSED_PAD src0_sel:WORD_1
	v_fma_f32 v55, -v52, v54, 1.0
	v_fmac_f32_e32 v54, v55, v54
	v_div_scale_f32 v55, vcc, 1.0, v51, 1.0
	v_mul_f32_e32 v56, v55, v54
	v_fma_f32 v60, -v52, v56, v55
	v_fmac_f32_e32 v56, v60, v54
	v_fma_f32 v52, -v52, v56, v55
	v_div_fmas_f32 v52, v52, v54, v56
	v_div_fixup_f32 v51, v52, v51, 1.0
	v_div_scale_f32 v52, s[0:1], v50, v50, 1.0
	v_rcp_f32_e32 v54, v52
	v_pk_add_f32 v[48:49], v[48:49], v[44:45] neg_lo:[0,1] neg_hi:[0,1]
	v_fma_f32 v55, -v52, v54, 1.0
	v_fmac_f32_e32 v54, v55, v54
	v_div_scale_f32 v55, vcc, 1.0, v50, 1.0
	v_mul_f32_e32 v56, v55, v54
	v_fma_f32 v60, -v52, v56, v55
	v_fmac_f32_e32 v56, v60, v54
	v_fma_f32 v52, -v52, v56, v55
	v_div_fmas_f32 v52, v52, v54, v56
	v_div_fixup_f32 v50, v52, v50, 1.0
	v_pk_fma_f32 v[44:45], v[50:51], v[48:49], v[44:45]
	v_cvt_f32_f16_e32 v50, v53
	v_cvt_pk_f16_f32 v44, v44, v45
	v_div_scale_f32 v45, s[0:1], v47, v47, 1.0
	v_rcp_f32_e32 v52, v45
	v_cvt_f32_f16_sdwa v51, v53 dst_sel:DWORD dst_unused:UNUSED_PAD src0_sel:WORD_1
	v_cvt_f32_f16_e32 v48, v57
	v_cvt_f32_f16_sdwa v49, v57 dst_sel:DWORD dst_unused:UNUSED_PAD src0_sel:WORD_1
	v_fma_f32 v53, -v45, v52, 1.0
	v_fmac_f32_e32 v52, v53, v52
	v_div_scale_f32 v53, vcc, 1.0, v47, 1.0
	v_mul_f32_e32 v54, v53, v52
	v_fma_f32 v55, -v45, v54, v53
	v_fmac_f32_e32 v54, v55, v52
	v_fma_f32 v45, -v45, v54, v53
	v_div_fmas_f32 v45, v45, v52, v54
	v_div_fixup_f32 v47, v45, v47, 1.0
	v_div_scale_f32 v45, s[0:1], v46, v46, 1.0
	v_rcp_f32_e32 v52, v45
	v_pk_add_f32 v[50:51], v[50:51], v[48:49] neg_lo:[0,1] neg_hi:[0,1]
	v_fma_f32 v53, -v45, v52, 1.0
	v_fmac_f32_e32 v52, v53, v52
	v_div_scale_f32 v53, vcc, 1.0, v46, 1.0
	v_mul_f32_e32 v54, v53, v52
	v_fma_f32 v55, -v45, v54, v53
	v_fmac_f32_e32 v54, v55, v52
	v_fma_f32 v45, -v45, v54, v53
	v_div_fmas_f32 v45, v45, v52, v54
	v_div_fixup_f32 v46, v45, v46, 1.0
	v_pk_fma_f32 v[46:47], v[46:47], v[50:51], v[48:49]
	s_nop 0
	v_cvt_pk_f16_f32 v45, v46, v47
	global_store_dwordx4 v[58:59], v[42:45], off
	v_lshl_add_u64 v[50:51], v[122:123], 0, v[82:83]
	global_load_dwordx4 v[46:49], v[50:51], off
	global_load_dwordx4 v[42:45], v[124:125], off offset:256
	v_add_f32_e32 v34, v34, v66
	v_mul_f32_e32 v34, 0xbfb8aa3b, v34
	v_exp_f32_e32 v52, v34
	v_add_f32_e32 v34, v39, v71
	v_mul_f32_e32 v34, 0xbfb8aa3b, v34
	v_exp_f32_e32 v57, v34
	v_add_f32_e32 v34, v35, v67
	v_mul_f32_e32 v34, 0xbfb8aa3b, v34
	v_add_f32_e32 v38, v38, v70
	v_exp_f32_e32 v53, v34
	v_add_f32_e32 v34, v40, v72
	v_mul_f32_e32 v38, 0xbfb8aa3b, v38
	v_mul_f32_e32 v34, 0xbfb8aa3b, v34
	v_exp_f32_e32 v56, v38
	v_exp_f32_e32 v54, v34
	v_add_f32_e32 v34, v36, v68
	v_mul_f32_e32 v34, 0xbfb8aa3b, v34
	v_exp_f32_e32 v38, v34
	v_add_f32_e32 v34, v41, v73
	v_mul_f32_e32 v34, 0xbfb8aa3b, v34
	v_exp_f32_e32 v55, v34
	v_add_f32_e32 v34, v37, v69
	v_pk_add_f32 v[40:41], v[56:57], 1.0 op_sel_hi:[1,0]
	v_mul_f32_e32 v34, 0xbfb8aa3b, v34
	v_exp_f32_e32 v39, v34
	s_waitcnt vmcnt(0)
; __device__ __forceinline__ float sigmoidf_(float x) { return 1.0f / (1.0f + __expf(-x)); }
;     template <int GI>
;     __device__ __forceinline__ void body(const f32x4 (&acc)[2][2][4][2], int row0, int colt) const {
;     ...
;             for (int ai = 0; ai < 2; ++ai)
; #pragma unroll
;                 for (int m = 0; m < 4; ++m) {
;                     const size_t row = (size_t)(row0 + ai * 128 + m * 16);
;                     f32x4 x0 = acc[ai][bj][m][0] + b0, x1 = acc[ai][bj][m][1] + b1;
;                     if (GI == 0) {
; #pragma unroll
;                         for (int j = 0; j < 4; ++j) {
;                             x0[j] = 0.6065306597126334f * sigmoidf_(x0[j]); x1[j] = 0.6065306597126334f * sigmoidf_(x1[j]); }
;                         *(u32x4*)(DEC + row * DM + c) = pack8(x0, x1);
;                     } else if (GI == 1) {
; #pragma unroll
;                         for (int j = 0; j < 4; ++j) { x0[j] = sigmoidf_(x0[j]); x1[j] = sigmoidf_(x1[j]); }
;                         *(u32x4*)(Ab + row * DM + c) = pack8(x0, x1);
;                     } else if (GI == 2) {
;                         *(u32x4*)(Gb + row * DM + c) = pack8(x0, x1);
;                     } else {
;                         h16* vp = C1 + row * LDC1 + 4096 + c;
;                         const h16x8 vv = *(const h16x8*)vp; const h16x8 vf = *(const h16x8*)(VF + row * DM + c);
;                         f32x4 o0, o1;
; #pragma unroll
;                         for (int j = 0; j < 4; ++j) { float v = (float)vv[j], f = (float)vf[j]; o0[j] = v + (f - v) * sigmoidf_(x0[j]); v = (float)vv[4 + j]; f = (float)vf[4 + j]; o1[j] = v + (f - v) * sigmoidf_(x1[j]); }
;                         *(u32x4*)vp = pack8(o0, o1);
;                     }
;                     __builtin_amdgcn_sched_barrier(0);
	v_cvt_f32_f16_e32 v34, v46
	v_cvt_f32_f16_e32 v36, v42
	v_cvt_f32_f16_sdwa v37, v42 dst_sel:DWORD dst_unused:UNUSED_PAD src0_sel:WORD_1
	v_div_scale_f32 v42, s[0:1], v41, v41, 1.0
	v_cvt_f32_f16_sdwa v35, v46 dst_sel:DWORD dst_unused:UNUSED_PAD src0_sel:WORD_1
	v_rcp_f32_e32 v46, v42
	v_pk_add_f32 v[38:39], v[38:39], 1.0 op_sel_hi:[1,0]
	v_pk_add_f32 v[36:37], v[36:37], v[34:35] neg_lo:[0,1] neg_hi:[0,1]
	v_fma_f32 v56, -v42, v46, 1.0
	v_fmac_f32_e32 v46, v56, v46
	v_div_scale_f32 v56, vcc, 1.0, v41, 1.0
	v_mul_f32_e32 v57, v56, v46
	v_fma_f32 v58, -v42, v57, v56
	v_fmac_f32_e32 v57, v58, v46
	v_fma_f32 v42, -v42, v57, v56
	v_div_fmas_f32 v42, v42, v46, v57
	v_div_fixup_f32 v41, v42, v41, 1.0
	v_div_scale_f32 v42, s[0:1], v40, v40, 1.0
	v_rcp_f32_e32 v46, v42
	s_nop 0
	v_fma_f32 v56, -v42, v46, 1.0
	v_fmac_f32_e32 v46, v56, v46
	v_div_scale_f32 v56, vcc, 1.0, v40, 1.0
	v_mul_f32_e32 v57, v56, v46
	v_fma_f32 v58, -v42, v57, v56
	v_fmac_f32_e32 v57, v58, v46
	v_fma_f32 v42, -v42, v57, v56
	v_div_fmas_f32 v42, v42, v46, v57
	v_div_fixup_f32 v40, v42, v40, 1.0
	v_pk_fma_f32 v[34:35], v[40:41], v[36:37], v[34:35]
	v_cvt_f32_f16_e32 v40, v43
	v_cvt_f32_f16_sdwa v41, v43 dst_sel:DWORD dst_unused:UNUSED_PAD src0_sel:WORD_1
	v_pk_add_f32 v[42:43], v[54:55], 1.0 op_sel_hi:[1,0]
	v_cvt_pk_f16_f32 v34, v34, v35
	v_div_scale_f32 v35, s[0:1], v43, v43, 1.0
	v_rcp_f32_e32 v46, v35
	v_cvt_f32_f16_e32 v36, v47
	v_cvt_f32_f16_sdwa v37, v47 dst_sel:DWORD dst_unused:UNUSED_PAD src0_sel:WORD_1
	v_fma_f32 v47, -v35, v46, 1.0
	v_fmac_f32_e32 v46, v47, v46
	v_div_scale_f32 v47, vcc, 1.0, v43, 1.0
	v_mul_f32_e32 v54, v47, v46
	v_fma_f32 v55, -v35, v54, v47
	v_fmac_f32_e32 v54, v55, v46
	v_fma_f32 v35, -v35, v54, v47
	v_div_fmas_f32 v35, v35, v46, v54
	v_div_fixup_f32 v43, v35, v43, 1.0
	v_div_scale_f32 v35, s[0:1], v42, v42, 1.0
	v_rcp_f32_e32 v46, v35
	v_pk_add_f32 v[40:41], v[40:41], v[36:37] neg_lo:[0,1] neg_hi:[0,1]
	v_fma_f32 v47, -v35, v46, 1.0
	v_fmac_f32_e32 v46, v47, v46
	v_div_scale_f32 v47, vcc, 1.0, v42, 1.0
	v_mul_f32_e32 v54, v47, v46
	v_fma_f32 v55, -v35, v54, v47
	v_fmac_f32_e32 v54, v55, v46
	v_fma_f32 v35, -v35, v54, v47
	v_div_fmas_f32 v35, v35, v46, v54
	v_div_fixup_f32 v42, v35, v42, 1.0
	v_pk_fma_f32 v[36:37], v[42:43], v[40:41], v[36:37]
	v_pk_add_f32 v[42:43], v[52:53], 1.0 op_sel_hi:[1,0]
	v_cvt_f32_f16_e32 v40, v44
	v_cvt_f32_f16_sdwa v41, v44 dst_sel:DWORD dst_unused:UNUSED_PAD src0_sel:WORD_1
	v_div_scale_f32 v44, s[0:1], v43, v43, 1.0
	v_rcp_f32_e32 v46, v44
	v_cvt_pk_f16_f32 v35, v36, v37
	v_cvt_f32_f16_e32 v36, v48
	v_cvt_f32_f16_sdwa v37, v48 dst_sel:DWORD dst_unused:UNUSED_PAD src0_sel:WORD_1
	v_fma_f32 v47, -v44, v46, 1.0
	v_fmac_f32_e32 v46, v47, v46
	v_div_scale_f32 v47, vcc, 1.0, v43, 1.0
	v_mul_f32_e32 v48, v47, v46
	v_fma_f32 v52, -v44, v48, v47
	v_fmac_f32_e32 v48, v52, v46
	v_fma_f32 v44, -v44, v48, v47
	v_div_fmas_f32 v44, v44, v46, v48
	v_div_fixup_f32 v43, v44, v43, 1.0
	v_div_scale_f32 v44, s[0:1], v42, v42, 1.0
	v_rcp_f32_e32 v46, v44
	v_pk_add_f32 v[40:41], v[40:41], v[36:37] neg_lo:[0,1] neg_hi:[0,1]
	v_fma_f32 v47, -v44, v46, 1.0
	v_fmac_f32_e32 v46, v47, v46
	v_div_scale_f32 v47, vcc, 1.0, v42, 1.0
	v_mul_f32_e32 v48, v47, v46
	v_fma_f32 v52, -v44, v48, v47
	v_fmac_f32_e32 v48, v52, v46
	v_fma_f32 v44, -v44, v48, v47
	v_div_fmas_f32 v44, v44, v46, v48
	v_div_fixup_f32 v42, v44, v42, 1.0
	v_pk_fma_f32 v[36:37], v[42:43], v[40:41], v[36:37]
	v_cvt_f32_f16_e32 v42, v45
	v_cvt_pk_f16_f32 v36, v36, v37
	v_div_scale_f32 v37, s[0:1], v39, v39, 1.0
	v_rcp_f32_e32 v44, v37
	v_cvt_f32_f16_sdwa v43, v45 dst_sel:DWORD dst_unused:UNUSED_PAD src0_sel:WORD_1
	v_cvt_f32_f16_e32 v40, v49
	v_cvt_f32_f16_sdwa v41, v49 dst_sel:DWORD dst_unused:UNUSED_PAD src0_sel:WORD_1
	v_fma_f32 v45, -v37, v44, 1.0
	v_fmac_f32_e32 v44, v45, v44
	v_div_scale_f32 v45, vcc, 1.0, v39, 1.0
	v_mul_f32_e32 v46, v45, v44
	v_fma_f32 v47, -v37, v46, v45
	v_fmac_f32_e32 v46, v47, v44
	v_fma_f32 v37, -v37, v46, v45
	v_div_fmas_f32 v37, v37, v44, v46
	v_div_fixup_f32 v39, v37, v39, 1.0
	v_div_scale_f32 v37, s[0:1], v38, v38, 1.0
	v_rcp_f32_e32 v44, v37
	v_pk_add_f32 v[42:43], v[42:43], v[40:41] neg_lo:[0,1] neg_hi:[0,1]
	v_fma_f32 v45, -v37, v44, 1.0
	v_fmac_f32_e32 v44, v45, v44
	v_div_scale_f32 v45, vcc, 1.0, v38, 1.0
	v_mul_f32_e32 v46, v45, v44
	v_fma_f32 v47, -v37, v46, v45
	v_fmac_f32_e32 v46, v47, v44
	v_fma_f32 v37, -v37, v46, v45
	v_div_fmas_f32 v37, v37, v44, v46
	v_div_fixup_f32 v38, v37, v38, 1.0
	v_pk_fma_f32 v[38:39], v[38:39], v[42:43], v[40:41]
	s_nop 0
	v_cvt_pk_f16_f32 v37, v38, v39
	global_store_dwordx4 v[50:51], v[34:37], off
	v_lshl_add_u64 v[42:43], v[114:115], 0, v[82:83]
	global_load_dwordx4 v[38:41], v[42:43], off
	global_load_dwordx4 v[34:37], v[116:117], off offset:256
	v_add_f32_e32 v26, v26, v66
	v_mul_f32_e32 v26, 0xbfb8aa3b, v26
	v_exp_f32_e32 v44, v26
	v_add_f32_e32 v26, v31, v71
	v_mul_f32_e32 v26, 0xbfb8aa3b, v26
	v_exp_f32_e32 v49, v26
	v_add_f32_e32 v26, v27, v67
	v_mul_f32_e32 v26, 0xbfb8aa3b, v26
	v_add_f32_e32 v30, v30, v70
	v_exp_f32_e32 v45, v26
	v_add_f32_e32 v26, v32, v72
	v_mul_f32_e32 v30, 0xbfb8aa3b, v30
	v_mul_f32_e32 v26, 0xbfb8aa3b, v26
	v_exp_f32_e32 v48, v30
	v_exp_f32_e32 v46, v26
	v_add_f32_e32 v26, v28, v68
	v_mul_f32_e32 v26, 0xbfb8aa3b, v26
	v_exp_f32_e32 v30, v26
	v_add_f32_e32 v26, v33, v73
	v_mul_f32_e32 v26, 0xbfb8aa3b, v26
	v_exp_f32_e32 v47, v26
	v_add_f32_e32 v26, v29, v69
	v_pk_add_f32 v[32:33], v[48:49], 1.0 op_sel_hi:[1,0]
	v_mul_f32_e32 v26, 0xbfb8aa3b, v26
	v_exp_f32_e32 v31, v26
	s_waitcnt vmcnt(0)
; __device__ __forceinline__ float sigmoidf_(float x) { return 1.0f / (1.0f + __expf(-x)); }
;     template <int GI>
;     __device__ __forceinline__ void body(const f32x4 (&acc)[2][2][4][2], int row0, int colt) const {
;     ...
;             for (int ai = 0; ai < 2; ++ai)
; #pragma unroll
;                 for (int m = 0; m < 4; ++m) {
;                     const size_t row = (size_t)(row0 + ai * 128 + m * 16);
;                     f32x4 x0 = acc[ai][bj][m][0] + b0, x1 = acc[ai][bj][m][1] + b1;
;                     if (GI == 0) {
; #pragma unroll
;                         for (int j = 0; j < 4; ++j) {
;                             x0[j] = 0.6065306597126334f * sigmoidf_(x0[j]); x1[j] = 0.6065306597126334f * sigmoidf_(x1[j]); }
;                         *(u32x4*)(DEC + row * DM + c) = pack8(x0, x1);
;                     } else if (GI == 1) {
; #pragma unroll
;                         for (int j = 0; j < 4; ++j) { x0[j] = sigmoidf_(x0[j]); x1[j] = sigmoidf_(x1[j]); }
;                         *(u32x4*)(Ab + row * DM + c) = pack8(x0, x1);
;                     } else if (GI == 2) {
;                         *(u32x4*)(Gb + row * DM + c) = pack8(x0, x1);
;                     } else {
;                         h16* vp = C1 + row * LDC1 + 4096 + c;
;                         const h16x8 vv = *(const h16x8*)vp; const h16x8 vf = *(const h16x8*)(VF + row * DM + c);
;                         f32x4 o0, o1;
; #pragma unroll
;                         for (int j = 0; j < 4; ++j) { float v = (float)vv[j], f = (float)vf[j]; o0[j] = v + (f - v) * sigmoidf_(x0[j]); v = (float)vv[4 + j]; f = (float)vf[4 + j]; o1[j] = v + (f - v) * sigmoidf_(x1[j]); }
;                         *(u32x4*)vp = pack8(o0, o1);
;                     }
;                     __builtin_amdgcn_sched_barrier(0);
	v_cvt_f32_f16_e32 v26, v38
	v_cvt_f32_f16_e32 v28, v34
	v_cvt_f32_f16_sdwa v29, v34 dst_sel:DWORD dst_unused:UNUSED_PAD src0_sel:WORD_1
	v_div_scale_f32 v34, s[0:1], v33, v33, 1.0
	v_cvt_f32_f16_sdwa v27, v38 dst_sel:DWORD dst_unused:UNUSED_PAD src0_sel:WORD_1
	v_rcp_f32_e32 v38, v34
	v_pk_add_f32 v[30:31], v[30:31], 1.0 op_sel_hi:[1,0]
	v_pk_add_f32 v[28:29], v[28:29], v[26:27] neg_lo:[0,1] neg_hi:[0,1]
	v_fma_f32 v48, -v34, v38, 1.0
	v_fmac_f32_e32 v38, v48, v38
	v_div_scale_f32 v48, vcc, 1.0, v33, 1.0
	v_mul_f32_e32 v49, v48, v38
	v_fma_f32 v50, -v34, v49, v48
	v_fmac_f32_e32 v49, v50, v38
	v_fma_f32 v34, -v34, v49, v48
	v_div_fmas_f32 v34, v34, v38, v49
	v_div_fixup_f32 v33, v34, v33, 1.0
	v_div_scale_f32 v34, s[0:1], v32, v32, 1.0
	v_rcp_f32_e32 v38, v34
	s_nop 0
	v_fma_f32 v48, -v34, v38, 1.0
	v_fmac_f32_e32 v38, v48, v38
	v_div_scale_f32 v48, vcc, 1.0, v32, 1.0
	v_mul_f32_e32 v49, v48, v38
	v_fma_f32 v50, -v34, v49, v48
	v_fmac_f32_e32 v49, v50, v38
	v_fma_f32 v34, -v34, v49, v48
	v_div_fmas_f32 v34, v34, v38, v49
	v_div_fixup_f32 v32, v34, v32, 1.0
	v_pk_fma_f32 v[26:27], v[32:33], v[28:29], v[26:27]
	v_cvt_f32_f16_e32 v32, v35
	v_cvt_f32_f16_sdwa v33, v35 dst_sel:DWORD dst_unused:UNUSED_PAD src0_sel:WORD_1
	v_pk_add_f32 v[34:35], v[46:47], 1.0 op_sel_hi:[1,0]
	v_cvt_pk_f16_f32 v26, v26, v27
	v_div_scale_f32 v27, s[0:1], v35, v35, 1.0
	v_rcp_f32_e32 v38, v27
	v_cvt_f32_f16_e32 v28, v39
	v_cvt_f32_f16_sdwa v29, v39 dst_sel:DWORD dst_unused:UNUSED_PAD src0_sel:WORD_1
	v_fma_f32 v39, -v27, v38, 1.0
	v_fmac_f32_e32 v38, v39, v38
	v_div_scale_f32 v39, vcc, 1.0, v35, 1.0
	v_mul_f32_e32 v46, v39, v38
	v_fma_f32 v47, -v27, v46, v39
	v_fmac_f32_e32 v46, v47, v38
	v_fma_f32 v27, -v27, v46, v39
	v_div_fmas_f32 v27, v27, v38, v46
	v_div_fixup_f32 v35, v27, v35, 1.0
	v_div_scale_f32 v27, s[0:1], v34, v34, 1.0
	v_rcp_f32_e32 v38, v27
	v_pk_add_f32 v[32:33], v[32:33], v[28:29] neg_lo:[0,1] neg_hi:[0,1]
	v_fma_f32 v39, -v27, v38, 1.0
	v_fmac_f32_e32 v38, v39, v38
	v_div_scale_f32 v39, vcc, 1.0, v34, 1.0
	v_mul_f32_e32 v46, v39, v38
	v_fma_f32 v47, -v27, v46, v39
	v_fmac_f32_e32 v46, v47, v38
	v_fma_f32 v27, -v27, v46, v39
	v_div_fmas_f32 v27, v27, v38, v46
	v_div_fixup_f32 v34, v27, v34, 1.0
	v_pk_fma_f32 v[28:29], v[34:35], v[32:33], v[28:29]
	v_pk_add_f32 v[34:35], v[44:45], 1.0 op_sel_hi:[1,0]
	v_cvt_f32_f16_e32 v32, v36
	v_cvt_f32_f16_sdwa v33, v36 dst_sel:DWORD dst_unused:UNUSED_PAD src0_sel:WORD_1
	v_div_scale_f32 v36, s[0:1], v35, v35, 1.0
	v_rcp_f32_e32 v38, v36
	v_cvt_pk_f16_f32 v27, v28, v29
	v_cvt_f32_f16_e32 v28, v40
	v_cvt_f32_f16_sdwa v29, v40 dst_sel:DWORD dst_unused:UNUSED_PAD src0_sel:WORD_1
	v_fma_f32 v39, -v36, v38, 1.0
	v_fmac_f32_e32 v38, v39, v38
	v_div_scale_f32 v39, vcc, 1.0, v35, 1.0
	v_mul_f32_e32 v40, v39, v38
	v_fma_f32 v44, -v36, v40, v39
	v_fmac_f32_e32 v40, v44, v38
	v_fma_f32 v36, -v36, v40, v39
	v_div_fmas_f32 v36, v36, v38, v40
	v_div_fixup_f32 v35, v36, v35, 1.0
	v_div_scale_f32 v36, s[0:1], v34, v34, 1.0
	v_rcp_f32_e32 v38, v36
	v_pk_add_f32 v[32:33], v[32:33], v[28:29] neg_lo:[0,1] neg_hi:[0,1]
	v_fma_f32 v39, -v36, v38, 1.0
	v_fmac_f32_e32 v38, v39, v38
	v_div_scale_f32 v39, vcc, 1.0, v34, 1.0
	v_mul_f32_e32 v40, v39, v38
	v_fma_f32 v44, -v36, v40, v39
	v_fmac_f32_e32 v40, v44, v38
	v_fma_f32 v36, -v36, v40, v39
	v_div_fmas_f32 v36, v36, v38, v40
	v_div_fixup_f32 v34, v36, v34, 1.0
	v_pk_fma_f32 v[28:29], v[34:35], v[32:33], v[28:29]
	v_cvt_f32_f16_e32 v34, v37
	v_cvt_pk_f16_f32 v28, v28, v29
	v_div_scale_f32 v29, s[0:1], v31, v31, 1.0
	v_rcp_f32_e32 v36, v29
	v_cvt_f32_f16_sdwa v35, v37 dst_sel:DWORD dst_unused:UNUSED_PAD src0_sel:WORD_1
	v_cvt_f32_f16_e32 v32, v41
	v_cvt_f32_f16_sdwa v33, v41 dst_sel:DWORD dst_unused:UNUSED_PAD src0_sel:WORD_1
	v_fma_f32 v37, -v29, v36, 1.0
	v_fmac_f32_e32 v36, v37, v36
	v_div_scale_f32 v37, vcc, 1.0, v31, 1.0
	v_mul_f32_e32 v38, v37, v36
	v_fma_f32 v39, -v29, v38, v37
	v_fmac_f32_e32 v38, v39, v36
	v_fma_f32 v29, -v29, v38, v37
	v_div_fmas_f32 v29, v29, v36, v38
	v_div_fixup_f32 v31, v29, v31, 1.0
	v_div_scale_f32 v29, s[0:1], v30, v30, 1.0
	v_rcp_f32_e32 v36, v29
	v_pk_add_f32 v[34:35], v[34:35], v[32:33] neg_lo:[0,1] neg_hi:[0,1]
	v_fma_f32 v37, -v29, v36, 1.0
	v_fmac_f32_e32 v36, v37, v36
	v_div_scale_f32 v37, vcc, 1.0, v30, 1.0
	v_mul_f32_e32 v38, v37, v36
	v_fma_f32 v39, -v29, v38, v37
	v_fmac_f32_e32 v38, v39, v36
	v_fma_f32 v29, -v29, v38, v37
	v_div_fmas_f32 v29, v29, v36, v38
	v_div_fixup_f32 v30, v29, v30, 1.0
	v_pk_fma_f32 v[30:31], v[30:31], v[34:35], v[32:33]
	s_nop 0
	v_cvt_pk_f16_f32 v29, v30, v31
	global_store_dwordx4 v[42:43], v[26:29], off
	v_lshl_add_u64 v[34:35], v[106:107], 0, v[82:83]
	global_load_dwordx4 v[30:33], v[34:35], off
	global_load_dwordx4 v[26:29], v[108:109], off offset:256
	v_add_f32_e32 v18, v18, v66
	v_mul_f32_e32 v18, 0xbfb8aa3b, v18
	v_exp_f32_e32 v36, v18
	v_add_f32_e32 v18, v23, v71
	v_mul_f32_e32 v18, 0xbfb8aa3b, v18
	v_exp_f32_e32 v41, v18
	v_add_f32_e32 v18, v19, v67
	v_mul_f32_e32 v18, 0xbfb8aa3b, v18
	v_add_f32_e32 v22, v22, v70
	v_exp_f32_e32 v37, v18
	v_add_f32_e32 v18, v24, v72
	v_mul_f32_e32 v22, 0xbfb8aa3b, v22
	v_mul_f32_e32 v18, 0xbfb8aa3b, v18
	v_exp_f32_e32 v40, v22
	v_exp_f32_e32 v38, v18
	v_add_f32_e32 v18, v20, v68
	v_mul_f32_e32 v18, 0xbfb8aa3b, v18
	v_exp_f32_e32 v22, v18
	v_add_f32_e32 v18, v25, v73
	v_mul_f32_e32 v18, 0xbfb8aa3b, v18
	v_exp_f32_e32 v39, v18
	v_add_f32_e32 v18, v21, v69
	v_pk_add_f32 v[24:25], v[40:41], 1.0 op_sel_hi:[1,0]
	v_mul_f32_e32 v18, 0xbfb8aa3b, v18
	v_exp_f32_e32 v23, v18
	s_waitcnt vmcnt(0)
; __device__ __forceinline__ float sigmoidf_(float x) { return 1.0f / (1.0f + __expf(-x)); }
;     template <int GI>
;     __device__ __forceinline__ void body(const f32x4 (&acc)[2][2][4][2], int row0, int colt) const {
;     ...
;             for (int ai = 0; ai < 2; ++ai)
; #pragma unroll
;                 for (int m = 0; m < 4; ++m) {
;                     const size_t row = (size_t)(row0 + ai * 128 + m * 16);
;                     f32x4 x0 = acc[ai][bj][m][0] + b0, x1 = acc[ai][bj][m][1] + b1;
;                     if (GI == 0) {
; #pragma unroll
;                         for (int j = 0; j < 4; ++j) {
;                             x0[j] = 0.6065306597126334f * sigmoidf_(x0[j]); x1[j] = 0.6065306597126334f * sigmoidf_(x1[j]); }
;                         *(u32x4*)(DEC + row * DM + c) = pack8(x0, x1);
;                     } else if (GI == 1) {
; #pragma unroll
;                         for (int j = 0; j < 4; ++j) { x0[j] = sigmoidf_(x0[j]); x1[j] = sigmoidf_(x1[j]); }
;                         *(u32x4*)(Ab + row * DM + c) = pack8(x0, x1);
;                     } else if (GI == 2) {
;                         *(u32x4*)(Gb + row * DM + c) = pack8(x0, x1);
;                     } else {
;                         h16* vp = C1 + row * LDC1 + 4096 + c;
;                         const h16x8 vv = *(const h16x8*)vp; const h16x8 vf = *(const h16x8*)(VF + row * DM + c);
;                         f32x4 o0, o1;
; #pragma unroll
;                         for (int j = 0; j < 4; ++j) { float v = (float)vv[j], f = (float)vf[j]; o0[j] = v + (f - v) * sigmoidf_(x0[j]); v = (float)vv[4 + j]; f = (float)vf[4 + j]; o1[j] = v + (f - v) * sigmoidf_(x1[j]); }
;                         *(u32x4*)vp = pack8(o0, o1);
;                     }
;                     __builtin_amdgcn_sched_barrier(0);
	v_cvt_f32_f16_e32 v18, v30
	v_cvt_f32_f16_e32 v20, v26
	v_cvt_f32_f16_sdwa v21, v26 dst_sel:DWORD dst_unused:UNUSED_PAD src0_sel:WORD_1
	v_div_scale_f32 v26, s[0:1], v25, v25, 1.0
	v_cvt_f32_f16_sdwa v19, v30 dst_sel:DWORD dst_unused:UNUSED_PAD src0_sel:WORD_1
	v_rcp_f32_e32 v30, v26
	v_pk_add_f32 v[22:23], v[22:23], 1.0 op_sel_hi:[1,0]
	v_pk_add_f32 v[20:21], v[20:21], v[18:19] neg_lo:[0,1] neg_hi:[0,1]
	v_fma_f32 v40, -v26, v30, 1.0
	v_fmac_f32_e32 v30, v40, v30
	v_div_scale_f32 v40, vcc, 1.0, v25, 1.0
	v_mul_f32_e32 v41, v40, v30
	v_fma_f32 v42, -v26, v41, v40
	v_fmac_f32_e32 v41, v42, v30
	v_fma_f32 v26, -v26, v41, v40
	v_div_fmas_f32 v26, v26, v30, v41
	v_div_fixup_f32 v25, v26, v25, 1.0
	v_div_scale_f32 v26, s[0:1], v24, v24, 1.0
	v_rcp_f32_e32 v30, v26
	s_nop 0
	v_fma_f32 v40, -v26, v30, 1.0
	v_fmac_f32_e32 v30, v40, v30
	v_div_scale_f32 v40, vcc, 1.0, v24, 1.0
	v_mul_f32_e32 v41, v40, v30
	v_fma_f32 v42, -v26, v41, v40
	v_fmac_f32_e32 v41, v42, v30
	v_fma_f32 v26, -v26, v41, v40
	v_div_fmas_f32 v26, v26, v30, v41
	v_div_fixup_f32 v24, v26, v24, 1.0
	v_pk_fma_f32 v[18:19], v[24:25], v[20:21], v[18:19]
	v_cvt_f32_f16_e32 v24, v27
	v_cvt_f32_f16_sdwa v25, v27 dst_sel:DWORD dst_unused:UNUSED_PAD src0_sel:WORD_1
	v_pk_add_f32 v[26:27], v[38:39], 1.0 op_sel_hi:[1,0]
	v_cvt_pk_f16_f32 v18, v18, v19
	v_div_scale_f32 v19, s[0:1], v27, v27, 1.0
	v_rcp_f32_e32 v30, v19
	v_cvt_f32_f16_e32 v20, v31
	v_cvt_f32_f16_sdwa v21, v31 dst_sel:DWORD dst_unused:UNUSED_PAD src0_sel:WORD_1
	v_fma_f32 v31, -v19, v30, 1.0
	v_fmac_f32_e32 v30, v31, v30
	v_div_scale_f32 v31, vcc, 1.0, v27, 1.0
	v_mul_f32_e32 v38, v31, v30
	v_fma_f32 v39, -v19, v38, v31
	v_fmac_f32_e32 v38, v39, v30
	v_fma_f32 v19, -v19, v38, v31
	v_div_fmas_f32 v19, v19, v30, v38
	v_div_fixup_f32 v27, v19, v27, 1.0
	v_div_scale_f32 v19, s[0:1], v26, v26, 1.0
	v_rcp_f32_e32 v30, v19
	v_pk_add_f32 v[24:25], v[24:25], v[20:21] neg_lo:[0,1] neg_hi:[0,1]
	v_fma_f32 v31, -v19, v30, 1.0
	v_fmac_f32_e32 v30, v31, v30
	v_div_scale_f32 v31, vcc, 1.0, v26, 1.0
	v_mul_f32_e32 v38, v31, v30
	v_fma_f32 v39, -v19, v38, v31
	v_fmac_f32_e32 v38, v39, v30
	v_fma_f32 v19, -v19, v38, v31
	v_div_fmas_f32 v19, v19, v30, v38
	v_div_fixup_f32 v26, v19, v26, 1.0
	v_pk_fma_f32 v[20:21], v[26:27], v[24:25], v[20:21]
	v_pk_add_f32 v[26:27], v[36:37], 1.0 op_sel_hi:[1,0]
	v_cvt_f32_f16_e32 v24, v28
	v_cvt_f32_f16_sdwa v25, v28 dst_sel:DWORD dst_unused:UNUSED_PAD src0_sel:WORD_1
	v_div_scale_f32 v28, s[0:1], v27, v27, 1.0
	v_rcp_f32_e32 v30, v28
	v_cvt_pk_f16_f32 v19, v20, v21
	v_cvt_f32_f16_e32 v20, v32
	v_cvt_f32_f16_sdwa v21, v32 dst_sel:DWORD dst_unused:UNUSED_PAD src0_sel:WORD_1
	v_fma_f32 v31, -v28, v30, 1.0
	v_fmac_f32_e32 v30, v31, v30
	v_div_scale_f32 v31, vcc, 1.0, v27, 1.0
	v_mul_f32_e32 v32, v31, v30
	v_fma_f32 v36, -v28, v32, v31
	v_fmac_f32_e32 v32, v36, v30
	v_fma_f32 v28, -v28, v32, v31
	v_div_fmas_f32 v28, v28, v30, v32
	v_div_fixup_f32 v27, v28, v27, 1.0
	v_div_scale_f32 v28, s[0:1], v26, v26, 1.0
	v_rcp_f32_e32 v30, v28
	v_pk_add_f32 v[24:25], v[24:25], v[20:21] neg_lo:[0,1] neg_hi:[0,1]
	v_fma_f32 v31, -v28, v30, 1.0
	v_fmac_f32_e32 v30, v31, v30
	v_div_scale_f32 v31, vcc, 1.0, v26, 1.0
	v_mul_f32_e32 v32, v31, v30
	v_fma_f32 v36, -v28, v32, v31
	v_fmac_f32_e32 v32, v36, v30
	v_fma_f32 v28, -v28, v32, v31
	v_div_fmas_f32 v28, v28, v30, v32
	v_div_fixup_f32 v26, v28, v26, 1.0
	v_pk_fma_f32 v[20:21], v[26:27], v[24:25], v[20:21]
	v_cvt_f32_f16_e32 v26, v29
	v_cvt_pk_f16_f32 v20, v20, v21
	v_div_scale_f32 v21, s[0:1], v23, v23, 1.0
	v_rcp_f32_e32 v28, v21
	v_cvt_f32_f16_sdwa v27, v29 dst_sel:DWORD dst_unused:UNUSED_PAD src0_sel:WORD_1
	v_cvt_f32_f16_e32 v24, v33
	v_cvt_f32_f16_sdwa v25, v33 dst_sel:DWORD dst_unused:UNUSED_PAD src0_sel:WORD_1
	v_fma_f32 v29, -v21, v28, 1.0
	v_fmac_f32_e32 v28, v29, v28
	v_div_scale_f32 v29, vcc, 1.0, v23, 1.0
	v_mul_f32_e32 v30, v29, v28
	v_fma_f32 v31, -v21, v30, v29
	v_fmac_f32_e32 v30, v31, v28
	v_fma_f32 v21, -v21, v30, v29
	v_div_fmas_f32 v21, v21, v28, v30
	v_div_fixup_f32 v23, v21, v23, 1.0
	v_div_scale_f32 v21, s[0:1], v22, v22, 1.0
	v_rcp_f32_e32 v28, v21
	v_pk_add_f32 v[26:27], v[26:27], v[24:25] neg_lo:[0,1] neg_hi:[0,1]
	v_fma_f32 v29, -v21, v28, 1.0
	v_fmac_f32_e32 v28, v29, v28
	v_div_scale_f32 v29, vcc, 1.0, v22, 1.0
	v_mul_f32_e32 v30, v29, v28
	v_fma_f32 v31, -v21, v30, v29
	v_fmac_f32_e32 v30, v31, v28
	v_fma_f32 v21, -v21, v30, v29
	v_div_fmas_f32 v21, v21, v28, v30
	v_div_fixup_f32 v22, v21, v22, 1.0
	v_pk_fma_f32 v[22:23], v[22:23], v[26:27], v[24:25]
	s_nop 0
	v_cvt_pk_f16_f32 v21, v22, v23
	global_store_dwordx4 v[34:35], v[18:21], off
	v_lshl_add_u64 v[26:27], v[98:99], 0, v[82:83]
	global_load_dwordx4 v[22:25], v[26:27], off
	global_load_dwordx4 v[18:21], v[100:101], off offset:256
	v_add_f32_e32 v10, v10, v66
	v_mul_f32_e32 v10, 0xbfb8aa3b, v10
	v_exp_f32_e32 v28, v10
	v_add_f32_e32 v10, v15, v71
	v_mul_f32_e32 v10, 0xbfb8aa3b, v10
	v_exp_f32_e32 v33, v10
	v_add_f32_e32 v10, v11, v67
	v_mul_f32_e32 v10, 0xbfb8aa3b, v10
	v_add_f32_e32 v14, v14, v70
	v_exp_f32_e32 v29, v10
	v_add_f32_e32 v10, v16, v72
	v_mul_f32_e32 v14, 0xbfb8aa3b, v14
	v_mul_f32_e32 v10, 0xbfb8aa3b, v10
	v_exp_f32_e32 v32, v14
	v_exp_f32_e32 v30, v10
	v_add_f32_e32 v10, v12, v68
	v_mul_f32_e32 v10, 0xbfb8aa3b, v10
	v_exp_f32_e32 v14, v10
	v_add_f32_e32 v10, v17, v73
	v_mul_f32_e32 v10, 0xbfb8aa3b, v10
	v_exp_f32_e32 v31, v10
	v_add_f32_e32 v10, v13, v69
	v_pk_add_f32 v[16:17], v[32:33], 1.0 op_sel_hi:[1,0]
	v_mul_f32_e32 v10, 0xbfb8aa3b, v10
	v_exp_f32_e32 v15, v10
	s_waitcnt vmcnt(0)
; __device__ __forceinline__ float sigmoidf_(float x) { return 1.0f / (1.0f + __expf(-x)); }
;     template <int GI>
;     __device__ __forceinline__ void body(const f32x4 (&acc)[2][2][4][2], int row0, int colt) const {
;     ...
;             for (int ai = 0; ai < 2; ++ai)
; #pragma unroll
;                 for (int m = 0; m < 4; ++m) {
;                     const size_t row = (size_t)(row0 + ai * 128 + m * 16);
;                     f32x4 x0 = acc[ai][bj][m][0] + b0, x1 = acc[ai][bj][m][1] + b1;
;                     if (GI == 0) {
; #pragma unroll
;                         for (int j = 0; j < 4; ++j) {
;                             x0[j] = 0.6065306597126334f * sigmoidf_(x0[j]); x1[j] = 0.6065306597126334f * sigmoidf_(x1[j]); }
;                         *(u32x4*)(DEC + row * DM + c) = pack8(x0, x1);
;                     } else if (GI == 1) {
; #pragma unroll
;                         for (int j = 0; j < 4; ++j) { x0[j] = sigmoidf_(x0[j]); x1[j] = sigmoidf_(x1[j]); }
;                         *(u32x4*)(Ab + row * DM + c) = pack8(x0, x1);
;                     } else if (GI == 2) {
;                         *(u32x4*)(Gb + row * DM + c) = pack8(x0, x1);
;                     } else {
;                         h16* vp = C1 + row * LDC1 + 4096 + c;
;                         const h16x8 vv = *(const h16x8*)vp; const h16x8 vf = *(const h16x8*)(VF + row * DM + c);
;                         f32x4 o0, o1;
; #pragma unroll
;                         for (int j = 0; j < 4; ++j) { float v = (float)vv[j], f = (float)vf[j]; o0[j] = v + (f - v) * sigmoidf_(x0[j]); v = (float)vv[4 + j]; f = (float)vf[4 + j]; o1[j] = v + (f - v) * sigmoidf_(x1[j]); }
;                         *(u32x4*)vp = pack8(o0, o1);
;                     }
;                     __builtin_amdgcn_sched_barrier(0);
	v_cvt_f32_f16_e32 v10, v22
	v_cvt_f32_f16_e32 v12, v18
	v_cvt_f32_f16_sdwa v13, v18 dst_sel:DWORD dst_unused:UNUSED_PAD src0_sel:WORD_1
	v_div_scale_f32 v18, s[0:1], v17, v17, 1.0
	v_cvt_f32_f16_sdwa v11, v22 dst_sel:DWORD dst_unused:UNUSED_PAD src0_sel:WORD_1
	v_rcp_f32_e32 v22, v18
	v_pk_add_f32 v[14:15], v[14:15], 1.0 op_sel_hi:[1,0]
	v_pk_add_f32 v[12:13], v[12:13], v[10:11] neg_lo:[0,1] neg_hi:[0,1]
	v_fma_f32 v32, -v18, v22, 1.0
	v_fmac_f32_e32 v22, v32, v22
	v_div_scale_f32 v32, vcc, 1.0, v17, 1.0
	v_mul_f32_e32 v33, v32, v22
	v_fma_f32 v34, -v18, v33, v32
	v_fmac_f32_e32 v33, v34, v22
	v_fma_f32 v18, -v18, v33, v32
	v_div_fmas_f32 v18, v18, v22, v33
	v_div_fixup_f32 v17, v18, v17, 1.0
	v_div_scale_f32 v18, s[0:1], v16, v16, 1.0
	v_rcp_f32_e32 v22, v18
	s_nop 0
	v_fma_f32 v32, -v18, v22, 1.0
	v_fmac_f32_e32 v22, v32, v22
	v_div_scale_f32 v32, vcc, 1.0, v16, 1.0
	v_mul_f32_e32 v33, v32, v22
	v_fma_f32 v34, -v18, v33, v32
	v_fmac_f32_e32 v33, v34, v22
	v_fma_f32 v18, -v18, v33, v32
	v_div_fmas_f32 v18, v18, v22, v33
	v_div_fixup_f32 v16, v18, v16, 1.0
	v_pk_fma_f32 v[10:11], v[16:17], v[12:13], v[10:11]
	v_cvt_f32_f16_e32 v16, v19
	v_cvt_f32_f16_sdwa v17, v19 dst_sel:DWORD dst_unused:UNUSED_PAD src0_sel:WORD_1
	v_pk_add_f32 v[18:19], v[30:31], 1.0 op_sel_hi:[1,0]
	v_cvt_pk_f16_f32 v10, v10, v11
	v_div_scale_f32 v11, s[0:1], v19, v19, 1.0
	v_rcp_f32_e32 v22, v11
	v_cvt_f32_f16_e32 v12, v23
	v_cvt_f32_f16_sdwa v13, v23 dst_sel:DWORD dst_unused:UNUSED_PAD src0_sel:WORD_1
	v_fma_f32 v23, -v11, v22, 1.0
	v_fmac_f32_e32 v22, v23, v22
	v_div_scale_f32 v23, vcc, 1.0, v19, 1.0
	v_mul_f32_e32 v30, v23, v22
	v_fma_f32 v31, -v11, v30, v23
	v_fmac_f32_e32 v30, v31, v22
	v_fma_f32 v11, -v11, v30, v23
	v_div_fmas_f32 v11, v11, v22, v30
	v_div_fixup_f32 v19, v11, v19, 1.0
	v_div_scale_f32 v11, s[0:1], v18, v18, 1.0
	v_rcp_f32_e32 v22, v11
	v_pk_add_f32 v[16:17], v[16:17], v[12:13] neg_lo:[0,1] neg_hi:[0,1]
	v_fma_f32 v23, -v11, v22, 1.0
	v_fmac_f32_e32 v22, v23, v22
	v_div_scale_f32 v23, vcc, 1.0, v18, 1.0
	v_mul_f32_e32 v30, v23, v22
	v_fma_f32 v31, -v11, v30, v23
	v_fmac_f32_e32 v30, v31, v22
	v_fma_f32 v11, -v11, v30, v23
	v_div_fmas_f32 v11, v11, v22, v30
	v_div_fixup_f32 v18, v11, v18, 1.0
	v_pk_fma_f32 v[12:13], v[18:19], v[16:17], v[12:13]
	v_pk_add_f32 v[18:19], v[28:29], 1.0 op_sel_hi:[1,0]
	v_cvt_f32_f16_e32 v16, v20
	v_cvt_f32_f16_sdwa v17, v20 dst_sel:DWORD dst_unused:UNUSED_PAD src0_sel:WORD_1
	v_div_scale_f32 v20, s[0:1], v19, v19, 1.0
	v_rcp_f32_e32 v22, v20
	v_cvt_pk_f16_f32 v11, v12, v13
	v_cvt_f32_f16_e32 v12, v24
	v_cvt_f32_f16_sdwa v13, v24 dst_sel:DWORD dst_unused:UNUSED_PAD src0_sel:WORD_1
	v_fma_f32 v23, -v20, v22, 1.0
	v_fmac_f32_e32 v22, v23, v22
	v_div_scale_f32 v23, vcc, 1.0, v19, 1.0
	v_mul_f32_e32 v24, v23, v22
	v_fma_f32 v28, -v20, v24, v23
	v_fmac_f32_e32 v24, v28, v22
	v_fma_f32 v20, -v20, v24, v23
	v_div_fmas_f32 v20, v20, v22, v24
	v_div_fixup_f32 v19, v20, v19, 1.0
	v_div_scale_f32 v20, s[0:1], v18, v18, 1.0
	v_rcp_f32_e32 v22, v20
	v_pk_add_f32 v[16:17], v[16:17], v[12:13] neg_lo:[0,1] neg_hi:[0,1]
	v_fma_f32 v23, -v20, v22, 1.0
	v_fmac_f32_e32 v22, v23, v22
	v_div_scale_f32 v23, vcc, 1.0, v18, 1.0
	v_mul_f32_e32 v24, v23, v22
	v_fma_f32 v28, -v20, v24, v23
	v_fmac_f32_e32 v24, v28, v22
	v_fma_f32 v20, -v20, v24, v23
	v_div_fmas_f32 v20, v20, v22, v24
	v_div_fixup_f32 v18, v20, v18, 1.0
	v_pk_fma_f32 v[12:13], v[18:19], v[16:17], v[12:13]
	v_cvt_f32_f16_e32 v18, v21
	v_cvt_pk_f16_f32 v12, v12, v13
	v_div_scale_f32 v13, s[0:1], v15, v15, 1.0
	v_rcp_f32_e32 v20, v13
	v_cvt_f32_f16_sdwa v19, v21 dst_sel:DWORD dst_unused:UNUSED_PAD src0_sel:WORD_1
	v_cvt_f32_f16_e32 v16, v25
	v_cvt_f32_f16_sdwa v17, v25 dst_sel:DWORD dst_unused:UNUSED_PAD src0_sel:WORD_1
	v_fma_f32 v21, -v13, v20, 1.0
	v_fmac_f32_e32 v20, v21, v20
	v_div_scale_f32 v21, vcc, 1.0, v15, 1.0
	v_mul_f32_e32 v22, v21, v20
	v_fma_f32 v23, -v13, v22, v21
	v_fmac_f32_e32 v22, v23, v20
	v_fma_f32 v13, -v13, v22, v21
	v_div_fmas_f32 v13, v13, v20, v22
	v_div_fixup_f32 v15, v13, v15, 1.0
	v_div_scale_f32 v13, s[0:1], v14, v14, 1.0
	v_rcp_f32_e32 v20, v13
	v_pk_add_f32 v[18:19], v[18:19], v[16:17] neg_lo:[0,1] neg_hi:[0,1]
	v_fma_f32 v21, -v13, v20, 1.0
	v_fmac_f32_e32 v20, v21, v20
	v_div_scale_f32 v21, vcc, 1.0, v14, 1.0
	v_mul_f32_e32 v22, v21, v20
	v_fma_f32 v23, -v13, v22, v21
	v_fmac_f32_e32 v22, v23, v20
	v_fma_f32 v13, -v13, v22, v21
	v_div_fmas_f32 v13, v13, v20, v22
	v_div_fixup_f32 v14, v13, v14, 1.0
	v_pk_fma_f32 v[14:15], v[14:15], v[18:19], v[16:17]
	s_nop 0
	v_cvt_pk_f16_f32 v13, v14, v15
	global_store_dwordx4 v[26:27], v[10:13], off
	v_lshl_add_u64 v[18:19], v[90:91], 0, v[82:83]
	global_load_dwordx4 v[14:17], v[18:19], off
	global_load_dwordx4 v[10:13], v[92:93], off offset:256
	v_add_f32_e32 v2, v2, v66
	v_mul_f32_e32 v2, 0xbfb8aa3b, v2
	v_exp_f32_e32 v20, v2
	v_add_f32_e32 v2, v7, v71
	v_mul_f32_e32 v2, 0xbfb8aa3b, v2
	v_exp_f32_e32 v25, v2
	v_add_f32_e32 v2, v3, v67
	v_mul_f32_e32 v2, 0xbfb8aa3b, v2
	v_add_f32_e32 v6, v6, v70
	v_exp_f32_e32 v21, v2
	v_add_f32_e32 v2, v8, v72
	v_mul_f32_e32 v6, 0xbfb8aa3b, v6
	v_mul_f32_e32 v2, 0xbfb8aa3b, v2
	v_exp_f32_e32 v24, v6
	v_exp_f32_e32 v22, v2
	v_add_f32_e32 v2, v4, v68
	v_mul_f32_e32 v2, 0xbfb8aa3b, v2
	v_exp_f32_e32 v6, v2
	v_add_f32_e32 v2, v9, v73
	v_mul_f32_e32 v2, 0xbfb8aa3b, v2
	v_exp_f32_e32 v23, v2
	v_add_f32_e32 v2, v5, v69
	v_pk_add_f32 v[8:9], v[24:25], 1.0 op_sel_hi:[1,0]
	v_mul_f32_e32 v2, 0xbfb8aa3b, v2
	v_exp_f32_e32 v7, v2
	s_waitcnt vmcnt(0)
; __device__ __forceinline__ float sigmoidf_(float x) { return 1.0f / (1.0f + __expf(-x)); }
; template <class Epi, class AMap>
; __device__ __forceinline__ void gemm_phase(LAS unsigned char* lds, const AMap am, const int lda, const h16* Bt, const int ldb, const int M, const int N, const int K, const Epi& E) {
;     ...
;         if (!has_next) break;
; #pragma unroll
;         for (int a = 0; a < 2; ++a)
; #pragma unroll
;             for (int b = 0; b < 2; ++b)
; #pragma unroll
;                 for (int m = 0; m < 4; ++m)
; #pragma unroll
;                     for (int n = 0; n < 2; ++n) acc[a][b][m][n] = (f32x4){0.f, 0.f, 0.f, 0.f};
;         cur = nxt; cA = nA; cB = nB; ++ui;
;     template <int GI>
;     __device__ __forceinline__ void body(const f32x4 (&acc)[2][2][4][2], int row0, int colt) const {
;     ...
;             for (int ai = 0; ai < 2; ++ai)
; #pragma unroll
;                 for (int m = 0; m < 4; ++m) {
;                     const size_t row = (size_t)(row0 + ai * 128 + m * 16);
;                     f32x4 x0 = acc[ai][bj][m][0] + b0, x1 = acc[ai][bj][m][1] + b1;
;                     if (GI == 0) {
; #pragma unroll
;                         for (int j = 0; j < 4; ++j) {
;                             x0[j] = 0.6065306597126334f * sigmoidf_(x0[j]); x1[j] = 0.6065306597126334f * sigmoidf_(x1[j]); }
;                         *(u32x4*)(DEC + row * DM + c) = pack8(x0, x1);
;                     } else if (GI == 1) {
; #pragma unroll
;                         for (int j = 0; j < 4; ++j) { x0[j] = sigmoidf_(x0[j]); x1[j] = sigmoidf_(x1[j]); }
;                         *(u32x4*)(Ab + row * DM + c) = pack8(x0, x1);
;                     } else if (GI == 2) {
;                         *(u32x4*)(Gb + row * DM + c) = pack8(x0, x1);
;                     } else {
;                         h16* vp = C1 + row * LDC1 + 4096 + c;
;                         const h16x8 vv = *(const h16x8*)vp; const h16x8 vf = *(const h16x8*)(VF + row * DM + c);
;                         f32x4 o0, o1;
; #pragma unroll
;                         for (int j = 0; j < 4; ++j) { float v = (float)vv[j], f = (float)vf[j]; o0[j] = v + (f - v) * sigmoidf_(x0[j]); v = (float)vv[4 + j]; f = (float)vf[4 + j]; o1[j] = v + (f - v) * sigmoidf_(x1[j]); }
;                         *(u32x4*)vp = pack8(o0, o1);
;                     }
;                     __builtin_amdgcn_sched_barrier(0);
	v_cvt_f32_f16_e32 v2, v14
	v_cvt_f32_f16_e32 v4, v10
	v_cvt_f32_f16_sdwa v5, v10 dst_sel:DWORD dst_unused:UNUSED_PAD src0_sel:WORD_1
	v_div_scale_f32 v10, s[0:1], v9, v9, 1.0
	v_cvt_f32_f16_sdwa v3, v14 dst_sel:DWORD dst_unused:UNUSED_PAD src0_sel:WORD_1
	v_rcp_f32_e32 v14, v10
	v_pk_add_f32 v[6:7], v[6:7], 1.0 op_sel_hi:[1,0]
	v_pk_add_f32 v[4:5], v[4:5], v[2:3] neg_lo:[0,1] neg_hi:[0,1]
	v_fma_f32 v24, -v10, v14, 1.0
	v_fmac_f32_e32 v14, v24, v14
	v_div_scale_f32 v24, vcc, 1.0, v9, 1.0
	v_mul_f32_e32 v25, v24, v14
	v_fma_f32 v26, -v10, v25, v24
	v_fmac_f32_e32 v25, v26, v14
	v_fma_f32 v10, -v10, v25, v24
	v_div_fmas_f32 v10, v10, v14, v25
	v_div_fixup_f32 v9, v10, v9, 1.0
	v_div_scale_f32 v10, s[0:1], v8, v8, 1.0
	v_rcp_f32_e32 v14, v10
	s_nop 0
	v_fma_f32 v24, -v10, v14, 1.0
	v_fmac_f32_e32 v14, v24, v14
	v_div_scale_f32 v24, vcc, 1.0, v8, 1.0
	v_mul_f32_e32 v25, v24, v14
	v_fma_f32 v26, -v10, v25, v24
	v_fmac_f32_e32 v25, v26, v14
	v_fma_f32 v10, -v10, v25, v24
	v_div_fmas_f32 v10, v10, v14, v25
	v_div_fixup_f32 v8, v10, v8, 1.0
	v_pk_fma_f32 v[2:3], v[8:9], v[4:5], v[2:3]
	v_cvt_f32_f16_e32 v8, v11
	v_cvt_f32_f16_sdwa v9, v11 dst_sel:DWORD dst_unused:UNUSED_PAD src0_sel:WORD_1
	v_pk_add_f32 v[10:11], v[22:23], 1.0 op_sel_hi:[1,0]
	v_cvt_pk_f16_f32 v2, v2, v3
	v_div_scale_f32 v3, s[0:1], v11, v11, 1.0
	v_rcp_f32_e32 v14, v3
	v_cvt_f32_f16_e32 v4, v15
	v_cvt_f32_f16_sdwa v5, v15 dst_sel:DWORD dst_unused:UNUSED_PAD src0_sel:WORD_1
	v_fma_f32 v15, -v3, v14, 1.0
	v_fmac_f32_e32 v14, v15, v14
	v_div_scale_f32 v15, vcc, 1.0, v11, 1.0
	v_mul_f32_e32 v22, v15, v14
	v_fma_f32 v23, -v3, v22, v15
	v_fmac_f32_e32 v22, v23, v14
	v_fma_f32 v3, -v3, v22, v15
	v_div_fmas_f32 v3, v3, v14, v22
	v_div_fixup_f32 v11, v3, v11, 1.0
	v_div_scale_f32 v3, s[0:1], v10, v10, 1.0
	v_rcp_f32_e32 v14, v3
	v_pk_add_f32 v[8:9], v[8:9], v[4:5] neg_lo:[0,1] neg_hi:[0,1]
	v_fma_f32 v15, -v3, v14, 1.0
	v_fmac_f32_e32 v14, v15, v14
	v_div_scale_f32 v15, vcc, 1.0, v10, 1.0
	v_mul_f32_e32 v22, v15, v14
	v_fma_f32 v23, -v3, v22, v15
	v_fmac_f32_e32 v22, v23, v14
	v_fma_f32 v3, -v3, v22, v15
	v_div_fmas_f32 v3, v3, v14, v22
	v_div_fixup_f32 v10, v3, v10, 1.0
	v_pk_fma_f32 v[4:5], v[10:11], v[8:9], v[4:5]
	v_pk_add_f32 v[10:11], v[20:21], 1.0 op_sel_hi:[1,0]
	v_cvt_f32_f16_e32 v8, v12
	v_cvt_f32_f16_sdwa v9, v12 dst_sel:DWORD dst_unused:UNUSED_PAD src0_sel:WORD_1
	v_div_scale_f32 v12, s[0:1], v11, v11, 1.0
	v_rcp_f32_e32 v14, v12
	v_cvt_pk_f16_f32 v3, v4, v5
	v_cvt_f32_f16_e32 v4, v16
	v_cvt_f32_f16_sdwa v5, v16 dst_sel:DWORD dst_unused:UNUSED_PAD src0_sel:WORD_1
	v_fma_f32 v15, -v12, v14, 1.0
	v_fmac_f32_e32 v14, v15, v14
	v_div_scale_f32 v15, vcc, 1.0, v11, 1.0
	v_mul_f32_e32 v16, v15, v14
	v_fma_f32 v20, -v12, v16, v15
	v_fmac_f32_e32 v16, v20, v14
	v_fma_f32 v12, -v12, v16, v15
	v_div_fmas_f32 v12, v12, v14, v16
	v_div_fixup_f32 v11, v12, v11, 1.0
	v_div_scale_f32 v12, s[0:1], v10, v10, 1.0
	v_rcp_f32_e32 v14, v12
	v_pk_add_f32 v[8:9], v[8:9], v[4:5] neg_lo:[0,1] neg_hi:[0,1]
	v_fma_f32 v15, -v12, v14, 1.0
	v_fmac_f32_e32 v14, v15, v14
	v_div_scale_f32 v15, vcc, 1.0, v10, 1.0
	v_mul_f32_e32 v16, v15, v14
	v_fma_f32 v20, -v12, v16, v15
	v_fmac_f32_e32 v16, v20, v14
	v_fma_f32 v12, -v12, v16, v15
	v_div_fmas_f32 v12, v12, v14, v16
	v_div_fixup_f32 v10, v12, v10, 1.0
	v_pk_fma_f32 v[4:5], v[10:11], v[8:9], v[4:5]
	v_cvt_f32_f16_e32 v10, v13
	v_cvt_pk_f16_f32 v4, v4, v5
	v_div_scale_f32 v5, s[0:1], v7, v7, 1.0
	v_rcp_f32_e32 v12, v5
	v_cvt_f32_f16_sdwa v11, v13 dst_sel:DWORD dst_unused:UNUSED_PAD src0_sel:WORD_1
	v_cvt_f32_f16_e32 v8, v17
	v_cvt_f32_f16_sdwa v9, v17 dst_sel:DWORD dst_unused:UNUSED_PAD src0_sel:WORD_1
	v_fma_f32 v13, -v5, v12, 1.0
	v_fmac_f32_e32 v12, v13, v12
	v_div_scale_f32 v13, vcc, 1.0, v7, 1.0
	v_mul_f32_e32 v14, v13, v12
	v_fma_f32 v15, -v5, v14, v13
	v_fmac_f32_e32 v14, v15, v12
	v_fma_f32 v5, -v5, v14, v13
	v_div_fmas_f32 v5, v5, v12, v14
	v_div_fixup_f32 v7, v5, v7, 1.0
	v_div_scale_f32 v5, s[0:1], v6, v6, 1.0
	v_rcp_f32_e32 v12, v5
	v_pk_add_f32 v[10:11], v[10:11], v[8:9] neg_lo:[0,1] neg_hi:[0,1]
	v_fma_f32 v13, -v5, v12, 1.0
	v_fmac_f32_e32 v12, v13, v12
	v_div_scale_f32 v13, vcc, 1.0, v6, 1.0
	v_mul_f32_e32 v14, v13, v12
	v_fma_f32 v15, -v5, v14, v13
	v_fmac_f32_e32 v14, v15, v12
	v_fma_f32 v5, -v5, v14, v13
	v_div_fmas_f32 v5, v5, v12, v14
	v_div_fixup_f32 v6, v5, v6, 1.0
	v_pk_fma_f32 v[6:7], v[6:7], v[10:11], v[8:9]
	s_nop 0
	v_cvt_pk_f16_f32 v5, v6, v7
	global_store_dwordx4 v[18:19], v[2:5], off
	s_and_b64 vcc, exec, s[38:39]
	s_mov_b32 s50, s44
	s_mov_b32 s35, s81
	s_mov_b64 s[26:27], s[64:65]
	s_mov_b64 s[22:23], s[46:47]
	s_cmpk_lt_u32 s69, 0x100
	s_cbranch_scc1 .Lgy7
	s_barrier

; #define PG8_STAGE(bufoff, gbase, voff) do { _Pragma("unroll") for (int _i = 0; _i < 2; ++_i) \
;         __builtin_amdgcn_global_load_lds((const unsigned*)((const char*)(gbase) + (voff)[_i]), (LAS unsigned*)(lds + (bufoff) + ldsw + _i * 8192), 16, 0, 0); } while (0)
; #define PG8_LDA(dst, b, h) do { _Pragma("unroll") for (int m = 0; m < 4; ++m) _Pragma("unroll") for (int k = 0; k < 2; ++k) dst[m][k] = *(const LAS h16x8*)(lds + PG8_SA(b, h) + aoff + m * 2048 + k * 1024); } while (0)
; #define PG8_LDB(dst, b, h) do { _Pragma("unroll") for (int n = 0; n < 2; ++n) _Pragma("unroll") for (int k = 0; k < 2; ++k) dst[n][k] = *(const LAS h16x8*)(lds + PG8_SB(b, h) + boff + n * 2048 + k * 1024); } while (0)
; #define PG8_WAIT_L(n) asm volatile("s_waitcnt lgkmcnt(" #n ")" ::: "memory")
; #define PG8_BAR __builtin_amdgcn_s_barrier()
; #define PG8_SCHED __builtin_amdgcn_sched_barrier(0)
; template <class Epi, class AMap>
; __device__ __forceinline__ void gemm_phase(LAS unsigned char* lds, const AMap am, const int lda, const h16* Bt, const int ldb, const int M, const int N, const int K, const Epi& E) {
;     ...
;         const bool has_next = S.next(ui + 1, nxt);
;         const char* nA = has_next ? am(nxt.pn) + (size_t)nxt.pm * tstepA : cA; const char* nB = has_next ? (const char*)Bt + (size_t)nxt.pn * tstepB : cB;
; #pragma unroll 1
;         for (int t = 0; t < nt; t += 2) {
;             const bool last = (t == nt - 2);
;             const char* a1 = cA + (size_t)(t + 1) * kstep;
;             const char* a2 = last ? nA : cA + (size_t)(t + 2) * kstep; const char* b2 = last ? nB : cB + (size_t)(t + 2) * kstep;
;             const char* a3 = a2 + kstep; const char* b3 = b2 + kstep;
;             PG8_LDB(B0, 0, 0); PG8_SCHED; PG8_LDA(At, 0, 0); PG8_STAGE(PG8_SA(1, 1), a1 + hstepA, voffA);
;             PG8_WAIT_L(8); PG8_BAR; PG8_WAIT_L(0); PG8_MMA(0, 0, At, B0); PG8_BAR; PG8_SCHED;
;             PG8_LDB(B1, 0, 1); PG8_STAGE(PG8_SB(0, 0), b2, voffB);
;             PG8_BAR; PG8_WAIT_L(0); PG8_MMA(0, 1, At, B1); PG8_BAR;
;             PG8_LDA(At, 0, 1); PG8_STAGE(PG8_SA(0, 0), a2, voffA);
;             PG8_BAR; PG8_WAIT_L(0); PG8_MMA(1, 0, At, B0); PG8_BAR; PG8_SCHED;
;             PG8_STAGE(PG8_SB(0, 1), b2 + hstepB, voffB);
.LBB0_692:
	s_add_i32 s51, s26, 2
	s_add_u32 s0, s22, 0x100
	s_addc_u32 s1, s23, 0
	s_add_i32 s60, 0, 0x10000
	v_add_u32_e32 v234, s60, v175
	ds_read_b128 v[82:85], v234
	ds_read_b128 v[86:89], v234 offset:1024
	ds_read_b128 v[138:141], v234 offset:2048
	ds_read_b128 v[142:145], v234 offset:3072
	s_cmp_eq_u32 s61, s26
	s_cselect_b32 s26, s21, s29
	s_cselect_b32 s49, s47, s1
	s_cselect_b32 s48, s46, s0
	s_cselect_b32 s27, s20, s45
	v_lshl_add_u64 v[172:173], s[22:23], 0, v[152:153]
	s_add_i32 m0, s74, 0xc000
	ds_read_b128 v[156:159], v177
	ds_read_b128 v[160:163], v177 offset:1024
	ds_read_b128 v[164:167], v177 offset:2048
	ds_read_b128 v[168:171], v177 offset:3072
	ds_read_b128 v[178:181], v177 offset:4096
	ds_read_b128 v[182:185], v177 offset:5120
	ds_read_b128 v[186:189], v177 offset:6144
	ds_read_b128 v[190:193], v177 offset:7168
	global_load_lds_dwordx4 v[172:173], off
	v_lshl_add_u64 v[172:173], s[22:23], 0, v[154:155]
	s_add_i32 m0, s74, 0xe000
	s_nop 0
	global_load_lds_dwordx4 v[172:173], off
	s_waitcnt lgkmcnt(11)
	s_add_i32 s62, 0, 0x14000
	v_add_u32_e32 v172, s62, v175
	s_add_i32 s22, s60, s71
	ds_read_b128 v[194:197], v172
	ds_read_b128 v[198:201], v172 offset:1024
	ds_read_b128 v[202:205], v172 offset:2048
	ds_read_b128 v[220:223], v172 offset:3072
	s_waitcnt vmcnt(8) lgkmcnt(0)
	s_barrier
	v_mfma_f32_16x16x32_f16 v[134:137], v[82:85], v[156:159], v[134:137]
	v_mfma_f32_16x16x32_f16 v[130:133], v[138:141], v[156:159], v[130:133]
	v_mfma_f32_16x16x32_f16 v[126:129], v[82:85], v[164:167], v[126:129]
	v_mfma_f32_16x16x32_f16 v[122:125], v[138:141], v[164:167], v[122:125]
	v_mfma_f32_16x16x32_f16 v[118:121], v[82:85], v[178:181], v[118:121]
	v_mfma_f32_16x16x32_f16 v[114:117], v[138:141], v[178:181], v[114:117]
	v_mfma_f32_16x16x32_f16 v[110:113], v[82:85], v[186:189], v[110:113]
	v_mfma_f32_16x16x32_f16 v[106:109], v[138:141], v[186:189], v[106:109]
	v_mfma_f32_16x16x32_f16 v[134:137], v[86:89], v[160:163], v[134:137]
	v_mfma_f32_16x16x32_f16 v[130:133], v[142:145], v[160:163], v[130:133]
	v_mfma_f32_16x16x32_f16 v[126:129], v[86:89], v[168:171], v[126:129]
	v_mfma_f32_16x16x32_f16 v[122:125], v[142:145], v[168:171], v[122:125]
	v_mfma_f32_16x16x32_f16 v[118:121], v[86:89], v[182:185], v[118:121]
	v_mfma_f32_16x16x32_f16 v[114:117], v[142:145], v[182:185], v[114:117]
	v_mfma_f32_16x16x32_f16 v[110:113], v[86:89], v[190:193], v[110:113]
	v_mfma_f32_16x16x32_f16 v[106:109], v[142:145], v[190:193], v[106:109]
	v_mfma_f32_16x16x32_f16 v[62:65], v[194:197], v[156:159], v[62:65]
	v_mfma_f32_16x16x32_f16 v[58:61], v[202:205], v[156:159], v[58:61]
	v_mfma_f32_16x16x32_f16 v[54:57], v[194:197], v[164:167], v[54:57]
	v_mfma_f32_16x16x32_f16 v[50:53], v[202:205], v[164:167], v[50:53]
	v_mfma_f32_16x16x32_f16 v[46:49], v[194:197], v[178:181], v[46:49]
	v_mfma_f32_16x16x32_f16 v[42:45], v[202:205], v[178:181], v[42:45]
	v_mfma_f32_16x16x32_f16 v[38:41], v[194:197], v[186:189], v[38:41]
	v_mfma_f32_16x16x32_f16 v[34:37], v[202:205], v[186:189], v[34:37]
	v_mfma_f32_16x16x32_f16 v[62:65], v[198:201], v[160:163], v[62:65]
	v_mfma_f32_16x16x32_f16 v[58:61], v[220:223], v[160:163], v[58:61]
	v_mfma_f32_16x16x32_f16 v[54:57], v[198:201], v[168:171], v[54:57]
	v_mfma_f32_16x16x32_f16 v[50:53], v[220:223], v[168:171], v[50:53]
	v_mfma_f32_16x16x32_f16 v[46:49], v[198:201], v[182:185], v[46:49]
	v_mfma_f32_16x16x32_f16 v[42:45], v[220:223], v[182:185], v[42:45]
	v_mfma_f32_16x16x32_f16 v[38:41], v[198:201], v[190:193], v[38:41]
	v_mfma_f32_16x16x32_f16 v[34:37], v[220:223], v[190:193], v[34:37]
	s_barrier
	v_lshl_add_u64 v[172:173], s[26:27], 0, v[0:1]
	s_mov_b32 m0, s22
	v_lshl_add_u64 v[206:207], s[26:27], 0, v[150:151]
	global_load_lds_dwordx4 v[172:173], off
	s_add_i32 m0, s22, 0x2000
	s_nop 0
	global_load_lds_dwordx4 v[206:207], off
	s_mov_b32 m0, s74
	v_lshl_add_u64 v[212:213], s[48:49], 0, v[146:147]
	ds_read_b128 v[156:159], v177 offset:16384
	ds_read_b128 v[160:163], v177 offset:17408
	ds_read_b128 v[164:167], v177 offset:18432
	ds_read_b128 v[168:171], v177 offset:19456
	ds_read_b128 v[178:181], v177 offset:20480
	ds_read_b128 v[182:185], v177 offset:21504
	ds_read_b128 v[186:189], v177 offset:22528
	ds_read_b128 v[190:193], v177 offset:23552
	global_load_lds_dwordx4 v[212:213], off
	v_lshl_add_u64 v[224:225], s[48:49], 0, v[148:149]
	s_mov_b32 m0, s75
	s_nop 0
	global_load_lds_dwordx4 v[224:225], off
	s_add_u32 s22, s26, 0x10000
	s_addc_u32 s23, s27, 0
	s_add_i32 s60, s62, s71
	v_lshl_add_u64 v[232:233], s[22:23], 0, v[0:1]
	s_mov_b32 m0, s60
	s_nop 0
	global_load_lds_dwordx4 v[232:233], off
	v_lshl_add_u64 v[232:233], s[22:23], 0, v[150:151]
	s_add_i32 m0, s60, 0x2000
	s_nop 0
	global_load_lds_dwordx4 v[232:233], off
	s_waitcnt vmcnt(8) lgkmcnt(0)
	s_barrier
; #define PG8_STAGE(bufoff, gbase, voff) do { _Pragma("unroll") for (int _i = 0; _i < 2; ++_i) \
;         __builtin_amdgcn_global_load_lds((const unsigned*)((const char*)(gbase) + (voff)[_i]), (LAS unsigned*)(lds + (bufoff) + ldsw + _i * 8192), 16, 0, 0); } while (0)
; #define PG8_LDA(dst, b, h) do { _Pragma("unroll") for (int m = 0; m < 4; ++m) _Pragma("unroll") for (int k = 0; k < 2; ++k) dst[m][k] = *(const LAS h16x8*)(lds + PG8_SA(b, h) + aoff + m * 2048 + k * 1024); } while (0)
; #define PG8_LDB(dst, b, h) do { _Pragma("unroll") for (int n = 0; n < 2; ++n) _Pragma("unroll") for (int k = 0; k < 2; ++k) dst[n][k] = *(const LAS h16x8*)(lds + PG8_SB(b, h) + boff + n * 2048 + k * 1024); } while (0)
; #define PG8_MMA(ai, bj, At, Bt_) do { __builtin_amdgcn_s_setprio(1); _Pragma("unroll") for (int m = 0; m < 4; ++m) _Pragma("unroll") for (int n = 0; n < 2; ++n) _Pragma("unroll") for (int k = 0; k < 2; ++k) \
;         acc[ai][bj][m][n] = __builtin_amdgcn_mfma_f32_16x16x32_f16(Bt_[n][k], At[m][k], acc[ai][bj][m][n], 0, 0, 0); __builtin_amdgcn_s_setprio(0); } while (0)
; #define PG8_WAIT_V(n) asm volatile("s_waitcnt vmcnt(" #n ")" ::: "memory")
; #define PG8_WAIT_L(n) asm volatile("s_waitcnt lgkmcnt(" #n ")" ::: "memory")
; #define PG8_BAR __builtin_amdgcn_s_barrier()
; #define PG8_SCHED __builtin_amdgcn_sched_barrier(0)
; template <class Epi, class AMap>
; __device__ __forceinline__ void gemm_phase(LAS unsigned char* lds, const AMap am, const int lda, const h16* Bt, const int ldb, const int M, const int N, const int K, const Epi& E) {
;     ...
;             PG8_BAR; PG8_WAIT_L(0); PG8_MMA(1, 0, At, B0); PG8_BAR; PG8_SCHED;
;             PG8_STAGE(PG8_SB(0, 1), b2 + hstepB, voffB);
;             PG8_WAIT_V(6); PG8_BAR; PG8_MMA(1, 1, At, B1); PG8_BAR;
;             PG8_LDB(B0, 1, 0); PG8_SCHED; PG8_LDA(At, 1, 0); PG8_STAGE(PG8_SA(0, 1), a2 + hstepA, voffA);
;             PG8_WAIT_L(8); PG8_BAR; PG8_WAIT_L(0); PG8_MMA(0, 0, At, B0); PG8_BAR; PG8_SCHED;
;             PG8_LDB(B1, 1, 1); PG8_STAGE(PG8_SB(1, 0), b3, voffB);
;             PG8_BAR; PG8_WAIT_L(0); PG8_MMA(0, 1, At, B1); PG8_BAR;
	v_mfma_f32_16x16x32_f16 v[102:105], v[82:85], v[156:159], v[102:105]
	v_mfma_f32_16x16x32_f16 v[98:101], v[138:141], v[156:159], v[98:101]
	v_mfma_f32_16x16x32_f16 v[94:97], v[82:85], v[164:167], v[94:97]
	v_mfma_f32_16x16x32_f16 v[90:93], v[138:141], v[164:167], v[90:93]
	v_mfma_f32_16x16x32_f16 v[78:81], v[82:85], v[178:181], v[78:81]
	v_mfma_f32_16x16x32_f16 v[74:77], v[138:141], v[178:181], v[74:77]
	v_mfma_f32_16x16x32_f16 v[70:73], v[82:85], v[186:189], v[70:73]
	v_mfma_f32_16x16x32_f16 v[66:69], v[138:141], v[186:189], v[66:69]
	v_mfma_f32_16x16x32_f16 v[102:105], v[86:89], v[160:163], v[102:105]
	v_mfma_f32_16x16x32_f16 v[98:101], v[142:145], v[160:163], v[98:101]
	v_mfma_f32_16x16x32_f16 v[94:97], v[86:89], v[168:171], v[94:97]
	v_mfma_f32_16x16x32_f16 v[90:93], v[142:145], v[168:171], v[90:93]
	v_mfma_f32_16x16x32_f16 v[78:81], v[86:89], v[182:185], v[78:81]
	v_mfma_f32_16x16x32_f16 v[74:77], v[142:145], v[182:185], v[74:77]
	v_mfma_f32_16x16x32_f16 v[70:73], v[86:89], v[190:193], v[70:73]
	v_mfma_f32_16x16x32_f16 v[66:69], v[142:145], v[190:193], v[66:69]
	v_mfma_f32_16x16x32_f16 v[30:33], v[194:197], v[156:159], v[30:33]
	v_mfma_f32_16x16x32_f16 v[26:29], v[202:205], v[156:159], v[26:29]
	v_mfma_f32_16x16x32_f16 v[22:25], v[194:197], v[164:167], v[22:25]
	v_mfma_f32_16x16x32_f16 v[18:21], v[202:205], v[164:167], v[18:21]
	v_mfma_f32_16x16x32_f16 v[14:17], v[194:197], v[178:181], v[14:17]
	v_mfma_f32_16x16x32_f16 v[10:13], v[202:205], v[178:181], v[10:13]
	v_mfma_f32_16x16x32_f16 v[6:9], v[194:197], v[186:189], v[6:9]
	v_mfma_f32_16x16x32_f16 v[2:5], v[202:205], v[186:189], v[2:5]
	v_mfma_f32_16x16x32_f16 v[30:33], v[198:201], v[160:163], v[30:33]
	v_mfma_f32_16x16x32_f16 v[26:29], v[220:223], v[160:163], v[26:29]
	v_mfma_f32_16x16x32_f16 v[22:25], v[198:201], v[168:171], v[22:25]
	v_mfma_f32_16x16x32_f16 v[18:21], v[220:223], v[168:171], v[18:21]
	v_mfma_f32_16x16x32_f16 v[14:17], v[198:201], v[182:185], v[14:17]
	v_mfma_f32_16x16x32_f16 v[10:13], v[220:223], v[182:185], v[10:13]
	v_mfma_f32_16x16x32_f16 v[6:9], v[198:201], v[190:193], v[6:9]
	v_mfma_f32_16x16x32_f16 v[2:5], v[220:223], v[190:193], v[2:5]
	s_barrier
	s_add_i32 s60, 0, 0x18000
	v_add_u32_e32 v234, s60, v175
	ds_read_b128 v[82:85], v234
	ds_read_b128 v[86:89], v234 offset:1024
	ds_read_b128 v[138:141], v234 offset:2048
	ds_read_b128 v[142:145], v234 offset:3072
	s_add_u32 s22, s48, 0x1c0000
	s_addc_u32 s23, s49, 0
	s_mov_b32 m0, s76
	v_lshl_add_u64 v[232:233], s[22:23], 0, v[146:147]
	ds_read_b128 v[156:159], v177 offset:32768
	ds_read_b128 v[160:163], v177 offset:33792
	ds_read_b128 v[164:167], v177 offset:34816
	ds_read_b128 v[168:171], v177 offset:35840
	ds_read_b128 v[178:181], v177 offset:36864
	ds_read_b128 v[182:185], v177 offset:37888
	ds_read_b128 v[186:189], v177 offset:38912
	ds_read_b128 v[190:193], v177 offset:39936
	global_load_lds_dwordx4 v[232:233], off
	v_lshl_add_u64 v[232:233], s[22:23], 0, v[148:149]
	s_mov_b32 m0, s77
	s_nop 0
	global_load_lds_dwordx4 v[232:233], off
	s_waitcnt lgkmcnt(11)
	s_add_i32 s48, 0, 0x1c000
	s_add_i32 s22, s60, s71
	v_add_u32_e32 v214, s48, v175
	v_lshl_add_u64 v[172:173], v[172:173], 0, s[92:93]
	s_mov_b32 m0, s22
	ds_read_b128 v[194:197], v214
	ds_read_b128 v[198:201], v214 offset:1024
	ds_read_b128 v[202:205], v214 offset:2048
	ds_read_b128 v[220:223], v214 offset:3072
	s_waitcnt vmcnt(8) lgkmcnt(0)
	s_barrier
	v_mfma_f32_16x16x32_f16 v[134:137], v[82:85], v[156:159], v[134:137]
	v_mfma_f32_16x16x32_f16 v[130:133], v[138:141], v[156:159], v[130:133]
	v_mfma_f32_16x16x32_f16 v[126:129], v[82:85], v[164:167], v[126:129]
	v_mfma_f32_16x16x32_f16 v[122:125], v[138:141], v[164:167], v[122:125]
	v_mfma_f32_16x16x32_f16 v[118:121], v[82:85], v[178:181], v[118:121]
	v_mfma_f32_16x16x32_f16 v[114:117], v[138:141], v[178:181], v[114:117]
	v_mfma_f32_16x16x32_f16 v[110:113], v[82:85], v[186:189], v[110:113]
	v_mfma_f32_16x16x32_f16 v[106:109], v[138:141], v[186:189], v[106:109]
	v_mfma_f32_16x16x32_f16 v[134:137], v[86:89], v[160:163], v[134:137]
	v_mfma_f32_16x16x32_f16 v[130:133], v[142:145], v[160:163], v[130:133]
	v_mfma_f32_16x16x32_f16 v[126:129], v[86:89], v[168:171], v[126:129]
	v_mfma_f32_16x16x32_f16 v[122:125], v[142:145], v[168:171], v[122:125]
	v_mfma_f32_16x16x32_f16 v[118:121], v[86:89], v[182:185], v[118:121]
	v_mfma_f32_16x16x32_f16 v[114:117], v[142:145], v[182:185], v[114:117]
	v_mfma_f32_16x16x32_f16 v[110:113], v[86:89], v[190:193], v[110:113]
	v_mfma_f32_16x16x32_f16 v[106:109], v[142:145], v[190:193], v[106:109]
	v_mfma_f32_16x16x32_f16 v[62:65], v[194:197], v[156:159], v[62:65]
	v_mfma_f32_16x16x32_f16 v[58:61], v[202:205], v[156:159], v[58:61]
	v_mfma_f32_16x16x32_f16 v[54:57], v[194:197], v[164:167], v[54:57]
	v_mfma_f32_16x16x32_f16 v[50:53], v[202:205], v[164:167], v[50:53]
	v_mfma_f32_16x16x32_f16 v[46:49], v[194:197], v[178:181], v[46:49]
	v_mfma_f32_16x16x32_f16 v[42:45], v[202:205], v[178:181], v[42:45]
	v_mfma_f32_16x16x32_f16 v[38:41], v[194:197], v[186:189], v[38:41]
	v_mfma_f32_16x16x32_f16 v[34:37], v[202:205], v[186:189], v[34:37]
	v_mfma_f32_16x16x32_f16 v[62:65], v[198:201], v[160:163], v[62:65]
	v_mfma_f32_16x16x32_f16 v[58:61], v[220:223], v[160:163], v[58:61]
	v_mfma_f32_16x16x32_f16 v[54:57], v[198:201], v[168:171], v[54:57]
	v_mfma_f32_16x16x32_f16 v[50:53], v[220:223], v[168:171], v[50:53]
	v_mfma_f32_16x16x32_f16 v[46:49], v[198:201], v[182:185], v[46:49]
	v_mfma_f32_16x16x32_f16 v[42:45], v[220:223], v[182:185], v[42:45]
	v_mfma_f32_16x16x32_f16 v[38:41], v[198:201], v[190:193], v[38:41]
	v_mfma_f32_16x16x32_f16 v[34:37], v[220:223], v[190:193], v[34:37]
	s_barrier
; #define PG8_STAGE(bufoff, gbase, voff) do { _Pragma("unroll") for (int _i = 0; _i < 2; ++_i) \
;         __builtin_amdgcn_global_load_lds((const unsigned*)((const char*)(gbase) + (voff)[_i]), (LAS unsigned*)(lds + (bufoff) + ldsw + _i * 8192), 16, 0, 0); } while (0)
; #define PG8_LDA(dst, b, h) do { _Pragma("unroll") for (int m = 0; m < 4; ++m) _Pragma("unroll") for (int k = 0; k < 2; ++k) dst[m][k] = *(const LAS h16x8*)(lds + PG8_SA(b, h) + aoff + m * 2048 + k * 1024); } while (0)
; #define PG8_LDB(dst, b, h) do { _Pragma("unroll") for (int n = 0; n < 2; ++n) _Pragma("unroll") for (int k = 0; k < 2; ++k) dst[n][k] = *(const LAS h16x8*)(lds + PG8_SB(b, h) + boff + n * 2048 + k * 1024); } while (0)
; #define PG8_MMA(ai, bj, At, Bt_) do { __builtin_amdgcn_s_setprio(1); _Pragma("unroll") for (int m = 0; m < 4; ++m) _Pragma("unroll") for (int n = 0; n < 2; ++n) _Pragma("unroll") for (int k = 0; k < 2; ++k) \
;         acc[ai][bj][m][n] = __builtin_amdgcn_mfma_f32_16x16x32_f16(Bt_[n][k], At[m][k], acc[ai][bj][m][n], 0, 0, 0); __builtin_amdgcn_s_setprio(0); } while (0)
; #define PG8_WAIT_V(n) asm volatile("s_waitcnt vmcnt(" #n ")" ::: "memory")
; #define PG8_WAIT_L(n) asm volatile("s_waitcnt lgkmcnt(" #n ")" ::: "memory")
; #define PG8_BAR __builtin_amdgcn_s_barrier()
; #define PG8_SCHED __builtin_amdgcn_sched_barrier(0)
; template <class Epi, class AMap>
; __device__ __forceinline__ void gemm_phase(LAS unsigned char* lds, const AMap am, const int lda, const h16* Bt, const int ldb, const int M, const int N, const int K, const Epi& E) {
;     ...
;             PG8_LDB(B1, 1, 1); PG8_STAGE(PG8_SB(1, 0), b3, voffB);
;             PG8_BAR; PG8_WAIT_L(0); PG8_MMA(0, 1, At, B1); PG8_BAR;
;             PG8_LDA(At, 1, 1); PG8_STAGE(PG8_SA(1, 0), a3, voffA);
;             PG8_BAR; PG8_WAIT_L(0); PG8_MMA(1, 0, At, B0); PG8_BAR; PG8_SCHED;
;             PG8_STAGE(PG8_SB(1, 1), b3 + hstepB, voffB);
;             PG8_WAIT_V(6); PG8_BAR; PG8_MMA(1, 1, At, B1); PG8_BAR;
;         }
;         E(acc, cur, wr, wc, fr, fq);
;         if (!has_next) break;
	global_load_lds_dwordx4 v[172:173], off
	v_lshl_add_u64 v[172:173], v[206:207], 0, s[92:93]
	s_add_i32 m0, s22, 0x2000
	s_nop 0
	global_load_lds_dwordx4 v[172:173], off
	s_mov_b32 m0, s79
	v_lshl_add_u64 v[172:173], v[212:213], 0, s[92:93]
	ds_read_b128 v[156:159], v177 offset:49152
	ds_read_b128 v[160:163], v177 offset:50176
	ds_read_b128 v[164:167], v177 offset:51200
	ds_read_b128 v[168:171], v177 offset:52224
	ds_read_b128 v[178:181], v177 offset:53248
	ds_read_b128 v[182:185], v177 offset:54272
	ds_read_b128 v[186:189], v177 offset:55296
	ds_read_b128 v[190:193], v177 offset:56320
	global_load_lds_dwordx4 v[172:173], off
	v_lshl_add_u64 v[172:173], v[224:225], 0, s[92:93]
	s_mov_b32 m0, s80
	s_nop 0
	global_load_lds_dwordx4 v[172:173], off
	s_add_u32 s22, s26, 0x10080
	s_addc_u32 s23, s27, 0
	s_add_i32 s26, s48, s71
	v_lshl_add_u64 v[232:233], s[22:23], 0, v[0:1]
	s_mov_b32 m0, s26
	s_nop 0
	global_load_lds_dwordx4 v[232:233], off
	v_lshl_add_u64 v[232:233], s[22:23], 0, v[150:151]
	s_add_i32 m0, s26, 0x2000
	s_nop 0
	global_load_lds_dwordx4 v[232:233], off
	s_add_u32 s29, s29, 0x100
	s_addc_u32 s45, s45, 0
	s_cmp_ge_i32 s51, s24
	s_mov_b64 s[22:23], s[0:1]
	s_mov_b32 s26, s51
	s_waitcnt vmcnt(8) lgkmcnt(0)
	s_barrier
	v_mfma_f32_16x16x32_f16 v[102:105], v[82:85], v[156:159], v[102:105]
	v_mfma_f32_16x16x32_f16 v[98:101], v[138:141], v[156:159], v[98:101]
	v_mfma_f32_16x16x32_f16 v[94:97], v[82:85], v[164:167], v[94:97]
	v_mfma_f32_16x16x32_f16 v[90:93], v[138:141], v[164:167], v[90:93]
	v_mfma_f32_16x16x32_f16 v[78:81], v[82:85], v[178:181], v[78:81]
	v_mfma_f32_16x16x32_f16 v[74:77], v[138:141], v[178:181], v[74:77]
	v_mfma_f32_16x16x32_f16 v[70:73], v[82:85], v[186:189], v[70:73]
	v_mfma_f32_16x16x32_f16 v[66:69], v[138:141], v[186:189], v[66:69]
	v_mfma_f32_16x16x32_f16 v[102:105], v[86:89], v[160:163], v[102:105]
	v_mfma_f32_16x16x32_f16 v[98:101], v[142:145], v[160:163], v[98:101]
	v_mfma_f32_16x16x32_f16 v[94:97], v[86:89], v[168:171], v[94:97]
	v_mfma_f32_16x16x32_f16 v[90:93], v[142:145], v[168:171], v[90:93]
	v_mfma_f32_16x16x32_f16 v[78:81], v[86:89], v[182:185], v[78:81]
	v_mfma_f32_16x16x32_f16 v[74:77], v[142:145], v[182:185], v[74:77]
	v_mfma_f32_16x16x32_f16 v[70:73], v[86:89], v[190:193], v[70:73]
	v_mfma_f32_16x16x32_f16 v[66:69], v[142:145], v[190:193], v[66:69]
	v_mfma_f32_16x16x32_f16 v[30:33], v[194:197], v[156:159], v[30:33]
	v_mfma_f32_16x16x32_f16 v[26:29], v[202:205], v[156:159], v[26:29]
	v_mfma_f32_16x16x32_f16 v[22:25], v[194:197], v[164:167], v[22:25]
	v_mfma_f32_16x16x32_f16 v[18:21], v[202:205], v[164:167], v[18:21]
	v_mfma_f32_16x16x32_f16 v[14:17], v[194:197], v[178:181], v[14:17]
	v_mfma_f32_16x16x32_f16 v[10:13], v[202:205], v[178:181], v[10:13]
	v_mfma_f32_16x16x32_f16 v[6:9], v[194:197], v[186:189], v[6:9]
	v_mfma_f32_16x16x32_f16 v[2:5], v[202:205], v[186:189], v[2:5]
	v_mfma_f32_16x16x32_f16 v[30:33], v[198:201], v[160:163], v[30:33]
	v_mfma_f32_16x16x32_f16 v[26:29], v[220:223], v[160:163], v[26:29]
	v_mfma_f32_16x16x32_f16 v[22:25], v[198:201], v[168:171], v[22:25]
	v_mfma_f32_16x16x32_f16 v[18:21], v[220:223], v[168:171], v[18:21]
	v_mfma_f32_16x16x32_f16 v[14:17], v[198:201], v[182:185], v[14:17]
	v_mfma_f32_16x16x32_f16 v[10:13], v[220:223], v[182:185], v[10:13]
	v_mfma_f32_16x16x32_f16 v[6:9], v[198:201], v[190:193], v[6:9]
	v_mfma_f32_16x16x32_f16 v[2:5], v[220:223], v[190:193], v[2:5]
	s_barrier
	s_cbranch_scc0 .LBB0_692
	s_branch .LBB0_681

; #define PG8_STAGE(bufoff, gbase, voff) do { _Pragma("unroll") for (int _i = 0; _i < 2; ++_i) \
;         __builtin_amdgcn_global_load_lds((const unsigned*)((const char*)(gbase) + (voff)[_i]), (LAS unsigned*)(lds + (bufoff) + ldsw + _i * 8192), 16, 0, 0); } while (0)
; #define PG8_LDA(dst, b, h) do { _Pragma("unroll") for (int m = 0; m < 4; ++m) _Pragma("unroll") for (int k = 0; k < 2; ++k) dst[m][k] = *(const LAS h16x8*)(lds + PG8_SA(b, h) + aoff + m * 2048 + k * 1024); } while (0)
; #define PG8_LDB(dst, b, h) do { _Pragma("unroll") for (int n = 0; n < 2; ++n) _Pragma("unroll") for (int k = 0; k < 2; ++k) dst[n][k] = *(const LAS h16x8*)(lds + PG8_SB(b, h) + boff + n * 2048 + k * 1024); } while (0)
; #define PG8_MMA(ai, bj, At, Bt_) do { __builtin_amdgcn_s_setprio(1); _Pragma("unroll") for (int m = 0; m < 4; ++m) _Pragma("unroll") for (int n = 0; n < 2; ++n) _Pragma("unroll") for (int k = 0; k < 2; ++k) \
;         acc[ai][bj][m][n] = __builtin_amdgcn_mfma_f32_16x16x32_f16(Bt_[n][k], At[m][k], acc[ai][bj][m][n], 0, 0, 0); __builtin_amdgcn_s_setprio(0); } while (0)
; #define PG8_WAIT_L(n) asm volatile("s_waitcnt lgkmcnt(" #n ")" ::: "memory")
; #define PG8_BAR __builtin_amdgcn_s_barrier()
; #define PG8_SCHED __builtin_amdgcn_sched_barrier(0)
; template <class Epi, class AMap>
; __device__ __forceinline__ void gemm_phase(LAS unsigned char* lds, const AMap am, const int lda, const h16* Bt, const int ldb, const int M, const int N, const int K, const Epi& E) {
;     ...
;         for (int t = 0; t < nt; t += 2) {
;             const bool last = (t == nt - 2);
;             const char* a1 = cA + (size_t)(t + 1) * kstep;
;             const char* a2 = last ? nA : cA + (size_t)(t + 2) * kstep; const char* b2 = last ? nB : cB + (size_t)(t + 2) * kstep;
;             const char* a3 = a2 + kstep; const char* b3 = b2 + kstep;
;             PG8_LDB(B0, 0, 0); PG8_SCHED; PG8_LDA(At, 0, 0); PG8_STAGE(PG8_SA(1, 1), a1 + hstepA, voffA);
;             PG8_WAIT_L(8); PG8_BAR; PG8_WAIT_L(0); PG8_MMA(0, 0, At, B0); PG8_BAR; PG8_SCHED;
;             PG8_LDB(B1, 0, 1); PG8_STAGE(PG8_SB(0, 0), b2, voffB);
;             PG8_BAR; PG8_WAIT_L(0); PG8_MMA(0, 1, At, B1); PG8_BAR;
;             PG8_LDA(At, 0, 1); PG8_STAGE(PG8_SA(0, 0), a2, voffA);
;             PG8_BAR; PG8_WAIT_L(0); PG8_MMA(1, 0, At, B0); PG8_BAR; PG8_SCHED;
;             PG8_STAGE(PG8_SB(0, 1), b2 + hstepB, voffB);
.LBB0_799:
	s_add_u32 s40, s0, 0xfff80080
	s_addc_u32 s41, s1, -1
	s_add_i32 s45, 0, 0x10000
	v_add_u32_e32 v152, s45, v155
	ds_read_b128 v[130:133], v152
	ds_read_b128 v[134:137], v152 offset:1024
	ds_read_b128 v[148:151], v152 offset:2048
	ds_read_b128 v[158:161], v152 offset:3072
	s_cmp_eq_u32 s43, 28
	s_cselect_b32 s49, s47, s41
	s_cselect_b32 s48, s46, s40
	s_cselect_b32 s41, s29, s35
	s_cselect_b32 s40, s20, s21
	v_lshl_add_u64 v[152:153], s[0:1], 0, v[144:145]
	s_add_i32 m0, s23, 0xc000
	ds_read_b128 v[162:165], v157
	ds_read_b128 v[166:169], v157 offset:1024
	ds_read_b128 v[170:173], v157 offset:2048
	ds_read_b128 v[174:177], v157 offset:3072
	ds_read_b128 v[178:181], v157 offset:4096
	ds_read_b128 v[182:185], v157 offset:5120
	ds_read_b128 v[186:189], v157 offset:6144
	ds_read_b128 v[190:193], v157 offset:7168
	global_load_lds_dwordx4 v[152:153], off
	v_lshl_add_u64 v[152:153], s[0:1], 0, v[146:147]
	s_add_i32 m0, s23, 0xe000
	s_nop 0
	global_load_lds_dwordx4 v[152:153], off
	s_waitcnt lgkmcnt(11)
	s_add_i32 s60, 0, 0x14000
	v_add_u32_e32 v152, s60, v155
	s_add_i32 s45, s45, s72
	ds_read_b128 v[194:197], v152
	ds_read_b128 v[198:201], v152 offset:1024
	ds_read_b128 v[202:205], v152 offset:2048
	ds_read_b128 v[220:223], v152 offset:3072
	s_waitcnt vmcnt(8) lgkmcnt(0)
	s_barrier
	v_mfma_f32_16x16x32_f16 v[126:129], v[130:133], v[162:165], v[126:129]
	v_mfma_f32_16x16x32_f16 v[122:125], v[148:151], v[162:165], v[122:125]
	v_mfma_f32_16x16x32_f16 v[110:113], v[130:133], v[170:173], v[110:113]
	v_mfma_f32_16x16x32_f16 v[106:109], v[148:151], v[170:173], v[106:109]
	v_mfma_f32_16x16x32_f16 v[94:97], v[130:133], v[178:181], v[94:97]
	v_mfma_f32_16x16x32_f16 v[90:93], v[148:151], v[178:181], v[90:93]
	v_mfma_f32_16x16x32_f16 v[78:81], v[130:133], v[186:189], v[78:81]
	v_mfma_f32_16x16x32_f16 v[74:77], v[148:151], v[186:189], v[74:77]
	v_mfma_f32_16x16x32_f16 v[126:129], v[134:137], v[166:169], v[126:129]
	v_mfma_f32_16x16x32_f16 v[122:125], v[158:161], v[166:169], v[122:125]
	v_mfma_f32_16x16x32_f16 v[110:113], v[134:137], v[174:177], v[110:113]
	v_mfma_f32_16x16x32_f16 v[106:109], v[158:161], v[174:177], v[106:109]
	v_mfma_f32_16x16x32_f16 v[94:97], v[134:137], v[182:185], v[94:97]
	v_mfma_f32_16x16x32_f16 v[90:93], v[158:161], v[182:185], v[90:93]
	v_mfma_f32_16x16x32_f16 v[78:81], v[134:137], v[190:193], v[78:81]
	v_mfma_f32_16x16x32_f16 v[74:77], v[158:161], v[190:193], v[74:77]
	v_mfma_f32_16x16x32_f16 v[118:121], v[194:197], v[162:165], v[118:121]
	v_mfma_f32_16x16x32_f16 v[114:117], v[202:205], v[162:165], v[114:117]
	v_mfma_f32_16x16x32_f16 v[102:105], v[194:197], v[170:173], v[102:105]
	v_mfma_f32_16x16x32_f16 v[98:101], v[202:205], v[170:173], v[98:101]
	v_mfma_f32_16x16x32_f16 v[86:89], v[194:197], v[178:181], v[86:89]
	v_mfma_f32_16x16x32_f16 v[82:85], v[202:205], v[178:181], v[82:85]
	v_mfma_f32_16x16x32_f16 v[70:73], v[194:197], v[186:189], v[70:73]
	v_mfma_f32_16x16x32_f16 v[66:69], v[202:205], v[186:189], v[66:69]
	v_mfma_f32_16x16x32_f16 v[118:121], v[198:201], v[166:169], v[118:121]
	v_mfma_f32_16x16x32_f16 v[114:117], v[220:223], v[166:169], v[114:117]
	v_mfma_f32_16x16x32_f16 v[102:105], v[198:201], v[174:177], v[102:105]
	v_mfma_f32_16x16x32_f16 v[98:101], v[220:223], v[174:177], v[98:101]
	v_mfma_f32_16x16x32_f16 v[86:89], v[198:201], v[182:185], v[86:89]
	v_mfma_f32_16x16x32_f16 v[82:85], v[220:223], v[182:185], v[82:85]
	v_mfma_f32_16x16x32_f16 v[70:73], v[198:201], v[190:193], v[70:73]
	v_mfma_f32_16x16x32_f16 v[66:69], v[220:223], v[190:193], v[66:69]
	s_barrier
	v_lshl_add_u64 v[152:153], s[40:41], 0, v[0:1]
	s_mov_b32 m0, s45
	v_lshl_add_u64 v[206:207], s[40:41], 0, v[142:143]
	global_load_lds_dwordx4 v[152:153], off
	s_add_i32 m0, s45, 0x2000
	s_nop 0
	global_load_lds_dwordx4 v[206:207], off
	s_mov_b32 m0, s23
	v_lshl_add_u64 v[212:213], s[48:49], 0, v[138:139]
	ds_read_b128 v[162:165], v157 offset:16384
	ds_read_b128 v[166:169], v157 offset:17408
	ds_read_b128 v[170:173], v157 offset:18432
	ds_read_b128 v[174:177], v157 offset:19456
	ds_read_b128 v[178:181], v157 offset:20480
	ds_read_b128 v[182:185], v157 offset:21504
	ds_read_b128 v[186:189], v157 offset:22528
	ds_read_b128 v[190:193], v157 offset:23552
	global_load_lds_dwordx4 v[212:213], off
	v_lshl_add_u64 v[224:225], s[48:49], 0, v[140:141]
	s_mov_b32 m0, s27
	s_nop 0
	global_load_lds_dwordx4 v[224:225], off
	s_add_u32 s50, s40, 0x80000
	s_addc_u32 s51, s41, 0
	s_add_i32 s45, s60, s72
	v_lshl_add_u64 v[232:233], s[50:51], 0, v[0:1]
	s_mov_b32 m0, s45
	s_nop 0
	global_load_lds_dwordx4 v[232:233], off
	v_lshl_add_u64 v[232:233], s[50:51], 0, v[142:143]
	s_add_i32 m0, s45, 0x2000
	s_nop 0
	global_load_lds_dwordx4 v[232:233], off
	s_waitcnt vmcnt(8) lgkmcnt(0)
	s_barrier
; #define PG8_STAGE(bufoff, gbase, voff) do { _Pragma("unroll") for (int _i = 0; _i < 2; ++_i) \
;         __builtin_amdgcn_global_load_lds((const unsigned*)((const char*)(gbase) + (voff)[_i]), (LAS unsigned*)(lds + (bufoff) + ldsw + _i * 8192), 16, 0, 0); } while (0)
; #define PG8_LDA(dst, b, h) do { _Pragma("unroll") for (int m = 0; m < 4; ++m) _Pragma("unroll") for (int k = 0; k < 2; ++k) dst[m][k] = *(const LAS h16x8*)(lds + PG8_SA(b, h) + aoff + m * 2048 + k * 1024); } while (0)
; #define PG8_LDB(dst, b, h) do { _Pragma("unroll") for (int n = 0; n < 2; ++n) _Pragma("unroll") for (int k = 0; k < 2; ++k) dst[n][k] = *(const LAS h16x8*)(lds + PG8_SB(b, h) + boff + n * 2048 + k * 1024); } while (0)
; #define PG8_MMA(ai, bj, At, Bt_) do { __builtin_amdgcn_s_setprio(1); _Pragma("unroll") for (int m = 0; m < 4; ++m) _Pragma("unroll") for (int n = 0; n < 2; ++n) _Pragma("unroll") for (int k = 0; k < 2; ++k) \
;         acc[ai][bj][m][n] = __builtin_amdgcn_mfma_f32_16x16x32_f16(Bt_[n][k], At[m][k], acc[ai][bj][m][n], 0, 0, 0); __builtin_amdgcn_s_setprio(0); } while (0)
; #define PG8_WAIT_V(n) asm volatile("s_waitcnt vmcnt(" #n ")" ::: "memory")
; #define PG8_WAIT_L(n) asm volatile("s_waitcnt lgkmcnt(" #n ")" ::: "memory")
; #define PG8_BAR __builtin_amdgcn_s_barrier()
; #define PG8_SCHED __builtin_amdgcn_sched_barrier(0)
; template <class Epi, class AMap>
; __device__ __forceinline__ void gemm_phase(LAS unsigned char* lds, const AMap am, const int lda, const h16* Bt, const int ldb, const int M, const int N, const int K, const Epi& E) {
;     ...
;             PG8_BAR; PG8_WAIT_L(0); PG8_MMA(1, 0, At, B0); PG8_BAR; PG8_SCHED;
;             PG8_STAGE(PG8_SB(0, 1), b2 + hstepB, voffB);
;             PG8_WAIT_V(6); PG8_BAR; PG8_MMA(1, 1, At, B1); PG8_BAR;
;             PG8_LDB(B0, 1, 0); PG8_SCHED; PG8_LDA(At, 1, 0); PG8_STAGE(PG8_SA(0, 1), a2 + hstepA, voffA);
;             PG8_WAIT_L(8); PG8_BAR; PG8_WAIT_L(0); PG8_MMA(0, 0, At, B0); PG8_BAR; PG8_SCHED;
;             PG8_LDB(B1, 1, 1); PG8_STAGE(PG8_SB(1, 0), b3, voffB);
;             PG8_BAR; PG8_WAIT_L(0); PG8_MMA(0, 1, At, B1); PG8_BAR;
	v_mfma_f32_16x16x32_f16 v[62:65], v[130:133], v[162:165], v[62:65]
	v_mfma_f32_16x16x32_f16 v[58:61], v[148:151], v[162:165], v[58:61]
	v_mfma_f32_16x16x32_f16 v[46:49], v[130:133], v[170:173], v[46:49]
	v_mfma_f32_16x16x32_f16 v[42:45], v[148:151], v[170:173], v[42:45]
	v_mfma_f32_16x16x32_f16 v[30:33], v[130:133], v[178:181], v[30:33]
	v_mfma_f32_16x16x32_f16 v[26:29], v[148:151], v[178:181], v[26:29]
	v_mfma_f32_16x16x32_f16 v[14:17], v[130:133], v[186:189], v[14:17]
	v_mfma_f32_16x16x32_f16 v[10:13], v[148:151], v[186:189], v[10:13]
	v_mfma_f32_16x16x32_f16 v[62:65], v[134:137], v[166:169], v[62:65]
	v_mfma_f32_16x16x32_f16 v[58:61], v[158:161], v[166:169], v[58:61]
	v_mfma_f32_16x16x32_f16 v[46:49], v[134:137], v[174:177], v[46:49]
	v_mfma_f32_16x16x32_f16 v[42:45], v[158:161], v[174:177], v[42:45]
	v_mfma_f32_16x16x32_f16 v[30:33], v[134:137], v[182:185], v[30:33]
	v_mfma_f32_16x16x32_f16 v[26:29], v[158:161], v[182:185], v[26:29]
	v_mfma_f32_16x16x32_f16 v[14:17], v[134:137], v[190:193], v[14:17]
	v_mfma_f32_16x16x32_f16 v[10:13], v[158:161], v[190:193], v[10:13]
	v_mfma_f32_16x16x32_f16 v[54:57], v[194:197], v[162:165], v[54:57]
	v_mfma_f32_16x16x32_f16 v[50:53], v[202:205], v[162:165], v[50:53]
	v_mfma_f32_16x16x32_f16 v[38:41], v[194:197], v[170:173], v[38:41]
	v_mfma_f32_16x16x32_f16 v[34:37], v[202:205], v[170:173], v[34:37]
	v_mfma_f32_16x16x32_f16 v[22:25], v[194:197], v[178:181], v[22:25]
	v_mfma_f32_16x16x32_f16 v[18:21], v[202:205], v[178:181], v[18:21]
	v_mfma_f32_16x16x32_f16 v[6:9], v[194:197], v[186:189], v[6:9]
	v_mfma_f32_16x16x32_f16 v[2:5], v[202:205], v[186:189], v[2:5]
	v_mfma_f32_16x16x32_f16 v[54:57], v[198:201], v[166:169], v[54:57]
	v_mfma_f32_16x16x32_f16 v[50:53], v[220:223], v[166:169], v[50:53]
	v_mfma_f32_16x16x32_f16 v[38:41], v[198:201], v[174:177], v[38:41]
	v_mfma_f32_16x16x32_f16 v[34:37], v[220:223], v[174:177], v[34:37]
	v_mfma_f32_16x16x32_f16 v[22:25], v[198:201], v[182:185], v[22:25]
	v_mfma_f32_16x16x32_f16 v[18:21], v[220:223], v[182:185], v[18:21]
	v_mfma_f32_16x16x32_f16 v[6:9], v[198:201], v[190:193], v[6:9]
	v_mfma_f32_16x16x32_f16 v[2:5], v[220:223], v[190:193], v[2:5]
	s_barrier
	s_add_i32 s45, 0, 0x18000
	v_add_u32_e32 v234, s45, v155
	ds_read_b128 v[130:133], v234
	ds_read_b128 v[134:137], v234 offset:1024
	ds_read_b128 v[148:151], v234 offset:2048
	ds_read_b128 v[158:161], v234 offset:3072
	s_add_u32 s48, s48, 0x80000
	s_addc_u32 s49, s49, 0
	s_mov_b32 m0, s73
	v_lshl_add_u64 v[232:233], s[48:49], 0, v[138:139]
	ds_read_b128 v[162:165], v157 offset:32768
	ds_read_b128 v[166:169], v157 offset:33792
	ds_read_b128 v[170:173], v157 offset:34816
	ds_read_b128 v[174:177], v157 offset:35840
	ds_read_b128 v[178:181], v157 offset:36864
	ds_read_b128 v[182:185], v157 offset:37888
	ds_read_b128 v[186:189], v157 offset:38912
	ds_read_b128 v[190:193], v157 offset:39936
	global_load_lds_dwordx4 v[232:233], off
	v_lshl_add_u64 v[232:233], s[48:49], 0, v[140:141]
	s_mov_b32 m0, s74
	s_nop 0
	global_load_lds_dwordx4 v[232:233], off
	s_waitcnt lgkmcnt(11)
	s_add_i32 s48, 0, 0x1c000
	s_add_i32 s45, s45, s72
	v_add_u32_e32 v214, s48, v155
	v_lshl_add_u64 v[152:153], v[152:153], 0, s[92:93]
	s_mov_b32 m0, s45
	ds_read_b128 v[194:197], v214
	ds_read_b128 v[198:201], v214 offset:1024
	ds_read_b128 v[202:205], v214 offset:2048
	ds_read_b128 v[220:223], v214 offset:3072
	s_waitcnt vmcnt(8) lgkmcnt(0)
	s_barrier
	v_mfma_f32_16x16x32_f16 v[126:129], v[130:133], v[162:165], v[126:129]
	v_mfma_f32_16x16x32_f16 v[122:125], v[148:151], v[162:165], v[122:125]
	v_mfma_f32_16x16x32_f16 v[110:113], v[130:133], v[170:173], v[110:113]
	v_mfma_f32_16x16x32_f16 v[106:109], v[148:151], v[170:173], v[106:109]
	v_mfma_f32_16x16x32_f16 v[94:97], v[130:133], v[178:181], v[94:97]
	v_mfma_f32_16x16x32_f16 v[90:93], v[148:151], v[178:181], v[90:93]
	v_mfma_f32_16x16x32_f16 v[78:81], v[130:133], v[186:189], v[78:81]
	v_mfma_f32_16x16x32_f16 v[74:77], v[148:151], v[186:189], v[74:77]
	v_mfma_f32_16x16x32_f16 v[126:129], v[134:137], v[166:169], v[126:129]
	v_mfma_f32_16x16x32_f16 v[122:125], v[158:161], v[166:169], v[122:125]
	v_mfma_f32_16x16x32_f16 v[110:113], v[134:137], v[174:177], v[110:113]
	v_mfma_f32_16x16x32_f16 v[106:109], v[158:161], v[174:177], v[106:109]
	v_mfma_f32_16x16x32_f16 v[94:97], v[134:137], v[182:185], v[94:97]
	v_mfma_f32_16x16x32_f16 v[90:93], v[158:161], v[182:185], v[90:93]
	v_mfma_f32_16x16x32_f16 v[78:81], v[134:137], v[190:193], v[78:81]
	v_mfma_f32_16x16x32_f16 v[74:77], v[158:161], v[190:193], v[74:77]
	v_mfma_f32_16x16x32_f16 v[118:121], v[194:197], v[162:165], v[118:121]
	v_mfma_f32_16x16x32_f16 v[114:117], v[202:205], v[162:165], v[114:117]
	v_mfma_f32_16x16x32_f16 v[102:105], v[194:197], v[170:173], v[102:105]
	v_mfma_f32_16x16x32_f16 v[98:101], v[202:205], v[170:173], v[98:101]
	v_mfma_f32_16x16x32_f16 v[86:89], v[194:197], v[178:181], v[86:89]
	v_mfma_f32_16x16x32_f16 v[82:85], v[202:205], v[178:181], v[82:85]
	v_mfma_f32_16x16x32_f16 v[70:73], v[194:197], v[186:189], v[70:73]
	v_mfma_f32_16x16x32_f16 v[66:69], v[202:205], v[186:189], v[66:69]
	v_mfma_f32_16x16x32_f16 v[118:121], v[198:201], v[166:169], v[118:121]
	v_mfma_f32_16x16x32_f16 v[114:117], v[220:223], v[166:169], v[114:117]
	v_mfma_f32_16x16x32_f16 v[102:105], v[198:201], v[174:177], v[102:105]
	v_mfma_f32_16x16x32_f16 v[98:101], v[220:223], v[174:177], v[98:101]
	v_mfma_f32_16x16x32_f16 v[86:89], v[198:201], v[182:185], v[86:89]
	v_mfma_f32_16x16x32_f16 v[82:85], v[220:223], v[182:185], v[82:85]
	v_mfma_f32_16x16x32_f16 v[70:73], v[198:201], v[190:193], v[70:73]
	v_mfma_f32_16x16x32_f16 v[66:69], v[220:223], v[190:193], v[66:69]
	s_barrier
; #define PG8_STAGE(bufoff, gbase, voff) do { _Pragma("unroll") for (int _i = 0; _i < 2; ++_i) \
;         __builtin_amdgcn_global_load_lds((const unsigned*)((const char*)(gbase) + (voff)[_i]), (LAS unsigned*)(lds + (bufoff) + ldsw + _i * 8192), 16, 0, 0); } while (0)
; #define PG8_LDA(dst, b, h) do { _Pragma("unroll") for (int m = 0; m < 4; ++m) _Pragma("unroll") for (int k = 0; k < 2; ++k) dst[m][k] = *(const LAS h16x8*)(lds + PG8_SA(b, h) + aoff + m * 2048 + k * 1024); } while (0)
; #define PG8_LDB(dst, b, h) do { _Pragma("unroll") for (int n = 0; n < 2; ++n) _Pragma("unroll") for (int k = 0; k < 2; ++k) dst[n][k] = *(const LAS h16x8*)(lds + PG8_SB(b, h) + boff + n * 2048 + k * 1024); } while (0)
; #define PG8_MMA(ai, bj, At, Bt_) do { __builtin_amdgcn_s_setprio(1); _Pragma("unroll") for (int m = 0; m < 4; ++m) _Pragma("unroll") for (int n = 0; n < 2; ++n) _Pragma("unroll") for (int k = 0; k < 2; ++k) \
;         acc[ai][bj][m][n] = __builtin_amdgcn_mfma_f32_16x16x32_f16(Bt_[n][k], At[m][k], acc[ai][bj][m][n], 0, 0, 0); __builtin_amdgcn_s_setprio(0); } while (0)
; #define PG8_WAIT_V(n) asm volatile("s_waitcnt vmcnt(" #n ")" ::: "memory")
; #define PG8_WAIT_L(n) asm volatile("s_waitcnt lgkmcnt(" #n ")" ::: "memory")
; #define PG8_BAR __builtin_amdgcn_s_barrier()
; #define PG8_SCHED __builtin_amdgcn_sched_barrier(0)
; template <class Epi, class AMap>
; __device__ __forceinline__ void gemm_phase(LAS unsigned char* lds, const AMap am, const int lda, const h16* Bt, const int ldb, const int M, const int N, const int K, const Epi& E) {
;     ...
;             PG8_LDB(B1, 1, 1); PG8_STAGE(PG8_SB(1, 0), b3, voffB);
;             PG8_BAR; PG8_WAIT_L(0); PG8_MMA(0, 1, At, B1); PG8_BAR;
;             PG8_LDA(At, 1, 1); PG8_STAGE(PG8_SA(1, 0), a3, voffA);
;             PG8_BAR; PG8_WAIT_L(0); PG8_MMA(1, 0, At, B0); PG8_BAR; PG8_SCHED;
;             PG8_STAGE(PG8_SB(1, 1), b3 + hstepB, voffB);
;             PG8_WAIT_V(6); PG8_BAR; PG8_MMA(1, 1, At, B1); PG8_BAR;
;         }
;         E(acc, cur, wr, wc, fr, fq);
;         if (!has_next) break;
	global_load_lds_dwordx4 v[152:153], off
	v_lshl_add_u64 v[152:153], v[206:207], 0, s[92:93]
	s_add_i32 m0, s45, 0x2000
	s_nop 0
	global_load_lds_dwordx4 v[152:153], off
	s_mov_b32 m0, s75
	v_lshl_add_u64 v[152:153], v[212:213], 0, s[92:93]
	ds_read_b128 v[162:165], v157 offset:49152
	ds_read_b128 v[166:169], v157 offset:50176
	ds_read_b128 v[170:173], v157 offset:51200
	ds_read_b128 v[174:177], v157 offset:52224
	ds_read_b128 v[178:181], v157 offset:53248
	ds_read_b128 v[182:185], v157 offset:54272
	ds_read_b128 v[186:189], v157 offset:55296
	ds_read_b128 v[190:193], v157 offset:56320
	global_load_lds_dwordx4 v[152:153], off
	v_lshl_add_u64 v[152:153], v[224:225], 0, s[92:93]
	s_mov_b32 m0, s76
	s_nop 0
	global_load_lds_dwordx4 v[152:153], off
	s_add_u32 s40, s40, 0x80080
	s_addc_u32 s41, s41, 0
	s_add_i32 s45, s48, s72
	v_lshl_add_u64 v[232:233], s[40:41], 0, v[0:1]
	s_mov_b32 m0, s45
	s_nop 0
	global_load_lds_dwordx4 v[232:233], off
	v_lshl_add_u64 v[232:233], s[40:41], 0, v[142:143]
	s_add_i32 m0, s45, 0x2000
	s_nop 0
	global_load_lds_dwordx4 v[232:233], off
	s_add_i32 s43, s43, 2
	s_add_u32 s0, s0, 0x100
	s_addc_u32 s1, s1, 0
	s_add_u32 s21, s21, 0x100
	s_addc_u32 s35, s35, 0
	s_cmp_gt_u32 s43, 29
	s_waitcnt vmcnt(8) lgkmcnt(0)
	s_barrier
	v_mfma_f32_16x16x32_f16 v[62:65], v[130:133], v[162:165], v[62:65]
	v_mfma_f32_16x16x32_f16 v[58:61], v[148:151], v[162:165], v[58:61]
	v_mfma_f32_16x16x32_f16 v[46:49], v[130:133], v[170:173], v[46:49]
	v_mfma_f32_16x16x32_f16 v[42:45], v[148:151], v[170:173], v[42:45]
	v_mfma_f32_16x16x32_f16 v[30:33], v[130:133], v[178:181], v[30:33]
	v_mfma_f32_16x16x32_f16 v[26:29], v[148:151], v[178:181], v[26:29]
	v_mfma_f32_16x16x32_f16 v[14:17], v[130:133], v[186:189], v[14:17]
	v_mfma_f32_16x16x32_f16 v[10:13], v[148:151], v[186:189], v[10:13]
	v_mfma_f32_16x16x32_f16 v[62:65], v[134:137], v[166:169], v[62:65]
	v_mfma_f32_16x16x32_f16 v[58:61], v[158:161], v[166:169], v[58:61]
	v_mfma_f32_16x16x32_f16 v[46:49], v[134:137], v[174:177], v[46:49]
	v_mfma_f32_16x16x32_f16 v[42:45], v[158:161], v[174:177], v[42:45]
	v_mfma_f32_16x16x32_f16 v[30:33], v[134:137], v[182:185], v[30:33]
	v_mfma_f32_16x16x32_f16 v[26:29], v[158:161], v[182:185], v[26:29]
	v_mfma_f32_16x16x32_f16 v[14:17], v[134:137], v[190:193], v[14:17]
	v_mfma_f32_16x16x32_f16 v[10:13], v[158:161], v[190:193], v[10:13]
	v_mfma_f32_16x16x32_f16 v[54:57], v[194:197], v[162:165], v[54:57]
	v_mfma_f32_16x16x32_f16 v[50:53], v[202:205], v[162:165], v[50:53]
	v_mfma_f32_16x16x32_f16 v[38:41], v[194:197], v[170:173], v[38:41]
	v_mfma_f32_16x16x32_f16 v[34:37], v[202:205], v[170:173], v[34:37]
	v_mfma_f32_16x16x32_f16 v[22:25], v[194:197], v[178:181], v[22:25]
	v_mfma_f32_16x16x32_f16 v[18:21], v[202:205], v[178:181], v[18:21]
	v_mfma_f32_16x16x32_f16 v[6:9], v[194:197], v[186:189], v[6:9]
	v_mfma_f32_16x16x32_f16 v[2:5], v[202:205], v[186:189], v[2:5]
	v_mfma_f32_16x16x32_f16 v[54:57], v[198:201], v[166:169], v[54:57]
	v_mfma_f32_16x16x32_f16 v[50:53], v[220:223], v[166:169], v[50:53]
	v_mfma_f32_16x16x32_f16 v[38:41], v[198:201], v[174:177], v[38:41]
	v_mfma_f32_16x16x32_f16 v[34:37], v[220:223], v[174:177], v[34:37]
	v_mfma_f32_16x16x32_f16 v[22:25], v[198:201], v[182:185], v[22:25]
	v_mfma_f32_16x16x32_f16 v[18:21], v[220:223], v[182:185], v[18:21]
	v_mfma_f32_16x16x32_f16 v[6:9], v[198:201], v[190:193], v[6:9]
	v_mfma_f32_16x16x32_f16 v[2:5], v[220:223], v[190:193], v[2:5]
	s_barrier
	s_cbranch_scc0 .LBB0_799
	s_cmpk_gt_u32 s71, 0xff
	s_cbranch_scc1 .Lgx8
	s_barrier
